# speedup vs baseline: 1.0211x; 1.0211x over previous
; template <int DH, int MODE>
; __device__ void attn_item(const Params& p, int layer, int b, int blk, int head, char* smem) {
;     ...
;   {
;     constexpr int OST = DH + 4;
;     constexpr int CPR = DH / 8;
;     constexpr int NCH = 128 * CPR / 256;
;     float* Of = reinterpret_cast<float*>(smem);
;     uint4 gt[NCH];
; #pragma unroll
;     for (int i = 0; i < NCH; ++i) {
;       int q = tid + 256 * i, r = q / CPR, c = (q % CPR) * 8;
;       gt[i] = *reinterpret_cast<const uint4*>(P + (tq0 + r) * NP + gcol + c);
;     }
;     float lis[2][4];
; #pragma unroll
;     for (int m = 0; m < 2; ++m)
; #pragma unroll
;       for (int j = 0; j < 4; ++j) lis[m][j] = (MODE == 0) ? linv_s[wid * 32 + m * 16 + fq * 4 + j] : 1.f;
;     if (MODE == 0) __syncthreads();
; #pragma unroll
;     for (int m = 0; m < 2; ++m)
; #pragma unroll
;       for (int j = 0; j < 4; ++j) {
;         int r = wid * 32 + m * 16 + fq * 4 + j;
; #pragma unroll
;         for (int n = 0; n < NDT; ++n) Of[r * OST + n * 16 + fr] = o[m][n][j] * lis[m][j];
;       }
.LBB0_149:
	s_ashr_i32 s5, s83, 31
	s_add_u32 s4, s28, s83
	s_addc_u32 s5, s29, s5
	s_lshl_b32 s6, s80, 1
	s_add_u32 s8, s48, s6
	s_addc_u32 s9, s49, 0
	v_lshl_add_u64 v[2:3], s[10:11], 0, v[134:135]
	v_mov_b64_e32 v[4:5], s[8:9]
	v_mad_u64_u32 v[0:1], s[8:9], v2, s55, v[4:5]
	v_mad_i32_i24 v1, v3, s55, v1
	s_waitcnt vmcnt(12)
	v_lshl_add_u64 v[76:77], v[0:1], 0, v[138:139]
	v_add_u32_e32 v0, 0x100, v161
	v_ashrrev_i32_e32 v1, 31, v0
	v_lshrrev_b32_e32 v1, 28, v1
	v_add_u32_e32 v1, v0, v1
	v_ashrrev_i32_e32 v8, 4, v1
	v_and_b32_e32 v1, -16, v1
	s_waitcnt vmcnt(5)
	v_sub_u32_e32 v99, v0, v1
	v_lshlrev_b32_e32 v0, 3, v99
	v_ashrrev_i32_e32 v1, 31, v0
	s_waitcnt vmcnt(3)
	v_lshlrev_b64 v[92:93], 1, v[0:1]
	v_add_u32_e32 v0, 0x200, v161
	v_ashrrev_i32_e32 v1, 31, v0
	v_lshrrev_b32_e32 v1, 28, v1
	v_add_u32_e32 v1, v0, v1
	v_ashrrev_i32_e32 v9, 31, v8
	v_ashrrev_i32_e32 v94, 4, v1
	v_and_b32_e32 v1, -16, v1
	v_lshl_add_u64 v[10:11], s[10:11], 0, v[8:9]
	v_sub_u32_e32 v9, v0, v1
	v_lshlrev_b32_e32 v0, 3, v9
	v_ashrrev_i32_e32 v1, 31, v0
	v_lshlrev_b64 v[100:101], 1, v[0:1]
	v_add_u32_e32 v0, 0x300, v161
	v_ashrrev_i32_e32 v1, 31, v0
	v_lshrrev_b32_e32 v1, 28, v1
	v_add_u32_e32 v1, v0, v1
	v_ashrrev_i32_e32 v102, 4, v1
	v_and_b32_e32 v1, -16, v1
	v_sub_u32_e32 v128, v0, v1
	v_lshlrev_b32_e32 v0, 3, v128
	v_ashrrev_i32_e32 v1, 31, v0
	s_waitcnt vmcnt(0)
	v_lshlrev_b64 v[106:107], 1, v[0:1]
	v_add_u32_e32 v0, 0x400, v161
	v_ashrrev_i32_e32 v1, 31, v0
	v_lshrrev_b32_e32 v1, 28, v1
	v_add_u32_e32 v1, v0, v1
	v_ashrrev_i32_e32 v103, 31, v102
	v_ashrrev_i32_e32 v108, 4, v1
	v_and_b32_e32 v1, -16, v1
	v_lshl_add_u64 v[104:105], s[10:11], 0, v[102:103]
	v_sub_u32_e32 v103, v0, v1
	v_lshlrev_b32_e32 v0, 3, v103
	v_ashrrev_i32_e32 v1, 31, v0
	v_lshlrev_b64 v[112:113], 1, v[0:1]
	v_add_u32_e32 v0, 0x500, v161
	v_ashrrev_i32_e32 v1, 31, v0
	v_lshrrev_b32_e32 v1, 28, v1
	v_add_u32_e32 v1, v0, v1
	v_ashrrev_i32_e32 v109, 31, v108
	v_ashrrev_i32_e32 v114, 4, v1
	v_and_b32_e32 v1, -16, v1
	v_mad_u64_u32 v[6:7], s[8:9], v10, s55, v[4:5]
	v_ashrrev_i32_e32 v95, 31, v94
	v_lshl_add_u64 v[110:111], s[10:11], 0, v[108:109]
	v_sub_u32_e32 v109, v0, v1
	v_mad_i32_i24 v7, v11, s55, v7
	v_lshl_add_u64 v[96:97], s[10:11], 0, v[94:95]
	v_lshlrev_b32_e32 v0, 3, v109
	v_lshl_add_u64 v[78:79], v[6:7], 0, v[92:93]
	v_mad_u64_u32 v[6:7], s[8:9], v96, s55, v[4:5]
	v_ashrrev_i32_e32 v1, 31, v0
	v_mad_i32_i24 v7, v97, s55, v7
	v_lshlrev_b64 v[118:119], 1, v[0:1]
	v_add_u32_e32 v0, 0x600, v161
	v_lshl_add_u64 v[80:81], v[6:7], 0, v[100:101]
	v_mad_u64_u32 v[6:7], s[8:9], v104, s55, v[4:5]
	v_ashrrev_i32_e32 v1, 31, v0
	v_mad_i32_i24 v7, v105, s55, v7
	v_lshrrev_b32_e32 v1, 28, v1
	v_lshl_add_u64 v[82:83], v[6:7], 0, v[106:107]
	v_mad_u64_u32 v[6:7], s[8:9], v110, s55, v[4:5]
	v_ashrrev_i32_e32 v115, 31, v114
	v_add_u32_e32 v1, v0, v1
	v_mad_i32_i24 v7, v111, s55, v7
	v_lshl_add_u64 v[116:117], s[10:11], 0, v[114:115]
	v_ashrrev_i32_e32 v120, 4, v1
	v_and_b32_e32 v1, -16, v1
	v_lshl_add_u64 v[84:85], v[6:7], 0, v[112:113]
	v_mad_u64_u32 v[6:7], s[8:9], v116, s55, v[4:5]
	v_sub_u32_e32 v115, v0, v1
	v_ashrrev_i32_e32 v121, 31, v120
	v_mad_i32_i24 v7, v117, s55, v7
	v_lshlrev_b32_e32 v0, 3, v115
	v_lshl_add_u64 v[122:123], s[10:11], 0, v[120:121]
	v_lshl_add_u64 v[86:87], v[6:7], 0, v[118:119]
	v_mad_u64_u32 v[6:7], s[8:9], v122, s55, v[4:5]
	v_ashrrev_i32_e32 v1, 31, v0
	v_mad_i32_i24 v7, v123, s55, v7
	v_lshlrev_b64 v[124:125], 1, v[0:1]
	v_lshl_add_u64 v[0:1], v[6:7], 0, v[124:125]
	v_add_u32_e32 v6, 0x700, v161
	v_ashrrev_i32_e32 v7, 31, v6
	v_lshrrev_b32_e32 v7, 28, v7
	v_add_u32_e32 v7, v6, v7
	v_ashrrev_i32_e32 v126, 4, v7
	v_and_b32_e32 v7, -16, v7
	v_sub_u32_e32 v121, v6, v7
	v_lshlrev_b32_e32 v6, 3, v121
	v_ashrrev_i32_e32 v127, 31, v126
	v_lshl_add_u64 v[88:89], s[10:11], 0, v[126:127]
	v_ashrrev_i32_e32 v7, 31, v6
	v_mad_u64_u32 v[4:5], s[8:9], v88, s55, v[4:5]
	v_lshlrev_b64 v[90:91], 1, v[6:7]
	v_lshl_or_b32 v6, v137, 2, v130
	v_mad_i32_i24 v5, v89, s55, v5
	v_mul_lo_u32 v6, v6, s67
	v_lshl_add_u64 v[4:5], v[4:5], 0, v[90:91]
	v_lshl_add_u32 v95, v162, 2, v6
	s_barrier
	ds_write2_b32 v95, v12, v48 offset1:16
	ds_write2_b32 v95, v52, v56 offset0:32 offset1:48
	ds_write2_b32 v95, v60, v64 offset0:64 offset1:80
	ds_write2_b32 v95, v68, v72 offset0:96 offset1:112
	ds_write2_b32 v95, v13, v49 offset0:132 offset1:148
	ds_write2_b32 v95, v53, v57 offset0:164 offset1:180
	ds_write2_b32 v95, v61, v65 offset0:196 offset1:212
	ds_write2_b32 v95, v69, v73 offset0:228 offset1:244
	v_add_u32_e32 v12, 0x400, v95
	v_add_co_u32_e32 v4, vcc, s77, v4
	ds_write2_b32 v12, v14, v50 offset0:8 offset1:24
	ds_write2_b32 v12, v54, v58 offset0:40 offset1:56
	v_addc_co_u32_e32 v5, vcc, 0, v5, vcc
	global_load_dwordx4 v[4:7], v[4:5], off offset:512
	ds_write2_b32 v12, v62, v66 offset0:72 offset1:88
	ds_write2_b32 v12, v70, v74 offset0:104 offset1:120
	ds_write2_b32 v12, v15, v51 offset0:140 offset1:156
	ds_write2_b32 v12, v55, v59 offset0:172 offset1:188
	ds_write2_b32 v12, v63, v67 offset0:204 offset1:220
	ds_write2_b32 v12, v71, v75 offset0:236 offset1:252
	v_add_u32_e32 v12, 0x2000, v95
	ds_write2_b32 v12, v16, v20 offset0:64 offset1:80
	ds_write2_b32 v12, v24, v36 offset0:96 offset1:112
	ds_write2_b32 v12, v28, v40 offset0:128 offset1:144
	ds_write2_b32 v12, v44, v32 offset0:160 offset1:176
	ds_write2_b32 v12, v17, v21 offset0:196 offset1:212
	ds_write2_b32 v12, v25, v37 offset0:228 offset1:244
	v_add_u32_e32 v12, 0x2400, v95
	s_add_u32 s4, s4, s6
	ds_write2_b32 v12, v29, v41 offset0:4 offset1:20
	ds_write2_b32 v12, v45, v33 offset0:36 offset1:52
	ds_write2_b32 v12, v18, v22 offset0:72 offset1:88
; __device__ __forceinline__ unsigned pack2(float a, float b) { return (unsigned)f2bf(a) | ((unsigned)f2bf(b) << 16); }
; __device__ __forceinline__ float bflo(unsigned w) { return __uint_as_float(w << 16); }
; __device__ __forceinline__ float bfhi(unsigned w) { return __uint_as_float(w & 0xffff0000u); }
; __device__ __forceinline__ float silu_f(float g) { return g / (1.f + __expf(-g)); }
; template <int DH, int MODE>
; __device__ void attn_item(const Params& p, int layer, int b, int blk, int head, char* smem) {
;     ...
;     for (int i = 0; i < NCH; ++i) {
;       int q = tid + 256 * i, r = q / CPR, c = (q % CPR) * 8;
;       float4 m0 = *reinterpret_cast<const float4*>(Of + r * OST + c);
;       float4 m1 = *reinterpret_cast<const float4*>(Of + r * OST + c + 4);
;       float mm[8] = {m0.x, m0.y, m0.z, m0.w, m1.x, m1.y, m1.z, m1.w};
;       unsigned gw[4] = {gt[i].x, gt[i].y, gt[i].z, gt[i].w};
;       unsigned ow[4];
; #pragma unroll
;       for (int e = 0; e < 4; ++e)
;         ow[e] = pack2(mm[2 * e] * silu_f(bflo(gw[e])), mm[2 * e + 1] * silu_f(bfhi(gw[e])));
	ds_write2_b32 v12, v26, v38 offset0:104 offset1:120
	ds_write2_b32 v12, v30, v42 offset0:136 offset1:152
	ds_write2_b32 v12, v46, v34 offset0:168 offset1:184
	ds_write2_b32 v12, v19, v23 offset0:204 offset1:220
	ds_write2_b32 v12, v27, v39 offset0:236 offset1:252
	v_add_u32_e32 v12, 0x2800, v95
	s_addc_u32 s5, s5, 0
	ds_write2_b32 v12, v31, v43 offset0:12 offset1:28
	ds_write2_b32 v12, v47, v35 offset0:44 offset1:60
	v_mul_lo_u32 v12, v134, s67
	v_mov_b64_e32 v[14:15], s[4:5]
	v_lshl_add_u32 v98, v136, 2, v12
	v_mad_u64_u32 v[12:13], s[4:5], v2, s68, v[14:15]
	v_mul_lo_u32 v2, v8, s67
	v_mad_i32_i24 v13, v3, s68, v13
	v_lshl_add_u32 v95, v99, 5, v2
	v_mad_u64_u32 v[2:3], s[4:5], v10, s68, v[14:15]
	v_mad_i32_i24 v3, v11, s68, v3
	v_lshl_add_u64 v[26:27], v[2:3], 0, v[92:93]
	v_mul_lo_u32 v2, v94, s67
	v_lshl_add_u32 v93, v9, 5, v2
	v_mad_u64_u32 v[2:3], s[4:5], v96, s68, v[14:15]
	v_mad_i32_i24 v3, v97, s68, v3
	v_lshl_add_u64 v[20:21], v[2:3], 0, v[100:101]
	v_mul_lo_u32 v2, v102, s67
	v_lshl_add_u32 v92, v128, 5, v2
	v_mad_u64_u32 v[2:3], s[4:5], v104, s68, v[14:15]
	v_mad_i32_i24 v3, v105, s68, v3
	v_lshl_add_u64 v[16:17], v[2:3], 0, v[106:107]
	v_mul_lo_u32 v2, v108, s67
	v_lshl_add_u32 v75, v103, 5, v2
	v_mad_u64_u32 v[2:3], s[4:5], v110, s68, v[14:15]
	v_mad_i32_i24 v3, v111, s68, v3
	v_lshl_add_u64 v[30:31], v[12:13], 0, v[138:139]
	v_lshl_add_u64 v[12:13], v[2:3], 0, v[112:113]
	v_mul_lo_u32 v2, v114, s67
	v_lshl_add_u32 v74, v109, 5, v2
	v_mad_u64_u32 v[2:3], s[4:5], v116, s68, v[14:15]
	v_mad_i32_i24 v3, v117, s68, v3
	v_lshl_add_u64 v[10:11], v[2:3], 0, v[118:119]
	v_mul_lo_u32 v2, v120, s67
	v_lshl_add_u32 v73, v115, 5, v2
	v_mad_u64_u32 v[2:3], s[4:5], v122, s68, v[14:15]
	v_mad_i32_i24 v3, v123, s68, v3
	v_add_co_u32_e32 v0, vcc, s77, v0
	v_lshl_add_u64 v[8:9], v[2:3], 0, v[124:125]
	v_mul_lo_u32 v2, v126, s67
	v_addc_co_u32_e32 v1, vcc, 0, v1, vcc
	v_lshl_add_u32 v72, v121, 5, v2
	global_load_dwordx4 v[0:3], v[0:1], off offset:512
	v_mad_u64_u32 v[14:15], s[4:5], v88, s68, v[14:15]
	v_mad_i32_i24 v15, v89, s68, v15
	v_lshl_add_u64 v[14:15], v[14:15], 0, v[90:91]
	s_waitcnt vmcnt(1)
	v_lshlrev_b32_e32 v22, 16, v5
	v_lshlrev_b32_e32 v23, 16, v4
	v_mul_f32_e32 v18, 0xbfb8aa3b, v23
	v_mul_f32_e32 v19, 0xbfb8aa3b, v22
	v_exp_f32_e32 v18, v18
	v_exp_f32_e32 v19, v19
	v_and_b32_e32 v24, 0xffff0000, v5
	v_and_b32_e32 v28, 0xffff0000, v4
	v_mul_f32_e32 v4, 0xbfb8aa3b, v28
	v_pk_add_f32 v[18:19], v[18:19], 1.0 op_sel_hi:[1,0]
	v_exp_f32_e32 v4, v4
	v_and_b32_e32 v34, 0xffff0000, v6
	v_rcp_f32_e32 v19, v19
	s_nop 0
	v_mul_f32_e32 v19, v22, v19
	v_mul_f32_e32 v5, 0xbfb8aa3b, v24
	v_exp_f32_e32 v5, v5
	s_nop 0
	v_pk_add_f32 v[4:5], v[4:5], 1.0 op_sel_hi:[1,0]
	v_rcp_f32_e32 v18, v18
	s_nop 0
	v_mul_f32_e32 v18, v23, v18
	v_lshlrev_b32_e32 v33, 16, v6
	v_rcp_f32_e32 v23, v5
	s_nop 0
	v_mul_f32_e32 v23, v24, v23
	v_lshlrev_b32_e32 v32, 16, v7
	v_mul_f32_e32 v24, 0xbfb8aa3b, v33
	v_mul_f32_e32 v25, 0xbfb8aa3b, v32
	v_exp_f32_e32 v24, v24
	v_exp_f32_e32 v25, v25
	v_rcp_f32_e32 v22, v4
	s_nop 0
	v_mul_f32_e32 v22, v28, v22
	v_and_b32_e32 v28, 0xffff0000, v7
	v_pk_add_f32 v[4:5], v[24:25], 1.0 op_sel_hi:[1,0]
	v_mul_f32_e32 v6, 0xbfb8aa3b, v34
	v_exp_f32_e32 v6, v6
	s_waitcnt vmcnt(0)
	v_lshlrev_b32_e32 v40, 16, v3
	v_lshlrev_b32_e32 v41, 16, v2
	v_rcp_f32_e32 v25, v5
	s_nop 0
	v_mul_f32_e32 v25, v32, v25
	v_mul_f32_e32 v7, 0xbfb8aa3b, v28
	v_exp_f32_e32 v7, v7
	s_nop 0
	v_pk_add_f32 v[6:7], v[6:7], 1.0 op_sel_hi:[1,0]
	v_rcp_f32_e32 v24, v4
	s_nop 0
	v_mul_f32_e32 v24, v33, v24
	v_rcp_f32_e32 v29, v7
	s_nop 0
	v_mul_f32_e32 v29, v28, v29
	v_lshlrev_b32_e32 v32, 16, v1
	v_lshlrev_b32_e32 v36, 16, v0
	v_mul_f32_e32 v4, 0xbfb8aa3b, v36
	v_mul_f32_e32 v5, 0xbfb8aa3b, v32
	v_exp_f32_e32 v4, v4
	v_exp_f32_e32 v5, v5
	v_rcp_f32_e32 v28, v6
	s_nop 0
	v_mul_f32_e32 v28, v34, v28
	v_and_b32_e32 v6, 0xffff0000, v1
	v_pk_add_f32 v[4:5], v[4:5], 1.0 op_sel_hi:[1,0]
	v_and_b32_e32 v34, 0xffff0000, v0
	v_mul_f32_e32 v0, 0xbfb8aa3b, v34
	v_exp_f32_e32 v0, v0
	v_and_b32_e32 v42, 0xffff0000, v3
	v_rcp_f32_e32 v33, v5
	s_nop 0
	v_mul_f32_e32 v33, v32, v33
	v_mul_f32_e32 v1, 0xbfb8aa3b, v6
	v_exp_f32_e32 v1, v1
	s_nop 0
	v_pk_add_f32 v[0:1], v[0:1], 1.0 op_sel_hi:[1,0]
	v_rcp_f32_e32 v32, v4
	s_nop 0
	v_mul_f32_e32 v32, v36, v32
	v_rcp_f32_e32 v35, v1
	s_nop 0
	v_mul_f32_e32 v35, v6, v35
	v_add_co_u32_e64 v4, s[4:5], s77, v86
	s_nop 0
	s_nop 0
	v_addc_co_u32_e64 v5, s[4:5], 0, v87, s[4:5]
	global_load_dwordx4 v[4:7], v[4:5], off offset:512
	v_mul_f32_e32 v36, 0xbfb8aa3b, v41
	v_mul_f32_e32 v37, 0xbfb8aa3b, v40
	v_exp_f32_e32 v36, v36
	v_exp_f32_e32 v37, v37
	v_rcp_f32_e32 v1, v0
	s_nop 0
	v_mul_f32_e32 v34, v34, v1
	v_and_b32_e32 v43, 0xffff0000, v2
	v_pk_add_f32 v[0:1], v[36:37], 1.0 op_sel_hi:[1,0]
	v_mul_f32_e32 v2, 0xbfb8aa3b, v43
	v_exp_f32_e32 v2, v2
	v_rcp_f32_e32 v37, v1
	s_nop 0
	v_mul_f32_e32 v37, v40, v37
	v_mul_f32_e32 v3, 0xbfb8aa3b, v42
	v_exp_f32_e32 v3, v3
	s_nop 0
	v_pk_add_f32 v[38:39], v[2:3], 1.0 op_sel_hi:[1,0]
	v_rcp_f32_e32 v36, v0
	s_nop 0
	v_mul_f32_e32 v36, v41, v36
	v_rcp_f32_e32 v39, v39
	s_nop 0
	v_mul_f32_e32 v39, v42, v39
	v_add_co_u32_e64 v0, s[4:5], s77, v84
	s_waitcnt vmcnt(0)
; __device__ __forceinline__ unsigned pack2(float a, float b) { return (unsigned)f2bf(a) | ((unsigned)f2bf(b) << 16); }
; __device__ __forceinline__ float bflo(unsigned w) { return __uint_as_float(w << 16); }
; __device__ __forceinline__ float bfhi(unsigned w) { return __uint_as_float(w & 0xffff0000u); }
; __device__ __forceinline__ float silu_f(float g) { return g / (1.f + __expf(-g)); }
; template <int DH, int MODE>
; __device__ void attn_item(const Params& p, int layer, int b, int blk, int head, char* smem) {
;     ...
;     for (int i = 0; i < NCH; ++i) {
;       int q = tid + 256 * i, r = q / CPR, c = (q % CPR) * 8;
;       float4 m0 = *reinterpret_cast<const float4*>(Of + r * OST + c);
;       float4 m1 = *reinterpret_cast<const float4*>(Of + r * OST + c + 4);
;       float mm[8] = {m0.x, m0.y, m0.z, m0.w, m1.x, m1.y, m1.z, m1.w};
;       unsigned gw[4] = {gt[i].x, gt[i].y, gt[i].z, gt[i].w};
;       unsigned ow[4];
; #pragma unroll
;       for (int e = 0; e < 4; ++e)
;         ow[e] = pack2(mm[2 * e] * silu_f(bflo(gw[e])), mm[2 * e + 1] * silu_f(bfhi(gw[e])));
	v_lshlrev_b32_e32 v46, 16, v5
	v_lshlrev_b32_e32 v47, 16, v4
	v_mul_f32_e32 v40, 0xbfb8aa3b, v47
	v_mul_f32_e32 v41, 0xbfb8aa3b, v46
	v_exp_f32_e32 v40, v40
	v_exp_f32_e32 v41, v41
	v_addc_co_u32_e64 v1, s[4:5], 0, v85, s[4:5]
	v_rcp_f32_e32 v38, v38
	s_nop 0
	v_mul_f32_e32 v38, v43, v38
	v_pk_add_f32 v[40:41], v[40:41], 1.0 op_sel_hi:[1,0]
	v_and_b32_e32 v42, 0xffff0000, v5
	global_load_dwordx4 v[0:3], v[0:1], off offset:512
	v_and_b32_e32 v48, 0xffff0000, v4
	v_mul_f32_e32 v4, 0xbfb8aa3b, v48
	v_rcp_f32_e32 v41, v41
	s_nop 0
	v_mul_f32_e32 v41, v46, v41
	v_exp_f32_e32 v4, v4
	v_mul_f32_e32 v5, 0xbfb8aa3b, v42
	v_exp_f32_e32 v5, v5
	s_nop 0
	v_pk_add_f32 v[4:5], v[4:5], 1.0 op_sel_hi:[1,0]
	v_rcp_f32_e32 v40, v40
	s_nop 0
	v_mul_f32_e32 v40, v47, v40
	v_lshlrev_b32_e32 v49, 16, v6
	v_rcp_f32_e32 v43, v5
	s_nop 0
	v_mul_f32_e32 v43, v42, v43
	v_lshlrev_b32_e32 v46, 16, v7
	v_mul_f32_e32 v44, 0xbfb8aa3b, v49
	v_mul_f32_e32 v45, 0xbfb8aa3b, v46
	v_exp_f32_e32 v44, v44
	v_exp_f32_e32 v45, v45
	v_rcp_f32_e32 v42, v4
	s_nop 0
	v_mul_f32_e32 v42, v48, v42
	v_and_b32_e32 v47, 0xffff0000, v7
	v_pk_add_f32 v[4:5], v[44:45], 1.0 op_sel_hi:[1,0]
	v_and_b32_e32 v48, 0xffff0000, v6
	v_mul_f32_e32 v6, 0xbfb8aa3b, v48
	v_exp_f32_e32 v6, v6
	v_rcp_f32_e32 v45, v5
	s_nop 0
	v_mul_f32_e32 v45, v46, v45
	v_mul_f32_e32 v7, 0xbfb8aa3b, v47
	v_exp_f32_e32 v7, v7
	s_nop 0
	v_pk_add_f32 v[6:7], v[6:7], 1.0 op_sel_hi:[1,0]
	v_rcp_f32_e32 v44, v4
	s_nop 0
	v_mul_f32_e32 v44, v49, v44
	v_rcp_f32_e32 v4, v7
	s_nop 0
	v_mul_f32_e32 v47, v47, v4
	s_waitcnt vmcnt(0)
	v_lshlrev_b32_e32 v50, 16, v1
	v_lshlrev_b32_e32 v51, 16, v0
	v_mul_f32_e32 v4, 0xbfb8aa3b, v51
	v_mul_f32_e32 v5, 0xbfb8aa3b, v50
	v_exp_f32_e32 v4, v4
	v_exp_f32_e32 v5, v5
	v_rcp_f32_e32 v46, v6
	s_nop 0
	v_mul_f32_e32 v46, v48, v46
	v_and_b32_e32 v6, 0xffff0000, v1
	v_pk_add_f32 v[4:5], v[4:5], 1.0 op_sel_hi:[1,0]
	v_and_b32_e32 v54, 0xffff0000, v0
	v_mul_f32_e32 v0, 0xbfb8aa3b, v54
	v_exp_f32_e32 v0, v0
	v_lshlrev_b32_e32 v58, 16, v2
	v_rcp_f32_e32 v49, v5
	s_nop 0
	v_mul_f32_e32 v49, v50, v49
	v_mul_f32_e32 v1, 0xbfb8aa3b, v6
	v_exp_f32_e32 v1, v1
	s_nop 0
	v_pk_add_f32 v[0:1], v[0:1], 1.0 op_sel_hi:[1,0]
	v_rcp_f32_e32 v48, v4
	s_nop 0
	v_mul_f32_e32 v48, v51, v48
	v_lshlrev_b32_e32 v57, 16, v3
	v_rcp_f32_e32 v51, v1
	s_nop 0
	v_mul_f32_e32 v51, v6, v51
	v_add_co_u32_e64 v4, s[4:5], s77, v82
	s_nop 0
	s_nop 0
	v_addc_co_u32_e64 v5, s[4:5], 0, v83, s[4:5]
	global_load_dwordx4 v[4:7], v[4:5], off offset:512
	v_mul_f32_e32 v50, 0xbfb8aa3b, v58
	v_exp_f32_e32 v52, v50
	v_mul_f32_e32 v50, 0xbfb8aa3b, v57
	v_exp_f32_e32 v53, v50
	v_rcp_f32_e32 v50, v0
	s_nop 0
	v_mul_f32_e32 v50, v54, v50
	v_and_b32_e32 v56, 0xffff0000, v3
	v_pk_add_f32 v[0:1], v[52:53], 1.0 op_sel_hi:[1,0]
	v_and_b32_e32 v59, 0xffff0000, v2
	v_mul_f32_e32 v2, 0xbfb8aa3b, v59
	v_exp_f32_e32 v2, v2
	v_rcp_f32_e32 v53, v1
	s_nop 0
	v_mul_f32_e32 v53, v57, v53
	v_mul_f32_e32 v3, 0xbfb8aa3b, v56
	v_exp_f32_e32 v3, v3
	s_nop 0
	v_pk_add_f32 v[54:55], v[2:3], 1.0 op_sel_hi:[1,0]
	v_rcp_f32_e32 v52, v0
	s_nop 0
	v_mul_f32_e32 v52, v58, v52
	v_rcp_f32_e32 v55, v55
	s_nop 0
	v_mul_f32_e32 v55, v56, v55
	v_add_co_u32_e64 v0, s[4:5], s77, v80
	s_waitcnt vmcnt(0)
	v_lshlrev_b32_e32 v62, 16, v5
	v_lshlrev_b32_e32 v63, 16, v4
	v_mul_f32_e32 v56, 0xbfb8aa3b, v63
	v_mul_f32_e32 v57, 0xbfb8aa3b, v62
	v_exp_f32_e32 v56, v56
	v_exp_f32_e32 v57, v57
	v_addc_co_u32_e64 v1, s[4:5], 0, v81, s[4:5]
	v_rcp_f32_e32 v54, v54
	s_nop 0
	v_mul_f32_e32 v54, v59, v54
	v_pk_add_f32 v[56:57], v[56:57], 1.0 op_sel_hi:[1,0]
	v_and_b32_e32 v58, 0xffff0000, v5
	global_load_dwordx4 v[0:3], v[0:1], off offset:512
	v_and_b32_e32 v64, 0xffff0000, v4
	v_mul_f32_e32 v4, 0xbfb8aa3b, v64
	v_rcp_f32_e32 v57, v57
	s_nop 0
	v_mul_f32_e32 v57, v62, v57
	v_exp_f32_e32 v4, v4
	v_mul_f32_e32 v5, 0xbfb8aa3b, v58
	v_exp_f32_e32 v5, v5
	s_nop 0
	v_pk_add_f32 v[4:5], v[4:5], 1.0 op_sel_hi:[1,0]
	v_rcp_f32_e32 v56, v56
	s_nop 0
	v_mul_f32_e32 v56, v63, v56
	v_lshlrev_b32_e32 v65, 16, v6
	v_rcp_f32_e32 v59, v5
	s_nop 0
	v_mul_f32_e32 v59, v58, v59
	v_lshlrev_b32_e32 v62, 16, v7
	v_mul_f32_e32 v60, 0xbfb8aa3b, v65
	v_mul_f32_e32 v61, 0xbfb8aa3b, v62
	v_exp_f32_e32 v60, v60
	v_exp_f32_e32 v61, v61
	v_rcp_f32_e32 v58, v4
	s_nop 0
	v_mul_f32_e32 v58, v64, v58
	v_and_b32_e32 v63, 0xffff0000, v7
	v_pk_add_f32 v[4:5], v[60:61], 1.0 op_sel_hi:[1,0]
	v_and_b32_e32 v64, 0xffff0000, v6
	v_mul_f32_e32 v6, 0xbfb8aa3b, v64
	v_exp_f32_e32 v6, v6
	v_rcp_f32_e32 v61, v5
	s_nop 0
	v_mul_f32_e32 v61, v62, v61
	v_mul_f32_e32 v7, 0xbfb8aa3b, v63
	v_exp_f32_e32 v7, v7
	s_nop 0
	v_pk_add_f32 v[6:7], v[6:7], 1.0 op_sel_hi:[1,0]
	v_rcp_f32_e32 v60, v4
	s_nop 0
	v_mul_f32_e32 v60, v65, v60
	v_rcp_f32_e32 v4, v7
	s_nop 0
	v_mul_f32_e32 v63, v63, v4
	s_waitcnt vmcnt(0)
	v_lshlrev_b32_e32 v66, 16, v1
	v_lshlrev_b32_e32 v67, 16, v0
	v_mul_f32_e32 v4, 0xbfb8aa3b, v67
	v_mul_f32_e32 v5, 0xbfb8aa3b, v66
	v_exp_f32_e32 v4, v4
	v_exp_f32_e32 v5, v5
	v_and_b32_e32 v68, 0xffff0000, v1
	v_rcp_f32_e32 v62, v6
	s_nop 0
	v_mul_f32_e32 v62, v64, v62
	v_pk_add_f32 v[4:5], v[4:5], 1.0 op_sel_hi:[1,0]
	v_and_b32_e32 v69, 0xffff0000, v0
	v_mul_f32_e32 v0, 0xbfb8aa3b, v69
	v_exp_f32_e32 v6, v0
	v_and_b32_e32 v80, 0xffff0000, v2
	v_rcp_f32_e32 v1, v5
	s_nop 0
	v_mul_f32_e32 v1, v66, v1
	v_mul_f32_e32 v7, 0xbfb8aa3b, v68
	v_exp_f32_e32 v7, v7
	s_nop 0
	v_pk_add_f32 v[64:65], v[6:7], 1.0 op_sel_hi:[1,0]
	v_rcp_f32_e32 v0, v4
	s_nop 0
	v_mul_f32_e32 v0, v67, v0
	v_rcp_f32_e32 v65, v65
	s_nop 0
	v_mul_f32_e32 v65, v68, v65
	v_add_co_u32_e64 v4, s[4:5], s77, v78
	s_nop 0
	s_nop 0
	v_addc_co_u32_e64 v5, s[4:5], 0, v79, s[4:5]
	global_load_dwordx4 v[4:7], v[4:5], off offset:512
	v_lshlrev_b32_e32 v78, 16, v3
	v_lshlrev_b32_e32 v79, 16, v2
	v_mul_f32_e32 v66, 0xbfb8aa3b, v79
	v_mul_f32_e32 v67, 0xbfb8aa3b, v78
	v_exp_f32_e32 v66, v66
	v_exp_f32_e32 v67, v67
	v_and_b32_e32 v70, 0xffff0000, v3
	v_rcp_f32_e32 v64, v64
	s_nop 0
	v_mul_f32_e32 v64, v69, v64
	v_pk_add_f32 v[66:67], v[66:67], 1.0 op_sel_hi:[1,0]
	v_mul_f32_e32 v2, 0xbfb8aa3b, v80
	v_exp_f32_e32 v68, v2
	v_mul_f32_e32 v69, 0xbfb8aa3b, v70
	v_exp_f32_e32 v69, v69
	v_rcp_f32_e32 v3, v67
	s_nop 0
	v_mul_f32_e32 v3, v78, v3
	v_pk_add_f32 v[68:69], v[68:69], 1.0 op_sel_hi:[1,0]
	v_rcp_f32_e32 v2, v66
	s_nop 0
	v_mul_f32_e32 v2, v79, v2
	v_rcp_f32_e32 v67, v69
	s_nop 0
	v_mul_f32_e32 v67, v70, v67
	v_add_co_u32_e64 v70, s[4:5], s77, v76
	s_nop 0
	s_nop 0
	v_addc_co_u32_e64 v71, s[4:5], 0, v77, s[4:5]
	global_load_dwordx4 v[76:79], v[70:71], off offset:512
	v_rcp_f32_e32 v66, v68
	s_nop 0
	v_mul_f32_e32 v66, v80, v66
	s_waitcnt vmcnt(1)
	v_lshlrev_b32_e32 v82, 16, v5
	v_lshlrev_b32_e32 v83, 16, v4
	v_mul_f32_e32 v70, 0xbfb8aa3b, v83
	v_mul_f32_e32 v71, 0xbfb8aa3b, v82
	v_exp_f32_e32 v70, v70
	v_exp_f32_e32 v71, v71
	v_and_b32_e32 v80, 0xffff0000, v5
	v_and_b32_e32 v84, 0xffff0000, v4
	v_mul_f32_e32 v4, 0xbfb8aa3b, v84
	v_pk_add_f32 v[68:69], v[70:71], 1.0 op_sel_hi:[1,0]
	v_exp_f32_e32 v70, v4
	s_waitcnt lgkmcnt(0)
	s_barrier
; __device__ __forceinline__ unsigned pack2(float a, float b) { return (unsigned)f2bf(a) | ((unsigned)f2bf(b) << 16); }
; __device__ __forceinline__ float bflo(unsigned w) { return __uint_as_float(w << 16); }
; __device__ __forceinline__ float bfhi(unsigned w) { return __uint_as_float(w & 0xffff0000u); }
; __device__ __forceinline__ float silu_f(float g) { return g / (1.f + __expf(-g)); }
; template <int DH, int MODE>
; __device__ void attn_item(const Params& p, int layer, int b, int blk, int head, char* smem) {
;     ...
;     for (int i = 0; i < NCH; ++i) {
;       int q = tid + 256 * i, r = q / CPR, c = (q % CPR) * 8;
;       float4 m0 = *reinterpret_cast<const float4*>(Of + r * OST + c);
;       float4 m1 = *reinterpret_cast<const float4*>(Of + r * OST + c + 4);
;       float mm[8] = {m0.x, m0.y, m0.z, m0.w, m1.x, m1.y, m1.z, m1.w};
;       unsigned gw[4] = {gt[i].x, gt[i].y, gt[i].z, gt[i].w};
;       unsigned ow[4];
; #pragma unroll
;       for (int e = 0; e < 4; ++e)
;         ow[e] = pack2(mm[2 * e] * silu_f(bflo(gw[e])), mm[2 * e + 1] * silu_f(bfhi(gw[e])));
;       *reinterpret_cast<uint4*>(Y + (tq0 + r) * YW + ycol + c) = make_uint4(ow[0], ow[1], ow[2], ow[3]);
	v_mul_f32_e32 v71, 0xbfb8aa3b, v80
	v_exp_f32_e32 v71, v71
	v_rcp_f32_e32 v5, v69
	s_nop 0
	v_mul_f32_e32 v5, v82, v5
	v_pk_add_f32 v[70:71], v[70:71], 1.0 op_sel_hi:[1,0]
	v_rcp_f32_e32 v4, v68
	s_nop 0
	v_mul_f32_e32 v4, v83, v4
	v_rcp_f32_e32 v69, v71
	s_nop 0
	v_mul_f32_e32 v69, v80, v69
	v_lshlrev_b32_e32 v82, 16, v7
	v_lshlrev_b32_e32 v85, 16, v6
	v_mul_f32_e32 v80, 0xbfb8aa3b, v85
	v_mul_f32_e32 v81, 0xbfb8aa3b, v82
	v_exp_f32_e32 v80, v80
	v_exp_f32_e32 v81, v81
	v_rcp_f32_e32 v68, v70
	s_nop 0
	v_mul_f32_e32 v68, v84, v68
	v_and_b32_e32 v83, 0xffff0000, v7
	v_pk_add_f32 v[70:71], v[80:81], 1.0 op_sel_hi:[1,0]
	v_and_b32_e32 v84, 0xffff0000, v6
	v_mul_f32_e32 v6, 0xbfb8aa3b, v84
	v_exp_f32_e32 v80, v6
	s_waitcnt vmcnt(0)
	v_and_b32_e32 v94, 0xffff0000, v78
	v_mul_f32_e32 v81, 0xbfb8aa3b, v83
	v_exp_f32_e32 v81, v81
	v_rcp_f32_e32 v7, v71
	s_nop 0
	v_mul_f32_e32 v7, v82, v7
	v_pk_add_f32 v[80:81], v[80:81], 1.0 op_sel_hi:[1,0]
	v_rcp_f32_e32 v6, v70
	s_nop 0
	v_mul_f32_e32 v6, v85, v6
	v_rcp_f32_e32 v71, v81
	s_nop 0
	v_mul_f32_e32 v71, v83, v71
	v_lshlrev_b32_e32 v86, 16, v77
	v_lshlrev_b32_e32 v87, 16, v76
	v_mul_f32_e32 v82, 0xbfb8aa3b, v87
	v_mul_f32_e32 v83, 0xbfb8aa3b, v86
	v_exp_f32_e32 v82, v82
	v_exp_f32_e32 v83, v83
	v_rcp_f32_e32 v70, v80
	s_nop 0
	v_mul_f32_e32 v70, v84, v70
	v_and_b32_e32 v88, 0xffff0000, v77
	v_pk_add_f32 v[80:81], v[82:83], 1.0 op_sel_hi:[1,0]
	v_and_b32_e32 v83, 0xffff0000, v76
	v_mul_f32_e32 v76, 0xbfb8aa3b, v83
	v_exp_f32_e32 v76, v76
	v_rcp_f32_e32 v85, v81
	s_nop 0
	v_mul_f32_e32 v85, v86, v85
	v_mul_f32_e32 v77, 0xbfb8aa3b, v88
	v_exp_f32_e32 v77, v77
	s_nop 0
	v_pk_add_f32 v[76:77], v[76:77], 1.0 op_sel_hi:[1,0]
	v_rcp_f32_e32 v84, v80
	s_nop 0
	v_mul_f32_e32 v84, v87, v84
	v_rcp_f32_e32 v87, v77
	s_nop 0
	v_mul_f32_e32 v87, v88, v87
	v_lshlrev_b32_e32 v90, 16, v78
	v_lshlrev_b32_e32 v82, 16, v79
	v_mul_f32_e32 v80, 0xbfb8aa3b, v90
	v_mul_f32_e32 v81, 0xbfb8aa3b, v82
	v_exp_f32_e32 v80, v80
	v_exp_f32_e32 v81, v81
	v_rcp_f32_e32 v86, v76
	s_nop 0
	v_mul_f32_e32 v86, v83, v86
	v_and_b32_e32 v83, 0xffff0000, v79
	v_pk_add_f32 v[76:77], v[80:81], 1.0 op_sel_hi:[1,0]
	v_mul_f32_e32 v78, 0xbfb8aa3b, v94
	v_exp_f32_e32 v78, v78
	v_rcp_f32_e32 v89, v77
	s_nop 0
	v_mul_f32_e32 v89, v82, v89
	v_mul_f32_e32 v79, 0xbfb8aa3b, v83
	v_exp_f32_e32 v79, v79
	s_nop 0
	v_pk_add_f32 v[80:81], v[78:79], 1.0 op_sel_hi:[1,0]
	v_rcp_f32_e32 v88, v76
	s_nop 0
	v_mul_f32_e32 v88, v90, v88
	v_rcp_f32_e32 v91, v81
	s_nop 0
	v_mul_f32_e32 v91, v83, v91
	ds_read_b128 v[76:79], v98
	v_rcp_f32_e32 v90, v80
	s_nop 0
	v_mul_f32_e32 v90, v94, v90
	ds_read_b128 v[80:83], v98 offset:16
	v_add_co_u32_e32 v30, vcc, s74, v30
	s_waitcnt lgkmcnt(1)
	v_mov_b32_e32 v96, v76
	v_mov_b32_e32 v97, v78
	v_pk_mul_f32 v[84:85], v[84:85], v[96:97]
	v_mov_b32_e32 v78, v77
	v_pk_mul_f32 v[76:77], v[86:87], v[78:79]
	v_and_b32_sdwa v78, v85, v155 dst_sel:DWORD dst_unused:UNUSED_PAD src0_sel:WORD_1 src1_sel:DWORD
	v_and_b32_sdwa v79, v84, v155 dst_sel:DWORD dst_unused:UNUSED_PAD src0_sel:WORD_1 src1_sel:DWORD
	v_add3_u32 v79, v84, v79, s66
	v_add3_u32 v78, v85, v78, s66
	v_and_b32_sdwa v84, v77, v155 dst_sel:DWORD dst_unused:UNUSED_PAD src0_sel:WORD_1 src1_sel:DWORD
	v_and_b32_sdwa v85, v76, v155 dst_sel:DWORD dst_unused:UNUSED_PAD src0_sel:WORD_1 src1_sel:DWORD
	v_add3_u32 v77, v77, v84, s66
	v_add3_u32 v76, v76, v85, s66
	v_and_b32_e32 v77, 0xffff0000, v77
	v_and_b32_e32 v76, 0xffff0000, v76
	v_or_b32_sdwa v77, v77, v78 dst_sel:DWORD dst_unused:UNUSED_PAD src0_sel:DWORD src1_sel:WORD_1
	v_or_b32_sdwa v76, v76, v79 dst_sel:DWORD dst_unused:UNUSED_PAD src0_sel:DWORD src1_sel:WORD_1
	s_waitcnt lgkmcnt(0)
	v_mov_b32_e32 v78, v80
	v_mov_b32_e32 v79, v82
	v_pk_mul_f32 v[78:79], v[88:89], v[78:79]
	v_mov_b32_e32 v82, v81
	v_pk_mul_f32 v[80:81], v[90:91], v[82:83]
	v_and_b32_sdwa v82, v79, v155 dst_sel:DWORD dst_unused:UNUSED_PAD src0_sel:WORD_1 src1_sel:DWORD
	v_and_b32_sdwa v83, v78, v155 dst_sel:DWORD dst_unused:UNUSED_PAD src0_sel:WORD_1 src1_sel:DWORD
	v_add3_u32 v78, v78, v83, s66
	v_add3_u32 v79, v79, v82, s66
	v_and_b32_sdwa v82, v81, v155 dst_sel:DWORD dst_unused:UNUSED_PAD src0_sel:WORD_1 src1_sel:DWORD
	v_and_b32_sdwa v83, v80, v155 dst_sel:DWORD dst_unused:UNUSED_PAD src0_sel:WORD_1 src1_sel:DWORD
	v_add3_u32 v81, v81, v82, s66
	v_add3_u32 v80, v80, v83, s66
	v_and_b32_e32 v81, 0xffff0000, v81
	v_and_b32_e32 v80, 0xffff0000, v80
	v_or_b32_sdwa v79, v81, v79 dst_sel:DWORD dst_unused:UNUSED_PAD src0_sel:DWORD src1_sel:WORD_1
	v_or_b32_sdwa v78, v80, v78 dst_sel:DWORD dst_unused:UNUSED_PAD src0_sel:DWORD src1_sel:WORD_1
	ds_read_b128 v[80:83], v95
	v_addc_co_u32_e32 v31, vcc, 0, v31, vcc
	global_store_dwordx4 v[30:31], v[76:79], off offset:2048
	ds_read_b128 v[76:79], v95 offset:16
	s_waitcnt lgkmcnt(1)
	v_mov_b32_e32 v30, v80
	v_mov_b32_e32 v31, v82
	v_pk_mul_f32 v[4:5], v[4:5], v[30:31]
	v_mov_b32_e32 v82, v81
	v_pk_mul_f32 v[30:31], v[68:69], v[82:83]
	v_and_b32_sdwa v68, v5, v155 dst_sel:DWORD dst_unused:UNUSED_PAD src0_sel:WORD_1 src1_sel:DWORD
	v_and_b32_sdwa v69, v4, v155 dst_sel:DWORD dst_unused:UNUSED_PAD src0_sel:WORD_1 src1_sel:DWORD
	v_add3_u32 v4, v4, v69, s66
	v_add3_u32 v5, v5, v68, s66
	v_and_b32_sdwa v68, v31, v155 dst_sel:DWORD dst_unused:UNUSED_PAD src0_sel:WORD_1 src1_sel:DWORD
	v_and_b32_sdwa v69, v30, v155 dst_sel:DWORD dst_unused:UNUSED_PAD src0_sel:WORD_1 src1_sel:DWORD
	v_add3_u32 v31, v31, v68, s66
	v_add3_u32 v30, v30, v69, s66
	v_and_b32_e32 v31, 0xffff0000, v31
	v_and_b32_e32 v30, 0xffff0000, v30
	v_or_b32_sdwa v5, v31, v5 dst_sel:DWORD dst_unused:UNUSED_PAD src0_sel:DWORD src1_sel:WORD_1
	v_or_b32_sdwa v4, v30, v4 dst_sel:DWORD dst_unused:UNUSED_PAD src0_sel:DWORD src1_sel:WORD_1
	s_waitcnt lgkmcnt(0)
; __device__ __forceinline__ unsigned pack2(float a, float b) { return (unsigned)f2bf(a) | ((unsigned)f2bf(b) << 16); }
; __device__ __forceinline__ float bflo(unsigned w) { return __uint_as_float(w << 16); }
; __device__ __forceinline__ float bfhi(unsigned w) { return __uint_as_float(w & 0xffff0000u); }
; __device__ __forceinline__ float silu_f(float g) { return g / (1.f + __expf(-g)); }
; template <int DH, int MODE>
; __device__ void attn_item(const Params& p, int layer, int b, int blk, int head, char* smem) {
;     ...
;     for (int i = 0; i < NCH; ++i) {
;       int q = tid + 256 * i, r = q / CPR, c = (q % CPR) * 8;
;       float4 m0 = *reinterpret_cast<const float4*>(Of + r * OST + c);
;       float4 m1 = *reinterpret_cast<const float4*>(Of + r * OST + c + 4);
;       float mm[8] = {m0.x, m0.y, m0.z, m0.w, m1.x, m1.y, m1.z, m1.w};
;       unsigned gw[4] = {gt[i].x, gt[i].y, gt[i].z, gt[i].w};
;       unsigned ow[4];
; #pragma unroll
;       for (int e = 0; e < 4; ++e)
;         ow[e] = pack2(mm[2 * e] * silu_f(bflo(gw[e])), mm[2 * e + 1] * silu_f(bfhi(gw[e])));
;       *reinterpret_cast<uint4*>(Y + (tq0 + r) * YW + ycol + c) = make_uint4(ow[0], ow[1], ow[2], ow[3]);
	v_mov_b32_e32 v30, v76
	v_mov_b32_e32 v31, v78
	v_pk_mul_f32 v[6:7], v[6:7], v[30:31]
	v_mov_b32_e32 v78, v77
	v_pk_mul_f32 v[30:31], v[70:71], v[78:79]
	v_and_b32_sdwa v68, v7, v155 dst_sel:DWORD dst_unused:UNUSED_PAD src0_sel:WORD_1 src1_sel:DWORD
	v_and_b32_sdwa v69, v6, v155 dst_sel:DWORD dst_unused:UNUSED_PAD src0_sel:WORD_1 src1_sel:DWORD
	v_add3_u32 v6, v6, v69, s66
	v_add3_u32 v7, v7, v68, s66
	v_and_b32_sdwa v68, v31, v155 dst_sel:DWORD dst_unused:UNUSED_PAD src0_sel:WORD_1 src1_sel:DWORD
	v_and_b32_sdwa v69, v30, v155 dst_sel:DWORD dst_unused:UNUSED_PAD src0_sel:WORD_1 src1_sel:DWORD
	v_add3_u32 v31, v31, v68, s66
	v_add3_u32 v30, v30, v69, s66
	ds_read_b128 v[68:71], v93
	v_and_b32_e32 v31, 0xffff0000, v31
	v_and_b32_e32 v30, 0xffff0000, v30
	v_add_co_u32_e32 v26, vcc, s74, v26
	v_or_b32_sdwa v7, v31, v7 dst_sel:DWORD dst_unused:UNUSED_PAD src0_sel:DWORD src1_sel:WORD_1
	v_or_b32_sdwa v6, v30, v6 dst_sel:DWORD dst_unused:UNUSED_PAD src0_sel:DWORD src1_sel:WORD_1
	v_addc_co_u32_e32 v27, vcc, 0, v27, vcc
	global_store_dwordx4 v[26:27], v[4:7], off offset:2048
	s_waitcnt lgkmcnt(0)
	v_mov_b32_e32 v26, v68
	v_mov_b32_e32 v27, v70
	ds_read_b128 v[4:7], v93 offset:16
	v_pk_mul_f32 v[0:1], v[0:1], v[26:27]
	v_mov_b32_e32 v70, v69
	v_pk_mul_f32 v[26:27], v[64:65], v[70:71]
	v_and_b32_sdwa v30, v1, v155 dst_sel:DWORD dst_unused:UNUSED_PAD src0_sel:WORD_1 src1_sel:DWORD
	v_and_b32_sdwa v31, v0, v155 dst_sel:DWORD dst_unused:UNUSED_PAD src0_sel:WORD_1 src1_sel:DWORD
	v_add3_u32 v0, v0, v31, s66
	v_add3_u32 v1, v1, v30, s66
	v_and_b32_sdwa v30, v27, v155 dst_sel:DWORD dst_unused:UNUSED_PAD src0_sel:WORD_1 src1_sel:DWORD
	v_and_b32_sdwa v31, v26, v155 dst_sel:DWORD dst_unused:UNUSED_PAD src0_sel:WORD_1 src1_sel:DWORD
	v_add3_u32 v27, v27, v30, s66
	v_add3_u32 v26, v26, v31, s66
	v_and_b32_e32 v27, 0xffff0000, v27
	v_and_b32_e32 v26, 0xffff0000, v26
	v_or_b32_sdwa v1, v27, v1 dst_sel:DWORD dst_unused:UNUSED_PAD src0_sel:DWORD src1_sel:WORD_1
	v_or_b32_sdwa v0, v26, v0 dst_sel:DWORD dst_unused:UNUSED_PAD src0_sel:DWORD src1_sel:WORD_1
	s_waitcnt lgkmcnt(0)
	v_mov_b32_e32 v26, v4
	v_mov_b32_e32 v27, v6
	v_pk_mul_f32 v[2:3], v[2:3], v[26:27]
	v_mov_b32_e32 v6, v5
	v_pk_mul_f32 v[4:5], v[66:67], v[6:7]
	v_and_b32_sdwa v6, v3, v155 dst_sel:DWORD dst_unused:UNUSED_PAD src0_sel:WORD_1 src1_sel:DWORD
	v_and_b32_sdwa v7, v2, v155 dst_sel:DWORD dst_unused:UNUSED_PAD src0_sel:WORD_1 src1_sel:DWORD
	v_add3_u32 v2, v2, v7, s66
	v_add3_u32 v3, v3, v6, s66
	v_and_b32_sdwa v6, v5, v155 dst_sel:DWORD dst_unused:UNUSED_PAD src0_sel:WORD_1 src1_sel:DWORD
	v_and_b32_sdwa v7, v4, v155 dst_sel:DWORD dst_unused:UNUSED_PAD src0_sel:WORD_1 src1_sel:DWORD
	v_add3_u32 v5, v5, v6, s66
	v_add3_u32 v4, v4, v7, s66
	v_and_b32_e32 v5, 0xffff0000, v5
	v_and_b32_e32 v4, 0xffff0000, v4
	v_or_b32_sdwa v3, v5, v3 dst_sel:DWORD dst_unused:UNUSED_PAD src0_sel:DWORD src1_sel:WORD_1
	v_or_b32_sdwa v2, v4, v2 dst_sel:DWORD dst_unused:UNUSED_PAD src0_sel:DWORD src1_sel:WORD_1
	ds_read_b128 v[4:7], v92
	v_add_co_u32_e32 v20, vcc, s74, v20
	s_nop 1
	v_addc_co_u32_e32 v21, vcc, 0, v21, vcc
	global_store_dwordx4 v[20:21], v[0:3], off offset:2048
	s_waitcnt lgkmcnt(0)
	v_mov_b32_e32 v20, v4
	v_mov_b32_e32 v21, v6
	ds_read_b128 v[0:3], v92 offset:16
	v_pk_mul_f32 v[20:21], v[56:57], v[20:21]
	v_mov_b32_e32 v6, v5
	v_pk_mul_f32 v[4:5], v[58:59], v[6:7]
	v_and_b32_sdwa v6, v21, v155 dst_sel:DWORD dst_unused:UNUSED_PAD src0_sel:WORD_1 src1_sel:DWORD
	v_and_b32_sdwa v7, v20, v155 dst_sel:DWORD dst_unused:UNUSED_PAD src0_sel:WORD_1 src1_sel:DWORD
	v_add3_u32 v7, v20, v7, s66
	v_add3_u32 v6, v21, v6, s66
	v_and_b32_sdwa v20, v5, v155 dst_sel:DWORD dst_unused:UNUSED_PAD src0_sel:WORD_1 src1_sel:DWORD
	v_and_b32_sdwa v21, v4, v155 dst_sel:DWORD dst_unused:UNUSED_PAD src0_sel:WORD_1 src1_sel:DWORD
	v_add3_u32 v5, v5, v20, s66
	v_add3_u32 v4, v4, v21, s66
	v_and_b32_e32 v5, 0xffff0000, v5
	v_and_b32_e32 v4, 0xffff0000, v4
	v_or_b32_sdwa v5, v5, v6 dst_sel:DWORD dst_unused:UNUSED_PAD src0_sel:DWORD src1_sel:WORD_1
	v_or_b32_sdwa v4, v4, v7 dst_sel:DWORD dst_unused:UNUSED_PAD src0_sel:DWORD src1_sel:WORD_1
	s_waitcnt lgkmcnt(0)
	v_mov_b32_e32 v6, v0
	v_mov_b32_e32 v7, v2
	v_pk_mul_f32 v[6:7], v[60:61], v[6:7]
	v_mov_b32_e32 v2, v1
	v_pk_mul_f32 v[0:1], v[62:63], v[2:3]
	v_and_b32_sdwa v2, v7, v155 dst_sel:DWORD dst_unused:UNUSED_PAD src0_sel:WORD_1 src1_sel:DWORD
	v_and_b32_sdwa v3, v6, v155 dst_sel:DWORD dst_unused:UNUSED_PAD src0_sel:WORD_1 src1_sel:DWORD
	v_add3_u32 v3, v6, v3, s66
	v_add3_u32 v2, v7, v2, s66
	v_and_b32_sdwa v6, v1, v155 dst_sel:DWORD dst_unused:UNUSED_PAD src0_sel:WORD_1 src1_sel:DWORD
	v_and_b32_sdwa v7, v0, v155 dst_sel:DWORD dst_unused:UNUSED_PAD src0_sel:WORD_1 src1_sel:DWORD
	v_add3_u32 v1, v1, v6, s66
	v_add3_u32 v0, v0, v7, s66
	v_and_b32_e32 v1, 0xffff0000, v1
	v_and_b32_e32 v0, 0xffff0000, v0
	v_or_b32_sdwa v7, v1, v2 dst_sel:DWORD dst_unused:UNUSED_PAD src0_sel:DWORD src1_sel:WORD_1
	v_or_b32_sdwa v6, v0, v3 dst_sel:DWORD dst_unused:UNUSED_PAD src0_sel:DWORD src1_sel:WORD_1
	ds_read_b128 v[0:3], v75
	v_add_co_u32_e32 v16, vcc, s74, v16
	s_nop 1
	v_addc_co_u32_e32 v17, vcc, 0, v17, vcc
	global_store_dwordx4 v[16:17], v[4:7], off offset:2048
	s_waitcnt lgkmcnt(0)
; __device__ __forceinline__ unsigned pack2(float a, float b) { return (unsigned)f2bf(a) | ((unsigned)f2bf(b) << 16); }
; __device__ __forceinline__ float bflo(unsigned w) { return __uint_as_float(w << 16); }
; __device__ __forceinline__ float bfhi(unsigned w) { return __uint_as_float(w & 0xffff0000u); }
; __device__ __forceinline__ float silu_f(float g) { return g / (1.f + __expf(-g)); }
; template <int DH, int MODE>
; __device__ void attn_item(const Params& p, int layer, int b, int blk, int head, char* smem) {
;     ...
;     for (int i = 0; i < NCH; ++i) {
;       int q = tid + 256 * i, r = q / CPR, c = (q % CPR) * 8;
;       float4 m0 = *reinterpret_cast<const float4*>(Of + r * OST + c);
;       float4 m1 = *reinterpret_cast<const float4*>(Of + r * OST + c + 4);
;       float mm[8] = {m0.x, m0.y, m0.z, m0.w, m1.x, m1.y, m1.z, m1.w};
;       unsigned gw[4] = {gt[i].x, gt[i].y, gt[i].z, gt[i].w};
;       unsigned ow[4];
; #pragma unroll
;       for (int e = 0; e < 4; ++e)
;         ow[e] = pack2(mm[2 * e] * silu_f(bflo(gw[e])), mm[2 * e + 1] * silu_f(bfhi(gw[e])));
;       *reinterpret_cast<uint4*>(Y + (tq0 + r) * YW + ycol + c) = make_uint4(ow[0], ow[1], ow[2], ow[3]);
	v_mov_b32_e32 v16, v0
	v_mov_b32_e32 v17, v2
	ds_read_b128 v[4:7], v75 offset:16
	v_pk_mul_f32 v[16:17], v[48:49], v[16:17]
	v_mov_b32_e32 v2, v1
	v_pk_mul_f32 v[0:1], v[50:51], v[2:3]
	v_and_b32_sdwa v2, v17, v155 dst_sel:DWORD dst_unused:UNUSED_PAD src0_sel:WORD_1 src1_sel:DWORD
	v_and_b32_sdwa v3, v16, v155 dst_sel:DWORD dst_unused:UNUSED_PAD src0_sel:WORD_1 src1_sel:DWORD
	v_add3_u32 v3, v16, v3, s66
	v_add3_u32 v2, v17, v2, s66
	v_and_b32_sdwa v16, v1, v155 dst_sel:DWORD dst_unused:UNUSED_PAD src0_sel:WORD_1 src1_sel:DWORD
	v_and_b32_sdwa v17, v0, v155 dst_sel:DWORD dst_unused:UNUSED_PAD src0_sel:WORD_1 src1_sel:DWORD
	v_add3_u32 v1, v1, v16, s66
	v_add3_u32 v0, v0, v17, s66
	v_and_b32_e32 v1, 0xffff0000, v1
	v_and_b32_e32 v0, 0xffff0000, v0
	v_or_b32_sdwa v1, v1, v2 dst_sel:DWORD dst_unused:UNUSED_PAD src0_sel:DWORD src1_sel:WORD_1
	v_or_b32_sdwa v0, v0, v3 dst_sel:DWORD dst_unused:UNUSED_PAD src0_sel:DWORD src1_sel:WORD_1
	s_waitcnt lgkmcnt(0)
	v_mov_b32_e32 v2, v4
	v_mov_b32_e32 v3, v6
	v_pk_mul_f32 v[2:3], v[52:53], v[2:3]
	v_mov_b32_e32 v6, v5
	v_pk_mul_f32 v[4:5], v[54:55], v[6:7]
	v_and_b32_sdwa v6, v3, v155 dst_sel:DWORD dst_unused:UNUSED_PAD src0_sel:WORD_1 src1_sel:DWORD
	v_and_b32_sdwa v7, v2, v155 dst_sel:DWORD dst_unused:UNUSED_PAD src0_sel:WORD_1 src1_sel:DWORD
	v_add3_u32 v2, v2, v7, s66
	v_add3_u32 v3, v3, v6, s66
	v_and_b32_sdwa v6, v5, v155 dst_sel:DWORD dst_unused:UNUSED_PAD src0_sel:WORD_1 src1_sel:DWORD
	v_and_b32_sdwa v7, v4, v155 dst_sel:DWORD dst_unused:UNUSED_PAD src0_sel:WORD_1 src1_sel:DWORD
	v_add3_u32 v5, v5, v6, s66
	v_add3_u32 v4, v4, v7, s66
	v_and_b32_e32 v5, 0xffff0000, v5
	v_and_b32_e32 v4, 0xffff0000, v4
	v_or_b32_sdwa v3, v5, v3 dst_sel:DWORD dst_unused:UNUSED_PAD src0_sel:DWORD src1_sel:WORD_1
	v_or_b32_sdwa v2, v4, v2 dst_sel:DWORD dst_unused:UNUSED_PAD src0_sel:DWORD src1_sel:WORD_1
	ds_read_b128 v[4:7], v74
	v_add_co_u32_e32 v12, vcc, s74, v12
	s_nop 1
	v_addc_co_u32_e32 v13, vcc, 0, v13, vcc
	global_store_dwordx4 v[12:13], v[0:3], off offset:2048
	s_waitcnt lgkmcnt(0)
	v_mov_b32_e32 v12, v4
	v_mov_b32_e32 v13, v6
	ds_read_b128 v[0:3], v74 offset:16
	v_pk_mul_f32 v[12:13], v[40:41], v[12:13]
	v_mov_b32_e32 v6, v5
	v_pk_mul_f32 v[4:5], v[42:43], v[6:7]
	v_and_b32_sdwa v6, v13, v155 dst_sel:DWORD dst_unused:UNUSED_PAD src0_sel:WORD_1 src1_sel:DWORD
	v_and_b32_sdwa v7, v12, v155 dst_sel:DWORD dst_unused:UNUSED_PAD src0_sel:WORD_1 src1_sel:DWORD
	v_add3_u32 v7, v12, v7, s66
	v_add3_u32 v6, v13, v6, s66
	v_and_b32_sdwa v12, v5, v155 dst_sel:DWORD dst_unused:UNUSED_PAD src0_sel:WORD_1 src1_sel:DWORD
	v_and_b32_sdwa v13, v4, v155 dst_sel:DWORD dst_unused:UNUSED_PAD src0_sel:WORD_1 src1_sel:DWORD
	v_add3_u32 v5, v5, v12, s66
	v_add3_u32 v4, v4, v13, s66
	v_and_b32_e32 v5, 0xffff0000, v5
	v_and_b32_e32 v4, 0xffff0000, v4
	v_or_b32_sdwa v5, v5, v6 dst_sel:DWORD dst_unused:UNUSED_PAD src0_sel:DWORD src1_sel:WORD_1
	v_or_b32_sdwa v4, v4, v7 dst_sel:DWORD dst_unused:UNUSED_PAD src0_sel:DWORD src1_sel:WORD_1
	s_waitcnt lgkmcnt(0)
	v_mov_b32_e32 v6, v0
	v_mov_b32_e32 v7, v2
	v_pk_mul_f32 v[6:7], v[44:45], v[6:7]
	v_mov_b32_e32 v2, v1
	v_pk_mul_f32 v[0:1], v[46:47], v[2:3]
	v_and_b32_sdwa v2, v7, v155 dst_sel:DWORD dst_unused:UNUSED_PAD src0_sel:WORD_1 src1_sel:DWORD
	v_and_b32_sdwa v3, v6, v155 dst_sel:DWORD dst_unused:UNUSED_PAD src0_sel:WORD_1 src1_sel:DWORD
	v_add3_u32 v3, v6, v3, s66
	v_add3_u32 v2, v7, v2, s66
	v_and_b32_sdwa v6, v1, v155 dst_sel:DWORD dst_unused:UNUSED_PAD src0_sel:WORD_1 src1_sel:DWORD
	v_and_b32_sdwa v7, v0, v155 dst_sel:DWORD dst_unused:UNUSED_PAD src0_sel:WORD_1 src1_sel:DWORD
	v_add3_u32 v1, v1, v6, s66
	v_add3_u32 v0, v0, v7, s66
	v_and_b32_e32 v1, 0xffff0000, v1
	v_and_b32_e32 v0, 0xffff0000, v0
	v_or_b32_sdwa v7, v1, v2 dst_sel:DWORD dst_unused:UNUSED_PAD src0_sel:DWORD src1_sel:WORD_1
	v_or_b32_sdwa v6, v0, v3 dst_sel:DWORD dst_unused:UNUSED_PAD src0_sel:DWORD src1_sel:WORD_1
	ds_read_b128 v[0:3], v73
	v_add_co_u32_e32 v10, vcc, s74, v10
	s_nop 1
	v_addc_co_u32_e32 v11, vcc, 0, v11, vcc
	global_store_dwordx4 v[10:11], v[4:7], off offset:2048
	s_waitcnt lgkmcnt(0)
; __device__ __forceinline__ unsigned pack2(float a, float b) { return (unsigned)f2bf(a) | ((unsigned)f2bf(b) << 16); }
; __device__ __forceinline__ float bflo(unsigned w) { return __uint_as_float(w << 16); }
; __device__ __forceinline__ float bfhi(unsigned w) { return __uint_as_float(w & 0xffff0000u); }
; __device__ __forceinline__ float silu_f(float g) { return g / (1.f + __expf(-g)); }
; template <int DH, int MODE>
; __device__ void attn_item(const Params& p, int layer, int b, int blk, int head, char* smem) {
;     ...
;     for (int i = 0; i < NCH; ++i) {
;       int q = tid + 256 * i, r = q / CPR, c = (q % CPR) * 8;
;       float4 m0 = *reinterpret_cast<const float4*>(Of + r * OST + c);
;       float4 m1 = *reinterpret_cast<const float4*>(Of + r * OST + c + 4);
;       float mm[8] = {m0.x, m0.y, m0.z, m0.w, m1.x, m1.y, m1.z, m1.w};
;       unsigned gw[4] = {gt[i].x, gt[i].y, gt[i].z, gt[i].w};
;       unsigned ow[4];
; #pragma unroll
;       for (int e = 0; e < 4; ++e)
;         ow[e] = pack2(mm[2 * e] * silu_f(bflo(gw[e])), mm[2 * e + 1] * silu_f(bfhi(gw[e])));
;       *reinterpret_cast<uint4*>(Y + (tq0 + r) * YW + ycol + c) = make_uint4(ow[0], ow[1], ow[2], ow[3]);
;     }
;   }
;   __syncthreads();
	v_mov_b32_e32 v10, v0
	v_mov_b32_e32 v11, v2
	ds_read_b128 v[4:7], v73 offset:16
	v_pk_mul_f32 v[10:11], v[32:33], v[10:11]
	v_mov_b32_e32 v2, v1
	v_pk_mul_f32 v[0:1], v[34:35], v[2:3]
	v_and_b32_sdwa v2, v11, v155 dst_sel:DWORD dst_unused:UNUSED_PAD src0_sel:WORD_1 src1_sel:DWORD
	v_and_b32_sdwa v3, v10, v155 dst_sel:DWORD dst_unused:UNUSED_PAD src0_sel:WORD_1 src1_sel:DWORD
	v_add3_u32 v3, v10, v3, s66
	v_add3_u32 v2, v11, v2, s66
	v_and_b32_sdwa v10, v1, v155 dst_sel:DWORD dst_unused:UNUSED_PAD src0_sel:WORD_1 src1_sel:DWORD
	v_and_b32_sdwa v11, v0, v155 dst_sel:DWORD dst_unused:UNUSED_PAD src0_sel:WORD_1 src1_sel:DWORD
	v_add3_u32 v1, v1, v10, s66
	v_add3_u32 v0, v0, v11, s66
	v_and_b32_e32 v1, 0xffff0000, v1
	v_and_b32_e32 v0, 0xffff0000, v0
	v_or_b32_sdwa v1, v1, v2 dst_sel:DWORD dst_unused:UNUSED_PAD src0_sel:DWORD src1_sel:WORD_1
	v_or_b32_sdwa v0, v0, v3 dst_sel:DWORD dst_unused:UNUSED_PAD src0_sel:DWORD src1_sel:WORD_1
	s_waitcnt lgkmcnt(0)
	v_mov_b32_e32 v2, v4
	v_mov_b32_e32 v3, v6
	v_pk_mul_f32 v[2:3], v[36:37], v[2:3]
	v_mov_b32_e32 v6, v5
	v_pk_mul_f32 v[4:5], v[38:39], v[6:7]
	v_and_b32_sdwa v6, v3, v155 dst_sel:DWORD dst_unused:UNUSED_PAD src0_sel:WORD_1 src1_sel:DWORD
	v_and_b32_sdwa v7, v2, v155 dst_sel:DWORD dst_unused:UNUSED_PAD src0_sel:WORD_1 src1_sel:DWORD
	v_add3_u32 v2, v2, v7, s66
	v_add3_u32 v3, v3, v6, s66
	v_and_b32_sdwa v6, v5, v155 dst_sel:DWORD dst_unused:UNUSED_PAD src0_sel:WORD_1 src1_sel:DWORD
	v_and_b32_sdwa v7, v4, v155 dst_sel:DWORD dst_unused:UNUSED_PAD src0_sel:WORD_1 src1_sel:DWORD
	v_add3_u32 v5, v5, v6, s66
	v_add3_u32 v4, v4, v7, s66
	v_and_b32_e32 v5, 0xffff0000, v5
	v_and_b32_e32 v4, 0xffff0000, v4
	v_or_b32_sdwa v3, v5, v3 dst_sel:DWORD dst_unused:UNUSED_PAD src0_sel:DWORD src1_sel:WORD_1
	v_or_b32_sdwa v2, v4, v2 dst_sel:DWORD dst_unused:UNUSED_PAD src0_sel:DWORD src1_sel:WORD_1
	ds_read_b128 v[4:7], v72
	v_add_co_u32_e32 v8, vcc, s74, v8
	s_nop 1
	v_addc_co_u32_e32 v9, vcc, 0, v9, vcc
	global_store_dwordx4 v[8:9], v[0:3], off offset:2048
	s_waitcnt lgkmcnt(0)
	v_mov_b32_e32 v8, v4
	v_mov_b32_e32 v9, v6
	ds_read_b128 v[0:3], v72 offset:16
	v_pk_mul_f32 v[8:9], v[18:19], v[8:9]
	v_mov_b32_e32 v6, v5
	v_pk_mul_f32 v[4:5], v[22:23], v[6:7]
	v_and_b32_sdwa v6, v9, v155 dst_sel:DWORD dst_unused:UNUSED_PAD src0_sel:WORD_1 src1_sel:DWORD
	v_and_b32_sdwa v7, v8, v155 dst_sel:DWORD dst_unused:UNUSED_PAD src0_sel:WORD_1 src1_sel:DWORD
	v_add3_u32 v7, v8, v7, s66
	v_add3_u32 v6, v9, v6, s66
	v_and_b32_sdwa v8, v5, v155 dst_sel:DWORD dst_unused:UNUSED_PAD src0_sel:WORD_1 src1_sel:DWORD
	v_and_b32_sdwa v9, v4, v155 dst_sel:DWORD dst_unused:UNUSED_PAD src0_sel:WORD_1 src1_sel:DWORD
	v_add3_u32 v5, v5, v8, s66
	v_add3_u32 v4, v4, v9, s66
	v_and_b32_e32 v5, 0xffff0000, v5
	v_and_b32_e32 v4, 0xffff0000, v4
	v_or_b32_sdwa v5, v5, v6 dst_sel:DWORD dst_unused:UNUSED_PAD src0_sel:DWORD src1_sel:WORD_1
	v_or_b32_sdwa v4, v4, v7 dst_sel:DWORD dst_unused:UNUSED_PAD src0_sel:DWORD src1_sel:WORD_1
	s_waitcnt lgkmcnt(0)
	v_mov_b32_e32 v6, v0
	v_mov_b32_e32 v7, v2
	v_pk_mul_f32 v[6:7], v[24:25], v[6:7]
	v_mov_b32_e32 v2, v1
	v_pk_mul_f32 v[0:1], v[28:29], v[2:3]
	v_and_b32_sdwa v2, v7, v155 dst_sel:DWORD dst_unused:UNUSED_PAD src0_sel:WORD_1 src1_sel:DWORD
	v_and_b32_sdwa v3, v6, v155 dst_sel:DWORD dst_unused:UNUSED_PAD src0_sel:WORD_1 src1_sel:DWORD
	v_add3_u32 v2, v7, v2, s66
	v_and_b32_sdwa v7, v0, v155 dst_sel:DWORD dst_unused:UNUSED_PAD src0_sel:WORD_1 src1_sel:DWORD
	v_add3_u32 v3, v6, v3, s66
	v_and_b32_sdwa v6, v1, v155 dst_sel:DWORD dst_unused:UNUSED_PAD src0_sel:WORD_1 src1_sel:DWORD
	v_add3_u32 v0, v0, v7, s66
	v_add3_u32 v1, v1, v6, s66
	v_and_b32_e32 v0, 0xffff0000, v0
	v_and_b32_e32 v1, 0xffff0000, v1
	v_or_b32_sdwa v6, v0, v3 dst_sel:DWORD dst_unused:UNUSED_PAD src0_sel:DWORD src1_sel:WORD_1
	v_add_co_u32_e32 v0, vcc, 0x184a1000, v14
	v_or_b32_sdwa v7, v1, v2 dst_sel:DWORD dst_unused:UNUSED_PAD src0_sel:DWORD src1_sel:WORD_1
	s_nop 0
	v_addc_co_u32_e32 v1, vcc, 0, v15, vcc
	global_store_dwordx4 v[0:1], v[4:7], off offset:2048
	s_barrier

; #define MFMA16(a, b, c) __builtin_amdgcn_mfma_f32_16x16x32_bf16(a, b, c, 0, 0, 0)
; __device__ void gmlp_item(const Params& p, int layer, int b, int n, int g, char* smem) {
;     ...
; #pragma unroll 2
;   for (int i = 0; i < 8; ++i) {
;     int q = tid + 256 * i;
;     int t = q >> 4, cch = q & 15;
;     uint4 v = *reinterpret_cast<const uint4*>(Ws + (size_t)g * 16384 + t * 128 + cch * 8);
;     *reinterpret_cast<uint4*>(smem + (cch >> 2) * 8192 + t * 64 + (cch & 3) * 16) = v;
;   }
;   __syncthreads();
;   f32x4 acc[4][4];
; #pragma unroll
;   for (int m = 0; m < 4; ++m)
; #pragma unroll
;     for (int nn = 0; nn < 4; ++nn) acc[m][nn] = f32x4{0.f, 0.f, 0.f, 0.f};
; #pragma unroll
;   for (int ks = 0; ks < 4; ++ks) {
;     bf16x8 a[4], bb[4];
; #pragma unroll
;     for (int m = 0; m < 4; ++m)
;       a[m] = *reinterpret_cast<const bf16x8*>(smem + ks * 8192 + (wr * 64 + m * 16 + fr) * 64 + fq * 16);
; #pragma unroll
;     for (int nn = 0; nn < 4; ++nn)
;       bb[nn] = *reinterpret_cast<const bf16x8*>(smem + 32768 + ks * 8192 + (wc * 64 + nn * 16 + fr) * 64 + fq * 16);
; #pragma unroll
;     for (int m = 0; m < 4; ++m)
; #pragma unroll
;       for (int nn = 0; nn < 4; ++nn) acc[m][nn] = MFMA16(a[m], bb[nn], acc[m][nn]);
.LBB0_159:
	v_add_u32_e32 v3, s6, v60
	v_ashrrev_i32_e32 v12, 4, v3
	v_add_u32_e32 v3, 0x100, v3
	v_ashrrev_i32_e32 v3, 4, v3
	v_lshlrev_b32_e32 v4, 7, v12
	v_lshlrev_b32_e32 v6, 7, v3
	v_ashrrev_i32_e32 v5, 31, v4
	v_ashrrev_i32_e32 v7, 31, v6
	v_lshl_add_u64 v[4:5], v[4:5], 1, v[0:1]
	v_lshl_add_u64 v[8:9], v[6:7], 1, v[0:1]
	global_load_dwordx4 v[4:7], v[4:5], off
	s_nop 0
	global_load_dwordx4 v[8:11], v[8:9], off
	s_addk_i32 s6, 0x200
	s_cmpk_lg_i32 s6, 0x800
	v_lshl_add_u32 v12, v12, 6, v2
	v_lshl_add_u32 v3, v3, 6, v2
	s_waitcnt vmcnt(1)
	ds_write_b128 v12, v[4:7]
	s_waitcnt vmcnt(0)
	ds_write_b128 v3, v[8:11]
	s_cbranch_scc1 .LBB0_159
	v_bfe_u32 v32, v60, 4, 2
	v_ashrrev_i32_e32 v33, 7, v60
	v_lshlrev_b32_e32 v4, 4, v32
	v_lshlrev_b32_e32 v0, 12, v33
	v_lshlrev_b32_e32 v5, 6, v35
	v_or3_b32 v37, v4, v0, v5
	s_waitcnt lgkmcnt(0)
	s_barrier
	ds_read_b128 v[0:3], v37
	v_bfe_u32 v39, v60, 6, 1
	v_lshlrev_b32_e32 v6, 12, v39
	v_or3_b32 v41, v4, v6, v5
	ds_read_b128 v[4:7], v41 offset:32768
	ds_read_b128 v[8:11], v37 offset:1024
	ds_read_b128 v[12:15], v41 offset:33792
	ds_read_b128 v[24:27], v41 offset:34816
	ds_read_b128 v[28:31], v41 offset:35840
	s_waitcnt lgkmcnt(4)
	v_mfma_f32_16x16x32_bf16 v[16:19], v[0:3], v[4:7], 0
	s_ashr_i32 s7, s9, 31
	s_add_u32 s6, s28, s9
	s_addc_u32 s7, s29, s7
	s_waitcnt lgkmcnt(2)
	v_mfma_f32_16x16x32_bf16 v[20:23], v[0:3], v[12:15], 0
	v_lshlrev_b32_e32 v33, 6, v33
	s_lshl_b32 s9, s8, 2
	v_lshl_or_b32 v32, v32, 2, v33
	s_waitcnt lgkmcnt(1)
	v_mfma_f32_16x16x32_bf16 v[50:53], v[0:3], v[24:27], 0
	s_add_u32 s10, s12, s9
	s_addc_u32 s11, s13, 0
	v_ashrrev_i32_e32 v33, 31, v32
	s_waitcnt lgkmcnt(0)
	v_mfma_f32_16x16x32_bf16 v[54:57], v[0:3], v[28:31], 0
	ds_read_b128 v[0:3], v37 offset:2048
	ds_read_b128 v[74:77], v37 offset:3072
	ds_read_b128 v[98:101], v37 offset:8192
	v_lshl_add_u64 v[58:59], v[32:33], 2, s[10:11]
	v_mfma_f32_16x16x32_bf16 v[62:65], v[8:11], v[4:7], 0
	v_lshlrev_b32_e32 v33, 2, v35
	v_lshl_or_b32 v126, v39, 8, v33
	v_mad_u64_u32 v[32:33], s[10:11], v32, s67, v[126:127]
	v_mfma_f32_16x16x32_bf16 v[66:69], v[8:11], v[12:15], 0
	v_add_u32_e32 v33, 0x400, v32
	v_ashrrev_i32_e32 v49, 31, v48
	v_ashrrev_i32_e32 v47, 31, v46
	v_mfma_f32_16x16x32_bf16 v[70:73], v[8:11], v[24:27], 0
	v_ashrrev_i32_e32 v45, 31, v44
	v_ashrrev_i32_e32 v43, 31, v42
	v_ashrrev_i32_e32 v39, 31, v38
	v_mfma_f32_16x16x32_bf16 v[8:11], v[8:11], v[28:31], 0
	s_waitcnt lgkmcnt(2)
	v_mfma_f32_16x16x32_bf16 v[78:81], v[0:3], v[4:7], 0
	v_mfma_f32_16x16x32_bf16 v[82:85], v[0:3], v[12:15], 0
	v_mfma_f32_16x16x32_bf16 v[86:89], v[0:3], v[24:27], 0
	v_mfma_f32_16x16x32_bf16 v[90:93], v[0:3], v[28:31], 0
	s_waitcnt lgkmcnt(1)
	v_mfma_f32_16x16x32_bf16 v[94:97], v[74:77], v[4:7], 0
	v_mfma_f32_16x16x32_bf16 v[12:15], v[74:77], v[12:15], 0
	v_mfma_f32_16x16x32_bf16 v[24:27], v[74:77], v[24:27], 0
	v_mfma_f32_16x16x32_bf16 v[0:3], v[74:77], v[28:31], 0
	ds_read_b128 v[28:31], v41 offset:40960
	ds_read_b128 v[74:77], v37 offset:9216
	ds_read_b128 v[102:105], v41 offset:41984
	ds_read_b128 v[106:109], v41 offset:43008
	ds_read_b128 v[4:7], v41 offset:44032
	s_waitcnt lgkmcnt(4)
	v_mfma_f32_16x16x32_bf16 v[16:19], v[98:101], v[28:31], v[16:19]
	s_waitcnt lgkmcnt(2)
	v_mfma_f32_16x16x32_bf16 v[20:23], v[98:101], v[102:105], v[20:23]
	s_waitcnt lgkmcnt(1)
	v_mfma_f32_16x16x32_bf16 v[50:53], v[98:101], v[106:109], v[50:53]
	s_waitcnt lgkmcnt(0)
	v_mfma_f32_16x16x32_bf16 v[54:57], v[98:101], v[4:7], v[54:57]
	ds_read_b128 v[98:101], v37 offset:10240
	v_mfma_f32_16x16x32_bf16 v[62:65], v[74:77], v[28:31], v[62:65]
	v_mfma_f32_16x16x32_bf16 v[66:69], v[74:77], v[102:105], v[66:69]
	v_mfma_f32_16x16x32_bf16 v[70:73], v[74:77], v[106:109], v[70:73]
	v_mfma_f32_16x16x32_bf16 v[8:11], v[74:77], v[4:7], v[8:11]
	ds_read_b128 v[74:77], v37 offset:11264
	ds_read_b128 v[110:113], v37 offset:16384
	ds_read_b128 v[114:117], v37 offset:17408
	ds_read_b128 v[118:121], v37 offset:18432
	ds_read_b128 v[122:125], v37 offset:19456
	ds_read_b128 v[134:137], v41 offset:49152
	ds_read_b128 v[138:141], v41 offset:50176
	ds_read_b128 v[146:149], v41 offset:51200
	ds_read_b128 v[150:153], v41 offset:52224
	ds_read_b128 v[162:165], v37 offset:24576
	ds_read_b128 v[166:169], v37 offset:25600
	s_waitcnt lgkmcnt(11)
	v_mfma_f32_16x16x32_bf16 v[78:81], v[98:101], v[28:31], v[78:81]
	v_mfma_f32_16x16x32_bf16 v[82:85], v[98:101], v[102:105], v[82:85]
	v_mfma_f32_16x16x32_bf16 v[86:89], v[98:101], v[106:109], v[86:89]
	v_mfma_f32_16x16x32_bf16 v[90:93], v[98:101], v[4:7], v[90:93]
	ds_read_b128 v[98:101], v37 offset:26624
	ds_read_b128 v[170:173], v37 offset:27648
	ds_read_b128 v[174:177], v41 offset:57344
	ds_read_b128 v[178:181], v41 offset:58368
	s_waitcnt lgkmcnt(14)
	v_mfma_f32_16x16x32_bf16 v[28:31], v[74:77], v[28:31], v[94:97]
	s_nop 2
	ds_read_b128 v[94:97], v41 offset:59392
	ds_read_b128 v[182:185], v41 offset:60416
	s_waitcnt lgkmcnt(0)
	s_barrier
; #define MFMA16(a, b, c) __builtin_amdgcn_mfma_f32_16x16x32_bf16(a, b, c, 0, 0, 0)
; __device__ void gmlp_item(const Params& p, int layer, int b, int n, int g, char* smem) {
;     ...
; #pragma unroll
;     for (int m = 0; m < 4; ++m)
; #pragma unroll
;       for (int nn = 0; nn < 4; ++nn) acc[m][nn] = MFMA16(a[m], bb[nn], acc[m][nn]);
;   }
;   __syncthreads();
;   {
;     float* Tf = reinterpret_cast<float*>(smem);
; #pragma unroll
;     for (int m = 0; m < 4; ++m)
; #pragma unroll
;       for (int j = 0; j < 4; ++j) {
;         int t = wr * 64 + m * 16 + fq * 4 + j;
;         float bias = p.gm_b_s[(size_t)layer * 512 + g * 128 + t];
; #pragma unroll
;         for (int nn = 0; nn < 4; ++nn) Tf[t * 132 + wc * 64 + nn * 16 + fr] = acc[m][nn][j] + bias;
;       }
	v_mfma_f32_16x16x32_bf16 v[16:19], v[110:113], v[134:137], v[16:19]
	global_load_dwordx4 v[186:189], v[58:59], off offset:64
	global_load_dwordx4 v[190:193], v[58:59], off offset:128
	v_mfma_f32_16x16x32_bf16 v[20:23], v[110:113], v[138:141], v[20:23]
	v_ashrrev_i32_e32 v41, 31, v40
	v_mfma_f32_16x16x32_bf16 v[50:53], v[110:113], v[146:149], v[50:53]
	v_mfma_f32_16x16x32_bf16 v[54:57], v[110:113], v[150:153], v[54:57]
	global_load_dwordx4 v[110:113], v[58:59], off
	v_mfma_f32_16x16x32_bf16 v[16:19], v[162:165], v[174:177], v[16:19]
	v_mfma_f32_16x16x32_bf16 v[20:23], v[162:165], v[178:181], v[20:23]
	v_mfma_f32_16x16x32_bf16 v[50:53], v[162:165], v[94:97], v[50:53]
	s_waitcnt vmcnt(0)
	s_nop 4
	v_add_f32_e32 v16, v16, v110
	v_mfma_f32_16x16x32_bf16 v[54:57], v[162:165], v[182:185], v[54:57]
	v_add_f32_e32 v20, v20, v110
	ds_write2_b32 v32, v16, v20 offset1:16
	v_add_f32_e32 v16, v50, v110
	v_add_f32_e32 v35, v53, v113
	v_mfma_f32_16x16x32_bf16 v[62:65], v[114:117], v[134:137], v[62:65]
	s_nop 2
	v_add_f32_e32 v20, v54, v110
	ds_write2_b32 v32, v16, v20 offset0:32 offset1:48
	v_add_f32_e32 v16, v17, v111
	v_add_f32_e32 v17, v21, v111
	ds_write2_b32 v32, v16, v17 offset0:132 offset1:148
	v_add_f32_e32 v16, v51, v111
	v_add_f32_e32 v17, v55, v111
	ds_write2_b32 v32, v16, v17 offset0:164 offset1:180
	v_add_f32_e32 v16, v18, v112
	v_add_f32_e32 v17, v22, v112
	ds_write2_b32 v33, v16, v17 offset0:8 offset1:24
	v_add_f32_e32 v16, v52, v112
	global_load_dwordx4 v[50:53], v[58:59], off offset:192
	v_mfma_f32_16x16x32_bf16 v[66:69], v[114:117], v[138:141], v[66:69]
	v_add_f32_e32 v17, v56, v112
	v_add_f32_e32 v20, v19, v113
	v_add_f32_e32 v21, v23, v113
	v_mfma_f32_16x16x32_bf16 v[70:73], v[114:117], v[146:149], v[70:73]
	ds_write2_b32 v33, v16, v17 offset0:40 offset1:56
	ds_write2_b32 v33, v20, v21 offset0:140 offset1:156
	v_add_f32_e32 v37, v57, v113
	v_mfma_f32_16x16x32_bf16 v[8:11], v[114:117], v[150:153], v[8:11]
	ds_write2_b32 v33, v35, v37 offset0:172 offset1:188
	v_add_u32_e32 v33, 0x2000, v32
	v_ashrrev_i32_e32 v35, 31, v34
	v_mfma_f32_16x16x32_bf16 v[16:19], v[166:169], v[174:177], v[62:65]
	v_ashrrev_i32_e32 v37, 31, v36
	v_lshl_add_u64 v[58:59], v[42:43], 0, s[26:27]
	v_mfma_f32_16x16x32_bf16 v[20:23], v[166:169], v[178:181], v[66:69]
	v_mfma_f32_16x16x32_bf16 v[54:57], v[166:169], v[94:97], v[70:73]
	s_nop 3
	v_add_f32_e32 v16, v16, v186
	s_nop 1
	v_add_f32_e32 v20, v20, v186
	ds_write2_b32 v33, v16, v20 offset0:64 offset1:80
	v_mfma_f32_16x16x32_bf16 v[8:11], v[166:169], v[182:185], v[8:11]
	v_add_u32_e32 v20, 0x2400, v32
	v_add_f32_e32 v16, v54, v186
	v_mfma_f32_16x16x32_bf16 v[62:65], v[118:121], v[134:137], v[78:81]
	v_mfma_f32_16x16x32_bf16 v[66:69], v[118:121], v[138:141], v[82:85]
	s_nop 3
	v_add_f32_e32 v8, v8, v186
	ds_write2_b32 v33, v16, v8 offset0:96 offset1:112
	v_add_f32_e32 v8, v17, v187
	v_add_f32_e32 v16, v21, v187
	ds_write2_b32 v33, v8, v16 offset0:196 offset1:212
	v_add_f32_e32 v8, v55, v187
	v_add_f32_e32 v9, v9, v187
	ds_write2_b32 v33, v8, v9 offset0:228 offset1:244
	v_add_f32_e32 v8, v18, v188
	v_add_f32_e32 v9, v22, v188
	v_mfma_f32_16x16x32_bf16 v[70:73], v[118:121], v[146:149], v[86:89]
	ds_write2_b32 v20, v8, v9 offset0:72 offset1:88
	v_add_f32_e32 v8, v56, v188
	v_add_f32_e32 v9, v10, v188
	v_mfma_f32_16x16x32_bf16 v[78:81], v[118:121], v[150:153], v[90:93]
	ds_write2_b32 v20, v8, v9 offset0:104 offset1:120
	v_add_f32_e32 v8, v19, v189
	v_add_f32_e32 v9, v23, v189
	v_mfma_f32_16x16x32_bf16 v[16:19], v[98:101], v[174:177], v[62:65]
	ds_write2_b32 v20, v8, v9 offset0:204 offset1:220
	v_add_f32_e32 v21, v57, v189
	v_add_f32_e32 v22, v11, v189
	v_mfma_f32_16x16x32_bf16 v[8:11], v[98:101], v[178:181], v[66:69]
	ds_write2_b32 v20, v21, v22 offset0:236 offset1:252
	s_nop 2
	v_add_f32_e32 v16, v16, v190
	v_add_u32_e32 v33, 0x4000, v32
	v_mfma_f32_16x16x32_bf16 v[20:23], v[98:101], v[94:97], v[70:73]
	v_lshl_add_u64 v[62:63], v[38:39], 0, s[26:27]
	v_add_f32_e32 v8, v8, v190
	ds_write2_b32 v33, v16, v8 offset0:128 offset1:144
	v_mfma_f32_16x16x32_bf16 v[54:57], v[98:101], v[182:185], v[78:81]
	v_add_f32_e32 v10, v10, v192
	s_nop 2
	v_add_f32_e32 v8, v20, v190
	v_mfma_f32_16x16x32_bf16 v[12:15], v[74:77], v[102:105], v[12:15]
	v_mfma_f32_16x16x32_bf16 v[24:27], v[74:77], v[106:109], v[24:27]
	s_nop 0
	v_add_f32_e32 v16, v54, v190
	ds_write2_b32 v33, v8, v16 offset0:160 offset1:176
	v_add_f32_e32 v8, v17, v191
	v_mfma_f32_16x16x32_bf16 v[0:3], v[74:77], v[4:7], v[0:3]
	v_add_f32_e32 v4, v9, v191
	v_add_u32_e32 v9, 0x4400, v32
	ds_write2_b32 v9, v8, v4 offset0:4 offset1:20
	v_mfma_f32_16x16x32_bf16 v[4:7], v[122:125], v[134:137], v[28:31]
	v_add_f32_e32 v8, v21, v191
	v_add_f32_e32 v16, v55, v191
	ds_write2_b32 v9, v8, v16 offset0:36 offset1:52
	v_mfma_f32_16x16x32_bf16 v[12:15], v[122:125], v[138:141], v[12:15]
	v_add_f32_e32 v8, v18, v192
	ds_write2_b32 v9, v8, v10 offset0:136 offset1:152
	v_add_f32_e32 v8, v22, v192
	v_mfma_f32_16x16x32_bf16 v[24:27], v[122:125], v[146:149], v[24:27]
	v_add_f32_e32 v10, v56, v192
	ds_write2_b32 v9, v8, v10 offset0:168 offset1:184
	v_add_f32_e32 v8, v19, v193
	v_mfma_f32_16x16x32_bf16 v[0:3], v[122:125], v[150:153], v[0:3]
	v_add_f32_e32 v9, v11, v193
	v_add_u32_e32 v16, 0x4800, v32
	ds_write2_b32 v16, v8, v9 offset0:12 offset1:28
	v_mfma_f32_16x16x32_bf16 v[4:7], v[170:173], v[174:177], v[4:7]
	v_add_f32_e32 v17, v23, v193
	v_add_f32_e32 v18, v57, v193
	ds_write2_b32 v16, v17, v18 offset0:44 offset1:60
	v_mfma_f32_16x16x32_bf16 v[8:11], v[170:173], v[178:181], v[12:15]
	v_add_u32_e32 v16, 0x6000, v32
	s_waitcnt vmcnt(0)
; __device__ void gmlp_item(const Params& p, int layer, int b, int n, int g, char* smem) {
;     ...
;     for (int m = 0; m < 4; ++m)
; #pragma unroll
;       for (int j = 0; j < 4; ++j) {
;         int t = wr * 64 + m * 16 + fq * 4 + j;
;         float bias = p.gm_b_s[(size_t)layer * 512 + g * 128 + t];
; #pragma unroll
;         for (int nn = 0; nn < 4; ++nn) Tf[t * 132 + wc * 64 + nn * 16 + fr] = acc[m][nn][j] + bias;
;       }
;     __syncthreads();
;     uint4 uu[8], gt[8];
; #pragma unroll
;     for (int i = 0; i < 8; ++i) {
;       int q = tid + 256 * i, t = q >> 4, c = (q & 15) * 8;
;       uu[i] = *reinterpret_cast<const uint4*>(P + (t0 + t) * NP + g * 128 + c);
;       gt[i] = *reinterpret_cast<const uint4*>(P + (t0 + t) * NP + 1024 + g * 128 + c);
;     }
; #pragma unroll
;     for (int i = 0; i < 8; ++i) {
;       int q = tid + 256 * i, t = q >> 4, c = (q & 15) * 8;
;       float4 m0 = *reinterpret_cast<const float4*>(Tf + t * 132 + c);
	s_nop 1
	v_add_f32_e32 v4, v4, v50
	v_lshl_add_u64 v[56:57], v[36:37], 0, s[26:27]
	v_mfma_f32_16x16x32_bf16 v[12:15], v[170:173], v[94:97], v[24:27]
	v_lshl_add_u64 v[20:21], v[44:45], 0, s[26:27]
	v_add_f32_e32 v8, v8, v50
	ds_write2_b32 v16, v4, v8 offset0:192 offset1:208
	v_mfma_f32_16x16x32_bf16 v[0:3], v[170:173], v[182:185], v[0:3]
	s_nop 3
	v_add_f32_e32 v4, v12, v50
	s_nop 2
	v_add_f32_e32 v0, v0, v50
	ds_write2_b32 v16, v4, v0 offset0:224 offset1:240
	v_add_f32_e32 v0, v5, v51
	v_add_f32_e32 v4, v9, v51
	v_add_u32_e32 v5, 0x6400, v32
	ds_write2_b32 v5, v0, v4 offset0:68 offset1:84
	v_add_f32_e32 v0, v13, v51
	v_add_f32_e32 v1, v1, v51
	ds_write2_b32 v5, v0, v1 offset0:100 offset1:116
	v_add_f32_e32 v0, v6, v52
	v_add_f32_e32 v1, v10, v52
	ds_write2_b32 v5, v0, v1 offset0:200 offset1:216
	v_add_f32_e32 v0, v14, v52
	v_add_f32_e32 v1, v2, v52
	ds_write2_b32 v5, v0, v1 offset0:232 offset1:248
	v_add_f32_e32 v0, v7, v53
	v_add_f32_e32 v1, v11, v53
	v_add_u32_e32 v2, 0x6800, v32
	ds_write2_b32 v2, v0, v1 offset0:76 offset1:92
	v_add_f32_e32 v0, v15, v53
	v_add_f32_e32 v1, v3, v53
	ds_write2_b32 v2, v0, v1 offset0:108 offset1:124
	v_lshlrev_b32_e32 v0, 3, v60
	v_lshl_add_u64 v[8:9], v[34:35], 0, s[26:27]
	v_mov_b64_e32 v[10:11], s[4:5]
	v_and_b32_e32 v24, 0x78, v0
	v_mad_u64_u32 v[0:1], s[4:5], v8, s55, v[10:11]
	v_mad_i32_i24 v1, v9, s55, v1
	s_lshl_b32 s4, s8, 1
	s_mov_b32 s5, s27
	v_lshl_add_u64 v[0:1], v[0:1], 0, s[4:5]
	v_lshlrev_b32_e32 v128, 1, v24
	v_lshl_add_u64 v[12:13], v[48:49], 0, s[26:27]
	v_lshl_add_u64 v[52:53], v[0:1], 0, v[128:129]
	v_mad_u64_u32 v[0:1], s[8:9], v12, s55, v[10:11]
	v_mad_i32_i24 v1, v13, s55, v1
	v_lshl_add_u64 v[0:1], v[0:1], 0, s[4:5]
	v_lshl_add_u64 v[32:33], v[0:1], 0, v[128:129]
	v_mad_u64_u32 v[0:1], s[8:9], v56, s55, v[10:11]
	v_mad_i32_i24 v1, v57, s55, v1
	v_lshl_add_u64 v[0:1], v[0:1], 0, s[4:5]
	v_lshl_add_u64 v[4:5], v[0:1], 0, v[128:129]
	s_waitcnt lgkmcnt(0)
	s_barrier
	global_load_dwordx4 v[0:3], v[4:5], off
	s_nop 0
	global_load_dwordx4 v[4:7], v[4:5], off offset:2048
	v_lshl_add_u64 v[16:17], v[46:47], 0, s[26:27]
	v_mad_u64_u32 v[14:15], s[8:9], v16, s55, v[10:11]
	v_mad_i32_i24 v15, v17, s55, v15
	v_lshl_add_u64 v[14:15], v[14:15], 0, s[4:5]
	v_lshl_add_u64 v[30:31], v[14:15], 0, v[128:129]
	v_mad_u64_u32 v[14:15], s[8:9], v20, s55, v[10:11]
	v_mad_i32_i24 v15, v21, s55, v15
	v_lshl_add_u64 v[14:15], v[14:15], 0, s[4:5]
	v_lshl_add_u64 v[26:27], v[14:15], 0, v[128:129]
	v_mad_u64_u32 v[14:15], s[8:9], v58, s55, v[10:11]
	v_mad_i32_i24 v15, v59, s55, v15
	v_lshl_add_u64 v[14:15], v[14:15], 0, s[4:5]
	v_lshl_add_u64 v[60:61], v[40:41], 0, s[26:27]
	v_lshl_add_u64 v[22:23], v[14:15], 0, v[128:129]
	v_mad_u64_u32 v[14:15], s[8:9], v60, s55, v[10:11]
	v_mad_u64_u32 v[10:11], s[8:9], v62, s55, v[10:11]
	v_mad_i32_i24 v15, v61, s55, v15
	v_mad_i32_i24 v11, v63, s55, v11
	v_lshl_add_u64 v[14:15], v[14:15], 0, s[4:5]
	v_lshl_add_u64 v[10:11], v[10:11], 0, s[4:5]
	s_add_u32 s4, s6, s4
	s_addc_u32 s5, s7, 0
	v_lshl_add_u64 v[18:19], v[14:15], 0, v[128:129]
	v_lshl_add_u64 v[14:15], v[10:11], 0, v[128:129]
	v_lshlrev_b32_e32 v10, 2, v24
	v_lshl_add_u64 v[24:25], s[4:5], 0, v[128:129]
	v_lshl_add_u64 v[64:65], v[24:25], 0, s[40:41]
	v_mad_u64_u32 v[54:55], s[4:5], v34, s67, v[10:11]
	v_mad_u64_u32 v[34:35], s[4:5], v48, s67, v[10:11]
	v_mad_u64_u32 v[48:49], s[4:5], v12, s68, v[64:65]
	v_mad_u64_u32 v[28:29], s[4:5], v46, s67, v[10:11]
	v_mad_u64_u32 v[46:47], s[4:5], v16, s68, v[64:65]
	v_mad_u64_u32 v[50:51], s[4:5], v8, s68, v[64:65]
	v_mad_i32_i24 v49, v13, s68, v49
	v_mad_i32_i24 v47, v17, s68, v47
	v_mad_u64_u32 v[24:25], s[4:5], v44, s67, v[10:11]
	v_mad_u64_u32 v[44:45], s[4:5], v20, s68, v[64:65]
	v_mad_u64_u32 v[16:17], s[4:5], v40, s67, v[10:11]
	v_mad_u64_u32 v[12:13], s[4:5], v38, s67, v[10:11]
	v_mad_i32_i24 v51, v9, s68, v51
	v_mad_i32_i24 v45, v21, s68, v45
	v_mad_u64_u32 v[20:21], s[4:5], v42, s67, v[10:11]
	v_mad_u64_u32 v[8:9], s[4:5], v36, s67, v[10:11]
	v_mad_u64_u32 v[40:41], s[4:5], v60, s68, v[64:65]
	v_mad_i32_i24 v41, v61, s68, v41
	v_mad_u64_u32 v[42:43], s[4:5], v58, s68, v[64:65]
	v_mad_u64_u32 v[36:37], s[4:5], v56, s68, v[64:65]
	v_mad_i32_i24 v43, v59, s68, v43
	v_mad_i32_i24 v37, v57, s68, v37
	v_mad_u64_u32 v[38:39], s[4:5], v62, s68, v[64:65]
	v_mad_i32_i24 v39, v63, s68, v39
	s_waitcnt vmcnt(1)
	v_lshlrev_b32_e32 v63, 16, v1
	s_waitcnt vmcnt(0)
	v_lshlrev_b32_e32 v13, 16, v5
	v_lshlrev_b32_e32 v17, 16, v4
	v_mul_f32_e32 v9, 0xbfb8aa3b, v17
	v_and_b32_e32 v21, 0xffff0000, v5
	v_mul_f32_e32 v5, 0xbfb8aa3b, v13
	v_exp_f32_e32 v60, v9
	v_exp_f32_e32 v61, v5
	ds_read_b128 v[56:59], v8
	ds_read_b128 v[8:11], v8 offset:16
	v_and_b32_e32 v25, 0xffff0000, v4
	v_mul_f32_e32 v4, 0xbfb8aa3b, v25
	v_pk_add_f32 v[60:61], v[60:61], 1.0 op_sel_hi:[1,0]
	s_waitcnt lgkmcnt(1)
; __device__ __forceinline__ unsigned pack2(float a, float b) { return (unsigned)f2bf(a) | ((unsigned)f2bf(b) << 16); }
; __device__ __forceinline__ float bflo(unsigned w) { return __uint_as_float(w << 16); }
; __device__ __forceinline__ float bfhi(unsigned w) { return __uint_as_float(w & 0xffff0000u); }
; __device__ __forceinline__ float silu_f(float g) { return g / (1.f + __expf(-g)); }
; __device__ void gmlp_item(const Params& p, int layer, int b, int n, int g, char* smem) {
;     ...
;     uint4 uu[8], gt[8];
; #pragma unroll
;     for (int i = 0; i < 8; ++i) {
;       int q = tid + 256 * i, t = q >> 4, c = (q & 15) * 8;
;       uu[i] = *reinterpret_cast<const uint4*>(P + (t0 + t) * NP + g * 128 + c);
;       gt[i] = *reinterpret_cast<const uint4*>(P + (t0 + t) * NP + 1024 + g * 128 + c);
;     }
; #pragma unroll
;     for (int i = 0; i < 8; ++i) {
;       int q = tid + 256 * i, t = q >> 4, c = (q & 15) * 8;
;       float4 m0 = *reinterpret_cast<const float4*>(Tf + t * 132 + c);
;       float4 m1 = *reinterpret_cast<const float4*>(Tf + t * 132 + c + 4);
;       float mm[8] = {m0.x, m0.y, m0.z, m0.w, m1.x, m1.y, m1.z, m1.w};
;       unsigned uw[4] = {uu[i].x, uu[i].y, uu[i].z, uu[i].w};
;       unsigned gw[4] = {gt[i].x, gt[i].y, gt[i].z, gt[i].w};
;       unsigned ow[4];
; #pragma unroll
;       for (int e = 0; e < 4; ++e) {
;         float y0 = bflo(uw[e]) * mm[2 * e] * silu_f(bflo(gw[e]));
;         float y1 = bfhi(uw[e]) * mm[2 * e + 1] * silu_f(bfhi(gw[e]));
;         ow[e] = pack2(y0, y1);
;       }
;       *reinterpret_cast<uint4*>(Y + (t0 + t) * YW + g * 128 + c) = make_uint4(ow[0], ow[1], ow[2], ow[3]);
;     }
	v_mov_b32_e32 v64, v56
	v_exp_f32_e32 v4, v4
	v_lshlrev_b32_e32 v62, 16, v0
	v_mov_b32_e32 v65, v58
	v_rcp_f32_e32 v61, v61
	s_nop 0
	v_mul_f32_e32 v61, v13, v61
	v_and_b32_e32 v1, 0xffff0000, v1
	v_mul_f32_e32 v5, 0xbfb8aa3b, v21
	v_exp_f32_e32 v5, v5
	v_rcp_f32_e32 v60, v60
	s_nop 0
	v_mul_f32_e32 v60, v17, v60
	v_and_b32_e32 v0, 0xffff0000, v0
	v_mov_b32_e32 v58, v57
	v_pk_add_f32 v[4:5], v[4:5], 1.0 op_sel_hi:[1,0]
	v_pk_mul_f32 v[0:1], v[58:59], v[0:1]
	v_pk_mul_f32 v[62:63], v[64:65], v[62:63]
	v_rcp_f32_e32 v5, v5
	s_nop 0
	v_mul_f32_e32 v5, v21, v5
	v_pk_mul_f32 v[60:61], v[60:61], v[62:63]
	v_rcp_f32_e32 v4, v4
	s_nop 0
	v_mul_f32_e32 v4, v25, v4
	v_pk_mul_f32 v[0:1], v[4:5], v[0:1]
	v_and_b32_sdwa v4, v61, v155 dst_sel:DWORD dst_unused:UNUSED_PAD src0_sel:WORD_1 src1_sel:DWORD
	v_and_b32_sdwa v13, v1, v155 dst_sel:DWORD dst_unused:UNUSED_PAD src0_sel:WORD_1 src1_sel:DWORD
	v_and_b32_sdwa v17, v0, v155 dst_sel:DWORD dst_unused:UNUSED_PAD src0_sel:WORD_1 src1_sel:DWORD
	v_and_b32_sdwa v5, v60, v155 dst_sel:DWORD dst_unused:UNUSED_PAD src0_sel:WORD_1 src1_sel:DWORD
	v_add3_u32 v1, v1, v13, s66
	v_add3_u32 v0, v0, v17, s66
	v_add3_u32 v5, v60, v5, s66
	v_add3_u32 v4, v61, v4, s66
	v_and_b32_e32 v1, 0xffff0000, v1
	v_and_b32_e32 v0, 0xffff0000, v0
	v_lshlrev_b32_e32 v13, 16, v7
	v_lshlrev_b32_e32 v17, 16, v6
	v_or_b32_sdwa v1, v1, v4 dst_sel:DWORD dst_unused:UNUSED_PAD src0_sel:DWORD src1_sel:WORD_1
	v_or_b32_sdwa v0, v0, v5 dst_sel:DWORD dst_unused:UNUSED_PAD src0_sel:DWORD src1_sel:WORD_1
	v_mul_f32_e32 v4, 0xbfb8aa3b, v17
	v_mul_f32_e32 v5, 0xbfb8aa3b, v13
	v_exp_f32_e32 v4, v4
	v_exp_f32_e32 v5, v5
	v_and_b32_e32 v25, 0xffff0000, v6
	v_mul_f32_e32 v6, 0xbfb8aa3b, v25
	v_and_b32_e32 v21, 0xffff0000, v7
	v_exp_f32_e32 v60, v6
	v_pk_add_f32 v[64:65], v[4:5], 1.0 op_sel_hi:[1,0]
	global_load_dwordx4 v[4:7], v[14:15], off
	global_load_dwordx4 v[56:59], v[14:15], off offset:2048
	s_waitcnt lgkmcnt(0)
	v_mov_b32_e32 v14, v8
	v_mov_b32_e32 v15, v10
	v_lshlrev_b32_e32 v63, 16, v3
	v_lshlrev_b32_e32 v62, 16, v2
	v_pk_mul_f32 v[14:15], v[14:15], v[62:63]
	v_rcp_f32_e32 v63, v65
	s_nop 0
	v_mul_f32_e32 v63, v13, v63
	v_mul_f32_e32 v10, 0xbfb8aa3b, v21
	v_exp_f32_e32 v61, v10
	v_rcp_f32_e32 v62, v64
	s_nop 0
	v_mul_f32_e32 v62, v17, v62
	v_mov_b32_e32 v10, v9
	v_and_b32_e32 v3, 0xffff0000, v3
	v_pk_add_f32 v[60:61], v[60:61], 1.0 op_sel_hi:[1,0]
	v_and_b32_e32 v2, 0xffff0000, v2
	v_pk_mul_f32 v[2:3], v[10:11], v[2:3]
	v_pk_mul_f32 v[14:15], v[62:63], v[14:15]
	v_rcp_f32_e32 v9, v61
	s_nop 0
	v_mul_f32_e32 v9, v21, v9
	v_rcp_f32_e32 v8, v60
	s_nop 0
	v_mul_f32_e32 v8, v25, v8
	v_pk_mul_f32 v[2:3], v[8:9], v[2:3]
	v_and_b32_sdwa v8, v15, v155 dst_sel:DWORD dst_unused:UNUSED_PAD src0_sel:WORD_1 src1_sel:DWORD
	v_and_b32_sdwa v10, v3, v155 dst_sel:DWORD dst_unused:UNUSED_PAD src0_sel:WORD_1 src1_sel:DWORD
	v_add3_u32 v3, v3, v10, s66
	v_add3_u32 v8, v15, v8, s66
	v_and_b32_e32 v3, 0xffff0000, v3
	v_or_b32_sdwa v3, v3, v8 dst_sel:DWORD dst_unused:UNUSED_PAD src0_sel:DWORD src1_sel:WORD_1
	v_and_b32_sdwa v11, v2, v155 dst_sel:DWORD dst_unused:UNUSED_PAD src0_sel:WORD_1 src1_sel:DWORD
	v_and_b32_sdwa v9, v14, v155 dst_sel:DWORD dst_unused:UNUSED_PAD src0_sel:WORD_1 src1_sel:DWORD
	v_add3_u32 v2, v2, v11, s66
	v_add3_u32 v9, v14, v9, s66
	v_and_b32_e32 v2, 0xffff0000, v2
	v_or_b32_sdwa v2, v2, v9 dst_sel:DWORD dst_unused:UNUSED_PAD src0_sel:DWORD src1_sel:WORD_1
	s_waitcnt vmcnt(0)
	v_lshlrev_b32_e32 v21, 16, v56
	v_mul_f32_e32 v8, 0xbfb8aa3b, v21
	v_and_b32_e32 v29, 0xffff0000, v56
	v_lshlrev_b32_e32 v17, 16, v57
	v_exp_f32_e32 v60, v8
	v_mul_f32_e32 v8, 0xbfb8aa3b, v29
	v_exp_f32_e32 v56, v8
	v_mul_f32_e32 v8, 0xbfb8aa3b, v17
	v_exp_f32_e32 v61, v8
	ds_read_b128 v[8:11], v12
	ds_read_b128 v[12:15], v12 offset:16
	v_and_b32_e32 v25, 0xffff0000, v57
	v_lshlrev_b32_e32 v63, 16, v5
	v_pk_add_f32 v[60:61], v[60:61], 1.0 op_sel_hi:[1,0]
	s_waitcnt lgkmcnt(1)
	v_mov_b32_e32 v64, v8
	v_mov_b32_e32 v65, v10
	v_lshlrev_b32_e32 v62, 16, v4
	v_and_b32_e32 v5, 0xffff0000, v5
	v_rcp_f32_e32 v61, v61
	s_nop 0
	v_mul_f32_e32 v61, v17, v61
	v_and_b32_e32 v4, 0xffff0000, v4
	v_mul_f32_e32 v10, 0xbfb8aa3b, v25
	v_exp_f32_e32 v57, v10
	v_rcp_f32_e32 v60, v60
	s_nop 0
	v_mul_f32_e32 v60, v21, v60
	v_mov_b32_e32 v10, v9
	v_pk_mul_f32 v[4:5], v[10:11], v[4:5]
	v_pk_add_f32 v[56:57], v[56:57], 1.0 op_sel_hi:[1,0]
	v_pk_mul_f32 v[62:63], v[64:65], v[62:63]
	v_pk_mul_f32 v[60:61], v[60:61], v[62:63]
	v_lshlrev_b32_e32 v63, 16, v7
	v_lshlrev_b32_e32 v62, 16, v6
	v_rcp_f32_e32 v9, v57
	s_nop 0
	v_mul_f32_e32 v9, v25, v9
	v_rcp_f32_e32 v8, v56
	s_nop 0
	v_mul_f32_e32 v8, v29, v8
	v_pk_mul_f32 v[4:5], v[8:9], v[4:5]
	v_and_b32_sdwa v8, v61, v155 dst_sel:DWORD dst_unused:UNUSED_PAD src0_sel:WORD_1 src1_sel:DWORD
	v_and_b32_sdwa v10, v5, v155 dst_sel:DWORD dst_unused:UNUSED_PAD src0_sel:WORD_1 src1_sel:DWORD
	v_and_b32_sdwa v11, v4, v155 dst_sel:DWORD dst_unused:UNUSED_PAD src0_sel:WORD_1 src1_sel:DWORD
	v_and_b32_sdwa v9, v60, v155 dst_sel:DWORD dst_unused:UNUSED_PAD src0_sel:WORD_1 src1_sel:DWORD
	v_add3_u32 v5, v5, v10, s66
	v_add3_u32 v4, v4, v11, s66
	v_add3_u32 v9, v60, v9, s66
	v_add3_u32 v8, v61, v8, s66
	v_and_b32_e32 v5, 0xffff0000, v5
	v_and_b32_e32 v4, 0xffff0000, v4
	v_lshlrev_b32_e32 v17, 16, v59
	v_lshlrev_b32_e32 v21, 16, v58
	v_or_b32_sdwa v5, v5, v8 dst_sel:DWORD dst_unused:UNUSED_PAD src0_sel:DWORD src1_sel:WORD_1
	v_or_b32_sdwa v4, v4, v9 dst_sel:DWORD dst_unused:UNUSED_PAD src0_sel:DWORD src1_sel:WORD_1
	v_mul_f32_e32 v8, 0xbfb8aa3b, v21
	v_mul_f32_e32 v9, 0xbfb8aa3b, v17
	v_exp_f32_e32 v8, v8
	v_exp_f32_e32 v9, v9
	v_and_b32_e32 v29, 0xffff0000, v58
	v_mul_f32_e32 v10, 0xbfb8aa3b, v29
	v_and_b32_e32 v25, 0xffff0000, v59
	v_exp_f32_e32 v60, v10
	v_pk_add_f32 v[64:65], v[8:9], 1.0 op_sel_hi:[1,0]
	global_load_dwordx4 v[8:11], v[18:19], off
	global_load_dwordx4 v[56:59], v[18:19], off offset:2048
	s_waitcnt lgkmcnt(0)
; __device__ __forceinline__ unsigned pack2(float a, float b) { return (unsigned)f2bf(a) | ((unsigned)f2bf(b) << 16); }
; __device__ __forceinline__ float bflo(unsigned w) { return __uint_as_float(w << 16); }
; __device__ __forceinline__ float bfhi(unsigned w) { return __uint_as_float(w & 0xffff0000u); }
; __device__ __forceinline__ float silu_f(float g) { return g / (1.f + __expf(-g)); }
; __device__ void gmlp_item(const Params& p, int layer, int b, int n, int g, char* smem) {
;     ...
;     uint4 uu[8], gt[8];
; #pragma unroll
;     for (int i = 0; i < 8; ++i) {
;       int q = tid + 256 * i, t = q >> 4, c = (q & 15) * 8;
;       uu[i] = *reinterpret_cast<const uint4*>(P + (t0 + t) * NP + g * 128 + c);
;       gt[i] = *reinterpret_cast<const uint4*>(P + (t0 + t) * NP + 1024 + g * 128 + c);
;     }
; #pragma unroll
;     for (int i = 0; i < 8; ++i) {
;       int q = tid + 256 * i, t = q >> 4, c = (q & 15) * 8;
;       float4 m0 = *reinterpret_cast<const float4*>(Tf + t * 132 + c);
;       float4 m1 = *reinterpret_cast<const float4*>(Tf + t * 132 + c + 4);
;       float mm[8] = {m0.x, m0.y, m0.z, m0.w, m1.x, m1.y, m1.z, m1.w};
;       unsigned uw[4] = {uu[i].x, uu[i].y, uu[i].z, uu[i].w};
;       unsigned gw[4] = {gt[i].x, gt[i].y, gt[i].z, gt[i].w};
;       unsigned ow[4];
; #pragma unroll
;       for (int e = 0; e < 4; ++e) {
;         float y0 = bflo(uw[e]) * mm[2 * e] * silu_f(bflo(gw[e]));
;         float y1 = bfhi(uw[e]) * mm[2 * e + 1] * silu_f(bfhi(gw[e]));
;         ow[e] = pack2(y0, y1);
;       }
;       *reinterpret_cast<uint4*>(Y + (t0 + t) * YW + g * 128 + c) = make_uint4(ow[0], ow[1], ow[2], ow[3]);
;     }
	v_mov_b32_e32 v18, v12
	v_mov_b32_e32 v19, v14
	v_pk_mul_f32 v[18:19], v[18:19], v[62:63]
	v_rcp_f32_e32 v63, v65
	s_nop 0
	v_mul_f32_e32 v63, v17, v63
	v_and_b32_e32 v7, 0xffff0000, v7
	v_mul_f32_e32 v14, 0xbfb8aa3b, v25
	v_exp_f32_e32 v61, v14
	v_rcp_f32_e32 v62, v64
	s_nop 0
	v_mul_f32_e32 v62, v21, v62
	v_mov_b32_e32 v14, v13
	v_and_b32_e32 v6, 0xffff0000, v6
	v_pk_add_f32 v[60:61], v[60:61], 1.0 op_sel_hi:[1,0]
	v_pk_mul_f32 v[6:7], v[14:15], v[6:7]
	v_pk_mul_f32 v[18:19], v[62:63], v[18:19]
	v_rcp_f32_e32 v13, v61
	s_nop 0
	v_mul_f32_e32 v13, v25, v13
	v_rcp_f32_e32 v12, v60
	s_nop 0
	v_mul_f32_e32 v12, v29, v12
	v_pk_mul_f32 v[6:7], v[12:13], v[6:7]
	v_and_b32_sdwa v12, v19, v155 dst_sel:DWORD dst_unused:UNUSED_PAD src0_sel:WORD_1 src1_sel:DWORD
	v_and_b32_sdwa v14, v7, v155 dst_sel:DWORD dst_unused:UNUSED_PAD src0_sel:WORD_1 src1_sel:DWORD
	v_add3_u32 v7, v7, v14, s66
	v_add3_u32 v12, v19, v12, s66
	v_and_b32_e32 v7, 0xffff0000, v7
	v_or_b32_sdwa v7, v7, v12 dst_sel:DWORD dst_unused:UNUSED_PAD src0_sel:DWORD src1_sel:WORD_1
	v_and_b32_sdwa v15, v6, v155 dst_sel:DWORD dst_unused:UNUSED_PAD src0_sel:WORD_1 src1_sel:DWORD
	v_and_b32_sdwa v13, v18, v155 dst_sel:DWORD dst_unused:UNUSED_PAD src0_sel:WORD_1 src1_sel:DWORD
	v_add3_u32 v6, v6, v15, s66
	v_add3_u32 v13, v18, v13, s66
	v_and_b32_e32 v6, 0xffff0000, v6
	v_or_b32_sdwa v6, v6, v13 dst_sel:DWORD dst_unused:UNUSED_PAD src0_sel:DWORD src1_sel:WORD_1
	s_waitcnt vmcnt(1)
	v_lshlrev_b32_e32 v63, 16, v9
	s_waitcnt vmcnt(0)
	v_lshlrev_b32_e32 v25, 16, v56
	v_mul_f32_e32 v12, 0xbfb8aa3b, v25
	v_and_b32_e32 v35, 0xffff0000, v56
	v_lshlrev_b32_e32 v21, 16, v57
	v_exp_f32_e32 v60, v12
	v_mul_f32_e32 v12, 0xbfb8aa3b, v35
	v_exp_f32_e32 v56, v12
	v_mul_f32_e32 v12, 0xbfb8aa3b, v21
	v_exp_f32_e32 v61, v12
	v_and_b32_e32 v29, 0xffff0000, v57
	ds_read_b128 v[12:15], v16
	ds_read_b128 v[16:19], v16 offset:16
	v_lshlrev_b32_e32 v62, 16, v8
	v_pk_add_f32 v[60:61], v[60:61], 1.0 op_sel_hi:[1,0]
	v_and_b32_e32 v9, 0xffff0000, v9
	s_waitcnt lgkmcnt(1)
	v_mov_b32_e32 v64, v12
	v_mov_b32_e32 v65, v14
	v_pk_mul_f32 v[62:63], v[64:65], v[62:63]
	v_rcp_f32_e32 v61, v61
	s_nop 0
	v_mul_f32_e32 v61, v21, v61
	v_and_b32_e32 v8, 0xffff0000, v8
	v_mul_f32_e32 v14, 0xbfb8aa3b, v29
	v_exp_f32_e32 v57, v14
	v_rcp_f32_e32 v60, v60
	s_nop 0
	v_mul_f32_e32 v60, v25, v60
	v_mov_b32_e32 v14, v13
	v_pk_mul_f32 v[8:9], v[14:15], v[8:9]
	v_pk_add_f32 v[56:57], v[56:57], 1.0 op_sel_hi:[1,0]
	v_pk_mul_f32 v[60:61], v[60:61], v[62:63]
	v_lshlrev_b32_e32 v63, 16, v11
	v_lshlrev_b32_e32 v62, 16, v10
	v_and_b32_e32 v11, 0xffff0000, v11
	v_rcp_f32_e32 v13, v57
	s_nop 0
	v_mul_f32_e32 v13, v29, v13
	v_rcp_f32_e32 v12, v56
	s_nop 0
	v_mul_f32_e32 v12, v35, v12
	v_pk_mul_f32 v[8:9], v[12:13], v[8:9]
	v_and_b32_sdwa v12, v61, v155 dst_sel:DWORD dst_unused:UNUSED_PAD src0_sel:WORD_1 src1_sel:DWORD
	v_and_b32_sdwa v14, v9, v155 dst_sel:DWORD dst_unused:UNUSED_PAD src0_sel:WORD_1 src1_sel:DWORD
	v_and_b32_sdwa v15, v8, v155 dst_sel:DWORD dst_unused:UNUSED_PAD src0_sel:WORD_1 src1_sel:DWORD
	v_and_b32_sdwa v13, v60, v155 dst_sel:DWORD dst_unused:UNUSED_PAD src0_sel:WORD_1 src1_sel:DWORD
	v_add3_u32 v9, v9, v14, s66
	v_add3_u32 v8, v8, v15, s66
	v_add3_u32 v13, v60, v13, s66
	v_add3_u32 v12, v61, v12, s66
	v_and_b32_e32 v9, 0xffff0000, v9
	v_and_b32_e32 v8, 0xffff0000, v8
	v_lshlrev_b32_e32 v21, 16, v59
	v_lshlrev_b32_e32 v25, 16, v58
	v_or_b32_sdwa v9, v9, v12 dst_sel:DWORD dst_unused:UNUSED_PAD src0_sel:DWORD src1_sel:WORD_1
	v_or_b32_sdwa v8, v8, v13 dst_sel:DWORD dst_unused:UNUSED_PAD src0_sel:DWORD src1_sel:WORD_1
	v_mul_f32_e32 v12, 0xbfb8aa3b, v25
	v_mul_f32_e32 v13, 0xbfb8aa3b, v21
	v_exp_f32_e32 v12, v12
	v_exp_f32_e32 v13, v13
	v_and_b32_e32 v35, 0xffff0000, v58
	v_mul_f32_e32 v14, 0xbfb8aa3b, v35
	v_and_b32_e32 v29, 0xffff0000, v59
	v_exp_f32_e32 v60, v14
	v_pk_add_f32 v[64:65], v[12:13], 1.0 op_sel_hi:[1,0]
	global_load_dwordx4 v[12:15], v[22:23], off
	global_load_dwordx4 v[56:59], v[22:23], off offset:2048
	s_waitcnt lgkmcnt(0)
	v_mov_b32_e32 v22, v16
	v_mov_b32_e32 v23, v18
	v_pk_mul_f32 v[22:23], v[22:23], v[62:63]
	v_rcp_f32_e32 v63, v65
	s_nop 0
	v_mul_f32_e32 v63, v21, v63
	v_and_b32_e32 v10, 0xffff0000, v10
	v_mul_f32_e32 v18, 0xbfb8aa3b, v29
	v_exp_f32_e32 v61, v18
	v_rcp_f32_e32 v62, v64
	s_nop 0
	v_mul_f32_e32 v62, v25, v62
	v_mov_b32_e32 v18, v17
	v_pk_mul_f32 v[10:11], v[18:19], v[10:11]
	v_pk_add_f32 v[60:61], v[60:61], 1.0 op_sel_hi:[1,0]
	v_pk_mul_f32 v[22:23], v[62:63], v[22:23]
	s_waitcnt vmcnt(1)
	v_lshlrev_b32_e32 v63, 16, v13
	v_rcp_f32_e32 v17, v61
	s_nop 0
	v_mul_f32_e32 v17, v29, v17
	v_rcp_f32_e32 v16, v60
	s_nop 0
	v_mul_f32_e32 v16, v35, v16
	v_pk_mul_f32 v[10:11], v[16:17], v[10:11]
	v_and_b32_sdwa v16, v23, v155 dst_sel:DWORD dst_unused:UNUSED_PAD src0_sel:WORD_1 src1_sel:DWORD
	v_and_b32_sdwa v18, v11, v155 dst_sel:DWORD dst_unused:UNUSED_PAD src0_sel:WORD_1 src1_sel:DWORD
	v_add3_u32 v11, v11, v18, s66
	v_add3_u32 v16, v23, v16, s66
	v_and_b32_e32 v11, 0xffff0000, v11
	s_waitcnt vmcnt(0)
	v_lshlrev_b32_e32 v29, 16, v56
	v_or_b32_sdwa v11, v11, v16 dst_sel:DWORD dst_unused:UNUSED_PAD src0_sel:DWORD src1_sel:WORD_1
	v_mul_f32_e32 v16, 0xbfb8aa3b, v29
	v_and_b32_e32 v55, 0xffff0000, v56
	v_lshlrev_b32_e32 v25, 16, v57
	v_exp_f32_e32 v60, v16
	v_mul_f32_e32 v16, 0xbfb8aa3b, v55
	v_exp_f32_e32 v56, v16
	v_mul_f32_e32 v16, 0xbfb8aa3b, v25
	v_exp_f32_e32 v61, v16
	v_and_b32_sdwa v19, v10, v155 dst_sel:DWORD dst_unused:UNUSED_PAD src0_sel:WORD_1 src1_sel:DWORD
	v_and_b32_sdwa v17, v22, v155 dst_sel:DWORD dst_unused:UNUSED_PAD src0_sel:WORD_1 src1_sel:DWORD
	v_add3_u32 v10, v10, v19, s66
	v_pk_add_f32 v[60:61], v[60:61], 1.0 op_sel_hi:[1,0]
	v_add3_u32 v17, v22, v17, s66
	v_and_b32_e32 v10, 0xffff0000, v10
	v_and_b32_e32 v35, 0xffff0000, v57
	v_or_b32_sdwa v10, v10, v17 dst_sel:DWORD dst_unused:UNUSED_PAD src0_sel:DWORD src1_sel:WORD_1
	ds_read_b128 v[16:19], v20
	ds_read_b128 v[20:23], v20 offset:16
	v_lshlrev_b32_e32 v62, 16, v12
	v_and_b32_e32 v13, 0xffff0000, v13
	s_waitcnt lgkmcnt(1)
; __device__ __forceinline__ unsigned pack2(float a, float b) { return (unsigned)f2bf(a) | ((unsigned)f2bf(b) << 16); }
; __device__ __forceinline__ float bflo(unsigned w) { return __uint_as_float(w << 16); }
; __device__ __forceinline__ float bfhi(unsigned w) { return __uint_as_float(w & 0xffff0000u); }
; __device__ __forceinline__ float silu_f(float g) { return g / (1.f + __expf(-g)); }
; __device__ void gmlp_item(const Params& p, int layer, int b, int n, int g, char* smem) {
;     ...
;     uint4 uu[8], gt[8];
; #pragma unroll
;     for (int i = 0; i < 8; ++i) {
;       int q = tid + 256 * i, t = q >> 4, c = (q & 15) * 8;
;       uu[i] = *reinterpret_cast<const uint4*>(P + (t0 + t) * NP + g * 128 + c);
;       gt[i] = *reinterpret_cast<const uint4*>(P + (t0 + t) * NP + 1024 + g * 128 + c);
;     }
; #pragma unroll
;     for (int i = 0; i < 8; ++i) {
;       int q = tid + 256 * i, t = q >> 4, c = (q & 15) * 8;
;       float4 m0 = *reinterpret_cast<const float4*>(Tf + t * 132 + c);
;       float4 m1 = *reinterpret_cast<const float4*>(Tf + t * 132 + c + 4);
;       float mm[8] = {m0.x, m0.y, m0.z, m0.w, m1.x, m1.y, m1.z, m1.w};
;       unsigned uw[4] = {uu[i].x, uu[i].y, uu[i].z, uu[i].w};
;       unsigned gw[4] = {gt[i].x, gt[i].y, gt[i].z, gt[i].w};
;       unsigned ow[4];
; #pragma unroll
;       for (int e = 0; e < 4; ++e) {
;         float y0 = bflo(uw[e]) * mm[2 * e] * silu_f(bflo(gw[e]));
;         float y1 = bfhi(uw[e]) * mm[2 * e + 1] * silu_f(bfhi(gw[e]));
;         ow[e] = pack2(y0, y1);
;       }
;       *reinterpret_cast<uint4*>(Y + (t0 + t) * YW + g * 128 + c) = make_uint4(ow[0], ow[1], ow[2], ow[3]);
;     }
	v_mov_b32_e32 v64, v16
	v_mov_b32_e32 v65, v18
	v_pk_mul_f32 v[62:63], v[64:65], v[62:63]
	v_rcp_f32_e32 v61, v61
	s_nop 0
	v_mul_f32_e32 v61, v25, v61
	v_and_b32_e32 v12, 0xffff0000, v12
	v_mul_f32_e32 v18, 0xbfb8aa3b, v35
	v_exp_f32_e32 v57, v18
	v_rcp_f32_e32 v60, v60
	s_nop 0
	v_mul_f32_e32 v60, v29, v60
	v_mov_b32_e32 v18, v17
	v_pk_mul_f32 v[12:13], v[18:19], v[12:13]
	v_pk_add_f32 v[56:57], v[56:57], 1.0 op_sel_hi:[1,0]
	v_pk_mul_f32 v[60:61], v[60:61], v[62:63]
	v_lshlrev_b32_e32 v63, 16, v15
	v_lshlrev_b32_e32 v62, 16, v14
	v_and_b32_e32 v15, 0xffff0000, v15
	v_rcp_f32_e32 v17, v57
	s_nop 0
	v_mul_f32_e32 v17, v35, v17
	v_rcp_f32_e32 v16, v56
	s_nop 0
	v_mul_f32_e32 v16, v55, v16
	v_pk_mul_f32 v[12:13], v[16:17], v[12:13]
	v_and_b32_sdwa v16, v61, v155 dst_sel:DWORD dst_unused:UNUSED_PAD src0_sel:WORD_1 src1_sel:DWORD
	v_and_b32_sdwa v18, v13, v155 dst_sel:DWORD dst_unused:UNUSED_PAD src0_sel:WORD_1 src1_sel:DWORD
	v_and_b32_sdwa v19, v12, v155 dst_sel:DWORD dst_unused:UNUSED_PAD src0_sel:WORD_1 src1_sel:DWORD
	v_and_b32_sdwa v17, v60, v155 dst_sel:DWORD dst_unused:UNUSED_PAD src0_sel:WORD_1 src1_sel:DWORD
	v_add3_u32 v13, v13, v18, s66
	v_add3_u32 v12, v12, v19, s66
	v_add3_u32 v17, v60, v17, s66
	v_add3_u32 v16, v61, v16, s66
	v_and_b32_e32 v13, 0xffff0000, v13
	v_and_b32_e32 v12, 0xffff0000, v12
	v_lshlrev_b32_e32 v25, 16, v59
	v_lshlrev_b32_e32 v29, 16, v58
	v_or_b32_sdwa v13, v13, v16 dst_sel:DWORD dst_unused:UNUSED_PAD src0_sel:DWORD src1_sel:WORD_1
	v_or_b32_sdwa v12, v12, v17 dst_sel:DWORD dst_unused:UNUSED_PAD src0_sel:DWORD src1_sel:WORD_1
	v_mul_f32_e32 v16, 0xbfb8aa3b, v29
	v_mul_f32_e32 v17, 0xbfb8aa3b, v25
	v_exp_f32_e32 v16, v16
	v_exp_f32_e32 v17, v17
	v_and_b32_e32 v55, 0xffff0000, v58
	v_mul_f32_e32 v18, 0xbfb8aa3b, v55
	v_and_b32_e32 v35, 0xffff0000, v59
	v_exp_f32_e32 v60, v18
	v_pk_add_f32 v[64:65], v[16:17], 1.0 op_sel_hi:[1,0]
	global_load_dwordx4 v[16:19], v[26:27], off
	global_load_dwordx4 v[56:59], v[26:27], off offset:2048
	s_waitcnt lgkmcnt(0)
	v_mov_b32_e32 v26, v20
	v_mov_b32_e32 v27, v22
	v_pk_mul_f32 v[26:27], v[26:27], v[62:63]
	v_rcp_f32_e32 v63, v65
	s_nop 0
	v_mul_f32_e32 v63, v25, v63
	v_and_b32_e32 v14, 0xffff0000, v14
	v_mul_f32_e32 v22, 0xbfb8aa3b, v35
	v_exp_f32_e32 v61, v22
	v_rcp_f32_e32 v62, v64
	s_nop 0
	v_mul_f32_e32 v62, v29, v62
	v_mov_b32_e32 v22, v21
	v_pk_mul_f32 v[14:15], v[22:23], v[14:15]
	v_pk_add_f32 v[60:61], v[60:61], 1.0 op_sel_hi:[1,0]
	v_pk_mul_f32 v[26:27], v[62:63], v[26:27]
	s_waitcnt vmcnt(1)
	v_lshlrev_b32_e32 v63, 16, v17
	v_rcp_f32_e32 v21, v61
	s_nop 0
	v_mul_f32_e32 v21, v35, v21
	v_rcp_f32_e32 v20, v60
	s_nop 0
	v_mul_f32_e32 v20, v55, v20
	v_pk_mul_f32 v[14:15], v[20:21], v[14:15]
	v_and_b32_sdwa v20, v27, v155 dst_sel:DWORD dst_unused:UNUSED_PAD src0_sel:WORD_1 src1_sel:DWORD
	v_and_b32_sdwa v22, v15, v155 dst_sel:DWORD dst_unused:UNUSED_PAD src0_sel:WORD_1 src1_sel:DWORD
	v_add3_u32 v15, v15, v22, s66
	v_add3_u32 v20, v27, v20, s66
	v_and_b32_e32 v15, 0xffff0000, v15
	s_waitcnt vmcnt(0)
	v_lshlrev_b32_e32 v35, 16, v56
	v_or_b32_sdwa v15, v15, v20 dst_sel:DWORD dst_unused:UNUSED_PAD src0_sel:DWORD src1_sel:WORD_1
	v_mul_f32_e32 v20, 0xbfb8aa3b, v35
	v_and_b32_e32 v66, 0xffff0000, v56
	v_lshlrev_b32_e32 v29, 16, v57
	v_exp_f32_e32 v60, v20
	v_mul_f32_e32 v20, 0xbfb8aa3b, v66
	v_exp_f32_e32 v56, v20
	v_mul_f32_e32 v20, 0xbfb8aa3b, v29
	v_exp_f32_e32 v61, v20
	v_and_b32_sdwa v23, v14, v155 dst_sel:DWORD dst_unused:UNUSED_PAD src0_sel:WORD_1 src1_sel:DWORD
	v_and_b32_sdwa v21, v26, v155 dst_sel:DWORD dst_unused:UNUSED_PAD src0_sel:WORD_1 src1_sel:DWORD
	v_add3_u32 v14, v14, v23, s66
	v_pk_add_f32 v[60:61], v[60:61], 1.0 op_sel_hi:[1,0]
	v_add3_u32 v21, v26, v21, s66
	v_and_b32_e32 v14, 0xffff0000, v14
	v_and_b32_e32 v55, 0xffff0000, v57
	v_or_b32_sdwa v14, v14, v21 dst_sel:DWORD dst_unused:UNUSED_PAD src0_sel:DWORD src1_sel:WORD_1
	ds_read_b128 v[20:23], v24
	ds_read_b128 v[24:27], v24 offset:16
	v_lshlrev_b32_e32 v62, 16, v16
	v_and_b32_e32 v17, 0xffff0000, v17
	s_waitcnt lgkmcnt(1)
	v_mov_b32_e32 v64, v20
	v_mov_b32_e32 v65, v22
	v_pk_mul_f32 v[62:63], v[64:65], v[62:63]
	v_rcp_f32_e32 v61, v61
	s_nop 0
	v_mul_f32_e32 v61, v29, v61
	v_and_b32_e32 v16, 0xffff0000, v16
	v_mul_f32_e32 v22, 0xbfb8aa3b, v55
	v_exp_f32_e32 v57, v22
	v_rcp_f32_e32 v60, v60
	s_nop 0
	v_mul_f32_e32 v60, v35, v60
	v_mov_b32_e32 v22, v21
	v_pk_mul_f32 v[16:17], v[22:23], v[16:17]
	v_pk_add_f32 v[56:57], v[56:57], 1.0 op_sel_hi:[1,0]
	v_pk_mul_f32 v[60:61], v[60:61], v[62:63]
	v_lshlrev_b32_e32 v63, 16, v19
	v_lshlrev_b32_e32 v62, 16, v18
	v_and_b32_e32 v19, 0xffff0000, v19
	v_rcp_f32_e32 v21, v57
	s_nop 0
	v_mul_f32_e32 v21, v55, v21
	v_rcp_f32_e32 v20, v56
	s_nop 0
	v_mul_f32_e32 v20, v66, v20
	v_pk_mul_f32 v[16:17], v[20:21], v[16:17]
	v_and_b32_sdwa v20, v61, v155 dst_sel:DWORD dst_unused:UNUSED_PAD src0_sel:WORD_1 src1_sel:DWORD
	v_and_b32_sdwa v22, v17, v155 dst_sel:DWORD dst_unused:UNUSED_PAD src0_sel:WORD_1 src1_sel:DWORD
	v_and_b32_sdwa v23, v16, v155 dst_sel:DWORD dst_unused:UNUSED_PAD src0_sel:WORD_1 src1_sel:DWORD
	v_and_b32_sdwa v21, v60, v155 dst_sel:DWORD dst_unused:UNUSED_PAD src0_sel:WORD_1 src1_sel:DWORD
	v_add3_u32 v17, v17, v22, s66
	v_add3_u32 v16, v16, v23, s66
	v_add3_u32 v21, v60, v21, s66
	v_add3_u32 v20, v61, v20, s66
	v_and_b32_e32 v17, 0xffff0000, v17
	v_and_b32_e32 v16, 0xffff0000, v16
	v_lshlrev_b32_e32 v29, 16, v59
	v_lshlrev_b32_e32 v35, 16, v58
	v_or_b32_sdwa v17, v17, v20 dst_sel:DWORD dst_unused:UNUSED_PAD src0_sel:DWORD src1_sel:WORD_1
	v_or_b32_sdwa v16, v16, v21 dst_sel:DWORD dst_unused:UNUSED_PAD src0_sel:DWORD src1_sel:WORD_1
	v_mul_f32_e32 v20, 0xbfb8aa3b, v35
	v_mul_f32_e32 v21, 0xbfb8aa3b, v29
	v_exp_f32_e32 v20, v20
	v_exp_f32_e32 v21, v21
	v_and_b32_e32 v66, 0xffff0000, v58
	v_mul_f32_e32 v22, 0xbfb8aa3b, v66
	v_and_b32_e32 v55, 0xffff0000, v59
	v_exp_f32_e32 v60, v22
	v_pk_add_f32 v[64:65], v[20:21], 1.0 op_sel_hi:[1,0]
	global_load_dwordx4 v[20:23], v[30:31], off
	global_load_dwordx4 v[56:59], v[30:31], off offset:2048
	s_waitcnt lgkmcnt(0)
; __device__ __forceinline__ unsigned pack2(float a, float b) { return (unsigned)f2bf(a) | ((unsigned)f2bf(b) << 16); }
; __device__ __forceinline__ float bflo(unsigned w) { return __uint_as_float(w << 16); }
; __device__ __forceinline__ float bfhi(unsigned w) { return __uint_as_float(w & 0xffff0000u); }
; __device__ __forceinline__ float silu_f(float g) { return g / (1.f + __expf(-g)); }
; __device__ void gmlp_item(const Params& p, int layer, int b, int n, int g, char* smem) {
;     ...
;     uint4 uu[8], gt[8];
; #pragma unroll
;     for (int i = 0; i < 8; ++i) {
;       int q = tid + 256 * i, t = q >> 4, c = (q & 15) * 8;
;       uu[i] = *reinterpret_cast<const uint4*>(P + (t0 + t) * NP + g * 128 + c);
;       gt[i] = *reinterpret_cast<const uint4*>(P + (t0 + t) * NP + 1024 + g * 128 + c);
;     }
; #pragma unroll
;     for (int i = 0; i < 8; ++i) {
;       int q = tid + 256 * i, t = q >> 4, c = (q & 15) * 8;
;       float4 m0 = *reinterpret_cast<const float4*>(Tf + t * 132 + c);
;       float4 m1 = *reinterpret_cast<const float4*>(Tf + t * 132 + c + 4);
;       float mm[8] = {m0.x, m0.y, m0.z, m0.w, m1.x, m1.y, m1.z, m1.w};
;       unsigned uw[4] = {uu[i].x, uu[i].y, uu[i].z, uu[i].w};
;       unsigned gw[4] = {gt[i].x, gt[i].y, gt[i].z, gt[i].w};
;       unsigned ow[4];
; #pragma unroll
;       for (int e = 0; e < 4; ++e) {
;         float y0 = bflo(uw[e]) * mm[2 * e] * silu_f(bflo(gw[e]));
;         float y1 = bfhi(uw[e]) * mm[2 * e + 1] * silu_f(bfhi(gw[e]));
;         ow[e] = pack2(y0, y1);
;       }
;       *reinterpret_cast<uint4*>(Y + (t0 + t) * YW + g * 128 + c) = make_uint4(ow[0], ow[1], ow[2], ow[3]);
;     }
	v_mov_b32_e32 v30, v24
	v_mov_b32_e32 v31, v26
	v_pk_mul_f32 v[30:31], v[30:31], v[62:63]
	v_rcp_f32_e32 v63, v65
	s_nop 0
	v_mul_f32_e32 v63, v29, v63
	v_and_b32_e32 v18, 0xffff0000, v18
	v_mul_f32_e32 v26, 0xbfb8aa3b, v55
	v_exp_f32_e32 v61, v26
	v_rcp_f32_e32 v62, v64
	s_nop 0
	v_mul_f32_e32 v62, v35, v62
	v_mov_b32_e32 v26, v25
	v_pk_mul_f32 v[18:19], v[26:27], v[18:19]
	v_pk_add_f32 v[60:61], v[60:61], 1.0 op_sel_hi:[1,0]
	v_pk_mul_f32 v[30:31], v[62:63], v[30:31]
	s_waitcnt vmcnt(1)
	v_lshlrev_b32_e32 v63, 16, v21
	v_rcp_f32_e32 v25, v61
	s_nop 0
	v_mul_f32_e32 v25, v55, v25
	v_rcp_f32_e32 v24, v60
	s_nop 0
	v_mul_f32_e32 v24, v66, v24
	v_pk_mul_f32 v[18:19], v[24:25], v[18:19]
	v_and_b32_sdwa v24, v31, v155 dst_sel:DWORD dst_unused:UNUSED_PAD src0_sel:WORD_1 src1_sel:DWORD
	v_and_b32_sdwa v26, v19, v155 dst_sel:DWORD dst_unused:UNUSED_PAD src0_sel:WORD_1 src1_sel:DWORD
	v_add3_u32 v19, v19, v26, s66
	v_add3_u32 v24, v31, v24, s66
	v_and_b32_e32 v19, 0xffff0000, v19
	s_waitcnt vmcnt(0)
	v_lshlrev_b32_e32 v55, 16, v56
	v_or_b32_sdwa v19, v19, v24 dst_sel:DWORD dst_unused:UNUSED_PAD src0_sel:DWORD src1_sel:WORD_1
	v_mul_f32_e32 v24, 0xbfb8aa3b, v55
	v_and_b32_e32 v67, 0xffff0000, v56
	v_lshlrev_b32_e32 v35, 16, v57
	v_exp_f32_e32 v60, v24
	v_mul_f32_e32 v24, 0xbfb8aa3b, v67
	v_exp_f32_e32 v56, v24
	v_mul_f32_e32 v24, 0xbfb8aa3b, v35
	v_exp_f32_e32 v61, v24
	v_and_b32_sdwa v27, v18, v155 dst_sel:DWORD dst_unused:UNUSED_PAD src0_sel:WORD_1 src1_sel:DWORD
	v_and_b32_sdwa v25, v30, v155 dst_sel:DWORD dst_unused:UNUSED_PAD src0_sel:WORD_1 src1_sel:DWORD
	v_add3_u32 v18, v18, v27, s66
	v_pk_add_f32 v[60:61], v[60:61], 1.0 op_sel_hi:[1,0]
	v_add3_u32 v25, v30, v25, s66
	v_and_b32_e32 v18, 0xffff0000, v18
	v_and_b32_e32 v66, 0xffff0000, v57
	v_or_b32_sdwa v18, v18, v25 dst_sel:DWORD dst_unused:UNUSED_PAD src0_sel:DWORD src1_sel:WORD_1
	ds_read_b128 v[24:27], v28
	ds_read_b128 v[28:31], v28 offset:16
	v_lshlrev_b32_e32 v62, 16, v20
	v_and_b32_e32 v21, 0xffff0000, v21
	s_waitcnt lgkmcnt(1)
	v_mov_b32_e32 v64, v24
	v_mov_b32_e32 v65, v26
	v_pk_mul_f32 v[62:63], v[64:65], v[62:63]
	v_rcp_f32_e32 v61, v61
	s_nop 0
	v_mul_f32_e32 v61, v35, v61
	v_and_b32_e32 v20, 0xffff0000, v20
	v_mul_f32_e32 v26, 0xbfb8aa3b, v66
	v_exp_f32_e32 v57, v26
	v_rcp_f32_e32 v60, v60
	s_nop 0
	v_mul_f32_e32 v60, v55, v60
	v_mov_b32_e32 v26, v25
	v_pk_mul_f32 v[20:21], v[26:27], v[20:21]
	v_pk_add_f32 v[56:57], v[56:57], 1.0 op_sel_hi:[1,0]
	v_pk_mul_f32 v[60:61], v[60:61], v[62:63]
	v_lshlrev_b32_e32 v63, 16, v23
	v_lshlrev_b32_e32 v62, 16, v22
	v_and_b32_e32 v23, 0xffff0000, v23
	v_rcp_f32_e32 v25, v57
	s_nop 0
	v_mul_f32_e32 v25, v66, v25
	v_rcp_f32_e32 v24, v56
	s_nop 0
	v_mul_f32_e32 v24, v67, v24
	v_pk_mul_f32 v[20:21], v[24:25], v[20:21]
	v_and_b32_sdwa v24, v61, v155 dst_sel:DWORD dst_unused:UNUSED_PAD src0_sel:WORD_1 src1_sel:DWORD
	v_and_b32_sdwa v26, v21, v155 dst_sel:DWORD dst_unused:UNUSED_PAD src0_sel:WORD_1 src1_sel:DWORD
	v_and_b32_sdwa v27, v20, v155 dst_sel:DWORD dst_unused:UNUSED_PAD src0_sel:WORD_1 src1_sel:DWORD
	v_and_b32_sdwa v25, v60, v155 dst_sel:DWORD dst_unused:UNUSED_PAD src0_sel:WORD_1 src1_sel:DWORD
	v_add3_u32 v21, v21, v26, s66
	v_add3_u32 v20, v20, v27, s66
	v_add3_u32 v25, v60, v25, s66
	v_add3_u32 v24, v61, v24, s66
	v_and_b32_e32 v21, 0xffff0000, v21
	v_and_b32_e32 v20, 0xffff0000, v20
	v_lshlrev_b32_e32 v35, 16, v59
	v_lshlrev_b32_e32 v55, 16, v58
	v_or_b32_sdwa v21, v21, v24 dst_sel:DWORD dst_unused:UNUSED_PAD src0_sel:DWORD src1_sel:WORD_1
	v_or_b32_sdwa v20, v20, v25 dst_sel:DWORD dst_unused:UNUSED_PAD src0_sel:DWORD src1_sel:WORD_1
	v_mul_f32_e32 v24, 0xbfb8aa3b, v55
	v_mul_f32_e32 v25, 0xbfb8aa3b, v35
	v_exp_f32_e32 v24, v24
	v_exp_f32_e32 v25, v25
	v_and_b32_e32 v67, 0xffff0000, v58
	v_mul_f32_e32 v26, 0xbfb8aa3b, v67
	v_and_b32_e32 v66, 0xffff0000, v59
	v_exp_f32_e32 v60, v26
	v_pk_add_f32 v[64:65], v[24:25], 1.0 op_sel_hi:[1,0]
	global_load_dwordx4 v[24:27], v[32:33], off
	global_load_dwordx4 v[56:59], v[32:33], off offset:2048
	s_waitcnt lgkmcnt(0)
	v_mov_b32_e32 v32, v28
	v_mov_b32_e32 v33, v30
	v_pk_mul_f32 v[32:33], v[32:33], v[62:63]
	v_rcp_f32_e32 v63, v65
	s_nop 0
	v_mul_f32_e32 v63, v35, v63
	v_and_b32_e32 v22, 0xffff0000, v22
	v_mul_f32_e32 v30, 0xbfb8aa3b, v66
	v_exp_f32_e32 v61, v30
	v_rcp_f32_e32 v62, v64
	s_nop 0
	v_mul_f32_e32 v62, v55, v62
	v_mov_b32_e32 v30, v29
	v_pk_mul_f32 v[22:23], v[30:31], v[22:23]
	v_pk_add_f32 v[60:61], v[60:61], 1.0 op_sel_hi:[1,0]
	v_pk_mul_f32 v[32:33], v[62:63], v[32:33]
	s_waitcnt vmcnt(1)
	v_lshlrev_b32_e32 v63, 16, v25
	v_rcp_f32_e32 v29, v61
	s_nop 0
	v_mul_f32_e32 v29, v66, v29
	v_rcp_f32_e32 v28, v60
	s_nop 0
	v_mul_f32_e32 v28, v67, v28
	v_pk_mul_f32 v[22:23], v[28:29], v[22:23]
	v_and_b32_sdwa v28, v33, v155 dst_sel:DWORD dst_unused:UNUSED_PAD src0_sel:WORD_1 src1_sel:DWORD
	v_and_b32_sdwa v30, v23, v155 dst_sel:DWORD dst_unused:UNUSED_PAD src0_sel:WORD_1 src1_sel:DWORD
	v_add3_u32 v23, v23, v30, s66
	v_add3_u32 v28, v33, v28, s66
	v_and_b32_e32 v23, 0xffff0000, v23
	s_waitcnt vmcnt(0)
	v_lshlrev_b32_e32 v66, 16, v56
	v_or_b32_sdwa v23, v23, v28 dst_sel:DWORD dst_unused:UNUSED_PAD src0_sel:DWORD src1_sel:WORD_1
	v_mul_f32_e32 v28, 0xbfb8aa3b, v66
	v_and_b32_e32 v68, 0xffff0000, v56
	v_lshlrev_b32_e32 v55, 16, v57
	v_exp_f32_e32 v60, v28
	v_mul_f32_e32 v28, 0xbfb8aa3b, v68
	v_exp_f32_e32 v56, v28
	v_mul_f32_e32 v28, 0xbfb8aa3b, v55
	v_exp_f32_e32 v61, v28
	v_and_b32_sdwa v31, v22, v155 dst_sel:DWORD dst_unused:UNUSED_PAD src0_sel:WORD_1 src1_sel:DWORD
	v_and_b32_sdwa v29, v32, v155 dst_sel:DWORD dst_unused:UNUSED_PAD src0_sel:WORD_1 src1_sel:DWORD
	v_add3_u32 v22, v22, v31, s66
	v_pk_add_f32 v[60:61], v[60:61], 1.0 op_sel_hi:[1,0]
	v_add3_u32 v29, v32, v29, s66
	v_and_b32_e32 v22, 0xffff0000, v22
	v_and_b32_e32 v67, 0xffff0000, v57
	v_or_b32_sdwa v22, v22, v29 dst_sel:DWORD dst_unused:UNUSED_PAD src0_sel:DWORD src1_sel:WORD_1
	ds_read_b128 v[28:31], v34
	ds_read_b128 v[32:35], v34 offset:16
	v_lshlrev_b32_e32 v62, 16, v24
	v_and_b32_e32 v25, 0xffff0000, v25
	s_waitcnt lgkmcnt(1)
; __device__ __forceinline__ unsigned pack2(float a, float b) { return (unsigned)f2bf(a) | ((unsigned)f2bf(b) << 16); }
; __device__ __forceinline__ float bflo(unsigned w) { return __uint_as_float(w << 16); }
; __device__ __forceinline__ float bfhi(unsigned w) { return __uint_as_float(w & 0xffff0000u); }
; __device__ __forceinline__ float silu_f(float g) { return g / (1.f + __expf(-g)); }
; __device__ void gmlp_item(const Params& p, int layer, int b, int n, int g, char* smem) {
;     ...
;     uint4 uu[8], gt[8];
; #pragma unroll
;     for (int i = 0; i < 8; ++i) {
;       int q = tid + 256 * i, t = q >> 4, c = (q & 15) * 8;
;       uu[i] = *reinterpret_cast<const uint4*>(P + (t0 + t) * NP + g * 128 + c);
;       gt[i] = *reinterpret_cast<const uint4*>(P + (t0 + t) * NP + 1024 + g * 128 + c);
;     }
; #pragma unroll
;     for (int i = 0; i < 8; ++i) {
;       int q = tid + 256 * i, t = q >> 4, c = (q & 15) * 8;
;       float4 m0 = *reinterpret_cast<const float4*>(Tf + t * 132 + c);
;       float4 m1 = *reinterpret_cast<const float4*>(Tf + t * 132 + c + 4);
;       float mm[8] = {m0.x, m0.y, m0.z, m0.w, m1.x, m1.y, m1.z, m1.w};
;       unsigned uw[4] = {uu[i].x, uu[i].y, uu[i].z, uu[i].w};
;       unsigned gw[4] = {gt[i].x, gt[i].y, gt[i].z, gt[i].w};
;       unsigned ow[4];
; #pragma unroll
;       for (int e = 0; e < 4; ++e) {
;         float y0 = bflo(uw[e]) * mm[2 * e] * silu_f(bflo(gw[e]));
;         float y1 = bfhi(uw[e]) * mm[2 * e + 1] * silu_f(bfhi(gw[e]));
;         ow[e] = pack2(y0, y1);
;       }
;       *reinterpret_cast<uint4*>(Y + (t0 + t) * YW + g * 128 + c) = make_uint4(ow[0], ow[1], ow[2], ow[3]);
;     }
	v_mov_b32_e32 v64, v28
	v_mov_b32_e32 v65, v30
	v_pk_mul_f32 v[62:63], v[64:65], v[62:63]
	v_rcp_f32_e32 v61, v61
	s_nop 0
	v_mul_f32_e32 v61, v55, v61
	v_and_b32_e32 v24, 0xffff0000, v24
	v_mul_f32_e32 v30, 0xbfb8aa3b, v67
	v_exp_f32_e32 v57, v30
	v_rcp_f32_e32 v60, v60
	s_nop 0
	v_mul_f32_e32 v60, v66, v60
	v_mov_b32_e32 v30, v29
	v_pk_mul_f32 v[24:25], v[30:31], v[24:25]
	v_pk_add_f32 v[56:57], v[56:57], 1.0 op_sel_hi:[1,0]
	v_pk_mul_f32 v[60:61], v[60:61], v[62:63]
	v_lshlrev_b32_e32 v66, 16, v58
	v_lshlrev_b32_e32 v63, 16, v27
	v_and_b32_e32 v27, 0xffff0000, v27
	v_rcp_f32_e32 v29, v57
	s_nop 0
	v_mul_f32_e32 v29, v67, v29
	v_rcp_f32_e32 v28, v56
	s_nop 0
	v_mul_f32_e32 v28, v68, v28
	v_pk_mul_f32 v[24:25], v[28:29], v[24:25]
	v_and_b32_sdwa v28, v61, v155 dst_sel:DWORD dst_unused:UNUSED_PAD src0_sel:WORD_1 src1_sel:DWORD
	v_and_b32_sdwa v30, v25, v155 dst_sel:DWORD dst_unused:UNUSED_PAD src0_sel:WORD_1 src1_sel:DWORD
	v_and_b32_sdwa v31, v24, v155 dst_sel:DWORD dst_unused:UNUSED_PAD src0_sel:WORD_1 src1_sel:DWORD
	v_and_b32_sdwa v29, v60, v155 dst_sel:DWORD dst_unused:UNUSED_PAD src0_sel:WORD_1 src1_sel:DWORD
	v_add3_u32 v25, v25, v30, s66
	v_add3_u32 v24, v24, v31, s66
	v_add3_u32 v29, v60, v29, s66
	v_add3_u32 v28, v61, v28, s66
	v_and_b32_e32 v25, 0xffff0000, v25
	v_and_b32_e32 v24, 0xffff0000, v24
	v_lshlrev_b32_e32 v55, 16, v59
	v_or_b32_sdwa v25, v25, v28 dst_sel:DWORD dst_unused:UNUSED_PAD src0_sel:DWORD src1_sel:WORD_1
	v_or_b32_sdwa v24, v24, v29 dst_sel:DWORD dst_unused:UNUSED_PAD src0_sel:DWORD src1_sel:WORD_1
	v_mul_f32_e32 v28, 0xbfb8aa3b, v66
	v_mul_f32_e32 v29, 0xbfb8aa3b, v55
	v_exp_f32_e32 v28, v28
	v_exp_f32_e32 v29, v29
	v_and_b32_e32 v68, 0xffff0000, v58
	v_mul_f32_e32 v30, 0xbfb8aa3b, v68
	v_and_b32_e32 v67, 0xffff0000, v59
	v_exp_f32_e32 v60, v30
	v_pk_add_f32 v[64:65], v[28:29], 1.0 op_sel_hi:[1,0]
	global_load_dwordx4 v[28:31], v[52:53], off
	global_load_dwordx4 v[56:59], v[52:53], off offset:2048
	s_waitcnt lgkmcnt(0)
	v_mov_b32_e32 v52, v32
	v_lshlrev_b32_e32 v62, 16, v26
	v_mov_b32_e32 v53, v34
	v_pk_mul_f32 v[52:53], v[52:53], v[62:63]
	v_rcp_f32_e32 v63, v65
	s_nop 0
	v_mul_f32_e32 v63, v55, v63
	v_and_b32_e32 v26, 0xffff0000, v26
	v_mul_f32_e32 v34, 0xbfb8aa3b, v67
	v_exp_f32_e32 v61, v34
	v_rcp_f32_e32 v62, v64
	s_nop 0
	v_mul_f32_e32 v62, v66, v62
	v_mov_b32_e32 v34, v33
	v_pk_mul_f32 v[26:27], v[34:35], v[26:27]
	v_pk_add_f32 v[60:61], v[60:61], 1.0 op_sel_hi:[1,0]
	v_pk_mul_f32 v[52:53], v[62:63], v[52:53]
	s_waitcnt vmcnt(1)
	v_lshlrev_b32_e32 v63, 16, v29
	v_rcp_f32_e32 v33, v61
	s_nop 0
	v_mul_f32_e32 v33, v67, v33
	v_rcp_f32_e32 v32, v60
	s_nop 0
	v_mul_f32_e32 v32, v68, v32
	v_pk_mul_f32 v[26:27], v[32:33], v[26:27]
	v_and_b32_sdwa v32, v53, v155 dst_sel:DWORD dst_unused:UNUSED_PAD src0_sel:WORD_1 src1_sel:DWORD
	v_and_b32_sdwa v34, v27, v155 dst_sel:DWORD dst_unused:UNUSED_PAD src0_sel:WORD_1 src1_sel:DWORD
	v_add3_u32 v27, v27, v34, s66
	v_add3_u32 v32, v53, v32, s66
	v_and_b32_e32 v27, 0xffff0000, v27
	s_waitcnt vmcnt(0)
	v_lshlrev_b32_e32 v67, 16, v56
	v_or_b32_sdwa v27, v27, v32 dst_sel:DWORD dst_unused:UNUSED_PAD src0_sel:DWORD src1_sel:WORD_1
	v_mul_f32_e32 v32, 0xbfb8aa3b, v67
	v_and_b32_e32 v69, 0xffff0000, v56
	v_lshlrev_b32_e32 v66, 16, v57
	v_exp_f32_e32 v60, v32
	v_mul_f32_e32 v32, 0xbfb8aa3b, v69
	v_exp_f32_e32 v56, v32
	v_mul_f32_e32 v32, 0xbfb8aa3b, v66
	v_exp_f32_e32 v61, v32
	v_and_b32_sdwa v35, v26, v155 dst_sel:DWORD dst_unused:UNUSED_PAD src0_sel:WORD_1 src1_sel:DWORD
	v_and_b32_sdwa v33, v52, v155 dst_sel:DWORD dst_unused:UNUSED_PAD src0_sel:WORD_1 src1_sel:DWORD
	v_add3_u32 v26, v26, v35, s66
	v_pk_add_f32 v[60:61], v[60:61], 1.0 op_sel_hi:[1,0]
	v_add3_u32 v33, v52, v33, s66
	v_and_b32_e32 v26, 0xffff0000, v26
	v_and_b32_e32 v68, 0xffff0000, v57
	v_or_b32_sdwa v26, v26, v33 dst_sel:DWORD dst_unused:UNUSED_PAD src0_sel:DWORD src1_sel:WORD_1
	ds_read_b128 v[32:35], v54
	ds_read_b128 v[52:55], v54 offset:16
	v_lshlrev_b32_e32 v62, 16, v28
	v_and_b32_e32 v29, 0xffff0000, v29
	s_waitcnt lgkmcnt(1)
; __device__ __forceinline__ unsigned pack2(float a, float b) { return (unsigned)f2bf(a) | ((unsigned)f2bf(b) << 16); }
; __device__ __forceinline__ float bflo(unsigned w) { return __uint_as_float(w << 16); }
; __device__ __forceinline__ float bfhi(unsigned w) { return __uint_as_float(w & 0xffff0000u); }
; __device__ __forceinline__ float silu_f(float g) { return g / (1.f + __expf(-g)); }
; template <int DH, int MODE>
; __device__ void attn_item(const Params& p, int layer, int b, int blk, int head, char* smem) {
;     ...
; #pragma unroll
;     for (int i = 0; i < NCH; ++i) {
;       int q = tid + 256 * i, r = q / CPR, c = (q % CPR) * 8;
;       float4 m0 = *reinterpret_cast<const float4*>(Of + r * OST + c);
;       float4 m1 = *reinterpret_cast<const float4*>(Of + r * OST + c + 4);
;       float mm[8] = {m0.x, m0.y, m0.z, m0.w, m1.x, m1.y, m1.z, m1.w};
;       unsigned gw[4] = {gt[i].x, gt[i].y, gt[i].z, gt[i].w};
;       unsigned ow[4];
; #pragma unroll
;       for (int e = 0; e < 4; ++e)
;         ow[e] = pack2(mm[2 * e] * silu_f(bflo(gw[e])), mm[2 * e + 1] * silu_f(bfhi(gw[e])));
;       *reinterpret_cast<uint4*>(Y + (tq0 + r) * YW + ycol + c) = make_uint4(ow[0], ow[1], ow[2], ow[3]);
;     }
;   }
;   __syncthreads();
	v_mov_b32_e32 v64, v32
	v_mov_b32_e32 v65, v34
	v_pk_mul_f32 v[62:63], v[64:65], v[62:63]
	v_rcp_f32_e32 v61, v61
	s_nop 0
	v_mul_f32_e32 v61, v66, v61
	v_and_b32_e32 v28, 0xffff0000, v28
	v_mul_f32_e32 v34, 0xbfb8aa3b, v68
	v_exp_f32_e32 v57, v34
	v_rcp_f32_e32 v60, v60
	s_nop 0
	v_mul_f32_e32 v60, v67, v60
	v_pk_mul_f32 v[60:61], v[60:61], v[62:63]
	v_mov_b32_e32 v34, v33
	v_pk_add_f32 v[56:57], v[56:57], 1.0 op_sel_hi:[1,0]
	v_pk_mul_f32 v[28:29], v[34:35], v[28:29]
	s_nop 0
	v_rcp_f32_e32 v33, v57
	s_nop 0
	v_mul_f32_e32 v33, v68, v33
	v_rcp_f32_e32 v32, v56
	s_nop 0
	v_mul_f32_e32 v32, v69, v32
	v_pk_mul_f32 v[28:29], v[32:33], v[28:29]
	v_and_b32_sdwa v32, v61, v155 dst_sel:DWORD dst_unused:UNUSED_PAD src0_sel:WORD_1 src1_sel:DWORD
	v_and_b32_sdwa v34, v29, v155 dst_sel:DWORD dst_unused:UNUSED_PAD src0_sel:WORD_1 src1_sel:DWORD
	v_and_b32_sdwa v35, v28, v155 dst_sel:DWORD dst_unused:UNUSED_PAD src0_sel:WORD_1 src1_sel:DWORD
	v_and_b32_sdwa v33, v60, v155 dst_sel:DWORD dst_unused:UNUSED_PAD src0_sel:WORD_1 src1_sel:DWORD
	v_add3_u32 v29, v29, v34, s66
	v_add3_u32 v28, v28, v35, s66
	v_add3_u32 v33, v60, v33, s66
	v_add3_u32 v32, v61, v32, s66
	v_and_b32_e32 v29, 0xffff0000, v29
	v_and_b32_e32 v28, 0xffff0000, v28
	v_lshlrev_b32_e32 v35, 16, v59
	v_lshlrev_b32_e32 v60, 16, v58
	v_or_b32_sdwa v29, v29, v32 dst_sel:DWORD dst_unused:UNUSED_PAD src0_sel:DWORD src1_sel:WORD_1
	v_or_b32_sdwa v28, v28, v33 dst_sel:DWORD dst_unused:UNUSED_PAD src0_sel:DWORD src1_sel:WORD_1
	v_mul_f32_e32 v32, 0xbfb8aa3b, v60
	v_mul_f32_e32 v33, 0xbfb8aa3b, v35
	v_exp_f32_e32 v32, v32
	v_exp_f32_e32 v33, v33
	v_and_b32_e32 v62, 0xffff0000, v58
	s_waitcnt lgkmcnt(0)
	v_mov_b32_e32 v58, v52
	v_and_b32_e32 v61, 0xffff0000, v59
	v_pk_add_f32 v[32:33], v[32:33], 1.0 op_sel_hi:[1,0]
	v_lshlrev_b32_e32 v57, 16, v31
	v_lshlrev_b32_e32 v56, 16, v30
	v_mov_b32_e32 v59, v54
	v_pk_mul_f32 v[56:57], v[58:59], v[56:57]
	v_rcp_f32_e32 v33, v33
	s_nop 0
	v_mul_f32_e32 v33, v35, v33
	v_mul_f32_e32 v34, 0xbfb8aa3b, v62
	v_mul_f32_e32 v35, 0xbfb8aa3b, v61
	v_exp_f32_e32 v34, v34
	v_exp_f32_e32 v35, v35
	v_rcp_f32_e32 v32, v32
	s_nop 0
	v_mul_f32_e32 v32, v60, v32
	v_pk_mul_f32 v[32:33], v[32:33], v[56:57]
	v_mov_b32_e32 v54, v53
	v_pk_add_f32 v[34:35], v[34:35], 1.0 op_sel_hi:[1,0]
	v_and_b32_e32 v31, 0xffff0000, v31
	v_and_b32_e32 v30, 0xffff0000, v30
	v_pk_mul_f32 v[30:31], v[54:55], v[30:31]
	v_rcp_f32_e32 v35, v35
	s_nop 0
	v_mul_f32_e32 v35, v61, v35
	s_mov_b64 s[4:5], 0
	v_rcp_f32_e32 v34, v34
	s_nop 0
	v_mul_f32_e32 v34, v62, v34
	v_pk_mul_f32 v[30:31], v[34:35], v[30:31]
	v_and_b32_sdwa v34, v33, v155 dst_sel:DWORD dst_unused:UNUSED_PAD src0_sel:WORD_1 src1_sel:DWORD
	v_and_b32_sdwa v35, v32, v155 dst_sel:DWORD dst_unused:UNUSED_PAD src0_sel:WORD_1 src1_sel:DWORD
	v_add3_u32 v32, v32, v35, s66
	v_add3_u32 v33, v33, v34, s66
	v_and_b32_sdwa v34, v31, v155 dst_sel:DWORD dst_unused:UNUSED_PAD src0_sel:WORD_1 src1_sel:DWORD
	v_and_b32_sdwa v35, v30, v155 dst_sel:DWORD dst_unused:UNUSED_PAD src0_sel:WORD_1 src1_sel:DWORD
	v_add3_u32 v31, v31, v34, s66
	v_add3_u32 v30, v30, v35, s66
	v_and_b32_e32 v31, 0xffff0000, v31
	v_and_b32_e32 v30, 0xffff0000, v30
	v_or_b32_sdwa v31, v31, v33 dst_sel:DWORD dst_unused:UNUSED_PAD src0_sel:DWORD src1_sel:WORD_1
	v_or_b32_sdwa v30, v30, v32 dst_sel:DWORD dst_unused:UNUSED_PAD src0_sel:DWORD src1_sel:WORD_1
	global_store_dwordx4 v[50:51], v[28:31], off
	global_store_dwordx4 v[48:49], v[24:27], off
	global_store_dwordx4 v[46:47], v[20:23], off
	global_store_dwordx4 v[44:45], v[16:19], off
	global_store_dwordx4 v[42:43], v[12:15], off
	global_store_dwordx4 v[40:41], v[8:11], off
	global_store_dwordx4 v[38:39], v[4:7], off
	global_store_dwordx4 v[36:37], v[0:3], off
	s_barrier

; __device__ __forceinline__ unsigned pack2(float a, float b) { return (unsigned)f2bf(a) | ((unsigned)f2bf(b) << 16); }
; __device__ __forceinline__ float bflo(unsigned w) { return __uint_as_float(w << 16); }
; __device__ __forceinline__ float bfhi(unsigned w) { return __uint_as_float(w & 0xffff0000u); }
; __device__ __forceinline__ float silu_f(float g) { return g / (1.f + __expf(-g)); }
; template <int DH, int MODE>
; __device__ void attn_item(const Params& p, int layer, int b, int blk, int head, char* smem) {
;     ...
;   if (MODE == 0 && half == 0) linv_s[row] = 1.f / l_run;
;   __syncthreads();
;   {
;     constexpr int OST = DH + 4;
;     constexpr int CPR = DH / 8;
;     constexpr int NCH = 128 * CPR / 256;
;     float* Of = reinterpret_cast<float*>(smem);
;     uint4 gt[NCH];
; #pragma unroll
;     for (int i = 0; i < NCH; ++i) {
;       int q = tid + 256 * i, r = q / CPR, c = (q % CPR) * 8;
;       gt[i] = *reinterpret_cast<const uint4*>(P + (tq0 + r) * NP + gcol + c);
;     }
;     float lis[2][4];
; #pragma unroll
;     for (int m = 0; m < 2; ++m)
; #pragma unroll
;       for (int j = 0; j < 4; ++j) lis[m][j] = (MODE == 0) ? linv_s[wid * 32 + m * 16 + fq * 4 + j] : 1.f;
;     if (MODE == 0) __syncthreads();
; #pragma unroll
;     for (int m = 0; m < 2; ++m)
; #pragma unroll
;       for (int j = 0; j < 4; ++j) {
;         int r = wid * 32 + m * 16 + fq * 4 + j;
; #pragma unroll
;         for (int n = 0; n < NDT; ++n) Of[r * OST + n * 16 + fr] = o[m][n][j] * lis[m][j];
;       }
;     __syncthreads();
; #pragma unroll
;     for (int i = 0; i < NCH; ++i) {
;       int q = tid + 256 * i, r = q / CPR, c = (q % CPR) * 8;
;       float4 m0 = *reinterpret_cast<const float4*>(Of + r * OST + c);
;       float4 m1 = *reinterpret_cast<const float4*>(Of + r * OST + c + 4);
;       float mm[8] = {m0.x, m0.y, m0.z, m0.w, m1.x, m1.y, m1.z, m1.w};
;       unsigned gw[4] = {gt[i].x, gt[i].y, gt[i].z, gt[i].w};
;       unsigned ow[4];
; #pragma unroll
;       for (int e = 0; e < 4; ++e)
;         ow[e] = pack2(mm[2 * e] * silu_f(bflo(gw[e])), mm[2 * e + 1] * silu_f(bfhi(gw[e])));
.LBB0_190:
	v_readfirstlane_b32 s8, v85
	s_and_saveexec_b64 s[6:7], s[4:5]
	s_cbranch_execz .LBB0_192
	v_rcp_f32_e32 v32, v88
	s_nop 0
	v_lshlrev_b32_e32 v33, 2, v74
	ds_write_b32 v33, v32 offset:8704
.LBB0_192:
	s_or_b64 exec, exec, s[6:7]
	v_lshl_add_u64 v[44:45], v[66:67], 0, s[26:27]
	v_mov_b64_e32 v[46:47], s[48:49]
	v_mad_u64_u32 v[32:33], s[6:7], v44, s55, v[46:47]
	v_mad_i32_i24 v33, v45, s55, v33
	v_lshl_add_u64 v[36:37], v[32:33], 0, v[70:71]
	v_add_u32_e32 v32, 0x100, v81
	v_ashrrev_i32_e32 v33, 31, v32
	v_lshrrev_b32_e32 v33, 29, v33
	v_add_u32_e32 v33, v32, v33
	v_ashrrev_i32_e32 v86, 3, v33
	v_and_b32_e32 v33, -8, v33
	v_sub_u32_e32 v85, v32, v33
	v_lshlrev_b32_e32 v32, 3, v85
	v_ashrrev_i32_e32 v33, 31, v32
	s_waitcnt vmcnt(2)
	v_add_u32_e32 v48, 0x200, v81
	v_lshlrev_b64 v[90:91], 1, v[32:33]
	v_ashrrev_i32_e32 v32, 31, v48
	v_lshrrev_b32_e32 v32, 29, v32
	v_add_u32_e32 v32, v48, v32
	v_ashrrev_i32_e32 v92, 3, v32
	v_and_b32_e32 v49, -8, v32
	v_add_u32_e32 v32, 0x300, v81
	v_ashrrev_i32_e32 v33, 31, v32
	v_lshrrev_b32_e32 v33, 29, v33
	v_ashrrev_i32_e32 v87, 31, v86
	v_add_u32_e32 v33, v32, v33
	v_lshl_add_u64 v[88:89], v[86:87], 0, s[26:27]
	v_ashrrev_i32_e32 v94, 3, v33
	v_and_b32_e32 v33, -8, v33
	v_mad_u64_u32 v[34:35], s[6:7], v88, s55, v[46:47]
	v_sub_u32_e32 v87, v32, v33
	v_ashrrev_i32_e32 v95, 31, v94
	v_mad_i32_i24 v35, v89, s55, v35
	v_lshlrev_b32_e32 v32, 3, v87
	v_lshl_add_u64 v[40:41], v[94:95], 0, s[26:27]
	v_lshl_add_u64 v[38:39], v[34:35], 0, v[90:91]
	v_mad_u64_u32 v[34:35], s[6:7], v40, s55, v[46:47]
	v_ashrrev_i32_e32 v33, 31, v32
	v_mad_i32_i24 v35, v41, s55, v35
	v_lshlrev_b64 v[42:43], 1, v[32:33]
	v_lshl_add_u64 v[32:33], v[34:35], 0, v[42:43]
	v_add_co_u32_e32 v32, vcc, s37, v32
	s_waitcnt lgkmcnt(0)
	s_nop 0
	v_addc_co_u32_e32 v33, vcc, 0, v33, vcc
	s_barrier
	global_load_dwordx4 v[32:35], v[32:33], off offset:512
	v_sub_u32_e32 v95, v48, v49
	v_ashrrev_i32_e32 v93, 31, v92
	v_lshlrev_b32_e32 v48, 3, v95
	v_lshl_add_u64 v[96:97], v[92:93], 0, s[26:27]
	v_mad_u64_u32 v[46:47], s[6:7], v96, s55, v[46:47]
	v_ashrrev_i32_e32 v49, 31, v48
	v_mad_i32_i24 v47, v97, s55, v47
	v_lshlrev_b64 v[98:99], 1, v[48:49]
	v_lshl_add_u64 v[100:101], v[46:47], 0, v[98:99]
	v_lshl_or_b32 v46, v75, 7, v128
	ds_read_b128 v[60:63], v46 offset:8704
	ds_read_b128 v[80:83], v46 offset:8768
	s_ashr_i32 s5, s8, 31
	s_add_u32 s4, s28, s8
	s_addc_u32 s5, s29, s5
	s_lshl_b32 s6, s80, 1
	s_add_u32 s4, s4, s6
	v_lshl_or_b32 v46, v84, 2, v64
	s_waitcnt lgkmcnt(0)
	v_mul_f32_e32 v69, v0, v80
	s_addc_u32 s5, s5, 0
	v_mul_lo_u32 v0, v66, s71
	v_mul_lo_u32 v46, v46, s71
	v_mul_f32_e32 v75, v1, v81
	v_lshl_add_u32 v66, v68, 2, v0
	v_mov_b64_e32 v[0:1], s[4:5]
	v_lshl_add_u32 v47, v73, 2, v46
	v_mul_f32_e32 v48, v16, v60
	v_mul_f32_e32 v49, v28, v60
	v_mul_f32_e32 v50, v24, v60
	v_mul_f32_e32 v51, v20, v60
	s_waitcnt vmcnt(1)
	v_mul_f32_e32 v52, v17, v61
	v_mul_f32_e32 v53, v29, v61
	v_mul_f32_e32 v54, v25, v61
	v_mul_f32_e32 v55, v21, v61
	v_mul_f32_e32 v56, v18, v62
	v_mul_f32_e32 v57, v30, v62
	v_mul_f32_e32 v58, v26, v62
	v_mul_f32_e32 v59, v22, v62
	v_mul_f32_e32 v60, v19, v63
	v_mul_f32_e32 v61, v31, v63
	v_mul_f32_e32 v62, v27, v63
	v_mul_f32_e32 v64, v23, v63
	v_mul_f32_e32 v63, v12, v80
	v_mul_f32_e32 v65, v8, v80
	v_mul_f32_e32 v67, v4, v80
	v_mul_f32_e32 v72, v13, v81
	v_mul_f32_e32 v73, v9, v81
	v_mul_f32_e32 v74, v5, v81
	v_mul_f32_e32 v76, v14, v82
	v_mul_f32_e32 v77, v10, v82
	v_mul_f32_e32 v78, v6, v82
	v_mul_f32_e32 v80, v2, v82
	v_mul_f32_e32 v79, v15, v83
	v_mul_f32_e32 v81, v11, v83
	v_mul_f32_e32 v82, v7, v83
	v_mul_f32_e32 v83, v3, v83
	v_mad_u64_u32 v[2:3], s[4:5], v44, s68, v[0:1]
	v_mad_i32_i24 v3, v45, s68, v3
	v_lshl_add_u64 v[12:13], v[2:3], 0, v[70:71]
	v_mul_lo_u32 v2, v86, s71
	v_lshl_add_u32 v46, v85, 5, v2
	v_mad_u64_u32 v[2:3], s[4:5], v88, s68, v[0:1]
	v_mad_i32_i24 v3, v89, s68, v3
	v_mad_u64_u32 v[4:5], s[4:5], v40, s68, v[0:1]
	v_lshl_add_u64 v[10:11], v[2:3], 0, v[90:91]
	v_mul_lo_u32 v2, v92, s71
	v_mad_i32_i24 v5, v41, s68, v5
	v_lshl_add_u32 v45, v95, 5, v2
	v_mad_u64_u32 v[2:3], s[4:5], v96, s68, v[0:1]
	v_lshl_add_u64 v[14:15], v[4:5], 0, v[42:43]
	v_mad_i32_i24 v3, v97, s68, v3
	v_add_co_u32_e32 v0, vcc, s37, v100
	v_lshl_add_u64 v[8:9], v[2:3], 0, v[98:99]
	v_mul_lo_u32 v2, v94, s71
	s_waitcnt vmcnt(0)
	v_lshlrev_b32_e32 v16, 16, v33
	v_lshlrev_b32_e32 v18, 16, v32
	v_mul_f32_e32 v6, 0xbfb8aa3b, v18
	v_mul_f32_e32 v7, 0xbfb8aa3b, v16
	v_exp_f32_e32 v6, v6
	v_exp_f32_e32 v7, v7
	v_addc_co_u32_e32 v1, vcc, 0, v101, vcc
	v_lshl_add_u32 v44, v87, 5, v2
	v_pk_add_f32 v[4:5], v[6:7], 1.0 op_sel_hi:[1,0]
	global_load_dwordx4 v[0:3], v[0:1], off offset:512
	v_and_b32_e32 v19, 0xffff0000, v33
	v_and_b32_e32 v20, 0xffff0000, v32
	v_mul_f32_e32 v6, 0xbfb8aa3b, v20
	v_rcp_f32_e32 v17, v5
	s_nop 0
	v_mul_f32_e32 v17, v16, v17
	v_mul_f32_e32 v7, 0xbfb8aa3b, v19
	v_exp_f32_e32 v6, v6
	v_exp_f32_e32 v7, v7
	s_nop 0
	v_pk_add_f32 v[6:7], v[6:7], 1.0 op_sel_hi:[1,0]
	v_rcp_f32_e32 v16, v4
	s_nop 0
	v_mul_f32_e32 v16, v18, v16
	v_lshlrev_b32_e32 v23, 16, v34
	v_rcp_f32_e32 v4, v7
	s_nop 0
	v_mul_f32_e32 v19, v19, v4
	v_lshlrev_b32_e32 v22, 16, v35
	v_mul_f32_e32 v4, 0xbfb8aa3b, v23
	v_mul_f32_e32 v5, 0xbfb8aa3b, v22
	v_exp_f32_e32 v4, v4
	v_exp_f32_e32 v5, v5
	v_rcp_f32_e32 v18, v6
	s_nop 0
	v_mul_f32_e32 v18, v20, v18
	v_and_b32_e32 v24, 0xffff0000, v35
	v_pk_add_f32 v[4:5], v[4:5], 1.0 op_sel_hi:[1,0]
	v_and_b32_e32 v25, 0xffff0000, v34
	v_mul_f32_e32 v6, 0xbfb8aa3b, v25
	v_exp_f32_e32 v6, v6
	v_rcp_f32_e32 v21, v5
	s_nop 0
	v_mul_f32_e32 v21, v22, v21
	v_mul_f32_e32 v7, 0xbfb8aa3b, v24
	v_exp_f32_e32 v7, v7
	s_nop 0
	v_pk_add_f32 v[6:7], v[6:7], 1.0 op_sel_hi:[1,0]
	v_rcp_f32_e32 v20, v4
	s_nop 0
	v_mul_f32_e32 v20, v23, v20
	v_rcp_f32_e32 v23, v7
	s_nop 0
	v_mul_f32_e32 v23, v24, v23
	s_waitcnt vmcnt(0)
; __device__ __forceinline__ unsigned pack2(float a, float b) { return (unsigned)f2bf(a) | ((unsigned)f2bf(b) << 16); }
; __device__ __forceinline__ float bflo(unsigned w) { return __uint_as_float(w << 16); }
; __device__ __forceinline__ float bfhi(unsigned w) { return __uint_as_float(w & 0xffff0000u); }
; __device__ __forceinline__ float silu_f(float g) { return g / (1.f + __expf(-g)); }
; template <int DH, int MODE>
; __device__ void attn_item(const Params& p, int layer, int b, int blk, int head, char* smem) {
;     ...
;     for (int m = 0; m < 2; ++m)
; #pragma unroll
;       for (int j = 0; j < 4; ++j) {
;         int r = wid * 32 + m * 16 + fq * 4 + j;
; #pragma unroll
;         for (int n = 0; n < NDT; ++n) Of[r * OST + n * 16 + fr] = o[m][n][j] * lis[m][j];
;       }
;     __syncthreads();
; #pragma unroll
;     for (int i = 0; i < NCH; ++i) {
;       int q = tid + 256 * i, r = q / CPR, c = (q % CPR) * 8;
;       float4 m0 = *reinterpret_cast<const float4*>(Of + r * OST + c);
;       float4 m1 = *reinterpret_cast<const float4*>(Of + r * OST + c + 4);
;       float mm[8] = {m0.x, m0.y, m0.z, m0.w, m1.x, m1.y, m1.z, m1.w};
;       unsigned gw[4] = {gt[i].x, gt[i].y, gt[i].z, gt[i].w};
;       unsigned ow[4];
; #pragma unroll
;       for (int e = 0; e < 4; ++e)
;         ow[e] = pack2(mm[2 * e] * silu_f(bflo(gw[e])), mm[2 * e + 1] * silu_f(bfhi(gw[e])));
	v_lshlrev_b32_e32 v24, 16, v1
	v_lshlrev_b32_e32 v26, 16, v0
	v_mul_f32_e32 v4, 0xbfb8aa3b, v26
	v_mul_f32_e32 v5, 0xbfb8aa3b, v24
	v_exp_f32_e32 v4, v4
	v_exp_f32_e32 v5, v5
	v_and_b32_e32 v27, 0xffff0000, v1
	v_rcp_f32_e32 v22, v6
	s_nop 0
	v_mul_f32_e32 v22, v25, v22
	v_pk_add_f32 v[4:5], v[4:5], 1.0 op_sel_hi:[1,0]
	v_and_b32_e32 v28, 0xffff0000, v0
	v_mul_f32_e32 v0, 0xbfb8aa3b, v28
	v_exp_f32_e32 v6, v0
	v_lshlrev_b32_e32 v32, 16, v3
	v_mul_f32_e32 v7, 0xbfb8aa3b, v27
	v_rcp_f32_e32 v1, v5
	s_nop 0
	v_mul_f32_e32 v1, v24, v1
	v_exp_f32_e32 v7, v7
	s_nop 0
	v_pk_add_f32 v[24:25], v[6:7], 1.0 op_sel_hi:[1,0]
	v_rcp_f32_e32 v0, v4
	s_nop 0
	v_mul_f32_e32 v0, v26, v0
	v_lshlrev_b32_e32 v33, 16, v2
	v_rcp_f32_e32 v25, v25
	s_nop 0
	v_mul_f32_e32 v25, v27, v25
	v_add_co_u32_e64 v4, s[4:5], s37, v38
	s_nop 0
	s_nop 0
	v_addc_co_u32_e64 v5, s[4:5], 0, v39, s[4:5]
	global_load_dwordx4 v[4:7], v[4:5], off offset:512
	v_mul_f32_e32 v26, 0xbfb8aa3b, v33
	v_mul_f32_e32 v27, 0xbfb8aa3b, v32
	v_exp_f32_e32 v26, v26
	v_exp_f32_e32 v27, v27
	v_and_b32_e32 v30, 0xffff0000, v3
	v_rcp_f32_e32 v24, v24
	s_nop 0
	v_mul_f32_e32 v24, v28, v24
	v_pk_add_f32 v[26:27], v[26:27], 1.0 op_sel_hi:[1,0]
	v_and_b32_e32 v38, 0xffff0000, v2
	v_mul_f32_e32 v2, 0xbfb8aa3b, v38
	v_exp_f32_e32 v28, v2
	v_mul_f32_e32 v29, 0xbfb8aa3b, v30
	v_exp_f32_e32 v29, v29
	v_rcp_f32_e32 v3, v27
	s_nop 0
	v_mul_f32_e32 v3, v32, v3
	v_pk_add_f32 v[28:29], v[28:29], 1.0 op_sel_hi:[1,0]
	v_rcp_f32_e32 v2, v26
	s_nop 0
	v_mul_f32_e32 v2, v33, v2
	v_rcp_f32_e32 v27, v29
	s_nop 0
	v_mul_f32_e32 v27, v30, v27
	v_add_co_u32_e64 v30, s[4:5], s37, v36
	s_nop 0
	s_nop 0
	v_addc_co_u32_e64 v31, s[4:5], 0, v37, s[4:5]
	global_load_dwordx4 v[32:35], v[30:31], off offset:512
	v_rcp_f32_e32 v26, v28
	s_nop 0
	v_mul_f32_e32 v26, v38, v26
	s_barrier
	s_waitcnt vmcnt(1)
	v_lshlrev_b32_e32 v36, 16, v5
	v_lshlrev_b32_e32 v37, 16, v4
	v_mul_f32_e32 v30, 0xbfb8aa3b, v37
	v_mul_f32_e32 v31, 0xbfb8aa3b, v36
	v_exp_f32_e32 v30, v30
	v_exp_f32_e32 v31, v31
	v_and_b32_e32 v38, 0xffff0000, v5
	v_and_b32_e32 v39, 0xffff0000, v4
	v_mul_f32_e32 v4, 0xbfb8aa3b, v39
	v_pk_add_f32 v[28:29], v[30:31], 1.0 op_sel_hi:[1,0]
	v_exp_f32_e32 v30, v4
	ds_write2_b32 v47, v48, v49 offset1:16
	ds_write2_b32 v47, v50, v51 offset0:32 offset1:48
	ds_write2_b32 v47, v52, v53 offset0:68 offset1:84
	ds_write2_b32 v47, v54, v55 offset0:100 offset1:116
	ds_write2_b32 v47, v56, v57 offset0:136 offset1:152
	ds_write2_b32 v47, v58, v59 offset0:168 offset1:184
	ds_write2_b32 v47, v60, v61 offset0:204 offset1:220
	ds_write2_b32 v47, v62, v64 offset0:236 offset1:252
	v_mul_f32_e32 v31, 0xbfb8aa3b, v38
	v_exp_f32_e32 v31, v31
	v_rcp_f32_e32 v5, v29
	s_nop 0
	v_mul_f32_e32 v5, v36, v5
	v_pk_add_f32 v[30:31], v[30:31], 1.0 op_sel_hi:[1,0]
	v_rcp_f32_e32 v4, v28
	s_nop 0
	v_mul_f32_e32 v4, v37, v4
	v_rcp_f32_e32 v29, v31
	s_nop 0
	v_mul_f32_e32 v29, v38, v29
	v_lshlrev_b32_e32 v38, 16, v7
	v_lshlrev_b32_e32 v40, 16, v6
	v_mul_f32_e32 v36, 0xbfb8aa3b, v40
	v_mul_f32_e32 v37, 0xbfb8aa3b, v38
	v_exp_f32_e32 v36, v36
	v_exp_f32_e32 v37, v37
	v_rcp_f32_e32 v28, v30
	s_nop 0
	v_mul_f32_e32 v28, v39, v28
	v_and_b32_e32 v39, 0xffff0000, v7
	v_pk_add_f32 v[30:31], v[36:37], 1.0 op_sel_hi:[1,0]
	v_and_b32_e32 v41, 0xffff0000, v6
	v_mul_f32_e32 v6, 0xbfb8aa3b, v41
	v_exp_f32_e32 v36, v6
	v_mul_f32_e32 v37, 0xbfb8aa3b, v39
	v_exp_f32_e32 v37, v37
	v_rcp_f32_e32 v7, v31
	s_nop 0
	v_mul_f32_e32 v7, v38, v7
	v_pk_add_f32 v[36:37], v[36:37], 1.0 op_sel_hi:[1,0]
	v_rcp_f32_e32 v6, v30
	s_nop 0
	v_mul_f32_e32 v6, v40, v6
	v_rcp_f32_e32 v31, v37
	s_nop 0
	v_mul_f32_e32 v31, v39, v31
	s_waitcnt vmcnt(0)
	v_lshlrev_b32_e32 v42, 16, v33
	v_lshlrev_b32_e32 v43, 16, v32
	v_mul_f32_e32 v38, 0xbfb8aa3b, v43
	v_mul_f32_e32 v39, 0xbfb8aa3b, v42
	v_exp_f32_e32 v38, v38
	v_exp_f32_e32 v39, v39
	v_rcp_f32_e32 v30, v36
	s_nop 0
	v_mul_f32_e32 v30, v41, v30
	v_and_b32_e32 v68, 0xffff0000, v33
	v_pk_add_f32 v[36:37], v[38:39], 1.0 op_sel_hi:[1,0]
	v_and_b32_e32 v39, 0xffff0000, v32
	v_mul_f32_e32 v32, 0xbfb8aa3b, v39
	v_exp_f32_e32 v32, v32
	v_rcp_f32_e32 v41, v37
	s_nop 0
	v_mul_f32_e32 v41, v42, v41
	v_mul_f32_e32 v33, 0xbfb8aa3b, v68
	v_exp_f32_e32 v33, v33
	s_nop 0
	v_pk_add_f32 v[32:33], v[32:33], 1.0 op_sel_hi:[1,0]
	v_rcp_f32_e32 v40, v36
	s_nop 0
	v_mul_f32_e32 v40, v43, v40
	v_lshlrev_b32_e32 v70, 16, v34
	v_rcp_f32_e32 v43, v33
	s_nop 0
	v_mul_f32_e32 v43, v68, v43
	v_lshlrev_b32_e32 v38, 16, v35
	v_mul_f32_e32 v36, 0xbfb8aa3b, v70
	v_mul_f32_e32 v37, 0xbfb8aa3b, v38
	v_exp_f32_e32 v36, v36
	v_exp_f32_e32 v37, v37
	v_rcp_f32_e32 v42, v32
	s_nop 0
	v_mul_f32_e32 v42, v39, v42
	v_and_b32_e32 v39, 0xffff0000, v35
	v_pk_add_f32 v[32:33], v[36:37], 1.0 op_sel_hi:[1,0]
	v_and_b32_e32 v68, 0xffff0000, v34
	v_mul_f32_e32 v34, 0xbfb8aa3b, v68
	v_exp_f32_e32 v34, v34
	v_rcp_f32_e32 v71, v33
	s_nop 0
	v_mul_f32_e32 v71, v38, v71
	v_mul_f32_e32 v35, 0xbfb8aa3b, v39
	v_exp_f32_e32 v35, v35
	s_nop 0
	v_pk_add_f32 v[36:37], v[34:35], 1.0 op_sel_hi:[1,0]
	v_rcp_f32_e32 v33, v32
	s_nop 0
	v_mul_f32_e32 v70, v70, v33
	v_rcp_f32_e32 v85, v37
	s_nop 0
	v_mul_f32_e32 v85, v39, v85
	v_add_u32_e32 v32, 0x1000, v47
	ds_write2_b32 v32, v63, v65 offset0:64 offset1:80
	ds_write2_b32 v32, v67, v69 offset0:96 offset1:112
	ds_write2_b32 v32, v72, v73 offset0:132 offset1:148
	ds_write2_b32 v32, v74, v75 offset0:164 offset1:180
	ds_write2_b32 v32, v76, v77 offset0:200 offset1:216
	ds_write2_b32 v32, v78, v80 offset0:232 offset1:248
	v_add_u32_e32 v32, 0x1400, v47
	ds_write2_b32 v32, v79, v81 offset0:12 offset1:28
	ds_write2_b32 v32, v82, v83 offset0:44 offset1:60
	s_waitcnt lgkmcnt(0)
	s_barrier
; __device__ __forceinline__ unsigned pack2(float a, float b) { return (unsigned)f2bf(a) | ((unsigned)f2bf(b) << 16); }
; __device__ __forceinline__ float bflo(unsigned w) { return __uint_as_float(w << 16); }
; __device__ __forceinline__ float bfhi(unsigned w) { return __uint_as_float(w & 0xffff0000u); }
; __device__ __forceinline__ float silu_f(float g) { return g / (1.f + __expf(-g)); }
; template <int DH, int MODE>
; __device__ void attn_item(const Params& p, int layer, int b, int blk, int head, char* smem) {
;     ...
; #pragma unroll
;     for (int i = 0; i < NCH; ++i) {
;       int q = tid + 256 * i, r = q / CPR, c = (q % CPR) * 8;
;       float4 m0 = *reinterpret_cast<const float4*>(Of + r * OST + c);
;       float4 m1 = *reinterpret_cast<const float4*>(Of + r * OST + c + 4);
;       float mm[8] = {m0.x, m0.y, m0.z, m0.w, m1.x, m1.y, m1.z, m1.w};
;       unsigned gw[4] = {gt[i].x, gt[i].y, gt[i].z, gt[i].w};
;       unsigned ow[4];
; #pragma unroll
;       for (int e = 0; e < 4; ++e)
;         ow[e] = pack2(mm[2 * e] * silu_f(bflo(gw[e])), mm[2 * e + 1] * silu_f(bfhi(gw[e])));
;       *reinterpret_cast<uint4*>(Y + (tq0 + r) * YW + ycol + c) = make_uint4(ow[0], ow[1], ow[2], ow[3]);
	ds_read_b128 v[32:35], v66
	v_rcp_f32_e32 v84, v36
	s_nop 0
	v_mul_f32_e32 v84, v68, v84
	ds_read_b128 v[36:39], v66 offset:16
	v_add_co_u32_e32 v12, vcc, s74, v12
	s_waitcnt lgkmcnt(1)
	v_mov_b32_e32 v48, v32
	v_mov_b32_e32 v49, v34
	v_pk_mul_f32 v[40:41], v[40:41], v[48:49]
	v_mov_b32_e32 v34, v33
	v_pk_mul_f32 v[32:33], v[42:43], v[34:35]
	v_and_b32_sdwa v34, v41, v155 dst_sel:DWORD dst_unused:UNUSED_PAD src0_sel:WORD_1 src1_sel:DWORD
	v_and_b32_sdwa v35, v40, v155 dst_sel:DWORD dst_unused:UNUSED_PAD src0_sel:WORD_1 src1_sel:DWORD
	v_add3_u32 v35, v40, v35, s66
	v_add3_u32 v34, v41, v34, s66
	v_and_b32_sdwa v40, v33, v155 dst_sel:DWORD dst_unused:UNUSED_PAD src0_sel:WORD_1 src1_sel:DWORD
	v_and_b32_sdwa v41, v32, v155 dst_sel:DWORD dst_unused:UNUSED_PAD src0_sel:WORD_1 src1_sel:DWORD
	v_add3_u32 v33, v33, v40, s66
	v_add3_u32 v32, v32, v41, s66
	v_and_b32_e32 v33, 0xffff0000, v33
	v_and_b32_e32 v32, 0xffff0000, v32
	v_or_b32_sdwa v33, v33, v34 dst_sel:DWORD dst_unused:UNUSED_PAD src0_sel:DWORD src1_sel:WORD_1
	v_or_b32_sdwa v32, v32, v35 dst_sel:DWORD dst_unused:UNUSED_PAD src0_sel:DWORD src1_sel:WORD_1
	s_waitcnt lgkmcnt(0)
	v_mov_b32_e32 v34, v36
	v_mov_b32_e32 v35, v38
	v_pk_mul_f32 v[34:35], v[70:71], v[34:35]
	v_mov_b32_e32 v38, v37
	v_pk_mul_f32 v[36:37], v[84:85], v[38:39]
	v_and_b32_sdwa v38, v35, v155 dst_sel:DWORD dst_unused:UNUSED_PAD src0_sel:WORD_1 src1_sel:DWORD
	v_and_b32_sdwa v39, v34, v155 dst_sel:DWORD dst_unused:UNUSED_PAD src0_sel:WORD_1 src1_sel:DWORD
	v_add3_u32 v34, v34, v39, s66
	v_add3_u32 v35, v35, v38, s66
	v_and_b32_sdwa v38, v37, v155 dst_sel:DWORD dst_unused:UNUSED_PAD src0_sel:WORD_1 src1_sel:DWORD
	v_and_b32_sdwa v39, v36, v155 dst_sel:DWORD dst_unused:UNUSED_PAD src0_sel:WORD_1 src1_sel:DWORD
	v_add3_u32 v37, v37, v38, s66
	v_add3_u32 v36, v36, v39, s66
	v_and_b32_e32 v37, 0xffff0000, v37
	v_and_b32_e32 v36, 0xffff0000, v36
	v_or_b32_sdwa v35, v37, v35 dst_sel:DWORD dst_unused:UNUSED_PAD src0_sel:DWORD src1_sel:WORD_1
	v_or_b32_sdwa v34, v36, v34 dst_sel:DWORD dst_unused:UNUSED_PAD src0_sel:DWORD src1_sel:WORD_1
	ds_read_b128 v[36:39], v46
	v_addc_co_u32_e32 v13, vcc, 0, v13, vcc
	global_store_dwordx4 v[12:13], v[32:35], off offset:1024
	ds_read_b128 v[32:35], v46 offset:16
	s_waitcnt lgkmcnt(1)
	v_mov_b32_e32 v12, v36
	v_mov_b32_e32 v13, v38
	v_pk_mul_f32 v[4:5], v[4:5], v[12:13]
	v_mov_b32_e32 v38, v37
	v_pk_mul_f32 v[12:13], v[28:29], v[38:39]
	v_and_b32_sdwa v28, v5, v155 dst_sel:DWORD dst_unused:UNUSED_PAD src0_sel:WORD_1 src1_sel:DWORD
	v_and_b32_sdwa v29, v4, v155 dst_sel:DWORD dst_unused:UNUSED_PAD src0_sel:WORD_1 src1_sel:DWORD
	v_add3_u32 v4, v4, v29, s66
	v_add3_u32 v5, v5, v28, s66
	v_and_b32_sdwa v28, v13, v155 dst_sel:DWORD dst_unused:UNUSED_PAD src0_sel:WORD_1 src1_sel:DWORD
	v_and_b32_sdwa v29, v12, v155 dst_sel:DWORD dst_unused:UNUSED_PAD src0_sel:WORD_1 src1_sel:DWORD
	v_add3_u32 v13, v13, v28, s66
	v_add3_u32 v12, v12, v29, s66
	v_and_b32_e32 v13, 0xffff0000, v13
	v_and_b32_e32 v12, 0xffff0000, v12
	v_or_b32_sdwa v5, v13, v5 dst_sel:DWORD dst_unused:UNUSED_PAD src0_sel:DWORD src1_sel:WORD_1
	v_or_b32_sdwa v4, v12, v4 dst_sel:DWORD dst_unused:UNUSED_PAD src0_sel:DWORD src1_sel:WORD_1
	s_waitcnt lgkmcnt(0)
	v_mov_b32_e32 v12, v32
	v_mov_b32_e32 v13, v34
	v_pk_mul_f32 v[6:7], v[6:7], v[12:13]
	v_mov_b32_e32 v34, v33
	v_pk_mul_f32 v[12:13], v[30:31], v[34:35]
	v_and_b32_sdwa v28, v7, v155 dst_sel:DWORD dst_unused:UNUSED_PAD src0_sel:WORD_1 src1_sel:DWORD
	v_and_b32_sdwa v29, v6, v155 dst_sel:DWORD dst_unused:UNUSED_PAD src0_sel:WORD_1 src1_sel:DWORD
	v_add3_u32 v6, v6, v29, s66
	v_add3_u32 v7, v7, v28, s66
	v_and_b32_sdwa v28, v13, v155 dst_sel:DWORD dst_unused:UNUSED_PAD src0_sel:WORD_1 src1_sel:DWORD
	v_and_b32_sdwa v29, v12, v155 dst_sel:DWORD dst_unused:UNUSED_PAD src0_sel:WORD_1 src1_sel:DWORD
	v_add3_u32 v13, v13, v28, s66
	v_add3_u32 v12, v12, v29, s66
	ds_read_b128 v[28:31], v45
	v_and_b32_e32 v13, 0xffff0000, v13
	v_and_b32_e32 v12, 0xffff0000, v12
	v_add_co_u32_e32 v10, vcc, s74, v10
	v_or_b32_sdwa v7, v13, v7 dst_sel:DWORD dst_unused:UNUSED_PAD src0_sel:DWORD src1_sel:WORD_1
	v_or_b32_sdwa v6, v12, v6 dst_sel:DWORD dst_unused:UNUSED_PAD src0_sel:DWORD src1_sel:WORD_1
	v_addc_co_u32_e32 v11, vcc, 0, v11, vcc
	global_store_dwordx4 v[10:11], v[4:7], off offset:1024
	s_waitcnt lgkmcnt(0)
; __device__ __forceinline__ unsigned pack2(float a, float b) { return (unsigned)f2bf(a) | ((unsigned)f2bf(b) << 16); }
; __device__ __forceinline__ float bflo(unsigned w) { return __uint_as_float(w << 16); }
; __device__ __forceinline__ float bfhi(unsigned w) { return __uint_as_float(w & 0xffff0000u); }
; __device__ __forceinline__ float silu_f(float g) { return g / (1.f + __expf(-g)); }
; template <int DH, int MODE>
; __device__ void attn_item(const Params& p, int layer, int b, int blk, int head, char* smem) {
;     ...
; #pragma unroll
;     for (int i = 0; i < NCH; ++i) {
;       int q = tid + 256 * i, r = q / CPR, c = (q % CPR) * 8;
;       float4 m0 = *reinterpret_cast<const float4*>(Of + r * OST + c);
;       float4 m1 = *reinterpret_cast<const float4*>(Of + r * OST + c + 4);
;       float mm[8] = {m0.x, m0.y, m0.z, m0.w, m1.x, m1.y, m1.z, m1.w};
;       unsigned gw[4] = {gt[i].x, gt[i].y, gt[i].z, gt[i].w};
;       unsigned ow[4];
; #pragma unroll
;       for (int e = 0; e < 4; ++e)
;         ow[e] = pack2(mm[2 * e] * silu_f(bflo(gw[e])), mm[2 * e + 1] * silu_f(bfhi(gw[e])));
;       *reinterpret_cast<uint4*>(Y + (tq0 + r) * YW + ycol + c) = make_uint4(ow[0], ow[1], ow[2], ow[3]);
;     }
;   }
;   __syncthreads();
	v_mov_b32_e32 v10, v28
	v_mov_b32_e32 v11, v30
	ds_read_b128 v[4:7], v45 offset:16
	v_pk_mul_f32 v[0:1], v[0:1], v[10:11]
	v_mov_b32_e32 v30, v29
	v_pk_mul_f32 v[10:11], v[24:25], v[30:31]
	v_and_b32_sdwa v12, v1, v155 dst_sel:DWORD dst_unused:UNUSED_PAD src0_sel:WORD_1 src1_sel:DWORD
	v_and_b32_sdwa v13, v0, v155 dst_sel:DWORD dst_unused:UNUSED_PAD src0_sel:WORD_1 src1_sel:DWORD
	v_add3_u32 v0, v0, v13, s66
	v_add3_u32 v1, v1, v12, s66
	v_and_b32_sdwa v12, v11, v155 dst_sel:DWORD dst_unused:UNUSED_PAD src0_sel:WORD_1 src1_sel:DWORD
	v_and_b32_sdwa v13, v10, v155 dst_sel:DWORD dst_unused:UNUSED_PAD src0_sel:WORD_1 src1_sel:DWORD
	v_add3_u32 v11, v11, v12, s66
	v_add3_u32 v10, v10, v13, s66
	v_and_b32_e32 v11, 0xffff0000, v11
	v_and_b32_e32 v10, 0xffff0000, v10
	v_or_b32_sdwa v1, v11, v1 dst_sel:DWORD dst_unused:UNUSED_PAD src0_sel:DWORD src1_sel:WORD_1
	v_or_b32_sdwa v0, v10, v0 dst_sel:DWORD dst_unused:UNUSED_PAD src0_sel:DWORD src1_sel:WORD_1
	s_waitcnt lgkmcnt(0)
	v_mov_b32_e32 v10, v4
	v_mov_b32_e32 v11, v6
	v_pk_mul_f32 v[2:3], v[2:3], v[10:11]
	v_mov_b32_e32 v6, v5
	v_pk_mul_f32 v[4:5], v[26:27], v[6:7]
	v_and_b32_sdwa v6, v3, v155 dst_sel:DWORD dst_unused:UNUSED_PAD src0_sel:WORD_1 src1_sel:DWORD
	v_and_b32_sdwa v7, v2, v155 dst_sel:DWORD dst_unused:UNUSED_PAD src0_sel:WORD_1 src1_sel:DWORD
	v_add3_u32 v2, v2, v7, s66
	v_add3_u32 v3, v3, v6, s66
	v_and_b32_sdwa v6, v5, v155 dst_sel:DWORD dst_unused:UNUSED_PAD src0_sel:WORD_1 src1_sel:DWORD
	v_and_b32_sdwa v7, v4, v155 dst_sel:DWORD dst_unused:UNUSED_PAD src0_sel:WORD_1 src1_sel:DWORD
	v_add3_u32 v5, v5, v6, s66
	v_add3_u32 v4, v4, v7, s66
	v_and_b32_e32 v5, 0xffff0000, v5
	v_and_b32_e32 v4, 0xffff0000, v4
	v_or_b32_sdwa v3, v5, v3 dst_sel:DWORD dst_unused:UNUSED_PAD src0_sel:DWORD src1_sel:WORD_1
	v_or_b32_sdwa v2, v4, v2 dst_sel:DWORD dst_unused:UNUSED_PAD src0_sel:DWORD src1_sel:WORD_1
	ds_read_b128 v[4:7], v44
	v_add_co_u32_e32 v8, vcc, s74, v8
	s_nop 1
	v_addc_co_u32_e32 v9, vcc, 0, v9, vcc
	global_store_dwordx4 v[8:9], v[0:3], off offset:1024
	s_waitcnt lgkmcnt(0)
	v_mov_b32_e32 v8, v4
	v_mov_b32_e32 v9, v6
	ds_read_b128 v[0:3], v44 offset:16
	v_pk_mul_f32 v[8:9], v[16:17], v[8:9]
	v_mov_b32_e32 v6, v5
	v_pk_mul_f32 v[4:5], v[18:19], v[6:7]
	v_and_b32_sdwa v6, v9, v155 dst_sel:DWORD dst_unused:UNUSED_PAD src0_sel:WORD_1 src1_sel:DWORD
	v_and_b32_sdwa v7, v8, v155 dst_sel:DWORD dst_unused:UNUSED_PAD src0_sel:WORD_1 src1_sel:DWORD
	v_add3_u32 v7, v8, v7, s66
	v_add3_u32 v6, v9, v6, s66
	v_and_b32_sdwa v8, v5, v155 dst_sel:DWORD dst_unused:UNUSED_PAD src0_sel:WORD_1 src1_sel:DWORD
	v_and_b32_sdwa v9, v4, v155 dst_sel:DWORD dst_unused:UNUSED_PAD src0_sel:WORD_1 src1_sel:DWORD
	v_add3_u32 v5, v5, v8, s66
	v_add3_u32 v4, v4, v9, s66
	v_and_b32_e32 v5, 0xffff0000, v5
	v_and_b32_e32 v4, 0xffff0000, v4
	v_or_b32_sdwa v5, v5, v6 dst_sel:DWORD dst_unused:UNUSED_PAD src0_sel:DWORD src1_sel:WORD_1
	v_or_b32_sdwa v4, v4, v7 dst_sel:DWORD dst_unused:UNUSED_PAD src0_sel:DWORD src1_sel:WORD_1
	s_waitcnt lgkmcnt(0)
	v_mov_b32_e32 v6, v0
	v_mov_b32_e32 v7, v2
	v_pk_mul_f32 v[6:7], v[20:21], v[6:7]
	v_mov_b32_e32 v2, v1
	v_pk_mul_f32 v[0:1], v[22:23], v[2:3]
	v_and_b32_sdwa v2, v7, v155 dst_sel:DWORD dst_unused:UNUSED_PAD src0_sel:WORD_1 src1_sel:DWORD
	v_and_b32_sdwa v3, v6, v155 dst_sel:DWORD dst_unused:UNUSED_PAD src0_sel:WORD_1 src1_sel:DWORD
	v_add3_u32 v2, v7, v2, s66
	v_and_b32_sdwa v7, v0, v155 dst_sel:DWORD dst_unused:UNUSED_PAD src0_sel:WORD_1 src1_sel:DWORD
	v_add3_u32 v3, v6, v3, s66
	v_and_b32_sdwa v6, v1, v155 dst_sel:DWORD dst_unused:UNUSED_PAD src0_sel:WORD_1 src1_sel:DWORD
	v_add3_u32 v0, v0, v7, s66
	v_add3_u32 v1, v1, v6, s66
	v_and_b32_e32 v0, 0xffff0000, v0
	v_and_b32_e32 v1, 0xffff0000, v1
	v_or_b32_sdwa v6, v0, v3 dst_sel:DWORD dst_unused:UNUSED_PAD src0_sel:DWORD src1_sel:WORD_1
	v_add_co_u32_e32 v0, vcc, 0x184a1000, v14
	v_or_b32_sdwa v7, v1, v2 dst_sel:DWORD dst_unused:UNUSED_PAD src0_sel:DWORD src1_sel:WORD_1
	s_nop 0
	v_addc_co_u32_e32 v1, vcc, 0, v15, vcc
	global_store_dwordx4 v[0:1], v[4:7], off offset:1024
	s_barrier

; __device__ void phase_merge(const Params& p, int layer, char* smem) {
;     ...
;           if (r == 31) {
; #pragma unroll
;             for (int n = 0; n < 4; ++n) {
;               float bm = bmp[seg * 1024 + n * 16];
; #pragma unroll
;               for (int m = 0; m < 4; ++m)
; #pragma unroll
;                 for (int j = 0; j < 4; ++j) {
;                   GL[((m * 4 + n) * 4 + j) * 256] = f2bf(1.f / (1.f + __expf(-(acc[m][n][j] + bm))));
;                   acc[m][n][j] = 0.f;
;                 }
;             }
.LBB0_274:
	s_cmp_eq_u32 s8, 31
	s_cbranch_scc0 .LBB0_276
	s_mul_i32 s4, s67, 0xab
	s_lshr_b32 s4, s4, 1
	s_and_b32 s14, s4, 0x7000
	v_lshl_add_u64 v[2:3], v[230:231], 0, s[14:15]
	global_load_dword v164, v[2:3], off
	global_load_dword v165, v[2:3], off offset:64
	global_load_dword v166, v[2:3], off offset:128
	global_load_dword v1, v[2:3], off offset:192
	s_waitcnt vmcnt(3)
	v_add_f32_e32 v2, v160, v164
	v_add_f32_e32 v3, v161, v164
	v_mul_f32_e32 v2, 0xbfb8aa3b, v2
	v_add_f32_e32 v167, v162, v164
	v_mul_f32_e32 v3, 0xbfb8aa3b, v3
	v_exp_f32_e32 v2, v2
	v_add_f32_e32 v168, v163, v164
	v_mul_f32_e32 v167, 0xbfb8aa3b, v167
	v_exp_f32_e32 v3, v3
	v_mul_f32_e32 v168, 0xbfb8aa3b, v168
	v_exp_f32_e32 v167, v167
	v_exp_f32_e32 v168, v168
	v_add_f32_e32 v2, 1.0, v2
	v_add_f32_e32 v3, 1.0, v3
	v_add_f32_e32 v169, v144, v164
	v_add_f32_e32 v167, 1.0, v167
	v_mul_f32_e32 v169, 0xbfb8aa3b, v169
	v_add_f32_e32 v168, 1.0, v168
	v_exp_f32_e32 v169, v169
	s_nop 0
	v_add_f32_e32 v169, 1.0, v169
	v_div_scale_f32 v174, s[4:5], 1.0, v3, 1.0
	v_div_scale_f32 v176, s[6:7], 1.0, v167, 1.0
	v_div_scale_f32 v178, s[8:9], 1.0, v168, 1.0
	v_add_f32_e32 v170, v145, v164
	s_mov_b64 vcc, s[4:5]
	v_mul_f32_e32 v170, 0xbfb8aa3b, v170
	v_rcp_f32_e32 v2, v2
	s_nop 0
	s_mov_b64 vcc, s[6:7]
	v_exp_f32_e32 v170, v170
	v_bfe_u32 v172, v2, 16, 1
	v_rcp_f32_e32 v3, v3
	s_nop 0
	s_mov_b64 vcc, s[8:9]
	v_div_scale_f32 v180, s[10:11], 1.0, v169, 1.0
	v_add3_u32 v2, v2, v172, s63
	v_bfe_u32 v172, v3, 16, 1
	v_rcp_f32_e32 v167, v167
	s_nop 0
	ds_write_b16_d16_hi v234, v2 offset:32768
	v_add3_u32 v2, v3, v172, s63
	v_bfe_u32 v3, v167, 16, 1
	v_rcp_f32_e32 v168, v168
	s_nop 0
	ds_write_b16_d16_hi v234, v2 offset:33280
	v_add3_u32 v2, v167, v3, s63
	v_bfe_u32 v3, v168, 16, 1
	ds_write_b16_d16_hi v234, v2 offset:33792
	v_add3_u32 v2, v168, v3, s63
	v_add_f32_e32 v3, 1.0, v170
	s_mov_b64 vcc, s[10:11]
	ds_write_b16_d16_hi v234, v2 offset:34304
	v_rcp_f32_e32 v2, v169
	s_nop 0
	v_bfe_u32 v169, v2, 16, 1
	v_add3_u32 v2, v2, v169, s63
	ds_write_b16_d16_hi v234, v2 offset:40960
	v_add_f32_e32 v167, v146, v164
	v_mul_f32_e32 v167, 0xbfb8aa3b, v167
	v_exp_f32_e32 v167, v167
	v_rcp_f32_e32 v2, v3
	s_nop 0
	v_bfe_u32 v169, v2, 16, 1
	v_add_f32_e32 v3, 1.0, v167
	v_add3_u32 v2, v2, v169, s63
	ds_write_b16_d16_hi v234, v2 offset:41472
	v_add_f32_e32 v167, v147, v164
	v_mul_f32_e32 v167, 0xbfb8aa3b, v167
	v_exp_f32_e32 v167, v167
	v_rcp_f32_e32 v2, v3
	s_nop 0
	v_bfe_u32 v169, v2, 16, 1
	v_add_f32_e32 v3, 1.0, v167
	v_add3_u32 v2, v2, v169, s63
	ds_write_b16_d16_hi v234, v2 offset:41984
	v_add_f32_e32 v167, v128, v164
	v_mul_f32_e32 v167, 0xbfb8aa3b, v167
	v_exp_f32_e32 v167, v167
	v_rcp_f32_e32 v2, v3
	s_nop 0
	v_bfe_u32 v169, v2, 16, 1
	v_add_f32_e32 v3, 1.0, v167
	v_add3_u32 v2, v2, v169, s63
	ds_write_b16_d16_hi v234, v2 offset:42496
	v_add_f32_e32 v167, v129, v164
	v_mul_f32_e32 v167, 0xbfb8aa3b, v167
	v_exp_f32_e32 v167, v167
	v_rcp_f32_e32 v2, v3
	s_nop 0
	v_bfe_u32 v169, v2, 16, 1
	v_add_f32_e32 v3, 1.0, v167
	v_add3_u32 v2, v2, v169, s63
	ds_write_b16_d16_hi v234, v2 offset:49152
	v_add_f32_e32 v167, v130, v164
	v_mul_f32_e32 v167, 0xbfb8aa3b, v167
	v_exp_f32_e32 v167, v167
	v_rcp_f32_e32 v2, v3
	s_nop 0
	v_bfe_u32 v169, v2, 16, 1
	v_add_f32_e32 v3, 1.0, v167
	v_add3_u32 v2, v2, v169, s63
	ds_write_b16_d16_hi v234, v2 offset:49664
	v_add_f32_e32 v167, v131, v164
	v_mul_f32_e32 v167, 0xbfb8aa3b, v167
	v_exp_f32_e32 v167, v167
	v_rcp_f32_e32 v2, v3
	s_nop 0
	v_bfe_u32 v169, v2, 16, 1
	v_add_f32_e32 v3, 1.0, v167
	v_add3_u32 v2, v2, v169, s63
	ds_write_b16_d16_hi v234, v2 offset:50176
	v_add_f32_e32 v167, v112, v164
	v_mul_f32_e32 v167, 0xbfb8aa3b, v167
	v_exp_f32_e32 v167, v167
	v_rcp_f32_e32 v2, v3
	s_nop 0
	v_bfe_u32 v169, v2, 16, 1
	v_add_f32_e32 v3, 1.0, v167
	v_add3_u32 v2, v2, v169, s63
	ds_write_b16_d16_hi v234, v2 offset:50688
	v_add_f32_e32 v167, v113, v164
	v_mul_f32_e32 v167, 0xbfb8aa3b, v167
	v_exp_f32_e32 v167, v167
	v_rcp_f32_e32 v2, v3
	s_nop 0
	v_bfe_u32 v169, v2, 16, 1
	v_add_f32_e32 v3, 1.0, v167
	v_add3_u32 v2, v2, v169, s63
	ds_write_b16_d16_hi v234, v2 offset:57344
	v_add_f32_e32 v167, v114, v164
	v_mul_f32_e32 v167, 0xbfb8aa3b, v167
	v_exp_f32_e32 v167, v167
	v_rcp_f32_e32 v2, v3
	s_nop 0
	v_bfe_u32 v169, v2, 16, 1
	v_add_f32_e32 v3, 1.0, v167
	v_add3_u32 v2, v2, v169, s63
	ds_write_b16_d16_hi v234, v2 offset:57856
	v_add_f32_e32 v164, v115, v164
	v_mul_f32_e32 v164, 0xbfb8aa3b, v164
	v_exp_f32_e32 v164, v164
	v_rcp_f32_e32 v2, v3
	s_nop 0
	v_add_f32_e32 v3, 1.0, v164
	v_bfe_u32 v168, v2, 16, 1
	v_add3_u32 v2, v2, v168, s63
	ds_write_b16_d16_hi v234, v2 offset:58368
	s_waitcnt vmcnt(2)
; __device__ void phase_merge(const Params& p, int layer, char* smem) {
;     ...
;             for (int n = 0; n < 4; ++n) {
;               float bm = bmp[seg * 1024 + n * 16];
; #pragma unroll
;               for (int m = 0; m < 4; ++m)
; #pragma unroll
;                 for (int j = 0; j < 4; ++j) {
;                   GL[((m * 4 + n) * 4 + j) * 256] = f2bf(1.f / (1.f + __expf(-(acc[m][n][j] + bm))));
;                   acc[m][n][j] = 0.f;
;                 }
;             }
	v_add_f32_e32 v164, v156, v165
	v_mul_f32_e32 v164, 0xbfb8aa3b, v164
	v_exp_f32_e32 v164, v164
	v_rcp_f32_e32 v2, v3
	s_nop 0
	v_bfe_u32 v168, v2, 16, 1
	v_add_f32_e32 v3, 1.0, v164
	v_add3_u32 v2, v2, v168, s63
	ds_write_b16_d16_hi v234, v2 offset:58880
	v_add_f32_e32 v164, v157, v165
	v_mul_f32_e32 v164, 0xbfb8aa3b, v164
	v_exp_f32_e32 v164, v164
	v_rcp_f32_e32 v2, v3
	s_nop 0
	v_bfe_u32 v168, v2, 16, 1
	v_add_f32_e32 v3, 1.0, v164
	v_add3_u32 v2, v2, v168, s63
	ds_write_b16_d16_hi v234, v2 offset:34816
	v_add_f32_e32 v164, v158, v165
	v_mul_f32_e32 v164, 0xbfb8aa3b, v164
	v_exp_f32_e32 v164, v164
	v_rcp_f32_e32 v2, v3
	s_nop 0
	v_bfe_u32 v168, v2, 16, 1
	v_add_f32_e32 v3, 1.0, v164
	v_add3_u32 v2, v2, v168, s63
	ds_write_b16_d16_hi v234, v2 offset:35328
	v_add_f32_e32 v164, v159, v165
	v_mul_f32_e32 v164, 0xbfb8aa3b, v164
	v_exp_f32_e32 v164, v164
	v_rcp_f32_e32 v2, v3
	s_nop 0
	v_bfe_u32 v168, v2, 16, 1
	v_add_f32_e32 v3, 1.0, v164
	v_add3_u32 v2, v2, v168, s63
	ds_write_b16_d16_hi v234, v2 offset:35840
	v_add_f32_e32 v164, v140, v165
	v_mul_f32_e32 v164, 0xbfb8aa3b, v164
	v_exp_f32_e32 v164, v164
	v_rcp_f32_e32 v2, v3
	s_nop 0
	v_bfe_u32 v168, v2, 16, 1
	v_add_f32_e32 v3, 1.0, v164
	v_add3_u32 v2, v2, v168, s63
	ds_write_b16_d16_hi v234, v2 offset:36352
	v_add_f32_e32 v164, v141, v165
	v_mul_f32_e32 v164, 0xbfb8aa3b, v164
	v_exp_f32_e32 v164, v164
	v_rcp_f32_e32 v2, v3
	s_nop 0
	v_bfe_u32 v168, v2, 16, 1
	v_add_f32_e32 v3, 1.0, v164
	v_add3_u32 v2, v2, v168, s63
	ds_write_b16_d16_hi v234, v2 offset:43008
	v_add_f32_e32 v164, v142, v165
	v_mul_f32_e32 v164, 0xbfb8aa3b, v164
	v_exp_f32_e32 v164, v164
	v_rcp_f32_e32 v2, v3
	s_nop 0
	v_bfe_u32 v168, v2, 16, 1
	v_add_f32_e32 v3, 1.0, v164
	v_add3_u32 v2, v2, v168, s63
	ds_write_b16_d16_hi v234, v2 offset:43520
	v_add_f32_e32 v164, v143, v165
	v_mul_f32_e32 v164, 0xbfb8aa3b, v164
	v_exp_f32_e32 v164, v164
	v_rcp_f32_e32 v2, v3
	s_nop 0
	v_bfe_u32 v168, v2, 16, 1
	v_add_f32_e32 v3, 1.0, v164
	v_add3_u32 v2, v2, v168, s63
	ds_write_b16_d16_hi v234, v2 offset:44032
	v_add_f32_e32 v164, v124, v165
	v_mul_f32_e32 v164, 0xbfb8aa3b, v164
	v_exp_f32_e32 v164, v164
	v_rcp_f32_e32 v2, v3
	s_nop 0
	v_bfe_u32 v168, v2, 16, 1
	v_add_f32_e32 v3, 1.0, v164
	v_add3_u32 v2, v2, v168, s63
	ds_write_b16_d16_hi v234, v2 offset:44544
	v_add_f32_e32 v164, v125, v165
	v_mul_f32_e32 v164, 0xbfb8aa3b, v164
	v_exp_f32_e32 v164, v164
	v_rcp_f32_e32 v2, v3
	s_nop 0
	v_bfe_u32 v168, v2, 16, 1
	v_add_f32_e32 v3, 1.0, v164
	v_add3_u32 v2, v2, v168, s63
	ds_write_b16_d16_hi v234, v2 offset:51200
	v_add_f32_e32 v164, v126, v165
	v_mul_f32_e32 v164, 0xbfb8aa3b, v164
	v_exp_f32_e32 v164, v164
	v_rcp_f32_e32 v2, v3
	s_nop 0
	v_bfe_u32 v168, v2, 16, 1
	v_add_f32_e32 v3, 1.0, v164
	v_add3_u32 v2, v2, v168, s63
	ds_write_b16_d16_hi v234, v2 offset:51712
	v_add_f32_e32 v164, v127, v165
	v_mul_f32_e32 v164, 0xbfb8aa3b, v164
	v_exp_f32_e32 v164, v164
	v_rcp_f32_e32 v2, v3
	s_nop 0
	v_bfe_u32 v168, v2, 16, 1
	v_add_f32_e32 v3, 1.0, v164
	v_add3_u32 v2, v2, v168, s63
	ds_write_b16_d16_hi v234, v2 offset:52224
	v_add_f32_e32 v164, v108, v165
	v_mul_f32_e32 v164, 0xbfb8aa3b, v164
	v_exp_f32_e32 v164, v164
	v_rcp_f32_e32 v2, v3
	s_nop 0
	v_bfe_u32 v168, v2, 16, 1
	v_add_f32_e32 v3, 1.0, v164
	v_add3_u32 v2, v2, v168, s63
	ds_write_b16_d16_hi v234, v2 offset:52736
	v_add_f32_e32 v164, v109, v165
	v_mul_f32_e32 v164, 0xbfb8aa3b, v164
	v_exp_f32_e32 v164, v164
	v_rcp_f32_e32 v2, v3
	s_nop 0
	v_bfe_u32 v168, v2, 16, 1
	v_add_f32_e32 v3, 1.0, v164
	v_add3_u32 v2, v2, v168, s63
	ds_write_b16_d16_hi v234, v2 offset:59392
	v_add_f32_e32 v164, v110, v165
	v_mul_f32_e32 v164, 0xbfb8aa3b, v164
	v_exp_f32_e32 v164, v164
	v_rcp_f32_e32 v2, v3
	s_nop 0
	v_bfe_u32 v168, v2, 16, 1
	v_add_f32_e32 v3, 1.0, v164
	v_add3_u32 v2, v2, v168, s63
	ds_write_b16_d16_hi v234, v2 offset:59904
	v_add_f32_e32 v164, v111, v165
	v_mul_f32_e32 v164, 0xbfb8aa3b, v164
	v_exp_f32_e32 v164, v164
	v_rcp_f32_e32 v2, v3
	s_nop 0
	v_bfe_u32 v167, v2, 16, 1
	v_add_f32_e32 v3, 1.0, v164
	v_add3_u32 v2, v2, v167, s63
	ds_write_b16_d16_hi v234, v2 offset:60416
	s_waitcnt vmcnt(1)
	v_add_f32_e32 v164, v152, v166
	v_mul_f32_e32 v164, 0xbfb8aa3b, v164
	v_exp_f32_e32 v164, v164
	v_rcp_f32_e32 v2, v3
	s_nop 0
	v_bfe_u32 v167, v2, 16, 1
	v_add_f32_e32 v3, 1.0, v164
	v_add3_u32 v2, v2, v167, s63
	ds_write_b16_d16_hi v234, v2 offset:60928
	v_add_f32_e32 v164, v153, v166
	v_mul_f32_e32 v164, 0xbfb8aa3b, v164
	v_exp_f32_e32 v164, v164
	v_rcp_f32_e32 v2, v3
	s_nop 0
	v_bfe_u32 v167, v2, 16, 1
	v_add_f32_e32 v3, 1.0, v164
	v_add3_u32 v2, v2, v167, s63
	ds_write_b16_d16_hi v234, v2 offset:36864
	v_add_f32_e32 v164, v154, v166
	v_mul_f32_e32 v164, 0xbfb8aa3b, v164
	v_exp_f32_e32 v164, v164
	v_rcp_f32_e32 v2, v3
	s_nop 0
	v_bfe_u32 v167, v2, 16, 1
	v_add_f32_e32 v3, 1.0, v164
	v_add3_u32 v2, v2, v167, s63
	ds_write_b16_d16_hi v234, v2 offset:37376
	v_add_f32_e32 v164, v155, v166
	v_mul_f32_e32 v164, 0xbfb8aa3b, v164
	v_exp_f32_e32 v164, v164
	v_rcp_f32_e32 v2, v3
	s_nop 0
	v_bfe_u32 v167, v2, 16, 1
	v_add_f32_e32 v3, 1.0, v164
	v_add3_u32 v2, v2, v167, s63
	ds_write_b16_d16_hi v234, v2 offset:37888
	v_add_f32_e32 v164, v136, v166
	v_mul_f32_e32 v164, 0xbfb8aa3b, v164
	v_exp_f32_e32 v164, v164
	v_rcp_f32_e32 v2, v3
	s_nop 0
	v_bfe_u32 v167, v2, 16, 1
	v_add_f32_e32 v3, 1.0, v164
	v_add3_u32 v2, v2, v167, s63
	ds_write_b16_d16_hi v234, v2 offset:38400
	v_add_f32_e32 v164, v137, v166
	v_mul_f32_e32 v164, 0xbfb8aa3b, v164
	v_exp_f32_e32 v164, v164
	v_rcp_f32_e32 v2, v3
	s_nop 0
	v_bfe_u32 v167, v2, 16, 1
	v_add_f32_e32 v3, 1.0, v164
	v_add3_u32 v2, v2, v167, s63
	ds_write_b16_d16_hi v234, v2 offset:45056
; __device__ void phase_merge(const Params& p, int layer, char* smem) {
;     ...
;             for (int n = 0; n < 4; ++n) {
;               float bm = bmp[seg * 1024 + n * 16];
; #pragma unroll
;               for (int m = 0; m < 4; ++m)
; #pragma unroll
;                 for (int j = 0; j < 4; ++j) {
;                   GL[((m * 4 + n) * 4 + j) * 256] = f2bf(1.f / (1.f + __expf(-(acc[m][n][j] + bm))));
;                   acc[m][n][j] = 0.f;
;                 }
;             }
	v_add_f32_e32 v164, v138, v166
	v_mul_f32_e32 v164, 0xbfb8aa3b, v164
	v_exp_f32_e32 v164, v164
	v_rcp_f32_e32 v2, v3
	s_nop 0
	v_bfe_u32 v167, v2, 16, 1
	v_add_f32_e32 v3, 1.0, v164
	v_add3_u32 v2, v2, v167, s63
	ds_write_b16_d16_hi v234, v2 offset:45568
	v_add_f32_e32 v164, v139, v166
	v_mul_f32_e32 v164, 0xbfb8aa3b, v164
	v_exp_f32_e32 v164, v164
	v_rcp_f32_e32 v2, v3
	s_nop 0
	v_bfe_u32 v167, v2, 16, 1
	v_add_f32_e32 v3, 1.0, v164
	v_add3_u32 v2, v2, v167, s63
	ds_write_b16_d16_hi v234, v2 offset:46080
	v_add_f32_e32 v164, v120, v166
	v_mul_f32_e32 v164, 0xbfb8aa3b, v164
	v_exp_f32_e32 v164, v164
	v_rcp_f32_e32 v2, v3
	s_nop 0
	v_bfe_u32 v167, v2, 16, 1
	v_add_f32_e32 v3, 1.0, v164
	v_add3_u32 v2, v2, v167, s63
	ds_write_b16_d16_hi v234, v2 offset:46592
	v_add_f32_e32 v164, v121, v166
	v_mul_f32_e32 v164, 0xbfb8aa3b, v164
	v_exp_f32_e32 v164, v164
	v_rcp_f32_e32 v2, v3
	s_nop 0
	v_bfe_u32 v167, v2, 16, 1
	v_add_f32_e32 v3, 1.0, v164
	v_add3_u32 v2, v2, v167, s63
	ds_write_b16_d16_hi v234, v2 offset:53248
	v_add_f32_e32 v164, v122, v166
	v_mul_f32_e32 v164, 0xbfb8aa3b, v164
	v_exp_f32_e32 v164, v164
	v_rcp_f32_e32 v2, v3
	s_nop 0
	v_bfe_u32 v167, v2, 16, 1
	v_add_f32_e32 v3, 1.0, v164
	v_add3_u32 v2, v2, v167, s63
	ds_write_b16_d16_hi v234, v2 offset:53760
	v_add_f32_e32 v164, v123, v166
	v_mul_f32_e32 v164, 0xbfb8aa3b, v164
	v_exp_f32_e32 v164, v164
	v_rcp_f32_e32 v2, v3
	s_nop 0
	v_bfe_u32 v167, v2, 16, 1
	v_add_f32_e32 v3, 1.0, v164
	v_add3_u32 v2, v2, v167, s63
	ds_write_b16_d16_hi v234, v2 offset:54272
	v_add_f32_e32 v164, v100, v166
	v_mul_f32_e32 v164, 0xbfb8aa3b, v164
	v_exp_f32_e32 v164, v164
	v_rcp_f32_e32 v2, v3
	s_nop 0
	v_bfe_u32 v167, v2, 16, 1
	v_add_f32_e32 v3, 1.0, v164
	v_add3_u32 v2, v2, v167, s63
	ds_write_b16_d16_hi v234, v2 offset:54784
	v_add_f32_e32 v164, v101, v166
	v_mul_f32_e32 v164, 0xbfb8aa3b, v164
	v_exp_f32_e32 v164, v164
	v_rcp_f32_e32 v2, v3
	s_nop 0
	v_bfe_u32 v167, v2, 16, 1
	v_add_f32_e32 v3, 1.0, v164
	v_add3_u32 v2, v2, v167, s63
	ds_write_b16_d16_hi v234, v2 offset:61440
	v_add_f32_e32 v164, v102, v166
	v_mul_f32_e32 v164, 0xbfb8aa3b, v164
	v_exp_f32_e32 v164, v164
	v_rcp_f32_e32 v2, v3
	s_nop 0
	v_bfe_u32 v167, v2, 16, 1
	v_add_f32_e32 v3, 1.0, v164
	v_add3_u32 v2, v2, v167, s63
	ds_write_b16_d16_hi v234, v2 offset:61952
	v_add_f32_e32 v164, v103, v166
	v_mul_f32_e32 v164, 0xbfb8aa3b, v164
	v_exp_f32_e32 v164, v164
	v_rcp_f32_e32 v2, v3
	s_nop 0
	v_bfe_u32 v166, v2, 16, 1
	v_add_f32_e32 v3, 1.0, v164
	v_add3_u32 v2, v2, v166, s63
	ds_write_b16_d16_hi v234, v2 offset:62464
	s_waitcnt vmcnt(0)
	v_add_f32_e32 v164, v148, v1
	v_mul_f32_e32 v164, 0xbfb8aa3b, v164
	v_exp_f32_e32 v164, v164
	v_rcp_f32_e32 v2, v3
	s_nop 0
	v_bfe_u32 v166, v2, 16, 1
	v_add_f32_e32 v3, 1.0, v164
	v_add3_u32 v2, v2, v166, s63
	ds_write_b16_d16_hi v234, v2 offset:62976
	v_add_f32_e32 v164, v149, v1
	v_mul_f32_e32 v164, 0xbfb8aa3b, v164
	v_exp_f32_e32 v164, v164
	v_rcp_f32_e32 v2, v3
	s_nop 0
	v_bfe_u32 v166, v2, 16, 1
	v_add_f32_e32 v3, 1.0, v164
	v_add3_u32 v2, v2, v166, s63
	ds_write_b16_d16_hi v234, v2 offset:38912
	v_add_f32_e32 v164, v150, v1
	v_mul_f32_e32 v164, 0xbfb8aa3b, v164
	v_exp_f32_e32 v164, v164
	v_rcp_f32_e32 v2, v3
	s_nop 0
	v_bfe_u32 v166, v2, 16, 1
	v_add_f32_e32 v3, 1.0, v164
	v_add3_u32 v2, v2, v166, s63
	ds_write_b16_d16_hi v234, v2 offset:39424
	v_add_f32_e32 v164, v151, v1
	v_mul_f32_e32 v164, 0xbfb8aa3b, v164
	v_exp_f32_e32 v164, v164
	v_rcp_f32_e32 v2, v3
	s_nop 0
	v_bfe_u32 v166, v2, 16, 1
	v_add_f32_e32 v3, 1.0, v164
	v_add3_u32 v2, v2, v166, s63
	ds_write_b16_d16_hi v234, v2 offset:39936
	v_add_f32_e32 v164, v132, v1
	v_mul_f32_e32 v164, 0xbfb8aa3b, v164
	v_exp_f32_e32 v164, v164
	v_rcp_f32_e32 v2, v3
	s_nop 0
	v_bfe_u32 v166, v2, 16, 1
	v_add_f32_e32 v3, 1.0, v164
	v_add3_u32 v2, v2, v166, s63
	ds_write_b16_d16_hi v234, v2 offset:40448
	v_add_f32_e32 v164, v133, v1
	v_mul_f32_e32 v164, 0xbfb8aa3b, v164
	v_exp_f32_e32 v164, v164
	v_rcp_f32_e32 v2, v3
	s_nop 0
	v_bfe_u32 v166, v2, 16, 1
	v_add_f32_e32 v3, 1.0, v164
	v_add3_u32 v2, v2, v166, s63
	ds_write_b16_d16_hi v234, v2 offset:47104
	v_add_f32_e32 v164, v134, v1
	v_mul_f32_e32 v164, 0xbfb8aa3b, v164
	v_exp_f32_e32 v164, v164
	v_rcp_f32_e32 v2, v3
	s_nop 0
	v_bfe_u32 v166, v2, 16, 1
	v_add_f32_e32 v3, 1.0, v164
	v_add3_u32 v2, v2, v166, s63
	ds_write_b16_d16_hi v234, v2 offset:47616
	v_add_f32_e32 v164, v135, v1
	v_mul_f32_e32 v164, 0xbfb8aa3b, v164
	v_exp_f32_e32 v164, v164
	v_rcp_f32_e32 v2, v3
	s_nop 0
	v_bfe_u32 v166, v2, 16, 1
	v_add_f32_e32 v3, 1.0, v164
	v_add3_u32 v2, v2, v166, s63
	ds_write_b16_d16_hi v234, v2 offset:48128
	v_add_f32_e32 v164, v116, v1
	v_mul_f32_e32 v164, 0xbfb8aa3b, v164
	v_exp_f32_e32 v164, v164
	v_rcp_f32_e32 v2, v3
	s_nop 0
	v_bfe_u32 v166, v2, 16, 1
	v_add_f32_e32 v3, 1.0, v164
	v_add3_u32 v2, v2, v166, s63
	ds_write_b16_d16_hi v234, v2 offset:48640
	v_add_f32_e32 v164, v117, v1
	v_mul_f32_e32 v164, 0xbfb8aa3b, v164
	v_exp_f32_e32 v164, v164
	v_rcp_f32_e32 v2, v3
	s_nop 0
	v_bfe_u32 v166, v2, 16, 1
	v_add_f32_e32 v3, 1.0, v164
	v_add3_u32 v2, v2, v166, s63
	ds_write_b16_d16_hi v234, v2 offset:55296
	v_add_f32_e32 v164, v118, v1
	v_mul_f32_e32 v164, 0xbfb8aa3b, v164
	v_exp_f32_e32 v164, v164
	v_rcp_f32_e32 v2, v3
	s_nop 0
	v_bfe_u32 v166, v2, 16, 1
	v_add_f32_e32 v3, 1.0, v164
	v_add3_u32 v2, v2, v166, s63
	ds_write_b16_d16_hi v234, v2 offset:55808
	v_add_f32_e32 v164, v119, v1
	v_mul_f32_e32 v164, 0xbfb8aa3b, v164
	v_exp_f32_e32 v164, v164
	v_rcp_f32_e32 v2, v3
	s_nop 0
	v_bfe_u32 v166, v2, 16, 1
	v_add_f32_e32 v3, 1.0, v164
	v_add3_u32 v2, v2, v166, s63
	ds_write_b16_d16_hi v234, v2 offset:56320
	v_add_f32_e32 v164, v104, v1
	v_mul_f32_e32 v164, 0xbfb8aa3b, v164
	v_exp_f32_e32 v164, v164
	v_rcp_f32_e32 v2, v3
	s_nop 0
	v_bfe_u32 v166, v2, 16, 1
	v_add_f32_e32 v3, 1.0, v164
	v_add3_u32 v2, v2, v166, s63
	ds_write_b16_d16_hi v234, v2 offset:56832
	v_add_f32_e32 v164, v105, v1
	v_mul_f32_e32 v164, 0xbfb8aa3b, v164
	v_exp_f32_e32 v164, v164
	v_rcp_f32_e32 v2, v3
	s_nop 0
	v_bfe_u32 v166, v2, 16, 1
	v_add_f32_e32 v3, 1.0, v164
	v_add3_u32 v2, v2, v166, s63
	ds_write_b16_d16_hi v234, v2 offset:63488
	v_add_f32_e32 v164, v106, v1
	v_mul_f32_e32 v164, 0xbfb8aa3b, v164
	v_exp_f32_e32 v164, v164
	v_rcp_f32_e32 v2, v3
	s_nop 0
	v_bfe_u32 v166, v2, 16, 1
	v_add_f32_e32 v3, 1.0, v164
	v_add3_u32 v2, v2, v166, s63
	ds_write_b16_d16_hi v234, v2 offset:64000
	v_add_f32_e32 v1, v107, v1
	v_mul_f32_e32 v1, 0xbfb8aa3b, v1
	v_exp_f32_e32 v1, v1
	v_rcp_f32_e32 v2, v3
	s_nop 0
	v_bfe_u32 v3, v2, 16, 1
	v_add3_u32 v2, v2, v3, s63
	v_add_f32_e32 v3, 1.0, v1
	ds_write_b16_d16_hi v234, v2 offset:64512
	v_mov_b32_e32 v1, v0
	v_mov_b32_e32 v2, v0
	v_rcp_f32_e32 v3, v3
	s_nop 0
	v_bfe_u32 v164, v3, 16, 1
	v_add3_u32 v3, v3, v164, s63
	ds_write_b16_d16_hi v234, v3 offset:65024
	s_mov_b64 s[4:5], -1

; template <int DH, int MODE>
; __device__ void attn_item(const Params& p, int layer, int b, int blk, int head, char* smem) {
;     ...
;   {
;     constexpr int OST = DH + 4;
;     constexpr int CPR = DH / 8;
;     constexpr int NCH = 128 * CPR / 256;
;     float* Of = reinterpret_cast<float*>(smem);
;     uint4 gt[NCH];
; #pragma unroll
;     for (int i = 0; i < NCH; ++i) {
;       int q = tid + 256 * i, r = q / CPR, c = (q % CPR) * 8;
;       gt[i] = *reinterpret_cast<const uint4*>(P + (tq0 + r) * NP + gcol + c);
;     }
;     float lis[2][4];
; #pragma unroll
;     for (int m = 0; m < 2; ++m)
; #pragma unroll
;       for (int j = 0; j < 4; ++j) lis[m][j] = (MODE == 0) ? linv_s[wid * 32 + m * 16 + fq * 4 + j] : 1.f;
;     if (MODE == 0) __syncthreads();
; #pragma unroll
;     for (int m = 0; m < 2; ++m)
; #pragma unroll
;       for (int j = 0; j < 4; ++j) {
;         int r = wid * 32 + m * 16 + fq * 4 + j;
; #pragma unroll
;         for (int n = 0; n < NDT; ++n) Of[r * OST + n * 16 + fr] = o[m][n][j] * lis[m][j];
;       }
;     __syncthreads();
; #pragma unroll
;     for (int i = 0; i < NCH; ++i) {
;       int q = tid + 256 * i, r = q / CPR, c = (q % CPR) * 8;
;       float4 m0 = *reinterpret_cast<const float4*>(Of + r * OST + c);
;       float4 m1 = *reinterpret_cast<const float4*>(Of + r * OST + c + 4);
.LBB0_470:
	s_ashr_i32 s13, s86, 31
	s_add_u32 s12, s28, s86
	s_addc_u32 s13, s29, s13
	s_lshl_b32 s14, s83, 1
	s_add_u32 s16, s50, s14
	s_addc_u32 s17, s51, 0
	v_lshl_add_u64 v[2:3], s[20:21], 0, v[134:135]
	v_mov_b64_e32 v[4:5], s[16:17]
	v_mad_u64_u32 v[0:1], s[16:17], v2, s63, v[4:5]
	v_mad_i32_i24 v1, v3, s63, v1
	s_waitcnt vmcnt(12)
	v_lshl_add_u64 v[76:77], v[0:1], 0, v[138:139]
	v_add_u32_e32 v0, 0x100, v161
	v_ashrrev_i32_e32 v1, 31, v0
	v_lshrrev_b32_e32 v1, 28, v1
	v_add_u32_e32 v1, v0, v1
	v_ashrrev_i32_e32 v8, 4, v1
	v_and_b32_e32 v1, -16, v1
	s_waitcnt vmcnt(5)
	v_sub_u32_e32 v99, v0, v1
	v_lshlrev_b32_e32 v0, 3, v99
	v_ashrrev_i32_e32 v1, 31, v0
	s_waitcnt vmcnt(3)
	v_lshlrev_b64 v[92:93], 1, v[0:1]
	v_add_u32_e32 v0, 0x200, v161
	v_ashrrev_i32_e32 v1, 31, v0
	v_lshrrev_b32_e32 v1, 28, v1
	v_add_u32_e32 v1, v0, v1
	v_ashrrev_i32_e32 v9, 31, v8
	v_ashrrev_i32_e32 v94, 4, v1
	v_and_b32_e32 v1, -16, v1
	v_lshl_add_u64 v[10:11], s[20:21], 0, v[8:9]
	v_sub_u32_e32 v9, v0, v1
	v_lshlrev_b32_e32 v0, 3, v9
	v_ashrrev_i32_e32 v1, 31, v0
	v_lshlrev_b64 v[100:101], 1, v[0:1]
	v_add_u32_e32 v0, 0x300, v161
	v_ashrrev_i32_e32 v1, 31, v0
	v_lshrrev_b32_e32 v1, 28, v1
	v_add_u32_e32 v1, v0, v1
	v_ashrrev_i32_e32 v102, 4, v1
	v_and_b32_e32 v1, -16, v1
	v_sub_u32_e32 v128, v0, v1
	v_lshlrev_b32_e32 v0, 3, v128
	v_ashrrev_i32_e32 v1, 31, v0
	s_waitcnt vmcnt(0)
	v_lshlrev_b64 v[106:107], 1, v[0:1]
	v_add_u32_e32 v0, 0x400, v161
	v_ashrrev_i32_e32 v1, 31, v0
	v_lshrrev_b32_e32 v1, 28, v1
	v_add_u32_e32 v1, v0, v1
	v_ashrrev_i32_e32 v103, 31, v102
	v_ashrrev_i32_e32 v108, 4, v1
	v_and_b32_e32 v1, -16, v1
	v_lshl_add_u64 v[104:105], s[20:21], 0, v[102:103]
	v_sub_u32_e32 v103, v0, v1
	v_lshlrev_b32_e32 v0, 3, v103
	v_ashrrev_i32_e32 v1, 31, v0
	v_lshlrev_b64 v[112:113], 1, v[0:1]
	v_add_u32_e32 v0, 0x500, v161
	v_ashrrev_i32_e32 v1, 31, v0
	v_lshrrev_b32_e32 v1, 28, v1
	v_add_u32_e32 v1, v0, v1
	v_ashrrev_i32_e32 v109, 31, v108
	v_ashrrev_i32_e32 v114, 4, v1
	v_and_b32_e32 v1, -16, v1
	v_mad_u64_u32 v[6:7], s[16:17], v10, s63, v[4:5]
	v_ashrrev_i32_e32 v95, 31, v94
	v_lshl_add_u64 v[110:111], s[20:21], 0, v[108:109]
	v_sub_u32_e32 v109, v0, v1
	v_mad_i32_i24 v7, v11, s63, v7
	v_lshl_add_u64 v[96:97], s[20:21], 0, v[94:95]
	v_lshlrev_b32_e32 v0, 3, v109
	v_lshl_add_u64 v[78:79], v[6:7], 0, v[92:93]
	v_mad_u64_u32 v[6:7], s[16:17], v96, s63, v[4:5]
	v_ashrrev_i32_e32 v1, 31, v0
	v_mad_i32_i24 v7, v97, s63, v7
	v_lshlrev_b64 v[118:119], 1, v[0:1]
	v_add_u32_e32 v0, 0x600, v161
	v_lshl_add_u64 v[80:81], v[6:7], 0, v[100:101]
	v_mad_u64_u32 v[6:7], s[16:17], v104, s63, v[4:5]
	v_ashrrev_i32_e32 v1, 31, v0
	v_mad_i32_i24 v7, v105, s63, v7
	v_lshrrev_b32_e32 v1, 28, v1
	v_lshl_add_u64 v[82:83], v[6:7], 0, v[106:107]
	v_mad_u64_u32 v[6:7], s[16:17], v110, s63, v[4:5]
	v_ashrrev_i32_e32 v115, 31, v114
	v_add_u32_e32 v1, v0, v1
	v_mad_i32_i24 v7, v111, s63, v7
	v_lshl_add_u64 v[116:117], s[20:21], 0, v[114:115]
	v_ashrrev_i32_e32 v120, 4, v1
	v_and_b32_e32 v1, -16, v1
	v_lshl_add_u64 v[84:85], v[6:7], 0, v[112:113]
	v_mad_u64_u32 v[6:7], s[16:17], v116, s63, v[4:5]
	v_sub_u32_e32 v115, v0, v1
	v_ashrrev_i32_e32 v121, 31, v120
	v_mad_i32_i24 v7, v117, s63, v7
	v_lshlrev_b32_e32 v0, 3, v115
	v_lshl_add_u64 v[122:123], s[20:21], 0, v[120:121]
	v_lshl_add_u64 v[86:87], v[6:7], 0, v[118:119]
	v_mad_u64_u32 v[6:7], s[16:17], v122, s63, v[4:5]
	v_ashrrev_i32_e32 v1, 31, v0
	v_mad_i32_i24 v7, v123, s63, v7
	v_lshlrev_b64 v[124:125], 1, v[0:1]
	v_lshl_add_u64 v[0:1], v[6:7], 0, v[124:125]
	v_add_u32_e32 v6, 0x700, v161
	v_ashrrev_i32_e32 v7, 31, v6
	v_lshrrev_b32_e32 v7, 28, v7
	v_add_u32_e32 v7, v6, v7
	v_ashrrev_i32_e32 v126, 4, v7
	v_and_b32_e32 v7, -16, v7
	v_sub_u32_e32 v121, v6, v7
	v_lshlrev_b32_e32 v6, 3, v121
	v_ashrrev_i32_e32 v127, 31, v126
	v_lshl_add_u64 v[88:89], s[20:21], 0, v[126:127]
	v_ashrrev_i32_e32 v7, 31, v6
	v_mad_u64_u32 v[4:5], s[16:17], v88, s63, v[4:5]
	v_lshlrev_b64 v[90:91], 1, v[6:7]
	v_lshl_or_b32 v6, v137, 2, v130
	v_mad_i32_i24 v5, v89, s63, v5
	v_mul_lo_u32 v6, v6, s69
	v_lshl_add_u64 v[4:5], v[4:5], 0, v[90:91]
	v_lshl_add_u32 v95, v162, 2, v6
	s_barrier
	ds_write2_b32 v95, v12, v48 offset1:16
	ds_write2_b32 v95, v52, v56 offset0:32 offset1:48
	ds_write2_b32 v95, v60, v64 offset0:64 offset1:80
	ds_write2_b32 v95, v68, v72 offset0:96 offset1:112
	ds_write2_b32 v95, v13, v49 offset0:132 offset1:148
	ds_write2_b32 v95, v53, v57 offset0:164 offset1:180
	ds_write2_b32 v95, v61, v65 offset0:196 offset1:212
	ds_write2_b32 v95, v69, v73 offset0:228 offset1:244
	v_add_u32_e32 v12, 0x400, v95
	v_add_co_u32_e32 v4, vcc, s80, v4
	ds_write2_b32 v12, v14, v50 offset0:8 offset1:24
	ds_write2_b32 v12, v54, v58 offset0:40 offset1:56
	v_addc_co_u32_e32 v5, vcc, 0, v5, vcc
	global_load_dwordx4 v[4:7], v[4:5], off offset:512
	ds_write2_b32 v12, v62, v66 offset0:72 offset1:88
	ds_write2_b32 v12, v70, v74 offset0:104 offset1:120
	ds_write2_b32 v12, v15, v51 offset0:140 offset1:156
	ds_write2_b32 v12, v55, v59 offset0:172 offset1:188
	ds_write2_b32 v12, v63, v67 offset0:204 offset1:220
	ds_write2_b32 v12, v71, v75 offset0:236 offset1:252
	v_add_u32_e32 v12, 0x2000, v95
	ds_write2_b32 v12, v16, v20 offset0:64 offset1:80
	ds_write2_b32 v12, v24, v36 offset0:96 offset1:112
	ds_write2_b32 v12, v28, v40 offset0:128 offset1:144
	ds_write2_b32 v12, v44, v32 offset0:160 offset1:176
	ds_write2_b32 v12, v17, v21 offset0:196 offset1:212
	ds_write2_b32 v12, v25, v37 offset0:228 offset1:244
	v_add_u32_e32 v12, 0x2400, v95
	s_add_u32 s12, s12, s14
	ds_write2_b32 v12, v29, v41 offset0:4 offset1:20
	ds_write2_b32 v12, v45, v33 offset0:36 offset1:52
; __device__ __forceinline__ unsigned pack2(float a, float b) { return (unsigned)f2bf(a) | ((unsigned)f2bf(b) << 16); }
; __device__ __forceinline__ float bflo(unsigned w) { return __uint_as_float(w << 16); }
; __device__ __forceinline__ float bfhi(unsigned w) { return __uint_as_float(w & 0xffff0000u); }
; __device__ __forceinline__ float silu_f(float g) { return g / (1.f + __expf(-g)); }
; template <int DH, int MODE>
; __device__ void attn_item(const Params& p, int layer, int b, int blk, int head, char* smem) {
;     ...
;     uint4 gt[NCH];
; #pragma unroll
;     for (int i = 0; i < NCH; ++i) {
;       int q = tid + 256 * i, r = q / CPR, c = (q % CPR) * 8;
;       gt[i] = *reinterpret_cast<const uint4*>(P + (tq0 + r) * NP + gcol + c);
;     }
;     float lis[2][4];
; #pragma unroll
;     for (int m = 0; m < 2; ++m)
; #pragma unroll
;       for (int j = 0; j < 4; ++j) lis[m][j] = (MODE == 0) ? linv_s[wid * 32 + m * 16 + fq * 4 + j] : 1.f;
;     if (MODE == 0) __syncthreads();
; #pragma unroll
;     for (int m = 0; m < 2; ++m)
; #pragma unroll
;       for (int j = 0; j < 4; ++j) {
;         int r = wid * 32 + m * 16 + fq * 4 + j;
; #pragma unroll
;         for (int n = 0; n < NDT; ++n) Of[r * OST + n * 16 + fr] = o[m][n][j] * lis[m][j];
;       }
;     __syncthreads();
; #pragma unroll
;     for (int i = 0; i < NCH; ++i) {
;       int q = tid + 256 * i, r = q / CPR, c = (q % CPR) * 8;
;       float4 m0 = *reinterpret_cast<const float4*>(Of + r * OST + c);
;       float4 m1 = *reinterpret_cast<const float4*>(Of + r * OST + c + 4);
;       float mm[8] = {m0.x, m0.y, m0.z, m0.w, m1.x, m1.y, m1.z, m1.w};
;       unsigned gw[4] = {gt[i].x, gt[i].y, gt[i].z, gt[i].w};
;       unsigned ow[4];
; #pragma unroll
;       for (int e = 0; e < 4; ++e)
;         ow[e] = pack2(mm[2 * e] * silu_f(bflo(gw[e])), mm[2 * e + 1] * silu_f(bfhi(gw[e])));
	ds_write2_b32 v12, v18, v22 offset0:72 offset1:88
	ds_write2_b32 v12, v26, v38 offset0:104 offset1:120
	ds_write2_b32 v12, v30, v42 offset0:136 offset1:152
	ds_write2_b32 v12, v46, v34 offset0:168 offset1:184
	ds_write2_b32 v12, v19, v23 offset0:204 offset1:220
	ds_write2_b32 v12, v27, v39 offset0:236 offset1:252
	v_add_u32_e32 v12, 0x2800, v95
	s_addc_u32 s13, s13, 0
	ds_write2_b32 v12, v31, v43 offset0:12 offset1:28
	ds_write2_b32 v12, v47, v35 offset0:44 offset1:60
	v_mul_lo_u32 v12, v134, s69
	v_mov_b64_e32 v[14:15], s[12:13]
	v_lshl_add_u32 v98, v136, 2, v12
	v_mad_u64_u32 v[12:13], s[12:13], v2, s70, v[14:15]
	v_mul_lo_u32 v2, v8, s69
	v_mad_i32_i24 v13, v3, s70, v13
	v_lshl_add_u32 v95, v99, 5, v2
	v_mad_u64_u32 v[2:3], s[12:13], v10, s70, v[14:15]
	v_mad_i32_i24 v3, v11, s70, v3
	v_lshl_add_u64 v[26:27], v[2:3], 0, v[92:93]
	v_mul_lo_u32 v2, v94, s69
	v_lshl_add_u32 v93, v9, 5, v2
	v_mad_u64_u32 v[2:3], s[12:13], v96, s70, v[14:15]
	v_mad_i32_i24 v3, v97, s70, v3
	v_lshl_add_u64 v[20:21], v[2:3], 0, v[100:101]
	v_mul_lo_u32 v2, v102, s69
	v_lshl_add_u32 v92, v128, 5, v2
	v_mad_u64_u32 v[2:3], s[12:13], v104, s70, v[14:15]
	v_mad_i32_i24 v3, v105, s70, v3
	v_lshl_add_u64 v[16:17], v[2:3], 0, v[106:107]
	v_mul_lo_u32 v2, v108, s69
	v_lshl_add_u32 v75, v103, 5, v2
	v_mad_u64_u32 v[2:3], s[12:13], v110, s70, v[14:15]
	v_mad_i32_i24 v3, v111, s70, v3
	v_lshl_add_u64 v[30:31], v[12:13], 0, v[138:139]
	v_lshl_add_u64 v[12:13], v[2:3], 0, v[112:113]
	v_mul_lo_u32 v2, v114, s69
	v_lshl_add_u32 v74, v109, 5, v2
	v_mad_u64_u32 v[2:3], s[12:13], v116, s70, v[14:15]
	v_mad_i32_i24 v3, v117, s70, v3
	v_lshl_add_u64 v[10:11], v[2:3], 0, v[118:119]
	v_mul_lo_u32 v2, v120, s69
	v_lshl_add_u32 v73, v115, 5, v2
	v_mad_u64_u32 v[2:3], s[12:13], v122, s70, v[14:15]
	v_mad_i32_i24 v3, v123, s70, v3
	v_add_co_u32_e32 v0, vcc, s80, v0
	v_lshl_add_u64 v[8:9], v[2:3], 0, v[124:125]
	v_mul_lo_u32 v2, v126, s69
	v_addc_co_u32_e32 v1, vcc, 0, v1, vcc
	v_lshl_add_u32 v72, v121, 5, v2
	global_load_dwordx4 v[0:3], v[0:1], off offset:512
	v_mad_u64_u32 v[14:15], s[12:13], v88, s70, v[14:15]
	v_mad_i32_i24 v15, v89, s70, v15
	v_lshl_add_u64 v[14:15], v[14:15], 0, v[90:91]
	s_waitcnt vmcnt(1)
	v_lshlrev_b32_e32 v22, 16, v5
	v_lshlrev_b32_e32 v23, 16, v4
	v_mul_f32_e32 v18, 0xbfb8aa3b, v23
	v_mul_f32_e32 v19, 0xbfb8aa3b, v22
	v_exp_f32_e32 v18, v18
	v_exp_f32_e32 v19, v19
	v_and_b32_e32 v24, 0xffff0000, v5
	v_and_b32_e32 v28, 0xffff0000, v4
	v_mul_f32_e32 v4, 0xbfb8aa3b, v28
	v_pk_add_f32 v[18:19], v[18:19], 1.0 op_sel_hi:[1,0]
	v_exp_f32_e32 v4, v4
	v_and_b32_e32 v34, 0xffff0000, v6
	v_rcp_f32_e32 v19, v19
	s_nop 0
	v_mul_f32_e32 v19, v22, v19
	v_mul_f32_e32 v5, 0xbfb8aa3b, v24
	v_exp_f32_e32 v5, v5
	s_nop 0
	v_pk_add_f32 v[4:5], v[4:5], 1.0 op_sel_hi:[1,0]
	v_rcp_f32_e32 v18, v18
	s_nop 0
	v_mul_f32_e32 v18, v23, v18
	v_lshlrev_b32_e32 v33, 16, v6
	v_rcp_f32_e32 v23, v5
	s_nop 0
	v_mul_f32_e32 v23, v24, v23
	v_lshlrev_b32_e32 v32, 16, v7
	v_mul_f32_e32 v24, 0xbfb8aa3b, v33
	v_mul_f32_e32 v25, 0xbfb8aa3b, v32
	v_exp_f32_e32 v24, v24
	v_exp_f32_e32 v25, v25
	v_rcp_f32_e32 v22, v4
	s_nop 0
	v_mul_f32_e32 v22, v28, v22
	v_and_b32_e32 v28, 0xffff0000, v7
	v_pk_add_f32 v[4:5], v[24:25], 1.0 op_sel_hi:[1,0]
	v_mul_f32_e32 v6, 0xbfb8aa3b, v34
	v_exp_f32_e32 v6, v6
	s_waitcnt vmcnt(0)
	v_lshlrev_b32_e32 v40, 16, v3
	v_lshlrev_b32_e32 v41, 16, v2
	v_rcp_f32_e32 v25, v5
	s_nop 0
	v_mul_f32_e32 v25, v32, v25
	v_mul_f32_e32 v7, 0xbfb8aa3b, v28
	v_exp_f32_e32 v7, v7
	s_nop 0
	v_pk_add_f32 v[6:7], v[6:7], 1.0 op_sel_hi:[1,0]
	v_rcp_f32_e32 v24, v4
	s_nop 0
	v_mul_f32_e32 v24, v33, v24
	v_rcp_f32_e32 v29, v7
	s_nop 0
	v_mul_f32_e32 v29, v28, v29
	v_lshlrev_b32_e32 v32, 16, v1
	v_lshlrev_b32_e32 v36, 16, v0
	v_mul_f32_e32 v4, 0xbfb8aa3b, v36
	v_mul_f32_e32 v5, 0xbfb8aa3b, v32
	v_exp_f32_e32 v4, v4
	v_exp_f32_e32 v5, v5
	v_rcp_f32_e32 v28, v6
	s_nop 0
	v_mul_f32_e32 v28, v34, v28
	v_and_b32_e32 v6, 0xffff0000, v1
	v_pk_add_f32 v[4:5], v[4:5], 1.0 op_sel_hi:[1,0]
	v_and_b32_e32 v34, 0xffff0000, v0
	v_mul_f32_e32 v0, 0xbfb8aa3b, v34
	v_exp_f32_e32 v0, v0
	v_and_b32_e32 v42, 0xffff0000, v3
	v_rcp_f32_e32 v33, v5
	s_nop 0
	v_mul_f32_e32 v33, v32, v33
	v_mul_f32_e32 v1, 0xbfb8aa3b, v6
	v_exp_f32_e32 v1, v1
	s_nop 0
	v_pk_add_f32 v[0:1], v[0:1], 1.0 op_sel_hi:[1,0]
	v_rcp_f32_e32 v32, v4
	s_nop 0
	v_mul_f32_e32 v32, v36, v32
	v_rcp_f32_e32 v35, v1
	s_nop 0
	v_mul_f32_e32 v35, v6, v35
	v_add_co_u32_e64 v4, s[12:13], s80, v86
	s_nop 0
	s_nop 0
	v_addc_co_u32_e64 v5, s[12:13], 0, v87, s[12:13]
	global_load_dwordx4 v[4:7], v[4:5], off offset:512
	v_mul_f32_e32 v36, 0xbfb8aa3b, v41
	v_mul_f32_e32 v37, 0xbfb8aa3b, v40
	v_exp_f32_e32 v36, v36
	v_exp_f32_e32 v37, v37
	v_rcp_f32_e32 v1, v0
	s_nop 0
	v_mul_f32_e32 v34, v34, v1
	v_and_b32_e32 v43, 0xffff0000, v2
	v_pk_add_f32 v[0:1], v[36:37], 1.0 op_sel_hi:[1,0]
	v_mul_f32_e32 v2, 0xbfb8aa3b, v43
	v_exp_f32_e32 v2, v2
	v_rcp_f32_e32 v37, v1
	s_nop 0
	v_mul_f32_e32 v37, v40, v37
	v_mul_f32_e32 v3, 0xbfb8aa3b, v42
	v_exp_f32_e32 v3, v3
	s_nop 0
	v_pk_add_f32 v[38:39], v[2:3], 1.0 op_sel_hi:[1,0]
	v_rcp_f32_e32 v36, v0
	s_nop 0
	v_mul_f32_e32 v36, v41, v36
	v_rcp_f32_e32 v39, v39
	s_nop 0
	v_mul_f32_e32 v39, v42, v39
	v_add_co_u32_e64 v0, s[12:13], s80, v84
	s_waitcnt vmcnt(0)
; __device__ __forceinline__ unsigned pack2(float a, float b) { return (unsigned)f2bf(a) | ((unsigned)f2bf(b) << 16); }
; __device__ __forceinline__ float bflo(unsigned w) { return __uint_as_float(w << 16); }
; __device__ __forceinline__ float bfhi(unsigned w) { return __uint_as_float(w & 0xffff0000u); }
; __device__ __forceinline__ float silu_f(float g) { return g / (1.f + __expf(-g)); }
; template <int DH, int MODE>
; __device__ void attn_item(const Params& p, int layer, int b, int blk, int head, char* smem) {
;     ...
; #pragma unroll
;     for (int i = 0; i < NCH; ++i) {
;       int q = tid + 256 * i, r = q / CPR, c = (q % CPR) * 8;
;       float4 m0 = *reinterpret_cast<const float4*>(Of + r * OST + c);
;       float4 m1 = *reinterpret_cast<const float4*>(Of + r * OST + c + 4);
;       float mm[8] = {m0.x, m0.y, m0.z, m0.w, m1.x, m1.y, m1.z, m1.w};
;       unsigned gw[4] = {gt[i].x, gt[i].y, gt[i].z, gt[i].w};
;       unsigned ow[4];
; #pragma unroll
;       for (int e = 0; e < 4; ++e)
;         ow[e] = pack2(mm[2 * e] * silu_f(bflo(gw[e])), mm[2 * e + 1] * silu_f(bfhi(gw[e])));
;       *reinterpret_cast<uint4*>(Y + (tq0 + r) * YW + ycol + c) = make_uint4(ow[0], ow[1], ow[2], ow[3]);
	v_lshlrev_b32_e32 v46, 16, v5
	v_lshlrev_b32_e32 v47, 16, v4
	v_mul_f32_e32 v40, 0xbfb8aa3b, v47
	v_mul_f32_e32 v41, 0xbfb8aa3b, v46
	v_exp_f32_e32 v40, v40
	v_exp_f32_e32 v41, v41
	v_addc_co_u32_e64 v1, s[12:13], 0, v85, s[12:13]
	v_rcp_f32_e32 v38, v38
	s_nop 0
	v_mul_f32_e32 v38, v43, v38
	v_pk_add_f32 v[40:41], v[40:41], 1.0 op_sel_hi:[1,0]
	v_and_b32_e32 v42, 0xffff0000, v5
	global_load_dwordx4 v[0:3], v[0:1], off offset:512
	v_and_b32_e32 v48, 0xffff0000, v4
	v_mul_f32_e32 v4, 0xbfb8aa3b, v48
	v_rcp_f32_e32 v41, v41
	s_nop 0
	v_mul_f32_e32 v41, v46, v41
	v_exp_f32_e32 v4, v4
	v_mul_f32_e32 v5, 0xbfb8aa3b, v42
	v_exp_f32_e32 v5, v5
	s_nop 0
	v_pk_add_f32 v[4:5], v[4:5], 1.0 op_sel_hi:[1,0]
	v_rcp_f32_e32 v40, v40
	s_nop 0
	v_mul_f32_e32 v40, v47, v40
	v_lshlrev_b32_e32 v49, 16, v6
	v_rcp_f32_e32 v43, v5
	s_nop 0
	v_mul_f32_e32 v43, v42, v43
	v_lshlrev_b32_e32 v46, 16, v7
	v_mul_f32_e32 v44, 0xbfb8aa3b, v49
	v_mul_f32_e32 v45, 0xbfb8aa3b, v46
	v_exp_f32_e32 v44, v44
	v_exp_f32_e32 v45, v45
	v_rcp_f32_e32 v42, v4
	s_nop 0
	v_mul_f32_e32 v42, v48, v42
	v_and_b32_e32 v47, 0xffff0000, v7
	v_pk_add_f32 v[4:5], v[44:45], 1.0 op_sel_hi:[1,0]
	v_and_b32_e32 v48, 0xffff0000, v6
	v_mul_f32_e32 v6, 0xbfb8aa3b, v48
	v_exp_f32_e32 v6, v6
	v_rcp_f32_e32 v45, v5
	s_nop 0
	v_mul_f32_e32 v45, v46, v45
	v_mul_f32_e32 v7, 0xbfb8aa3b, v47
	v_exp_f32_e32 v7, v7
	s_nop 0
	v_pk_add_f32 v[6:7], v[6:7], 1.0 op_sel_hi:[1,0]
	v_rcp_f32_e32 v44, v4
	s_nop 0
	v_mul_f32_e32 v44, v49, v44
	v_rcp_f32_e32 v4, v7
	s_nop 0
	v_mul_f32_e32 v47, v47, v4
	s_waitcnt vmcnt(0)
	v_lshlrev_b32_e32 v50, 16, v1
	v_lshlrev_b32_e32 v51, 16, v0
	v_mul_f32_e32 v4, 0xbfb8aa3b, v51
	v_mul_f32_e32 v5, 0xbfb8aa3b, v50
	v_exp_f32_e32 v4, v4
	v_exp_f32_e32 v5, v5
	v_rcp_f32_e32 v46, v6
	s_nop 0
	v_mul_f32_e32 v46, v48, v46
	v_and_b32_e32 v6, 0xffff0000, v1
	v_pk_add_f32 v[4:5], v[4:5], 1.0 op_sel_hi:[1,0]
	v_and_b32_e32 v54, 0xffff0000, v0
	v_mul_f32_e32 v0, 0xbfb8aa3b, v54
	v_exp_f32_e32 v0, v0
	v_lshlrev_b32_e32 v58, 16, v2
	v_rcp_f32_e32 v49, v5
	s_nop 0
	v_mul_f32_e32 v49, v50, v49
	v_mul_f32_e32 v1, 0xbfb8aa3b, v6
	v_exp_f32_e32 v1, v1
	s_nop 0
	v_pk_add_f32 v[0:1], v[0:1], 1.0 op_sel_hi:[1,0]
	v_rcp_f32_e32 v48, v4
	s_nop 0
	v_mul_f32_e32 v48, v51, v48
	v_lshlrev_b32_e32 v57, 16, v3
	v_rcp_f32_e32 v51, v1
	s_nop 0
	v_mul_f32_e32 v51, v6, v51
	v_add_co_u32_e64 v4, s[12:13], s80, v82
	s_nop 0
	s_nop 0
	v_addc_co_u32_e64 v5, s[12:13], 0, v83, s[12:13]
	global_load_dwordx4 v[4:7], v[4:5], off offset:512
	v_mul_f32_e32 v50, 0xbfb8aa3b, v58
	v_exp_f32_e32 v52, v50
	v_mul_f32_e32 v50, 0xbfb8aa3b, v57
	v_exp_f32_e32 v53, v50
	v_rcp_f32_e32 v50, v0
	s_nop 0
	v_mul_f32_e32 v50, v54, v50
	v_and_b32_e32 v56, 0xffff0000, v3
	v_pk_add_f32 v[0:1], v[52:53], 1.0 op_sel_hi:[1,0]
	v_and_b32_e32 v59, 0xffff0000, v2
	v_mul_f32_e32 v2, 0xbfb8aa3b, v59
	v_exp_f32_e32 v2, v2
	v_rcp_f32_e32 v53, v1
	s_nop 0
	v_mul_f32_e32 v53, v57, v53
	v_mul_f32_e32 v3, 0xbfb8aa3b, v56
	v_exp_f32_e32 v3, v3
	s_nop 0
	v_pk_add_f32 v[54:55], v[2:3], 1.0 op_sel_hi:[1,0]
	v_rcp_f32_e32 v52, v0
	s_nop 0
	v_mul_f32_e32 v52, v58, v52
	v_rcp_f32_e32 v55, v55
	s_nop 0
	v_mul_f32_e32 v55, v56, v55
	v_add_co_u32_e64 v0, s[12:13], s80, v80
	s_waitcnt vmcnt(0)
	v_lshlrev_b32_e32 v62, 16, v5
	v_lshlrev_b32_e32 v63, 16, v4
	v_mul_f32_e32 v56, 0xbfb8aa3b, v63
	v_mul_f32_e32 v57, 0xbfb8aa3b, v62
	v_exp_f32_e32 v56, v56
	v_exp_f32_e32 v57, v57
	v_addc_co_u32_e64 v1, s[12:13], 0, v81, s[12:13]
	v_rcp_f32_e32 v54, v54
	s_nop 0
	v_mul_f32_e32 v54, v59, v54
	v_pk_add_f32 v[56:57], v[56:57], 1.0 op_sel_hi:[1,0]
	v_and_b32_e32 v58, 0xffff0000, v5
	global_load_dwordx4 v[0:3], v[0:1], off offset:512
	v_and_b32_e32 v64, 0xffff0000, v4
	v_mul_f32_e32 v4, 0xbfb8aa3b, v64
	v_rcp_f32_e32 v57, v57
	s_nop 0
	v_mul_f32_e32 v57, v62, v57
	v_exp_f32_e32 v4, v4
	v_mul_f32_e32 v5, 0xbfb8aa3b, v58
	v_exp_f32_e32 v5, v5
	s_nop 0
	v_pk_add_f32 v[4:5], v[4:5], 1.0 op_sel_hi:[1,0]
	v_rcp_f32_e32 v56, v56
	s_nop 0
	v_mul_f32_e32 v56, v63, v56
	v_lshlrev_b32_e32 v65, 16, v6
	v_rcp_f32_e32 v59, v5
	s_nop 0
	v_mul_f32_e32 v59, v58, v59
	v_lshlrev_b32_e32 v62, 16, v7
	v_mul_f32_e32 v60, 0xbfb8aa3b, v65
	v_mul_f32_e32 v61, 0xbfb8aa3b, v62
	v_exp_f32_e32 v60, v60
	v_exp_f32_e32 v61, v61
	v_rcp_f32_e32 v58, v4
	s_nop 0
	v_mul_f32_e32 v58, v64, v58
	v_and_b32_e32 v63, 0xffff0000, v7
	v_pk_add_f32 v[4:5], v[60:61], 1.0 op_sel_hi:[1,0]
	v_and_b32_e32 v64, 0xffff0000, v6
	v_mul_f32_e32 v6, 0xbfb8aa3b, v64
	v_exp_f32_e32 v6, v6
	v_rcp_f32_e32 v61, v5
	s_nop 0
	v_mul_f32_e32 v61, v62, v61
	v_mul_f32_e32 v7, 0xbfb8aa3b, v63
	v_exp_f32_e32 v7, v7
	s_nop 0
	v_pk_add_f32 v[6:7], v[6:7], 1.0 op_sel_hi:[1,0]
	v_rcp_f32_e32 v60, v4
	s_nop 0
	v_mul_f32_e32 v60, v65, v60
	v_rcp_f32_e32 v4, v7
	s_nop 0
	v_mul_f32_e32 v63, v63, v4
	s_waitcnt vmcnt(0)
	v_lshlrev_b32_e32 v66, 16, v1
	v_lshlrev_b32_e32 v67, 16, v0
	v_mul_f32_e32 v4, 0xbfb8aa3b, v67
	v_mul_f32_e32 v5, 0xbfb8aa3b, v66
	v_exp_f32_e32 v4, v4
	v_exp_f32_e32 v5, v5
	v_and_b32_e32 v68, 0xffff0000, v1
	v_rcp_f32_e32 v62, v6
	s_nop 0
	v_mul_f32_e32 v62, v64, v62
	v_pk_add_f32 v[4:5], v[4:5], 1.0 op_sel_hi:[1,0]
	v_and_b32_e32 v69, 0xffff0000, v0
	v_mul_f32_e32 v0, 0xbfb8aa3b, v69
	v_exp_f32_e32 v6, v0
	v_and_b32_e32 v80, 0xffff0000, v2
	v_rcp_f32_e32 v1, v5
	s_nop 0
	v_mul_f32_e32 v1, v66, v1
	v_mul_f32_e32 v7, 0xbfb8aa3b, v68
	v_exp_f32_e32 v7, v7
	s_nop 0
	v_pk_add_f32 v[64:65], v[6:7], 1.0 op_sel_hi:[1,0]
	v_rcp_f32_e32 v0, v4
	s_nop 0
	v_mul_f32_e32 v0, v67, v0
	v_rcp_f32_e32 v65, v65
	s_nop 0
	v_mul_f32_e32 v65, v68, v65
	v_add_co_u32_e64 v4, s[12:13], s80, v78
	s_nop 0
	s_nop 0
	v_addc_co_u32_e64 v5, s[12:13], 0, v79, s[12:13]
	global_load_dwordx4 v[4:7], v[4:5], off offset:512
	v_lshlrev_b32_e32 v78, 16, v3
	v_lshlrev_b32_e32 v79, 16, v2
	v_mul_f32_e32 v66, 0xbfb8aa3b, v79
	v_mul_f32_e32 v67, 0xbfb8aa3b, v78
	v_exp_f32_e32 v66, v66
	v_exp_f32_e32 v67, v67
	v_and_b32_e32 v70, 0xffff0000, v3
	v_rcp_f32_e32 v64, v64
	s_nop 0
	v_mul_f32_e32 v64, v69, v64
	v_pk_add_f32 v[66:67], v[66:67], 1.0 op_sel_hi:[1,0]
	v_mul_f32_e32 v2, 0xbfb8aa3b, v80
	v_exp_f32_e32 v68, v2
	v_mul_f32_e32 v69, 0xbfb8aa3b, v70
	v_exp_f32_e32 v69, v69
	v_rcp_f32_e32 v3, v67
	s_nop 0
	v_mul_f32_e32 v3, v78, v3
	v_pk_add_f32 v[68:69], v[68:69], 1.0 op_sel_hi:[1,0]
	v_rcp_f32_e32 v2, v66
	s_nop 0
	v_mul_f32_e32 v2, v79, v2
	v_rcp_f32_e32 v67, v69
	s_nop 0
	v_mul_f32_e32 v67, v70, v67
	v_add_co_u32_e64 v70, s[12:13], s80, v76
	s_nop 0
	s_nop 0
	v_addc_co_u32_e64 v71, s[12:13], 0, v77, s[12:13]
	global_load_dwordx4 v[76:79], v[70:71], off offset:512
	v_rcp_f32_e32 v66, v68
	s_nop 0
	v_mul_f32_e32 v66, v80, v66
	s_waitcnt vmcnt(1)
	v_lshlrev_b32_e32 v82, 16, v5
	v_lshlrev_b32_e32 v83, 16, v4
	v_mul_f32_e32 v70, 0xbfb8aa3b, v83
	v_mul_f32_e32 v71, 0xbfb8aa3b, v82
	v_exp_f32_e32 v70, v70
	v_exp_f32_e32 v71, v71
	v_and_b32_e32 v80, 0xffff0000, v5
	v_and_b32_e32 v84, 0xffff0000, v4
	v_mul_f32_e32 v4, 0xbfb8aa3b, v84
	v_pk_add_f32 v[68:69], v[70:71], 1.0 op_sel_hi:[1,0]
	v_exp_f32_e32 v70, v4
	s_waitcnt lgkmcnt(0)
	s_barrier
; __device__ __forceinline__ unsigned pack2(float a, float b) { return (unsigned)f2bf(a) | ((unsigned)f2bf(b) << 16); }
; __device__ __forceinline__ float bflo(unsigned w) { return __uint_as_float(w << 16); }
; __device__ __forceinline__ float bfhi(unsigned w) { return __uint_as_float(w & 0xffff0000u); }
; __device__ __forceinline__ float silu_f(float g) { return g / (1.f + __expf(-g)); }
; template <int DH, int MODE>
; __device__ void attn_item(const Params& p, int layer, int b, int blk, int head, char* smem) {
;     ...
; #pragma unroll
;     for (int i = 0; i < NCH; ++i) {
;       int q = tid + 256 * i, r = q / CPR, c = (q % CPR) * 8;
;       float4 m0 = *reinterpret_cast<const float4*>(Of + r * OST + c);
;       float4 m1 = *reinterpret_cast<const float4*>(Of + r * OST + c + 4);
;       float mm[8] = {m0.x, m0.y, m0.z, m0.w, m1.x, m1.y, m1.z, m1.w};
;       unsigned gw[4] = {gt[i].x, gt[i].y, gt[i].z, gt[i].w};
;       unsigned ow[4];
; #pragma unroll
;       for (int e = 0; e < 4; ++e)
;         ow[e] = pack2(mm[2 * e] * silu_f(bflo(gw[e])), mm[2 * e + 1] * silu_f(bfhi(gw[e])));
;       *reinterpret_cast<uint4*>(Y + (tq0 + r) * YW + ycol + c) = make_uint4(ow[0], ow[1], ow[2], ow[3]);
;     }
	v_mul_f32_e32 v71, 0xbfb8aa3b, v80
	v_exp_f32_e32 v71, v71
	v_rcp_f32_e32 v5, v69
	s_nop 0
	v_mul_f32_e32 v5, v82, v5
	v_pk_add_f32 v[70:71], v[70:71], 1.0 op_sel_hi:[1,0]
	v_rcp_f32_e32 v4, v68
	s_nop 0
	v_mul_f32_e32 v4, v83, v4
	v_rcp_f32_e32 v69, v71
	s_nop 0
	v_mul_f32_e32 v69, v80, v69
	v_lshlrev_b32_e32 v82, 16, v7
	v_lshlrev_b32_e32 v85, 16, v6
	v_mul_f32_e32 v80, 0xbfb8aa3b, v85
	v_mul_f32_e32 v81, 0xbfb8aa3b, v82
	v_exp_f32_e32 v80, v80
	v_exp_f32_e32 v81, v81
	v_rcp_f32_e32 v68, v70
	s_nop 0
	v_mul_f32_e32 v68, v84, v68
	v_and_b32_e32 v83, 0xffff0000, v7
	v_pk_add_f32 v[70:71], v[80:81], 1.0 op_sel_hi:[1,0]
	v_and_b32_e32 v84, 0xffff0000, v6
	v_mul_f32_e32 v6, 0xbfb8aa3b, v84
	v_exp_f32_e32 v80, v6
	s_waitcnt vmcnt(0)
	v_and_b32_e32 v94, 0xffff0000, v78
	v_mul_f32_e32 v81, 0xbfb8aa3b, v83
	v_exp_f32_e32 v81, v81
	v_rcp_f32_e32 v7, v71
	s_nop 0
	v_mul_f32_e32 v7, v82, v7
	v_pk_add_f32 v[80:81], v[80:81], 1.0 op_sel_hi:[1,0]
	v_rcp_f32_e32 v6, v70
	s_nop 0
	v_mul_f32_e32 v6, v85, v6
	v_rcp_f32_e32 v71, v81
	s_nop 0
	v_mul_f32_e32 v71, v83, v71
	v_lshlrev_b32_e32 v86, 16, v77
	v_lshlrev_b32_e32 v87, 16, v76
	v_mul_f32_e32 v82, 0xbfb8aa3b, v87
	v_mul_f32_e32 v83, 0xbfb8aa3b, v86
	v_exp_f32_e32 v82, v82
	v_exp_f32_e32 v83, v83
	v_rcp_f32_e32 v70, v80
	s_nop 0
	v_mul_f32_e32 v70, v84, v70
	v_and_b32_e32 v88, 0xffff0000, v77
	v_pk_add_f32 v[80:81], v[82:83], 1.0 op_sel_hi:[1,0]
	v_and_b32_e32 v83, 0xffff0000, v76
	v_mul_f32_e32 v76, 0xbfb8aa3b, v83
	v_exp_f32_e32 v76, v76
	v_rcp_f32_e32 v85, v81
	s_nop 0
	v_mul_f32_e32 v85, v86, v85
	v_mul_f32_e32 v77, 0xbfb8aa3b, v88
	v_exp_f32_e32 v77, v77
	s_nop 0
	v_pk_add_f32 v[76:77], v[76:77], 1.0 op_sel_hi:[1,0]
	v_rcp_f32_e32 v84, v80
	s_nop 0
	v_mul_f32_e32 v84, v87, v84
	v_rcp_f32_e32 v87, v77
	s_nop 0
	v_mul_f32_e32 v87, v88, v87
	v_lshlrev_b32_e32 v90, 16, v78
	v_lshlrev_b32_e32 v82, 16, v79
	v_mul_f32_e32 v80, 0xbfb8aa3b, v90
	v_mul_f32_e32 v81, 0xbfb8aa3b, v82
	v_exp_f32_e32 v80, v80
	v_exp_f32_e32 v81, v81
	v_rcp_f32_e32 v86, v76
	s_nop 0
	v_mul_f32_e32 v86, v83, v86
	v_and_b32_e32 v83, 0xffff0000, v79
	v_pk_add_f32 v[76:77], v[80:81], 1.0 op_sel_hi:[1,0]
	v_mul_f32_e32 v78, 0xbfb8aa3b, v94
	v_exp_f32_e32 v78, v78
	v_rcp_f32_e32 v89, v77
	s_nop 0
	v_mul_f32_e32 v89, v82, v89
	v_mul_f32_e32 v79, 0xbfb8aa3b, v83
	v_exp_f32_e32 v79, v79
	s_nop 0
	v_pk_add_f32 v[80:81], v[78:79], 1.0 op_sel_hi:[1,0]
	v_rcp_f32_e32 v88, v76
	s_nop 0
	v_mul_f32_e32 v88, v90, v88
	v_rcp_f32_e32 v91, v81
	s_nop 0
	v_mul_f32_e32 v91, v83, v91
	ds_read_b128 v[76:79], v98
	v_rcp_f32_e32 v90, v80
	s_nop 0
	v_mul_f32_e32 v90, v94, v90
	ds_read_b128 v[80:83], v98 offset:16
	v_add_co_u32_e32 v30, vcc, s77, v30
	s_waitcnt lgkmcnt(1)
	v_mov_b32_e32 v96, v76
	v_mov_b32_e32 v97, v78
	v_pk_mul_f32 v[84:85], v[84:85], v[96:97]
	v_mov_b32_e32 v78, v77
	v_pk_mul_f32 v[76:77], v[86:87], v[78:79]
	v_and_b32_sdwa v78, v85, v155 dst_sel:DWORD dst_unused:UNUSED_PAD src0_sel:WORD_1 src1_sel:DWORD
	v_and_b32_sdwa v79, v84, v155 dst_sel:DWORD dst_unused:UNUSED_PAD src0_sel:WORD_1 src1_sel:DWORD
	v_add3_u32 v79, v84, v79, s68
	v_add3_u32 v78, v85, v78, s68
	v_and_b32_sdwa v84, v77, v155 dst_sel:DWORD dst_unused:UNUSED_PAD src0_sel:WORD_1 src1_sel:DWORD
	v_and_b32_sdwa v85, v76, v155 dst_sel:DWORD dst_unused:UNUSED_PAD src0_sel:WORD_1 src1_sel:DWORD
	v_add3_u32 v77, v77, v84, s68
	v_add3_u32 v76, v76, v85, s68
	v_and_b32_e32 v77, 0xffff0000, v77
	v_and_b32_e32 v76, 0xffff0000, v76
	v_or_b32_sdwa v77, v77, v78 dst_sel:DWORD dst_unused:UNUSED_PAD src0_sel:DWORD src1_sel:WORD_1
	v_or_b32_sdwa v76, v76, v79 dst_sel:DWORD dst_unused:UNUSED_PAD src0_sel:DWORD src1_sel:WORD_1
	s_waitcnt lgkmcnt(0)
	v_mov_b32_e32 v78, v80
	v_mov_b32_e32 v79, v82
	v_pk_mul_f32 v[78:79], v[88:89], v[78:79]
	v_mov_b32_e32 v82, v81
	v_pk_mul_f32 v[80:81], v[90:91], v[82:83]
	v_and_b32_sdwa v82, v79, v155 dst_sel:DWORD dst_unused:UNUSED_PAD src0_sel:WORD_1 src1_sel:DWORD
	v_and_b32_sdwa v83, v78, v155 dst_sel:DWORD dst_unused:UNUSED_PAD src0_sel:WORD_1 src1_sel:DWORD
	v_add3_u32 v78, v78, v83, s68
	v_add3_u32 v79, v79, v82, s68
	v_and_b32_sdwa v82, v81, v155 dst_sel:DWORD dst_unused:UNUSED_PAD src0_sel:WORD_1 src1_sel:DWORD
	v_and_b32_sdwa v83, v80, v155 dst_sel:DWORD dst_unused:UNUSED_PAD src0_sel:WORD_1 src1_sel:DWORD
	v_add3_u32 v81, v81, v82, s68
	v_add3_u32 v80, v80, v83, s68
	v_and_b32_e32 v81, 0xffff0000, v81
	v_and_b32_e32 v80, 0xffff0000, v80
	v_or_b32_sdwa v79, v81, v79 dst_sel:DWORD dst_unused:UNUSED_PAD src0_sel:DWORD src1_sel:WORD_1
	v_or_b32_sdwa v78, v80, v78 dst_sel:DWORD dst_unused:UNUSED_PAD src0_sel:DWORD src1_sel:WORD_1
	ds_read_b128 v[80:83], v95
	v_addc_co_u32_e32 v31, vcc, 0, v31, vcc
	global_store_dwordx4 v[30:31], v[76:79], off offset:2048
	ds_read_b128 v[76:79], v95 offset:16
	s_waitcnt lgkmcnt(1)
	v_mov_b32_e32 v30, v80
	v_mov_b32_e32 v31, v82
	v_pk_mul_f32 v[4:5], v[4:5], v[30:31]
	v_mov_b32_e32 v82, v81
	v_pk_mul_f32 v[30:31], v[68:69], v[82:83]
	v_and_b32_sdwa v68, v5, v155 dst_sel:DWORD dst_unused:UNUSED_PAD src0_sel:WORD_1 src1_sel:DWORD
	v_and_b32_sdwa v69, v4, v155 dst_sel:DWORD dst_unused:UNUSED_PAD src0_sel:WORD_1 src1_sel:DWORD
	v_add3_u32 v4, v4, v69, s68
	v_add3_u32 v5, v5, v68, s68
	v_and_b32_sdwa v68, v31, v155 dst_sel:DWORD dst_unused:UNUSED_PAD src0_sel:WORD_1 src1_sel:DWORD
	v_and_b32_sdwa v69, v30, v155 dst_sel:DWORD dst_unused:UNUSED_PAD src0_sel:WORD_1 src1_sel:DWORD
	v_add3_u32 v31, v31, v68, s68
	v_add3_u32 v30, v30, v69, s68
	v_and_b32_e32 v31, 0xffff0000, v31
	v_and_b32_e32 v30, 0xffff0000, v30
	v_or_b32_sdwa v5, v31, v5 dst_sel:DWORD dst_unused:UNUSED_PAD src0_sel:DWORD src1_sel:WORD_1
	v_or_b32_sdwa v4, v30, v4 dst_sel:DWORD dst_unused:UNUSED_PAD src0_sel:DWORD src1_sel:WORD_1
	s_waitcnt lgkmcnt(0)
; __device__ __forceinline__ unsigned pack2(float a, float b) { return (unsigned)f2bf(a) | ((unsigned)f2bf(b) << 16); }
; __device__ __forceinline__ float bflo(unsigned w) { return __uint_as_float(w << 16); }
; __device__ __forceinline__ float bfhi(unsigned w) { return __uint_as_float(w & 0xffff0000u); }
; __device__ __forceinline__ float silu_f(float g) { return g / (1.f + __expf(-g)); }
; template <int DH, int MODE>
; __device__ void attn_item(const Params& p, int layer, int b, int blk, int head, char* smem) {
;     ...
; #pragma unroll
;     for (int i = 0; i < NCH; ++i) {
;       int q = tid + 256 * i, r = q / CPR, c = (q % CPR) * 8;
;       float4 m0 = *reinterpret_cast<const float4*>(Of + r * OST + c);
;       float4 m1 = *reinterpret_cast<const float4*>(Of + r * OST + c + 4);
;       float mm[8] = {m0.x, m0.y, m0.z, m0.w, m1.x, m1.y, m1.z, m1.w};
;       unsigned gw[4] = {gt[i].x, gt[i].y, gt[i].z, gt[i].w};
;       unsigned ow[4];
; #pragma unroll
;       for (int e = 0; e < 4; ++e)
;         ow[e] = pack2(mm[2 * e] * silu_f(bflo(gw[e])), mm[2 * e + 1] * silu_f(bfhi(gw[e])));
;       *reinterpret_cast<uint4*>(Y + (tq0 + r) * YW + ycol + c) = make_uint4(ow[0], ow[1], ow[2], ow[3]);
;     }
	v_mov_b32_e32 v30, v76
	v_mov_b32_e32 v31, v78
	v_pk_mul_f32 v[6:7], v[6:7], v[30:31]
	v_mov_b32_e32 v78, v77
	v_pk_mul_f32 v[30:31], v[70:71], v[78:79]
	v_and_b32_sdwa v68, v7, v155 dst_sel:DWORD dst_unused:UNUSED_PAD src0_sel:WORD_1 src1_sel:DWORD
	v_and_b32_sdwa v69, v6, v155 dst_sel:DWORD dst_unused:UNUSED_PAD src0_sel:WORD_1 src1_sel:DWORD
	v_add3_u32 v6, v6, v69, s68
	v_add3_u32 v7, v7, v68, s68
	v_and_b32_sdwa v68, v31, v155 dst_sel:DWORD dst_unused:UNUSED_PAD src0_sel:WORD_1 src1_sel:DWORD
	v_and_b32_sdwa v69, v30, v155 dst_sel:DWORD dst_unused:UNUSED_PAD src0_sel:WORD_1 src1_sel:DWORD
	v_add3_u32 v31, v31, v68, s68
	v_add3_u32 v30, v30, v69, s68
	ds_read_b128 v[68:71], v93
	v_and_b32_e32 v31, 0xffff0000, v31
	v_and_b32_e32 v30, 0xffff0000, v30
	v_add_co_u32_e32 v26, vcc, s77, v26
	v_or_b32_sdwa v7, v31, v7 dst_sel:DWORD dst_unused:UNUSED_PAD src0_sel:DWORD src1_sel:WORD_1
	v_or_b32_sdwa v6, v30, v6 dst_sel:DWORD dst_unused:UNUSED_PAD src0_sel:DWORD src1_sel:WORD_1
	v_addc_co_u32_e32 v27, vcc, 0, v27, vcc
	global_store_dwordx4 v[26:27], v[4:7], off offset:2048
	s_waitcnt lgkmcnt(0)
	v_mov_b32_e32 v26, v68
	v_mov_b32_e32 v27, v70
	ds_read_b128 v[4:7], v93 offset:16
	v_pk_mul_f32 v[0:1], v[0:1], v[26:27]
	v_mov_b32_e32 v70, v69
	v_pk_mul_f32 v[26:27], v[64:65], v[70:71]
	v_and_b32_sdwa v30, v1, v155 dst_sel:DWORD dst_unused:UNUSED_PAD src0_sel:WORD_1 src1_sel:DWORD
	v_and_b32_sdwa v31, v0, v155 dst_sel:DWORD dst_unused:UNUSED_PAD src0_sel:WORD_1 src1_sel:DWORD
	v_add3_u32 v0, v0, v31, s68
	v_add3_u32 v1, v1, v30, s68
	v_and_b32_sdwa v30, v27, v155 dst_sel:DWORD dst_unused:UNUSED_PAD src0_sel:WORD_1 src1_sel:DWORD
	v_and_b32_sdwa v31, v26, v155 dst_sel:DWORD dst_unused:UNUSED_PAD src0_sel:WORD_1 src1_sel:DWORD
	v_add3_u32 v27, v27, v30, s68
	v_add3_u32 v26, v26, v31, s68
	v_and_b32_e32 v27, 0xffff0000, v27
	v_and_b32_e32 v26, 0xffff0000, v26
	v_or_b32_sdwa v1, v27, v1 dst_sel:DWORD dst_unused:UNUSED_PAD src0_sel:DWORD src1_sel:WORD_1
	v_or_b32_sdwa v0, v26, v0 dst_sel:DWORD dst_unused:UNUSED_PAD src0_sel:DWORD src1_sel:WORD_1
	s_waitcnt lgkmcnt(0)
	v_mov_b32_e32 v26, v4
	v_mov_b32_e32 v27, v6
	v_pk_mul_f32 v[2:3], v[2:3], v[26:27]
	v_mov_b32_e32 v6, v5
	v_pk_mul_f32 v[4:5], v[66:67], v[6:7]
	v_and_b32_sdwa v6, v3, v155 dst_sel:DWORD dst_unused:UNUSED_PAD src0_sel:WORD_1 src1_sel:DWORD
	v_and_b32_sdwa v7, v2, v155 dst_sel:DWORD dst_unused:UNUSED_PAD src0_sel:WORD_1 src1_sel:DWORD
	v_add3_u32 v2, v2, v7, s68
	v_add3_u32 v3, v3, v6, s68
	v_and_b32_sdwa v6, v5, v155 dst_sel:DWORD dst_unused:UNUSED_PAD src0_sel:WORD_1 src1_sel:DWORD
	v_and_b32_sdwa v7, v4, v155 dst_sel:DWORD dst_unused:UNUSED_PAD src0_sel:WORD_1 src1_sel:DWORD
	v_add3_u32 v5, v5, v6, s68
	v_add3_u32 v4, v4, v7, s68
	v_and_b32_e32 v5, 0xffff0000, v5
	v_and_b32_e32 v4, 0xffff0000, v4
	v_or_b32_sdwa v3, v5, v3 dst_sel:DWORD dst_unused:UNUSED_PAD src0_sel:DWORD src1_sel:WORD_1
	v_or_b32_sdwa v2, v4, v2 dst_sel:DWORD dst_unused:UNUSED_PAD src0_sel:DWORD src1_sel:WORD_1
	ds_read_b128 v[4:7], v92
	v_add_co_u32_e32 v20, vcc, s77, v20
	s_nop 1
	v_addc_co_u32_e32 v21, vcc, 0, v21, vcc
	global_store_dwordx4 v[20:21], v[0:3], off offset:2048
	s_waitcnt lgkmcnt(0)
	v_mov_b32_e32 v20, v4
	v_mov_b32_e32 v21, v6
	ds_read_b128 v[0:3], v92 offset:16
	v_pk_mul_f32 v[20:21], v[56:57], v[20:21]
	v_mov_b32_e32 v6, v5
	v_pk_mul_f32 v[4:5], v[58:59], v[6:7]
	v_and_b32_sdwa v6, v21, v155 dst_sel:DWORD dst_unused:UNUSED_PAD src0_sel:WORD_1 src1_sel:DWORD
	v_and_b32_sdwa v7, v20, v155 dst_sel:DWORD dst_unused:UNUSED_PAD src0_sel:WORD_1 src1_sel:DWORD
	v_add3_u32 v7, v20, v7, s68
	v_add3_u32 v6, v21, v6, s68
	v_and_b32_sdwa v20, v5, v155 dst_sel:DWORD dst_unused:UNUSED_PAD src0_sel:WORD_1 src1_sel:DWORD
	v_and_b32_sdwa v21, v4, v155 dst_sel:DWORD dst_unused:UNUSED_PAD src0_sel:WORD_1 src1_sel:DWORD
	v_add3_u32 v5, v5, v20, s68
	v_add3_u32 v4, v4, v21, s68
	v_and_b32_e32 v5, 0xffff0000, v5
	v_and_b32_e32 v4, 0xffff0000, v4
	v_or_b32_sdwa v5, v5, v6 dst_sel:DWORD dst_unused:UNUSED_PAD src0_sel:DWORD src1_sel:WORD_1
	v_or_b32_sdwa v4, v4, v7 dst_sel:DWORD dst_unused:UNUSED_PAD src0_sel:DWORD src1_sel:WORD_1
	s_waitcnt lgkmcnt(0)
	v_mov_b32_e32 v6, v0
	v_mov_b32_e32 v7, v2
	v_pk_mul_f32 v[6:7], v[60:61], v[6:7]
	v_mov_b32_e32 v2, v1
	v_pk_mul_f32 v[0:1], v[62:63], v[2:3]
	v_and_b32_sdwa v2, v7, v155 dst_sel:DWORD dst_unused:UNUSED_PAD src0_sel:WORD_1 src1_sel:DWORD
	v_and_b32_sdwa v3, v6, v155 dst_sel:DWORD dst_unused:UNUSED_PAD src0_sel:WORD_1 src1_sel:DWORD
	v_add3_u32 v3, v6, v3, s68
	v_add3_u32 v2, v7, v2, s68
	v_and_b32_sdwa v6, v1, v155 dst_sel:DWORD dst_unused:UNUSED_PAD src0_sel:WORD_1 src1_sel:DWORD
	v_and_b32_sdwa v7, v0, v155 dst_sel:DWORD dst_unused:UNUSED_PAD src0_sel:WORD_1 src1_sel:DWORD
	v_add3_u32 v1, v1, v6, s68
	v_add3_u32 v0, v0, v7, s68
	v_and_b32_e32 v1, 0xffff0000, v1
	v_and_b32_e32 v0, 0xffff0000, v0
	v_or_b32_sdwa v7, v1, v2 dst_sel:DWORD dst_unused:UNUSED_PAD src0_sel:DWORD src1_sel:WORD_1
	v_or_b32_sdwa v6, v0, v3 dst_sel:DWORD dst_unused:UNUSED_PAD src0_sel:DWORD src1_sel:WORD_1
	ds_read_b128 v[0:3], v75
	v_add_co_u32_e32 v16, vcc, s77, v16
	s_nop 1
	v_addc_co_u32_e32 v17, vcc, 0, v17, vcc
	global_store_dwordx4 v[16:17], v[4:7], off offset:2048
	s_waitcnt lgkmcnt(0)
; __device__ __forceinline__ unsigned pack2(float a, float b) { return (unsigned)f2bf(a) | ((unsigned)f2bf(b) << 16); }
; __device__ __forceinline__ float bflo(unsigned w) { return __uint_as_float(w << 16); }
; __device__ __forceinline__ float bfhi(unsigned w) { return __uint_as_float(w & 0xffff0000u); }
; __device__ __forceinline__ float silu_f(float g) { return g / (1.f + __expf(-g)); }
; template <int DH, int MODE>
; __device__ void attn_item(const Params& p, int layer, int b, int blk, int head, char* smem) {
;     ...
; #pragma unroll
;     for (int i = 0; i < NCH; ++i) {
;       int q = tid + 256 * i, r = q / CPR, c = (q % CPR) * 8;
;       float4 m0 = *reinterpret_cast<const float4*>(Of + r * OST + c);
;       float4 m1 = *reinterpret_cast<const float4*>(Of + r * OST + c + 4);
;       float mm[8] = {m0.x, m0.y, m0.z, m0.w, m1.x, m1.y, m1.z, m1.w};
;       unsigned gw[4] = {gt[i].x, gt[i].y, gt[i].z, gt[i].w};
;       unsigned ow[4];
; #pragma unroll
;       for (int e = 0; e < 4; ++e)
;         ow[e] = pack2(mm[2 * e] * silu_f(bflo(gw[e])), mm[2 * e + 1] * silu_f(bfhi(gw[e])));
;       *reinterpret_cast<uint4*>(Y + (tq0 + r) * YW + ycol + c) = make_uint4(ow[0], ow[1], ow[2], ow[3]);
;     }
	v_mov_b32_e32 v16, v0
	v_mov_b32_e32 v17, v2
	ds_read_b128 v[4:7], v75 offset:16
	v_pk_mul_f32 v[16:17], v[48:49], v[16:17]
	v_mov_b32_e32 v2, v1
	v_pk_mul_f32 v[0:1], v[50:51], v[2:3]
	v_and_b32_sdwa v2, v17, v155 dst_sel:DWORD dst_unused:UNUSED_PAD src0_sel:WORD_1 src1_sel:DWORD
	v_and_b32_sdwa v3, v16, v155 dst_sel:DWORD dst_unused:UNUSED_PAD src0_sel:WORD_1 src1_sel:DWORD
	v_add3_u32 v3, v16, v3, s68
	v_add3_u32 v2, v17, v2, s68
	v_and_b32_sdwa v16, v1, v155 dst_sel:DWORD dst_unused:UNUSED_PAD src0_sel:WORD_1 src1_sel:DWORD
	v_and_b32_sdwa v17, v0, v155 dst_sel:DWORD dst_unused:UNUSED_PAD src0_sel:WORD_1 src1_sel:DWORD
	v_add3_u32 v1, v1, v16, s68
	v_add3_u32 v0, v0, v17, s68
	v_and_b32_e32 v1, 0xffff0000, v1
	v_and_b32_e32 v0, 0xffff0000, v0
	v_or_b32_sdwa v1, v1, v2 dst_sel:DWORD dst_unused:UNUSED_PAD src0_sel:DWORD src1_sel:WORD_1
	v_or_b32_sdwa v0, v0, v3 dst_sel:DWORD dst_unused:UNUSED_PAD src0_sel:DWORD src1_sel:WORD_1
	s_waitcnt lgkmcnt(0)
	v_mov_b32_e32 v2, v4
	v_mov_b32_e32 v3, v6
	v_pk_mul_f32 v[2:3], v[52:53], v[2:3]
	v_mov_b32_e32 v6, v5
	v_pk_mul_f32 v[4:5], v[54:55], v[6:7]
	v_and_b32_sdwa v6, v3, v155 dst_sel:DWORD dst_unused:UNUSED_PAD src0_sel:WORD_1 src1_sel:DWORD
	v_and_b32_sdwa v7, v2, v155 dst_sel:DWORD dst_unused:UNUSED_PAD src0_sel:WORD_1 src1_sel:DWORD
	v_add3_u32 v2, v2, v7, s68
	v_add3_u32 v3, v3, v6, s68
	v_and_b32_sdwa v6, v5, v155 dst_sel:DWORD dst_unused:UNUSED_PAD src0_sel:WORD_1 src1_sel:DWORD
	v_and_b32_sdwa v7, v4, v155 dst_sel:DWORD dst_unused:UNUSED_PAD src0_sel:WORD_1 src1_sel:DWORD
	v_add3_u32 v5, v5, v6, s68
	v_add3_u32 v4, v4, v7, s68
	v_and_b32_e32 v5, 0xffff0000, v5
	v_and_b32_e32 v4, 0xffff0000, v4
	v_or_b32_sdwa v3, v5, v3 dst_sel:DWORD dst_unused:UNUSED_PAD src0_sel:DWORD src1_sel:WORD_1
	v_or_b32_sdwa v2, v4, v2 dst_sel:DWORD dst_unused:UNUSED_PAD src0_sel:DWORD src1_sel:WORD_1
	ds_read_b128 v[4:7], v74
	v_add_co_u32_e32 v12, vcc, s77, v12
	s_nop 1
	v_addc_co_u32_e32 v13, vcc, 0, v13, vcc
	global_store_dwordx4 v[12:13], v[0:3], off offset:2048
	s_waitcnt lgkmcnt(0)
	v_mov_b32_e32 v12, v4
	v_mov_b32_e32 v13, v6
	ds_read_b128 v[0:3], v74 offset:16
	v_pk_mul_f32 v[12:13], v[40:41], v[12:13]
	v_mov_b32_e32 v6, v5
	v_pk_mul_f32 v[4:5], v[42:43], v[6:7]
	v_and_b32_sdwa v6, v13, v155 dst_sel:DWORD dst_unused:UNUSED_PAD src0_sel:WORD_1 src1_sel:DWORD
	v_and_b32_sdwa v7, v12, v155 dst_sel:DWORD dst_unused:UNUSED_PAD src0_sel:WORD_1 src1_sel:DWORD
	v_add3_u32 v7, v12, v7, s68
	v_add3_u32 v6, v13, v6, s68
	v_and_b32_sdwa v12, v5, v155 dst_sel:DWORD dst_unused:UNUSED_PAD src0_sel:WORD_1 src1_sel:DWORD
	v_and_b32_sdwa v13, v4, v155 dst_sel:DWORD dst_unused:UNUSED_PAD src0_sel:WORD_1 src1_sel:DWORD
	v_add3_u32 v5, v5, v12, s68
	v_add3_u32 v4, v4, v13, s68
	v_and_b32_e32 v5, 0xffff0000, v5
	v_and_b32_e32 v4, 0xffff0000, v4
	v_or_b32_sdwa v5, v5, v6 dst_sel:DWORD dst_unused:UNUSED_PAD src0_sel:DWORD src1_sel:WORD_1
	v_or_b32_sdwa v4, v4, v7 dst_sel:DWORD dst_unused:UNUSED_PAD src0_sel:DWORD src1_sel:WORD_1
	s_waitcnt lgkmcnt(0)
	v_mov_b32_e32 v6, v0
	v_mov_b32_e32 v7, v2
	v_pk_mul_f32 v[6:7], v[44:45], v[6:7]
	v_mov_b32_e32 v2, v1
	v_pk_mul_f32 v[0:1], v[46:47], v[2:3]
	v_and_b32_sdwa v2, v7, v155 dst_sel:DWORD dst_unused:UNUSED_PAD src0_sel:WORD_1 src1_sel:DWORD
	v_and_b32_sdwa v3, v6, v155 dst_sel:DWORD dst_unused:UNUSED_PAD src0_sel:WORD_1 src1_sel:DWORD
	v_add3_u32 v3, v6, v3, s68
	v_add3_u32 v2, v7, v2, s68
	v_and_b32_sdwa v6, v1, v155 dst_sel:DWORD dst_unused:UNUSED_PAD src0_sel:WORD_1 src1_sel:DWORD
	v_and_b32_sdwa v7, v0, v155 dst_sel:DWORD dst_unused:UNUSED_PAD src0_sel:WORD_1 src1_sel:DWORD
	v_add3_u32 v1, v1, v6, s68
	v_add3_u32 v0, v0, v7, s68
	v_and_b32_e32 v1, 0xffff0000, v1
	v_and_b32_e32 v0, 0xffff0000, v0
	v_or_b32_sdwa v7, v1, v2 dst_sel:DWORD dst_unused:UNUSED_PAD src0_sel:DWORD src1_sel:WORD_1
	v_or_b32_sdwa v6, v0, v3 dst_sel:DWORD dst_unused:UNUSED_PAD src0_sel:DWORD src1_sel:WORD_1
	ds_read_b128 v[0:3], v73
	v_add_co_u32_e32 v10, vcc, s77, v10
	s_nop 1
	v_addc_co_u32_e32 v11, vcc, 0, v11, vcc
	global_store_dwordx4 v[10:11], v[4:7], off offset:2048
	s_waitcnt lgkmcnt(0)
; __device__ __forceinline__ unsigned pack2(float a, float b) { return (unsigned)f2bf(a) | ((unsigned)f2bf(b) << 16); }
; __device__ __forceinline__ float bflo(unsigned w) { return __uint_as_float(w << 16); }
; __device__ __forceinline__ float bfhi(unsigned w) { return __uint_as_float(w & 0xffff0000u); }
; __device__ __forceinline__ float silu_f(float g) { return g / (1.f + __expf(-g)); }
; template <int DH, int MODE>
; __device__ void attn_item(const Params& p, int layer, int b, int blk, int head, char* smem) {
;     ...
; #pragma unroll
;     for (int i = 0; i < NCH; ++i) {
;       int q = tid + 256 * i, r = q / CPR, c = (q % CPR) * 8;
;       float4 m0 = *reinterpret_cast<const float4*>(Of + r * OST + c);
;       float4 m1 = *reinterpret_cast<const float4*>(Of + r * OST + c + 4);
;       float mm[8] = {m0.x, m0.y, m0.z, m0.w, m1.x, m1.y, m1.z, m1.w};
;       unsigned gw[4] = {gt[i].x, gt[i].y, gt[i].z, gt[i].w};
;       unsigned ow[4];
; #pragma unroll
;       for (int e = 0; e < 4; ++e)
;         ow[e] = pack2(mm[2 * e] * silu_f(bflo(gw[e])), mm[2 * e + 1] * silu_f(bfhi(gw[e])));
;       *reinterpret_cast<uint4*>(Y + (tq0 + r) * YW + ycol + c) = make_uint4(ow[0], ow[1], ow[2], ow[3]);
;     }
;   }
;   __syncthreads();
	v_mov_b32_e32 v10, v0
	v_mov_b32_e32 v11, v2
	ds_read_b128 v[4:7], v73 offset:16
	v_pk_mul_f32 v[10:11], v[32:33], v[10:11]
	v_mov_b32_e32 v2, v1
	v_pk_mul_f32 v[0:1], v[34:35], v[2:3]
	v_and_b32_sdwa v2, v11, v155 dst_sel:DWORD dst_unused:UNUSED_PAD src0_sel:WORD_1 src1_sel:DWORD
	v_and_b32_sdwa v3, v10, v155 dst_sel:DWORD dst_unused:UNUSED_PAD src0_sel:WORD_1 src1_sel:DWORD
	v_add3_u32 v3, v10, v3, s68
	v_add3_u32 v2, v11, v2, s68
	v_and_b32_sdwa v10, v1, v155 dst_sel:DWORD dst_unused:UNUSED_PAD src0_sel:WORD_1 src1_sel:DWORD
	v_and_b32_sdwa v11, v0, v155 dst_sel:DWORD dst_unused:UNUSED_PAD src0_sel:WORD_1 src1_sel:DWORD
	v_add3_u32 v1, v1, v10, s68
	v_add3_u32 v0, v0, v11, s68
	v_and_b32_e32 v1, 0xffff0000, v1
	v_and_b32_e32 v0, 0xffff0000, v0
	v_or_b32_sdwa v1, v1, v2 dst_sel:DWORD dst_unused:UNUSED_PAD src0_sel:DWORD src1_sel:WORD_1
	v_or_b32_sdwa v0, v0, v3 dst_sel:DWORD dst_unused:UNUSED_PAD src0_sel:DWORD src1_sel:WORD_1
	s_waitcnt lgkmcnt(0)
	v_mov_b32_e32 v2, v4
	v_mov_b32_e32 v3, v6
	v_pk_mul_f32 v[2:3], v[36:37], v[2:3]
	v_mov_b32_e32 v6, v5
	v_pk_mul_f32 v[4:5], v[38:39], v[6:7]
	v_and_b32_sdwa v6, v3, v155 dst_sel:DWORD dst_unused:UNUSED_PAD src0_sel:WORD_1 src1_sel:DWORD
	v_and_b32_sdwa v7, v2, v155 dst_sel:DWORD dst_unused:UNUSED_PAD src0_sel:WORD_1 src1_sel:DWORD
	v_add3_u32 v2, v2, v7, s68
	v_add3_u32 v3, v3, v6, s68
	v_and_b32_sdwa v6, v5, v155 dst_sel:DWORD dst_unused:UNUSED_PAD src0_sel:WORD_1 src1_sel:DWORD
	v_and_b32_sdwa v7, v4, v155 dst_sel:DWORD dst_unused:UNUSED_PAD src0_sel:WORD_1 src1_sel:DWORD
	v_add3_u32 v5, v5, v6, s68
	v_add3_u32 v4, v4, v7, s68
	v_and_b32_e32 v5, 0xffff0000, v5
	v_and_b32_e32 v4, 0xffff0000, v4
	v_or_b32_sdwa v3, v5, v3 dst_sel:DWORD dst_unused:UNUSED_PAD src0_sel:DWORD src1_sel:WORD_1
	v_or_b32_sdwa v2, v4, v2 dst_sel:DWORD dst_unused:UNUSED_PAD src0_sel:DWORD src1_sel:WORD_1
	ds_read_b128 v[4:7], v72
	v_add_co_u32_e32 v8, vcc, s77, v8
	s_nop 1
	v_addc_co_u32_e32 v9, vcc, 0, v9, vcc
	global_store_dwordx4 v[8:9], v[0:3], off offset:2048
	s_waitcnt lgkmcnt(0)
	v_mov_b32_e32 v8, v4
	v_mov_b32_e32 v9, v6
	ds_read_b128 v[0:3], v72 offset:16
	v_pk_mul_f32 v[8:9], v[18:19], v[8:9]
	v_mov_b32_e32 v6, v5
	v_pk_mul_f32 v[4:5], v[22:23], v[6:7]
	v_and_b32_sdwa v6, v9, v155 dst_sel:DWORD dst_unused:UNUSED_PAD src0_sel:WORD_1 src1_sel:DWORD
	v_and_b32_sdwa v7, v8, v155 dst_sel:DWORD dst_unused:UNUSED_PAD src0_sel:WORD_1 src1_sel:DWORD
	v_add3_u32 v7, v8, v7, s68
	v_add3_u32 v6, v9, v6, s68
	v_and_b32_sdwa v8, v5, v155 dst_sel:DWORD dst_unused:UNUSED_PAD src0_sel:WORD_1 src1_sel:DWORD
	v_and_b32_sdwa v9, v4, v155 dst_sel:DWORD dst_unused:UNUSED_PAD src0_sel:WORD_1 src1_sel:DWORD
	v_add3_u32 v5, v5, v8, s68
	v_add3_u32 v4, v4, v9, s68
	v_and_b32_e32 v5, 0xffff0000, v5
	v_and_b32_e32 v4, 0xffff0000, v4
	v_or_b32_sdwa v5, v5, v6 dst_sel:DWORD dst_unused:UNUSED_PAD src0_sel:DWORD src1_sel:WORD_1
	v_or_b32_sdwa v4, v4, v7 dst_sel:DWORD dst_unused:UNUSED_PAD src0_sel:DWORD src1_sel:WORD_1
	s_waitcnt lgkmcnt(0)
	v_mov_b32_e32 v6, v0
	v_mov_b32_e32 v7, v2
	v_pk_mul_f32 v[6:7], v[24:25], v[6:7]
	v_mov_b32_e32 v2, v1
	v_pk_mul_f32 v[0:1], v[28:29], v[2:3]
	v_and_b32_sdwa v2, v7, v155 dst_sel:DWORD dst_unused:UNUSED_PAD src0_sel:WORD_1 src1_sel:DWORD
	v_and_b32_sdwa v3, v6, v155 dst_sel:DWORD dst_unused:UNUSED_PAD src0_sel:WORD_1 src1_sel:DWORD
	v_add3_u32 v2, v7, v2, s68
	v_and_b32_sdwa v7, v0, v155 dst_sel:DWORD dst_unused:UNUSED_PAD src0_sel:WORD_1 src1_sel:DWORD
	v_add3_u32 v3, v6, v3, s68
	v_and_b32_sdwa v6, v1, v155 dst_sel:DWORD dst_unused:UNUSED_PAD src0_sel:WORD_1 src1_sel:DWORD
	v_add3_u32 v0, v0, v7, s68
	v_add3_u32 v1, v1, v6, s68
	v_and_b32_e32 v0, 0xffff0000, v0
	v_and_b32_e32 v1, 0xffff0000, v1
	v_or_b32_sdwa v6, v0, v3 dst_sel:DWORD dst_unused:UNUSED_PAD src0_sel:DWORD src1_sel:WORD_1
	v_add_co_u32_e32 v0, vcc, 0x184a1000, v14
	v_or_b32_sdwa v7, v1, v2 dst_sel:DWORD dst_unused:UNUSED_PAD src0_sel:DWORD src1_sel:WORD_1
	s_nop 0
	v_addc_co_u32_e32 v1, vcc, 0, v15, vcc
	global_store_dwordx4 v[0:1], v[4:7], off offset:2048
	s_barrier

; #define MFMA16(a, b, c) __builtin_amdgcn_mfma_f32_16x16x32_bf16(a, b, c, 0, 0, 0)
; __device__ void gmlp_item(const Params& p, int layer, int b, int n, int g, char* smem) {
;     ...
; #pragma unroll 2
;   for (int i = 0; i < 8; ++i) {
;     int q = tid + 256 * i;
;     int t = q >> 4, cch = q & 15;
;     uint4 v = *reinterpret_cast<const uint4*>(Ws + (size_t)g * 16384 + t * 128 + cch * 8);
;     *reinterpret_cast<uint4*>(smem + (cch >> 2) * 8192 + t * 64 + (cch & 3) * 16) = v;
;   }
;   __syncthreads();
;   f32x4 acc[4][4];
; #pragma unroll
;   for (int m = 0; m < 4; ++m)
; #pragma unroll
;     for (int nn = 0; nn < 4; ++nn) acc[m][nn] = f32x4{0.f, 0.f, 0.f, 0.f};
; #pragma unroll
;   for (int ks = 0; ks < 4; ++ks) {
;     bf16x8 a[4], bb[4];
; #pragma unroll
;     for (int m = 0; m < 4; ++m)
;       a[m] = *reinterpret_cast<const bf16x8*>(smem + ks * 8192 + (wr * 64 + m * 16 + fr) * 64 + fq * 16);
; #pragma unroll
;     for (int nn = 0; nn < 4; ++nn)
;       bb[nn] = *reinterpret_cast<const bf16x8*>(smem + 32768 + ks * 8192 + (wc * 64 + nn * 16 + fr) * 64 + fq * 16);
; #pragma unroll
;     for (int m = 0; m < 4; ++m)
; #pragma unroll
;       for (int nn = 0; nn < 4; ++nn) acc[m][nn] = MFMA16(a[m], bb[nn], acc[m][nn]);
;   }
.LBB0_480:
	v_add_u32_e32 v3, s14, v60
	v_ashrrev_i32_e32 v12, 4, v3
	v_add_u32_e32 v3, 0x100, v3
	v_ashrrev_i32_e32 v3, 4, v3
	v_lshlrev_b32_e32 v4, 7, v12
	v_lshlrev_b32_e32 v6, 7, v3
	v_ashrrev_i32_e32 v5, 31, v4
	v_ashrrev_i32_e32 v7, 31, v6
	v_lshl_add_u64 v[4:5], v[4:5], 1, v[0:1]
	v_lshl_add_u64 v[8:9], v[6:7], 1, v[0:1]
	global_load_dwordx4 v[4:7], v[4:5], off
	s_nop 0
	global_load_dwordx4 v[8:11], v[8:9], off
	s_addk_i32 s14, 0x200
	s_cmpk_lg_i32 s14, 0x800
	v_lshl_add_u32 v12, v12, 6, v2
	v_lshl_add_u32 v3, v3, 6, v2
	s_waitcnt vmcnt(1)
	ds_write_b128 v12, v[4:7]
	s_waitcnt vmcnt(0)
	ds_write_b128 v3, v[8:11]
	s_cbranch_scc1 .LBB0_480
	v_bfe_u32 v32, v60, 4, 2
	v_ashrrev_i32_e32 v33, 7, v60
	v_lshlrev_b32_e32 v4, 4, v32
	v_lshlrev_b32_e32 v0, 12, v33
	v_lshlrev_b32_e32 v5, 6, v35
	v_or3_b32 v37, v4, v0, v5
	s_waitcnt lgkmcnt(0)
	s_barrier
	ds_read_b128 v[0:3], v37
	v_bfe_u32 v39, v60, 6, 1
	v_lshlrev_b32_e32 v6, 12, v39
	v_or3_b32 v41, v4, v6, v5
	ds_read_b128 v[4:7], v41 offset:32768
	ds_read_b128 v[8:11], v37 offset:1024
	ds_read_b128 v[12:15], v41 offset:33792
	ds_read_b128 v[24:27], v41 offset:34816
	ds_read_b128 v[28:31], v41 offset:35840
	s_waitcnt lgkmcnt(4)
	v_mfma_f32_16x16x32_bf16 v[16:19], v[0:3], v[4:7], 0
	s_ashr_i32 s15, s17, 31
	s_add_u32 s14, s28, s17
	s_addc_u32 s15, s29, s15
	s_waitcnt lgkmcnt(2)
	v_mfma_f32_16x16x32_bf16 v[20:23], v[0:3], v[12:15], 0
	v_lshlrev_b32_e32 v33, 6, v33
	s_lshl_b32 s17, s16, 2
	v_lshl_or_b32 v32, v32, 2, v33
	s_waitcnt lgkmcnt(1)
	v_mfma_f32_16x16x32_bf16 v[50:53], v[0:3], v[24:27], 0
	s_add_u32 s20, s24, s17
	s_addc_u32 s21, s25, 0
	v_ashrrev_i32_e32 v33, 31, v32
	s_waitcnt lgkmcnt(0)
	v_mfma_f32_16x16x32_bf16 v[54:57], v[0:3], v[28:31], 0
	ds_read_b128 v[0:3], v37 offset:2048
	ds_read_b128 v[74:77], v37 offset:3072
	ds_read_b128 v[98:101], v37 offset:8192
	v_lshl_add_u64 v[58:59], v[32:33], 2, s[20:21]
	v_mfma_f32_16x16x32_bf16 v[62:65], v[8:11], v[4:7], 0
	v_lshlrev_b32_e32 v33, 2, v35
	v_lshl_or_b32 v126, v39, 8, v33
	v_mad_u64_u32 v[32:33], s[20:21], v32, s69, v[126:127]
	v_mfma_f32_16x16x32_bf16 v[66:69], v[8:11], v[12:15], 0
	v_add_u32_e32 v33, 0x400, v32
	v_ashrrev_i32_e32 v49, 31, v48
	v_ashrrev_i32_e32 v47, 31, v46
	v_mfma_f32_16x16x32_bf16 v[70:73], v[8:11], v[24:27], 0
	v_ashrrev_i32_e32 v45, 31, v44
	v_ashrrev_i32_e32 v43, 31, v42
	v_ashrrev_i32_e32 v39, 31, v38
	v_mfma_f32_16x16x32_bf16 v[8:11], v[8:11], v[28:31], 0
	s_waitcnt lgkmcnt(2)
	v_mfma_f32_16x16x32_bf16 v[78:81], v[0:3], v[4:7], 0
	v_mfma_f32_16x16x32_bf16 v[82:85], v[0:3], v[12:15], 0
	v_mfma_f32_16x16x32_bf16 v[86:89], v[0:3], v[24:27], 0
	v_mfma_f32_16x16x32_bf16 v[90:93], v[0:3], v[28:31], 0
	s_waitcnt lgkmcnt(1)
	v_mfma_f32_16x16x32_bf16 v[94:97], v[74:77], v[4:7], 0
	v_mfma_f32_16x16x32_bf16 v[12:15], v[74:77], v[12:15], 0
	v_mfma_f32_16x16x32_bf16 v[24:27], v[74:77], v[24:27], 0
	v_mfma_f32_16x16x32_bf16 v[0:3], v[74:77], v[28:31], 0
	ds_read_b128 v[28:31], v41 offset:40960
	ds_read_b128 v[74:77], v37 offset:9216
	ds_read_b128 v[102:105], v41 offset:41984
	ds_read_b128 v[106:109], v41 offset:43008
	ds_read_b128 v[4:7], v41 offset:44032
	s_waitcnt lgkmcnt(4)
	v_mfma_f32_16x16x32_bf16 v[16:19], v[98:101], v[28:31], v[16:19]
	s_waitcnt lgkmcnt(2)
	v_mfma_f32_16x16x32_bf16 v[20:23], v[98:101], v[102:105], v[20:23]
	s_waitcnt lgkmcnt(1)
	v_mfma_f32_16x16x32_bf16 v[50:53], v[98:101], v[106:109], v[50:53]
	s_waitcnt lgkmcnt(0)
	v_mfma_f32_16x16x32_bf16 v[54:57], v[98:101], v[4:7], v[54:57]
	ds_read_b128 v[98:101], v37 offset:10240
	v_mfma_f32_16x16x32_bf16 v[62:65], v[74:77], v[28:31], v[62:65]
	v_mfma_f32_16x16x32_bf16 v[66:69], v[74:77], v[102:105], v[66:69]
	v_mfma_f32_16x16x32_bf16 v[70:73], v[74:77], v[106:109], v[70:73]
	v_mfma_f32_16x16x32_bf16 v[8:11], v[74:77], v[4:7], v[8:11]
	ds_read_b128 v[74:77], v37 offset:11264
	ds_read_b128 v[110:113], v37 offset:16384
	ds_read_b128 v[114:117], v37 offset:17408
	ds_read_b128 v[118:121], v37 offset:18432
	ds_read_b128 v[122:125], v37 offset:19456
	ds_read_b128 v[134:137], v41 offset:49152
	ds_read_b128 v[138:141], v41 offset:50176
	ds_read_b128 v[146:149], v41 offset:51200
	ds_read_b128 v[150:153], v41 offset:52224
	ds_read_b128 v[162:165], v37 offset:24576
	ds_read_b128 v[166:169], v37 offset:25600
	s_waitcnt lgkmcnt(11)
	v_mfma_f32_16x16x32_bf16 v[78:81], v[98:101], v[28:31], v[78:81]
	v_mfma_f32_16x16x32_bf16 v[82:85], v[98:101], v[102:105], v[82:85]
	v_mfma_f32_16x16x32_bf16 v[86:89], v[98:101], v[106:109], v[86:89]
	v_mfma_f32_16x16x32_bf16 v[90:93], v[98:101], v[4:7], v[90:93]
	ds_read_b128 v[98:101], v37 offset:26624
	ds_read_b128 v[170:173], v37 offset:27648
	ds_read_b128 v[174:177], v41 offset:57344
	ds_read_b128 v[178:181], v41 offset:58368
	s_waitcnt lgkmcnt(14)
	v_mfma_f32_16x16x32_bf16 v[28:31], v[74:77], v[28:31], v[94:97]
	s_nop 2
	ds_read_b128 v[94:97], v41 offset:59392
	ds_read_b128 v[182:185], v41 offset:60416
	s_waitcnt lgkmcnt(0)
	s_barrier
; #define MFMA16(a, b, c) __builtin_amdgcn_mfma_f32_16x16x32_bf16(a, b, c, 0, 0, 0)
; __device__ void gmlp_item(const Params& p, int layer, int b, int n, int g, char* smem) {
;     ...
;   for (int ks = 0; ks < 4; ++ks) {
;     bf16x8 a[4], bb[4];
; #pragma unroll
;     for (int m = 0; m < 4; ++m)
;       a[m] = *reinterpret_cast<const bf16x8*>(smem + ks * 8192 + (wr * 64 + m * 16 + fr) * 64 + fq * 16);
; #pragma unroll
;     for (int nn = 0; nn < 4; ++nn)
;       bb[nn] = *reinterpret_cast<const bf16x8*>(smem + 32768 + ks * 8192 + (wc * 64 + nn * 16 + fr) * 64 + fq * 16);
; #pragma unroll
;     for (int m = 0; m < 4; ++m)
; #pragma unroll
;       for (int nn = 0; nn < 4; ++nn) acc[m][nn] = MFMA16(a[m], bb[nn], acc[m][nn]);
;   }
;   __syncthreads();
;   {
;     float* Tf = reinterpret_cast<float*>(smem);
; #pragma unroll
;     for (int m = 0; m < 4; ++m)
; #pragma unroll
;       for (int j = 0; j < 4; ++j) {
;         int t = wr * 64 + m * 16 + fq * 4 + j;
;         float bias = p.gm_b_s[(size_t)layer * 512 + g * 128 + t];
; #pragma unroll
;         for (int nn = 0; nn < 4; ++nn) Tf[t * 132 + wc * 64 + nn * 16 + fr] = acc[m][nn][j] + bias;
;       }
;     __syncthreads();
	v_mfma_f32_16x16x32_bf16 v[16:19], v[110:113], v[134:137], v[16:19]
	global_load_dwordx4 v[186:189], v[58:59], off offset:2112
	global_load_dwordx4 v[190:193], v[58:59], off offset:2176
	v_mfma_f32_16x16x32_bf16 v[20:23], v[110:113], v[138:141], v[20:23]
	v_ashrrev_i32_e32 v41, 31, v40
	v_mfma_f32_16x16x32_bf16 v[50:53], v[110:113], v[146:149], v[50:53]
	v_mfma_f32_16x16x32_bf16 v[54:57], v[110:113], v[150:153], v[54:57]
	global_load_dwordx4 v[110:113], v[58:59], off offset:2048
	v_mfma_f32_16x16x32_bf16 v[16:19], v[162:165], v[174:177], v[16:19]
	v_mfma_f32_16x16x32_bf16 v[20:23], v[162:165], v[178:181], v[20:23]
	v_mfma_f32_16x16x32_bf16 v[50:53], v[162:165], v[94:97], v[50:53]
	s_waitcnt vmcnt(0)
	s_nop 4
	v_add_f32_e32 v16, v16, v110
	v_mfma_f32_16x16x32_bf16 v[54:57], v[162:165], v[182:185], v[54:57]
	v_add_f32_e32 v20, v20, v110
	ds_write2_b32 v32, v16, v20 offset1:16
	v_add_f32_e32 v16, v50, v110
	v_add_f32_e32 v35, v53, v113
	v_mfma_f32_16x16x32_bf16 v[62:65], v[114:117], v[134:137], v[62:65]
	s_nop 2
	v_add_f32_e32 v20, v54, v110
	ds_write2_b32 v32, v16, v20 offset0:32 offset1:48
	v_add_f32_e32 v16, v17, v111
	v_add_f32_e32 v17, v21, v111
	ds_write2_b32 v32, v16, v17 offset0:132 offset1:148
	v_add_f32_e32 v16, v51, v111
	v_add_f32_e32 v17, v55, v111
	ds_write2_b32 v32, v16, v17 offset0:164 offset1:180
	v_add_f32_e32 v16, v18, v112
	v_add_f32_e32 v17, v22, v112
	ds_write2_b32 v33, v16, v17 offset0:8 offset1:24
	v_add_f32_e32 v16, v52, v112
	global_load_dwordx4 v[50:53], v[58:59], off offset:2240
	v_mfma_f32_16x16x32_bf16 v[66:69], v[114:117], v[138:141], v[66:69]
	v_add_f32_e32 v17, v56, v112
	v_add_f32_e32 v20, v19, v113
	v_add_f32_e32 v21, v23, v113
	v_mfma_f32_16x16x32_bf16 v[70:73], v[114:117], v[146:149], v[70:73]
	ds_write2_b32 v33, v16, v17 offset0:40 offset1:56
	ds_write2_b32 v33, v20, v21 offset0:140 offset1:156
	v_add_f32_e32 v37, v57, v113
	v_mfma_f32_16x16x32_bf16 v[8:11], v[114:117], v[150:153], v[8:11]
	ds_write2_b32 v33, v35, v37 offset0:172 offset1:188
	v_add_u32_e32 v33, 0x2000, v32
	v_ashrrev_i32_e32 v35, 31, v34
	v_mfma_f32_16x16x32_bf16 v[16:19], v[166:169], v[174:177], v[62:65]
	v_ashrrev_i32_e32 v37, 31, v36
	v_lshl_add_u64 v[58:59], v[42:43], 0, s[36:37]
	v_mfma_f32_16x16x32_bf16 v[20:23], v[166:169], v[178:181], v[66:69]
	v_mfma_f32_16x16x32_bf16 v[54:57], v[166:169], v[94:97], v[70:73]
	s_nop 3
	v_add_f32_e32 v16, v16, v186
	s_nop 1
	v_add_f32_e32 v20, v20, v186
	ds_write2_b32 v33, v16, v20 offset0:64 offset1:80
	v_mfma_f32_16x16x32_bf16 v[8:11], v[166:169], v[182:185], v[8:11]
	v_add_u32_e32 v20, 0x2400, v32
	v_add_f32_e32 v16, v54, v186
	v_mfma_f32_16x16x32_bf16 v[62:65], v[118:121], v[134:137], v[78:81]
	v_mfma_f32_16x16x32_bf16 v[66:69], v[118:121], v[138:141], v[82:85]
	s_nop 3
	v_add_f32_e32 v8, v8, v186
	ds_write2_b32 v33, v16, v8 offset0:96 offset1:112
	v_add_f32_e32 v8, v17, v187
	v_add_f32_e32 v16, v21, v187
	ds_write2_b32 v33, v8, v16 offset0:196 offset1:212
	v_add_f32_e32 v8, v55, v187
	v_add_f32_e32 v9, v9, v187
	ds_write2_b32 v33, v8, v9 offset0:228 offset1:244
	v_add_f32_e32 v8, v18, v188
	v_add_f32_e32 v9, v22, v188
	v_mfma_f32_16x16x32_bf16 v[70:73], v[118:121], v[146:149], v[86:89]
	ds_write2_b32 v20, v8, v9 offset0:72 offset1:88
	v_add_f32_e32 v8, v56, v188
	v_add_f32_e32 v9, v10, v188
	v_mfma_f32_16x16x32_bf16 v[78:81], v[118:121], v[150:153], v[90:93]
	ds_write2_b32 v20, v8, v9 offset0:104 offset1:120
	v_add_f32_e32 v8, v19, v189
	v_add_f32_e32 v9, v23, v189
	v_mfma_f32_16x16x32_bf16 v[16:19], v[98:101], v[174:177], v[62:65]
	ds_write2_b32 v20, v8, v9 offset0:204 offset1:220
	v_add_f32_e32 v21, v57, v189
	v_add_f32_e32 v22, v11, v189
	v_mfma_f32_16x16x32_bf16 v[8:11], v[98:101], v[178:181], v[66:69]
	ds_write2_b32 v20, v21, v22 offset0:236 offset1:252
	s_nop 2
	v_add_f32_e32 v16, v16, v190
	v_add_u32_e32 v33, 0x4000, v32
	v_mfma_f32_16x16x32_bf16 v[20:23], v[98:101], v[94:97], v[70:73]
	v_lshl_add_u64 v[62:63], v[38:39], 0, s[36:37]
	v_add_f32_e32 v8, v8, v190
	ds_write2_b32 v33, v16, v8 offset0:128 offset1:144
	v_mfma_f32_16x16x32_bf16 v[54:57], v[98:101], v[182:185], v[78:81]
	v_add_f32_e32 v10, v10, v192
	s_nop 2
	v_add_f32_e32 v8, v20, v190
	v_mfma_f32_16x16x32_bf16 v[12:15], v[74:77], v[102:105], v[12:15]
	v_mfma_f32_16x16x32_bf16 v[24:27], v[74:77], v[106:109], v[24:27]
	s_nop 0
	v_add_f32_e32 v16, v54, v190
	ds_write2_b32 v33, v8, v16 offset0:160 offset1:176
	v_add_f32_e32 v8, v17, v191
	v_mfma_f32_16x16x32_bf16 v[0:3], v[74:77], v[4:7], v[0:3]
	v_add_f32_e32 v4, v9, v191
	v_add_u32_e32 v9, 0x4400, v32
	ds_write2_b32 v9, v8, v4 offset0:4 offset1:20
	v_mfma_f32_16x16x32_bf16 v[4:7], v[122:125], v[134:137], v[28:31]
	v_add_f32_e32 v8, v21, v191
	v_add_f32_e32 v16, v55, v191
	ds_write2_b32 v9, v8, v16 offset0:36 offset1:52
	v_mfma_f32_16x16x32_bf16 v[12:15], v[122:125], v[138:141], v[12:15]
	v_add_f32_e32 v8, v18, v192
	ds_write2_b32 v9, v8, v10 offset0:136 offset1:152
	v_add_f32_e32 v8, v22, v192
	v_mfma_f32_16x16x32_bf16 v[24:27], v[122:125], v[146:149], v[24:27]
	v_add_f32_e32 v10, v56, v192
	ds_write2_b32 v9, v8, v10 offset0:168 offset1:184
	v_add_f32_e32 v8, v19, v193
	v_mfma_f32_16x16x32_bf16 v[0:3], v[122:125], v[150:153], v[0:3]
	v_add_f32_e32 v9, v11, v193
	v_add_u32_e32 v16, 0x4800, v32
	ds_write2_b32 v16, v8, v9 offset0:12 offset1:28
	v_mfma_f32_16x16x32_bf16 v[4:7], v[170:173], v[174:177], v[4:7]
	v_add_f32_e32 v17, v23, v193
	v_add_f32_e32 v18, v57, v193
	ds_write2_b32 v16, v17, v18 offset0:44 offset1:60
	v_mfma_f32_16x16x32_bf16 v[8:11], v[170:173], v[178:181], v[12:15]
	v_add_u32_e32 v16, 0x6000, v32
	s_waitcnt vmcnt(0)
; __device__ void gmlp_item(const Params& p, int layer, int b, int n, int g, char* smem) {
;     ...
;   {
;     float* Tf = reinterpret_cast<float*>(smem);
; #pragma unroll
;     for (int m = 0; m < 4; ++m)
; #pragma unroll
;       for (int j = 0; j < 4; ++j) {
;         int t = wr * 64 + m * 16 + fq * 4 + j;
;         float bias = p.gm_b_s[(size_t)layer * 512 + g * 128 + t];
; #pragma unroll
;         for (int nn = 0; nn < 4; ++nn) Tf[t * 132 + wc * 64 + nn * 16 + fr] = acc[m][nn][j] + bias;
;       }
;     __syncthreads();
;     uint4 uu[8], gt[8];
; #pragma unroll
;     for (int i = 0; i < 8; ++i) {
;       int q = tid + 256 * i, t = q >> 4, c = (q & 15) * 8;
;       uu[i] = *reinterpret_cast<const uint4*>(P + (t0 + t) * NP + g * 128 + c);
;       gt[i] = *reinterpret_cast<const uint4*>(P + (t0 + t) * NP + 1024 + g * 128 + c);
;     }
; #pragma unroll
;     for (int i = 0; i < 8; ++i) {
;       int q = tid + 256 * i, t = q >> 4, c = (q & 15) * 8;
;       float4 m0 = *reinterpret_cast<const float4*>(Tf + t * 132 + c);
	s_nop 1
	v_add_f32_e32 v4, v4, v50
	v_lshl_add_u64 v[56:57], v[36:37], 0, s[36:37]
	v_mfma_f32_16x16x32_bf16 v[12:15], v[170:173], v[94:97], v[24:27]
	v_lshl_add_u64 v[20:21], v[44:45], 0, s[36:37]
	v_add_f32_e32 v8, v8, v50
	ds_write2_b32 v16, v4, v8 offset0:192 offset1:208
	v_mfma_f32_16x16x32_bf16 v[0:3], v[170:173], v[182:185], v[0:3]
	s_nop 3
	v_add_f32_e32 v4, v12, v50
	s_nop 2
	v_add_f32_e32 v0, v0, v50
	ds_write2_b32 v16, v4, v0 offset0:224 offset1:240
	v_add_f32_e32 v0, v5, v51
	v_add_f32_e32 v4, v9, v51
	v_add_u32_e32 v5, 0x6400, v32
	ds_write2_b32 v5, v0, v4 offset0:68 offset1:84
	v_add_f32_e32 v0, v13, v51
	v_add_f32_e32 v1, v1, v51
	ds_write2_b32 v5, v0, v1 offset0:100 offset1:116
	v_add_f32_e32 v0, v6, v52
	v_add_f32_e32 v1, v10, v52
	ds_write2_b32 v5, v0, v1 offset0:200 offset1:216
	v_add_f32_e32 v0, v14, v52
	v_add_f32_e32 v1, v2, v52
	ds_write2_b32 v5, v0, v1 offset0:232 offset1:248
	v_add_f32_e32 v0, v7, v53
	v_add_f32_e32 v1, v11, v53
	v_add_u32_e32 v2, 0x6800, v32
	ds_write2_b32 v2, v0, v1 offset0:76 offset1:92
	v_add_f32_e32 v0, v15, v53
	v_add_f32_e32 v1, v3, v53
	ds_write2_b32 v2, v0, v1 offset0:108 offset1:124
	v_lshlrev_b32_e32 v0, 3, v60
	v_lshl_add_u64 v[8:9], v[34:35], 0, s[36:37]
	v_mov_b64_e32 v[10:11], s[12:13]
	v_and_b32_e32 v24, 0x78, v0
	v_mad_u64_u32 v[0:1], s[12:13], v8, s63, v[10:11]
	v_mad_i32_i24 v1, v9, s63, v1
	s_lshl_b32 s12, s16, 1
	s_mov_b32 s13, s37
	v_lshl_add_u64 v[0:1], v[0:1], 0, s[12:13]
	v_lshlrev_b32_e32 v128, 1, v24
	v_lshl_add_u64 v[12:13], v[48:49], 0, s[36:37]
	v_lshl_add_u64 v[52:53], v[0:1], 0, v[128:129]
	v_mad_u64_u32 v[0:1], s[16:17], v12, s63, v[10:11]
	v_mad_i32_i24 v1, v13, s63, v1
	v_lshl_add_u64 v[0:1], v[0:1], 0, s[12:13]
	v_lshl_add_u64 v[32:33], v[0:1], 0, v[128:129]
	v_mad_u64_u32 v[0:1], s[16:17], v56, s63, v[10:11]
	v_mad_i32_i24 v1, v57, s63, v1
	v_lshl_add_u64 v[0:1], v[0:1], 0, s[12:13]
	v_lshl_add_u64 v[4:5], v[0:1], 0, v[128:129]
	s_waitcnt lgkmcnt(0)
	s_barrier
	global_load_dwordx4 v[0:3], v[4:5], off
	s_nop 0
	global_load_dwordx4 v[4:7], v[4:5], off offset:2048
	v_lshl_add_u64 v[16:17], v[46:47], 0, s[36:37]
	v_mad_u64_u32 v[14:15], s[16:17], v16, s63, v[10:11]
	v_mad_i32_i24 v15, v17, s63, v15
	v_lshl_add_u64 v[14:15], v[14:15], 0, s[12:13]
	v_lshl_add_u64 v[30:31], v[14:15], 0, v[128:129]
	v_mad_u64_u32 v[14:15], s[16:17], v20, s63, v[10:11]
	v_mad_i32_i24 v15, v21, s63, v15
	v_lshl_add_u64 v[14:15], v[14:15], 0, s[12:13]
	v_lshl_add_u64 v[26:27], v[14:15], 0, v[128:129]
	v_mad_u64_u32 v[14:15], s[16:17], v58, s63, v[10:11]
	v_mad_i32_i24 v15, v59, s63, v15
	v_lshl_add_u64 v[14:15], v[14:15], 0, s[12:13]
	v_lshl_add_u64 v[60:61], v[40:41], 0, s[36:37]
	v_lshl_add_u64 v[22:23], v[14:15], 0, v[128:129]
	v_mad_u64_u32 v[14:15], s[16:17], v60, s63, v[10:11]
	v_mad_u64_u32 v[10:11], s[16:17], v62, s63, v[10:11]
	v_mad_i32_i24 v15, v61, s63, v15
	v_mad_i32_i24 v11, v63, s63, v11
	v_lshl_add_u64 v[14:15], v[14:15], 0, s[12:13]
	v_lshl_add_u64 v[10:11], v[10:11], 0, s[12:13]
	s_add_u32 s12, s14, s12
	s_addc_u32 s13, s15, 0
	v_lshl_add_u64 v[18:19], v[14:15], 0, v[128:129]
	v_lshl_add_u64 v[14:15], v[10:11], 0, v[128:129]
	v_lshlrev_b32_e32 v10, 2, v24
	v_lshl_add_u64 v[24:25], s[12:13], 0, v[128:129]
	v_lshl_add_u64 v[64:65], v[24:25], 0, s[42:43]
	v_mad_u64_u32 v[54:55], s[12:13], v34, s69, v[10:11]
	v_mad_u64_u32 v[34:35], s[12:13], v48, s69, v[10:11]
	v_mad_u64_u32 v[48:49], s[12:13], v12, s70, v[64:65]
	v_mad_u64_u32 v[28:29], s[12:13], v46, s69, v[10:11]
	v_mad_u64_u32 v[46:47], s[12:13], v16, s70, v[64:65]
	v_mad_u64_u32 v[50:51], s[12:13], v8, s70, v[64:65]
	v_mad_i32_i24 v49, v13, s70, v49
	v_mad_i32_i24 v47, v17, s70, v47
	v_mad_u64_u32 v[24:25], s[12:13], v44, s69, v[10:11]
	v_mad_u64_u32 v[44:45], s[12:13], v20, s70, v[64:65]
	v_mad_u64_u32 v[16:17], s[12:13], v40, s69, v[10:11]
	v_mad_u64_u32 v[12:13], s[12:13], v38, s69, v[10:11]
	v_mad_i32_i24 v51, v9, s70, v51
	v_mad_i32_i24 v45, v21, s70, v45
	v_mad_u64_u32 v[20:21], s[12:13], v42, s69, v[10:11]
	v_mad_u64_u32 v[8:9], s[12:13], v36, s69, v[10:11]
	v_mad_u64_u32 v[40:41], s[12:13], v60, s70, v[64:65]
	v_mad_i32_i24 v41, v61, s70, v41
	v_mad_u64_u32 v[42:43], s[12:13], v58, s70, v[64:65]
	v_mad_u64_u32 v[36:37], s[12:13], v56, s70, v[64:65]
	v_mad_i32_i24 v43, v59, s70, v43
	v_mad_i32_i24 v37, v57, s70, v37
	v_mad_u64_u32 v[38:39], s[12:13], v62, s70, v[64:65]
	v_mad_i32_i24 v39, v63, s70, v39
	s_waitcnt vmcnt(1)
	v_lshlrev_b32_e32 v63, 16, v1
	s_waitcnt vmcnt(0)
	v_lshlrev_b32_e32 v13, 16, v5
	v_lshlrev_b32_e32 v17, 16, v4
	v_mul_f32_e32 v9, 0xbfb8aa3b, v17
	v_and_b32_e32 v21, 0xffff0000, v5
	v_mul_f32_e32 v5, 0xbfb8aa3b, v13
	v_exp_f32_e32 v60, v9
	v_exp_f32_e32 v61, v5
	ds_read_b128 v[56:59], v8
	ds_read_b128 v[8:11], v8 offset:16
	v_and_b32_e32 v25, 0xffff0000, v4
	v_mul_f32_e32 v4, 0xbfb8aa3b, v25
	v_pk_add_f32 v[60:61], v[60:61], 1.0 op_sel_hi:[1,0]
	s_waitcnt lgkmcnt(1)
; __device__ __forceinline__ unsigned pack2(float a, float b) { return (unsigned)f2bf(a) | ((unsigned)f2bf(b) << 16); }
; __device__ __forceinline__ float bflo(unsigned w) { return __uint_as_float(w << 16); }
; __device__ __forceinline__ float bfhi(unsigned w) { return __uint_as_float(w & 0xffff0000u); }
; __device__ __forceinline__ float silu_f(float g) { return g / (1.f + __expf(-g)); }
; __device__ void gmlp_item(const Params& p, int layer, int b, int n, int g, char* smem) {
;     ...
; #pragma unroll
;     for (int i = 0; i < 8; ++i) {
;       int q = tid + 256 * i, t = q >> 4, c = (q & 15) * 8;
;       float4 m0 = *reinterpret_cast<const float4*>(Tf + t * 132 + c);
;       float4 m1 = *reinterpret_cast<const float4*>(Tf + t * 132 + c + 4);
;       float mm[8] = {m0.x, m0.y, m0.z, m0.w, m1.x, m1.y, m1.z, m1.w};
;       unsigned uw[4] = {uu[i].x, uu[i].y, uu[i].z, uu[i].w};
;       unsigned gw[4] = {gt[i].x, gt[i].y, gt[i].z, gt[i].w};
;       unsigned ow[4];
; #pragma unroll
;       for (int e = 0; e < 4; ++e) {
;         float y0 = bflo(uw[e]) * mm[2 * e] * silu_f(bflo(gw[e]));
;         float y1 = bfhi(uw[e]) * mm[2 * e + 1] * silu_f(bfhi(gw[e]));
;         ow[e] = pack2(y0, y1);
;       }
;       *reinterpret_cast<uint4*>(Y + (t0 + t) * YW + g * 128 + c) = make_uint4(ow[0], ow[1], ow[2], ow[3]);
;     }
	v_mov_b32_e32 v64, v56
	v_exp_f32_e32 v4, v4
	v_lshlrev_b32_e32 v62, 16, v0
	v_mov_b32_e32 v65, v58
	v_rcp_f32_e32 v61, v61
	s_nop 0
	v_mul_f32_e32 v61, v13, v61
	v_and_b32_e32 v1, 0xffff0000, v1
	v_mul_f32_e32 v5, 0xbfb8aa3b, v21
	v_exp_f32_e32 v5, v5
	v_rcp_f32_e32 v60, v60
	s_nop 0
	v_mul_f32_e32 v60, v17, v60
	v_and_b32_e32 v0, 0xffff0000, v0
	v_mov_b32_e32 v58, v57
	v_pk_add_f32 v[4:5], v[4:5], 1.0 op_sel_hi:[1,0]
	v_pk_mul_f32 v[0:1], v[58:59], v[0:1]
	v_pk_mul_f32 v[62:63], v[64:65], v[62:63]
	v_rcp_f32_e32 v5, v5
	s_nop 0
	v_mul_f32_e32 v5, v21, v5
	v_pk_mul_f32 v[60:61], v[60:61], v[62:63]
	v_rcp_f32_e32 v4, v4
	s_nop 0
	v_mul_f32_e32 v4, v25, v4
	v_pk_mul_f32 v[0:1], v[4:5], v[0:1]
	v_and_b32_sdwa v4, v61, v155 dst_sel:DWORD dst_unused:UNUSED_PAD src0_sel:WORD_1 src1_sel:DWORD
	v_and_b32_sdwa v13, v1, v155 dst_sel:DWORD dst_unused:UNUSED_PAD src0_sel:WORD_1 src1_sel:DWORD
	v_and_b32_sdwa v17, v0, v155 dst_sel:DWORD dst_unused:UNUSED_PAD src0_sel:WORD_1 src1_sel:DWORD
	v_and_b32_sdwa v5, v60, v155 dst_sel:DWORD dst_unused:UNUSED_PAD src0_sel:WORD_1 src1_sel:DWORD
	v_add3_u32 v1, v1, v13, s68
	v_add3_u32 v0, v0, v17, s68
	v_add3_u32 v5, v60, v5, s68
	v_add3_u32 v4, v61, v4, s68
	v_and_b32_e32 v1, 0xffff0000, v1
	v_and_b32_e32 v0, 0xffff0000, v0
	v_lshlrev_b32_e32 v13, 16, v7
	v_lshlrev_b32_e32 v17, 16, v6
	v_or_b32_sdwa v1, v1, v4 dst_sel:DWORD dst_unused:UNUSED_PAD src0_sel:DWORD src1_sel:WORD_1
	v_or_b32_sdwa v0, v0, v5 dst_sel:DWORD dst_unused:UNUSED_PAD src0_sel:DWORD src1_sel:WORD_1
	v_mul_f32_e32 v4, 0xbfb8aa3b, v17
	v_mul_f32_e32 v5, 0xbfb8aa3b, v13
	v_exp_f32_e32 v4, v4
	v_exp_f32_e32 v5, v5
	v_and_b32_e32 v25, 0xffff0000, v6
	v_mul_f32_e32 v6, 0xbfb8aa3b, v25
	v_and_b32_e32 v21, 0xffff0000, v7
	v_exp_f32_e32 v60, v6
	v_pk_add_f32 v[64:65], v[4:5], 1.0 op_sel_hi:[1,0]
	global_load_dwordx4 v[4:7], v[14:15], off
	global_load_dwordx4 v[56:59], v[14:15], off offset:2048
	s_waitcnt lgkmcnt(0)
	v_mov_b32_e32 v14, v8
	v_mov_b32_e32 v15, v10
	v_lshlrev_b32_e32 v63, 16, v3
	v_lshlrev_b32_e32 v62, 16, v2
	v_pk_mul_f32 v[14:15], v[14:15], v[62:63]
	v_rcp_f32_e32 v63, v65
	s_nop 0
	v_mul_f32_e32 v63, v13, v63
	v_mul_f32_e32 v10, 0xbfb8aa3b, v21
	v_exp_f32_e32 v61, v10
	v_rcp_f32_e32 v62, v64
	s_nop 0
	v_mul_f32_e32 v62, v17, v62
	v_mov_b32_e32 v10, v9
	v_and_b32_e32 v3, 0xffff0000, v3
	v_pk_add_f32 v[60:61], v[60:61], 1.0 op_sel_hi:[1,0]
	v_and_b32_e32 v2, 0xffff0000, v2
	v_pk_mul_f32 v[2:3], v[10:11], v[2:3]
	v_pk_mul_f32 v[14:15], v[62:63], v[14:15]
	v_rcp_f32_e32 v9, v61
	s_nop 0
	v_mul_f32_e32 v9, v21, v9
	v_rcp_f32_e32 v8, v60
	s_nop 0
	v_mul_f32_e32 v8, v25, v8
	v_pk_mul_f32 v[2:3], v[8:9], v[2:3]
	v_and_b32_sdwa v8, v15, v155 dst_sel:DWORD dst_unused:UNUSED_PAD src0_sel:WORD_1 src1_sel:DWORD
	v_and_b32_sdwa v10, v3, v155 dst_sel:DWORD dst_unused:UNUSED_PAD src0_sel:WORD_1 src1_sel:DWORD
	v_add3_u32 v3, v3, v10, s68
	v_add3_u32 v8, v15, v8, s68
	v_and_b32_e32 v3, 0xffff0000, v3
	v_or_b32_sdwa v3, v3, v8 dst_sel:DWORD dst_unused:UNUSED_PAD src0_sel:DWORD src1_sel:WORD_1
	v_and_b32_sdwa v11, v2, v155 dst_sel:DWORD dst_unused:UNUSED_PAD src0_sel:WORD_1 src1_sel:DWORD
	v_and_b32_sdwa v9, v14, v155 dst_sel:DWORD dst_unused:UNUSED_PAD src0_sel:WORD_1 src1_sel:DWORD
	v_add3_u32 v2, v2, v11, s68
	v_add3_u32 v9, v14, v9, s68
	v_and_b32_e32 v2, 0xffff0000, v2
	v_or_b32_sdwa v2, v2, v9 dst_sel:DWORD dst_unused:UNUSED_PAD src0_sel:DWORD src1_sel:WORD_1
	s_waitcnt vmcnt(0)
	v_lshlrev_b32_e32 v21, 16, v56
	v_mul_f32_e32 v8, 0xbfb8aa3b, v21
	v_and_b32_e32 v29, 0xffff0000, v56
	v_lshlrev_b32_e32 v17, 16, v57
	v_exp_f32_e32 v60, v8
	v_mul_f32_e32 v8, 0xbfb8aa3b, v29
	v_exp_f32_e32 v56, v8
	v_mul_f32_e32 v8, 0xbfb8aa3b, v17
	v_exp_f32_e32 v61, v8
	ds_read_b128 v[8:11], v12
	ds_read_b128 v[12:15], v12 offset:16
	v_and_b32_e32 v25, 0xffff0000, v57
	v_lshlrev_b32_e32 v63, 16, v5
	v_pk_add_f32 v[60:61], v[60:61], 1.0 op_sel_hi:[1,0]
	s_waitcnt lgkmcnt(1)
	v_mov_b32_e32 v64, v8
	v_mov_b32_e32 v65, v10
	v_lshlrev_b32_e32 v62, 16, v4
	v_and_b32_e32 v5, 0xffff0000, v5
	v_rcp_f32_e32 v61, v61
	s_nop 0
	v_mul_f32_e32 v61, v17, v61
	v_and_b32_e32 v4, 0xffff0000, v4
	v_mul_f32_e32 v10, 0xbfb8aa3b, v25
	v_exp_f32_e32 v57, v10
	v_rcp_f32_e32 v60, v60
	s_nop 0
	v_mul_f32_e32 v60, v21, v60
	v_mov_b32_e32 v10, v9
	v_pk_mul_f32 v[4:5], v[10:11], v[4:5]
	v_pk_add_f32 v[56:57], v[56:57], 1.0 op_sel_hi:[1,0]
	v_pk_mul_f32 v[62:63], v[64:65], v[62:63]
	v_pk_mul_f32 v[60:61], v[60:61], v[62:63]
	v_lshlrev_b32_e32 v63, 16, v7
	v_lshlrev_b32_e32 v62, 16, v6
	v_rcp_f32_e32 v9, v57
	s_nop 0
	v_mul_f32_e32 v9, v25, v9
	v_rcp_f32_e32 v8, v56
	s_nop 0
	v_mul_f32_e32 v8, v29, v8
	v_pk_mul_f32 v[4:5], v[8:9], v[4:5]
	v_and_b32_sdwa v8, v61, v155 dst_sel:DWORD dst_unused:UNUSED_PAD src0_sel:WORD_1 src1_sel:DWORD
	v_and_b32_sdwa v10, v5, v155 dst_sel:DWORD dst_unused:UNUSED_PAD src0_sel:WORD_1 src1_sel:DWORD
	v_and_b32_sdwa v11, v4, v155 dst_sel:DWORD dst_unused:UNUSED_PAD src0_sel:WORD_1 src1_sel:DWORD
	v_and_b32_sdwa v9, v60, v155 dst_sel:DWORD dst_unused:UNUSED_PAD src0_sel:WORD_1 src1_sel:DWORD
	v_add3_u32 v5, v5, v10, s68
	v_add3_u32 v4, v4, v11, s68
	v_add3_u32 v9, v60, v9, s68
	v_add3_u32 v8, v61, v8, s68
	v_and_b32_e32 v5, 0xffff0000, v5
	v_and_b32_e32 v4, 0xffff0000, v4
	v_lshlrev_b32_e32 v17, 16, v59
	v_lshlrev_b32_e32 v21, 16, v58
	v_or_b32_sdwa v5, v5, v8 dst_sel:DWORD dst_unused:UNUSED_PAD src0_sel:DWORD src1_sel:WORD_1
	v_or_b32_sdwa v4, v4, v9 dst_sel:DWORD dst_unused:UNUSED_PAD src0_sel:DWORD src1_sel:WORD_1
	v_mul_f32_e32 v8, 0xbfb8aa3b, v21
	v_mul_f32_e32 v9, 0xbfb8aa3b, v17
	v_exp_f32_e32 v8, v8
	v_exp_f32_e32 v9, v9
	v_and_b32_e32 v29, 0xffff0000, v58
	v_mul_f32_e32 v10, 0xbfb8aa3b, v29
	v_and_b32_e32 v25, 0xffff0000, v59
	v_exp_f32_e32 v60, v10
	v_pk_add_f32 v[64:65], v[8:9], 1.0 op_sel_hi:[1,0]
	global_load_dwordx4 v[8:11], v[18:19], off
	global_load_dwordx4 v[56:59], v[18:19], off offset:2048
	s_waitcnt lgkmcnt(0)
; __device__ __forceinline__ unsigned pack2(float a, float b) { return (unsigned)f2bf(a) | ((unsigned)f2bf(b) << 16); }
; __device__ __forceinline__ float bflo(unsigned w) { return __uint_as_float(w << 16); }
; __device__ __forceinline__ float bfhi(unsigned w) { return __uint_as_float(w & 0xffff0000u); }
; __device__ __forceinline__ float silu_f(float g) { return g / (1.f + __expf(-g)); }
; __device__ void gmlp_item(const Params& p, int layer, int b, int n, int g, char* smem) {
;     ...
; #pragma unroll
;     for (int i = 0; i < 8; ++i) {
;       int q = tid + 256 * i, t = q >> 4, c = (q & 15) * 8;
;       float4 m0 = *reinterpret_cast<const float4*>(Tf + t * 132 + c);
;       float4 m1 = *reinterpret_cast<const float4*>(Tf + t * 132 + c + 4);
;       float mm[8] = {m0.x, m0.y, m0.z, m0.w, m1.x, m1.y, m1.z, m1.w};
;       unsigned uw[4] = {uu[i].x, uu[i].y, uu[i].z, uu[i].w};
;       unsigned gw[4] = {gt[i].x, gt[i].y, gt[i].z, gt[i].w};
;       unsigned ow[4];
; #pragma unroll
;       for (int e = 0; e < 4; ++e) {
;         float y0 = bflo(uw[e]) * mm[2 * e] * silu_f(bflo(gw[e]));
;         float y1 = bfhi(uw[e]) * mm[2 * e + 1] * silu_f(bfhi(gw[e]));
;         ow[e] = pack2(y0, y1);
;       }
;       *reinterpret_cast<uint4*>(Y + (t0 + t) * YW + g * 128 + c) = make_uint4(ow[0], ow[1], ow[2], ow[3]);
;     }
	v_mov_b32_e32 v18, v12
	v_mov_b32_e32 v19, v14
	v_pk_mul_f32 v[18:19], v[18:19], v[62:63]
	v_rcp_f32_e32 v63, v65
	s_nop 0
	v_mul_f32_e32 v63, v17, v63
	v_and_b32_e32 v7, 0xffff0000, v7
	v_mul_f32_e32 v14, 0xbfb8aa3b, v25
	v_exp_f32_e32 v61, v14
	v_rcp_f32_e32 v62, v64
	s_nop 0
	v_mul_f32_e32 v62, v21, v62
	v_mov_b32_e32 v14, v13
	v_and_b32_e32 v6, 0xffff0000, v6
	v_pk_add_f32 v[60:61], v[60:61], 1.0 op_sel_hi:[1,0]
	v_pk_mul_f32 v[6:7], v[14:15], v[6:7]
	v_pk_mul_f32 v[18:19], v[62:63], v[18:19]
	v_rcp_f32_e32 v13, v61
	s_nop 0
	v_mul_f32_e32 v13, v25, v13
	v_rcp_f32_e32 v12, v60
	s_nop 0
	v_mul_f32_e32 v12, v29, v12
	v_pk_mul_f32 v[6:7], v[12:13], v[6:7]
	v_and_b32_sdwa v12, v19, v155 dst_sel:DWORD dst_unused:UNUSED_PAD src0_sel:WORD_1 src1_sel:DWORD
	v_and_b32_sdwa v14, v7, v155 dst_sel:DWORD dst_unused:UNUSED_PAD src0_sel:WORD_1 src1_sel:DWORD
	v_add3_u32 v7, v7, v14, s68
	v_add3_u32 v12, v19, v12, s68
	v_and_b32_e32 v7, 0xffff0000, v7
	v_or_b32_sdwa v7, v7, v12 dst_sel:DWORD dst_unused:UNUSED_PAD src0_sel:DWORD src1_sel:WORD_1
	v_and_b32_sdwa v15, v6, v155 dst_sel:DWORD dst_unused:UNUSED_PAD src0_sel:WORD_1 src1_sel:DWORD
	v_and_b32_sdwa v13, v18, v155 dst_sel:DWORD dst_unused:UNUSED_PAD src0_sel:WORD_1 src1_sel:DWORD
	v_add3_u32 v6, v6, v15, s68
	v_add3_u32 v13, v18, v13, s68
	v_and_b32_e32 v6, 0xffff0000, v6
	v_or_b32_sdwa v6, v6, v13 dst_sel:DWORD dst_unused:UNUSED_PAD src0_sel:DWORD src1_sel:WORD_1
	s_waitcnt vmcnt(1)
	v_lshlrev_b32_e32 v63, 16, v9
	s_waitcnt vmcnt(0)
	v_lshlrev_b32_e32 v25, 16, v56
	v_mul_f32_e32 v12, 0xbfb8aa3b, v25
	v_and_b32_e32 v35, 0xffff0000, v56
	v_lshlrev_b32_e32 v21, 16, v57
	v_exp_f32_e32 v60, v12
	v_mul_f32_e32 v12, 0xbfb8aa3b, v35
	v_exp_f32_e32 v56, v12
	v_mul_f32_e32 v12, 0xbfb8aa3b, v21
	v_exp_f32_e32 v61, v12
	v_and_b32_e32 v29, 0xffff0000, v57
	ds_read_b128 v[12:15], v16
	ds_read_b128 v[16:19], v16 offset:16
	v_lshlrev_b32_e32 v62, 16, v8
	v_pk_add_f32 v[60:61], v[60:61], 1.0 op_sel_hi:[1,0]
	v_and_b32_e32 v9, 0xffff0000, v9
	s_waitcnt lgkmcnt(1)
	v_mov_b32_e32 v64, v12
	v_mov_b32_e32 v65, v14
	v_pk_mul_f32 v[62:63], v[64:65], v[62:63]
	v_rcp_f32_e32 v61, v61
	s_nop 0
	v_mul_f32_e32 v61, v21, v61
	v_and_b32_e32 v8, 0xffff0000, v8
	v_mul_f32_e32 v14, 0xbfb8aa3b, v29
	v_exp_f32_e32 v57, v14
	v_rcp_f32_e32 v60, v60
	s_nop 0
	v_mul_f32_e32 v60, v25, v60
	v_mov_b32_e32 v14, v13
	v_pk_mul_f32 v[8:9], v[14:15], v[8:9]
	v_pk_add_f32 v[56:57], v[56:57], 1.0 op_sel_hi:[1,0]
	v_pk_mul_f32 v[60:61], v[60:61], v[62:63]
	v_lshlrev_b32_e32 v63, 16, v11
	v_lshlrev_b32_e32 v62, 16, v10
	v_and_b32_e32 v11, 0xffff0000, v11
	v_rcp_f32_e32 v13, v57
	s_nop 0
	v_mul_f32_e32 v13, v29, v13
	v_rcp_f32_e32 v12, v56
	s_nop 0
	v_mul_f32_e32 v12, v35, v12
	v_pk_mul_f32 v[8:9], v[12:13], v[8:9]
	v_and_b32_sdwa v12, v61, v155 dst_sel:DWORD dst_unused:UNUSED_PAD src0_sel:WORD_1 src1_sel:DWORD
	v_and_b32_sdwa v14, v9, v155 dst_sel:DWORD dst_unused:UNUSED_PAD src0_sel:WORD_1 src1_sel:DWORD
	v_and_b32_sdwa v15, v8, v155 dst_sel:DWORD dst_unused:UNUSED_PAD src0_sel:WORD_1 src1_sel:DWORD
	v_and_b32_sdwa v13, v60, v155 dst_sel:DWORD dst_unused:UNUSED_PAD src0_sel:WORD_1 src1_sel:DWORD
	v_add3_u32 v9, v9, v14, s68
	v_add3_u32 v8, v8, v15, s68
	v_add3_u32 v13, v60, v13, s68
	v_add3_u32 v12, v61, v12, s68
	v_and_b32_e32 v9, 0xffff0000, v9
	v_and_b32_e32 v8, 0xffff0000, v8
	v_lshlrev_b32_e32 v21, 16, v59
	v_lshlrev_b32_e32 v25, 16, v58
	v_or_b32_sdwa v9, v9, v12 dst_sel:DWORD dst_unused:UNUSED_PAD src0_sel:DWORD src1_sel:WORD_1
	v_or_b32_sdwa v8, v8, v13 dst_sel:DWORD dst_unused:UNUSED_PAD src0_sel:DWORD src1_sel:WORD_1
	v_mul_f32_e32 v12, 0xbfb8aa3b, v25
	v_mul_f32_e32 v13, 0xbfb8aa3b, v21
	v_exp_f32_e32 v12, v12
	v_exp_f32_e32 v13, v13
	v_and_b32_e32 v35, 0xffff0000, v58
	v_mul_f32_e32 v14, 0xbfb8aa3b, v35
	v_and_b32_e32 v29, 0xffff0000, v59
	v_exp_f32_e32 v60, v14
	v_pk_add_f32 v[64:65], v[12:13], 1.0 op_sel_hi:[1,0]
	global_load_dwordx4 v[12:15], v[22:23], off
	global_load_dwordx4 v[56:59], v[22:23], off offset:2048
	s_waitcnt lgkmcnt(0)
	v_mov_b32_e32 v22, v16
	v_mov_b32_e32 v23, v18
	v_pk_mul_f32 v[22:23], v[22:23], v[62:63]
	v_rcp_f32_e32 v63, v65
	s_nop 0
	v_mul_f32_e32 v63, v21, v63
	v_and_b32_e32 v10, 0xffff0000, v10
	v_mul_f32_e32 v18, 0xbfb8aa3b, v29
	v_exp_f32_e32 v61, v18
	v_rcp_f32_e32 v62, v64
	s_nop 0
	v_mul_f32_e32 v62, v25, v62
	v_mov_b32_e32 v18, v17
	v_pk_mul_f32 v[10:11], v[18:19], v[10:11]
	v_pk_add_f32 v[60:61], v[60:61], 1.0 op_sel_hi:[1,0]
	v_pk_mul_f32 v[22:23], v[62:63], v[22:23]
	s_waitcnt vmcnt(1)
	v_lshlrev_b32_e32 v63, 16, v13
	v_rcp_f32_e32 v17, v61
	s_nop 0
	v_mul_f32_e32 v17, v29, v17
	v_rcp_f32_e32 v16, v60
	s_nop 0
	v_mul_f32_e32 v16, v35, v16
	v_pk_mul_f32 v[10:11], v[16:17], v[10:11]
	v_and_b32_sdwa v16, v23, v155 dst_sel:DWORD dst_unused:UNUSED_PAD src0_sel:WORD_1 src1_sel:DWORD
	v_and_b32_sdwa v18, v11, v155 dst_sel:DWORD dst_unused:UNUSED_PAD src0_sel:WORD_1 src1_sel:DWORD
	v_add3_u32 v11, v11, v18, s68
	v_add3_u32 v16, v23, v16, s68
	v_and_b32_e32 v11, 0xffff0000, v11
	s_waitcnt vmcnt(0)
	v_lshlrev_b32_e32 v29, 16, v56
	v_or_b32_sdwa v11, v11, v16 dst_sel:DWORD dst_unused:UNUSED_PAD src0_sel:DWORD src1_sel:WORD_1
	v_mul_f32_e32 v16, 0xbfb8aa3b, v29
	v_and_b32_e32 v55, 0xffff0000, v56
	v_lshlrev_b32_e32 v25, 16, v57
	v_exp_f32_e32 v60, v16
	v_mul_f32_e32 v16, 0xbfb8aa3b, v55
	v_exp_f32_e32 v56, v16
	v_mul_f32_e32 v16, 0xbfb8aa3b, v25
	v_exp_f32_e32 v61, v16
	v_and_b32_sdwa v19, v10, v155 dst_sel:DWORD dst_unused:UNUSED_PAD src0_sel:WORD_1 src1_sel:DWORD
	v_and_b32_sdwa v17, v22, v155 dst_sel:DWORD dst_unused:UNUSED_PAD src0_sel:WORD_1 src1_sel:DWORD
	v_add3_u32 v10, v10, v19, s68
	v_pk_add_f32 v[60:61], v[60:61], 1.0 op_sel_hi:[1,0]
	v_add3_u32 v17, v22, v17, s68
	v_and_b32_e32 v10, 0xffff0000, v10
	v_and_b32_e32 v35, 0xffff0000, v57
	v_or_b32_sdwa v10, v10, v17 dst_sel:DWORD dst_unused:UNUSED_PAD src0_sel:DWORD src1_sel:WORD_1
	ds_read_b128 v[16:19], v20
	ds_read_b128 v[20:23], v20 offset:16
	v_lshlrev_b32_e32 v62, 16, v12
	v_and_b32_e32 v13, 0xffff0000, v13
	s_waitcnt lgkmcnt(1)
; __device__ __forceinline__ unsigned pack2(float a, float b) { return (unsigned)f2bf(a) | ((unsigned)f2bf(b) << 16); }
; __device__ __forceinline__ float bflo(unsigned w) { return __uint_as_float(w << 16); }
; __device__ __forceinline__ float bfhi(unsigned w) { return __uint_as_float(w & 0xffff0000u); }
; __device__ __forceinline__ float silu_f(float g) { return g / (1.f + __expf(-g)); }
; __device__ void gmlp_item(const Params& p, int layer, int b, int n, int g, char* smem) {
;     ...
; #pragma unroll
;     for (int i = 0; i < 8; ++i) {
;       int q = tid + 256 * i, t = q >> 4, c = (q & 15) * 8;
;       float4 m0 = *reinterpret_cast<const float4*>(Tf + t * 132 + c);
;       float4 m1 = *reinterpret_cast<const float4*>(Tf + t * 132 + c + 4);
;       float mm[8] = {m0.x, m0.y, m0.z, m0.w, m1.x, m1.y, m1.z, m1.w};
;       unsigned uw[4] = {uu[i].x, uu[i].y, uu[i].z, uu[i].w};
;       unsigned gw[4] = {gt[i].x, gt[i].y, gt[i].z, gt[i].w};
;       unsigned ow[4];
; #pragma unroll
;       for (int e = 0; e < 4; ++e) {
;         float y0 = bflo(uw[e]) * mm[2 * e] * silu_f(bflo(gw[e]));
;         float y1 = bfhi(uw[e]) * mm[2 * e + 1] * silu_f(bfhi(gw[e]));
;         ow[e] = pack2(y0, y1);
;       }
;       *reinterpret_cast<uint4*>(Y + (t0 + t) * YW + g * 128 + c) = make_uint4(ow[0], ow[1], ow[2], ow[3]);
;     }
	v_mov_b32_e32 v64, v16
	v_mov_b32_e32 v65, v18
	v_pk_mul_f32 v[62:63], v[64:65], v[62:63]
	v_rcp_f32_e32 v61, v61
	s_nop 0
	v_mul_f32_e32 v61, v25, v61
	v_and_b32_e32 v12, 0xffff0000, v12
	v_mul_f32_e32 v18, 0xbfb8aa3b, v35
	v_exp_f32_e32 v57, v18
	v_rcp_f32_e32 v60, v60
	s_nop 0
	v_mul_f32_e32 v60, v29, v60
	v_mov_b32_e32 v18, v17
	v_pk_mul_f32 v[12:13], v[18:19], v[12:13]
	v_pk_add_f32 v[56:57], v[56:57], 1.0 op_sel_hi:[1,0]
	v_pk_mul_f32 v[60:61], v[60:61], v[62:63]
	v_lshlrev_b32_e32 v63, 16, v15
	v_lshlrev_b32_e32 v62, 16, v14
	v_and_b32_e32 v15, 0xffff0000, v15
	v_rcp_f32_e32 v17, v57
	s_nop 0
	v_mul_f32_e32 v17, v35, v17
	v_rcp_f32_e32 v16, v56
	s_nop 0
	v_mul_f32_e32 v16, v55, v16
	v_pk_mul_f32 v[12:13], v[16:17], v[12:13]
	v_and_b32_sdwa v16, v61, v155 dst_sel:DWORD dst_unused:UNUSED_PAD src0_sel:WORD_1 src1_sel:DWORD
	v_and_b32_sdwa v18, v13, v155 dst_sel:DWORD dst_unused:UNUSED_PAD src0_sel:WORD_1 src1_sel:DWORD
	v_and_b32_sdwa v19, v12, v155 dst_sel:DWORD dst_unused:UNUSED_PAD src0_sel:WORD_1 src1_sel:DWORD
	v_and_b32_sdwa v17, v60, v155 dst_sel:DWORD dst_unused:UNUSED_PAD src0_sel:WORD_1 src1_sel:DWORD
	v_add3_u32 v13, v13, v18, s68
	v_add3_u32 v12, v12, v19, s68
	v_add3_u32 v17, v60, v17, s68
	v_add3_u32 v16, v61, v16, s68
	v_and_b32_e32 v13, 0xffff0000, v13
	v_and_b32_e32 v12, 0xffff0000, v12
	v_lshlrev_b32_e32 v25, 16, v59
	v_lshlrev_b32_e32 v29, 16, v58
	v_or_b32_sdwa v13, v13, v16 dst_sel:DWORD dst_unused:UNUSED_PAD src0_sel:DWORD src1_sel:WORD_1
	v_or_b32_sdwa v12, v12, v17 dst_sel:DWORD dst_unused:UNUSED_PAD src0_sel:DWORD src1_sel:WORD_1
	v_mul_f32_e32 v16, 0xbfb8aa3b, v29
	v_mul_f32_e32 v17, 0xbfb8aa3b, v25
	v_exp_f32_e32 v16, v16
	v_exp_f32_e32 v17, v17
	v_and_b32_e32 v55, 0xffff0000, v58
	v_mul_f32_e32 v18, 0xbfb8aa3b, v55
	v_and_b32_e32 v35, 0xffff0000, v59
	v_exp_f32_e32 v60, v18
	v_pk_add_f32 v[64:65], v[16:17], 1.0 op_sel_hi:[1,0]
	global_load_dwordx4 v[16:19], v[26:27], off
	global_load_dwordx4 v[56:59], v[26:27], off offset:2048
	s_waitcnt lgkmcnt(0)
	v_mov_b32_e32 v26, v20
	v_mov_b32_e32 v27, v22
	v_pk_mul_f32 v[26:27], v[26:27], v[62:63]
	v_rcp_f32_e32 v63, v65
	s_nop 0
	v_mul_f32_e32 v63, v25, v63
	v_and_b32_e32 v14, 0xffff0000, v14
	v_mul_f32_e32 v22, 0xbfb8aa3b, v35
	v_exp_f32_e32 v61, v22
	v_rcp_f32_e32 v62, v64
	s_nop 0
	v_mul_f32_e32 v62, v29, v62
	v_mov_b32_e32 v22, v21
	v_pk_mul_f32 v[14:15], v[22:23], v[14:15]
	v_pk_add_f32 v[60:61], v[60:61], 1.0 op_sel_hi:[1,0]
	v_pk_mul_f32 v[26:27], v[62:63], v[26:27]
	s_waitcnt vmcnt(1)
	v_lshlrev_b32_e32 v63, 16, v17
	v_rcp_f32_e32 v21, v61
	s_nop 0
	v_mul_f32_e32 v21, v35, v21
	v_rcp_f32_e32 v20, v60
	s_nop 0
	v_mul_f32_e32 v20, v55, v20
	v_pk_mul_f32 v[14:15], v[20:21], v[14:15]
	v_and_b32_sdwa v20, v27, v155 dst_sel:DWORD dst_unused:UNUSED_PAD src0_sel:WORD_1 src1_sel:DWORD
	v_and_b32_sdwa v22, v15, v155 dst_sel:DWORD dst_unused:UNUSED_PAD src0_sel:WORD_1 src1_sel:DWORD
	v_add3_u32 v15, v15, v22, s68
	v_add3_u32 v20, v27, v20, s68
	v_and_b32_e32 v15, 0xffff0000, v15
	s_waitcnt vmcnt(0)
	v_lshlrev_b32_e32 v35, 16, v56
	v_or_b32_sdwa v15, v15, v20 dst_sel:DWORD dst_unused:UNUSED_PAD src0_sel:DWORD src1_sel:WORD_1
	v_mul_f32_e32 v20, 0xbfb8aa3b, v35
	v_and_b32_e32 v66, 0xffff0000, v56
	v_lshlrev_b32_e32 v29, 16, v57
	v_exp_f32_e32 v60, v20
	v_mul_f32_e32 v20, 0xbfb8aa3b, v66
	v_exp_f32_e32 v56, v20
	v_mul_f32_e32 v20, 0xbfb8aa3b, v29
	v_exp_f32_e32 v61, v20
	v_and_b32_sdwa v23, v14, v155 dst_sel:DWORD dst_unused:UNUSED_PAD src0_sel:WORD_1 src1_sel:DWORD
	v_and_b32_sdwa v21, v26, v155 dst_sel:DWORD dst_unused:UNUSED_PAD src0_sel:WORD_1 src1_sel:DWORD
	v_add3_u32 v14, v14, v23, s68
	v_pk_add_f32 v[60:61], v[60:61], 1.0 op_sel_hi:[1,0]
	v_add3_u32 v21, v26, v21, s68
	v_and_b32_e32 v14, 0xffff0000, v14
	v_and_b32_e32 v55, 0xffff0000, v57
	v_or_b32_sdwa v14, v14, v21 dst_sel:DWORD dst_unused:UNUSED_PAD src0_sel:DWORD src1_sel:WORD_1
	ds_read_b128 v[20:23], v24
	ds_read_b128 v[24:27], v24 offset:16
	v_lshlrev_b32_e32 v62, 16, v16
	v_and_b32_e32 v17, 0xffff0000, v17
	s_waitcnt lgkmcnt(1)
	v_mov_b32_e32 v64, v20
	v_mov_b32_e32 v65, v22
	v_pk_mul_f32 v[62:63], v[64:65], v[62:63]
	v_rcp_f32_e32 v61, v61
	s_nop 0
	v_mul_f32_e32 v61, v29, v61
	v_and_b32_e32 v16, 0xffff0000, v16
	v_mul_f32_e32 v22, 0xbfb8aa3b, v55
	v_exp_f32_e32 v57, v22
	v_rcp_f32_e32 v60, v60
	s_nop 0
	v_mul_f32_e32 v60, v35, v60
	v_mov_b32_e32 v22, v21
	v_pk_mul_f32 v[16:17], v[22:23], v[16:17]
	v_pk_add_f32 v[56:57], v[56:57], 1.0 op_sel_hi:[1,0]
	v_pk_mul_f32 v[60:61], v[60:61], v[62:63]
	v_lshlrev_b32_e32 v63, 16, v19
	v_lshlrev_b32_e32 v62, 16, v18
	v_and_b32_e32 v19, 0xffff0000, v19
	v_rcp_f32_e32 v21, v57
	s_nop 0
	v_mul_f32_e32 v21, v55, v21
	v_rcp_f32_e32 v20, v56
	s_nop 0
	v_mul_f32_e32 v20, v66, v20
	v_pk_mul_f32 v[16:17], v[20:21], v[16:17]
	v_and_b32_sdwa v20, v61, v155 dst_sel:DWORD dst_unused:UNUSED_PAD src0_sel:WORD_1 src1_sel:DWORD
	v_and_b32_sdwa v22, v17, v155 dst_sel:DWORD dst_unused:UNUSED_PAD src0_sel:WORD_1 src1_sel:DWORD
	v_and_b32_sdwa v23, v16, v155 dst_sel:DWORD dst_unused:UNUSED_PAD src0_sel:WORD_1 src1_sel:DWORD
	v_and_b32_sdwa v21, v60, v155 dst_sel:DWORD dst_unused:UNUSED_PAD src0_sel:WORD_1 src1_sel:DWORD
	v_add3_u32 v17, v17, v22, s68
	v_add3_u32 v16, v16, v23, s68
	v_add3_u32 v21, v60, v21, s68
	v_add3_u32 v20, v61, v20, s68
	v_and_b32_e32 v17, 0xffff0000, v17
	v_and_b32_e32 v16, 0xffff0000, v16
	v_lshlrev_b32_e32 v29, 16, v59
	v_lshlrev_b32_e32 v35, 16, v58
	v_or_b32_sdwa v17, v17, v20 dst_sel:DWORD dst_unused:UNUSED_PAD src0_sel:DWORD src1_sel:WORD_1
	v_or_b32_sdwa v16, v16, v21 dst_sel:DWORD dst_unused:UNUSED_PAD src0_sel:DWORD src1_sel:WORD_1
	v_mul_f32_e32 v20, 0xbfb8aa3b, v35
	v_mul_f32_e32 v21, 0xbfb8aa3b, v29
	v_exp_f32_e32 v20, v20
	v_exp_f32_e32 v21, v21
	v_and_b32_e32 v66, 0xffff0000, v58
	v_mul_f32_e32 v22, 0xbfb8aa3b, v66
	v_and_b32_e32 v55, 0xffff0000, v59
	v_exp_f32_e32 v60, v22
	v_pk_add_f32 v[64:65], v[20:21], 1.0 op_sel_hi:[1,0]
	global_load_dwordx4 v[20:23], v[30:31], off
	global_load_dwordx4 v[56:59], v[30:31], off offset:2048
	s_waitcnt lgkmcnt(0)
; __device__ __forceinline__ unsigned pack2(float a, float b) { return (unsigned)f2bf(a) | ((unsigned)f2bf(b) << 16); }
; __device__ __forceinline__ float bflo(unsigned w) { return __uint_as_float(w << 16); }
; __device__ __forceinline__ float bfhi(unsigned w) { return __uint_as_float(w & 0xffff0000u); }
; __device__ __forceinline__ float silu_f(float g) { return g / (1.f + __expf(-g)); }
; __device__ void gmlp_item(const Params& p, int layer, int b, int n, int g, char* smem) {
;     ...
; #pragma unroll
;     for (int i = 0; i < 8; ++i) {
;       int q = tid + 256 * i, t = q >> 4, c = (q & 15) * 8;
;       float4 m0 = *reinterpret_cast<const float4*>(Tf + t * 132 + c);
;       float4 m1 = *reinterpret_cast<const float4*>(Tf + t * 132 + c + 4);
;       float mm[8] = {m0.x, m0.y, m0.z, m0.w, m1.x, m1.y, m1.z, m1.w};
;       unsigned uw[4] = {uu[i].x, uu[i].y, uu[i].z, uu[i].w};
;       unsigned gw[4] = {gt[i].x, gt[i].y, gt[i].z, gt[i].w};
;       unsigned ow[4];
; #pragma unroll
;       for (int e = 0; e < 4; ++e) {
;         float y0 = bflo(uw[e]) * mm[2 * e] * silu_f(bflo(gw[e]));
;         float y1 = bfhi(uw[e]) * mm[2 * e + 1] * silu_f(bfhi(gw[e]));
;         ow[e] = pack2(y0, y1);
;       }
;       *reinterpret_cast<uint4*>(Y + (t0 + t) * YW + g * 128 + c) = make_uint4(ow[0], ow[1], ow[2], ow[3]);
;     }
	v_mov_b32_e32 v30, v24
	v_mov_b32_e32 v31, v26
	v_pk_mul_f32 v[30:31], v[30:31], v[62:63]
	v_rcp_f32_e32 v63, v65
	s_nop 0
	v_mul_f32_e32 v63, v29, v63
	v_and_b32_e32 v18, 0xffff0000, v18
	v_mul_f32_e32 v26, 0xbfb8aa3b, v55
	v_exp_f32_e32 v61, v26
	v_rcp_f32_e32 v62, v64
	s_nop 0
	v_mul_f32_e32 v62, v35, v62
	v_mov_b32_e32 v26, v25
	v_pk_mul_f32 v[18:19], v[26:27], v[18:19]
	v_pk_add_f32 v[60:61], v[60:61], 1.0 op_sel_hi:[1,0]
	v_pk_mul_f32 v[30:31], v[62:63], v[30:31]
	s_waitcnt vmcnt(1)
	v_lshlrev_b32_e32 v63, 16, v21
	v_rcp_f32_e32 v25, v61
	s_nop 0
	v_mul_f32_e32 v25, v55, v25
	v_rcp_f32_e32 v24, v60
	s_nop 0
	v_mul_f32_e32 v24, v66, v24
	v_pk_mul_f32 v[18:19], v[24:25], v[18:19]
	v_and_b32_sdwa v24, v31, v155 dst_sel:DWORD dst_unused:UNUSED_PAD src0_sel:WORD_1 src1_sel:DWORD
	v_and_b32_sdwa v26, v19, v155 dst_sel:DWORD dst_unused:UNUSED_PAD src0_sel:WORD_1 src1_sel:DWORD
	v_add3_u32 v19, v19, v26, s68
	v_add3_u32 v24, v31, v24, s68
	v_and_b32_e32 v19, 0xffff0000, v19
	s_waitcnt vmcnt(0)
	v_lshlrev_b32_e32 v55, 16, v56
	v_or_b32_sdwa v19, v19, v24 dst_sel:DWORD dst_unused:UNUSED_PAD src0_sel:DWORD src1_sel:WORD_1
	v_mul_f32_e32 v24, 0xbfb8aa3b, v55
	v_and_b32_e32 v67, 0xffff0000, v56
	v_lshlrev_b32_e32 v35, 16, v57
	v_exp_f32_e32 v60, v24
	v_mul_f32_e32 v24, 0xbfb8aa3b, v67
	v_exp_f32_e32 v56, v24
	v_mul_f32_e32 v24, 0xbfb8aa3b, v35
	v_exp_f32_e32 v61, v24
	v_and_b32_sdwa v27, v18, v155 dst_sel:DWORD dst_unused:UNUSED_PAD src0_sel:WORD_1 src1_sel:DWORD
	v_and_b32_sdwa v25, v30, v155 dst_sel:DWORD dst_unused:UNUSED_PAD src0_sel:WORD_1 src1_sel:DWORD
	v_add3_u32 v18, v18, v27, s68
	v_pk_add_f32 v[60:61], v[60:61], 1.0 op_sel_hi:[1,0]
	v_add3_u32 v25, v30, v25, s68
	v_and_b32_e32 v18, 0xffff0000, v18
	v_and_b32_e32 v66, 0xffff0000, v57
	v_or_b32_sdwa v18, v18, v25 dst_sel:DWORD dst_unused:UNUSED_PAD src0_sel:DWORD src1_sel:WORD_1
	ds_read_b128 v[24:27], v28
	ds_read_b128 v[28:31], v28 offset:16
	v_lshlrev_b32_e32 v62, 16, v20
	v_and_b32_e32 v21, 0xffff0000, v21
	s_waitcnt lgkmcnt(1)
	v_mov_b32_e32 v64, v24
	v_mov_b32_e32 v65, v26
	v_pk_mul_f32 v[62:63], v[64:65], v[62:63]
	v_rcp_f32_e32 v61, v61
	s_nop 0
	v_mul_f32_e32 v61, v35, v61
	v_and_b32_e32 v20, 0xffff0000, v20
	v_mul_f32_e32 v26, 0xbfb8aa3b, v66
	v_exp_f32_e32 v57, v26
	v_rcp_f32_e32 v60, v60
	s_nop 0
	v_mul_f32_e32 v60, v55, v60
	v_mov_b32_e32 v26, v25
	v_pk_mul_f32 v[20:21], v[26:27], v[20:21]
	v_pk_add_f32 v[56:57], v[56:57], 1.0 op_sel_hi:[1,0]
	v_pk_mul_f32 v[60:61], v[60:61], v[62:63]
	v_lshlrev_b32_e32 v63, 16, v23
	v_lshlrev_b32_e32 v62, 16, v22
	v_and_b32_e32 v23, 0xffff0000, v23
	v_rcp_f32_e32 v25, v57
	s_nop 0
	v_mul_f32_e32 v25, v66, v25
	v_rcp_f32_e32 v24, v56
	s_nop 0
	v_mul_f32_e32 v24, v67, v24
	v_pk_mul_f32 v[20:21], v[24:25], v[20:21]
	v_and_b32_sdwa v24, v61, v155 dst_sel:DWORD dst_unused:UNUSED_PAD src0_sel:WORD_1 src1_sel:DWORD
	v_and_b32_sdwa v26, v21, v155 dst_sel:DWORD dst_unused:UNUSED_PAD src0_sel:WORD_1 src1_sel:DWORD
	v_and_b32_sdwa v27, v20, v155 dst_sel:DWORD dst_unused:UNUSED_PAD src0_sel:WORD_1 src1_sel:DWORD
	v_and_b32_sdwa v25, v60, v155 dst_sel:DWORD dst_unused:UNUSED_PAD src0_sel:WORD_1 src1_sel:DWORD
	v_add3_u32 v21, v21, v26, s68
	v_add3_u32 v20, v20, v27, s68
	v_add3_u32 v25, v60, v25, s68
	v_add3_u32 v24, v61, v24, s68
	v_and_b32_e32 v21, 0xffff0000, v21
	v_and_b32_e32 v20, 0xffff0000, v20
	v_lshlrev_b32_e32 v35, 16, v59
	v_lshlrev_b32_e32 v55, 16, v58
	v_or_b32_sdwa v21, v21, v24 dst_sel:DWORD dst_unused:UNUSED_PAD src0_sel:DWORD src1_sel:WORD_1
	v_or_b32_sdwa v20, v20, v25 dst_sel:DWORD dst_unused:UNUSED_PAD src0_sel:DWORD src1_sel:WORD_1
	v_mul_f32_e32 v24, 0xbfb8aa3b, v55
	v_mul_f32_e32 v25, 0xbfb8aa3b, v35
	v_exp_f32_e32 v24, v24
	v_exp_f32_e32 v25, v25
	v_and_b32_e32 v67, 0xffff0000, v58
	v_mul_f32_e32 v26, 0xbfb8aa3b, v67
	v_and_b32_e32 v66, 0xffff0000, v59
	v_exp_f32_e32 v60, v26
	v_pk_add_f32 v[64:65], v[24:25], 1.0 op_sel_hi:[1,0]
	global_load_dwordx4 v[24:27], v[32:33], off
	global_load_dwordx4 v[56:59], v[32:33], off offset:2048
	s_waitcnt lgkmcnt(0)
	v_mov_b32_e32 v32, v28
	v_mov_b32_e32 v33, v30
	v_pk_mul_f32 v[32:33], v[32:33], v[62:63]
	v_rcp_f32_e32 v63, v65
	s_nop 0
	v_mul_f32_e32 v63, v35, v63
	v_and_b32_e32 v22, 0xffff0000, v22
	v_mul_f32_e32 v30, 0xbfb8aa3b, v66
	v_exp_f32_e32 v61, v30
	v_rcp_f32_e32 v62, v64
	s_nop 0
	v_mul_f32_e32 v62, v55, v62
	v_mov_b32_e32 v30, v29
	v_pk_mul_f32 v[22:23], v[30:31], v[22:23]
	v_pk_add_f32 v[60:61], v[60:61], 1.0 op_sel_hi:[1,0]
	v_pk_mul_f32 v[32:33], v[62:63], v[32:33]
	s_waitcnt vmcnt(1)
	v_lshlrev_b32_e32 v63, 16, v25
	v_rcp_f32_e32 v29, v61
	s_nop 0
	v_mul_f32_e32 v29, v66, v29
	v_rcp_f32_e32 v28, v60
	s_nop 0
	v_mul_f32_e32 v28, v67, v28
	v_pk_mul_f32 v[22:23], v[28:29], v[22:23]
	v_and_b32_sdwa v28, v33, v155 dst_sel:DWORD dst_unused:UNUSED_PAD src0_sel:WORD_1 src1_sel:DWORD
	v_and_b32_sdwa v30, v23, v155 dst_sel:DWORD dst_unused:UNUSED_PAD src0_sel:WORD_1 src1_sel:DWORD
	v_add3_u32 v23, v23, v30, s68
	v_add3_u32 v28, v33, v28, s68
	v_and_b32_e32 v23, 0xffff0000, v23
	s_waitcnt vmcnt(0)
	v_lshlrev_b32_e32 v66, 16, v56
	v_or_b32_sdwa v23, v23, v28 dst_sel:DWORD dst_unused:UNUSED_PAD src0_sel:DWORD src1_sel:WORD_1
	v_mul_f32_e32 v28, 0xbfb8aa3b, v66
	v_and_b32_e32 v68, 0xffff0000, v56
	v_lshlrev_b32_e32 v55, 16, v57
	v_exp_f32_e32 v60, v28
	v_mul_f32_e32 v28, 0xbfb8aa3b, v68
	v_exp_f32_e32 v56, v28
	v_mul_f32_e32 v28, 0xbfb8aa3b, v55
	v_exp_f32_e32 v61, v28
	v_and_b32_sdwa v31, v22, v155 dst_sel:DWORD dst_unused:UNUSED_PAD src0_sel:WORD_1 src1_sel:DWORD
	v_and_b32_sdwa v29, v32, v155 dst_sel:DWORD dst_unused:UNUSED_PAD src0_sel:WORD_1 src1_sel:DWORD
	v_add3_u32 v22, v22, v31, s68
	v_pk_add_f32 v[60:61], v[60:61], 1.0 op_sel_hi:[1,0]
	v_add3_u32 v29, v32, v29, s68
	v_and_b32_e32 v22, 0xffff0000, v22
	v_and_b32_e32 v67, 0xffff0000, v57
	v_or_b32_sdwa v22, v22, v29 dst_sel:DWORD dst_unused:UNUSED_PAD src0_sel:DWORD src1_sel:WORD_1
	ds_read_b128 v[28:31], v34
	ds_read_b128 v[32:35], v34 offset:16
	v_lshlrev_b32_e32 v62, 16, v24
	v_and_b32_e32 v25, 0xffff0000, v25
	s_waitcnt lgkmcnt(1)
; __device__ __forceinline__ unsigned pack2(float a, float b) { return (unsigned)f2bf(a) | ((unsigned)f2bf(b) << 16); }
; __device__ __forceinline__ float bflo(unsigned w) { return __uint_as_float(w << 16); }
; __device__ __forceinline__ float bfhi(unsigned w) { return __uint_as_float(w & 0xffff0000u); }
; __device__ __forceinline__ float silu_f(float g) { return g / (1.f + __expf(-g)); }
; __device__ void gmlp_item(const Params& p, int layer, int b, int n, int g, char* smem) {
;     ...
; #pragma unroll
;     for (int i = 0; i < 8; ++i) {
;       int q = tid + 256 * i, t = q >> 4, c = (q & 15) * 8;
;       float4 m0 = *reinterpret_cast<const float4*>(Tf + t * 132 + c);
;       float4 m1 = *reinterpret_cast<const float4*>(Tf + t * 132 + c + 4);
;       float mm[8] = {m0.x, m0.y, m0.z, m0.w, m1.x, m1.y, m1.z, m1.w};
;       unsigned uw[4] = {uu[i].x, uu[i].y, uu[i].z, uu[i].w};
;       unsigned gw[4] = {gt[i].x, gt[i].y, gt[i].z, gt[i].w};
;       unsigned ow[4];
; #pragma unroll
;       for (int e = 0; e < 4; ++e) {
;         float y0 = bflo(uw[e]) * mm[2 * e] * silu_f(bflo(gw[e]));
;         float y1 = bfhi(uw[e]) * mm[2 * e + 1] * silu_f(bfhi(gw[e]));
;         ow[e] = pack2(y0, y1);
;       }
;       *reinterpret_cast<uint4*>(Y + (t0 + t) * YW + g * 128 + c) = make_uint4(ow[0], ow[1], ow[2], ow[3]);
;     }
	v_mov_b32_e32 v64, v28
	v_mov_b32_e32 v65, v30
	v_pk_mul_f32 v[62:63], v[64:65], v[62:63]
	v_rcp_f32_e32 v61, v61
	s_nop 0
	v_mul_f32_e32 v61, v55, v61
	v_and_b32_e32 v24, 0xffff0000, v24
	v_mul_f32_e32 v30, 0xbfb8aa3b, v67
	v_exp_f32_e32 v57, v30
	v_rcp_f32_e32 v60, v60
	s_nop 0
	v_mul_f32_e32 v60, v66, v60
	v_mov_b32_e32 v30, v29
	v_pk_mul_f32 v[24:25], v[30:31], v[24:25]
	v_pk_add_f32 v[56:57], v[56:57], 1.0 op_sel_hi:[1,0]
	v_pk_mul_f32 v[60:61], v[60:61], v[62:63]
	v_lshlrev_b32_e32 v66, 16, v58
	v_lshlrev_b32_e32 v63, 16, v27
	v_and_b32_e32 v27, 0xffff0000, v27
	v_rcp_f32_e32 v29, v57
	s_nop 0
	v_mul_f32_e32 v29, v67, v29
	v_rcp_f32_e32 v28, v56
	s_nop 0
	v_mul_f32_e32 v28, v68, v28
	v_pk_mul_f32 v[24:25], v[28:29], v[24:25]
	v_and_b32_sdwa v28, v61, v155 dst_sel:DWORD dst_unused:UNUSED_PAD src0_sel:WORD_1 src1_sel:DWORD
	v_and_b32_sdwa v30, v25, v155 dst_sel:DWORD dst_unused:UNUSED_PAD src0_sel:WORD_1 src1_sel:DWORD
	v_and_b32_sdwa v31, v24, v155 dst_sel:DWORD dst_unused:UNUSED_PAD src0_sel:WORD_1 src1_sel:DWORD
	v_and_b32_sdwa v29, v60, v155 dst_sel:DWORD dst_unused:UNUSED_PAD src0_sel:WORD_1 src1_sel:DWORD
	v_add3_u32 v25, v25, v30, s68
	v_add3_u32 v24, v24, v31, s68
	v_add3_u32 v29, v60, v29, s68
	v_add3_u32 v28, v61, v28, s68
	v_and_b32_e32 v25, 0xffff0000, v25
	v_and_b32_e32 v24, 0xffff0000, v24
	v_lshlrev_b32_e32 v55, 16, v59
	v_or_b32_sdwa v25, v25, v28 dst_sel:DWORD dst_unused:UNUSED_PAD src0_sel:DWORD src1_sel:WORD_1
	v_or_b32_sdwa v24, v24, v29 dst_sel:DWORD dst_unused:UNUSED_PAD src0_sel:DWORD src1_sel:WORD_1
	v_mul_f32_e32 v28, 0xbfb8aa3b, v66
	v_mul_f32_e32 v29, 0xbfb8aa3b, v55
	v_exp_f32_e32 v28, v28
	v_exp_f32_e32 v29, v29
	v_and_b32_e32 v68, 0xffff0000, v58
	v_mul_f32_e32 v30, 0xbfb8aa3b, v68
	v_and_b32_e32 v67, 0xffff0000, v59
	v_exp_f32_e32 v60, v30
	v_pk_add_f32 v[64:65], v[28:29], 1.0 op_sel_hi:[1,0]
	global_load_dwordx4 v[28:31], v[52:53], off
	global_load_dwordx4 v[56:59], v[52:53], off offset:2048
	s_waitcnt lgkmcnt(0)
	v_mov_b32_e32 v52, v32
	v_lshlrev_b32_e32 v62, 16, v26
	v_mov_b32_e32 v53, v34
	v_pk_mul_f32 v[52:53], v[52:53], v[62:63]
	v_rcp_f32_e32 v63, v65
	s_nop 0
	v_mul_f32_e32 v63, v55, v63
	v_and_b32_e32 v26, 0xffff0000, v26
	v_mul_f32_e32 v34, 0xbfb8aa3b, v67
	v_exp_f32_e32 v61, v34
	v_rcp_f32_e32 v62, v64
	s_nop 0
	v_mul_f32_e32 v62, v66, v62
	v_mov_b32_e32 v34, v33
	v_pk_mul_f32 v[26:27], v[34:35], v[26:27]
	v_pk_add_f32 v[60:61], v[60:61], 1.0 op_sel_hi:[1,0]
	v_pk_mul_f32 v[52:53], v[62:63], v[52:53]
	s_waitcnt vmcnt(1)
	v_lshlrev_b32_e32 v63, 16, v29
	v_rcp_f32_e32 v33, v61
	s_nop 0
	v_mul_f32_e32 v33, v67, v33
	v_rcp_f32_e32 v32, v60
	s_nop 0
	v_mul_f32_e32 v32, v68, v32
	v_pk_mul_f32 v[26:27], v[32:33], v[26:27]
	v_and_b32_sdwa v32, v53, v155 dst_sel:DWORD dst_unused:UNUSED_PAD src0_sel:WORD_1 src1_sel:DWORD
	v_and_b32_sdwa v34, v27, v155 dst_sel:DWORD dst_unused:UNUSED_PAD src0_sel:WORD_1 src1_sel:DWORD
	v_add3_u32 v27, v27, v34, s68
	v_add3_u32 v32, v53, v32, s68
	v_and_b32_e32 v27, 0xffff0000, v27
	s_waitcnt vmcnt(0)
	v_lshlrev_b32_e32 v67, 16, v56
	v_or_b32_sdwa v27, v27, v32 dst_sel:DWORD dst_unused:UNUSED_PAD src0_sel:DWORD src1_sel:WORD_1
	v_mul_f32_e32 v32, 0xbfb8aa3b, v67
	v_and_b32_e32 v69, 0xffff0000, v56
	v_lshlrev_b32_e32 v66, 16, v57
	v_exp_f32_e32 v60, v32
	v_mul_f32_e32 v32, 0xbfb8aa3b, v69
	v_exp_f32_e32 v56, v32
	v_mul_f32_e32 v32, 0xbfb8aa3b, v66
	v_exp_f32_e32 v61, v32
	v_and_b32_sdwa v35, v26, v155 dst_sel:DWORD dst_unused:UNUSED_PAD src0_sel:WORD_1 src1_sel:DWORD
	v_and_b32_sdwa v33, v52, v155 dst_sel:DWORD dst_unused:UNUSED_PAD src0_sel:WORD_1 src1_sel:DWORD
	v_add3_u32 v26, v26, v35, s68
	v_pk_add_f32 v[60:61], v[60:61], 1.0 op_sel_hi:[1,0]
	v_add3_u32 v33, v52, v33, s68
	v_and_b32_e32 v26, 0xffff0000, v26
	v_and_b32_e32 v68, 0xffff0000, v57
	v_or_b32_sdwa v26, v26, v33 dst_sel:DWORD dst_unused:UNUSED_PAD src0_sel:DWORD src1_sel:WORD_1
	ds_read_b128 v[32:35], v54
	ds_read_b128 v[52:55], v54 offset:16
	v_lshlrev_b32_e32 v62, 16, v28
	v_and_b32_e32 v29, 0xffff0000, v29
	s_waitcnt lgkmcnt(1)
; __device__ __forceinline__ unsigned pack2(float a, float b) { return (unsigned)f2bf(a) | ((unsigned)f2bf(b) << 16); }
; __device__ __forceinline__ float bflo(unsigned w) { return __uint_as_float(w << 16); }
; __device__ __forceinline__ float bfhi(unsigned w) { return __uint_as_float(w & 0xffff0000u); }
; __device__ __forceinline__ float silu_f(float g) { return g / (1.f + __expf(-g)); }
; __device__ void gmlp_item(const Params& p, int layer, int b, int n, int g, char* smem) {
;     ...
; #pragma unroll
;     for (int i = 0; i < 8; ++i) {
;       int q = tid + 256 * i, t = q >> 4, c = (q & 15) * 8;
;       float4 m0 = *reinterpret_cast<const float4*>(Tf + t * 132 + c);
;       float4 m1 = *reinterpret_cast<const float4*>(Tf + t * 132 + c + 4);
;       float mm[8] = {m0.x, m0.y, m0.z, m0.w, m1.x, m1.y, m1.z, m1.w};
;       unsigned uw[4] = {uu[i].x, uu[i].y, uu[i].z, uu[i].w};
;       unsigned gw[4] = {gt[i].x, gt[i].y, gt[i].z, gt[i].w};
;       unsigned ow[4];
; #pragma unroll
;       for (int e = 0; e < 4; ++e) {
;         float y0 = bflo(uw[e]) * mm[2 * e] * silu_f(bflo(gw[e]));
;         float y1 = bfhi(uw[e]) * mm[2 * e + 1] * silu_f(bfhi(gw[e]));
;         ow[e] = pack2(y0, y1);
;       }
;       *reinterpret_cast<uint4*>(Y + (t0 + t) * YW + g * 128 + c) = make_uint4(ow[0], ow[1], ow[2], ow[3]);
;     }
	v_mov_b32_e32 v64, v32
	v_mov_b32_e32 v65, v34
	v_pk_mul_f32 v[62:63], v[64:65], v[62:63]
	v_rcp_f32_e32 v61, v61
	s_nop 0
	v_mul_f32_e32 v61, v66, v61
	v_and_b32_e32 v28, 0xffff0000, v28
	v_mul_f32_e32 v34, 0xbfb8aa3b, v68
	v_exp_f32_e32 v57, v34
	v_rcp_f32_e32 v60, v60
	s_nop 0
	v_mul_f32_e32 v60, v67, v60
	v_pk_mul_f32 v[60:61], v[60:61], v[62:63]
	v_mov_b32_e32 v34, v33
	v_pk_add_f32 v[56:57], v[56:57], 1.0 op_sel_hi:[1,0]
	v_pk_mul_f32 v[28:29], v[34:35], v[28:29]
	s_nop 0
	v_rcp_f32_e32 v33, v57
	s_nop 0
	v_mul_f32_e32 v33, v68, v33
	v_rcp_f32_e32 v32, v56
	s_nop 0
	v_mul_f32_e32 v32, v69, v32
	v_pk_mul_f32 v[28:29], v[32:33], v[28:29]
	v_and_b32_sdwa v32, v61, v155 dst_sel:DWORD dst_unused:UNUSED_PAD src0_sel:WORD_1 src1_sel:DWORD
	v_and_b32_sdwa v34, v29, v155 dst_sel:DWORD dst_unused:UNUSED_PAD src0_sel:WORD_1 src1_sel:DWORD
	v_and_b32_sdwa v35, v28, v155 dst_sel:DWORD dst_unused:UNUSED_PAD src0_sel:WORD_1 src1_sel:DWORD
	v_and_b32_sdwa v33, v60, v155 dst_sel:DWORD dst_unused:UNUSED_PAD src0_sel:WORD_1 src1_sel:DWORD
	v_add3_u32 v29, v29, v34, s68
	v_add3_u32 v28, v28, v35, s68
	v_add3_u32 v33, v60, v33, s68
	v_add3_u32 v32, v61, v32, s68
	v_and_b32_e32 v29, 0xffff0000, v29
	v_and_b32_e32 v28, 0xffff0000, v28
	v_lshlrev_b32_e32 v35, 16, v59
	v_lshlrev_b32_e32 v60, 16, v58
	v_or_b32_sdwa v29, v29, v32 dst_sel:DWORD dst_unused:UNUSED_PAD src0_sel:DWORD src1_sel:WORD_1
	v_or_b32_sdwa v28, v28, v33 dst_sel:DWORD dst_unused:UNUSED_PAD src0_sel:DWORD src1_sel:WORD_1
	v_mul_f32_e32 v32, 0xbfb8aa3b, v60
	v_mul_f32_e32 v33, 0xbfb8aa3b, v35
	v_exp_f32_e32 v32, v32
	v_exp_f32_e32 v33, v33
	v_and_b32_e32 v62, 0xffff0000, v58
	s_waitcnt lgkmcnt(0)
	v_mov_b32_e32 v58, v52
	v_and_b32_e32 v61, 0xffff0000, v59
	v_pk_add_f32 v[32:33], v[32:33], 1.0 op_sel_hi:[1,0]
	v_lshlrev_b32_e32 v57, 16, v31
	v_lshlrev_b32_e32 v56, 16, v30
	v_mov_b32_e32 v59, v54
	v_pk_mul_f32 v[56:57], v[58:59], v[56:57]
	v_rcp_f32_e32 v33, v33
	s_nop 0
	v_mul_f32_e32 v33, v35, v33
	v_mul_f32_e32 v34, 0xbfb8aa3b, v62
	v_mul_f32_e32 v35, 0xbfb8aa3b, v61
	v_exp_f32_e32 v34, v34
	v_exp_f32_e32 v35, v35
	v_rcp_f32_e32 v32, v32
	s_nop 0
	v_mul_f32_e32 v32, v60, v32
	v_pk_mul_f32 v[32:33], v[32:33], v[56:57]
	v_mov_b32_e32 v54, v53
	v_pk_add_f32 v[34:35], v[34:35], 1.0 op_sel_hi:[1,0]
	v_and_b32_e32 v31, 0xffff0000, v31
	v_and_b32_e32 v30, 0xffff0000, v30
	v_pk_mul_f32 v[30:31], v[54:55], v[30:31]
	v_rcp_f32_e32 v35, v35
	s_nop 0
	v_mul_f32_e32 v35, v61, v35
	s_mov_b64 s[12:13], 0
	v_rcp_f32_e32 v34, v34
	s_nop 0
	v_mul_f32_e32 v34, v62, v34
	v_pk_mul_f32 v[30:31], v[34:35], v[30:31]
	v_and_b32_sdwa v34, v33, v155 dst_sel:DWORD dst_unused:UNUSED_PAD src0_sel:WORD_1 src1_sel:DWORD
	v_and_b32_sdwa v35, v32, v155 dst_sel:DWORD dst_unused:UNUSED_PAD src0_sel:WORD_1 src1_sel:DWORD
	v_add3_u32 v32, v32, v35, s68
	v_add3_u32 v33, v33, v34, s68
	v_and_b32_sdwa v34, v31, v155 dst_sel:DWORD dst_unused:UNUSED_PAD src0_sel:WORD_1 src1_sel:DWORD
	v_and_b32_sdwa v35, v30, v155 dst_sel:DWORD dst_unused:UNUSED_PAD src0_sel:WORD_1 src1_sel:DWORD
	v_add3_u32 v31, v31, v34, s68
	v_add3_u32 v30, v30, v35, s68
	v_and_b32_e32 v31, 0xffff0000, v31
	v_and_b32_e32 v30, 0xffff0000, v30
	v_or_b32_sdwa v31, v31, v33 dst_sel:DWORD dst_unused:UNUSED_PAD src0_sel:DWORD src1_sel:WORD_1
	v_or_b32_sdwa v30, v30, v32 dst_sel:DWORD dst_unused:UNUSED_PAD src0_sel:DWORD src1_sel:WORD_1
	global_store_dwordx4 v[50:51], v[28:31], off
	global_store_dwordx4 v[48:49], v[24:27], off
	global_store_dwordx4 v[46:47], v[20:23], off
	global_store_dwordx4 v[44:45], v[16:19], off
	global_store_dwordx4 v[42:43], v[12:15], off
	global_store_dwordx4 v[40:41], v[8:11], off
	global_store_dwordx4 v[38:39], v[4:7], off
	global_store_dwordx4 v[36:37], v[0:3], off
	s_barrier

; __device__ __forceinline__ unsigned pack2(float a, float b) { return (unsigned)f2bf(a) | ((unsigned)f2bf(b) << 16); }
; __device__ __forceinline__ float bflo(unsigned w) { return __uint_as_float(w << 16); }
; __device__ __forceinline__ float bfhi(unsigned w) { return __uint_as_float(w & 0xffff0000u); }
; __device__ __forceinline__ float silu_f(float g) { return g / (1.f + __expf(-g)); }
; template <int DH, int MODE>
; __device__ void attn_item(const Params& p, int layer, int b, int blk, int head, char* smem) {
;     ...
;   if (MODE == 0 && half == 0) linv_s[row] = 1.f / l_run;
;   __syncthreads();
;   {
;     constexpr int OST = DH + 4;
;     constexpr int CPR = DH / 8;
;     constexpr int NCH = 128 * CPR / 256;
;     float* Of = reinterpret_cast<float*>(smem);
;     uint4 gt[NCH];
; #pragma unroll
;     for (int i = 0; i < NCH; ++i) {
;       int q = tid + 256 * i, r = q / CPR, c = (q % CPR) * 8;
;       gt[i] = *reinterpret_cast<const uint4*>(P + (tq0 + r) * NP + gcol + c);
;     }
;     float lis[2][4];
; #pragma unroll
;     for (int m = 0; m < 2; ++m)
; #pragma unroll
;       for (int j = 0; j < 4; ++j) lis[m][j] = (MODE == 0) ? linv_s[wid * 32 + m * 16 + fq * 4 + j] : 1.f;
;     if (MODE == 0) __syncthreads();
; #pragma unroll
;     for (int m = 0; m < 2; ++m)
; #pragma unroll
;       for (int j = 0; j < 4; ++j) {
;         int r = wid * 32 + m * 16 + fq * 4 + j;
; #pragma unroll
;         for (int n = 0; n < NDT; ++n) Of[r * OST + n * 16 + fr] = o[m][n][j] * lis[m][j];
;       }
;     __syncthreads();
; #pragma unroll
;     for (int i = 0; i < NCH; ++i) {
;       int q = tid + 256 * i, r = q / CPR, c = (q % CPR) * 8;
;       float4 m0 = *reinterpret_cast<const float4*>(Of + r * OST + c);
;       float4 m1 = *reinterpret_cast<const float4*>(Of + r * OST + c + 4);
;       float mm[8] = {m0.x, m0.y, m0.z, m0.w, m1.x, m1.y, m1.z, m1.w};
;       unsigned gw[4] = {gt[i].x, gt[i].y, gt[i].z, gt[i].w};
;       unsigned ow[4];
; #pragma unroll
;       for (int e = 0; e < 4; ++e)
;         ow[e] = pack2(mm[2 * e] * silu_f(bflo(gw[e])), mm[2 * e + 1] * silu_f(bfhi(gw[e])));
.LBB0_511:
	v_readfirstlane_b32 s16, v85
	s_and_saveexec_b64 s[14:15], s[12:13]
	s_cbranch_execz .LBB0_513
	v_rcp_f32_e32 v32, v88
	s_nop 0
	v_lshlrev_b32_e32 v33, 2, v74
	ds_write_b32 v33, v32 offset:8704
.LBB0_513:
	s_or_b64 exec, exec, s[14:15]
	v_lshl_add_u64 v[44:45], v[66:67], 0, s[36:37]
	v_mov_b64_e32 v[46:47], s[50:51]
	v_mad_u64_u32 v[32:33], s[14:15], v44, s63, v[46:47]
	v_mad_i32_i24 v33, v45, s63, v33
	v_lshl_add_u64 v[36:37], v[32:33], 0, v[70:71]
	v_add_u32_e32 v32, 0x100, v81
	v_ashrrev_i32_e32 v33, 31, v32
	v_lshrrev_b32_e32 v33, 29, v33
	v_add_u32_e32 v33, v32, v33
	v_ashrrev_i32_e32 v86, 3, v33
	v_and_b32_e32 v33, -8, v33
	v_sub_u32_e32 v85, v32, v33
	v_lshlrev_b32_e32 v32, 3, v85
	v_ashrrev_i32_e32 v33, 31, v32
	s_waitcnt vmcnt(2)
	v_add_u32_e32 v48, 0x200, v81
	v_lshlrev_b64 v[90:91], 1, v[32:33]
	v_ashrrev_i32_e32 v32, 31, v48
	v_lshrrev_b32_e32 v32, 29, v32
	v_add_u32_e32 v32, v48, v32
	v_ashrrev_i32_e32 v92, 3, v32
	v_and_b32_e32 v49, -8, v32
	v_add_u32_e32 v32, 0x300, v81
	v_ashrrev_i32_e32 v33, 31, v32
	v_lshrrev_b32_e32 v33, 29, v33
	v_ashrrev_i32_e32 v87, 31, v86
	v_add_u32_e32 v33, v32, v33
	v_lshl_add_u64 v[88:89], v[86:87], 0, s[36:37]
	v_ashrrev_i32_e32 v94, 3, v33
	v_and_b32_e32 v33, -8, v33
	v_mad_u64_u32 v[34:35], s[14:15], v88, s63, v[46:47]
	v_sub_u32_e32 v87, v32, v33
	v_ashrrev_i32_e32 v95, 31, v94
	v_mad_i32_i24 v35, v89, s63, v35
	v_lshlrev_b32_e32 v32, 3, v87
	v_lshl_add_u64 v[40:41], v[94:95], 0, s[36:37]
	v_lshl_add_u64 v[38:39], v[34:35], 0, v[90:91]
	v_mad_u64_u32 v[34:35], s[14:15], v40, s63, v[46:47]
	v_ashrrev_i32_e32 v33, 31, v32
	v_mad_i32_i24 v35, v41, s63, v35
	v_lshlrev_b64 v[42:43], 1, v[32:33]
	v_lshl_add_u64 v[32:33], v[34:35], 0, v[42:43]
	v_add_co_u32_e32 v32, vcc, s72, v32
	s_waitcnt lgkmcnt(0)
	s_nop 0
	v_addc_co_u32_e32 v33, vcc, 0, v33, vcc
	s_barrier
	global_load_dwordx4 v[32:35], v[32:33], off offset:512
	v_sub_u32_e32 v95, v48, v49
	v_ashrrev_i32_e32 v93, 31, v92
	v_lshlrev_b32_e32 v48, 3, v95
	v_lshl_add_u64 v[96:97], v[92:93], 0, s[36:37]
	v_mad_u64_u32 v[46:47], s[14:15], v96, s63, v[46:47]
	v_ashrrev_i32_e32 v49, 31, v48
	v_mad_i32_i24 v47, v97, s63, v47
	v_lshlrev_b64 v[98:99], 1, v[48:49]
	v_lshl_add_u64 v[100:101], v[46:47], 0, v[98:99]
	v_lshl_or_b32 v46, v75, 7, v128
	ds_read_b128 v[60:63], v46 offset:8704
	ds_read_b128 v[80:83], v46 offset:8768
	s_ashr_i32 s13, s16, 31
	s_add_u32 s12, s28, s16
	s_addc_u32 s13, s29, s13
	s_lshl_b32 s14, s83, 1
	s_add_u32 s12, s12, s14
	v_lshl_or_b32 v46, v84, 2, v64
	s_waitcnt lgkmcnt(0)
	v_mul_f32_e32 v69, v0, v80
	s_addc_u32 s13, s13, 0
	v_mul_lo_u32 v0, v66, s74
	v_mul_lo_u32 v46, v46, s74
	v_mul_f32_e32 v75, v1, v81
	v_lshl_add_u32 v66, v68, 2, v0
	v_mov_b64_e32 v[0:1], s[12:13]
	v_lshl_add_u32 v47, v73, 2, v46
	v_mul_f32_e32 v48, v16, v60
	v_mul_f32_e32 v49, v28, v60
	v_mul_f32_e32 v50, v24, v60
	v_mul_f32_e32 v51, v20, v60
	s_waitcnt vmcnt(1)
	v_mul_f32_e32 v52, v17, v61
	v_mul_f32_e32 v53, v29, v61
	v_mul_f32_e32 v54, v25, v61
	v_mul_f32_e32 v55, v21, v61
	v_mul_f32_e32 v56, v18, v62
	v_mul_f32_e32 v57, v30, v62
	v_mul_f32_e32 v58, v26, v62
	v_mul_f32_e32 v59, v22, v62
	v_mul_f32_e32 v60, v19, v63
	v_mul_f32_e32 v61, v31, v63
	v_mul_f32_e32 v62, v27, v63
	v_mul_f32_e32 v64, v23, v63
	v_mul_f32_e32 v63, v12, v80
	v_mul_f32_e32 v65, v8, v80
	v_mul_f32_e32 v67, v4, v80
	v_mul_f32_e32 v72, v13, v81
	v_mul_f32_e32 v73, v9, v81
	v_mul_f32_e32 v74, v5, v81
	v_mul_f32_e32 v76, v14, v82
	v_mul_f32_e32 v77, v10, v82
	v_mul_f32_e32 v78, v6, v82
	v_mul_f32_e32 v80, v2, v82
	v_mul_f32_e32 v79, v15, v83
	v_mul_f32_e32 v81, v11, v83
	v_mul_f32_e32 v82, v7, v83
	v_mul_f32_e32 v83, v3, v83
	v_mad_u64_u32 v[2:3], s[12:13], v44, s70, v[0:1]
	v_mad_i32_i24 v3, v45, s70, v3
	v_lshl_add_u64 v[12:13], v[2:3], 0, v[70:71]
	v_mul_lo_u32 v2, v86, s74
	v_lshl_add_u32 v46, v85, 5, v2
	v_mad_u64_u32 v[2:3], s[12:13], v88, s70, v[0:1]
	v_mad_i32_i24 v3, v89, s70, v3
	v_mad_u64_u32 v[4:5], s[12:13], v40, s70, v[0:1]
	v_lshl_add_u64 v[10:11], v[2:3], 0, v[90:91]
	v_mul_lo_u32 v2, v92, s74
	v_mad_i32_i24 v5, v41, s70, v5
	v_lshl_add_u32 v45, v95, 5, v2
	v_mad_u64_u32 v[2:3], s[12:13], v96, s70, v[0:1]
	v_lshl_add_u64 v[14:15], v[4:5], 0, v[42:43]
	v_mad_i32_i24 v3, v97, s70, v3
	v_add_co_u32_e32 v0, vcc, s72, v100
	v_lshl_add_u64 v[8:9], v[2:3], 0, v[98:99]
	v_mul_lo_u32 v2, v94, s74
	s_waitcnt vmcnt(0)
	v_lshlrev_b32_e32 v16, 16, v33
	v_lshlrev_b32_e32 v18, 16, v32
	v_mul_f32_e32 v6, 0xbfb8aa3b, v18
	v_mul_f32_e32 v7, 0xbfb8aa3b, v16
	v_exp_f32_e32 v6, v6
	v_exp_f32_e32 v7, v7
	v_addc_co_u32_e32 v1, vcc, 0, v101, vcc
	v_lshl_add_u32 v44, v87, 5, v2
	v_pk_add_f32 v[4:5], v[6:7], 1.0 op_sel_hi:[1,0]
	global_load_dwordx4 v[0:3], v[0:1], off offset:512
	v_and_b32_e32 v19, 0xffff0000, v33
	v_and_b32_e32 v20, 0xffff0000, v32
	v_mul_f32_e32 v6, 0xbfb8aa3b, v20
	v_rcp_f32_e32 v17, v5
	s_nop 0
	v_mul_f32_e32 v17, v16, v17
	v_mul_f32_e32 v7, 0xbfb8aa3b, v19
	v_exp_f32_e32 v6, v6
	v_exp_f32_e32 v7, v7
	s_nop 0
	v_pk_add_f32 v[6:7], v[6:7], 1.0 op_sel_hi:[1,0]
	v_rcp_f32_e32 v16, v4
	s_nop 0
	v_mul_f32_e32 v16, v18, v16
	v_lshlrev_b32_e32 v23, 16, v34
	v_rcp_f32_e32 v4, v7
	s_nop 0
	v_mul_f32_e32 v19, v19, v4
	v_lshlrev_b32_e32 v22, 16, v35
	v_mul_f32_e32 v4, 0xbfb8aa3b, v23
	v_mul_f32_e32 v5, 0xbfb8aa3b, v22
	v_exp_f32_e32 v4, v4
	v_exp_f32_e32 v5, v5
	v_rcp_f32_e32 v18, v6
	s_nop 0
	v_mul_f32_e32 v18, v20, v18
	v_and_b32_e32 v24, 0xffff0000, v35
	v_pk_add_f32 v[4:5], v[4:5], 1.0 op_sel_hi:[1,0]
	v_and_b32_e32 v25, 0xffff0000, v34
	v_mul_f32_e32 v6, 0xbfb8aa3b, v25
	v_exp_f32_e32 v6, v6
	v_rcp_f32_e32 v21, v5
	s_nop 0
	v_mul_f32_e32 v21, v22, v21
	v_mul_f32_e32 v7, 0xbfb8aa3b, v24
	v_exp_f32_e32 v7, v7
	s_nop 0
	v_pk_add_f32 v[6:7], v[6:7], 1.0 op_sel_hi:[1,0]
	v_rcp_f32_e32 v20, v4
	s_nop 0
	v_mul_f32_e32 v20, v23, v20
	v_rcp_f32_e32 v23, v7
	s_nop 0
	v_mul_f32_e32 v23, v24, v23
	s_waitcnt vmcnt(0)
; __device__ __forceinline__ unsigned pack2(float a, float b) { return (unsigned)f2bf(a) | ((unsigned)f2bf(b) << 16); }
; __device__ __forceinline__ float bflo(unsigned w) { return __uint_as_float(w << 16); }
; __device__ __forceinline__ float bfhi(unsigned w) { return __uint_as_float(w & 0xffff0000u); }
; __device__ __forceinline__ float silu_f(float g) { return g / (1.f + __expf(-g)); }
; template <int DH, int MODE>
; __device__ void attn_item(const Params& p, int layer, int b, int blk, int head, char* smem) {
;     ...
; #pragma unroll
;     for (int m = 0; m < 2; ++m)
; #pragma unroll
;       for (int j = 0; j < 4; ++j) {
;         int r = wid * 32 + m * 16 + fq * 4 + j;
; #pragma unroll
;         for (int n = 0; n < NDT; ++n) Of[r * OST + n * 16 + fr] = o[m][n][j] * lis[m][j];
;       }
;     __syncthreads();
; #pragma unroll
;     for (int i = 0; i < NCH; ++i) {
;       int q = tid + 256 * i, r = q / CPR, c = (q % CPR) * 8;
;       float4 m0 = *reinterpret_cast<const float4*>(Of + r * OST + c);
;       float4 m1 = *reinterpret_cast<const float4*>(Of + r * OST + c + 4);
;       float mm[8] = {m0.x, m0.y, m0.z, m0.w, m1.x, m1.y, m1.z, m1.w};
;       unsigned gw[4] = {gt[i].x, gt[i].y, gt[i].z, gt[i].w};
;       unsigned ow[4];
; #pragma unroll
;       for (int e = 0; e < 4; ++e)
;         ow[e] = pack2(mm[2 * e] * silu_f(bflo(gw[e])), mm[2 * e + 1] * silu_f(bfhi(gw[e])));
	v_lshlrev_b32_e32 v24, 16, v1
	v_lshlrev_b32_e32 v26, 16, v0
	v_mul_f32_e32 v4, 0xbfb8aa3b, v26
	v_mul_f32_e32 v5, 0xbfb8aa3b, v24
	v_exp_f32_e32 v4, v4
	v_exp_f32_e32 v5, v5
	v_and_b32_e32 v27, 0xffff0000, v1
	v_rcp_f32_e32 v22, v6
	s_nop 0
	v_mul_f32_e32 v22, v25, v22
	v_pk_add_f32 v[4:5], v[4:5], 1.0 op_sel_hi:[1,0]
	v_and_b32_e32 v28, 0xffff0000, v0
	v_mul_f32_e32 v0, 0xbfb8aa3b, v28
	v_exp_f32_e32 v6, v0
	v_lshlrev_b32_e32 v32, 16, v3
	v_mul_f32_e32 v7, 0xbfb8aa3b, v27
	v_rcp_f32_e32 v1, v5
	s_nop 0
	v_mul_f32_e32 v1, v24, v1
	v_exp_f32_e32 v7, v7
	s_nop 0
	v_pk_add_f32 v[24:25], v[6:7], 1.0 op_sel_hi:[1,0]
	v_rcp_f32_e32 v0, v4
	s_nop 0
	v_mul_f32_e32 v0, v26, v0
	v_lshlrev_b32_e32 v33, 16, v2
	v_rcp_f32_e32 v25, v25
	s_nop 0
	v_mul_f32_e32 v25, v27, v25
	v_add_co_u32_e64 v4, s[12:13], s72, v38
	s_nop 0
	s_nop 0
	v_addc_co_u32_e64 v5, s[12:13], 0, v39, s[12:13]
	global_load_dwordx4 v[4:7], v[4:5], off offset:512
	v_mul_f32_e32 v26, 0xbfb8aa3b, v33
	v_mul_f32_e32 v27, 0xbfb8aa3b, v32
	v_exp_f32_e32 v26, v26
	v_exp_f32_e32 v27, v27
	v_and_b32_e32 v30, 0xffff0000, v3
	v_rcp_f32_e32 v24, v24
	s_nop 0
	v_mul_f32_e32 v24, v28, v24
	v_pk_add_f32 v[26:27], v[26:27], 1.0 op_sel_hi:[1,0]
	v_and_b32_e32 v38, 0xffff0000, v2
	v_mul_f32_e32 v2, 0xbfb8aa3b, v38
	v_exp_f32_e32 v28, v2
	v_mul_f32_e32 v29, 0xbfb8aa3b, v30
	v_exp_f32_e32 v29, v29
	v_rcp_f32_e32 v3, v27
	s_nop 0
	v_mul_f32_e32 v3, v32, v3
	v_pk_add_f32 v[28:29], v[28:29], 1.0 op_sel_hi:[1,0]
	v_rcp_f32_e32 v2, v26
	s_nop 0
	v_mul_f32_e32 v2, v33, v2
	v_rcp_f32_e32 v27, v29
	s_nop 0
	v_mul_f32_e32 v27, v30, v27
	v_add_co_u32_e64 v30, s[12:13], s72, v36
	s_nop 0
	s_nop 0
	v_addc_co_u32_e64 v31, s[12:13], 0, v37, s[12:13]
	global_load_dwordx4 v[32:35], v[30:31], off offset:512
	v_rcp_f32_e32 v26, v28
	s_nop 0
	v_mul_f32_e32 v26, v38, v26
	s_barrier
	s_waitcnt vmcnt(1)
	v_lshlrev_b32_e32 v36, 16, v5
	v_lshlrev_b32_e32 v37, 16, v4
	v_mul_f32_e32 v30, 0xbfb8aa3b, v37
	v_mul_f32_e32 v31, 0xbfb8aa3b, v36
	v_exp_f32_e32 v30, v30
	v_exp_f32_e32 v31, v31
	v_and_b32_e32 v38, 0xffff0000, v5
	v_and_b32_e32 v39, 0xffff0000, v4
	v_mul_f32_e32 v4, 0xbfb8aa3b, v39
	v_pk_add_f32 v[28:29], v[30:31], 1.0 op_sel_hi:[1,0]
	v_exp_f32_e32 v30, v4
	ds_write2_b32 v47, v48, v49 offset1:16
	ds_write2_b32 v47, v50, v51 offset0:32 offset1:48
	ds_write2_b32 v47, v52, v53 offset0:68 offset1:84
	ds_write2_b32 v47, v54, v55 offset0:100 offset1:116
	ds_write2_b32 v47, v56, v57 offset0:136 offset1:152
	ds_write2_b32 v47, v58, v59 offset0:168 offset1:184
	ds_write2_b32 v47, v60, v61 offset0:204 offset1:220
	ds_write2_b32 v47, v62, v64 offset0:236 offset1:252
	v_mul_f32_e32 v31, 0xbfb8aa3b, v38
	v_exp_f32_e32 v31, v31
	v_rcp_f32_e32 v5, v29
	s_nop 0
	v_mul_f32_e32 v5, v36, v5
	v_pk_add_f32 v[30:31], v[30:31], 1.0 op_sel_hi:[1,0]
	v_rcp_f32_e32 v4, v28
	s_nop 0
	v_mul_f32_e32 v4, v37, v4
	v_rcp_f32_e32 v29, v31
	s_nop 0
	v_mul_f32_e32 v29, v38, v29
	v_lshlrev_b32_e32 v38, 16, v7
	v_lshlrev_b32_e32 v40, 16, v6
	v_mul_f32_e32 v36, 0xbfb8aa3b, v40
	v_mul_f32_e32 v37, 0xbfb8aa3b, v38
	v_exp_f32_e32 v36, v36
	v_exp_f32_e32 v37, v37
	v_rcp_f32_e32 v28, v30
	s_nop 0
	v_mul_f32_e32 v28, v39, v28
	v_and_b32_e32 v39, 0xffff0000, v7
	v_pk_add_f32 v[30:31], v[36:37], 1.0 op_sel_hi:[1,0]
	v_and_b32_e32 v41, 0xffff0000, v6
	v_mul_f32_e32 v6, 0xbfb8aa3b, v41
	v_exp_f32_e32 v36, v6
	v_mul_f32_e32 v37, 0xbfb8aa3b, v39
	v_exp_f32_e32 v37, v37
	v_rcp_f32_e32 v7, v31
	s_nop 0
	v_mul_f32_e32 v7, v38, v7
	v_pk_add_f32 v[36:37], v[36:37], 1.0 op_sel_hi:[1,0]
	v_rcp_f32_e32 v6, v30
	s_nop 0
	v_mul_f32_e32 v6, v40, v6
	v_rcp_f32_e32 v31, v37
	s_nop 0
	v_mul_f32_e32 v31, v39, v31
	s_waitcnt vmcnt(0)
	v_lshlrev_b32_e32 v42, 16, v33
	v_lshlrev_b32_e32 v43, 16, v32
	v_mul_f32_e32 v38, 0xbfb8aa3b, v43
	v_mul_f32_e32 v39, 0xbfb8aa3b, v42
	v_exp_f32_e32 v38, v38
	v_exp_f32_e32 v39, v39
	v_rcp_f32_e32 v30, v36
	s_nop 0
	v_mul_f32_e32 v30, v41, v30
	v_and_b32_e32 v68, 0xffff0000, v33
	v_pk_add_f32 v[36:37], v[38:39], 1.0 op_sel_hi:[1,0]
	v_and_b32_e32 v39, 0xffff0000, v32
	v_mul_f32_e32 v32, 0xbfb8aa3b, v39
	v_exp_f32_e32 v32, v32
	v_rcp_f32_e32 v41, v37
	s_nop 0
	v_mul_f32_e32 v41, v42, v41
	v_mul_f32_e32 v33, 0xbfb8aa3b, v68
	v_exp_f32_e32 v33, v33
	s_nop 0
	v_pk_add_f32 v[32:33], v[32:33], 1.0 op_sel_hi:[1,0]
	v_rcp_f32_e32 v40, v36
	s_nop 0
	v_mul_f32_e32 v40, v43, v40
	v_lshlrev_b32_e32 v70, 16, v34
	v_rcp_f32_e32 v43, v33
	s_nop 0
	v_mul_f32_e32 v43, v68, v43
	v_lshlrev_b32_e32 v38, 16, v35
	v_mul_f32_e32 v36, 0xbfb8aa3b, v70
	v_mul_f32_e32 v37, 0xbfb8aa3b, v38
	v_exp_f32_e32 v36, v36
	v_exp_f32_e32 v37, v37
	v_rcp_f32_e32 v42, v32
	s_nop 0
	v_mul_f32_e32 v42, v39, v42
	v_and_b32_e32 v39, 0xffff0000, v35
	v_pk_add_f32 v[32:33], v[36:37], 1.0 op_sel_hi:[1,0]
	v_and_b32_e32 v68, 0xffff0000, v34
	v_mul_f32_e32 v34, 0xbfb8aa3b, v68
	v_exp_f32_e32 v34, v34
	v_rcp_f32_e32 v71, v33
	s_nop 0
	v_mul_f32_e32 v71, v38, v71
	v_mul_f32_e32 v35, 0xbfb8aa3b, v39
	v_exp_f32_e32 v35, v35
	s_nop 0
	v_pk_add_f32 v[36:37], v[34:35], 1.0 op_sel_hi:[1,0]
	v_rcp_f32_e32 v33, v32
	s_nop 0
	v_mul_f32_e32 v70, v70, v33
	v_rcp_f32_e32 v85, v37
	s_nop 0
	v_mul_f32_e32 v85, v39, v85
	v_add_u32_e32 v32, 0x1000, v47
	ds_write2_b32 v32, v63, v65 offset0:64 offset1:80
	ds_write2_b32 v32, v67, v69 offset0:96 offset1:112
	ds_write2_b32 v32, v72, v73 offset0:132 offset1:148
	ds_write2_b32 v32, v74, v75 offset0:164 offset1:180
	ds_write2_b32 v32, v76, v77 offset0:200 offset1:216
	ds_write2_b32 v32, v78, v80 offset0:232 offset1:248
	v_add_u32_e32 v32, 0x1400, v47
	ds_write2_b32 v32, v79, v81 offset0:12 offset1:28
	ds_write2_b32 v32, v82, v83 offset0:44 offset1:60
	s_waitcnt lgkmcnt(0)
	s_barrier
; __device__ __forceinline__ unsigned pack2(float a, float b) { return (unsigned)f2bf(a) | ((unsigned)f2bf(b) << 16); }
; __device__ __forceinline__ float bflo(unsigned w) { return __uint_as_float(w << 16); }
; __device__ __forceinline__ float bfhi(unsigned w) { return __uint_as_float(w & 0xffff0000u); }
; __device__ __forceinline__ float silu_f(float g) { return g / (1.f + __expf(-g)); }
; template <int DH, int MODE>
; __device__ void attn_item(const Params& p, int layer, int b, int blk, int head, char* smem) {
;     ...
; #pragma unroll
;     for (int i = 0; i < NCH; ++i) {
;       int q = tid + 256 * i, r = q / CPR, c = (q % CPR) * 8;
;       float4 m0 = *reinterpret_cast<const float4*>(Of + r * OST + c);
;       float4 m1 = *reinterpret_cast<const float4*>(Of + r * OST + c + 4);
;       float mm[8] = {m0.x, m0.y, m0.z, m0.w, m1.x, m1.y, m1.z, m1.w};
;       unsigned gw[4] = {gt[i].x, gt[i].y, gt[i].z, gt[i].w};
;       unsigned ow[4];
; #pragma unroll
;       for (int e = 0; e < 4; ++e)
;         ow[e] = pack2(mm[2 * e] * silu_f(bflo(gw[e])), mm[2 * e + 1] * silu_f(bfhi(gw[e])));
;       *reinterpret_cast<uint4*>(Y + (tq0 + r) * YW + ycol + c) = make_uint4(ow[0], ow[1], ow[2], ow[3]);
;     }
	ds_read_b128 v[32:35], v66
	v_rcp_f32_e32 v84, v36
	s_nop 0
	v_mul_f32_e32 v84, v68, v84
	ds_read_b128 v[36:39], v66 offset:16
	v_add_co_u32_e32 v12, vcc, s77, v12
	s_waitcnt lgkmcnt(1)
	v_mov_b32_e32 v48, v32
	v_mov_b32_e32 v49, v34
	v_pk_mul_f32 v[40:41], v[40:41], v[48:49]
	v_mov_b32_e32 v34, v33
	v_pk_mul_f32 v[32:33], v[42:43], v[34:35]
	v_and_b32_sdwa v34, v41, v155 dst_sel:DWORD dst_unused:UNUSED_PAD src0_sel:WORD_1 src1_sel:DWORD
	v_and_b32_sdwa v35, v40, v155 dst_sel:DWORD dst_unused:UNUSED_PAD src0_sel:WORD_1 src1_sel:DWORD
	v_add3_u32 v35, v40, v35, s68
	v_add3_u32 v34, v41, v34, s68
	v_and_b32_sdwa v40, v33, v155 dst_sel:DWORD dst_unused:UNUSED_PAD src0_sel:WORD_1 src1_sel:DWORD
	v_and_b32_sdwa v41, v32, v155 dst_sel:DWORD dst_unused:UNUSED_PAD src0_sel:WORD_1 src1_sel:DWORD
	v_add3_u32 v33, v33, v40, s68
	v_add3_u32 v32, v32, v41, s68
	v_and_b32_e32 v33, 0xffff0000, v33
	v_and_b32_e32 v32, 0xffff0000, v32
	v_or_b32_sdwa v33, v33, v34 dst_sel:DWORD dst_unused:UNUSED_PAD src0_sel:DWORD src1_sel:WORD_1
	v_or_b32_sdwa v32, v32, v35 dst_sel:DWORD dst_unused:UNUSED_PAD src0_sel:DWORD src1_sel:WORD_1
	s_waitcnt lgkmcnt(0)
	v_mov_b32_e32 v34, v36
	v_mov_b32_e32 v35, v38
	v_pk_mul_f32 v[34:35], v[70:71], v[34:35]
	v_mov_b32_e32 v38, v37
	v_pk_mul_f32 v[36:37], v[84:85], v[38:39]
	v_and_b32_sdwa v38, v35, v155 dst_sel:DWORD dst_unused:UNUSED_PAD src0_sel:WORD_1 src1_sel:DWORD
	v_and_b32_sdwa v39, v34, v155 dst_sel:DWORD dst_unused:UNUSED_PAD src0_sel:WORD_1 src1_sel:DWORD
	v_add3_u32 v34, v34, v39, s68
	v_add3_u32 v35, v35, v38, s68
	v_and_b32_sdwa v38, v37, v155 dst_sel:DWORD dst_unused:UNUSED_PAD src0_sel:WORD_1 src1_sel:DWORD
	v_and_b32_sdwa v39, v36, v155 dst_sel:DWORD dst_unused:UNUSED_PAD src0_sel:WORD_1 src1_sel:DWORD
	v_add3_u32 v37, v37, v38, s68
	v_add3_u32 v36, v36, v39, s68
	v_and_b32_e32 v37, 0xffff0000, v37
	v_and_b32_e32 v36, 0xffff0000, v36
	v_or_b32_sdwa v35, v37, v35 dst_sel:DWORD dst_unused:UNUSED_PAD src0_sel:DWORD src1_sel:WORD_1
	v_or_b32_sdwa v34, v36, v34 dst_sel:DWORD dst_unused:UNUSED_PAD src0_sel:DWORD src1_sel:WORD_1
	ds_read_b128 v[36:39], v46
	v_addc_co_u32_e32 v13, vcc, 0, v13, vcc
	global_store_dwordx4 v[12:13], v[32:35], off offset:1024
	ds_read_b128 v[32:35], v46 offset:16
	s_waitcnt lgkmcnt(1)
	v_mov_b32_e32 v12, v36
	v_mov_b32_e32 v13, v38
	v_pk_mul_f32 v[4:5], v[4:5], v[12:13]
	v_mov_b32_e32 v38, v37
	v_pk_mul_f32 v[12:13], v[28:29], v[38:39]
	v_and_b32_sdwa v28, v5, v155 dst_sel:DWORD dst_unused:UNUSED_PAD src0_sel:WORD_1 src1_sel:DWORD
	v_and_b32_sdwa v29, v4, v155 dst_sel:DWORD dst_unused:UNUSED_PAD src0_sel:WORD_1 src1_sel:DWORD
	v_add3_u32 v4, v4, v29, s68
	v_add3_u32 v5, v5, v28, s68
	v_and_b32_sdwa v28, v13, v155 dst_sel:DWORD dst_unused:UNUSED_PAD src0_sel:WORD_1 src1_sel:DWORD
	v_and_b32_sdwa v29, v12, v155 dst_sel:DWORD dst_unused:UNUSED_PAD src0_sel:WORD_1 src1_sel:DWORD
	v_add3_u32 v13, v13, v28, s68
	v_add3_u32 v12, v12, v29, s68
	v_and_b32_e32 v13, 0xffff0000, v13
	v_and_b32_e32 v12, 0xffff0000, v12
	v_or_b32_sdwa v5, v13, v5 dst_sel:DWORD dst_unused:UNUSED_PAD src0_sel:DWORD src1_sel:WORD_1
	v_or_b32_sdwa v4, v12, v4 dst_sel:DWORD dst_unused:UNUSED_PAD src0_sel:DWORD src1_sel:WORD_1
	s_waitcnt lgkmcnt(0)
	v_mov_b32_e32 v12, v32
	v_mov_b32_e32 v13, v34
	v_pk_mul_f32 v[6:7], v[6:7], v[12:13]
	v_mov_b32_e32 v34, v33
	v_pk_mul_f32 v[12:13], v[30:31], v[34:35]
	v_and_b32_sdwa v28, v7, v155 dst_sel:DWORD dst_unused:UNUSED_PAD src0_sel:WORD_1 src1_sel:DWORD
	v_and_b32_sdwa v29, v6, v155 dst_sel:DWORD dst_unused:UNUSED_PAD src0_sel:WORD_1 src1_sel:DWORD
	v_add3_u32 v6, v6, v29, s68
	v_add3_u32 v7, v7, v28, s68
	v_and_b32_sdwa v28, v13, v155 dst_sel:DWORD dst_unused:UNUSED_PAD src0_sel:WORD_1 src1_sel:DWORD
	v_and_b32_sdwa v29, v12, v155 dst_sel:DWORD dst_unused:UNUSED_PAD src0_sel:WORD_1 src1_sel:DWORD
	v_add3_u32 v13, v13, v28, s68
	v_add3_u32 v12, v12, v29, s68
	ds_read_b128 v[28:31], v45
	v_and_b32_e32 v13, 0xffff0000, v13
	v_and_b32_e32 v12, 0xffff0000, v12
	v_add_co_u32_e32 v10, vcc, s77, v10
	v_or_b32_sdwa v7, v13, v7 dst_sel:DWORD dst_unused:UNUSED_PAD src0_sel:DWORD src1_sel:WORD_1
	v_or_b32_sdwa v6, v12, v6 dst_sel:DWORD dst_unused:UNUSED_PAD src0_sel:DWORD src1_sel:WORD_1
	v_addc_co_u32_e32 v11, vcc, 0, v11, vcc
	global_store_dwordx4 v[10:11], v[4:7], off offset:1024
	s_waitcnt lgkmcnt(0)
; __device__ __forceinline__ unsigned pack2(float a, float b) { return (unsigned)f2bf(a) | ((unsigned)f2bf(b) << 16); }
; __device__ __forceinline__ float bflo(unsigned w) { return __uint_as_float(w << 16); }
; __device__ __forceinline__ float bfhi(unsigned w) { return __uint_as_float(w & 0xffff0000u); }
; __device__ __forceinline__ float silu_f(float g) { return g / (1.f + __expf(-g)); }
; template <int DH, int MODE>
; __device__ void attn_item(const Params& p, int layer, int b, int blk, int head, char* smem) {
;     ...
; #pragma unroll
;     for (int i = 0; i < NCH; ++i) {
;       int q = tid + 256 * i, r = q / CPR, c = (q % CPR) * 8;
;       float4 m0 = *reinterpret_cast<const float4*>(Of + r * OST + c);
;       float4 m1 = *reinterpret_cast<const float4*>(Of + r * OST + c + 4);
;       float mm[8] = {m0.x, m0.y, m0.z, m0.w, m1.x, m1.y, m1.z, m1.w};
;       unsigned gw[4] = {gt[i].x, gt[i].y, gt[i].z, gt[i].w};
;       unsigned ow[4];
; #pragma unroll
;       for (int e = 0; e < 4; ++e)
;         ow[e] = pack2(mm[2 * e] * silu_f(bflo(gw[e])), mm[2 * e + 1] * silu_f(bfhi(gw[e])));
;       *reinterpret_cast<uint4*>(Y + (tq0 + r) * YW + ycol + c) = make_uint4(ow[0], ow[1], ow[2], ow[3]);
;     }
;   }
;   __syncthreads();
	v_mov_b32_e32 v10, v28
	v_mov_b32_e32 v11, v30
	ds_read_b128 v[4:7], v45 offset:16
	v_pk_mul_f32 v[0:1], v[0:1], v[10:11]
	v_mov_b32_e32 v30, v29
	v_pk_mul_f32 v[10:11], v[24:25], v[30:31]
	v_and_b32_sdwa v12, v1, v155 dst_sel:DWORD dst_unused:UNUSED_PAD src0_sel:WORD_1 src1_sel:DWORD
	v_and_b32_sdwa v13, v0, v155 dst_sel:DWORD dst_unused:UNUSED_PAD src0_sel:WORD_1 src1_sel:DWORD
	v_add3_u32 v0, v0, v13, s68
	v_add3_u32 v1, v1, v12, s68
	v_and_b32_sdwa v12, v11, v155 dst_sel:DWORD dst_unused:UNUSED_PAD src0_sel:WORD_1 src1_sel:DWORD
	v_and_b32_sdwa v13, v10, v155 dst_sel:DWORD dst_unused:UNUSED_PAD src0_sel:WORD_1 src1_sel:DWORD
	v_add3_u32 v11, v11, v12, s68
	v_add3_u32 v10, v10, v13, s68
	v_and_b32_e32 v11, 0xffff0000, v11
	v_and_b32_e32 v10, 0xffff0000, v10
	v_or_b32_sdwa v1, v11, v1 dst_sel:DWORD dst_unused:UNUSED_PAD src0_sel:DWORD src1_sel:WORD_1
	v_or_b32_sdwa v0, v10, v0 dst_sel:DWORD dst_unused:UNUSED_PAD src0_sel:DWORD src1_sel:WORD_1
	s_waitcnt lgkmcnt(0)
	v_mov_b32_e32 v10, v4
	v_mov_b32_e32 v11, v6
	v_pk_mul_f32 v[2:3], v[2:3], v[10:11]
	v_mov_b32_e32 v6, v5
	v_pk_mul_f32 v[4:5], v[26:27], v[6:7]
	v_and_b32_sdwa v6, v3, v155 dst_sel:DWORD dst_unused:UNUSED_PAD src0_sel:WORD_1 src1_sel:DWORD
	v_and_b32_sdwa v7, v2, v155 dst_sel:DWORD dst_unused:UNUSED_PAD src0_sel:WORD_1 src1_sel:DWORD
	v_add3_u32 v2, v2, v7, s68
	v_add3_u32 v3, v3, v6, s68
	v_and_b32_sdwa v6, v5, v155 dst_sel:DWORD dst_unused:UNUSED_PAD src0_sel:WORD_1 src1_sel:DWORD
	v_and_b32_sdwa v7, v4, v155 dst_sel:DWORD dst_unused:UNUSED_PAD src0_sel:WORD_1 src1_sel:DWORD
	v_add3_u32 v5, v5, v6, s68
	v_add3_u32 v4, v4, v7, s68
	v_and_b32_e32 v5, 0xffff0000, v5
	v_and_b32_e32 v4, 0xffff0000, v4
	v_or_b32_sdwa v3, v5, v3 dst_sel:DWORD dst_unused:UNUSED_PAD src0_sel:DWORD src1_sel:WORD_1
	v_or_b32_sdwa v2, v4, v2 dst_sel:DWORD dst_unused:UNUSED_PAD src0_sel:DWORD src1_sel:WORD_1
	ds_read_b128 v[4:7], v44
	v_add_co_u32_e32 v8, vcc, s77, v8
	s_nop 1
	v_addc_co_u32_e32 v9, vcc, 0, v9, vcc
	global_store_dwordx4 v[8:9], v[0:3], off offset:1024
	s_waitcnt lgkmcnt(0)
	v_mov_b32_e32 v8, v4
	v_mov_b32_e32 v9, v6
	ds_read_b128 v[0:3], v44 offset:16
	v_pk_mul_f32 v[8:9], v[16:17], v[8:9]
	v_mov_b32_e32 v6, v5
	v_pk_mul_f32 v[4:5], v[18:19], v[6:7]
	v_and_b32_sdwa v6, v9, v155 dst_sel:DWORD dst_unused:UNUSED_PAD src0_sel:WORD_1 src1_sel:DWORD
	v_and_b32_sdwa v7, v8, v155 dst_sel:DWORD dst_unused:UNUSED_PAD src0_sel:WORD_1 src1_sel:DWORD
	v_add3_u32 v7, v8, v7, s68
	v_add3_u32 v6, v9, v6, s68
	v_and_b32_sdwa v8, v5, v155 dst_sel:DWORD dst_unused:UNUSED_PAD src0_sel:WORD_1 src1_sel:DWORD
	v_and_b32_sdwa v9, v4, v155 dst_sel:DWORD dst_unused:UNUSED_PAD src0_sel:WORD_1 src1_sel:DWORD
	v_add3_u32 v5, v5, v8, s68
	v_add3_u32 v4, v4, v9, s68
	v_and_b32_e32 v5, 0xffff0000, v5
	v_and_b32_e32 v4, 0xffff0000, v4
	v_or_b32_sdwa v5, v5, v6 dst_sel:DWORD dst_unused:UNUSED_PAD src0_sel:DWORD src1_sel:WORD_1
	v_or_b32_sdwa v4, v4, v7 dst_sel:DWORD dst_unused:UNUSED_PAD src0_sel:DWORD src1_sel:WORD_1
	s_waitcnt lgkmcnt(0)
	v_mov_b32_e32 v6, v0
	v_mov_b32_e32 v7, v2
	v_pk_mul_f32 v[6:7], v[20:21], v[6:7]
	v_mov_b32_e32 v2, v1
	v_pk_mul_f32 v[0:1], v[22:23], v[2:3]
	v_and_b32_sdwa v2, v7, v155 dst_sel:DWORD dst_unused:UNUSED_PAD src0_sel:WORD_1 src1_sel:DWORD
	v_and_b32_sdwa v3, v6, v155 dst_sel:DWORD dst_unused:UNUSED_PAD src0_sel:WORD_1 src1_sel:DWORD
	v_add3_u32 v2, v7, v2, s68
	v_and_b32_sdwa v7, v0, v155 dst_sel:DWORD dst_unused:UNUSED_PAD src0_sel:WORD_1 src1_sel:DWORD
	v_add3_u32 v3, v6, v3, s68
	v_and_b32_sdwa v6, v1, v155 dst_sel:DWORD dst_unused:UNUSED_PAD src0_sel:WORD_1 src1_sel:DWORD
	v_add3_u32 v0, v0, v7, s68
	v_add3_u32 v1, v1, v6, s68
	v_and_b32_e32 v0, 0xffff0000, v0
	v_and_b32_e32 v1, 0xffff0000, v1
	v_or_b32_sdwa v6, v0, v3 dst_sel:DWORD dst_unused:UNUSED_PAD src0_sel:DWORD src1_sel:WORD_1
	v_add_co_u32_e32 v0, vcc, 0x184a1000, v14
	v_or_b32_sdwa v7, v1, v2 dst_sel:DWORD dst_unused:UNUSED_PAD src0_sel:DWORD src1_sel:WORD_1
	s_nop 0
	v_addc_co_u32_e32 v1, vcc, 0, v15, vcc
	global_store_dwordx4 v[0:1], v[4:7], off offset:1024
	s_barrier

; __device__ void phase_merge(const Params& p, int layer, char* smem) {
;     ...
;         [&](int s) {
;           int seg = s / 48, r = s - seg * 48;
;           if (r == 31) {
; #pragma unroll
;             for (int n = 0; n < 4; ++n) {
;               float bm = bmp[seg * 1024 + n * 16];
; #pragma unroll
;               for (int m = 0; m < 4; ++m)
; #pragma unroll
;                 for (int j = 0; j < 4; ++j) {
;                   GL[((m * 4 + n) * 4 + j) * 256] = f2bf(1.f / (1.f + __expf(-(acc[m][n][j] + bm))));
;                   acc[m][n][j] = 0.f;
;                 }
;             }
.LBB0_595:
	s_cmp_eq_u32 s16, 31
	s_cbranch_scc0 .LBB0_597
	s_mul_i32 s12, s68, 0xab
	s_lshr_b32 s12, s12, 1
	s_and_b32 s22, s12, 0x7000
	v_lshl_add_u64 v[2:3], v[230:231], 0, s[22:23]
	global_load_dword v164, v[2:3], off
	global_load_dword v165, v[2:3], off offset:64
	global_load_dword v166, v[2:3], off offset:128
	global_load_dword v1, v[2:3], off offset:192
	s_waitcnt vmcnt(3)
	v_add_f32_e32 v2, v160, v164
	v_add_f32_e32 v3, v161, v164
	v_mul_f32_e32 v2, 0xbfb8aa3b, v2
	v_add_f32_e32 v167, v162, v164
	v_mul_f32_e32 v3, 0xbfb8aa3b, v3
	v_exp_f32_e32 v2, v2
	v_add_f32_e32 v168, v163, v164
	v_mul_f32_e32 v167, 0xbfb8aa3b, v167
	v_exp_f32_e32 v3, v3
	v_mul_f32_e32 v168, 0xbfb8aa3b, v168
	v_exp_f32_e32 v167, v167
	v_exp_f32_e32 v168, v168
	v_add_f32_e32 v2, 1.0, v2
	v_add_f32_e32 v3, 1.0, v3
	v_add_f32_e32 v169, v144, v164
	v_add_f32_e32 v167, 1.0, v167
	v_mul_f32_e32 v169, 0xbfb8aa3b, v169
	v_add_f32_e32 v168, 1.0, v168
	v_exp_f32_e32 v169, v169
	s_nop 0
	v_add_f32_e32 v169, 1.0, v169
	v_div_scale_f32 v174, s[12:13], 1.0, v3, 1.0
	v_div_scale_f32 v176, s[14:15], 1.0, v167, 1.0
	v_div_scale_f32 v178, s[16:17], 1.0, v168, 1.0
	v_add_f32_e32 v170, v145, v164
	s_mov_b64 vcc, s[12:13]
	v_mul_f32_e32 v170, 0xbfb8aa3b, v170
	v_rcp_f32_e32 v2, v2
	s_nop 0
	s_mov_b64 vcc, s[14:15]
	v_exp_f32_e32 v170, v170
	v_bfe_u32 v172, v2, 16, 1
	v_rcp_f32_e32 v3, v3
	s_nop 0
	s_mov_b64 vcc, s[16:17]
	v_div_scale_f32 v180, s[20:21], 1.0, v169, 1.0
	v_add3_u32 v2, v2, v172, s63
	v_bfe_u32 v172, v3, 16, 1
	v_rcp_f32_e32 v167, v167
	s_nop 0
	ds_write_b16_d16_hi v234, v2 offset:32768
	v_add3_u32 v2, v3, v172, s63
	v_bfe_u32 v3, v167, 16, 1
	v_rcp_f32_e32 v168, v168
	s_nop 0
	ds_write_b16_d16_hi v234, v2 offset:33280
	v_add3_u32 v2, v167, v3, s63
	v_bfe_u32 v3, v168, 16, 1
	ds_write_b16_d16_hi v234, v2 offset:33792
	v_add3_u32 v2, v168, v3, s63
	v_add_f32_e32 v3, 1.0, v170
	s_mov_b64 vcc, s[20:21]
	ds_write_b16_d16_hi v234, v2 offset:34304
	v_rcp_f32_e32 v2, v169
	s_nop 0
	v_bfe_u32 v169, v2, 16, 1
	v_add3_u32 v2, v2, v169, s63
	ds_write_b16_d16_hi v234, v2 offset:40960
	v_add_f32_e32 v167, v146, v164
	v_mul_f32_e32 v167, 0xbfb8aa3b, v167
	v_exp_f32_e32 v167, v167
	v_rcp_f32_e32 v2, v3
	s_nop 0
	v_bfe_u32 v169, v2, 16, 1
	v_add_f32_e32 v3, 1.0, v167
	v_add3_u32 v2, v2, v169, s63
	ds_write_b16_d16_hi v234, v2 offset:41472
	v_add_f32_e32 v167, v147, v164
	v_mul_f32_e32 v167, 0xbfb8aa3b, v167
	v_exp_f32_e32 v167, v167
	v_rcp_f32_e32 v2, v3
	s_nop 0
	v_bfe_u32 v169, v2, 16, 1
	v_add_f32_e32 v3, 1.0, v167
	v_add3_u32 v2, v2, v169, s63
	ds_write_b16_d16_hi v234, v2 offset:41984
	v_add_f32_e32 v167, v128, v164
	v_mul_f32_e32 v167, 0xbfb8aa3b, v167
	v_exp_f32_e32 v167, v167
	v_rcp_f32_e32 v2, v3
	s_nop 0
	v_bfe_u32 v169, v2, 16, 1
	v_add_f32_e32 v3, 1.0, v167
	v_add3_u32 v2, v2, v169, s63
	ds_write_b16_d16_hi v234, v2 offset:42496
	v_add_f32_e32 v167, v129, v164
	v_mul_f32_e32 v167, 0xbfb8aa3b, v167
	v_exp_f32_e32 v167, v167
	v_rcp_f32_e32 v2, v3
	s_nop 0
	v_bfe_u32 v169, v2, 16, 1
	v_add_f32_e32 v3, 1.0, v167
	v_add3_u32 v2, v2, v169, s63
	ds_write_b16_d16_hi v234, v2 offset:49152
	v_add_f32_e32 v167, v130, v164
	v_mul_f32_e32 v167, 0xbfb8aa3b, v167
	v_exp_f32_e32 v167, v167
	v_rcp_f32_e32 v2, v3
	s_nop 0
	v_bfe_u32 v169, v2, 16, 1
	v_add_f32_e32 v3, 1.0, v167
	v_add3_u32 v2, v2, v169, s63
	ds_write_b16_d16_hi v234, v2 offset:49664
	v_add_f32_e32 v167, v131, v164
	v_mul_f32_e32 v167, 0xbfb8aa3b, v167
	v_exp_f32_e32 v167, v167
	v_rcp_f32_e32 v2, v3
	s_nop 0
	v_bfe_u32 v169, v2, 16, 1
	v_add_f32_e32 v3, 1.0, v167
	v_add3_u32 v2, v2, v169, s63
	ds_write_b16_d16_hi v234, v2 offset:50176
	v_add_f32_e32 v167, v112, v164
	v_mul_f32_e32 v167, 0xbfb8aa3b, v167
	v_exp_f32_e32 v167, v167
	v_rcp_f32_e32 v2, v3
	s_nop 0
	v_bfe_u32 v169, v2, 16, 1
	v_add_f32_e32 v3, 1.0, v167
	v_add3_u32 v2, v2, v169, s63
	ds_write_b16_d16_hi v234, v2 offset:50688
	v_add_f32_e32 v167, v113, v164
	v_mul_f32_e32 v167, 0xbfb8aa3b, v167
	v_exp_f32_e32 v167, v167
	v_rcp_f32_e32 v2, v3
	s_nop 0
	v_bfe_u32 v169, v2, 16, 1
	v_add_f32_e32 v3, 1.0, v167
	v_add3_u32 v2, v2, v169, s63
	ds_write_b16_d16_hi v234, v2 offset:57344
	v_add_f32_e32 v167, v114, v164
	v_mul_f32_e32 v167, 0xbfb8aa3b, v167
	v_exp_f32_e32 v167, v167
	v_rcp_f32_e32 v2, v3
	s_nop 0
	v_bfe_u32 v169, v2, 16, 1
	v_add_f32_e32 v3, 1.0, v167
	v_add3_u32 v2, v2, v169, s63
	ds_write_b16_d16_hi v234, v2 offset:57856
	v_add_f32_e32 v164, v115, v164
	v_mul_f32_e32 v164, 0xbfb8aa3b, v164
	v_exp_f32_e32 v164, v164
	v_rcp_f32_e32 v2, v3
	s_nop 0
	v_add_f32_e32 v3, 1.0, v164
	v_bfe_u32 v168, v2, 16, 1
	v_add3_u32 v2, v2, v168, s63
	ds_write_b16_d16_hi v234, v2 offset:58368
	s_waitcnt vmcnt(2)
; __device__ void phase_merge(const Params& p, int layer, char* smem) {
;     ...
;         [&](int s) {
;           int seg = s / 48, r = s - seg * 48;
;           if (r == 31) {
; #pragma unroll
;             for (int n = 0; n < 4; ++n) {
;               float bm = bmp[seg * 1024 + n * 16];
; #pragma unroll
;               for (int m = 0; m < 4; ++m)
; #pragma unroll
;                 for (int j = 0; j < 4; ++j) {
;                   GL[((m * 4 + n) * 4 + j) * 256] = f2bf(1.f / (1.f + __expf(-(acc[m][n][j] + bm))));
;                   acc[m][n][j] = 0.f;
;                 }
;             }
	v_add_f32_e32 v164, v156, v165
	v_mul_f32_e32 v164, 0xbfb8aa3b, v164
	v_exp_f32_e32 v164, v164
	v_rcp_f32_e32 v2, v3
	s_nop 0
	v_bfe_u32 v168, v2, 16, 1
	v_add_f32_e32 v3, 1.0, v164
	v_add3_u32 v2, v2, v168, s63
	ds_write_b16_d16_hi v234, v2 offset:58880
	v_add_f32_e32 v164, v157, v165
	v_mul_f32_e32 v164, 0xbfb8aa3b, v164
	v_exp_f32_e32 v164, v164
	v_rcp_f32_e32 v2, v3
	s_nop 0
	v_bfe_u32 v168, v2, 16, 1
	v_add_f32_e32 v3, 1.0, v164
	v_add3_u32 v2, v2, v168, s63
	ds_write_b16_d16_hi v234, v2 offset:34816
	v_add_f32_e32 v164, v158, v165
	v_mul_f32_e32 v164, 0xbfb8aa3b, v164
	v_exp_f32_e32 v164, v164
	v_rcp_f32_e32 v2, v3
	s_nop 0
	v_bfe_u32 v168, v2, 16, 1
	v_add_f32_e32 v3, 1.0, v164
	v_add3_u32 v2, v2, v168, s63
	ds_write_b16_d16_hi v234, v2 offset:35328
	v_add_f32_e32 v164, v159, v165
	v_mul_f32_e32 v164, 0xbfb8aa3b, v164
	v_exp_f32_e32 v164, v164
	v_rcp_f32_e32 v2, v3
	s_nop 0
	v_bfe_u32 v168, v2, 16, 1
	v_add_f32_e32 v3, 1.0, v164
	v_add3_u32 v2, v2, v168, s63
	ds_write_b16_d16_hi v234, v2 offset:35840
	v_add_f32_e32 v164, v140, v165
	v_mul_f32_e32 v164, 0xbfb8aa3b, v164
	v_exp_f32_e32 v164, v164
	v_rcp_f32_e32 v2, v3
	s_nop 0
	v_bfe_u32 v168, v2, 16, 1
	v_add_f32_e32 v3, 1.0, v164
	v_add3_u32 v2, v2, v168, s63
	ds_write_b16_d16_hi v234, v2 offset:36352
	v_add_f32_e32 v164, v141, v165
	v_mul_f32_e32 v164, 0xbfb8aa3b, v164
	v_exp_f32_e32 v164, v164
	v_rcp_f32_e32 v2, v3
	s_nop 0
	v_bfe_u32 v168, v2, 16, 1
	v_add_f32_e32 v3, 1.0, v164
	v_add3_u32 v2, v2, v168, s63
	ds_write_b16_d16_hi v234, v2 offset:43008
	v_add_f32_e32 v164, v142, v165
	v_mul_f32_e32 v164, 0xbfb8aa3b, v164
	v_exp_f32_e32 v164, v164
	v_rcp_f32_e32 v2, v3
	s_nop 0
	v_bfe_u32 v168, v2, 16, 1
	v_add_f32_e32 v3, 1.0, v164
	v_add3_u32 v2, v2, v168, s63
	ds_write_b16_d16_hi v234, v2 offset:43520
	v_add_f32_e32 v164, v143, v165
	v_mul_f32_e32 v164, 0xbfb8aa3b, v164
	v_exp_f32_e32 v164, v164
	v_rcp_f32_e32 v2, v3
	s_nop 0
	v_bfe_u32 v168, v2, 16, 1
	v_add_f32_e32 v3, 1.0, v164
	v_add3_u32 v2, v2, v168, s63
	ds_write_b16_d16_hi v234, v2 offset:44032
	v_add_f32_e32 v164, v124, v165
	v_mul_f32_e32 v164, 0xbfb8aa3b, v164
	v_exp_f32_e32 v164, v164
	v_rcp_f32_e32 v2, v3
	s_nop 0
	v_bfe_u32 v168, v2, 16, 1
	v_add_f32_e32 v3, 1.0, v164
	v_add3_u32 v2, v2, v168, s63
	ds_write_b16_d16_hi v234, v2 offset:44544
	v_add_f32_e32 v164, v125, v165
	v_mul_f32_e32 v164, 0xbfb8aa3b, v164
	v_exp_f32_e32 v164, v164
	v_rcp_f32_e32 v2, v3
	s_nop 0
	v_bfe_u32 v168, v2, 16, 1
	v_add_f32_e32 v3, 1.0, v164
	v_add3_u32 v2, v2, v168, s63
	ds_write_b16_d16_hi v234, v2 offset:51200
	v_add_f32_e32 v164, v126, v165
	v_mul_f32_e32 v164, 0xbfb8aa3b, v164
	v_exp_f32_e32 v164, v164
	v_rcp_f32_e32 v2, v3
	s_nop 0
	v_bfe_u32 v168, v2, 16, 1
	v_add_f32_e32 v3, 1.0, v164
	v_add3_u32 v2, v2, v168, s63
	ds_write_b16_d16_hi v234, v2 offset:51712
	v_add_f32_e32 v164, v127, v165
	v_mul_f32_e32 v164, 0xbfb8aa3b, v164
	v_exp_f32_e32 v164, v164
	v_rcp_f32_e32 v2, v3
	s_nop 0
	v_bfe_u32 v168, v2, 16, 1
	v_add_f32_e32 v3, 1.0, v164
	v_add3_u32 v2, v2, v168, s63
	ds_write_b16_d16_hi v234, v2 offset:52224
	v_add_f32_e32 v164, v108, v165
	v_mul_f32_e32 v164, 0xbfb8aa3b, v164
	v_exp_f32_e32 v164, v164
	v_rcp_f32_e32 v2, v3
	s_nop 0
	v_bfe_u32 v168, v2, 16, 1
	v_add_f32_e32 v3, 1.0, v164
	v_add3_u32 v2, v2, v168, s63
	ds_write_b16_d16_hi v234, v2 offset:52736
	v_add_f32_e32 v164, v109, v165
	v_mul_f32_e32 v164, 0xbfb8aa3b, v164
	v_exp_f32_e32 v164, v164
	v_rcp_f32_e32 v2, v3
	s_nop 0
	v_bfe_u32 v168, v2, 16, 1
	v_add_f32_e32 v3, 1.0, v164
	v_add3_u32 v2, v2, v168, s63
	ds_write_b16_d16_hi v234, v2 offset:59392
	v_add_f32_e32 v164, v110, v165
	v_mul_f32_e32 v164, 0xbfb8aa3b, v164
	v_exp_f32_e32 v164, v164
	v_rcp_f32_e32 v2, v3
	s_nop 0
	v_bfe_u32 v168, v2, 16, 1
	v_add_f32_e32 v3, 1.0, v164
	v_add3_u32 v2, v2, v168, s63
	ds_write_b16_d16_hi v234, v2 offset:59904
	v_add_f32_e32 v164, v111, v165
	v_mul_f32_e32 v164, 0xbfb8aa3b, v164
	v_exp_f32_e32 v164, v164
	v_rcp_f32_e32 v2, v3
	s_nop 0
	v_bfe_u32 v167, v2, 16, 1
	v_add_f32_e32 v3, 1.0, v164
	v_add3_u32 v2, v2, v167, s63
	ds_write_b16_d16_hi v234, v2 offset:60416
	s_waitcnt vmcnt(1)
	v_add_f32_e32 v164, v152, v166
	v_mul_f32_e32 v164, 0xbfb8aa3b, v164
	v_exp_f32_e32 v164, v164
	v_rcp_f32_e32 v2, v3
	s_nop 0
	v_bfe_u32 v167, v2, 16, 1
	v_add_f32_e32 v3, 1.0, v164
	v_add3_u32 v2, v2, v167, s63
	ds_write_b16_d16_hi v234, v2 offset:60928
	v_add_f32_e32 v164, v153, v166
	v_mul_f32_e32 v164, 0xbfb8aa3b, v164
	v_exp_f32_e32 v164, v164
	v_rcp_f32_e32 v2, v3
	s_nop 0
	v_bfe_u32 v167, v2, 16, 1
	v_add_f32_e32 v3, 1.0, v164
	v_add3_u32 v2, v2, v167, s63
	ds_write_b16_d16_hi v234, v2 offset:36864
	v_add_f32_e32 v164, v154, v166
	v_mul_f32_e32 v164, 0xbfb8aa3b, v164
	v_exp_f32_e32 v164, v164
	v_rcp_f32_e32 v2, v3
	s_nop 0
	v_bfe_u32 v167, v2, 16, 1
	v_add_f32_e32 v3, 1.0, v164
	v_add3_u32 v2, v2, v167, s63
	ds_write_b16_d16_hi v234, v2 offset:37376
	v_add_f32_e32 v164, v155, v166
	v_mul_f32_e32 v164, 0xbfb8aa3b, v164
	v_exp_f32_e32 v164, v164
	v_rcp_f32_e32 v2, v3
	s_nop 0
	v_bfe_u32 v167, v2, 16, 1
	v_add_f32_e32 v3, 1.0, v164
	v_add3_u32 v2, v2, v167, s63
	ds_write_b16_d16_hi v234, v2 offset:37888
	v_add_f32_e32 v164, v136, v166
	v_mul_f32_e32 v164, 0xbfb8aa3b, v164
	v_exp_f32_e32 v164, v164
	v_rcp_f32_e32 v2, v3
	s_nop 0
	v_bfe_u32 v167, v2, 16, 1
	v_add_f32_e32 v3, 1.0, v164
	v_add3_u32 v2, v2, v167, s63
	ds_write_b16_d16_hi v234, v2 offset:38400
	v_add_f32_e32 v164, v137, v166
	v_mul_f32_e32 v164, 0xbfb8aa3b, v164
	v_exp_f32_e32 v164, v164
	v_rcp_f32_e32 v2, v3
	s_nop 0
	v_bfe_u32 v167, v2, 16, 1
	v_add_f32_e32 v3, 1.0, v164
	v_add3_u32 v2, v2, v167, s63
	ds_write_b16_d16_hi v234, v2 offset:45056
; __device__ void phase_merge(const Params& p, int layer, char* smem) {
;     ...
;         [&](int s) {
;           int seg = s / 48, r = s - seg * 48;
;           if (r == 31) {
; #pragma unroll
;             for (int n = 0; n < 4; ++n) {
;               float bm = bmp[seg * 1024 + n * 16];
; #pragma unroll
;               for (int m = 0; m < 4; ++m)
; #pragma unroll
;                 for (int j = 0; j < 4; ++j) {
;                   GL[((m * 4 + n) * 4 + j) * 256] = f2bf(1.f / (1.f + __expf(-(acc[m][n][j] + bm))));
;                   acc[m][n][j] = 0.f;
;                 }
;             }
	v_add_f32_e32 v164, v138, v166
	v_mul_f32_e32 v164, 0xbfb8aa3b, v164
	v_exp_f32_e32 v164, v164
	v_rcp_f32_e32 v2, v3
	s_nop 0
	v_bfe_u32 v167, v2, 16, 1
	v_add_f32_e32 v3, 1.0, v164
	v_add3_u32 v2, v2, v167, s63
	ds_write_b16_d16_hi v234, v2 offset:45568
	v_add_f32_e32 v164, v139, v166
	v_mul_f32_e32 v164, 0xbfb8aa3b, v164
	v_exp_f32_e32 v164, v164
	v_rcp_f32_e32 v2, v3
	s_nop 0
	v_bfe_u32 v167, v2, 16, 1
	v_add_f32_e32 v3, 1.0, v164
	v_add3_u32 v2, v2, v167, s63
	ds_write_b16_d16_hi v234, v2 offset:46080
	v_add_f32_e32 v164, v120, v166
	v_mul_f32_e32 v164, 0xbfb8aa3b, v164
	v_exp_f32_e32 v164, v164
	v_rcp_f32_e32 v2, v3
	s_nop 0
	v_bfe_u32 v167, v2, 16, 1
	v_add_f32_e32 v3, 1.0, v164
	v_add3_u32 v2, v2, v167, s63
	ds_write_b16_d16_hi v234, v2 offset:46592
	v_add_f32_e32 v164, v121, v166
	v_mul_f32_e32 v164, 0xbfb8aa3b, v164
	v_exp_f32_e32 v164, v164
	v_rcp_f32_e32 v2, v3
	s_nop 0
	v_bfe_u32 v167, v2, 16, 1
	v_add_f32_e32 v3, 1.0, v164
	v_add3_u32 v2, v2, v167, s63
	ds_write_b16_d16_hi v234, v2 offset:53248
	v_add_f32_e32 v164, v122, v166
	v_mul_f32_e32 v164, 0xbfb8aa3b, v164
	v_exp_f32_e32 v164, v164
	v_rcp_f32_e32 v2, v3
	s_nop 0
	v_bfe_u32 v167, v2, 16, 1
	v_add_f32_e32 v3, 1.0, v164
	v_add3_u32 v2, v2, v167, s63
	ds_write_b16_d16_hi v234, v2 offset:53760
	v_add_f32_e32 v164, v123, v166
	v_mul_f32_e32 v164, 0xbfb8aa3b, v164
	v_exp_f32_e32 v164, v164
	v_rcp_f32_e32 v2, v3
	s_nop 0
	v_bfe_u32 v167, v2, 16, 1
	v_add_f32_e32 v3, 1.0, v164
	v_add3_u32 v2, v2, v167, s63
	ds_write_b16_d16_hi v234, v2 offset:54272
	v_add_f32_e32 v164, v100, v166
	v_mul_f32_e32 v164, 0xbfb8aa3b, v164
	v_exp_f32_e32 v164, v164
	v_rcp_f32_e32 v2, v3
	s_nop 0
	v_bfe_u32 v167, v2, 16, 1
	v_add_f32_e32 v3, 1.0, v164
	v_add3_u32 v2, v2, v167, s63
	ds_write_b16_d16_hi v234, v2 offset:54784
	v_add_f32_e32 v164, v101, v166
	v_mul_f32_e32 v164, 0xbfb8aa3b, v164
	v_exp_f32_e32 v164, v164
	v_rcp_f32_e32 v2, v3
	s_nop 0
	v_bfe_u32 v167, v2, 16, 1
	v_add_f32_e32 v3, 1.0, v164
	v_add3_u32 v2, v2, v167, s63
	ds_write_b16_d16_hi v234, v2 offset:61440
	v_add_f32_e32 v164, v102, v166
	v_mul_f32_e32 v164, 0xbfb8aa3b, v164
	v_exp_f32_e32 v164, v164
	v_rcp_f32_e32 v2, v3
	s_nop 0
	v_bfe_u32 v167, v2, 16, 1
	v_add_f32_e32 v3, 1.0, v164
	v_add3_u32 v2, v2, v167, s63
	ds_write_b16_d16_hi v234, v2 offset:61952
	v_add_f32_e32 v164, v103, v166
	v_mul_f32_e32 v164, 0xbfb8aa3b, v164
	v_exp_f32_e32 v164, v164
	v_rcp_f32_e32 v2, v3
	s_nop 0
	v_bfe_u32 v166, v2, 16, 1
	v_add_f32_e32 v3, 1.0, v164
	v_add3_u32 v2, v2, v166, s63
	ds_write_b16_d16_hi v234, v2 offset:62464
	s_waitcnt vmcnt(0)
	v_add_f32_e32 v164, v148, v1
	v_mul_f32_e32 v164, 0xbfb8aa3b, v164
	v_exp_f32_e32 v164, v164
	v_rcp_f32_e32 v2, v3
	s_nop 0
	v_bfe_u32 v166, v2, 16, 1
	v_add_f32_e32 v3, 1.0, v164
	v_add3_u32 v2, v2, v166, s63
	ds_write_b16_d16_hi v234, v2 offset:62976
	v_add_f32_e32 v164, v149, v1
	v_mul_f32_e32 v164, 0xbfb8aa3b, v164
	v_exp_f32_e32 v164, v164
	v_rcp_f32_e32 v2, v3
	s_nop 0
	v_bfe_u32 v166, v2, 16, 1
	v_add_f32_e32 v3, 1.0, v164
	v_add3_u32 v2, v2, v166, s63
	ds_write_b16_d16_hi v234, v2 offset:38912
	v_add_f32_e32 v164, v150, v1
	v_mul_f32_e32 v164, 0xbfb8aa3b, v164
	v_exp_f32_e32 v164, v164
	v_rcp_f32_e32 v2, v3
	s_nop 0
	v_bfe_u32 v166, v2, 16, 1
	v_add_f32_e32 v3, 1.0, v164
	v_add3_u32 v2, v2, v166, s63
	ds_write_b16_d16_hi v234, v2 offset:39424
	v_add_f32_e32 v164, v151, v1
	v_mul_f32_e32 v164, 0xbfb8aa3b, v164
	v_exp_f32_e32 v164, v164
	v_rcp_f32_e32 v2, v3
	s_nop 0
	v_bfe_u32 v166, v2, 16, 1
	v_add_f32_e32 v3, 1.0, v164
	v_add3_u32 v2, v2, v166, s63
	ds_write_b16_d16_hi v234, v2 offset:39936
	v_add_f32_e32 v164, v132, v1
	v_mul_f32_e32 v164, 0xbfb8aa3b, v164
	v_exp_f32_e32 v164, v164
	v_rcp_f32_e32 v2, v3
	s_nop 0
	v_bfe_u32 v166, v2, 16, 1
	v_add_f32_e32 v3, 1.0, v164
	v_add3_u32 v2, v2, v166, s63
	ds_write_b16_d16_hi v234, v2 offset:40448
	v_add_f32_e32 v164, v133, v1
	v_mul_f32_e32 v164, 0xbfb8aa3b, v164
	v_exp_f32_e32 v164, v164
	v_rcp_f32_e32 v2, v3
	s_nop 0
	v_bfe_u32 v166, v2, 16, 1
	v_add_f32_e32 v3, 1.0, v164
	v_add3_u32 v2, v2, v166, s63
	ds_write_b16_d16_hi v234, v2 offset:47104
	v_add_f32_e32 v164, v134, v1
	v_mul_f32_e32 v164, 0xbfb8aa3b, v164
	v_exp_f32_e32 v164, v164
	v_rcp_f32_e32 v2, v3
	s_nop 0
	v_bfe_u32 v166, v2, 16, 1
	v_add_f32_e32 v3, 1.0, v164
	v_add3_u32 v2, v2, v166, s63
	ds_write_b16_d16_hi v234, v2 offset:47616
	v_add_f32_e32 v164, v135, v1
	v_mul_f32_e32 v164, 0xbfb8aa3b, v164
	v_exp_f32_e32 v164, v164
	v_rcp_f32_e32 v2, v3
	s_nop 0
	v_bfe_u32 v166, v2, 16, 1
	v_add_f32_e32 v3, 1.0, v164
	v_add3_u32 v2, v2, v166, s63
	ds_write_b16_d16_hi v234, v2 offset:48128
	v_add_f32_e32 v164, v116, v1
	v_mul_f32_e32 v164, 0xbfb8aa3b, v164
	v_exp_f32_e32 v164, v164
	v_rcp_f32_e32 v2, v3
	s_nop 0
	v_bfe_u32 v166, v2, 16, 1
	v_add_f32_e32 v3, 1.0, v164
	v_add3_u32 v2, v2, v166, s63
	ds_write_b16_d16_hi v234, v2 offset:48640
	v_add_f32_e32 v164, v117, v1
	v_mul_f32_e32 v164, 0xbfb8aa3b, v164
	v_exp_f32_e32 v164, v164
	v_rcp_f32_e32 v2, v3
	s_nop 0
	v_bfe_u32 v166, v2, 16, 1
	v_add_f32_e32 v3, 1.0, v164
	v_add3_u32 v2, v2, v166, s63
	ds_write_b16_d16_hi v234, v2 offset:55296
	v_add_f32_e32 v164, v118, v1
	v_mul_f32_e32 v164, 0xbfb8aa3b, v164
	v_exp_f32_e32 v164, v164
	v_rcp_f32_e32 v2, v3
	s_nop 0
	v_bfe_u32 v166, v2, 16, 1
	v_add_f32_e32 v3, 1.0, v164
	v_add3_u32 v2, v2, v166, s63
	ds_write_b16_d16_hi v234, v2 offset:55808
	v_add_f32_e32 v164, v119, v1
	v_mul_f32_e32 v164, 0xbfb8aa3b, v164
	v_exp_f32_e32 v164, v164
	v_rcp_f32_e32 v2, v3
	s_nop 0
	v_bfe_u32 v166, v2, 16, 1
	v_add_f32_e32 v3, 1.0, v164
	v_add3_u32 v2, v2, v166, s63
	ds_write_b16_d16_hi v234, v2 offset:56320
	v_add_f32_e32 v164, v104, v1
	v_mul_f32_e32 v164, 0xbfb8aa3b, v164
	v_exp_f32_e32 v164, v164
	v_rcp_f32_e32 v2, v3
	s_nop 0
	v_bfe_u32 v166, v2, 16, 1
	v_add_f32_e32 v3, 1.0, v164
	v_add3_u32 v2, v2, v166, s63
	ds_write_b16_d16_hi v234, v2 offset:56832
	v_add_f32_e32 v164, v105, v1
	v_mul_f32_e32 v164, 0xbfb8aa3b, v164
	v_exp_f32_e32 v164, v164
	v_rcp_f32_e32 v2, v3
	s_nop 0
	v_bfe_u32 v166, v2, 16, 1
	v_add_f32_e32 v3, 1.0, v164
	v_add3_u32 v2, v2, v166, s63
	ds_write_b16_d16_hi v234, v2 offset:63488
	v_add_f32_e32 v164, v106, v1
	v_mul_f32_e32 v164, 0xbfb8aa3b, v164
	v_exp_f32_e32 v164, v164
	v_rcp_f32_e32 v2, v3
	s_nop 0
	v_bfe_u32 v166, v2, 16, 1
	v_add_f32_e32 v3, 1.0, v164
	v_add3_u32 v2, v2, v166, s63
	ds_write_b16_d16_hi v234, v2 offset:64000
	v_add_f32_e32 v1, v107, v1
	v_mul_f32_e32 v1, 0xbfb8aa3b, v1
	v_exp_f32_e32 v1, v1
	v_rcp_f32_e32 v2, v3
	s_nop 0
	v_bfe_u32 v3, v2, 16, 1
	v_add3_u32 v2, v2, v3, s63
	v_add_f32_e32 v3, 1.0, v1
	ds_write_b16_d16_hi v234, v2 offset:64512
	v_mov_b32_e32 v1, v0
	v_mov_b32_e32 v2, v0
	v_rcp_f32_e32 v3, v3
	s_nop 0
	v_bfe_u32 v164, v3, 16, 1
	v_add3_u32 v3, v3, v164, s63
	ds_write_b16_d16_hi v234, v3 offset:65024
	s_mov_b64 s[12:13], -1

; template <int DH, int MODE>
; __device__ void attn_item(const Params& p, int layer, int b, int blk, int head, char* smem) {
;     ...
;   {
;     constexpr int OST = DH + 4;
;     constexpr int CPR = DH / 8;
;     constexpr int NCH = 128 * CPR / 256;
;     float* Of = reinterpret_cast<float*>(smem);
;     uint4 gt[NCH];
; #pragma unroll
;     for (int i = 0; i < NCH; ++i) {
;       int q = tid + 256 * i, r = q / CPR, c = (q % CPR) * 8;
;       gt[i] = *reinterpret_cast<const uint4*>(P + (tq0 + r) * NP + gcol + c);
;     }
;     float lis[2][4];
; #pragma unroll
;     for (int m = 0; m < 2; ++m)
; #pragma unroll
;       for (int j = 0; j < 4; ++j) lis[m][j] = (MODE == 0) ? linv_s[wid * 32 + m * 16 + fq * 4 + j] : 1.f;
;     if (MODE == 0) __syncthreads();
; #pragma unroll
;     for (int m = 0; m < 2; ++m)
; #pragma unroll
;       for (int j = 0; j < 4; ++j) {
;         int r = wid * 32 + m * 16 + fq * 4 + j;
; #pragma unroll
;         for (int n = 0; n < NDT; ++n) Of[r * OST + n * 16 + fr] = o[m][n][j] * lis[m][j];
;       }
.LBB0_791:
	s_ashr_i32 s13, s86, 31
	s_add_u32 s12, s28, s86
	s_addc_u32 s13, s29, s13
	s_lshl_b32 s14, s83, 1
	s_add_u32 s16, s48, s14
	s_addc_u32 s17, s49, 0
	v_lshl_add_u64 v[2:3], s[20:21], 0, v[134:135]
	v_mov_b64_e32 v[4:5], s[16:17]
	v_mad_u64_u32 v[0:1], s[16:17], v2, s45, v[4:5]
	v_mad_i32_i24 v1, v3, s45, v1
	s_waitcnt vmcnt(12)
	v_lshl_add_u64 v[76:77], v[0:1], 0, v[138:139]
	v_add_u32_e32 v0, 0x100, v161
	v_ashrrev_i32_e32 v1, 31, v0
	v_lshrrev_b32_e32 v1, 28, v1
	v_add_u32_e32 v1, v0, v1
	v_ashrrev_i32_e32 v8, 4, v1
	v_and_b32_e32 v1, -16, v1
	s_waitcnt vmcnt(5)
	v_sub_u32_e32 v99, v0, v1
	v_lshlrev_b32_e32 v0, 3, v99
	v_ashrrev_i32_e32 v1, 31, v0
	s_waitcnt vmcnt(3)
	v_lshlrev_b64 v[92:93], 1, v[0:1]
	v_add_u32_e32 v0, 0x200, v161
	v_ashrrev_i32_e32 v1, 31, v0
	v_lshrrev_b32_e32 v1, 28, v1
	v_add_u32_e32 v1, v0, v1
	v_ashrrev_i32_e32 v9, 31, v8
	v_ashrrev_i32_e32 v94, 4, v1
	v_and_b32_e32 v1, -16, v1
	v_lshl_add_u64 v[10:11], s[20:21], 0, v[8:9]
	v_sub_u32_e32 v9, v0, v1
	v_lshlrev_b32_e32 v0, 3, v9
	v_ashrrev_i32_e32 v1, 31, v0
	v_lshlrev_b64 v[100:101], 1, v[0:1]
	v_add_u32_e32 v0, 0x300, v161
	v_ashrrev_i32_e32 v1, 31, v0
	v_lshrrev_b32_e32 v1, 28, v1
	v_add_u32_e32 v1, v0, v1
	v_ashrrev_i32_e32 v102, 4, v1
	v_and_b32_e32 v1, -16, v1
	v_sub_u32_e32 v128, v0, v1
	v_lshlrev_b32_e32 v0, 3, v128
	v_ashrrev_i32_e32 v1, 31, v0
	s_waitcnt vmcnt(0)
	v_lshlrev_b64 v[106:107], 1, v[0:1]
	v_add_u32_e32 v0, 0x400, v161
	v_ashrrev_i32_e32 v1, 31, v0
	v_lshrrev_b32_e32 v1, 28, v1
	v_add_u32_e32 v1, v0, v1
	v_ashrrev_i32_e32 v103, 31, v102
	v_ashrrev_i32_e32 v108, 4, v1
	v_and_b32_e32 v1, -16, v1
	v_lshl_add_u64 v[104:105], s[20:21], 0, v[102:103]
	v_sub_u32_e32 v103, v0, v1
	v_lshlrev_b32_e32 v0, 3, v103
	v_ashrrev_i32_e32 v1, 31, v0
	v_lshlrev_b64 v[112:113], 1, v[0:1]
	v_add_u32_e32 v0, 0x500, v161
	v_ashrrev_i32_e32 v1, 31, v0
	v_lshrrev_b32_e32 v1, 28, v1
	v_add_u32_e32 v1, v0, v1
	v_ashrrev_i32_e32 v109, 31, v108
	v_ashrrev_i32_e32 v114, 4, v1
	v_and_b32_e32 v1, -16, v1
	v_mad_u64_u32 v[6:7], s[16:17], v10, s45, v[4:5]
	v_ashrrev_i32_e32 v95, 31, v94
	v_lshl_add_u64 v[110:111], s[20:21], 0, v[108:109]
	v_sub_u32_e32 v109, v0, v1
	v_mad_i32_i24 v7, v11, s45, v7
	v_lshl_add_u64 v[96:97], s[20:21], 0, v[94:95]
	v_lshlrev_b32_e32 v0, 3, v109
	v_lshl_add_u64 v[78:79], v[6:7], 0, v[92:93]
	v_mad_u64_u32 v[6:7], s[16:17], v96, s45, v[4:5]
	v_ashrrev_i32_e32 v1, 31, v0
	v_mad_i32_i24 v7, v97, s45, v7
	v_lshlrev_b64 v[118:119], 1, v[0:1]
	v_add_u32_e32 v0, 0x600, v161
	v_lshl_add_u64 v[80:81], v[6:7], 0, v[100:101]
	v_mad_u64_u32 v[6:7], s[16:17], v104, s45, v[4:5]
	v_ashrrev_i32_e32 v1, 31, v0
	v_mad_i32_i24 v7, v105, s45, v7
	v_lshrrev_b32_e32 v1, 28, v1
	v_lshl_add_u64 v[82:83], v[6:7], 0, v[106:107]
	v_mad_u64_u32 v[6:7], s[16:17], v110, s45, v[4:5]
	v_ashrrev_i32_e32 v115, 31, v114
	v_add_u32_e32 v1, v0, v1
	v_mad_i32_i24 v7, v111, s45, v7
	v_lshl_add_u64 v[116:117], s[20:21], 0, v[114:115]
	v_ashrrev_i32_e32 v120, 4, v1
	v_and_b32_e32 v1, -16, v1
	v_lshl_add_u64 v[84:85], v[6:7], 0, v[112:113]
	v_mad_u64_u32 v[6:7], s[16:17], v116, s45, v[4:5]
	v_sub_u32_e32 v115, v0, v1
	v_ashrrev_i32_e32 v121, 31, v120
	v_mad_i32_i24 v7, v117, s45, v7
	v_lshlrev_b32_e32 v0, 3, v115
	v_lshl_add_u64 v[122:123], s[20:21], 0, v[120:121]
	v_lshl_add_u64 v[86:87], v[6:7], 0, v[118:119]
	v_mad_u64_u32 v[6:7], s[16:17], v122, s45, v[4:5]
	v_ashrrev_i32_e32 v1, 31, v0
	v_mad_i32_i24 v7, v123, s45, v7
	v_lshlrev_b64 v[124:125], 1, v[0:1]
	v_lshl_add_u64 v[0:1], v[6:7], 0, v[124:125]
	v_add_u32_e32 v6, 0x700, v161
	v_ashrrev_i32_e32 v7, 31, v6
	v_lshrrev_b32_e32 v7, 28, v7
	v_add_u32_e32 v7, v6, v7
	v_ashrrev_i32_e32 v126, 4, v7
	v_and_b32_e32 v7, -16, v7
	v_sub_u32_e32 v121, v6, v7
	v_lshlrev_b32_e32 v6, 3, v121
	v_ashrrev_i32_e32 v127, 31, v126
	v_lshl_add_u64 v[88:89], s[20:21], 0, v[126:127]
	v_ashrrev_i32_e32 v7, 31, v6
	v_mad_u64_u32 v[4:5], s[16:17], v88, s45, v[4:5]
	v_lshlrev_b64 v[90:91], 1, v[6:7]
	v_lshl_or_b32 v6, v137, 2, v130
	v_mad_i32_i24 v5, v89, s45, v5
	v_mul_lo_u32 v6, v6, s69
	v_lshl_add_u64 v[4:5], v[4:5], 0, v[90:91]
	v_lshl_add_u32 v95, v162, 2, v6
	s_barrier
	ds_write2_b32 v95, v12, v48 offset1:16
	ds_write2_b32 v95, v52, v56 offset0:32 offset1:48
	ds_write2_b32 v95, v60, v64 offset0:64 offset1:80
	ds_write2_b32 v95, v68, v72 offset0:96 offset1:112
	ds_write2_b32 v95, v13, v49 offset0:132 offset1:148
	ds_write2_b32 v95, v53, v57 offset0:164 offset1:180
	ds_write2_b32 v95, v61, v65 offset0:196 offset1:212
	ds_write2_b32 v95, v69, v73 offset0:228 offset1:244
	v_add_u32_e32 v12, 0x400, v95
	v_add_co_u32_e32 v4, vcc, s80, v4
	ds_write2_b32 v12, v14, v50 offset0:8 offset1:24
	ds_write2_b32 v12, v54, v58 offset0:40 offset1:56
	v_addc_co_u32_e32 v5, vcc, 0, v5, vcc
	global_load_dwordx4 v[4:7], v[4:5], off offset:512
	ds_write2_b32 v12, v62, v66 offset0:72 offset1:88
	ds_write2_b32 v12, v70, v74 offset0:104 offset1:120
	ds_write2_b32 v12, v15, v51 offset0:140 offset1:156
	ds_write2_b32 v12, v55, v59 offset0:172 offset1:188
	ds_write2_b32 v12, v63, v67 offset0:204 offset1:220
	ds_write2_b32 v12, v71, v75 offset0:236 offset1:252
	v_add_u32_e32 v12, 0x2000, v95
	ds_write2_b32 v12, v16, v20 offset0:64 offset1:80
	ds_write2_b32 v12, v24, v36 offset0:96 offset1:112
	ds_write2_b32 v12, v28, v40 offset0:128 offset1:144
	ds_write2_b32 v12, v44, v32 offset0:160 offset1:176
	ds_write2_b32 v12, v17, v21 offset0:196 offset1:212
	ds_write2_b32 v12, v25, v37 offset0:228 offset1:244
	v_add_u32_e32 v12, 0x2400, v95
	s_add_u32 s12, s12, s14
	ds_write2_b32 v12, v29, v41 offset0:4 offset1:20
	ds_write2_b32 v12, v45, v33 offset0:36 offset1:52
; __device__ __forceinline__ unsigned pack2(float a, float b) { return (unsigned)f2bf(a) | ((unsigned)f2bf(b) << 16); }
; __device__ __forceinline__ float bflo(unsigned w) { return __uint_as_float(w << 16); }
; __device__ __forceinline__ float bfhi(unsigned w) { return __uint_as_float(w & 0xffff0000u); }
; __device__ __forceinline__ float silu_f(float g) { return g / (1.f + __expf(-g)); }
; template <int DH, int MODE>
; __device__ void attn_item(const Params& p, int layer, int b, int blk, int head, char* smem) {
;     ...
; #pragma unroll
;     for (int m = 0; m < 2; ++m)
; #pragma unroll
;       for (int j = 0; j < 4; ++j) {
;         int r = wid * 32 + m * 16 + fq * 4 + j;
; #pragma unroll
;         for (int n = 0; n < NDT; ++n) Of[r * OST + n * 16 + fr] = o[m][n][j] * lis[m][j];
;       }
;     __syncthreads();
; #pragma unroll
;     for (int i = 0; i < NCH; ++i) {
;       int q = tid + 256 * i, r = q / CPR, c = (q % CPR) * 8;
;       float4 m0 = *reinterpret_cast<const float4*>(Of + r * OST + c);
;       float4 m1 = *reinterpret_cast<const float4*>(Of + r * OST + c + 4);
;       float mm[8] = {m0.x, m0.y, m0.z, m0.w, m1.x, m1.y, m1.z, m1.w};
;       unsigned gw[4] = {gt[i].x, gt[i].y, gt[i].z, gt[i].w};
;       unsigned ow[4];
; #pragma unroll
;       for (int e = 0; e < 4; ++e)
;         ow[e] = pack2(mm[2 * e] * silu_f(bflo(gw[e])), mm[2 * e + 1] * silu_f(bfhi(gw[e])));
	ds_write2_b32 v12, v18, v22 offset0:72 offset1:88
	ds_write2_b32 v12, v26, v38 offset0:104 offset1:120
	ds_write2_b32 v12, v30, v42 offset0:136 offset1:152
	ds_write2_b32 v12, v46, v34 offset0:168 offset1:184
	ds_write2_b32 v12, v19, v23 offset0:204 offset1:220
	ds_write2_b32 v12, v27, v39 offset0:236 offset1:252
	v_add_u32_e32 v12, 0x2800, v95
	s_addc_u32 s13, s13, 0
	ds_write2_b32 v12, v31, v43 offset0:12 offset1:28
	ds_write2_b32 v12, v47, v35 offset0:44 offset1:60
	v_mul_lo_u32 v12, v134, s69
	v_mov_b64_e32 v[14:15], s[12:13]
	v_lshl_add_u32 v98, v136, 2, v12
	v_mad_u64_u32 v[12:13], s[12:13], v2, s70, v[14:15]
	v_mul_lo_u32 v2, v8, s69
	v_mad_i32_i24 v13, v3, s70, v13
	v_lshl_add_u32 v95, v99, 5, v2
	v_mad_u64_u32 v[2:3], s[12:13], v10, s70, v[14:15]
	v_mad_i32_i24 v3, v11, s70, v3
	v_lshl_add_u64 v[26:27], v[2:3], 0, v[92:93]
	v_mul_lo_u32 v2, v94, s69
	v_lshl_add_u32 v93, v9, 5, v2
	v_mad_u64_u32 v[2:3], s[12:13], v96, s70, v[14:15]
	v_mad_i32_i24 v3, v97, s70, v3
	v_lshl_add_u64 v[20:21], v[2:3], 0, v[100:101]
	v_mul_lo_u32 v2, v102, s69
	v_lshl_add_u32 v92, v128, 5, v2
	v_mad_u64_u32 v[2:3], s[12:13], v104, s70, v[14:15]
	v_mad_i32_i24 v3, v105, s70, v3
	v_lshl_add_u64 v[16:17], v[2:3], 0, v[106:107]
	v_mul_lo_u32 v2, v108, s69
	v_lshl_add_u32 v75, v103, 5, v2
	v_mad_u64_u32 v[2:3], s[12:13], v110, s70, v[14:15]
	v_mad_i32_i24 v3, v111, s70, v3
	v_lshl_add_u64 v[30:31], v[12:13], 0, v[138:139]
	v_lshl_add_u64 v[12:13], v[2:3], 0, v[112:113]
	v_mul_lo_u32 v2, v114, s69
	v_lshl_add_u32 v74, v109, 5, v2
	v_mad_u64_u32 v[2:3], s[12:13], v116, s70, v[14:15]
	v_mad_i32_i24 v3, v117, s70, v3
	v_lshl_add_u64 v[10:11], v[2:3], 0, v[118:119]
	v_mul_lo_u32 v2, v120, s69
	v_lshl_add_u32 v73, v115, 5, v2
	v_mad_u64_u32 v[2:3], s[12:13], v122, s70, v[14:15]
	v_mad_i32_i24 v3, v123, s70, v3
	v_add_co_u32_e32 v0, vcc, s80, v0
	v_lshl_add_u64 v[8:9], v[2:3], 0, v[124:125]
	v_mul_lo_u32 v2, v126, s69
	v_addc_co_u32_e32 v1, vcc, 0, v1, vcc
	v_lshl_add_u32 v72, v121, 5, v2
	global_load_dwordx4 v[0:3], v[0:1], off offset:512
	v_mad_u64_u32 v[14:15], s[12:13], v88, s70, v[14:15]
	v_mad_i32_i24 v15, v89, s70, v15
	v_lshl_add_u64 v[14:15], v[14:15], 0, v[90:91]
	s_waitcnt vmcnt(1)
	v_lshlrev_b32_e32 v22, 16, v5
	v_lshlrev_b32_e32 v23, 16, v4
	v_mul_f32_e32 v18, 0xbfb8aa3b, v23
	v_mul_f32_e32 v19, 0xbfb8aa3b, v22
	v_exp_f32_e32 v18, v18
	v_exp_f32_e32 v19, v19
	v_and_b32_e32 v24, 0xffff0000, v5
	v_and_b32_e32 v28, 0xffff0000, v4
	v_mul_f32_e32 v4, 0xbfb8aa3b, v28
	v_pk_add_f32 v[18:19], v[18:19], 1.0 op_sel_hi:[1,0]
	v_exp_f32_e32 v4, v4
	v_and_b32_e32 v34, 0xffff0000, v6
	v_rcp_f32_e32 v19, v19
	s_nop 0
	v_mul_f32_e32 v19, v22, v19
	v_mul_f32_e32 v5, 0xbfb8aa3b, v24
	v_exp_f32_e32 v5, v5
	s_nop 0
	v_pk_add_f32 v[4:5], v[4:5], 1.0 op_sel_hi:[1,0]
	v_rcp_f32_e32 v18, v18
	s_nop 0
	v_mul_f32_e32 v18, v23, v18
	v_lshlrev_b32_e32 v33, 16, v6
	v_rcp_f32_e32 v23, v5
	s_nop 0
	v_mul_f32_e32 v23, v24, v23
	v_lshlrev_b32_e32 v32, 16, v7
	v_mul_f32_e32 v24, 0xbfb8aa3b, v33
	v_mul_f32_e32 v25, 0xbfb8aa3b, v32
	v_exp_f32_e32 v24, v24
	v_exp_f32_e32 v25, v25
	v_rcp_f32_e32 v22, v4
	s_nop 0
	v_mul_f32_e32 v22, v28, v22
	v_and_b32_e32 v28, 0xffff0000, v7
	v_pk_add_f32 v[4:5], v[24:25], 1.0 op_sel_hi:[1,0]
	v_mul_f32_e32 v6, 0xbfb8aa3b, v34
	v_exp_f32_e32 v6, v6
	s_waitcnt vmcnt(0)
	v_lshlrev_b32_e32 v40, 16, v3
	v_lshlrev_b32_e32 v41, 16, v2
	v_rcp_f32_e32 v25, v5
	s_nop 0
	v_mul_f32_e32 v25, v32, v25
	v_mul_f32_e32 v7, 0xbfb8aa3b, v28
	v_exp_f32_e32 v7, v7
	s_nop 0
	v_pk_add_f32 v[6:7], v[6:7], 1.0 op_sel_hi:[1,0]
	v_rcp_f32_e32 v24, v4
	s_nop 0
	v_mul_f32_e32 v24, v33, v24
	v_rcp_f32_e32 v29, v7
	s_nop 0
	v_mul_f32_e32 v29, v28, v29
	v_lshlrev_b32_e32 v32, 16, v1
	v_lshlrev_b32_e32 v36, 16, v0
	v_mul_f32_e32 v4, 0xbfb8aa3b, v36
	v_mul_f32_e32 v5, 0xbfb8aa3b, v32
	v_exp_f32_e32 v4, v4
	v_exp_f32_e32 v5, v5
	v_rcp_f32_e32 v28, v6
	s_nop 0
	v_mul_f32_e32 v28, v34, v28
	v_and_b32_e32 v6, 0xffff0000, v1
	v_pk_add_f32 v[4:5], v[4:5], 1.0 op_sel_hi:[1,0]
	v_and_b32_e32 v34, 0xffff0000, v0
	v_mul_f32_e32 v0, 0xbfb8aa3b, v34
	v_exp_f32_e32 v0, v0
	v_and_b32_e32 v42, 0xffff0000, v3
	v_rcp_f32_e32 v33, v5
	s_nop 0
	v_mul_f32_e32 v33, v32, v33
	v_mul_f32_e32 v1, 0xbfb8aa3b, v6
	v_exp_f32_e32 v1, v1
	s_nop 0
	v_pk_add_f32 v[0:1], v[0:1], 1.0 op_sel_hi:[1,0]
	v_rcp_f32_e32 v32, v4
	s_nop 0
	v_mul_f32_e32 v32, v36, v32
	v_rcp_f32_e32 v35, v1
	s_nop 0
	v_mul_f32_e32 v35, v6, v35
	v_add_co_u32_e64 v4, s[12:13], s80, v86
	s_nop 0
	s_nop 0
	v_addc_co_u32_e64 v5, s[12:13], 0, v87, s[12:13]
	global_load_dwordx4 v[4:7], v[4:5], off offset:512
	v_mul_f32_e32 v36, 0xbfb8aa3b, v41
	v_mul_f32_e32 v37, 0xbfb8aa3b, v40
	v_exp_f32_e32 v36, v36
	v_exp_f32_e32 v37, v37
	v_rcp_f32_e32 v1, v0
	s_nop 0
	v_mul_f32_e32 v34, v34, v1
	v_and_b32_e32 v43, 0xffff0000, v2
	v_pk_add_f32 v[0:1], v[36:37], 1.0 op_sel_hi:[1,0]
	v_mul_f32_e32 v2, 0xbfb8aa3b, v43
	v_exp_f32_e32 v2, v2
	v_rcp_f32_e32 v37, v1
	s_nop 0
	v_mul_f32_e32 v37, v40, v37
	v_mul_f32_e32 v3, 0xbfb8aa3b, v42
	v_exp_f32_e32 v3, v3
	s_nop 0
	v_pk_add_f32 v[38:39], v[2:3], 1.0 op_sel_hi:[1,0]
	v_rcp_f32_e32 v36, v0
	s_nop 0
	v_mul_f32_e32 v36, v41, v36
	v_rcp_f32_e32 v39, v39
	s_nop 0
	v_mul_f32_e32 v39, v42, v39
	v_add_co_u32_e64 v0, s[12:13], s80, v84
	s_waitcnt vmcnt(0)
; __device__ __forceinline__ unsigned pack2(float a, float b) { return (unsigned)f2bf(a) | ((unsigned)f2bf(b) << 16); }
; __device__ __forceinline__ float bflo(unsigned w) { return __uint_as_float(w << 16); }
; __device__ __forceinline__ float bfhi(unsigned w) { return __uint_as_float(w & 0xffff0000u); }
; __device__ __forceinline__ float silu_f(float g) { return g / (1.f + __expf(-g)); }
; template <int DH, int MODE>
; __device__ void attn_item(const Params& p, int layer, int b, int blk, int head, char* smem) {
;     ...
; #pragma unroll
;     for (int i = 0; i < NCH; ++i) {
;       int q = tid + 256 * i, r = q / CPR, c = (q % CPR) * 8;
;       float4 m0 = *reinterpret_cast<const float4*>(Of + r * OST + c);
;       float4 m1 = *reinterpret_cast<const float4*>(Of + r * OST + c + 4);
;       float mm[8] = {m0.x, m0.y, m0.z, m0.w, m1.x, m1.y, m1.z, m1.w};
;       unsigned gw[4] = {gt[i].x, gt[i].y, gt[i].z, gt[i].w};
;       unsigned ow[4];
; #pragma unroll
;       for (int e = 0; e < 4; ++e)
;         ow[e] = pack2(mm[2 * e] * silu_f(bflo(gw[e])), mm[2 * e + 1] * silu_f(bfhi(gw[e])));
	v_lshlrev_b32_e32 v46, 16, v5
	v_lshlrev_b32_e32 v47, 16, v4
	v_mul_f32_e32 v40, 0xbfb8aa3b, v47
	v_mul_f32_e32 v41, 0xbfb8aa3b, v46
	v_exp_f32_e32 v40, v40
	v_exp_f32_e32 v41, v41
	v_addc_co_u32_e64 v1, s[12:13], 0, v85, s[12:13]
	v_rcp_f32_e32 v38, v38
	s_nop 0
	v_mul_f32_e32 v38, v43, v38
	v_pk_add_f32 v[40:41], v[40:41], 1.0 op_sel_hi:[1,0]
	v_and_b32_e32 v42, 0xffff0000, v5
	global_load_dwordx4 v[0:3], v[0:1], off offset:512
	v_and_b32_e32 v48, 0xffff0000, v4
	v_mul_f32_e32 v4, 0xbfb8aa3b, v48
	v_rcp_f32_e32 v41, v41
	s_nop 0
	v_mul_f32_e32 v41, v46, v41
	v_exp_f32_e32 v4, v4
	v_mul_f32_e32 v5, 0xbfb8aa3b, v42
	v_exp_f32_e32 v5, v5
	s_nop 0
	v_pk_add_f32 v[4:5], v[4:5], 1.0 op_sel_hi:[1,0]
	v_rcp_f32_e32 v40, v40
	s_nop 0
	v_mul_f32_e32 v40, v47, v40
	v_lshlrev_b32_e32 v49, 16, v6
	v_rcp_f32_e32 v43, v5
	s_nop 0
	v_mul_f32_e32 v43, v42, v43
	v_lshlrev_b32_e32 v46, 16, v7
	v_mul_f32_e32 v44, 0xbfb8aa3b, v49
	v_mul_f32_e32 v45, 0xbfb8aa3b, v46
	v_exp_f32_e32 v44, v44
	v_exp_f32_e32 v45, v45
	v_rcp_f32_e32 v42, v4
	s_nop 0
	v_mul_f32_e32 v42, v48, v42
	v_and_b32_e32 v47, 0xffff0000, v7
	v_pk_add_f32 v[4:5], v[44:45], 1.0 op_sel_hi:[1,0]
	v_and_b32_e32 v48, 0xffff0000, v6
	v_mul_f32_e32 v6, 0xbfb8aa3b, v48
	v_exp_f32_e32 v6, v6
	v_rcp_f32_e32 v45, v5
	s_nop 0
	v_mul_f32_e32 v45, v46, v45
	v_mul_f32_e32 v7, 0xbfb8aa3b, v47
	v_exp_f32_e32 v7, v7
	s_nop 0
	v_pk_add_f32 v[6:7], v[6:7], 1.0 op_sel_hi:[1,0]
	v_rcp_f32_e32 v44, v4
	s_nop 0
	v_mul_f32_e32 v44, v49, v44
	v_rcp_f32_e32 v4, v7
	s_nop 0
	v_mul_f32_e32 v47, v47, v4
	s_waitcnt vmcnt(0)
	v_lshlrev_b32_e32 v50, 16, v1
	v_lshlrev_b32_e32 v51, 16, v0
	v_mul_f32_e32 v4, 0xbfb8aa3b, v51
	v_mul_f32_e32 v5, 0xbfb8aa3b, v50
	v_exp_f32_e32 v4, v4
	v_exp_f32_e32 v5, v5
	v_rcp_f32_e32 v46, v6
	s_nop 0
	v_mul_f32_e32 v46, v48, v46
	v_and_b32_e32 v6, 0xffff0000, v1
	v_pk_add_f32 v[4:5], v[4:5], 1.0 op_sel_hi:[1,0]
	v_and_b32_e32 v54, 0xffff0000, v0
	v_mul_f32_e32 v0, 0xbfb8aa3b, v54
	v_exp_f32_e32 v0, v0
	v_lshlrev_b32_e32 v58, 16, v2
	v_rcp_f32_e32 v49, v5
	s_nop 0
	v_mul_f32_e32 v49, v50, v49
	v_mul_f32_e32 v1, 0xbfb8aa3b, v6
	v_exp_f32_e32 v1, v1
	s_nop 0
	v_pk_add_f32 v[0:1], v[0:1], 1.0 op_sel_hi:[1,0]
	v_rcp_f32_e32 v48, v4
	s_nop 0
	v_mul_f32_e32 v48, v51, v48
	v_lshlrev_b32_e32 v57, 16, v3
	v_rcp_f32_e32 v51, v1
	s_nop 0
	v_mul_f32_e32 v51, v6, v51
	v_add_co_u32_e64 v4, s[12:13], s80, v82
	s_nop 0
	s_nop 0
	v_addc_co_u32_e64 v5, s[12:13], 0, v83, s[12:13]
	global_load_dwordx4 v[4:7], v[4:5], off offset:512
	v_mul_f32_e32 v50, 0xbfb8aa3b, v58
	v_exp_f32_e32 v52, v50
	v_mul_f32_e32 v50, 0xbfb8aa3b, v57
	v_exp_f32_e32 v53, v50
	v_rcp_f32_e32 v50, v0
	s_nop 0
	v_mul_f32_e32 v50, v54, v50
	v_and_b32_e32 v56, 0xffff0000, v3
	v_pk_add_f32 v[0:1], v[52:53], 1.0 op_sel_hi:[1,0]
	v_and_b32_e32 v59, 0xffff0000, v2
	v_mul_f32_e32 v2, 0xbfb8aa3b, v59
	v_exp_f32_e32 v2, v2
	v_rcp_f32_e32 v53, v1
	s_nop 0
	v_mul_f32_e32 v53, v57, v53
	v_mul_f32_e32 v3, 0xbfb8aa3b, v56
	v_exp_f32_e32 v3, v3
	s_nop 0
	v_pk_add_f32 v[54:55], v[2:3], 1.0 op_sel_hi:[1,0]
	v_rcp_f32_e32 v52, v0
	s_nop 0
	v_mul_f32_e32 v52, v58, v52
	v_rcp_f32_e32 v55, v55
	s_nop 0
	v_mul_f32_e32 v55, v56, v55
	v_add_co_u32_e64 v0, s[12:13], s80, v80
	s_waitcnt vmcnt(0)
	v_lshlrev_b32_e32 v62, 16, v5
	v_lshlrev_b32_e32 v63, 16, v4
	v_mul_f32_e32 v56, 0xbfb8aa3b, v63
	v_mul_f32_e32 v57, 0xbfb8aa3b, v62
	v_exp_f32_e32 v56, v56
	v_exp_f32_e32 v57, v57
	v_addc_co_u32_e64 v1, s[12:13], 0, v81, s[12:13]
	v_rcp_f32_e32 v54, v54
	s_nop 0
	v_mul_f32_e32 v54, v59, v54
	v_pk_add_f32 v[56:57], v[56:57], 1.0 op_sel_hi:[1,0]
	v_and_b32_e32 v58, 0xffff0000, v5
	global_load_dwordx4 v[0:3], v[0:1], off offset:512
	v_and_b32_e32 v64, 0xffff0000, v4
	v_mul_f32_e32 v4, 0xbfb8aa3b, v64
	v_rcp_f32_e32 v57, v57
	s_nop 0
	v_mul_f32_e32 v57, v62, v57
	v_exp_f32_e32 v4, v4
	v_mul_f32_e32 v5, 0xbfb8aa3b, v58
	v_exp_f32_e32 v5, v5
	s_nop 0
	v_pk_add_f32 v[4:5], v[4:5], 1.0 op_sel_hi:[1,0]
	v_rcp_f32_e32 v56, v56
	s_nop 0
	v_mul_f32_e32 v56, v63, v56
	v_lshlrev_b32_e32 v65, 16, v6
	v_rcp_f32_e32 v59, v5
	s_nop 0
	v_mul_f32_e32 v59, v58, v59
	v_lshlrev_b32_e32 v62, 16, v7
	v_mul_f32_e32 v60, 0xbfb8aa3b, v65
	v_mul_f32_e32 v61, 0xbfb8aa3b, v62
	v_exp_f32_e32 v60, v60
	v_exp_f32_e32 v61, v61
	v_rcp_f32_e32 v58, v4
	s_nop 0
	v_mul_f32_e32 v58, v64, v58
	v_and_b32_e32 v63, 0xffff0000, v7
	v_pk_add_f32 v[4:5], v[60:61], 1.0 op_sel_hi:[1,0]
	v_and_b32_e32 v64, 0xffff0000, v6
	v_mul_f32_e32 v6, 0xbfb8aa3b, v64
	v_exp_f32_e32 v6, v6
	v_rcp_f32_e32 v61, v5
	s_nop 0
	v_mul_f32_e32 v61, v62, v61
	v_mul_f32_e32 v7, 0xbfb8aa3b, v63
	v_exp_f32_e32 v7, v7
	s_nop 0
	v_pk_add_f32 v[6:7], v[6:7], 1.0 op_sel_hi:[1,0]
	v_rcp_f32_e32 v60, v4
	s_nop 0
	v_mul_f32_e32 v60, v65, v60
	v_rcp_f32_e32 v4, v7
	s_nop 0
	v_mul_f32_e32 v63, v63, v4
	s_waitcnt vmcnt(0)
	v_lshlrev_b32_e32 v66, 16, v1
	v_lshlrev_b32_e32 v67, 16, v0
	v_mul_f32_e32 v4, 0xbfb8aa3b, v67
	v_mul_f32_e32 v5, 0xbfb8aa3b, v66
	v_exp_f32_e32 v4, v4
	v_exp_f32_e32 v5, v5
	v_and_b32_e32 v68, 0xffff0000, v1
	v_rcp_f32_e32 v62, v6
	s_nop 0
	v_mul_f32_e32 v62, v64, v62
	v_pk_add_f32 v[4:5], v[4:5], 1.0 op_sel_hi:[1,0]
	v_and_b32_e32 v69, 0xffff0000, v0
	v_mul_f32_e32 v0, 0xbfb8aa3b, v69
	v_exp_f32_e32 v6, v0
	v_and_b32_e32 v80, 0xffff0000, v2
	v_rcp_f32_e32 v1, v5
	s_nop 0
	v_mul_f32_e32 v1, v66, v1
	v_mul_f32_e32 v7, 0xbfb8aa3b, v68
	v_exp_f32_e32 v7, v7
	s_nop 0
	v_pk_add_f32 v[64:65], v[6:7], 1.0 op_sel_hi:[1,0]
	v_rcp_f32_e32 v0, v4
	s_nop 0
	v_mul_f32_e32 v0, v67, v0
	v_rcp_f32_e32 v65, v65
	s_nop 0
	v_mul_f32_e32 v65, v68, v65
	v_add_co_u32_e64 v4, s[12:13], s80, v78
	s_nop 0
	s_nop 0
	v_addc_co_u32_e64 v5, s[12:13], 0, v79, s[12:13]
	global_load_dwordx4 v[4:7], v[4:5], off offset:512
	v_lshlrev_b32_e32 v78, 16, v3
	v_lshlrev_b32_e32 v79, 16, v2
	v_mul_f32_e32 v66, 0xbfb8aa3b, v79
	v_mul_f32_e32 v67, 0xbfb8aa3b, v78
	v_exp_f32_e32 v66, v66
	v_exp_f32_e32 v67, v67
	v_and_b32_e32 v70, 0xffff0000, v3
	v_rcp_f32_e32 v64, v64
	s_nop 0
	v_mul_f32_e32 v64, v69, v64
	v_pk_add_f32 v[66:67], v[66:67], 1.0 op_sel_hi:[1,0]
	v_mul_f32_e32 v2, 0xbfb8aa3b, v80
	v_exp_f32_e32 v68, v2
	v_mul_f32_e32 v69, 0xbfb8aa3b, v70
	v_exp_f32_e32 v69, v69
	v_rcp_f32_e32 v3, v67
	s_nop 0
	v_mul_f32_e32 v3, v78, v3
	v_pk_add_f32 v[68:69], v[68:69], 1.0 op_sel_hi:[1,0]
	v_rcp_f32_e32 v2, v66
	s_nop 0
	v_mul_f32_e32 v2, v79, v2
	v_rcp_f32_e32 v67, v69
	s_nop 0
	v_mul_f32_e32 v67, v70, v67
	v_add_co_u32_e64 v70, s[12:13], s80, v76
	s_nop 0
	s_nop 0
	v_addc_co_u32_e64 v71, s[12:13], 0, v77, s[12:13]
	global_load_dwordx4 v[76:79], v[70:71], off offset:512
	v_rcp_f32_e32 v66, v68
	s_nop 0
	v_mul_f32_e32 v66, v80, v66
	s_waitcnt vmcnt(1)
	v_lshlrev_b32_e32 v82, 16, v5
	v_lshlrev_b32_e32 v83, 16, v4
	v_mul_f32_e32 v70, 0xbfb8aa3b, v83
	v_mul_f32_e32 v71, 0xbfb8aa3b, v82
	v_exp_f32_e32 v70, v70
	v_exp_f32_e32 v71, v71
	v_and_b32_e32 v80, 0xffff0000, v5
	v_and_b32_e32 v84, 0xffff0000, v4
	v_mul_f32_e32 v4, 0xbfb8aa3b, v84
	v_pk_add_f32 v[68:69], v[70:71], 1.0 op_sel_hi:[1,0]
	v_exp_f32_e32 v70, v4
	s_waitcnt lgkmcnt(0)
	s_barrier
; __device__ __forceinline__ unsigned pack2(float a, float b) { return (unsigned)f2bf(a) | ((unsigned)f2bf(b) << 16); }
; __device__ __forceinline__ float bflo(unsigned w) { return __uint_as_float(w << 16); }
; __device__ __forceinline__ float bfhi(unsigned w) { return __uint_as_float(w & 0xffff0000u); }
; __device__ __forceinline__ float silu_f(float g) { return g / (1.f + __expf(-g)); }
; template <int DH, int MODE>
; __device__ void attn_item(const Params& p, int layer, int b, int blk, int head, char* smem) {
;     ...
; #pragma unroll
;     for (int i = 0; i < NCH; ++i) {
;       int q = tid + 256 * i, r = q / CPR, c = (q % CPR) * 8;
;       float4 m0 = *reinterpret_cast<const float4*>(Of + r * OST + c);
;       float4 m1 = *reinterpret_cast<const float4*>(Of + r * OST + c + 4);
;       float mm[8] = {m0.x, m0.y, m0.z, m0.w, m1.x, m1.y, m1.z, m1.w};
;       unsigned gw[4] = {gt[i].x, gt[i].y, gt[i].z, gt[i].w};
;       unsigned ow[4];
; #pragma unroll
;       for (int e = 0; e < 4; ++e)
;         ow[e] = pack2(mm[2 * e] * silu_f(bflo(gw[e])), mm[2 * e + 1] * silu_f(bfhi(gw[e])));
;       *reinterpret_cast<uint4*>(Y + (tq0 + r) * YW + ycol + c) = make_uint4(ow[0], ow[1], ow[2], ow[3]);
	v_mul_f32_e32 v71, 0xbfb8aa3b, v80
	v_exp_f32_e32 v71, v71
	v_rcp_f32_e32 v5, v69
	s_nop 0
	v_mul_f32_e32 v5, v82, v5
	v_pk_add_f32 v[70:71], v[70:71], 1.0 op_sel_hi:[1,0]
	v_rcp_f32_e32 v4, v68
	s_nop 0
	v_mul_f32_e32 v4, v83, v4
	v_rcp_f32_e32 v69, v71
	s_nop 0
	v_mul_f32_e32 v69, v80, v69
	v_lshlrev_b32_e32 v82, 16, v7
	v_lshlrev_b32_e32 v85, 16, v6
	v_mul_f32_e32 v80, 0xbfb8aa3b, v85
	v_mul_f32_e32 v81, 0xbfb8aa3b, v82
	v_exp_f32_e32 v80, v80
	v_exp_f32_e32 v81, v81
	v_rcp_f32_e32 v68, v70
	s_nop 0
	v_mul_f32_e32 v68, v84, v68
	v_and_b32_e32 v83, 0xffff0000, v7
	v_pk_add_f32 v[70:71], v[80:81], 1.0 op_sel_hi:[1,0]
	v_and_b32_e32 v84, 0xffff0000, v6
	v_mul_f32_e32 v6, 0xbfb8aa3b, v84
	v_exp_f32_e32 v80, v6
	s_waitcnt vmcnt(0)
	v_and_b32_e32 v94, 0xffff0000, v78
	v_mul_f32_e32 v81, 0xbfb8aa3b, v83
	v_exp_f32_e32 v81, v81
	v_rcp_f32_e32 v7, v71
	s_nop 0
	v_mul_f32_e32 v7, v82, v7
	v_pk_add_f32 v[80:81], v[80:81], 1.0 op_sel_hi:[1,0]
	v_rcp_f32_e32 v6, v70
	s_nop 0
	v_mul_f32_e32 v6, v85, v6
	v_rcp_f32_e32 v71, v81
	s_nop 0
	v_mul_f32_e32 v71, v83, v71
	v_lshlrev_b32_e32 v86, 16, v77
	v_lshlrev_b32_e32 v87, 16, v76
	v_mul_f32_e32 v82, 0xbfb8aa3b, v87
	v_mul_f32_e32 v83, 0xbfb8aa3b, v86
	v_exp_f32_e32 v82, v82
	v_exp_f32_e32 v83, v83
	v_rcp_f32_e32 v70, v80
	s_nop 0
	v_mul_f32_e32 v70, v84, v70
	v_and_b32_e32 v88, 0xffff0000, v77
	v_pk_add_f32 v[80:81], v[82:83], 1.0 op_sel_hi:[1,0]
	v_and_b32_e32 v83, 0xffff0000, v76
	v_mul_f32_e32 v76, 0xbfb8aa3b, v83
	v_exp_f32_e32 v76, v76
	v_rcp_f32_e32 v85, v81
	s_nop 0
	v_mul_f32_e32 v85, v86, v85
	v_mul_f32_e32 v77, 0xbfb8aa3b, v88
	v_exp_f32_e32 v77, v77
	s_nop 0
	v_pk_add_f32 v[76:77], v[76:77], 1.0 op_sel_hi:[1,0]
	v_rcp_f32_e32 v84, v80
	s_nop 0
	v_mul_f32_e32 v84, v87, v84
	v_rcp_f32_e32 v87, v77
	s_nop 0
	v_mul_f32_e32 v87, v88, v87
	v_lshlrev_b32_e32 v90, 16, v78
	v_lshlrev_b32_e32 v82, 16, v79
	v_mul_f32_e32 v80, 0xbfb8aa3b, v90
	v_mul_f32_e32 v81, 0xbfb8aa3b, v82
	v_exp_f32_e32 v80, v80
	v_exp_f32_e32 v81, v81
	v_rcp_f32_e32 v86, v76
	s_nop 0
	v_mul_f32_e32 v86, v83, v86
	v_and_b32_e32 v83, 0xffff0000, v79
	v_pk_add_f32 v[76:77], v[80:81], 1.0 op_sel_hi:[1,0]
	v_mul_f32_e32 v78, 0xbfb8aa3b, v94
	v_exp_f32_e32 v78, v78
	v_rcp_f32_e32 v89, v77
	s_nop 0
	v_mul_f32_e32 v89, v82, v89
	v_mul_f32_e32 v79, 0xbfb8aa3b, v83
	v_exp_f32_e32 v79, v79
	s_nop 0
	v_pk_add_f32 v[80:81], v[78:79], 1.0 op_sel_hi:[1,0]
	v_rcp_f32_e32 v88, v76
	s_nop 0
	v_mul_f32_e32 v88, v90, v88
	v_rcp_f32_e32 v91, v81
	s_nop 0
	v_mul_f32_e32 v91, v83, v91
	ds_read_b128 v[76:79], v98
	v_rcp_f32_e32 v90, v80
	s_nop 0
	v_mul_f32_e32 v90, v94, v90
	ds_read_b128 v[80:83], v98 offset:16
	v_add_co_u32_e32 v30, vcc, s77, v30
	s_waitcnt lgkmcnt(1)
	v_mov_b32_e32 v96, v76
	v_mov_b32_e32 v97, v78
	v_pk_mul_f32 v[84:85], v[84:85], v[96:97]
	v_mov_b32_e32 v78, v77
	v_pk_mul_f32 v[76:77], v[86:87], v[78:79]
	v_and_b32_sdwa v78, v85, v155 dst_sel:DWORD dst_unused:UNUSED_PAD src0_sel:WORD_1 src1_sel:DWORD
	v_and_b32_sdwa v79, v84, v155 dst_sel:DWORD dst_unused:UNUSED_PAD src0_sel:WORD_1 src1_sel:DWORD
	v_add3_u32 v79, v84, v79, s68
	v_add3_u32 v78, v85, v78, s68
	v_and_b32_sdwa v84, v77, v155 dst_sel:DWORD dst_unused:UNUSED_PAD src0_sel:WORD_1 src1_sel:DWORD
	v_and_b32_sdwa v85, v76, v155 dst_sel:DWORD dst_unused:UNUSED_PAD src0_sel:WORD_1 src1_sel:DWORD
	v_add3_u32 v77, v77, v84, s68
	v_add3_u32 v76, v76, v85, s68
	v_and_b32_e32 v77, 0xffff0000, v77
	v_and_b32_e32 v76, 0xffff0000, v76
	v_or_b32_sdwa v77, v77, v78 dst_sel:DWORD dst_unused:UNUSED_PAD src0_sel:DWORD src1_sel:WORD_1
	v_or_b32_sdwa v76, v76, v79 dst_sel:DWORD dst_unused:UNUSED_PAD src0_sel:DWORD src1_sel:WORD_1
	s_waitcnt lgkmcnt(0)
	v_mov_b32_e32 v78, v80
	v_mov_b32_e32 v79, v82
	v_pk_mul_f32 v[78:79], v[88:89], v[78:79]
	v_mov_b32_e32 v82, v81
	v_pk_mul_f32 v[80:81], v[90:91], v[82:83]
	v_and_b32_sdwa v82, v79, v155 dst_sel:DWORD dst_unused:UNUSED_PAD src0_sel:WORD_1 src1_sel:DWORD
	v_and_b32_sdwa v83, v78, v155 dst_sel:DWORD dst_unused:UNUSED_PAD src0_sel:WORD_1 src1_sel:DWORD
	v_add3_u32 v78, v78, v83, s68
	v_add3_u32 v79, v79, v82, s68
	v_and_b32_sdwa v82, v81, v155 dst_sel:DWORD dst_unused:UNUSED_PAD src0_sel:WORD_1 src1_sel:DWORD
	v_and_b32_sdwa v83, v80, v155 dst_sel:DWORD dst_unused:UNUSED_PAD src0_sel:WORD_1 src1_sel:DWORD
	v_add3_u32 v81, v81, v82, s68
	v_add3_u32 v80, v80, v83, s68
	v_and_b32_e32 v81, 0xffff0000, v81
	v_and_b32_e32 v80, 0xffff0000, v80
	v_or_b32_sdwa v79, v81, v79 dst_sel:DWORD dst_unused:UNUSED_PAD src0_sel:DWORD src1_sel:WORD_1
	v_or_b32_sdwa v78, v80, v78 dst_sel:DWORD dst_unused:UNUSED_PAD src0_sel:DWORD src1_sel:WORD_1
	ds_read_b128 v[80:83], v95
	v_addc_co_u32_e32 v31, vcc, 0, v31, vcc
	global_store_dwordx4 v[30:31], v[76:79], off offset:2048
	ds_read_b128 v[76:79], v95 offset:16
	s_waitcnt lgkmcnt(1)
	v_mov_b32_e32 v30, v80
	v_mov_b32_e32 v31, v82
	v_pk_mul_f32 v[4:5], v[4:5], v[30:31]
	v_mov_b32_e32 v82, v81
	v_pk_mul_f32 v[30:31], v[68:69], v[82:83]
	v_and_b32_sdwa v68, v5, v155 dst_sel:DWORD dst_unused:UNUSED_PAD src0_sel:WORD_1 src1_sel:DWORD
	v_and_b32_sdwa v69, v4, v155 dst_sel:DWORD dst_unused:UNUSED_PAD src0_sel:WORD_1 src1_sel:DWORD
	v_add3_u32 v4, v4, v69, s68
	v_add3_u32 v5, v5, v68, s68
	v_and_b32_sdwa v68, v31, v155 dst_sel:DWORD dst_unused:UNUSED_PAD src0_sel:WORD_1 src1_sel:DWORD
	v_and_b32_sdwa v69, v30, v155 dst_sel:DWORD dst_unused:UNUSED_PAD src0_sel:WORD_1 src1_sel:DWORD
	v_add3_u32 v31, v31, v68, s68
	v_add3_u32 v30, v30, v69, s68
	v_and_b32_e32 v31, 0xffff0000, v31
	v_and_b32_e32 v30, 0xffff0000, v30
	v_or_b32_sdwa v5, v31, v5 dst_sel:DWORD dst_unused:UNUSED_PAD src0_sel:DWORD src1_sel:WORD_1
	v_or_b32_sdwa v4, v30, v4 dst_sel:DWORD dst_unused:UNUSED_PAD src0_sel:DWORD src1_sel:WORD_1
	s_waitcnt lgkmcnt(0)
; __device__ __forceinline__ unsigned pack2(float a, float b) { return (unsigned)f2bf(a) | ((unsigned)f2bf(b) << 16); }
; __device__ __forceinline__ float bflo(unsigned w) { return __uint_as_float(w << 16); }
; __device__ __forceinline__ float bfhi(unsigned w) { return __uint_as_float(w & 0xffff0000u); }
; __device__ __forceinline__ float silu_f(float g) { return g / (1.f + __expf(-g)); }
; template <int DH, int MODE>
; __device__ void attn_item(const Params& p, int layer, int b, int blk, int head, char* smem) {
;     ...
; #pragma unroll
;     for (int i = 0; i < NCH; ++i) {
;       int q = tid + 256 * i, r = q / CPR, c = (q % CPR) * 8;
;       float4 m0 = *reinterpret_cast<const float4*>(Of + r * OST + c);
;       float4 m1 = *reinterpret_cast<const float4*>(Of + r * OST + c + 4);
;       float mm[8] = {m0.x, m0.y, m0.z, m0.w, m1.x, m1.y, m1.z, m1.w};
;       unsigned gw[4] = {gt[i].x, gt[i].y, gt[i].z, gt[i].w};
;       unsigned ow[4];
; #pragma unroll
;       for (int e = 0; e < 4; ++e)
;         ow[e] = pack2(mm[2 * e] * silu_f(bflo(gw[e])), mm[2 * e + 1] * silu_f(bfhi(gw[e])));
;       *reinterpret_cast<uint4*>(Y + (tq0 + r) * YW + ycol + c) = make_uint4(ow[0], ow[1], ow[2], ow[3]);
;     }
	v_mov_b32_e32 v30, v76
	v_mov_b32_e32 v31, v78
	v_pk_mul_f32 v[6:7], v[6:7], v[30:31]
	v_mov_b32_e32 v78, v77
	v_pk_mul_f32 v[30:31], v[70:71], v[78:79]
	v_and_b32_sdwa v68, v7, v155 dst_sel:DWORD dst_unused:UNUSED_PAD src0_sel:WORD_1 src1_sel:DWORD
	v_and_b32_sdwa v69, v6, v155 dst_sel:DWORD dst_unused:UNUSED_PAD src0_sel:WORD_1 src1_sel:DWORD
	v_add3_u32 v6, v6, v69, s68
	v_add3_u32 v7, v7, v68, s68
	v_and_b32_sdwa v68, v31, v155 dst_sel:DWORD dst_unused:UNUSED_PAD src0_sel:WORD_1 src1_sel:DWORD
	v_and_b32_sdwa v69, v30, v155 dst_sel:DWORD dst_unused:UNUSED_PAD src0_sel:WORD_1 src1_sel:DWORD
	v_add3_u32 v31, v31, v68, s68
	v_add3_u32 v30, v30, v69, s68
	ds_read_b128 v[68:71], v93
	v_and_b32_e32 v31, 0xffff0000, v31
	v_and_b32_e32 v30, 0xffff0000, v30
	v_add_co_u32_e32 v26, vcc, s77, v26
	v_or_b32_sdwa v7, v31, v7 dst_sel:DWORD dst_unused:UNUSED_PAD src0_sel:DWORD src1_sel:WORD_1
	v_or_b32_sdwa v6, v30, v6 dst_sel:DWORD dst_unused:UNUSED_PAD src0_sel:DWORD src1_sel:WORD_1
	v_addc_co_u32_e32 v27, vcc, 0, v27, vcc
	global_store_dwordx4 v[26:27], v[4:7], off offset:2048
	s_waitcnt lgkmcnt(0)
	v_mov_b32_e32 v26, v68
	v_mov_b32_e32 v27, v70
	ds_read_b128 v[4:7], v93 offset:16
	v_pk_mul_f32 v[0:1], v[0:1], v[26:27]
	v_mov_b32_e32 v70, v69
	v_pk_mul_f32 v[26:27], v[64:65], v[70:71]
	v_and_b32_sdwa v30, v1, v155 dst_sel:DWORD dst_unused:UNUSED_PAD src0_sel:WORD_1 src1_sel:DWORD
	v_and_b32_sdwa v31, v0, v155 dst_sel:DWORD dst_unused:UNUSED_PAD src0_sel:WORD_1 src1_sel:DWORD
	v_add3_u32 v0, v0, v31, s68
	v_add3_u32 v1, v1, v30, s68
	v_and_b32_sdwa v30, v27, v155 dst_sel:DWORD dst_unused:UNUSED_PAD src0_sel:WORD_1 src1_sel:DWORD
	v_and_b32_sdwa v31, v26, v155 dst_sel:DWORD dst_unused:UNUSED_PAD src0_sel:WORD_1 src1_sel:DWORD
	v_add3_u32 v27, v27, v30, s68
	v_add3_u32 v26, v26, v31, s68
	v_and_b32_e32 v27, 0xffff0000, v27
	v_and_b32_e32 v26, 0xffff0000, v26
	v_or_b32_sdwa v1, v27, v1 dst_sel:DWORD dst_unused:UNUSED_PAD src0_sel:DWORD src1_sel:WORD_1
	v_or_b32_sdwa v0, v26, v0 dst_sel:DWORD dst_unused:UNUSED_PAD src0_sel:DWORD src1_sel:WORD_1
	s_waitcnt lgkmcnt(0)
	v_mov_b32_e32 v26, v4
	v_mov_b32_e32 v27, v6
	v_pk_mul_f32 v[2:3], v[2:3], v[26:27]
	v_mov_b32_e32 v6, v5
	v_pk_mul_f32 v[4:5], v[66:67], v[6:7]
	v_and_b32_sdwa v6, v3, v155 dst_sel:DWORD dst_unused:UNUSED_PAD src0_sel:WORD_1 src1_sel:DWORD
	v_and_b32_sdwa v7, v2, v155 dst_sel:DWORD dst_unused:UNUSED_PAD src0_sel:WORD_1 src1_sel:DWORD
	v_add3_u32 v2, v2, v7, s68
	v_add3_u32 v3, v3, v6, s68
	v_and_b32_sdwa v6, v5, v155 dst_sel:DWORD dst_unused:UNUSED_PAD src0_sel:WORD_1 src1_sel:DWORD
	v_and_b32_sdwa v7, v4, v155 dst_sel:DWORD dst_unused:UNUSED_PAD src0_sel:WORD_1 src1_sel:DWORD
	v_add3_u32 v5, v5, v6, s68
	v_add3_u32 v4, v4, v7, s68
	v_and_b32_e32 v5, 0xffff0000, v5
	v_and_b32_e32 v4, 0xffff0000, v4
	v_or_b32_sdwa v3, v5, v3 dst_sel:DWORD dst_unused:UNUSED_PAD src0_sel:DWORD src1_sel:WORD_1
	v_or_b32_sdwa v2, v4, v2 dst_sel:DWORD dst_unused:UNUSED_PAD src0_sel:DWORD src1_sel:WORD_1
	ds_read_b128 v[4:7], v92
	v_add_co_u32_e32 v20, vcc, s77, v20
	s_nop 1
	v_addc_co_u32_e32 v21, vcc, 0, v21, vcc
	global_store_dwordx4 v[20:21], v[0:3], off offset:2048
	s_waitcnt lgkmcnt(0)
	v_mov_b32_e32 v20, v4
	v_mov_b32_e32 v21, v6
	ds_read_b128 v[0:3], v92 offset:16
	v_pk_mul_f32 v[20:21], v[56:57], v[20:21]
	v_mov_b32_e32 v6, v5
	v_pk_mul_f32 v[4:5], v[58:59], v[6:7]
	v_and_b32_sdwa v6, v21, v155 dst_sel:DWORD dst_unused:UNUSED_PAD src0_sel:WORD_1 src1_sel:DWORD
	v_and_b32_sdwa v7, v20, v155 dst_sel:DWORD dst_unused:UNUSED_PAD src0_sel:WORD_1 src1_sel:DWORD
	v_add3_u32 v7, v20, v7, s68
	v_add3_u32 v6, v21, v6, s68
	v_and_b32_sdwa v20, v5, v155 dst_sel:DWORD dst_unused:UNUSED_PAD src0_sel:WORD_1 src1_sel:DWORD
	v_and_b32_sdwa v21, v4, v155 dst_sel:DWORD dst_unused:UNUSED_PAD src0_sel:WORD_1 src1_sel:DWORD
	v_add3_u32 v5, v5, v20, s68
	v_add3_u32 v4, v4, v21, s68
	v_and_b32_e32 v5, 0xffff0000, v5
	v_and_b32_e32 v4, 0xffff0000, v4
	v_or_b32_sdwa v5, v5, v6 dst_sel:DWORD dst_unused:UNUSED_PAD src0_sel:DWORD src1_sel:WORD_1
	v_or_b32_sdwa v4, v4, v7 dst_sel:DWORD dst_unused:UNUSED_PAD src0_sel:DWORD src1_sel:WORD_1
	s_waitcnt lgkmcnt(0)
	v_mov_b32_e32 v6, v0
	v_mov_b32_e32 v7, v2
	v_pk_mul_f32 v[6:7], v[60:61], v[6:7]
	v_mov_b32_e32 v2, v1
	v_pk_mul_f32 v[0:1], v[62:63], v[2:3]
	v_and_b32_sdwa v2, v7, v155 dst_sel:DWORD dst_unused:UNUSED_PAD src0_sel:WORD_1 src1_sel:DWORD
	v_and_b32_sdwa v3, v6, v155 dst_sel:DWORD dst_unused:UNUSED_PAD src0_sel:WORD_1 src1_sel:DWORD
	v_add3_u32 v3, v6, v3, s68
	v_add3_u32 v2, v7, v2, s68
	v_and_b32_sdwa v6, v1, v155 dst_sel:DWORD dst_unused:UNUSED_PAD src0_sel:WORD_1 src1_sel:DWORD
	v_and_b32_sdwa v7, v0, v155 dst_sel:DWORD dst_unused:UNUSED_PAD src0_sel:WORD_1 src1_sel:DWORD
	v_add3_u32 v1, v1, v6, s68
	v_add3_u32 v0, v0, v7, s68
	v_and_b32_e32 v1, 0xffff0000, v1
	v_and_b32_e32 v0, 0xffff0000, v0
	v_or_b32_sdwa v7, v1, v2 dst_sel:DWORD dst_unused:UNUSED_PAD src0_sel:DWORD src1_sel:WORD_1
	v_or_b32_sdwa v6, v0, v3 dst_sel:DWORD dst_unused:UNUSED_PAD src0_sel:DWORD src1_sel:WORD_1
	ds_read_b128 v[0:3], v75
	v_add_co_u32_e32 v16, vcc, s77, v16
	s_nop 1
	v_addc_co_u32_e32 v17, vcc, 0, v17, vcc
	global_store_dwordx4 v[16:17], v[4:7], off offset:2048
	s_waitcnt lgkmcnt(0)
; __device__ __forceinline__ unsigned pack2(float a, float b) { return (unsigned)f2bf(a) | ((unsigned)f2bf(b) << 16); }
; __device__ __forceinline__ float bflo(unsigned w) { return __uint_as_float(w << 16); }
; __device__ __forceinline__ float bfhi(unsigned w) { return __uint_as_float(w & 0xffff0000u); }
; __device__ __forceinline__ float silu_f(float g) { return g / (1.f + __expf(-g)); }
; template <int DH, int MODE>
; __device__ void attn_item(const Params& p, int layer, int b, int blk, int head, char* smem) {
;     ...
; #pragma unroll
;     for (int i = 0; i < NCH; ++i) {
;       int q = tid + 256 * i, r = q / CPR, c = (q % CPR) * 8;
;       float4 m0 = *reinterpret_cast<const float4*>(Of + r * OST + c);
;       float4 m1 = *reinterpret_cast<const float4*>(Of + r * OST + c + 4);
;       float mm[8] = {m0.x, m0.y, m0.z, m0.w, m1.x, m1.y, m1.z, m1.w};
;       unsigned gw[4] = {gt[i].x, gt[i].y, gt[i].z, gt[i].w};
;       unsigned ow[4];
; #pragma unroll
;       for (int e = 0; e < 4; ++e)
;         ow[e] = pack2(mm[2 * e] * silu_f(bflo(gw[e])), mm[2 * e + 1] * silu_f(bfhi(gw[e])));
;       *reinterpret_cast<uint4*>(Y + (tq0 + r) * YW + ycol + c) = make_uint4(ow[0], ow[1], ow[2], ow[3]);
;     }
	v_mov_b32_e32 v16, v0
	v_mov_b32_e32 v17, v2
	ds_read_b128 v[4:7], v75 offset:16
	v_pk_mul_f32 v[16:17], v[48:49], v[16:17]
	v_mov_b32_e32 v2, v1
	v_pk_mul_f32 v[0:1], v[50:51], v[2:3]
	v_and_b32_sdwa v2, v17, v155 dst_sel:DWORD dst_unused:UNUSED_PAD src0_sel:WORD_1 src1_sel:DWORD
	v_and_b32_sdwa v3, v16, v155 dst_sel:DWORD dst_unused:UNUSED_PAD src0_sel:WORD_1 src1_sel:DWORD
	v_add3_u32 v3, v16, v3, s68
	v_add3_u32 v2, v17, v2, s68
	v_and_b32_sdwa v16, v1, v155 dst_sel:DWORD dst_unused:UNUSED_PAD src0_sel:WORD_1 src1_sel:DWORD
	v_and_b32_sdwa v17, v0, v155 dst_sel:DWORD dst_unused:UNUSED_PAD src0_sel:WORD_1 src1_sel:DWORD
	v_add3_u32 v1, v1, v16, s68
	v_add3_u32 v0, v0, v17, s68
	v_and_b32_e32 v1, 0xffff0000, v1
	v_and_b32_e32 v0, 0xffff0000, v0
	v_or_b32_sdwa v1, v1, v2 dst_sel:DWORD dst_unused:UNUSED_PAD src0_sel:DWORD src1_sel:WORD_1
	v_or_b32_sdwa v0, v0, v3 dst_sel:DWORD dst_unused:UNUSED_PAD src0_sel:DWORD src1_sel:WORD_1
	s_waitcnt lgkmcnt(0)
	v_mov_b32_e32 v2, v4
	v_mov_b32_e32 v3, v6
	v_pk_mul_f32 v[2:3], v[52:53], v[2:3]
	v_mov_b32_e32 v6, v5
	v_pk_mul_f32 v[4:5], v[54:55], v[6:7]
	v_and_b32_sdwa v6, v3, v155 dst_sel:DWORD dst_unused:UNUSED_PAD src0_sel:WORD_1 src1_sel:DWORD
	v_and_b32_sdwa v7, v2, v155 dst_sel:DWORD dst_unused:UNUSED_PAD src0_sel:WORD_1 src1_sel:DWORD
	v_add3_u32 v2, v2, v7, s68
	v_add3_u32 v3, v3, v6, s68
	v_and_b32_sdwa v6, v5, v155 dst_sel:DWORD dst_unused:UNUSED_PAD src0_sel:WORD_1 src1_sel:DWORD
	v_and_b32_sdwa v7, v4, v155 dst_sel:DWORD dst_unused:UNUSED_PAD src0_sel:WORD_1 src1_sel:DWORD
	v_add3_u32 v5, v5, v6, s68
	v_add3_u32 v4, v4, v7, s68
	v_and_b32_e32 v5, 0xffff0000, v5
	v_and_b32_e32 v4, 0xffff0000, v4
	v_or_b32_sdwa v3, v5, v3 dst_sel:DWORD dst_unused:UNUSED_PAD src0_sel:DWORD src1_sel:WORD_1
	v_or_b32_sdwa v2, v4, v2 dst_sel:DWORD dst_unused:UNUSED_PAD src0_sel:DWORD src1_sel:WORD_1
	ds_read_b128 v[4:7], v74
	v_add_co_u32_e32 v12, vcc, s77, v12
	s_nop 1
	v_addc_co_u32_e32 v13, vcc, 0, v13, vcc
	global_store_dwordx4 v[12:13], v[0:3], off offset:2048
	s_waitcnt lgkmcnt(0)
	v_mov_b32_e32 v12, v4
	v_mov_b32_e32 v13, v6
	ds_read_b128 v[0:3], v74 offset:16
	v_pk_mul_f32 v[12:13], v[40:41], v[12:13]
	v_mov_b32_e32 v6, v5
	v_pk_mul_f32 v[4:5], v[42:43], v[6:7]
	v_and_b32_sdwa v6, v13, v155 dst_sel:DWORD dst_unused:UNUSED_PAD src0_sel:WORD_1 src1_sel:DWORD
	v_and_b32_sdwa v7, v12, v155 dst_sel:DWORD dst_unused:UNUSED_PAD src0_sel:WORD_1 src1_sel:DWORD
	v_add3_u32 v7, v12, v7, s68
	v_add3_u32 v6, v13, v6, s68
	v_and_b32_sdwa v12, v5, v155 dst_sel:DWORD dst_unused:UNUSED_PAD src0_sel:WORD_1 src1_sel:DWORD
	v_and_b32_sdwa v13, v4, v155 dst_sel:DWORD dst_unused:UNUSED_PAD src0_sel:WORD_1 src1_sel:DWORD
	v_add3_u32 v5, v5, v12, s68
	v_add3_u32 v4, v4, v13, s68
	v_and_b32_e32 v5, 0xffff0000, v5
	v_and_b32_e32 v4, 0xffff0000, v4
	v_or_b32_sdwa v5, v5, v6 dst_sel:DWORD dst_unused:UNUSED_PAD src0_sel:DWORD src1_sel:WORD_1
	v_or_b32_sdwa v4, v4, v7 dst_sel:DWORD dst_unused:UNUSED_PAD src0_sel:DWORD src1_sel:WORD_1
	s_waitcnt lgkmcnt(0)
	v_mov_b32_e32 v6, v0
	v_mov_b32_e32 v7, v2
	v_pk_mul_f32 v[6:7], v[44:45], v[6:7]
	v_mov_b32_e32 v2, v1
	v_pk_mul_f32 v[0:1], v[46:47], v[2:3]
	v_and_b32_sdwa v2, v7, v155 dst_sel:DWORD dst_unused:UNUSED_PAD src0_sel:WORD_1 src1_sel:DWORD
	v_and_b32_sdwa v3, v6, v155 dst_sel:DWORD dst_unused:UNUSED_PAD src0_sel:WORD_1 src1_sel:DWORD
	v_add3_u32 v3, v6, v3, s68
	v_add3_u32 v2, v7, v2, s68
	v_and_b32_sdwa v6, v1, v155 dst_sel:DWORD dst_unused:UNUSED_PAD src0_sel:WORD_1 src1_sel:DWORD
	v_and_b32_sdwa v7, v0, v155 dst_sel:DWORD dst_unused:UNUSED_PAD src0_sel:WORD_1 src1_sel:DWORD
	v_add3_u32 v1, v1, v6, s68
	v_add3_u32 v0, v0, v7, s68
	v_and_b32_e32 v1, 0xffff0000, v1
	v_and_b32_e32 v0, 0xffff0000, v0
	v_or_b32_sdwa v7, v1, v2 dst_sel:DWORD dst_unused:UNUSED_PAD src0_sel:DWORD src1_sel:WORD_1
	v_or_b32_sdwa v6, v0, v3 dst_sel:DWORD dst_unused:UNUSED_PAD src0_sel:DWORD src1_sel:WORD_1
	ds_read_b128 v[0:3], v73
	v_add_co_u32_e32 v10, vcc, s77, v10
	s_nop 1
	v_addc_co_u32_e32 v11, vcc, 0, v11, vcc
	global_store_dwordx4 v[10:11], v[4:7], off offset:2048
	s_waitcnt lgkmcnt(0)
; __device__ __forceinline__ unsigned pack2(float a, float b) { return (unsigned)f2bf(a) | ((unsigned)f2bf(b) << 16); }
; __device__ __forceinline__ float bflo(unsigned w) { return __uint_as_float(w << 16); }
; __device__ __forceinline__ float bfhi(unsigned w) { return __uint_as_float(w & 0xffff0000u); }
; __device__ __forceinline__ float silu_f(float g) { return g / (1.f + __expf(-g)); }
; template <int DH, int MODE>
; __device__ void attn_item(const Params& p, int layer, int b, int blk, int head, char* smem) {
;     ...
; #pragma unroll
;     for (int i = 0; i < NCH; ++i) {
;       int q = tid + 256 * i, r = q / CPR, c = (q % CPR) * 8;
;       float4 m0 = *reinterpret_cast<const float4*>(Of + r * OST + c);
;       float4 m1 = *reinterpret_cast<const float4*>(Of + r * OST + c + 4);
;       float mm[8] = {m0.x, m0.y, m0.z, m0.w, m1.x, m1.y, m1.z, m1.w};
;       unsigned gw[4] = {gt[i].x, gt[i].y, gt[i].z, gt[i].w};
;       unsigned ow[4];
; #pragma unroll
;       for (int e = 0; e < 4; ++e)
;         ow[e] = pack2(mm[2 * e] * silu_f(bflo(gw[e])), mm[2 * e + 1] * silu_f(bfhi(gw[e])));
;       *reinterpret_cast<uint4*>(Y + (tq0 + r) * YW + ycol + c) = make_uint4(ow[0], ow[1], ow[2], ow[3]);
;     }
;   }
;   __syncthreads();
	v_mov_b32_e32 v10, v0
	v_mov_b32_e32 v11, v2
	ds_read_b128 v[4:7], v73 offset:16
	v_pk_mul_f32 v[10:11], v[32:33], v[10:11]
	v_mov_b32_e32 v2, v1
	v_pk_mul_f32 v[0:1], v[34:35], v[2:3]
	v_and_b32_sdwa v2, v11, v155 dst_sel:DWORD dst_unused:UNUSED_PAD src0_sel:WORD_1 src1_sel:DWORD
	v_and_b32_sdwa v3, v10, v155 dst_sel:DWORD dst_unused:UNUSED_PAD src0_sel:WORD_1 src1_sel:DWORD
	v_add3_u32 v3, v10, v3, s68
	v_add3_u32 v2, v11, v2, s68
	v_and_b32_sdwa v10, v1, v155 dst_sel:DWORD dst_unused:UNUSED_PAD src0_sel:WORD_1 src1_sel:DWORD
	v_and_b32_sdwa v11, v0, v155 dst_sel:DWORD dst_unused:UNUSED_PAD src0_sel:WORD_1 src1_sel:DWORD
	v_add3_u32 v1, v1, v10, s68
	v_add3_u32 v0, v0, v11, s68
	v_and_b32_e32 v1, 0xffff0000, v1
	v_and_b32_e32 v0, 0xffff0000, v0
	v_or_b32_sdwa v1, v1, v2 dst_sel:DWORD dst_unused:UNUSED_PAD src0_sel:DWORD src1_sel:WORD_1
	v_or_b32_sdwa v0, v0, v3 dst_sel:DWORD dst_unused:UNUSED_PAD src0_sel:DWORD src1_sel:WORD_1
	s_waitcnt lgkmcnt(0)
	v_mov_b32_e32 v2, v4
	v_mov_b32_e32 v3, v6
	v_pk_mul_f32 v[2:3], v[36:37], v[2:3]
	v_mov_b32_e32 v6, v5
	v_pk_mul_f32 v[4:5], v[38:39], v[6:7]
	v_and_b32_sdwa v6, v3, v155 dst_sel:DWORD dst_unused:UNUSED_PAD src0_sel:WORD_1 src1_sel:DWORD
	v_and_b32_sdwa v7, v2, v155 dst_sel:DWORD dst_unused:UNUSED_PAD src0_sel:WORD_1 src1_sel:DWORD
	v_add3_u32 v2, v2, v7, s68
	v_add3_u32 v3, v3, v6, s68
	v_and_b32_sdwa v6, v5, v155 dst_sel:DWORD dst_unused:UNUSED_PAD src0_sel:WORD_1 src1_sel:DWORD
	v_and_b32_sdwa v7, v4, v155 dst_sel:DWORD dst_unused:UNUSED_PAD src0_sel:WORD_1 src1_sel:DWORD
	v_add3_u32 v5, v5, v6, s68
	v_add3_u32 v4, v4, v7, s68
	v_and_b32_e32 v5, 0xffff0000, v5
	v_and_b32_e32 v4, 0xffff0000, v4
	v_or_b32_sdwa v3, v5, v3 dst_sel:DWORD dst_unused:UNUSED_PAD src0_sel:DWORD src1_sel:WORD_1
	v_or_b32_sdwa v2, v4, v2 dst_sel:DWORD dst_unused:UNUSED_PAD src0_sel:DWORD src1_sel:WORD_1
	ds_read_b128 v[4:7], v72
	v_add_co_u32_e32 v8, vcc, s77, v8
	s_nop 1
	v_addc_co_u32_e32 v9, vcc, 0, v9, vcc
	global_store_dwordx4 v[8:9], v[0:3], off offset:2048
	s_waitcnt lgkmcnt(0)
	v_mov_b32_e32 v8, v4
	v_mov_b32_e32 v9, v6
	ds_read_b128 v[0:3], v72 offset:16
	v_pk_mul_f32 v[8:9], v[18:19], v[8:9]
	v_mov_b32_e32 v6, v5
	v_pk_mul_f32 v[4:5], v[22:23], v[6:7]
	v_and_b32_sdwa v6, v9, v155 dst_sel:DWORD dst_unused:UNUSED_PAD src0_sel:WORD_1 src1_sel:DWORD
	v_and_b32_sdwa v7, v8, v155 dst_sel:DWORD dst_unused:UNUSED_PAD src0_sel:WORD_1 src1_sel:DWORD
	v_add3_u32 v7, v8, v7, s68
	v_add3_u32 v6, v9, v6, s68
	v_and_b32_sdwa v8, v5, v155 dst_sel:DWORD dst_unused:UNUSED_PAD src0_sel:WORD_1 src1_sel:DWORD
	v_and_b32_sdwa v9, v4, v155 dst_sel:DWORD dst_unused:UNUSED_PAD src0_sel:WORD_1 src1_sel:DWORD
	v_add3_u32 v5, v5, v8, s68
	v_add3_u32 v4, v4, v9, s68
	v_and_b32_e32 v5, 0xffff0000, v5
	v_and_b32_e32 v4, 0xffff0000, v4
	v_or_b32_sdwa v5, v5, v6 dst_sel:DWORD dst_unused:UNUSED_PAD src0_sel:DWORD src1_sel:WORD_1
	v_or_b32_sdwa v4, v4, v7 dst_sel:DWORD dst_unused:UNUSED_PAD src0_sel:DWORD src1_sel:WORD_1
	s_waitcnt lgkmcnt(0)
	v_mov_b32_e32 v6, v0
	v_mov_b32_e32 v7, v2
	v_pk_mul_f32 v[6:7], v[24:25], v[6:7]
	v_mov_b32_e32 v2, v1
	v_pk_mul_f32 v[0:1], v[28:29], v[2:3]
	v_and_b32_sdwa v2, v7, v155 dst_sel:DWORD dst_unused:UNUSED_PAD src0_sel:WORD_1 src1_sel:DWORD
	v_and_b32_sdwa v3, v6, v155 dst_sel:DWORD dst_unused:UNUSED_PAD src0_sel:WORD_1 src1_sel:DWORD
	v_add3_u32 v2, v7, v2, s68
	v_and_b32_sdwa v7, v0, v155 dst_sel:DWORD dst_unused:UNUSED_PAD src0_sel:WORD_1 src1_sel:DWORD
	v_add3_u32 v3, v6, v3, s68
	v_and_b32_sdwa v6, v1, v155 dst_sel:DWORD dst_unused:UNUSED_PAD src0_sel:WORD_1 src1_sel:DWORD
	v_add3_u32 v0, v0, v7, s68
	v_add3_u32 v1, v1, v6, s68
	v_and_b32_e32 v0, 0xffff0000, v0
	v_and_b32_e32 v1, 0xffff0000, v1
	v_or_b32_sdwa v6, v0, v3 dst_sel:DWORD dst_unused:UNUSED_PAD src0_sel:DWORD src1_sel:WORD_1
	v_add_co_u32_e32 v0, vcc, 0x184a1000, v14
	v_or_b32_sdwa v7, v1, v2 dst_sel:DWORD dst_unused:UNUSED_PAD src0_sel:DWORD src1_sel:WORD_1
	s_nop 0
	v_addc_co_u32_e32 v1, vcc, 0, v15, vcc
	global_store_dwordx4 v[0:1], v[4:7], off offset:2048
	s_barrier

; #define MFMA16(a, b, c) __builtin_amdgcn_mfma_f32_16x16x32_bf16(a, b, c, 0, 0, 0)
; __device__ void gmlp_item(const Params& p, int layer, int b, int n, int g, char* smem) {
;     ...
; #pragma unroll 2
;   for (int i = 0; i < 8; ++i) {
;     int q = tid + 256 * i;
;     int t = q >> 4, cch = q & 15;
;     uint4 v = *reinterpret_cast<const uint4*>(Ws + (size_t)g * 16384 + t * 128 + cch * 8);
;     *reinterpret_cast<uint4*>(smem + (cch >> 2) * 8192 + t * 64 + (cch & 3) * 16) = v;
;   }
;   __syncthreads();
;   f32x4 acc[4][4];
; #pragma unroll
;   for (int m = 0; m < 4; ++m)
; #pragma unroll
;     for (int nn = 0; nn < 4; ++nn) acc[m][nn] = f32x4{0.f, 0.f, 0.f, 0.f};
; #pragma unroll
;   for (int ks = 0; ks < 4; ++ks) {
;     bf16x8 a[4], bb[4];
; #pragma unroll
;     for (int m = 0; m < 4; ++m)
;       a[m] = *reinterpret_cast<const bf16x8*>(smem + ks * 8192 + (wr * 64 + m * 16 + fr) * 64 + fq * 16);
; #pragma unroll
;     for (int nn = 0; nn < 4; ++nn)
;       bb[nn] = *reinterpret_cast<const bf16x8*>(smem + 32768 + ks * 8192 + (wc * 64 + nn * 16 + fr) * 64 + fq * 16);
; #pragma unroll
;     for (int m = 0; m < 4; ++m)
; #pragma unroll
;       for (int nn = 0; nn < 4; ++nn) acc[m][nn] = MFMA16(a[m], bb[nn], acc[m][nn]);
;   }
.LBB0_801:
	v_add_u32_e32 v3, s14, v59
	v_ashrrev_i32_e32 v12, 4, v3
	v_add_u32_e32 v3, 0x100, v3
	v_ashrrev_i32_e32 v3, 4, v3
	v_lshlrev_b32_e32 v4, 7, v12
	v_lshlrev_b32_e32 v6, 7, v3
	v_ashrrev_i32_e32 v5, 31, v4
	v_ashrrev_i32_e32 v7, 31, v6
	v_lshl_add_u64 v[4:5], v[4:5], 1, v[0:1]
	v_lshl_add_u64 v[8:9], v[6:7], 1, v[0:1]
	global_load_dwordx4 v[4:7], v[4:5], off
	s_nop 0
	global_load_dwordx4 v[8:11], v[8:9], off
	s_addk_i32 s14, 0x200
	s_cmpk_lg_i32 s14, 0x800
	v_lshl_add_u32 v12, v12, 6, v2
	v_lshl_add_u32 v3, v3, 6, v2
	s_waitcnt vmcnt(1)
	ds_write_b128 v12, v[4:7]
	s_waitcnt vmcnt(0)
	ds_write_b128 v3, v[8:11]
	s_cbranch_scc1 .LBB0_801
	v_bfe_u32 v54, v59, 4, 2
	v_ashrrev_i32_e32 v55, 7, v59
	v_lshlrev_b32_e32 v4, 4, v54
	v_lshlrev_b32_e32 v0, 12, v55
	v_lshlrev_b32_e32 v5, 6, v49
	v_or3_b32 v57, v4, v0, v5
	s_waitcnt lgkmcnt(0)
	s_barrier
	ds_read_b128 v[0:3], v57
	v_bfe_u32 v61, v59, 6, 1
	v_lshlrev_b32_e32 v6, 12, v61
	v_or3_b32 v63, v4, v6, v5
	ds_read_b128 v[4:7], v63 offset:32768
	ds_read_b128 v[8:11], v57 offset:1024
	ds_read_b128 v[12:15], v63 offset:33792
	ds_read_b128 v[24:27], v63 offset:34816
	ds_read_b128 v[28:31], v63 offset:35840
	s_waitcnt lgkmcnt(4)
	v_mfma_f32_16x16x32_bf16 v[16:19], v[0:3], v[4:7], 0
	s_ashr_i32 s14, s17, 31
	s_add_u32 s17, s28, s17
	s_addc_u32 s20, s29, s14
	s_waitcnt lgkmcnt(2)
	v_mfma_f32_16x16x32_bf16 v[20:23], v[0:3], v[12:15], 0
	s_lshl_b32 s14, s16, 2
	s_add_u32 s14, s24, s14
	v_lshlrev_b32_e32 v55, 6, v55
	s_waitcnt lgkmcnt(1)
	v_mfma_f32_16x16x32_bf16 v[36:39], v[0:3], v[24:27], 0
	s_addc_u32 s15, s25, 0
	v_lshl_or_b32 v54, v54, 2, v55
	s_add_u32 s14, s14, 0x1000
	s_waitcnt lgkmcnt(0)
	v_mfma_f32_16x16x32_bf16 v[40:43], v[0:3], v[28:31], 0
	s_addc_u32 s15, s15, 0
	v_ashrrev_i32_e32 v55, 31, v54
	v_lshl_add_u64 v[126:127], v[54:55], 2, s[14:15]
	v_mfma_f32_16x16x32_bf16 v[44:47], v[8:11], v[4:7], 0
	v_or_b32_e32 v130, 32, v54
	v_ashrrev_i32_e32 v131, 31, v130
	v_lshlrev_b32_e32 v49, 2, v49
	v_mfma_f32_16x16x32_bf16 v[50:53], v[8:11], v[12:15], 0
	v_lshl_add_u64 v[130:131], v[130:131], 2, s[14:15]
	v_ashrrev_i32_e32 v69, 31, v68
	v_ashrrev_i32_e32 v67, 31, v66
	v_mfma_f32_16x16x32_bf16 v[70:73], v[8:11], v[24:27], 0
	v_ashrrev_i32_e32 v65, 31, v64
	v_mfma_f32_16x16x32_bf16 v[74:77], v[8:11], v[28:31], 0
	ds_read_b128 v[0:3], v57 offset:2048
	ds_read_b128 v[8:11], v57 offset:3072
	s_waitcnt lgkmcnt(1)
	v_mfma_f32_16x16x32_bf16 v[82:85], v[0:3], v[12:15], 0
	s_waitcnt lgkmcnt(0)
	v_mfma_f32_16x16x32_bf16 v[98:101], v[8:11], v[12:15], 0
	ds_read_b128 v[12:15], v57 offset:8192
	v_mfma_f32_16x16x32_bf16 v[78:81], v[0:3], v[4:7], 0
	v_mfma_f32_16x16x32_bf16 v[86:89], v[0:3], v[24:27], 0
	v_mfma_f32_16x16x32_bf16 v[94:97], v[8:11], v[4:7], 0
	v_mfma_f32_16x16x32_bf16 v[32:35], v[8:11], v[24:27], 0
	ds_read_b128 v[102:105], v63 offset:40960
	ds_read_b128 v[24:27], v57 offset:9216
	ds_read_b128 v[106:109], v63 offset:41984
	ds_read_b128 v[118:121], v63 offset:43008
	ds_read_b128 v[4:7], v63 offset:44032
	v_mfma_f32_16x16x32_bf16 v[90:93], v[0:3], v[28:31], 0
	s_waitcnt lgkmcnt(4)
	v_mfma_f32_16x16x32_bf16 v[110:113], v[12:15], v[102:105], v[16:19]
	s_waitcnt lgkmcnt(2)
	v_mfma_f32_16x16x32_bf16 v[114:117], v[12:15], v[106:109], v[20:23]
	s_waitcnt lgkmcnt(1)
	v_mfma_f32_16x16x32_bf16 v[122:125], v[12:15], v[118:121], v[36:39]
	s_waitcnt lgkmcnt(0)
	v_mfma_f32_16x16x32_bf16 v[134:137], v[12:15], v[4:7], v[40:43]
	ds_read_b128 v[146:149], v57 offset:10240
	ds_read_b128 v[12:15], v57 offset:11264
	v_mfma_f32_16x16x32_bf16 v[0:3], v[8:11], v[28:31], 0
	ds_read_b128 v[150:153], v57 offset:16384
	ds_read_b128 v[162:165], v57 offset:17408
	ds_read_b128 v[166:169], v57 offset:18432
	ds_read_b128 v[8:11], v57 offset:19456
	ds_read_b128 v[36:39], v63 offset:49152
	ds_read_b128 v[28:31], v63 offset:50176
	ds_read_b128 v[20:23], v63 offset:51200
	ds_read_b128 v[16:19], v63 offset:52224
	v_mfma_f32_16x16x32_bf16 v[138:141], v[24:27], v[102:105], v[44:47]
	v_mfma_f32_16x16x32_bf16 v[50:53], v[24:27], v[106:109], v[50:53]
	v_mfma_f32_16x16x32_bf16 v[70:73], v[24:27], v[118:121], v[70:73]
	v_mfma_f32_16x16x32_bf16 v[74:77], v[24:27], v[4:7], v[74:77]
	ds_read_b128 v[170:173], v57 offset:24576
	ds_read_b128 v[174:177], v57 offset:25600
	ds_read_b128 v[178:181], v57 offset:26624
	ds_read_b128 v[24:27], v57 offset:27648
	ds_read_b128 v[182:185], v63 offset:57344
	ds_read_b128 v[186:189], v63 offset:58368
	ds_read_b128 v[44:47], v63 offset:59392
	ds_read_b128 v[40:43], v63 offset:60416
	s_waitcnt lgkmcnt(0)
	v_mfma_f32_16x16x32_bf16 v[78:81], v[146:149], v[102:105], v[78:81]
	s_barrier
; #define MFMA16(a, b, c) __builtin_amdgcn_mfma_f32_16x16x32_bf16(a, b, c, 0, 0, 0)
; __device__ void gmlp_item(const Params& p, int layer, int b, int n, int g, char* smem) {
;     ...
; #pragma unroll
;     for (int m = 0; m < 4; ++m)
; #pragma unroll
;       for (int nn = 0; nn < 4; ++nn) acc[m][nn] = MFMA16(a[m], bb[nn], acc[m][nn]);
;   }
;   __syncthreads();
;   {
;     float* Tf = reinterpret_cast<float*>(smem);
; #pragma unroll
;     for (int m = 0; m < 4; ++m)
; #pragma unroll
;       for (int j = 0; j < 4; ++j) {
;         int t = wr * 64 + m * 16 + fq * 4 + j;
;         float bias = p.gm_b_s[(size_t)layer * 512 + g * 128 + t];
; #pragma unroll
;         for (int nn = 0; nn < 4; ++nn) Tf[t * 132 + wc * 64 + nn * 16 + fr] = acc[m][nn][j] + bias;
;       }
	global_load_dwordx4 v[190:193], v[130:131], off
	v_mfma_f32_16x16x32_bf16 v[82:85], v[146:149], v[106:109], v[82:85]
	v_ashrrev_i32_e32 v63, 31, v62
	v_mfma_f32_16x16x32_bf16 v[86:89], v[146:149], v[118:121], v[86:89]
	v_mfma_f32_16x16x32_bf16 v[90:93], v[146:149], v[4:7], v[90:93]
	global_load_dwordx4 v[146:149], v[126:127], off
	v_or_b32_e32 v126, 16, v54
	v_ashrrev_i32_e32 v127, 31, v126
	v_lshl_add_u64 v[126:127], v[126:127], 2, s[14:15]
	v_mfma_f32_16x16x32_bf16 v[110:113], v[150:153], v[36:39], v[110:113]
	v_mfma_f32_16x16x32_bf16 v[114:117], v[150:153], v[28:31], v[114:117]
	v_mfma_f32_16x16x32_bf16 v[122:125], v[150:153], v[20:23], v[122:125]
	v_mfma_f32_16x16x32_bf16 v[134:137], v[150:153], v[16:19], v[134:137]
	global_load_dwordx4 v[150:153], v[126:127], off
	v_lshl_or_b32 v126, v61, 8, v49
	v_mad_u64_u32 v[126:127], s[48:49], v54, s69, v[126:127]
	v_mfma_f32_16x16x32_bf16 v[110:113], v[170:173], v[182:185], v[110:113]
	v_add_u32_e32 v57, 0x400, v126
	v_or_b32_e32 v54, 48, v54
	v_ashrrev_i32_e32 v61, 31, v60
	v_mfma_f32_16x16x32_bf16 v[114:117], v[170:173], v[186:189], v[114:117]
	v_mfma_f32_16x16x32_bf16 v[122:125], v[170:173], v[44:47], v[122:125]
	s_waitcnt vmcnt(1)
	s_nop 1
	v_add_f32_e32 v49, v110, v146
	v_mfma_f32_16x16x32_bf16 v[134:137], v[170:173], v[40:43], v[134:137]
	s_nop 1
	v_add_f32_e32 v55, v114, v146
	ds_write2_b32 v126, v49, v55 offset1:16
	v_add_f32_e32 v49, v122, v146
	v_mfma_f32_16x16x32_bf16 v[98:101], v[12:15], v[106:109], v[98:101]
	v_mfma_f32_16x16x32_bf16 v[94:97], v[12:15], v[102:105], v[94:97]
	s_nop 0
	v_add_f32_e32 v55, v134, v146
	ds_write2_b32 v126, v49, v55 offset0:32 offset1:48
	v_add_f32_e32 v49, v111, v147
	v_add_f32_e32 v55, v115, v147
	ds_write2_b32 v126, v49, v55 offset0:132 offset1:148
	v_add_f32_e32 v49, v123, v147
	v_add_f32_e32 v55, v135, v147
	ds_write2_b32 v126, v49, v55 offset0:164 offset1:180
	v_add_f32_e32 v49, v112, v148
	v_add_f32_e32 v55, v116, v148
	ds_write2_b32 v57, v49, v55 offset0:8 offset1:24
	v_add_f32_e32 v49, v124, v148
	v_add_f32_e32 v55, v136, v148
	ds_write2_b32 v57, v49, v55 offset0:40 offset1:56
	v_add_f32_e32 v49, v113, v149
	v_add_f32_e32 v55, v117, v149
	ds_write2_b32 v57, v49, v55 offset0:140 offset1:156
	v_add_f32_e32 v49, v125, v149
	v_add_f32_e32 v55, v137, v149
	ds_write2_b32 v57, v49, v55 offset0:172 offset1:188
	v_ashrrev_i32_e32 v55, 31, v54
	v_lshl_add_u64 v[54:55], v[54:55], 2, s[14:15]
	global_load_dwordx4 v[106:109], v[54:55], off
	v_mfma_f32_16x16x32_bf16 v[102:105], v[162:165], v[36:39], v[138:141]
	v_add_u32_e32 v54, 0x2000, v126
	v_ashrrev_i32_e32 v57, 31, v56
	v_mfma_f32_16x16x32_bf16 v[50:53], v[162:165], v[28:31], v[50:53]
	v_mfma_f32_16x16x32_bf16 v[70:73], v[162:165], v[20:23], v[70:73]
	v_mfma_f32_16x16x32_bf16 v[74:77], v[162:165], v[16:19], v[74:77]
	v_mfma_f32_16x16x32_bf16 v[102:105], v[174:177], v[182:185], v[102:105]
	v_mfma_f32_16x16x32_bf16 v[50:53], v[174:177], v[186:189], v[50:53]
	v_mfma_f32_16x16x32_bf16 v[70:73], v[174:177], v[44:47], v[70:73]
	s_waitcnt vmcnt(1)
	s_nop 4
	v_add_f32_e32 v49, v102, v150
	v_add_f32_e32 v50, v50, v150
	ds_write2_b32 v54, v49, v50 offset0:64 offset1:80
	v_mfma_f32_16x16x32_bf16 v[74:77], v[174:177], v[40:43], v[74:77]
	v_add_f32_e32 v55, v53, v153
	v_add_f32_e32 v49, v70, v150
	v_mfma_f32_16x16x32_bf16 v[78:81], v[166:169], v[36:39], v[78:81]
	v_mfma_f32_16x16x32_bf16 v[82:85], v[166:169], v[28:31], v[82:85]
	s_nop 3
	v_add_f32_e32 v50, v74, v150
	ds_write2_b32 v54, v49, v50 offset0:96 offset1:112
	v_add_f32_e32 v49, v103, v151
	v_add_f32_e32 v50, v51, v151
	ds_write2_b32 v54, v49, v50 offset0:196 offset1:212
	v_add_f32_e32 v49, v71, v151
	v_add_f32_e32 v50, v75, v151
	ds_write2_b32 v54, v49, v50 offset0:228 offset1:244
	v_add_f32_e32 v49, v104, v152
	v_add_f32_e32 v50, v52, v152
	v_add_u32_e32 v54, 0x2400, v126
	v_mfma_f32_16x16x32_bf16 v[86:89], v[166:169], v[20:23], v[86:89]
	ds_write2_b32 v54, v49, v50 offset0:72 offset1:88
	v_add_f32_e32 v49, v72, v152
	v_add_f32_e32 v50, v76, v152
	v_mfma_f32_16x16x32_bf16 v[90:93], v[166:169], v[16:19], v[90:93]
	ds_write2_b32 v54, v49, v50 offset0:104 offset1:120
	v_add_f32_e32 v49, v105, v153
	ds_write2_b32 v54, v49, v55 offset0:204 offset1:220
	v_mfma_f32_16x16x32_bf16 v[50:53], v[178:181], v[182:185], v[78:81]
	v_add_f32_e32 v49, v73, v153
	v_add_f32_e32 v55, v77, v153
	ds_write2_b32 v54, v49, v55 offset0:236 offset1:252
	v_mfma_f32_16x16x32_bf16 v[70:73], v[178:181], v[186:189], v[82:85]
	v_add_u32_e32 v54, 0x4000, v126
	s_nop 2
	v_add_f32_e32 v49, v50, v190
	v_mfma_f32_16x16x32_bf16 v[74:77], v[178:181], v[44:47], v[86:89]
	v_mfma_f32_16x16x32_bf16 v[78:81], v[178:181], v[40:43], v[90:93]
	s_nop 0
	v_add_f32_e32 v50, v70, v190
	ds_write2_b32 v54, v49, v50 offset0:128 offset1:144
	s_nop 3
	v_add_f32_e32 v49, v74, v190
	v_mfma_f32_16x16x32_bf16 v[32:35], v[12:15], v[118:121], v[32:35]
	v_mfma_f32_16x16x32_bf16 v[0:3], v[12:15], v[4:7], v[0:3]
	v_add_f32_e32 v50, v78, v190
	ds_write2_b32 v54, v49, v50 offset0:160 offset1:176
	v_add_f32_e32 v49, v51, v191
	v_add_f32_e32 v4, v71, v191
	v_add_u32_e32 v50, 0x4400, v126
	v_add_f32_e32 v12, v75, v191
	v_add_f32_e32 v13, v79, v191
	ds_write2_b32 v50, v49, v4 offset0:4 offset1:20
	v_mfma_f32_16x16x32_bf16 v[4:7], v[8:11], v[36:39], v[94:97]
	ds_write2_b32 v50, v12, v13 offset0:36 offset1:52
	v_ashrrev_i32_e32 v49, 31, v48
	v_lshl_add_u64 v[70:71], v[56:57], 0, s[36:37]
	v_mfma_f32_16x16x32_bf16 v[12:15], v[8:11], v[28:31], v[98:101]
	v_add_f32_e32 v28, v52, v192
	v_add_f32_e32 v29, v72, v192
	ds_write2_b32 v50, v28, v29 offset0:136 offset1:152
	v_mfma_f32_16x16x32_bf16 v[20:23], v[8:11], v[20:23], v[32:35]
	v_add_f32_e32 v28, v76, v192
	v_add_f32_e32 v29, v80, v192
	ds_write2_b32 v50, v28, v29 offset0:168 offset1:184
	v_mfma_f32_16x16x32_bf16 v[0:3], v[8:11], v[16:19], v[0:3]
	v_add_f32_e32 v8, v53, v193
	v_add_f32_e32 v9, v73, v193
	v_add_u32_e32 v16, 0x4800, v126
	v_mfma_f32_16x16x32_bf16 v[4:7], v[24:27], v[182:185], v[4:7]
	ds_write2_b32 v16, v8, v9 offset0:12 offset1:28
	v_add_f32_e32 v17, v77, v193
	v_add_f32_e32 v18, v81, v193
	v_mfma_f32_16x16x32_bf16 v[8:11], v[24:27], v[186:189], v[12:15]
	ds_write2_b32 v16, v17, v18 offset0:44 offset1:60
	s_waitcnt vmcnt(0)
; __device__ void gmlp_item(const Params& p, int layer, int b, int n, int g, char* smem) {
;     ...
;   {
;     float* Tf = reinterpret_cast<float*>(smem);
; #pragma unroll
;     for (int m = 0; m < 4; ++m)
; #pragma unroll
;       for (int j = 0; j < 4; ++j) {
;         int t = wr * 64 + m * 16 + fq * 4 + j;
;         float bias = p.gm_b_s[(size_t)layer * 512 + g * 128 + t];
; #pragma unroll
;         for (int nn = 0; nn < 4; ++nn) Tf[t * 132 + wc * 64 + nn * 16 + fr] = acc[m][nn][j] + bias;
;       }
;     __syncthreads();
;     uint4 uu[8], gt[8];
; #pragma unroll
;     for (int i = 0; i < 8; ++i) {
;       int q = tid + 256 * i, t = q >> 4, c = (q & 15) * 8;
;       uu[i] = *reinterpret_cast<const uint4*>(P + (t0 + t) * NP + g * 128 + c);
;       gt[i] = *reinterpret_cast<const uint4*>(P + (t0 + t) * NP + 1024 + g * 128 + c);
;     }
	s_nop 1
	v_add_f32_e32 v4, v4, v106
	v_add_u32_e32 v16, 0x6000, v126
	v_mfma_f32_16x16x32_bf16 v[12:15], v[24:27], v[44:47], v[20:23]
	v_lshl_add_u64 v[36:37], v[62:63], 0, s[36:37]
	v_add_f32_e32 v8, v8, v106
	ds_write2_b32 v16, v4, v8 offset0:192 offset1:208
	v_mfma_f32_16x16x32_bf16 v[0:3], v[24:27], v[40:43], v[0:3]
	v_lshl_add_u64 v[20:21], v[64:65], 0, s[36:37]
	s_nop 2
	v_add_f32_e32 v4, v12, v106
	v_lshl_add_u64 v[38:39], v[60:61], 0, s[36:37]
	s_nop 1
	v_add_f32_e32 v0, v0, v106
	ds_write2_b32 v16, v4, v0 offset0:224 offset1:240
	v_add_f32_e32 v0, v5, v107
	v_add_f32_e32 v4, v9, v107
	v_add_u32_e32 v5, 0x6400, v126
	ds_write2_b32 v5, v0, v4 offset0:68 offset1:84
	v_add_f32_e32 v0, v13, v107
	v_add_f32_e32 v1, v1, v107
	ds_write2_b32 v5, v0, v1 offset0:100 offset1:116
	v_add_f32_e32 v0, v6, v108
	v_add_f32_e32 v1, v10, v108
	ds_write2_b32 v5, v0, v1 offset0:200 offset1:216
	v_add_f32_e32 v0, v14, v108
	v_add_f32_e32 v1, v2, v108
	ds_write2_b32 v5, v0, v1 offset0:232 offset1:248
	v_add_f32_e32 v0, v7, v109
	v_add_f32_e32 v1, v11, v109
	v_add_u32_e32 v2, 0x6800, v126
	ds_write2_b32 v2, v0, v1 offset0:76 offset1:92
	v_add_f32_e32 v0, v15, v109
	v_add_f32_e32 v1, v3, v109
	ds_write2_b32 v2, v0, v1 offset0:108 offset1:124
	v_lshlrev_b32_e32 v0, 3, v59
	v_lshl_add_u64 v[8:9], v[48:49], 0, s[36:37]
	v_mov_b64_e32 v[10:11], s[12:13]
	v_and_b32_e32 v24, 0x78, v0
	v_mad_u64_u32 v[0:1], s[12:13], v8, s45, v[10:11]
	v_mad_i32_i24 v1, v9, s45, v1
	s_lshl_b32 s12, s16, 1
	s_mov_b32 s13, s37
	v_lshl_add_u64 v[0:1], v[0:1], 0, s[12:13]
	v_lshlrev_b32_e32 v128, 1, v24
	v_lshl_add_u64 v[12:13], v[68:69], 0, s[36:37]
	v_lshl_add_u64 v[52:53], v[0:1], 0, v[128:129]
	v_mad_u64_u32 v[0:1], s[14:15], v12, s45, v[10:11]
	v_mad_i32_i24 v1, v13, s45, v1
	v_lshl_add_u64 v[0:1], v[0:1], 0, s[12:13]
	v_lshl_add_u64 v[32:33], v[0:1], 0, v[128:129]
	v_mad_u64_u32 v[0:1], s[14:15], v70, s45, v[10:11]
	v_mad_i32_i24 v1, v71, s45, v1
	v_lshl_add_u64 v[0:1], v[0:1], 0, s[12:13]
	v_lshl_add_u64 v[4:5], v[0:1], 0, v[128:129]
	s_waitcnt lgkmcnt(0)
	s_barrier
	global_load_dwordx4 v[0:3], v[4:5], off
	s_nop 0
	global_load_dwordx4 v[4:7], v[4:5], off offset:2048
	v_lshl_add_u64 v[16:17], v[66:67], 0, s[36:37]
	v_mad_u64_u32 v[14:15], s[14:15], v16, s45, v[10:11]
	v_mad_i32_i24 v15, v17, s45, v15
	v_lshl_add_u64 v[14:15], v[14:15], 0, s[12:13]
	v_lshl_add_u64 v[30:31], v[14:15], 0, v[128:129]
	v_mad_u64_u32 v[14:15], s[14:15], v20, s45, v[10:11]
	v_mad_i32_i24 v15, v21, s45, v15
	v_lshl_add_u64 v[14:15], v[14:15], 0, s[12:13]
	v_lshl_add_u64 v[26:27], v[14:15], 0, v[128:129]
	v_mad_u64_u32 v[14:15], s[14:15], v36, s45, v[10:11]
	v_mad_i32_i24 v15, v37, s45, v15
	v_ashrrev_i32_e32 v59, 31, v58
	v_lshl_add_u64 v[14:15], v[14:15], 0, s[12:13]
	v_lshl_add_u64 v[72:73], v[58:59], 0, s[36:37]
	v_lshl_add_u64 v[22:23], v[14:15], 0, v[128:129]
	v_mad_u64_u32 v[14:15], s[14:15], v38, s45, v[10:11]
	v_mad_u64_u32 v[10:11], s[14:15], v72, s45, v[10:11]
	v_mad_i32_i24 v15, v39, s45, v15
	v_mad_i32_i24 v11, v73, s45, v11
	v_lshl_add_u64 v[14:15], v[14:15], 0, s[12:13]
	v_lshl_add_u64 v[10:11], v[10:11], 0, s[12:13]
	s_add_u32 s12, s17, s12
	s_addc_u32 s13, s20, 0
	v_lshl_add_u64 v[18:19], v[14:15], 0, v[128:129]
	v_lshl_add_u64 v[14:15], v[10:11], 0, v[128:129]
	v_lshlrev_b32_e32 v10, 2, v24
	v_lshl_add_u64 v[24:25], s[12:13], 0, v[128:129]
	v_lshl_add_u64 v[74:75], v[24:25], 0, s[40:41]
	v_mad_u64_u32 v[54:55], s[12:13], v48, s69, v[10:11]
	v_mad_u64_u32 v[48:49], s[12:13], v12, s70, v[74:75]
	v_mad_u64_u32 v[46:47], s[12:13], v16, s70, v[74:75]
	v_mad_u64_u32 v[50:51], s[12:13], v8, s70, v[74:75]
	v_mad_i32_i24 v49, v13, s70, v49
	v_mad_i32_i24 v47, v17, s70, v47
	v_mad_u64_u32 v[44:45], s[12:13], v20, s70, v[74:75]
	v_mad_u64_u32 v[16:17], s[12:13], v60, s69, v[10:11]
	v_mad_u64_u32 v[12:13], s[12:13], v58, s69, v[10:11]
	v_mad_i32_i24 v51, v9, s70, v51
	v_mad_i32_i24 v45, v21, s70, v45
	v_mad_u64_u32 v[20:21], s[12:13], v62, s69, v[10:11]
	v_mad_u64_u32 v[8:9], s[12:13], v56, s69, v[10:11]
	v_mad_u64_u32 v[28:29], s[12:13], v66, s69, v[10:11]
	v_mad_u64_u32 v[34:35], s[12:13], v68, s69, v[10:11]
	v_mad_u64_u32 v[24:25], s[12:13], v64, s69, v[10:11]
	v_mad_u64_u32 v[42:43], s[12:13], v36, s70, v[74:75]
	v_mad_i32_i24 v43, v37, s70, v43
	v_mad_u64_u32 v[36:37], s[12:13], v70, s70, v[74:75]
	v_mad_u64_u32 v[40:41], s[12:13], v38, s70, v[74:75]
	v_mad_i32_i24 v41, v39, s70, v41
	v_mad_u64_u32 v[38:39], s[12:13], v72, s70, v[74:75]
	v_mad_i32_i24 v39, v73, s70, v39
	v_mad_i32_i24 v37, v71, s70, v37
	s_waitcnt vmcnt(1)
	v_lshlrev_b32_e32 v63, 16, v1
	s_waitcnt vmcnt(0)
	v_lshlrev_b32_e32 v13, 16, v5
	v_lshlrev_b32_e32 v17, 16, v4
	v_mul_f32_e32 v9, 0xbfb8aa3b, v17
	v_and_b32_e32 v21, 0xffff0000, v5
	v_mul_f32_e32 v5, 0xbfb8aa3b, v13
	v_exp_f32_e32 v60, v9
	v_exp_f32_e32 v61, v5
	ds_read_b128 v[56:59], v8
	ds_read_b128 v[8:11], v8 offset:16
	v_and_b32_e32 v25, 0xffff0000, v4
	v_mul_f32_e32 v4, 0xbfb8aa3b, v25
	v_pk_add_f32 v[60:61], v[60:61], 1.0 op_sel_hi:[1,0]
	s_waitcnt lgkmcnt(1)
; __device__ __forceinline__ unsigned pack2(float a, float b) { return (unsigned)f2bf(a) | ((unsigned)f2bf(b) << 16); }
; __device__ __forceinline__ float bflo(unsigned w) { return __uint_as_float(w << 16); }
; __device__ __forceinline__ float bfhi(unsigned w) { return __uint_as_float(w & 0xffff0000u); }
; __device__ __forceinline__ float silu_f(float g) { return g / (1.f + __expf(-g)); }
; __device__ void gmlp_item(const Params& p, int layer, int b, int n, int g, char* smem) {
;     ...
;     uint4 uu[8], gt[8];
; #pragma unroll
;     for (int i = 0; i < 8; ++i) {
;       int q = tid + 256 * i, t = q >> 4, c = (q & 15) * 8;
;       uu[i] = *reinterpret_cast<const uint4*>(P + (t0 + t) * NP + g * 128 + c);
;       gt[i] = *reinterpret_cast<const uint4*>(P + (t0 + t) * NP + 1024 + g * 128 + c);
;     }
; #pragma unroll
;     for (int i = 0; i < 8; ++i) {
;       int q = tid + 256 * i, t = q >> 4, c = (q & 15) * 8;
;       float4 m0 = *reinterpret_cast<const float4*>(Tf + t * 132 + c);
;       float4 m1 = *reinterpret_cast<const float4*>(Tf + t * 132 + c + 4);
;       float mm[8] = {m0.x, m0.y, m0.z, m0.w, m1.x, m1.y, m1.z, m1.w};
;       unsigned uw[4] = {uu[i].x, uu[i].y, uu[i].z, uu[i].w};
;       unsigned gw[4] = {gt[i].x, gt[i].y, gt[i].z, gt[i].w};
;       unsigned ow[4];
; #pragma unroll
;       for (int e = 0; e < 4; ++e) {
;         float y0 = bflo(uw[e]) * mm[2 * e] * silu_f(bflo(gw[e]));
;         float y1 = bfhi(uw[e]) * mm[2 * e + 1] * silu_f(bfhi(gw[e]));
;         ow[e] = pack2(y0, y1);
;       }
;       *reinterpret_cast<uint4*>(Y + (t0 + t) * YW + g * 128 + c) = make_uint4(ow[0], ow[1], ow[2], ow[3]);
;     }
	v_mov_b32_e32 v64, v56
	v_exp_f32_e32 v4, v4
	v_lshlrev_b32_e32 v62, 16, v0
	v_mov_b32_e32 v65, v58
	v_rcp_f32_e32 v61, v61
	s_nop 0
	v_mul_f32_e32 v61, v13, v61
	v_and_b32_e32 v1, 0xffff0000, v1
	v_mul_f32_e32 v5, 0xbfb8aa3b, v21
	v_exp_f32_e32 v5, v5
	v_rcp_f32_e32 v60, v60
	s_nop 0
	v_mul_f32_e32 v60, v17, v60
	v_and_b32_e32 v0, 0xffff0000, v0
	v_mov_b32_e32 v58, v57
	v_pk_add_f32 v[4:5], v[4:5], 1.0 op_sel_hi:[1,0]
	v_pk_mul_f32 v[0:1], v[58:59], v[0:1]
	v_pk_mul_f32 v[62:63], v[64:65], v[62:63]
	v_rcp_f32_e32 v5, v5
	s_nop 0
	v_mul_f32_e32 v5, v21, v5
	v_pk_mul_f32 v[60:61], v[60:61], v[62:63]
	v_rcp_f32_e32 v4, v4
	s_nop 0
	v_mul_f32_e32 v4, v25, v4
	v_pk_mul_f32 v[0:1], v[4:5], v[0:1]
	v_and_b32_sdwa v4, v61, v155 dst_sel:DWORD dst_unused:UNUSED_PAD src0_sel:WORD_1 src1_sel:DWORD
	v_and_b32_sdwa v13, v1, v155 dst_sel:DWORD dst_unused:UNUSED_PAD src0_sel:WORD_1 src1_sel:DWORD
	v_and_b32_sdwa v17, v0, v155 dst_sel:DWORD dst_unused:UNUSED_PAD src0_sel:WORD_1 src1_sel:DWORD
	v_and_b32_sdwa v5, v60, v155 dst_sel:DWORD dst_unused:UNUSED_PAD src0_sel:WORD_1 src1_sel:DWORD
	v_add3_u32 v1, v1, v13, s68
	v_add3_u32 v0, v0, v17, s68
	v_add3_u32 v5, v60, v5, s68
	v_add3_u32 v4, v61, v4, s68
	v_and_b32_e32 v1, 0xffff0000, v1
	v_and_b32_e32 v0, 0xffff0000, v0
	v_lshlrev_b32_e32 v13, 16, v7
	v_lshlrev_b32_e32 v17, 16, v6
	v_or_b32_sdwa v1, v1, v4 dst_sel:DWORD dst_unused:UNUSED_PAD src0_sel:DWORD src1_sel:WORD_1
	v_or_b32_sdwa v0, v0, v5 dst_sel:DWORD dst_unused:UNUSED_PAD src0_sel:DWORD src1_sel:WORD_1
	v_mul_f32_e32 v4, 0xbfb8aa3b, v17
	v_mul_f32_e32 v5, 0xbfb8aa3b, v13
	v_exp_f32_e32 v4, v4
	v_exp_f32_e32 v5, v5
	v_and_b32_e32 v25, 0xffff0000, v6
	v_mul_f32_e32 v6, 0xbfb8aa3b, v25
	v_and_b32_e32 v21, 0xffff0000, v7
	v_exp_f32_e32 v60, v6
	v_pk_add_f32 v[64:65], v[4:5], 1.0 op_sel_hi:[1,0]
	global_load_dwordx4 v[4:7], v[14:15], off
	global_load_dwordx4 v[56:59], v[14:15], off offset:2048
	s_waitcnt lgkmcnt(0)
	v_mov_b32_e32 v14, v8
	v_mov_b32_e32 v15, v10
	v_lshlrev_b32_e32 v63, 16, v3
	v_lshlrev_b32_e32 v62, 16, v2
	v_pk_mul_f32 v[14:15], v[14:15], v[62:63]
	v_rcp_f32_e32 v63, v65
	s_nop 0
	v_mul_f32_e32 v63, v13, v63
	v_mul_f32_e32 v10, 0xbfb8aa3b, v21
	v_exp_f32_e32 v61, v10
	v_rcp_f32_e32 v62, v64
	s_nop 0
	v_mul_f32_e32 v62, v17, v62
	v_mov_b32_e32 v10, v9
	v_and_b32_e32 v3, 0xffff0000, v3
	v_pk_add_f32 v[60:61], v[60:61], 1.0 op_sel_hi:[1,0]
	v_and_b32_e32 v2, 0xffff0000, v2
	v_pk_mul_f32 v[2:3], v[10:11], v[2:3]
	v_pk_mul_f32 v[14:15], v[62:63], v[14:15]
	v_rcp_f32_e32 v9, v61
	s_nop 0
	v_mul_f32_e32 v9, v21, v9
	v_rcp_f32_e32 v8, v60
	s_nop 0
	v_mul_f32_e32 v8, v25, v8
	v_pk_mul_f32 v[2:3], v[8:9], v[2:3]
	v_and_b32_sdwa v8, v15, v155 dst_sel:DWORD dst_unused:UNUSED_PAD src0_sel:WORD_1 src1_sel:DWORD
	v_and_b32_sdwa v10, v3, v155 dst_sel:DWORD dst_unused:UNUSED_PAD src0_sel:WORD_1 src1_sel:DWORD
	v_add3_u32 v3, v3, v10, s68
	v_add3_u32 v8, v15, v8, s68
	v_and_b32_e32 v3, 0xffff0000, v3
	v_or_b32_sdwa v3, v3, v8 dst_sel:DWORD dst_unused:UNUSED_PAD src0_sel:DWORD src1_sel:WORD_1
	v_and_b32_sdwa v11, v2, v155 dst_sel:DWORD dst_unused:UNUSED_PAD src0_sel:WORD_1 src1_sel:DWORD
	v_and_b32_sdwa v9, v14, v155 dst_sel:DWORD dst_unused:UNUSED_PAD src0_sel:WORD_1 src1_sel:DWORD
	v_add3_u32 v2, v2, v11, s68
	v_add3_u32 v9, v14, v9, s68
	v_and_b32_e32 v2, 0xffff0000, v2
	v_or_b32_sdwa v2, v2, v9 dst_sel:DWORD dst_unused:UNUSED_PAD src0_sel:DWORD src1_sel:WORD_1
	s_waitcnt vmcnt(0)
	v_lshlrev_b32_e32 v21, 16, v56
	v_mul_f32_e32 v8, 0xbfb8aa3b, v21
	v_and_b32_e32 v29, 0xffff0000, v56
	v_lshlrev_b32_e32 v17, 16, v57
	v_exp_f32_e32 v60, v8
	v_mul_f32_e32 v8, 0xbfb8aa3b, v29
	v_exp_f32_e32 v56, v8
	v_mul_f32_e32 v8, 0xbfb8aa3b, v17
	v_exp_f32_e32 v61, v8
	ds_read_b128 v[8:11], v12
	ds_read_b128 v[12:15], v12 offset:16
	v_and_b32_e32 v25, 0xffff0000, v57
	v_lshlrev_b32_e32 v63, 16, v5
	v_pk_add_f32 v[60:61], v[60:61], 1.0 op_sel_hi:[1,0]
	s_waitcnt lgkmcnt(1)
	v_mov_b32_e32 v64, v8
	v_mov_b32_e32 v65, v10
	v_lshlrev_b32_e32 v62, 16, v4
	v_and_b32_e32 v5, 0xffff0000, v5
	v_rcp_f32_e32 v61, v61
	s_nop 0
	v_mul_f32_e32 v61, v17, v61
	v_and_b32_e32 v4, 0xffff0000, v4
	v_mul_f32_e32 v10, 0xbfb8aa3b, v25
	v_exp_f32_e32 v57, v10
	v_rcp_f32_e32 v60, v60
	s_nop 0
	v_mul_f32_e32 v60, v21, v60
	v_mov_b32_e32 v10, v9
	v_pk_mul_f32 v[4:5], v[10:11], v[4:5]
	v_pk_add_f32 v[56:57], v[56:57], 1.0 op_sel_hi:[1,0]
	v_pk_mul_f32 v[62:63], v[64:65], v[62:63]
	v_pk_mul_f32 v[60:61], v[60:61], v[62:63]
	v_lshlrev_b32_e32 v63, 16, v7
	v_lshlrev_b32_e32 v62, 16, v6
	v_rcp_f32_e32 v9, v57
	s_nop 0
	v_mul_f32_e32 v9, v25, v9
	v_rcp_f32_e32 v8, v56
	s_nop 0
	v_mul_f32_e32 v8, v29, v8
	v_pk_mul_f32 v[4:5], v[8:9], v[4:5]
	v_and_b32_sdwa v8, v61, v155 dst_sel:DWORD dst_unused:UNUSED_PAD src0_sel:WORD_1 src1_sel:DWORD
	v_and_b32_sdwa v10, v5, v155 dst_sel:DWORD dst_unused:UNUSED_PAD src0_sel:WORD_1 src1_sel:DWORD
	v_and_b32_sdwa v11, v4, v155 dst_sel:DWORD dst_unused:UNUSED_PAD src0_sel:WORD_1 src1_sel:DWORD
	v_and_b32_sdwa v9, v60, v155 dst_sel:DWORD dst_unused:UNUSED_PAD src0_sel:WORD_1 src1_sel:DWORD
	v_add3_u32 v5, v5, v10, s68
	v_add3_u32 v4, v4, v11, s68
	v_add3_u32 v9, v60, v9, s68
	v_add3_u32 v8, v61, v8, s68
	v_and_b32_e32 v5, 0xffff0000, v5
	v_and_b32_e32 v4, 0xffff0000, v4
	v_lshlrev_b32_e32 v17, 16, v59
	v_lshlrev_b32_e32 v21, 16, v58
	v_or_b32_sdwa v5, v5, v8 dst_sel:DWORD dst_unused:UNUSED_PAD src0_sel:DWORD src1_sel:WORD_1
	v_or_b32_sdwa v4, v4, v9 dst_sel:DWORD dst_unused:UNUSED_PAD src0_sel:DWORD src1_sel:WORD_1
	v_mul_f32_e32 v8, 0xbfb8aa3b, v21
	v_mul_f32_e32 v9, 0xbfb8aa3b, v17
	v_exp_f32_e32 v8, v8
	v_exp_f32_e32 v9, v9
	v_and_b32_e32 v29, 0xffff0000, v58
	v_mul_f32_e32 v10, 0xbfb8aa3b, v29
	v_and_b32_e32 v25, 0xffff0000, v59
	v_exp_f32_e32 v60, v10
	v_pk_add_f32 v[64:65], v[8:9], 1.0 op_sel_hi:[1,0]
	global_load_dwordx4 v[8:11], v[18:19], off
	global_load_dwordx4 v[56:59], v[18:19], off offset:2048
	s_waitcnt lgkmcnt(0)
; __device__ __forceinline__ unsigned pack2(float a, float b) { return (unsigned)f2bf(a) | ((unsigned)f2bf(b) << 16); }
; __device__ __forceinline__ float bflo(unsigned w) { return __uint_as_float(w << 16); }
; __device__ __forceinline__ float bfhi(unsigned w) { return __uint_as_float(w & 0xffff0000u); }
; __device__ __forceinline__ float silu_f(float g) { return g / (1.f + __expf(-g)); }
; __device__ void gmlp_item(const Params& p, int layer, int b, int n, int g, char* smem) {
;     ...
;     uint4 uu[8], gt[8];
; #pragma unroll
;     for (int i = 0; i < 8; ++i) {
;       int q = tid + 256 * i, t = q >> 4, c = (q & 15) * 8;
;       uu[i] = *reinterpret_cast<const uint4*>(P + (t0 + t) * NP + g * 128 + c);
;       gt[i] = *reinterpret_cast<const uint4*>(P + (t0 + t) * NP + 1024 + g * 128 + c);
;     }
; #pragma unroll
;     for (int i = 0; i < 8; ++i) {
;       int q = tid + 256 * i, t = q >> 4, c = (q & 15) * 8;
;       float4 m0 = *reinterpret_cast<const float4*>(Tf + t * 132 + c);
;       float4 m1 = *reinterpret_cast<const float4*>(Tf + t * 132 + c + 4);
;       float mm[8] = {m0.x, m0.y, m0.z, m0.w, m1.x, m1.y, m1.z, m1.w};
;       unsigned uw[4] = {uu[i].x, uu[i].y, uu[i].z, uu[i].w};
;       unsigned gw[4] = {gt[i].x, gt[i].y, gt[i].z, gt[i].w};
;       unsigned ow[4];
; #pragma unroll
;       for (int e = 0; e < 4; ++e) {
;         float y0 = bflo(uw[e]) * mm[2 * e] * silu_f(bflo(gw[e]));
;         float y1 = bfhi(uw[e]) * mm[2 * e + 1] * silu_f(bfhi(gw[e]));
;         ow[e] = pack2(y0, y1);
;       }
;       *reinterpret_cast<uint4*>(Y + (t0 + t) * YW + g * 128 + c) = make_uint4(ow[0], ow[1], ow[2], ow[3]);
;     }
	v_mov_b32_e32 v18, v12
	v_mov_b32_e32 v19, v14
	v_pk_mul_f32 v[18:19], v[18:19], v[62:63]
	v_rcp_f32_e32 v63, v65
	s_nop 0
	v_mul_f32_e32 v63, v17, v63
	v_and_b32_e32 v7, 0xffff0000, v7
	v_mul_f32_e32 v14, 0xbfb8aa3b, v25
	v_exp_f32_e32 v61, v14
	v_rcp_f32_e32 v62, v64
	s_nop 0
	v_mul_f32_e32 v62, v21, v62
	v_mov_b32_e32 v14, v13
	v_and_b32_e32 v6, 0xffff0000, v6
	v_pk_add_f32 v[60:61], v[60:61], 1.0 op_sel_hi:[1,0]
	v_pk_mul_f32 v[6:7], v[14:15], v[6:7]
	v_pk_mul_f32 v[18:19], v[62:63], v[18:19]
	v_rcp_f32_e32 v13, v61
	s_nop 0
	v_mul_f32_e32 v13, v25, v13
	v_rcp_f32_e32 v12, v60
	s_nop 0
	v_mul_f32_e32 v12, v29, v12
	v_pk_mul_f32 v[6:7], v[12:13], v[6:7]
	v_and_b32_sdwa v12, v19, v155 dst_sel:DWORD dst_unused:UNUSED_PAD src0_sel:WORD_1 src1_sel:DWORD
	v_and_b32_sdwa v14, v7, v155 dst_sel:DWORD dst_unused:UNUSED_PAD src0_sel:WORD_1 src1_sel:DWORD
	v_add3_u32 v7, v7, v14, s68
	v_add3_u32 v12, v19, v12, s68
	v_and_b32_e32 v7, 0xffff0000, v7
	v_or_b32_sdwa v7, v7, v12 dst_sel:DWORD dst_unused:UNUSED_PAD src0_sel:DWORD src1_sel:WORD_1
	v_and_b32_sdwa v15, v6, v155 dst_sel:DWORD dst_unused:UNUSED_PAD src0_sel:WORD_1 src1_sel:DWORD
	v_and_b32_sdwa v13, v18, v155 dst_sel:DWORD dst_unused:UNUSED_PAD src0_sel:WORD_1 src1_sel:DWORD
	v_add3_u32 v6, v6, v15, s68
	v_add3_u32 v13, v18, v13, s68
	v_and_b32_e32 v6, 0xffff0000, v6
	v_or_b32_sdwa v6, v6, v13 dst_sel:DWORD dst_unused:UNUSED_PAD src0_sel:DWORD src1_sel:WORD_1
	s_waitcnt vmcnt(1)
	v_lshlrev_b32_e32 v63, 16, v9
	s_waitcnt vmcnt(0)
	v_lshlrev_b32_e32 v25, 16, v56
	v_mul_f32_e32 v12, 0xbfb8aa3b, v25
	v_and_b32_e32 v35, 0xffff0000, v56
	v_lshlrev_b32_e32 v21, 16, v57
	v_exp_f32_e32 v60, v12
	v_mul_f32_e32 v12, 0xbfb8aa3b, v35
	v_exp_f32_e32 v56, v12
	v_mul_f32_e32 v12, 0xbfb8aa3b, v21
	v_exp_f32_e32 v61, v12
	v_and_b32_e32 v29, 0xffff0000, v57
	ds_read_b128 v[12:15], v16
	ds_read_b128 v[16:19], v16 offset:16
	v_lshlrev_b32_e32 v62, 16, v8
	v_pk_add_f32 v[60:61], v[60:61], 1.0 op_sel_hi:[1,0]
	v_and_b32_e32 v9, 0xffff0000, v9
	s_waitcnt lgkmcnt(1)
	v_mov_b32_e32 v64, v12
	v_mov_b32_e32 v65, v14
	v_pk_mul_f32 v[62:63], v[64:65], v[62:63]
	v_rcp_f32_e32 v61, v61
	s_nop 0
	v_mul_f32_e32 v61, v21, v61
	v_and_b32_e32 v8, 0xffff0000, v8
	v_mul_f32_e32 v14, 0xbfb8aa3b, v29
	v_exp_f32_e32 v57, v14
	v_rcp_f32_e32 v60, v60
	s_nop 0
	v_mul_f32_e32 v60, v25, v60
	v_mov_b32_e32 v14, v13
	v_pk_mul_f32 v[8:9], v[14:15], v[8:9]
	v_pk_add_f32 v[56:57], v[56:57], 1.0 op_sel_hi:[1,0]
	v_pk_mul_f32 v[60:61], v[60:61], v[62:63]
	v_lshlrev_b32_e32 v63, 16, v11
	v_lshlrev_b32_e32 v62, 16, v10
	v_and_b32_e32 v11, 0xffff0000, v11
	v_rcp_f32_e32 v13, v57
	s_nop 0
	v_mul_f32_e32 v13, v29, v13
	v_rcp_f32_e32 v12, v56
	s_nop 0
	v_mul_f32_e32 v12, v35, v12
	v_pk_mul_f32 v[8:9], v[12:13], v[8:9]
	v_and_b32_sdwa v12, v61, v155 dst_sel:DWORD dst_unused:UNUSED_PAD src0_sel:WORD_1 src1_sel:DWORD
	v_and_b32_sdwa v14, v9, v155 dst_sel:DWORD dst_unused:UNUSED_PAD src0_sel:WORD_1 src1_sel:DWORD
	v_and_b32_sdwa v15, v8, v155 dst_sel:DWORD dst_unused:UNUSED_PAD src0_sel:WORD_1 src1_sel:DWORD
	v_and_b32_sdwa v13, v60, v155 dst_sel:DWORD dst_unused:UNUSED_PAD src0_sel:WORD_1 src1_sel:DWORD
	v_add3_u32 v9, v9, v14, s68
	v_add3_u32 v8, v8, v15, s68
	v_add3_u32 v13, v60, v13, s68
	v_add3_u32 v12, v61, v12, s68
	v_and_b32_e32 v9, 0xffff0000, v9
	v_and_b32_e32 v8, 0xffff0000, v8
	v_lshlrev_b32_e32 v21, 16, v59
	v_lshlrev_b32_e32 v25, 16, v58
	v_or_b32_sdwa v9, v9, v12 dst_sel:DWORD dst_unused:UNUSED_PAD src0_sel:DWORD src1_sel:WORD_1
	v_or_b32_sdwa v8, v8, v13 dst_sel:DWORD dst_unused:UNUSED_PAD src0_sel:DWORD src1_sel:WORD_1
	v_mul_f32_e32 v12, 0xbfb8aa3b, v25
	v_mul_f32_e32 v13, 0xbfb8aa3b, v21
	v_exp_f32_e32 v12, v12
	v_exp_f32_e32 v13, v13
	v_and_b32_e32 v35, 0xffff0000, v58
	v_mul_f32_e32 v14, 0xbfb8aa3b, v35
	v_and_b32_e32 v29, 0xffff0000, v59
	v_exp_f32_e32 v60, v14
	v_pk_add_f32 v[64:65], v[12:13], 1.0 op_sel_hi:[1,0]
	global_load_dwordx4 v[12:15], v[22:23], off
	global_load_dwordx4 v[56:59], v[22:23], off offset:2048
	s_waitcnt lgkmcnt(0)
	v_mov_b32_e32 v22, v16
	v_mov_b32_e32 v23, v18
	v_pk_mul_f32 v[22:23], v[22:23], v[62:63]
	v_rcp_f32_e32 v63, v65
	s_nop 0
	v_mul_f32_e32 v63, v21, v63
	v_and_b32_e32 v10, 0xffff0000, v10
	v_mul_f32_e32 v18, 0xbfb8aa3b, v29
	v_exp_f32_e32 v61, v18
	v_rcp_f32_e32 v62, v64
	s_nop 0
	v_mul_f32_e32 v62, v25, v62
	v_mov_b32_e32 v18, v17
	v_pk_mul_f32 v[10:11], v[18:19], v[10:11]
	v_pk_add_f32 v[60:61], v[60:61], 1.0 op_sel_hi:[1,0]
	v_pk_mul_f32 v[22:23], v[62:63], v[22:23]
	s_waitcnt vmcnt(1)
	v_lshlrev_b32_e32 v63, 16, v13
	v_rcp_f32_e32 v17, v61
	s_nop 0
	v_mul_f32_e32 v17, v29, v17
	v_rcp_f32_e32 v16, v60
	s_nop 0
	v_mul_f32_e32 v16, v35, v16
	v_pk_mul_f32 v[10:11], v[16:17], v[10:11]
	v_and_b32_sdwa v16, v23, v155 dst_sel:DWORD dst_unused:UNUSED_PAD src0_sel:WORD_1 src1_sel:DWORD
	v_and_b32_sdwa v18, v11, v155 dst_sel:DWORD dst_unused:UNUSED_PAD src0_sel:WORD_1 src1_sel:DWORD
	v_add3_u32 v11, v11, v18, s68
	v_add3_u32 v16, v23, v16, s68
	v_and_b32_e32 v11, 0xffff0000, v11
	s_waitcnt vmcnt(0)
	v_lshlrev_b32_e32 v29, 16, v56
	v_or_b32_sdwa v11, v11, v16 dst_sel:DWORD dst_unused:UNUSED_PAD src0_sel:DWORD src1_sel:WORD_1
	v_mul_f32_e32 v16, 0xbfb8aa3b, v29
	v_and_b32_e32 v55, 0xffff0000, v56
	v_lshlrev_b32_e32 v25, 16, v57
	v_exp_f32_e32 v60, v16
	v_mul_f32_e32 v16, 0xbfb8aa3b, v55
	v_exp_f32_e32 v56, v16
	v_mul_f32_e32 v16, 0xbfb8aa3b, v25
	v_exp_f32_e32 v61, v16
	v_and_b32_sdwa v19, v10, v155 dst_sel:DWORD dst_unused:UNUSED_PAD src0_sel:WORD_1 src1_sel:DWORD
	v_and_b32_sdwa v17, v22, v155 dst_sel:DWORD dst_unused:UNUSED_PAD src0_sel:WORD_1 src1_sel:DWORD
	v_add3_u32 v10, v10, v19, s68
	v_pk_add_f32 v[60:61], v[60:61], 1.0 op_sel_hi:[1,0]
	v_add3_u32 v17, v22, v17, s68
	v_and_b32_e32 v10, 0xffff0000, v10
	v_and_b32_e32 v35, 0xffff0000, v57
	v_or_b32_sdwa v10, v10, v17 dst_sel:DWORD dst_unused:UNUSED_PAD src0_sel:DWORD src1_sel:WORD_1
	ds_read_b128 v[16:19], v20
	ds_read_b128 v[20:23], v20 offset:16
	v_lshlrev_b32_e32 v62, 16, v12
	v_and_b32_e32 v13, 0xffff0000, v13
	s_waitcnt lgkmcnt(1)
; __device__ __forceinline__ unsigned pack2(float a, float b) { return (unsigned)f2bf(a) | ((unsigned)f2bf(b) << 16); }
; __device__ __forceinline__ float bflo(unsigned w) { return __uint_as_float(w << 16); }
; __device__ __forceinline__ float bfhi(unsigned w) { return __uint_as_float(w & 0xffff0000u); }
; __device__ __forceinline__ float silu_f(float g) { return g / (1.f + __expf(-g)); }
; __device__ void gmlp_item(const Params& p, int layer, int b, int n, int g, char* smem) {
;     ...
;     uint4 uu[8], gt[8];
; #pragma unroll
;     for (int i = 0; i < 8; ++i) {
;       int q = tid + 256 * i, t = q >> 4, c = (q & 15) * 8;
;       uu[i] = *reinterpret_cast<const uint4*>(P + (t0 + t) * NP + g * 128 + c);
;       gt[i] = *reinterpret_cast<const uint4*>(P + (t0 + t) * NP + 1024 + g * 128 + c);
;     }
; #pragma unroll
;     for (int i = 0; i < 8; ++i) {
;       int q = tid + 256 * i, t = q >> 4, c = (q & 15) * 8;
;       float4 m0 = *reinterpret_cast<const float4*>(Tf + t * 132 + c);
;       float4 m1 = *reinterpret_cast<const float4*>(Tf + t * 132 + c + 4);
;       float mm[8] = {m0.x, m0.y, m0.z, m0.w, m1.x, m1.y, m1.z, m1.w};
;       unsigned uw[4] = {uu[i].x, uu[i].y, uu[i].z, uu[i].w};
;       unsigned gw[4] = {gt[i].x, gt[i].y, gt[i].z, gt[i].w};
;       unsigned ow[4];
; #pragma unroll
;       for (int e = 0; e < 4; ++e) {
;         float y0 = bflo(uw[e]) * mm[2 * e] * silu_f(bflo(gw[e]));
;         float y1 = bfhi(uw[e]) * mm[2 * e + 1] * silu_f(bfhi(gw[e]));
;         ow[e] = pack2(y0, y1);
;       }
;       *reinterpret_cast<uint4*>(Y + (t0 + t) * YW + g * 128 + c) = make_uint4(ow[0], ow[1], ow[2], ow[3]);
;     }
	v_mov_b32_e32 v64, v16
	v_mov_b32_e32 v65, v18
	v_pk_mul_f32 v[62:63], v[64:65], v[62:63]
	v_rcp_f32_e32 v61, v61
	s_nop 0
	v_mul_f32_e32 v61, v25, v61
	v_and_b32_e32 v12, 0xffff0000, v12
	v_mul_f32_e32 v18, 0xbfb8aa3b, v35
	v_exp_f32_e32 v57, v18
	v_rcp_f32_e32 v60, v60
	s_nop 0
	v_mul_f32_e32 v60, v29, v60
	v_mov_b32_e32 v18, v17
	v_pk_mul_f32 v[12:13], v[18:19], v[12:13]
	v_pk_add_f32 v[56:57], v[56:57], 1.0 op_sel_hi:[1,0]
	v_pk_mul_f32 v[60:61], v[60:61], v[62:63]
	v_lshlrev_b32_e32 v63, 16, v15
	v_lshlrev_b32_e32 v62, 16, v14
	v_and_b32_e32 v15, 0xffff0000, v15
	v_rcp_f32_e32 v17, v57
	s_nop 0
	v_mul_f32_e32 v17, v35, v17
	v_rcp_f32_e32 v16, v56
	s_nop 0
	v_mul_f32_e32 v16, v55, v16
	v_pk_mul_f32 v[12:13], v[16:17], v[12:13]
	v_and_b32_sdwa v16, v61, v155 dst_sel:DWORD dst_unused:UNUSED_PAD src0_sel:WORD_1 src1_sel:DWORD
	v_and_b32_sdwa v18, v13, v155 dst_sel:DWORD dst_unused:UNUSED_PAD src0_sel:WORD_1 src1_sel:DWORD
	v_and_b32_sdwa v19, v12, v155 dst_sel:DWORD dst_unused:UNUSED_PAD src0_sel:WORD_1 src1_sel:DWORD
	v_and_b32_sdwa v17, v60, v155 dst_sel:DWORD dst_unused:UNUSED_PAD src0_sel:WORD_1 src1_sel:DWORD
	v_add3_u32 v13, v13, v18, s68
	v_add3_u32 v12, v12, v19, s68
	v_add3_u32 v17, v60, v17, s68
	v_add3_u32 v16, v61, v16, s68
	v_and_b32_e32 v13, 0xffff0000, v13
	v_and_b32_e32 v12, 0xffff0000, v12
	v_lshlrev_b32_e32 v25, 16, v59
	v_lshlrev_b32_e32 v29, 16, v58
	v_or_b32_sdwa v13, v13, v16 dst_sel:DWORD dst_unused:UNUSED_PAD src0_sel:DWORD src1_sel:WORD_1
	v_or_b32_sdwa v12, v12, v17 dst_sel:DWORD dst_unused:UNUSED_PAD src0_sel:DWORD src1_sel:WORD_1
	v_mul_f32_e32 v16, 0xbfb8aa3b, v29
	v_mul_f32_e32 v17, 0xbfb8aa3b, v25
	v_exp_f32_e32 v16, v16
	v_exp_f32_e32 v17, v17
	v_and_b32_e32 v55, 0xffff0000, v58
	v_mul_f32_e32 v18, 0xbfb8aa3b, v55
	v_and_b32_e32 v35, 0xffff0000, v59
	v_exp_f32_e32 v60, v18
	v_pk_add_f32 v[64:65], v[16:17], 1.0 op_sel_hi:[1,0]
	global_load_dwordx4 v[16:19], v[26:27], off
	global_load_dwordx4 v[56:59], v[26:27], off offset:2048
	s_waitcnt lgkmcnt(0)
	v_mov_b32_e32 v26, v20
	v_mov_b32_e32 v27, v22
	v_pk_mul_f32 v[26:27], v[26:27], v[62:63]
	v_rcp_f32_e32 v63, v65
	s_nop 0
	v_mul_f32_e32 v63, v25, v63
	v_and_b32_e32 v14, 0xffff0000, v14
	v_mul_f32_e32 v22, 0xbfb8aa3b, v35
	v_exp_f32_e32 v61, v22
	v_rcp_f32_e32 v62, v64
	s_nop 0
	v_mul_f32_e32 v62, v29, v62
	v_mov_b32_e32 v22, v21
	v_pk_mul_f32 v[14:15], v[22:23], v[14:15]
	v_pk_add_f32 v[60:61], v[60:61], 1.0 op_sel_hi:[1,0]
	v_pk_mul_f32 v[26:27], v[62:63], v[26:27]
	s_waitcnt vmcnt(1)
	v_lshlrev_b32_e32 v63, 16, v17
	v_rcp_f32_e32 v21, v61
	s_nop 0
	v_mul_f32_e32 v21, v35, v21
	v_rcp_f32_e32 v20, v60
	s_nop 0
	v_mul_f32_e32 v20, v55, v20
	v_pk_mul_f32 v[14:15], v[20:21], v[14:15]
	v_and_b32_sdwa v20, v27, v155 dst_sel:DWORD dst_unused:UNUSED_PAD src0_sel:WORD_1 src1_sel:DWORD
	v_and_b32_sdwa v22, v15, v155 dst_sel:DWORD dst_unused:UNUSED_PAD src0_sel:WORD_1 src1_sel:DWORD
	v_add3_u32 v15, v15, v22, s68
	v_add3_u32 v20, v27, v20, s68
	v_and_b32_e32 v15, 0xffff0000, v15
	s_waitcnt vmcnt(0)
	v_lshlrev_b32_e32 v35, 16, v56
	v_or_b32_sdwa v15, v15, v20 dst_sel:DWORD dst_unused:UNUSED_PAD src0_sel:DWORD src1_sel:WORD_1
	v_mul_f32_e32 v20, 0xbfb8aa3b, v35
	v_and_b32_e32 v66, 0xffff0000, v56
	v_lshlrev_b32_e32 v29, 16, v57
	v_exp_f32_e32 v60, v20
	v_mul_f32_e32 v20, 0xbfb8aa3b, v66
	v_exp_f32_e32 v56, v20
	v_mul_f32_e32 v20, 0xbfb8aa3b, v29
	v_exp_f32_e32 v61, v20
	v_and_b32_sdwa v23, v14, v155 dst_sel:DWORD dst_unused:UNUSED_PAD src0_sel:WORD_1 src1_sel:DWORD
	v_and_b32_sdwa v21, v26, v155 dst_sel:DWORD dst_unused:UNUSED_PAD src0_sel:WORD_1 src1_sel:DWORD
	v_add3_u32 v14, v14, v23, s68
	v_pk_add_f32 v[60:61], v[60:61], 1.0 op_sel_hi:[1,0]
	v_add3_u32 v21, v26, v21, s68
	v_and_b32_e32 v14, 0xffff0000, v14
	v_and_b32_e32 v55, 0xffff0000, v57
	v_or_b32_sdwa v14, v14, v21 dst_sel:DWORD dst_unused:UNUSED_PAD src0_sel:DWORD src1_sel:WORD_1
	ds_read_b128 v[20:23], v24
	ds_read_b128 v[24:27], v24 offset:16
	v_lshlrev_b32_e32 v62, 16, v16
	v_and_b32_e32 v17, 0xffff0000, v17
	s_waitcnt lgkmcnt(1)
	v_mov_b32_e32 v64, v20
	v_mov_b32_e32 v65, v22
	v_pk_mul_f32 v[62:63], v[64:65], v[62:63]
	v_rcp_f32_e32 v61, v61
	s_nop 0
	v_mul_f32_e32 v61, v29, v61
	v_and_b32_e32 v16, 0xffff0000, v16
	v_mul_f32_e32 v22, 0xbfb8aa3b, v55
	v_exp_f32_e32 v57, v22
	v_rcp_f32_e32 v60, v60
	s_nop 0
	v_mul_f32_e32 v60, v35, v60
	v_mov_b32_e32 v22, v21
	v_pk_mul_f32 v[16:17], v[22:23], v[16:17]
	v_pk_add_f32 v[56:57], v[56:57], 1.0 op_sel_hi:[1,0]
	v_pk_mul_f32 v[60:61], v[60:61], v[62:63]
	v_lshlrev_b32_e32 v63, 16, v19
	v_lshlrev_b32_e32 v62, 16, v18
	v_and_b32_e32 v19, 0xffff0000, v19
	v_rcp_f32_e32 v21, v57
	s_nop 0
	v_mul_f32_e32 v21, v55, v21
	v_rcp_f32_e32 v20, v56
	s_nop 0
	v_mul_f32_e32 v20, v66, v20
	v_pk_mul_f32 v[16:17], v[20:21], v[16:17]
	v_and_b32_sdwa v20, v61, v155 dst_sel:DWORD dst_unused:UNUSED_PAD src0_sel:WORD_1 src1_sel:DWORD
	v_and_b32_sdwa v22, v17, v155 dst_sel:DWORD dst_unused:UNUSED_PAD src0_sel:WORD_1 src1_sel:DWORD
	v_and_b32_sdwa v23, v16, v155 dst_sel:DWORD dst_unused:UNUSED_PAD src0_sel:WORD_1 src1_sel:DWORD
	v_and_b32_sdwa v21, v60, v155 dst_sel:DWORD dst_unused:UNUSED_PAD src0_sel:WORD_1 src1_sel:DWORD
	v_add3_u32 v17, v17, v22, s68
	v_add3_u32 v16, v16, v23, s68
	v_add3_u32 v21, v60, v21, s68
	v_add3_u32 v20, v61, v20, s68
	v_and_b32_e32 v17, 0xffff0000, v17
	v_and_b32_e32 v16, 0xffff0000, v16
	v_lshlrev_b32_e32 v29, 16, v59
	v_lshlrev_b32_e32 v35, 16, v58
	v_or_b32_sdwa v17, v17, v20 dst_sel:DWORD dst_unused:UNUSED_PAD src0_sel:DWORD src1_sel:WORD_1
	v_or_b32_sdwa v16, v16, v21 dst_sel:DWORD dst_unused:UNUSED_PAD src0_sel:DWORD src1_sel:WORD_1
	v_mul_f32_e32 v20, 0xbfb8aa3b, v35
	v_mul_f32_e32 v21, 0xbfb8aa3b, v29
	v_exp_f32_e32 v20, v20
	v_exp_f32_e32 v21, v21
	v_and_b32_e32 v66, 0xffff0000, v58
	v_mul_f32_e32 v22, 0xbfb8aa3b, v66
	v_and_b32_e32 v55, 0xffff0000, v59
	v_exp_f32_e32 v60, v22
	v_pk_add_f32 v[64:65], v[20:21], 1.0 op_sel_hi:[1,0]
	global_load_dwordx4 v[20:23], v[30:31], off
	global_load_dwordx4 v[56:59], v[30:31], off offset:2048
	s_waitcnt lgkmcnt(0)
; __device__ __forceinline__ unsigned pack2(float a, float b) { return (unsigned)f2bf(a) | ((unsigned)f2bf(b) << 16); }
; __device__ __forceinline__ float bflo(unsigned w) { return __uint_as_float(w << 16); }
; __device__ __forceinline__ float bfhi(unsigned w) { return __uint_as_float(w & 0xffff0000u); }
; __device__ __forceinline__ float silu_f(float g) { return g / (1.f + __expf(-g)); }
; __device__ void gmlp_item(const Params& p, int layer, int b, int n, int g, char* smem) {
;     ...
;     uint4 uu[8], gt[8];
; #pragma unroll
;     for (int i = 0; i < 8; ++i) {
;       int q = tid + 256 * i, t = q >> 4, c = (q & 15) * 8;
;       uu[i] = *reinterpret_cast<const uint4*>(P + (t0 + t) * NP + g * 128 + c);
;       gt[i] = *reinterpret_cast<const uint4*>(P + (t0 + t) * NP + 1024 + g * 128 + c);
;     }
; #pragma unroll
;     for (int i = 0; i < 8; ++i) {
;       int q = tid + 256 * i, t = q >> 4, c = (q & 15) * 8;
;       float4 m0 = *reinterpret_cast<const float4*>(Tf + t * 132 + c);
;       float4 m1 = *reinterpret_cast<const float4*>(Tf + t * 132 + c + 4);
;       float mm[8] = {m0.x, m0.y, m0.z, m0.w, m1.x, m1.y, m1.z, m1.w};
;       unsigned uw[4] = {uu[i].x, uu[i].y, uu[i].z, uu[i].w};
;       unsigned gw[4] = {gt[i].x, gt[i].y, gt[i].z, gt[i].w};
;       unsigned ow[4];
; #pragma unroll
;       for (int e = 0; e < 4; ++e) {
;         float y0 = bflo(uw[e]) * mm[2 * e] * silu_f(bflo(gw[e]));
;         float y1 = bfhi(uw[e]) * mm[2 * e + 1] * silu_f(bfhi(gw[e]));
;         ow[e] = pack2(y0, y1);
;       }
;       *reinterpret_cast<uint4*>(Y + (t0 + t) * YW + g * 128 + c) = make_uint4(ow[0], ow[1], ow[2], ow[3]);
;     }
	v_mov_b32_e32 v30, v24
	v_mov_b32_e32 v31, v26
	v_pk_mul_f32 v[30:31], v[30:31], v[62:63]
	v_rcp_f32_e32 v63, v65
	s_nop 0
	v_mul_f32_e32 v63, v29, v63
	v_and_b32_e32 v18, 0xffff0000, v18
	v_mul_f32_e32 v26, 0xbfb8aa3b, v55
	v_exp_f32_e32 v61, v26
	v_rcp_f32_e32 v62, v64
	s_nop 0
	v_mul_f32_e32 v62, v35, v62
	v_mov_b32_e32 v26, v25
	v_pk_mul_f32 v[18:19], v[26:27], v[18:19]
	v_pk_add_f32 v[60:61], v[60:61], 1.0 op_sel_hi:[1,0]
	v_pk_mul_f32 v[30:31], v[62:63], v[30:31]
	s_waitcnt vmcnt(1)
	v_lshlrev_b32_e32 v63, 16, v21
	v_rcp_f32_e32 v25, v61
	s_nop 0
	v_mul_f32_e32 v25, v55, v25
	v_rcp_f32_e32 v24, v60
	s_nop 0
	v_mul_f32_e32 v24, v66, v24
	v_pk_mul_f32 v[18:19], v[24:25], v[18:19]
	v_and_b32_sdwa v24, v31, v155 dst_sel:DWORD dst_unused:UNUSED_PAD src0_sel:WORD_1 src1_sel:DWORD
	v_and_b32_sdwa v26, v19, v155 dst_sel:DWORD dst_unused:UNUSED_PAD src0_sel:WORD_1 src1_sel:DWORD
	v_add3_u32 v19, v19, v26, s68
	v_add3_u32 v24, v31, v24, s68
	v_and_b32_e32 v19, 0xffff0000, v19
	s_waitcnt vmcnt(0)
	v_lshlrev_b32_e32 v55, 16, v56
	v_or_b32_sdwa v19, v19, v24 dst_sel:DWORD dst_unused:UNUSED_PAD src0_sel:DWORD src1_sel:WORD_1
	v_mul_f32_e32 v24, 0xbfb8aa3b, v55
	v_and_b32_e32 v67, 0xffff0000, v56
	v_lshlrev_b32_e32 v35, 16, v57
	v_exp_f32_e32 v60, v24
	v_mul_f32_e32 v24, 0xbfb8aa3b, v67
	v_exp_f32_e32 v56, v24
	v_mul_f32_e32 v24, 0xbfb8aa3b, v35
	v_exp_f32_e32 v61, v24
	v_and_b32_sdwa v27, v18, v155 dst_sel:DWORD dst_unused:UNUSED_PAD src0_sel:WORD_1 src1_sel:DWORD
	v_and_b32_sdwa v25, v30, v155 dst_sel:DWORD dst_unused:UNUSED_PAD src0_sel:WORD_1 src1_sel:DWORD
	v_add3_u32 v18, v18, v27, s68
	v_pk_add_f32 v[60:61], v[60:61], 1.0 op_sel_hi:[1,0]
	v_add3_u32 v25, v30, v25, s68
	v_and_b32_e32 v18, 0xffff0000, v18
	v_and_b32_e32 v66, 0xffff0000, v57
	v_or_b32_sdwa v18, v18, v25 dst_sel:DWORD dst_unused:UNUSED_PAD src0_sel:DWORD src1_sel:WORD_1
	ds_read_b128 v[24:27], v28
	ds_read_b128 v[28:31], v28 offset:16
	v_lshlrev_b32_e32 v62, 16, v20
	v_and_b32_e32 v21, 0xffff0000, v21
	s_waitcnt lgkmcnt(1)
	v_mov_b32_e32 v64, v24
	v_mov_b32_e32 v65, v26
	v_pk_mul_f32 v[62:63], v[64:65], v[62:63]
	v_rcp_f32_e32 v61, v61
	s_nop 0
	v_mul_f32_e32 v61, v35, v61
	v_and_b32_e32 v20, 0xffff0000, v20
	v_mul_f32_e32 v26, 0xbfb8aa3b, v66
	v_exp_f32_e32 v57, v26
	v_rcp_f32_e32 v60, v60
	s_nop 0
	v_mul_f32_e32 v60, v55, v60
	v_mov_b32_e32 v26, v25
	v_pk_mul_f32 v[20:21], v[26:27], v[20:21]
	v_pk_add_f32 v[56:57], v[56:57], 1.0 op_sel_hi:[1,0]
	v_pk_mul_f32 v[60:61], v[60:61], v[62:63]
	v_lshlrev_b32_e32 v63, 16, v23
	v_lshlrev_b32_e32 v62, 16, v22
	v_and_b32_e32 v23, 0xffff0000, v23
	v_rcp_f32_e32 v25, v57
	s_nop 0
	v_mul_f32_e32 v25, v66, v25
	v_rcp_f32_e32 v24, v56
	s_nop 0
	v_mul_f32_e32 v24, v67, v24
	v_pk_mul_f32 v[20:21], v[24:25], v[20:21]
	v_and_b32_sdwa v24, v61, v155 dst_sel:DWORD dst_unused:UNUSED_PAD src0_sel:WORD_1 src1_sel:DWORD
	v_and_b32_sdwa v26, v21, v155 dst_sel:DWORD dst_unused:UNUSED_PAD src0_sel:WORD_1 src1_sel:DWORD
	v_and_b32_sdwa v27, v20, v155 dst_sel:DWORD dst_unused:UNUSED_PAD src0_sel:WORD_1 src1_sel:DWORD
	v_and_b32_sdwa v25, v60, v155 dst_sel:DWORD dst_unused:UNUSED_PAD src0_sel:WORD_1 src1_sel:DWORD
	v_add3_u32 v21, v21, v26, s68
	v_add3_u32 v20, v20, v27, s68
	v_add3_u32 v25, v60, v25, s68
	v_add3_u32 v24, v61, v24, s68
	v_and_b32_e32 v21, 0xffff0000, v21
	v_and_b32_e32 v20, 0xffff0000, v20
	v_lshlrev_b32_e32 v35, 16, v59
	v_lshlrev_b32_e32 v55, 16, v58
	v_or_b32_sdwa v21, v21, v24 dst_sel:DWORD dst_unused:UNUSED_PAD src0_sel:DWORD src1_sel:WORD_1
	v_or_b32_sdwa v20, v20, v25 dst_sel:DWORD dst_unused:UNUSED_PAD src0_sel:DWORD src1_sel:WORD_1
	v_mul_f32_e32 v24, 0xbfb8aa3b, v55
	v_mul_f32_e32 v25, 0xbfb8aa3b, v35
	v_exp_f32_e32 v24, v24
	v_exp_f32_e32 v25, v25
	v_and_b32_e32 v67, 0xffff0000, v58
	v_mul_f32_e32 v26, 0xbfb8aa3b, v67
	v_and_b32_e32 v66, 0xffff0000, v59
	v_exp_f32_e32 v60, v26
	v_pk_add_f32 v[64:65], v[24:25], 1.0 op_sel_hi:[1,0]
	global_load_dwordx4 v[24:27], v[32:33], off
	global_load_dwordx4 v[56:59], v[32:33], off offset:2048
	s_waitcnt lgkmcnt(0)
	v_mov_b32_e32 v32, v28
	v_mov_b32_e32 v33, v30
	v_pk_mul_f32 v[32:33], v[32:33], v[62:63]
	v_rcp_f32_e32 v63, v65
	s_nop 0
	v_mul_f32_e32 v63, v35, v63
	v_and_b32_e32 v22, 0xffff0000, v22
	v_mul_f32_e32 v30, 0xbfb8aa3b, v66
	v_exp_f32_e32 v61, v30
	v_rcp_f32_e32 v62, v64
	s_nop 0
	v_mul_f32_e32 v62, v55, v62
	v_mov_b32_e32 v30, v29
	v_pk_mul_f32 v[22:23], v[30:31], v[22:23]
	v_pk_add_f32 v[60:61], v[60:61], 1.0 op_sel_hi:[1,0]
	v_pk_mul_f32 v[32:33], v[62:63], v[32:33]
	s_waitcnt vmcnt(1)
	v_lshlrev_b32_e32 v63, 16, v25
	v_rcp_f32_e32 v29, v61
	s_nop 0
	v_mul_f32_e32 v29, v66, v29
	v_rcp_f32_e32 v28, v60
	s_nop 0
	v_mul_f32_e32 v28, v67, v28
	v_pk_mul_f32 v[22:23], v[28:29], v[22:23]
	v_and_b32_sdwa v28, v33, v155 dst_sel:DWORD dst_unused:UNUSED_PAD src0_sel:WORD_1 src1_sel:DWORD
	v_and_b32_sdwa v30, v23, v155 dst_sel:DWORD dst_unused:UNUSED_PAD src0_sel:WORD_1 src1_sel:DWORD
	v_add3_u32 v23, v23, v30, s68
	v_add3_u32 v28, v33, v28, s68
	v_and_b32_e32 v23, 0xffff0000, v23
	s_waitcnt vmcnt(0)
	v_lshlrev_b32_e32 v66, 16, v56
	v_or_b32_sdwa v23, v23, v28 dst_sel:DWORD dst_unused:UNUSED_PAD src0_sel:DWORD src1_sel:WORD_1
	v_mul_f32_e32 v28, 0xbfb8aa3b, v66
	v_and_b32_e32 v68, 0xffff0000, v56
	v_lshlrev_b32_e32 v55, 16, v57
	v_exp_f32_e32 v60, v28
	v_mul_f32_e32 v28, 0xbfb8aa3b, v68
	v_exp_f32_e32 v56, v28
	v_mul_f32_e32 v28, 0xbfb8aa3b, v55
	v_exp_f32_e32 v61, v28
	v_and_b32_sdwa v31, v22, v155 dst_sel:DWORD dst_unused:UNUSED_PAD src0_sel:WORD_1 src1_sel:DWORD
	v_and_b32_sdwa v29, v32, v155 dst_sel:DWORD dst_unused:UNUSED_PAD src0_sel:WORD_1 src1_sel:DWORD
	v_add3_u32 v22, v22, v31, s68
	v_pk_add_f32 v[60:61], v[60:61], 1.0 op_sel_hi:[1,0]
	v_add3_u32 v29, v32, v29, s68
	v_and_b32_e32 v22, 0xffff0000, v22
	v_and_b32_e32 v67, 0xffff0000, v57
	v_or_b32_sdwa v22, v22, v29 dst_sel:DWORD dst_unused:UNUSED_PAD src0_sel:DWORD src1_sel:WORD_1
	ds_read_b128 v[28:31], v34
	ds_read_b128 v[32:35], v34 offset:16
	v_lshlrev_b32_e32 v62, 16, v24
	v_and_b32_e32 v25, 0xffff0000, v25
	s_waitcnt lgkmcnt(1)
; __device__ __forceinline__ unsigned pack2(float a, float b) { return (unsigned)f2bf(a) | ((unsigned)f2bf(b) << 16); }
; __device__ __forceinline__ float bflo(unsigned w) { return __uint_as_float(w << 16); }
; __device__ __forceinline__ float bfhi(unsigned w) { return __uint_as_float(w & 0xffff0000u); }
; __device__ __forceinline__ float silu_f(float g) { return g / (1.f + __expf(-g)); }
; __device__ void gmlp_item(const Params& p, int layer, int b, int n, int g, char* smem) {
;     ...
;     uint4 uu[8], gt[8];
; #pragma unroll
;     for (int i = 0; i < 8; ++i) {
;       int q = tid + 256 * i, t = q >> 4, c = (q & 15) * 8;
;       uu[i] = *reinterpret_cast<const uint4*>(P + (t0 + t) * NP + g * 128 + c);
;       gt[i] = *reinterpret_cast<const uint4*>(P + (t0 + t) * NP + 1024 + g * 128 + c);
;     }
; #pragma unroll
;     for (int i = 0; i < 8; ++i) {
;       int q = tid + 256 * i, t = q >> 4, c = (q & 15) * 8;
;       float4 m0 = *reinterpret_cast<const float4*>(Tf + t * 132 + c);
;       float4 m1 = *reinterpret_cast<const float4*>(Tf + t * 132 + c + 4);
;       float mm[8] = {m0.x, m0.y, m0.z, m0.w, m1.x, m1.y, m1.z, m1.w};
;       unsigned uw[4] = {uu[i].x, uu[i].y, uu[i].z, uu[i].w};
;       unsigned gw[4] = {gt[i].x, gt[i].y, gt[i].z, gt[i].w};
;       unsigned ow[4];
; #pragma unroll
;       for (int e = 0; e < 4; ++e) {
;         float y0 = bflo(uw[e]) * mm[2 * e] * silu_f(bflo(gw[e]));
;         float y1 = bfhi(uw[e]) * mm[2 * e + 1] * silu_f(bfhi(gw[e]));
;         ow[e] = pack2(y0, y1);
;       }
;       *reinterpret_cast<uint4*>(Y + (t0 + t) * YW + g * 128 + c) = make_uint4(ow[0], ow[1], ow[2], ow[3]);
;     }
	v_mov_b32_e32 v64, v28
	v_mov_b32_e32 v65, v30
	v_pk_mul_f32 v[62:63], v[64:65], v[62:63]
	v_rcp_f32_e32 v61, v61
	s_nop 0
	v_mul_f32_e32 v61, v55, v61
	v_and_b32_e32 v24, 0xffff0000, v24
	v_mul_f32_e32 v30, 0xbfb8aa3b, v67
	v_exp_f32_e32 v57, v30
	v_rcp_f32_e32 v60, v60
	s_nop 0
	v_mul_f32_e32 v60, v66, v60
	v_mov_b32_e32 v30, v29
	v_pk_mul_f32 v[24:25], v[30:31], v[24:25]
	v_pk_add_f32 v[56:57], v[56:57], 1.0 op_sel_hi:[1,0]
	v_pk_mul_f32 v[60:61], v[60:61], v[62:63]
	v_lshlrev_b32_e32 v66, 16, v58
	v_lshlrev_b32_e32 v63, 16, v27
	v_and_b32_e32 v27, 0xffff0000, v27
	v_rcp_f32_e32 v29, v57
	s_nop 0
	v_mul_f32_e32 v29, v67, v29
	v_rcp_f32_e32 v28, v56
	s_nop 0
	v_mul_f32_e32 v28, v68, v28
	v_pk_mul_f32 v[24:25], v[28:29], v[24:25]
	v_and_b32_sdwa v28, v61, v155 dst_sel:DWORD dst_unused:UNUSED_PAD src0_sel:WORD_1 src1_sel:DWORD
	v_and_b32_sdwa v30, v25, v155 dst_sel:DWORD dst_unused:UNUSED_PAD src0_sel:WORD_1 src1_sel:DWORD
	v_and_b32_sdwa v31, v24, v155 dst_sel:DWORD dst_unused:UNUSED_PAD src0_sel:WORD_1 src1_sel:DWORD
	v_and_b32_sdwa v29, v60, v155 dst_sel:DWORD dst_unused:UNUSED_PAD src0_sel:WORD_1 src1_sel:DWORD
	v_add3_u32 v25, v25, v30, s68
	v_add3_u32 v24, v24, v31, s68
	v_add3_u32 v29, v60, v29, s68
	v_add3_u32 v28, v61, v28, s68
	v_and_b32_e32 v25, 0xffff0000, v25
	v_and_b32_e32 v24, 0xffff0000, v24
	v_lshlrev_b32_e32 v55, 16, v59
	v_or_b32_sdwa v25, v25, v28 dst_sel:DWORD dst_unused:UNUSED_PAD src0_sel:DWORD src1_sel:WORD_1
	v_or_b32_sdwa v24, v24, v29 dst_sel:DWORD dst_unused:UNUSED_PAD src0_sel:DWORD src1_sel:WORD_1
	v_mul_f32_e32 v28, 0xbfb8aa3b, v66
	v_mul_f32_e32 v29, 0xbfb8aa3b, v55
	v_exp_f32_e32 v28, v28
	v_exp_f32_e32 v29, v29
	v_and_b32_e32 v68, 0xffff0000, v58
	v_mul_f32_e32 v30, 0xbfb8aa3b, v68
	v_and_b32_e32 v67, 0xffff0000, v59
	v_exp_f32_e32 v60, v30
	v_pk_add_f32 v[64:65], v[28:29], 1.0 op_sel_hi:[1,0]
	global_load_dwordx4 v[28:31], v[52:53], off
	global_load_dwordx4 v[56:59], v[52:53], off offset:2048
	s_waitcnt lgkmcnt(0)
	v_mov_b32_e32 v52, v32
	v_lshlrev_b32_e32 v62, 16, v26
	v_mov_b32_e32 v53, v34
	v_pk_mul_f32 v[52:53], v[52:53], v[62:63]
	v_rcp_f32_e32 v63, v65
	s_nop 0
	v_mul_f32_e32 v63, v55, v63
	v_and_b32_e32 v26, 0xffff0000, v26
	v_mul_f32_e32 v34, 0xbfb8aa3b, v67
	v_exp_f32_e32 v61, v34
	v_rcp_f32_e32 v62, v64
	s_nop 0
	v_mul_f32_e32 v62, v66, v62
	v_mov_b32_e32 v34, v33
	v_pk_mul_f32 v[26:27], v[34:35], v[26:27]
	v_pk_add_f32 v[60:61], v[60:61], 1.0 op_sel_hi:[1,0]
	v_pk_mul_f32 v[52:53], v[62:63], v[52:53]
	s_waitcnt vmcnt(1)
	v_lshlrev_b32_e32 v63, 16, v29
	v_rcp_f32_e32 v33, v61
	s_nop 0
	v_mul_f32_e32 v33, v67, v33
	v_rcp_f32_e32 v32, v60
	s_nop 0
	v_mul_f32_e32 v32, v68, v32
	v_pk_mul_f32 v[26:27], v[32:33], v[26:27]
	v_and_b32_sdwa v32, v53, v155 dst_sel:DWORD dst_unused:UNUSED_PAD src0_sel:WORD_1 src1_sel:DWORD
	v_and_b32_sdwa v34, v27, v155 dst_sel:DWORD dst_unused:UNUSED_PAD src0_sel:WORD_1 src1_sel:DWORD
	v_add3_u32 v27, v27, v34, s68
	v_add3_u32 v32, v53, v32, s68
	v_and_b32_e32 v27, 0xffff0000, v27
	s_waitcnt vmcnt(0)
	v_lshlrev_b32_e32 v67, 16, v56
	v_or_b32_sdwa v27, v27, v32 dst_sel:DWORD dst_unused:UNUSED_PAD src0_sel:DWORD src1_sel:WORD_1
	v_mul_f32_e32 v32, 0xbfb8aa3b, v67
	v_and_b32_e32 v69, 0xffff0000, v56
	v_lshlrev_b32_e32 v66, 16, v57
	v_exp_f32_e32 v60, v32
	v_mul_f32_e32 v32, 0xbfb8aa3b, v69
	v_exp_f32_e32 v56, v32
	v_mul_f32_e32 v32, 0xbfb8aa3b, v66
	v_exp_f32_e32 v61, v32
	v_and_b32_sdwa v35, v26, v155 dst_sel:DWORD dst_unused:UNUSED_PAD src0_sel:WORD_1 src1_sel:DWORD
	v_and_b32_sdwa v33, v52, v155 dst_sel:DWORD dst_unused:UNUSED_PAD src0_sel:WORD_1 src1_sel:DWORD
	v_add3_u32 v26, v26, v35, s68
	v_pk_add_f32 v[60:61], v[60:61], 1.0 op_sel_hi:[1,0]
	v_add3_u32 v33, v52, v33, s68
	v_and_b32_e32 v26, 0xffff0000, v26
	v_and_b32_e32 v68, 0xffff0000, v57
	v_or_b32_sdwa v26, v26, v33 dst_sel:DWORD dst_unused:UNUSED_PAD src0_sel:DWORD src1_sel:WORD_1
	ds_read_b128 v[32:35], v54
	ds_read_b128 v[52:55], v54 offset:16
	v_lshlrev_b32_e32 v62, 16, v28
	v_and_b32_e32 v29, 0xffff0000, v29
	s_waitcnt lgkmcnt(1)
; __device__ __forceinline__ unsigned pack2(float a, float b) { return (unsigned)f2bf(a) | ((unsigned)f2bf(b) << 16); }
; __device__ __forceinline__ float bflo(unsigned w) { return __uint_as_float(w << 16); }
; __device__ __forceinline__ float bfhi(unsigned w) { return __uint_as_float(w & 0xffff0000u); }
; __device__ __forceinline__ float silu_f(float g) { return g / (1.f + __expf(-g)); }
; __device__ void gmlp_item(const Params& p, int layer, int b, int n, int g, char* smem) {
;     ...
;     uint4 uu[8], gt[8];
; #pragma unroll
;     for (int i = 0; i < 8; ++i) {
;       int q = tid + 256 * i, t = q >> 4, c = (q & 15) * 8;
;       uu[i] = *reinterpret_cast<const uint4*>(P + (t0 + t) * NP + g * 128 + c);
;       gt[i] = *reinterpret_cast<const uint4*>(P + (t0 + t) * NP + 1024 + g * 128 + c);
;     }
; #pragma unroll
;     for (int i = 0; i < 8; ++i) {
;       int q = tid + 256 * i, t = q >> 4, c = (q & 15) * 8;
;       float4 m0 = *reinterpret_cast<const float4*>(Tf + t * 132 + c);
;       float4 m1 = *reinterpret_cast<const float4*>(Tf + t * 132 + c + 4);
;       float mm[8] = {m0.x, m0.y, m0.z, m0.w, m1.x, m1.y, m1.z, m1.w};
;       unsigned uw[4] = {uu[i].x, uu[i].y, uu[i].z, uu[i].w};
;       unsigned gw[4] = {gt[i].x, gt[i].y, gt[i].z, gt[i].w};
;       unsigned ow[4];
; #pragma unroll
;       for (int e = 0; e < 4; ++e) {
;         float y0 = bflo(uw[e]) * mm[2 * e] * silu_f(bflo(gw[e]));
;         float y1 = bfhi(uw[e]) * mm[2 * e + 1] * silu_f(bfhi(gw[e]));
;         ow[e] = pack2(y0, y1);
;       }
;       *reinterpret_cast<uint4*>(Y + (t0 + t) * YW + g * 128 + c) = make_uint4(ow[0], ow[1], ow[2], ow[3]);
;     }
	v_mov_b32_e32 v64, v32
	v_mov_b32_e32 v65, v34
	v_pk_mul_f32 v[62:63], v[64:65], v[62:63]
	v_rcp_f32_e32 v61, v61
	s_nop 0
	v_mul_f32_e32 v61, v66, v61
	v_and_b32_e32 v28, 0xffff0000, v28
	v_mul_f32_e32 v34, 0xbfb8aa3b, v68
	v_exp_f32_e32 v57, v34
	v_rcp_f32_e32 v60, v60
	s_nop 0
	v_mul_f32_e32 v60, v67, v60
	v_pk_mul_f32 v[60:61], v[60:61], v[62:63]
	v_mov_b32_e32 v34, v33
	v_pk_add_f32 v[56:57], v[56:57], 1.0 op_sel_hi:[1,0]
	v_pk_mul_f32 v[28:29], v[34:35], v[28:29]
	s_nop 0
	v_rcp_f32_e32 v33, v57
	s_nop 0
	v_mul_f32_e32 v33, v68, v33
	v_rcp_f32_e32 v32, v56
	s_nop 0
	v_mul_f32_e32 v32, v69, v32
	v_pk_mul_f32 v[28:29], v[32:33], v[28:29]
	v_and_b32_sdwa v32, v61, v155 dst_sel:DWORD dst_unused:UNUSED_PAD src0_sel:WORD_1 src1_sel:DWORD
	v_and_b32_sdwa v34, v29, v155 dst_sel:DWORD dst_unused:UNUSED_PAD src0_sel:WORD_1 src1_sel:DWORD
	v_and_b32_sdwa v35, v28, v155 dst_sel:DWORD dst_unused:UNUSED_PAD src0_sel:WORD_1 src1_sel:DWORD
	v_and_b32_sdwa v33, v60, v155 dst_sel:DWORD dst_unused:UNUSED_PAD src0_sel:WORD_1 src1_sel:DWORD
	v_add3_u32 v29, v29, v34, s68
	v_add3_u32 v28, v28, v35, s68
	v_add3_u32 v33, v60, v33, s68
	v_add3_u32 v32, v61, v32, s68
	v_and_b32_e32 v29, 0xffff0000, v29
	v_and_b32_e32 v28, 0xffff0000, v28
	v_lshlrev_b32_e32 v35, 16, v59
	v_lshlrev_b32_e32 v60, 16, v58
	v_or_b32_sdwa v29, v29, v32 dst_sel:DWORD dst_unused:UNUSED_PAD src0_sel:DWORD src1_sel:WORD_1
	v_or_b32_sdwa v28, v28, v33 dst_sel:DWORD dst_unused:UNUSED_PAD src0_sel:DWORD src1_sel:WORD_1
	v_mul_f32_e32 v32, 0xbfb8aa3b, v60
	v_mul_f32_e32 v33, 0xbfb8aa3b, v35
	v_exp_f32_e32 v32, v32
	v_exp_f32_e32 v33, v33
	v_and_b32_e32 v62, 0xffff0000, v58
	s_waitcnt lgkmcnt(0)
	v_mov_b32_e32 v58, v52
	v_and_b32_e32 v61, 0xffff0000, v59
	v_pk_add_f32 v[32:33], v[32:33], 1.0 op_sel_hi:[1,0]
	v_lshlrev_b32_e32 v57, 16, v31
	v_lshlrev_b32_e32 v56, 16, v30
	v_mov_b32_e32 v59, v54
	v_pk_mul_f32 v[56:57], v[58:59], v[56:57]
	v_rcp_f32_e32 v33, v33
	s_nop 0
	v_mul_f32_e32 v33, v35, v33
	v_mul_f32_e32 v34, 0xbfb8aa3b, v62
	v_mul_f32_e32 v35, 0xbfb8aa3b, v61
	v_exp_f32_e32 v34, v34
	v_exp_f32_e32 v35, v35
	v_rcp_f32_e32 v32, v32
	s_nop 0
	v_mul_f32_e32 v32, v60, v32
	v_pk_mul_f32 v[32:33], v[32:33], v[56:57]
	v_mov_b32_e32 v54, v53
	v_pk_add_f32 v[34:35], v[34:35], 1.0 op_sel_hi:[1,0]
	v_and_b32_e32 v31, 0xffff0000, v31
	v_and_b32_e32 v30, 0xffff0000, v30
	v_pk_mul_f32 v[30:31], v[54:55], v[30:31]
	v_rcp_f32_e32 v35, v35
	s_nop 0
	v_mul_f32_e32 v35, v61, v35
	s_mov_b64 s[12:13], 0
	v_rcp_f32_e32 v34, v34
	s_nop 0
	v_mul_f32_e32 v34, v62, v34
	v_pk_mul_f32 v[30:31], v[34:35], v[30:31]
	v_and_b32_sdwa v34, v33, v155 dst_sel:DWORD dst_unused:UNUSED_PAD src0_sel:WORD_1 src1_sel:DWORD
	v_and_b32_sdwa v35, v32, v155 dst_sel:DWORD dst_unused:UNUSED_PAD src0_sel:WORD_1 src1_sel:DWORD
	v_add3_u32 v32, v32, v35, s68
	v_add3_u32 v33, v33, v34, s68
	v_and_b32_sdwa v34, v31, v155 dst_sel:DWORD dst_unused:UNUSED_PAD src0_sel:WORD_1 src1_sel:DWORD
	v_and_b32_sdwa v35, v30, v155 dst_sel:DWORD dst_unused:UNUSED_PAD src0_sel:WORD_1 src1_sel:DWORD
	v_add3_u32 v31, v31, v34, s68
	v_add3_u32 v30, v30, v35, s68
	v_and_b32_e32 v31, 0xffff0000, v31
	v_and_b32_e32 v30, 0xffff0000, v30
	v_or_b32_sdwa v31, v31, v33 dst_sel:DWORD dst_unused:UNUSED_PAD src0_sel:DWORD src1_sel:WORD_1
	v_or_b32_sdwa v30, v30, v32 dst_sel:DWORD dst_unused:UNUSED_PAD src0_sel:DWORD src1_sel:WORD_1
	global_store_dwordx4 v[50:51], v[28:31], off
	global_store_dwordx4 v[48:49], v[24:27], off
	global_store_dwordx4 v[46:47], v[20:23], off
	global_store_dwordx4 v[44:45], v[16:19], off
	global_store_dwordx4 v[42:43], v[12:15], off
	global_store_dwordx4 v[40:41], v[8:11], off
	global_store_dwordx4 v[38:39], v[4:7], off
	global_store_dwordx4 v[36:37], v[0:3], off
	s_barrier

; __device__ __forceinline__ unsigned pack2(float a, float b) { return (unsigned)f2bf(a) | ((unsigned)f2bf(b) << 16); }
; __device__ __forceinline__ float bflo(unsigned w) { return __uint_as_float(w << 16); }
; __device__ __forceinline__ float bfhi(unsigned w) { return __uint_as_float(w & 0xffff0000u); }
; __device__ __forceinline__ float silu_f(float g) { return g / (1.f + __expf(-g)); }
; template <int DH, int MODE>
; __device__ void attn_item(const Params& p, int layer, int b, int blk, int head, char* smem) {
;     ...
;     uint4 gt[NCH];
; #pragma unroll
;     for (int i = 0; i < NCH; ++i) {
;       int q = tid + 256 * i, r = q / CPR, c = (q % CPR) * 8;
;       gt[i] = *reinterpret_cast<const uint4*>(P + (tq0 + r) * NP + gcol + c);
;     }
;     float lis[2][4];
; #pragma unroll
;     for (int m = 0; m < 2; ++m)
; #pragma unroll
;       for (int j = 0; j < 4; ++j) lis[m][j] = (MODE == 0) ? linv_s[wid * 32 + m * 16 + fq * 4 + j] : 1.f;
;     if (MODE == 0) __syncthreads();
; #pragma unroll
;     for (int m = 0; m < 2; ++m)
; #pragma unroll
;       for (int j = 0; j < 4; ++j) {
;         int r = wid * 32 + m * 16 + fq * 4 + j;
; #pragma unroll
;         for (int n = 0; n < NDT; ++n) Of[r * OST + n * 16 + fr] = o[m][n][j] * lis[m][j];
;       }
;     __syncthreads();
; #pragma unroll
;     for (int i = 0; i < NCH; ++i) {
;       int q = tid + 256 * i, r = q / CPR, c = (q % CPR) * 8;
;       float4 m0 = *reinterpret_cast<const float4*>(Of + r * OST + c);
;       float4 m1 = *reinterpret_cast<const float4*>(Of + r * OST + c + 4);
;       float mm[8] = {m0.x, m0.y, m0.z, m0.w, m1.x, m1.y, m1.z, m1.w};
;       unsigned gw[4] = {gt[i].x, gt[i].y, gt[i].z, gt[i].w};
;       unsigned ow[4];
; #pragma unroll
;       for (int e = 0; e < 4; ++e)
;         ow[e] = pack2(mm[2 * e] * silu_f(bflo(gw[e])), mm[2 * e + 1] * silu_f(bfhi(gw[e])));
.LBB0_834:
	s_or_b64 exec, exec, s[14:15]
	v_lshl_add_u64 v[44:45], v[66:67], 0, s[36:37]
	v_mov_b64_e32 v[46:47], s[48:49]
	v_mad_u64_u32 v[32:33], s[14:15], v44, s45, v[46:47]
	v_mad_i32_i24 v33, v45, s45, v33
	v_lshl_add_u64 v[36:37], v[32:33], 0, v[70:71]
	v_add_u32_e32 v32, 0x100, v81
	v_ashrrev_i32_e32 v33, 31, v32
	v_lshrrev_b32_e32 v33, 29, v33
	v_add_u32_e32 v33, v32, v33
	v_ashrrev_i32_e32 v86, 3, v33
	v_and_b32_e32 v33, -8, v33
	v_sub_u32_e32 v85, v32, v33
	v_lshlrev_b32_e32 v32, 3, v85
	v_ashrrev_i32_e32 v33, 31, v32
	s_waitcnt vmcnt(2)
	v_add_u32_e32 v48, 0x200, v81
	v_lshlrev_b64 v[90:91], 1, v[32:33]
	v_ashrrev_i32_e32 v32, 31, v48
	v_lshrrev_b32_e32 v32, 29, v32
	v_add_u32_e32 v32, v48, v32
	v_ashrrev_i32_e32 v92, 3, v32
	v_and_b32_e32 v49, -8, v32
	v_add_u32_e32 v32, 0x300, v81
	v_ashrrev_i32_e32 v33, 31, v32
	v_lshrrev_b32_e32 v33, 29, v33
	v_ashrrev_i32_e32 v87, 31, v86
	v_add_u32_e32 v33, v32, v33
	v_lshl_add_u64 v[88:89], v[86:87], 0, s[36:37]
	v_ashrrev_i32_e32 v94, 3, v33
	v_and_b32_e32 v33, -8, v33
	v_mad_u64_u32 v[34:35], s[14:15], v88, s45, v[46:47]
	v_sub_u32_e32 v87, v32, v33
	v_ashrrev_i32_e32 v95, 31, v94
	v_mad_i32_i24 v35, v89, s45, v35
	v_lshlrev_b32_e32 v32, 3, v87
	v_lshl_add_u64 v[40:41], v[94:95], 0, s[36:37]
	v_lshl_add_u64 v[38:39], v[34:35], 0, v[90:91]
	v_mad_u64_u32 v[34:35], s[14:15], v40, s45, v[46:47]
	v_ashrrev_i32_e32 v33, 31, v32
	v_mad_i32_i24 v35, v41, s45, v35
	v_lshlrev_b64 v[42:43], 1, v[32:33]
	v_lshl_add_u64 v[32:33], v[34:35], 0, v[42:43]
	v_add_co_u32_e32 v32, vcc, s72, v32
	s_waitcnt lgkmcnt(0)
	s_nop 0
	v_addc_co_u32_e32 v33, vcc, 0, v33, vcc
	s_barrier
	global_load_dwordx4 v[32:35], v[32:33], off offset:512
	v_sub_u32_e32 v95, v48, v49
	v_ashrrev_i32_e32 v93, 31, v92
	v_lshlrev_b32_e32 v48, 3, v95
	v_lshl_add_u64 v[96:97], v[92:93], 0, s[36:37]
	v_mad_u64_u32 v[46:47], s[14:15], v96, s45, v[46:47]
	v_ashrrev_i32_e32 v49, 31, v48
	v_mad_i32_i24 v47, v97, s45, v47
	v_lshlrev_b64 v[98:99], 1, v[48:49]
	v_lshl_add_u64 v[100:101], v[46:47], 0, v[98:99]
	v_lshl_or_b32 v46, v75, 7, v128
	ds_read_b128 v[60:63], v46 offset:8704
	ds_read_b128 v[80:83], v46 offset:8768
	s_ashr_i32 s13, s16, 31
	s_add_u32 s12, s28, s16
	s_addc_u32 s13, s29, s13
	s_lshl_b32 s14, s83, 1
	s_add_u32 s12, s12, s14
	v_lshl_or_b32 v46, v84, 2, v64
	s_waitcnt lgkmcnt(0)
	v_mul_f32_e32 v69, v0, v80
	s_addc_u32 s13, s13, 0
	v_mul_lo_u32 v0, v66, s74
	v_mul_lo_u32 v46, v46, s74
	v_mul_f32_e32 v75, v1, v81
	v_lshl_add_u32 v66, v68, 2, v0
	v_mov_b64_e32 v[0:1], s[12:13]
	v_lshl_add_u32 v47, v73, 2, v46
	v_mul_f32_e32 v48, v16, v60
	v_mul_f32_e32 v49, v28, v60
	v_mul_f32_e32 v50, v24, v60
	v_mul_f32_e32 v51, v20, v60
	s_waitcnt vmcnt(1)
	v_mul_f32_e32 v52, v17, v61
	v_mul_f32_e32 v53, v29, v61
	v_mul_f32_e32 v54, v25, v61
	v_mul_f32_e32 v55, v21, v61
	v_mul_f32_e32 v56, v18, v62
	v_mul_f32_e32 v57, v30, v62
	v_mul_f32_e32 v58, v26, v62
	v_mul_f32_e32 v59, v22, v62
	v_mul_f32_e32 v60, v19, v63
	v_mul_f32_e32 v61, v31, v63
	v_mul_f32_e32 v62, v27, v63
	v_mul_f32_e32 v64, v23, v63
	v_mul_f32_e32 v63, v12, v80
	v_mul_f32_e32 v65, v8, v80
	v_mul_f32_e32 v67, v4, v80
	v_mul_f32_e32 v72, v13, v81
	v_mul_f32_e32 v73, v9, v81
	v_mul_f32_e32 v74, v5, v81
	v_mul_f32_e32 v76, v14, v82
	v_mul_f32_e32 v77, v10, v82
	v_mul_f32_e32 v78, v6, v82
	v_mul_f32_e32 v80, v2, v82
	v_mul_f32_e32 v79, v15, v83
	v_mul_f32_e32 v81, v11, v83
	v_mul_f32_e32 v82, v7, v83
	v_mul_f32_e32 v83, v3, v83
	v_mad_u64_u32 v[2:3], s[12:13], v44, s70, v[0:1]
	v_mad_i32_i24 v3, v45, s70, v3
	v_lshl_add_u64 v[12:13], v[2:3], 0, v[70:71]
	v_mul_lo_u32 v2, v86, s74
	v_lshl_add_u32 v46, v85, 5, v2
	v_mad_u64_u32 v[2:3], s[12:13], v88, s70, v[0:1]
	v_mad_i32_i24 v3, v89, s70, v3
	v_mad_u64_u32 v[4:5], s[12:13], v40, s70, v[0:1]
	v_lshl_add_u64 v[10:11], v[2:3], 0, v[90:91]
	v_mul_lo_u32 v2, v92, s74
	v_mad_i32_i24 v5, v41, s70, v5
	v_lshl_add_u32 v45, v95, 5, v2
	v_mad_u64_u32 v[2:3], s[12:13], v96, s70, v[0:1]
	v_lshl_add_u64 v[14:15], v[4:5], 0, v[42:43]
	v_mad_i32_i24 v3, v97, s70, v3
	v_add_co_u32_e32 v0, vcc, s72, v100
	v_lshl_add_u64 v[8:9], v[2:3], 0, v[98:99]
	v_mul_lo_u32 v2, v94, s74
	s_waitcnt vmcnt(0)
	v_lshlrev_b32_e32 v16, 16, v33
	v_lshlrev_b32_e32 v18, 16, v32
	v_mul_f32_e32 v6, 0xbfb8aa3b, v18
	v_mul_f32_e32 v7, 0xbfb8aa3b, v16
	v_exp_f32_e32 v6, v6
	v_exp_f32_e32 v7, v7
	v_addc_co_u32_e32 v1, vcc, 0, v101, vcc
	v_lshl_add_u32 v44, v87, 5, v2
	v_pk_add_f32 v[4:5], v[6:7], 1.0 op_sel_hi:[1,0]
	global_load_dwordx4 v[0:3], v[0:1], off offset:512
	v_and_b32_e32 v19, 0xffff0000, v33
	v_and_b32_e32 v20, 0xffff0000, v32
	v_mul_f32_e32 v6, 0xbfb8aa3b, v20
	v_rcp_f32_e32 v17, v5
	s_nop 0
	v_mul_f32_e32 v17, v16, v17
	v_mul_f32_e32 v7, 0xbfb8aa3b, v19
	v_exp_f32_e32 v6, v6
	v_exp_f32_e32 v7, v7
	s_nop 0
	v_pk_add_f32 v[6:7], v[6:7], 1.0 op_sel_hi:[1,0]
	v_rcp_f32_e32 v16, v4
	s_nop 0
	v_mul_f32_e32 v16, v18, v16
	v_lshlrev_b32_e32 v23, 16, v34
	v_rcp_f32_e32 v4, v7
	s_nop 0
	v_mul_f32_e32 v19, v19, v4
	v_lshlrev_b32_e32 v22, 16, v35
	v_mul_f32_e32 v4, 0xbfb8aa3b, v23
	v_mul_f32_e32 v5, 0xbfb8aa3b, v22
	v_exp_f32_e32 v4, v4
	v_exp_f32_e32 v5, v5
	v_rcp_f32_e32 v18, v6
	s_nop 0
	v_mul_f32_e32 v18, v20, v18
	v_and_b32_e32 v24, 0xffff0000, v35
	v_pk_add_f32 v[4:5], v[4:5], 1.0 op_sel_hi:[1,0]
	v_and_b32_e32 v25, 0xffff0000, v34
	v_mul_f32_e32 v6, 0xbfb8aa3b, v25
	v_exp_f32_e32 v6, v6
	v_rcp_f32_e32 v21, v5
	s_nop 0
	v_mul_f32_e32 v21, v22, v21
	v_mul_f32_e32 v7, 0xbfb8aa3b, v24
	v_exp_f32_e32 v7, v7
	s_nop 0
	v_pk_add_f32 v[6:7], v[6:7], 1.0 op_sel_hi:[1,0]
	v_rcp_f32_e32 v20, v4
	s_nop 0
	v_mul_f32_e32 v20, v23, v20
	v_rcp_f32_e32 v23, v7
	s_nop 0
	v_mul_f32_e32 v23, v24, v23
	s_waitcnt vmcnt(0)
; __device__ __forceinline__ unsigned pack2(float a, float b) { return (unsigned)f2bf(a) | ((unsigned)f2bf(b) << 16); }
; __device__ __forceinline__ float bflo(unsigned w) { return __uint_as_float(w << 16); }
; __device__ __forceinline__ float bfhi(unsigned w) { return __uint_as_float(w & 0xffff0000u); }
; __device__ __forceinline__ float silu_f(float g) { return g / (1.f + __expf(-g)); }
; template <int DH, int MODE>
; __device__ void attn_item(const Params& p, int layer, int b, int blk, int head, char* smem) {
;     ...
;     uint4 gt[NCH];
; #pragma unroll
;     for (int i = 0; i < NCH; ++i) {
;       int q = tid + 256 * i, r = q / CPR, c = (q % CPR) * 8;
;       gt[i] = *reinterpret_cast<const uint4*>(P + (tq0 + r) * NP + gcol + c);
;     }
;     float lis[2][4];
; #pragma unroll
;     for (int m = 0; m < 2; ++m)
; #pragma unroll
;       for (int j = 0; j < 4; ++j) lis[m][j] = (MODE == 0) ? linv_s[wid * 32 + m * 16 + fq * 4 + j] : 1.f;
;     if (MODE == 0) __syncthreads();
; #pragma unroll
;     for (int m = 0; m < 2; ++m)
; #pragma unroll
;       for (int j = 0; j < 4; ++j) {
;         int r = wid * 32 + m * 16 + fq * 4 + j;
; #pragma unroll
;         for (int n = 0; n < NDT; ++n) Of[r * OST + n * 16 + fr] = o[m][n][j] * lis[m][j];
;       }
;     __syncthreads();
; #pragma unroll
;     for (int i = 0; i < NCH; ++i) {
;       int q = tid + 256 * i, r = q / CPR, c = (q % CPR) * 8;
;       float4 m0 = *reinterpret_cast<const float4*>(Of + r * OST + c);
;       float4 m1 = *reinterpret_cast<const float4*>(Of + r * OST + c + 4);
;       float mm[8] = {m0.x, m0.y, m0.z, m0.w, m1.x, m1.y, m1.z, m1.w};
;       unsigned gw[4] = {gt[i].x, gt[i].y, gt[i].z, gt[i].w};
;       unsigned ow[4];
; #pragma unroll
;       for (int e = 0; e < 4; ++e)
;         ow[e] = pack2(mm[2 * e] * silu_f(bflo(gw[e])), mm[2 * e + 1] * silu_f(bfhi(gw[e])));
	v_lshlrev_b32_e32 v24, 16, v1
	v_lshlrev_b32_e32 v26, 16, v0
	v_mul_f32_e32 v4, 0xbfb8aa3b, v26
	v_mul_f32_e32 v5, 0xbfb8aa3b, v24
	v_exp_f32_e32 v4, v4
	v_exp_f32_e32 v5, v5
	v_and_b32_e32 v27, 0xffff0000, v1
	v_rcp_f32_e32 v22, v6
	s_nop 0
	v_mul_f32_e32 v22, v25, v22
	v_pk_add_f32 v[4:5], v[4:5], 1.0 op_sel_hi:[1,0]
	v_and_b32_e32 v28, 0xffff0000, v0
	v_mul_f32_e32 v0, 0xbfb8aa3b, v28
	v_exp_f32_e32 v6, v0
	v_lshlrev_b32_e32 v32, 16, v3
	v_mul_f32_e32 v7, 0xbfb8aa3b, v27
	v_rcp_f32_e32 v1, v5
	s_nop 0
	v_mul_f32_e32 v1, v24, v1
	v_exp_f32_e32 v7, v7
	s_nop 0
	v_pk_add_f32 v[24:25], v[6:7], 1.0 op_sel_hi:[1,0]
	v_rcp_f32_e32 v0, v4
	s_nop 0
	v_mul_f32_e32 v0, v26, v0
	v_lshlrev_b32_e32 v33, 16, v2
	v_rcp_f32_e32 v25, v25
	s_nop 0
	v_mul_f32_e32 v25, v27, v25
	v_add_co_u32_e64 v4, s[12:13], s72, v38
	s_nop 0
	s_nop 0
	v_addc_co_u32_e64 v5, s[12:13], 0, v39, s[12:13]
	global_load_dwordx4 v[4:7], v[4:5], off offset:512
	v_mul_f32_e32 v26, 0xbfb8aa3b, v33
	v_mul_f32_e32 v27, 0xbfb8aa3b, v32
	v_exp_f32_e32 v26, v26
	v_exp_f32_e32 v27, v27
	v_and_b32_e32 v30, 0xffff0000, v3
	v_rcp_f32_e32 v24, v24
	s_nop 0
	v_mul_f32_e32 v24, v28, v24
	v_pk_add_f32 v[26:27], v[26:27], 1.0 op_sel_hi:[1,0]
	v_and_b32_e32 v38, 0xffff0000, v2
	v_mul_f32_e32 v2, 0xbfb8aa3b, v38
	v_exp_f32_e32 v28, v2
	v_mul_f32_e32 v29, 0xbfb8aa3b, v30
	v_exp_f32_e32 v29, v29
	v_rcp_f32_e32 v3, v27
	s_nop 0
	v_mul_f32_e32 v3, v32, v3
	v_pk_add_f32 v[28:29], v[28:29], 1.0 op_sel_hi:[1,0]
	v_rcp_f32_e32 v2, v26
	s_nop 0
	v_mul_f32_e32 v2, v33, v2
	v_rcp_f32_e32 v27, v29
	s_nop 0
	v_mul_f32_e32 v27, v30, v27
	v_add_co_u32_e64 v30, s[12:13], s72, v36
	s_nop 0
	s_nop 0
	v_addc_co_u32_e64 v31, s[12:13], 0, v37, s[12:13]
	global_load_dwordx4 v[32:35], v[30:31], off offset:512
	v_rcp_f32_e32 v26, v28
	s_nop 0
	v_mul_f32_e32 v26, v38, v26
	s_barrier
	s_waitcnt vmcnt(1)
	v_lshlrev_b32_e32 v36, 16, v5
	v_lshlrev_b32_e32 v37, 16, v4
	v_mul_f32_e32 v30, 0xbfb8aa3b, v37
	v_mul_f32_e32 v31, 0xbfb8aa3b, v36
	v_exp_f32_e32 v30, v30
	v_exp_f32_e32 v31, v31
	v_and_b32_e32 v38, 0xffff0000, v5
	v_and_b32_e32 v39, 0xffff0000, v4
	v_mul_f32_e32 v4, 0xbfb8aa3b, v39
	v_pk_add_f32 v[28:29], v[30:31], 1.0 op_sel_hi:[1,0]
	v_exp_f32_e32 v30, v4
	ds_write2_b32 v47, v48, v49 offset1:16
	ds_write2_b32 v47, v50, v51 offset0:32 offset1:48
	ds_write2_b32 v47, v52, v53 offset0:68 offset1:84
	ds_write2_b32 v47, v54, v55 offset0:100 offset1:116
	ds_write2_b32 v47, v56, v57 offset0:136 offset1:152
	ds_write2_b32 v47, v58, v59 offset0:168 offset1:184
	ds_write2_b32 v47, v60, v61 offset0:204 offset1:220
	ds_write2_b32 v47, v62, v64 offset0:236 offset1:252
	v_mul_f32_e32 v31, 0xbfb8aa3b, v38
	v_exp_f32_e32 v31, v31
	v_rcp_f32_e32 v5, v29
	s_nop 0
	v_mul_f32_e32 v5, v36, v5
	v_pk_add_f32 v[30:31], v[30:31], 1.0 op_sel_hi:[1,0]
	v_rcp_f32_e32 v4, v28
	s_nop 0
	v_mul_f32_e32 v4, v37, v4
	v_rcp_f32_e32 v29, v31
	s_nop 0
	v_mul_f32_e32 v29, v38, v29
	v_lshlrev_b32_e32 v38, 16, v7
	v_lshlrev_b32_e32 v40, 16, v6
	v_mul_f32_e32 v36, 0xbfb8aa3b, v40
	v_mul_f32_e32 v37, 0xbfb8aa3b, v38
	v_exp_f32_e32 v36, v36
	v_exp_f32_e32 v37, v37
	v_rcp_f32_e32 v28, v30
	s_nop 0
	v_mul_f32_e32 v28, v39, v28
	v_and_b32_e32 v39, 0xffff0000, v7
	v_pk_add_f32 v[30:31], v[36:37], 1.0 op_sel_hi:[1,0]
	v_and_b32_e32 v41, 0xffff0000, v6
	v_mul_f32_e32 v6, 0xbfb8aa3b, v41
	v_exp_f32_e32 v36, v6
	v_mul_f32_e32 v37, 0xbfb8aa3b, v39
	v_exp_f32_e32 v37, v37
	v_rcp_f32_e32 v7, v31
	s_nop 0
	v_mul_f32_e32 v7, v38, v7
	v_pk_add_f32 v[36:37], v[36:37], 1.0 op_sel_hi:[1,0]
	v_rcp_f32_e32 v6, v30
	s_nop 0
	v_mul_f32_e32 v6, v40, v6
	v_rcp_f32_e32 v31, v37
	s_nop 0
	v_mul_f32_e32 v31, v39, v31
	s_waitcnt vmcnt(0)
	v_lshlrev_b32_e32 v42, 16, v33
	v_lshlrev_b32_e32 v43, 16, v32
	v_mul_f32_e32 v38, 0xbfb8aa3b, v43
	v_mul_f32_e32 v39, 0xbfb8aa3b, v42
	v_exp_f32_e32 v38, v38
	v_exp_f32_e32 v39, v39
	v_rcp_f32_e32 v30, v36
	s_nop 0
	v_mul_f32_e32 v30, v41, v30
	v_and_b32_e32 v68, 0xffff0000, v33
	v_pk_add_f32 v[36:37], v[38:39], 1.0 op_sel_hi:[1,0]
	v_and_b32_e32 v39, 0xffff0000, v32
	v_mul_f32_e32 v32, 0xbfb8aa3b, v39
	v_exp_f32_e32 v32, v32
	v_rcp_f32_e32 v41, v37
	s_nop 0
	v_mul_f32_e32 v41, v42, v41
	v_mul_f32_e32 v33, 0xbfb8aa3b, v68
	v_exp_f32_e32 v33, v33
	s_nop 0
	v_pk_add_f32 v[32:33], v[32:33], 1.0 op_sel_hi:[1,0]
	v_rcp_f32_e32 v40, v36
	s_nop 0
	v_mul_f32_e32 v40, v43, v40
	v_lshlrev_b32_e32 v70, 16, v34
	v_rcp_f32_e32 v43, v33
	s_nop 0
	v_mul_f32_e32 v43, v68, v43
	v_lshlrev_b32_e32 v38, 16, v35
	v_mul_f32_e32 v36, 0xbfb8aa3b, v70
	v_mul_f32_e32 v37, 0xbfb8aa3b, v38
	v_exp_f32_e32 v36, v36
	v_exp_f32_e32 v37, v37
	v_rcp_f32_e32 v42, v32
	s_nop 0
	v_mul_f32_e32 v42, v39, v42
	v_and_b32_e32 v39, 0xffff0000, v35
	v_pk_add_f32 v[32:33], v[36:37], 1.0 op_sel_hi:[1,0]
	v_and_b32_e32 v68, 0xffff0000, v34
	v_mul_f32_e32 v34, 0xbfb8aa3b, v68
	v_exp_f32_e32 v34, v34
	v_rcp_f32_e32 v71, v33
	s_nop 0
	v_mul_f32_e32 v71, v38, v71
	v_mul_f32_e32 v35, 0xbfb8aa3b, v39
	v_exp_f32_e32 v35, v35
	s_nop 0
	v_pk_add_f32 v[36:37], v[34:35], 1.0 op_sel_hi:[1,0]
	v_rcp_f32_e32 v33, v32
	s_nop 0
	v_mul_f32_e32 v70, v70, v33
	v_rcp_f32_e32 v85, v37
	s_nop 0
	v_mul_f32_e32 v85, v39, v85
	v_add_u32_e32 v32, 0x1000, v47
	ds_write2_b32 v32, v63, v65 offset0:64 offset1:80
	ds_write2_b32 v32, v67, v69 offset0:96 offset1:112
	ds_write2_b32 v32, v72, v73 offset0:132 offset1:148
	ds_write2_b32 v32, v74, v75 offset0:164 offset1:180
	ds_write2_b32 v32, v76, v77 offset0:200 offset1:216
	ds_write2_b32 v32, v78, v80 offset0:232 offset1:248
	v_add_u32_e32 v32, 0x1400, v47
	ds_write2_b32 v32, v79, v81 offset0:12 offset1:28
	ds_write2_b32 v32, v82, v83 offset0:44 offset1:60
	s_waitcnt lgkmcnt(0)
	s_barrier
; __device__ __forceinline__ unsigned pack2(float a, float b) { return (unsigned)f2bf(a) | ((unsigned)f2bf(b) << 16); }
; __device__ __forceinline__ float bflo(unsigned w) { return __uint_as_float(w << 16); }
; __device__ __forceinline__ float bfhi(unsigned w) { return __uint_as_float(w & 0xffff0000u); }
; __device__ __forceinline__ float silu_f(float g) { return g / (1.f + __expf(-g)); }
; template <int DH, int MODE>
; __device__ void attn_item(const Params& p, int layer, int b, int blk, int head, char* smem) {
;     ...
;     for (int i = 0; i < NCH; ++i) {
;       int q = tid + 256 * i, r = q / CPR, c = (q % CPR) * 8;
;       gt[i] = *reinterpret_cast<const uint4*>(P + (tq0 + r) * NP + gcol + c);
;     }
;     ...
; #pragma unroll
;     for (int i = 0; i < NCH; ++i) {
;       int q = tid + 256 * i, r = q / CPR, c = (q % CPR) * 8;
;       float4 m0 = *reinterpret_cast<const float4*>(Of + r * OST + c);
;       float4 m1 = *reinterpret_cast<const float4*>(Of + r * OST + c + 4);
;       float mm[8] = {m0.x, m0.y, m0.z, m0.w, m1.x, m1.y, m1.z, m1.w};
;       unsigned gw[4] = {gt[i].x, gt[i].y, gt[i].z, gt[i].w};
;       unsigned ow[4];
; #pragma unroll
;       for (int e = 0; e < 4; ++e)
;         ow[e] = pack2(mm[2 * e] * silu_f(bflo(gw[e])), mm[2 * e + 1] * silu_f(bfhi(gw[e])));
;       *reinterpret_cast<uint4*>(Y + (tq0 + r) * YW + ycol + c) = make_uint4(ow[0], ow[1], ow[2], ow[3]);
;     }
	ds_read_b128 v[32:35], v66
	v_rcp_f32_e32 v84, v36
	s_nop 0
	v_mul_f32_e32 v84, v68, v84
	ds_read_b128 v[36:39], v66 offset:16
	v_add_co_u32_e32 v12, vcc, s77, v12
	s_waitcnt lgkmcnt(1)
	v_mov_b32_e32 v48, v32
	v_mov_b32_e32 v49, v34
	v_pk_mul_f32 v[40:41], v[40:41], v[48:49]
	v_mov_b32_e32 v34, v33
	v_pk_mul_f32 v[32:33], v[42:43], v[34:35]
	v_and_b32_sdwa v34, v41, v155 dst_sel:DWORD dst_unused:UNUSED_PAD src0_sel:WORD_1 src1_sel:DWORD
	v_and_b32_sdwa v35, v40, v155 dst_sel:DWORD dst_unused:UNUSED_PAD src0_sel:WORD_1 src1_sel:DWORD
	v_add3_u32 v35, v40, v35, s68
	v_add3_u32 v34, v41, v34, s68
	v_and_b32_sdwa v40, v33, v155 dst_sel:DWORD dst_unused:UNUSED_PAD src0_sel:WORD_1 src1_sel:DWORD
	v_and_b32_sdwa v41, v32, v155 dst_sel:DWORD dst_unused:UNUSED_PAD src0_sel:WORD_1 src1_sel:DWORD
	v_add3_u32 v33, v33, v40, s68
	v_add3_u32 v32, v32, v41, s68
	v_and_b32_e32 v33, 0xffff0000, v33
	v_and_b32_e32 v32, 0xffff0000, v32
	v_or_b32_sdwa v33, v33, v34 dst_sel:DWORD dst_unused:UNUSED_PAD src0_sel:DWORD src1_sel:WORD_1
	v_or_b32_sdwa v32, v32, v35 dst_sel:DWORD dst_unused:UNUSED_PAD src0_sel:DWORD src1_sel:WORD_1
	s_waitcnt lgkmcnt(0)
	v_mov_b32_e32 v34, v36
	v_mov_b32_e32 v35, v38
	v_pk_mul_f32 v[34:35], v[70:71], v[34:35]
	v_mov_b32_e32 v38, v37
	v_pk_mul_f32 v[36:37], v[84:85], v[38:39]
	v_and_b32_sdwa v38, v35, v155 dst_sel:DWORD dst_unused:UNUSED_PAD src0_sel:WORD_1 src1_sel:DWORD
	v_and_b32_sdwa v39, v34, v155 dst_sel:DWORD dst_unused:UNUSED_PAD src0_sel:WORD_1 src1_sel:DWORD
	v_add3_u32 v34, v34, v39, s68
	v_add3_u32 v35, v35, v38, s68
	v_and_b32_sdwa v38, v37, v155 dst_sel:DWORD dst_unused:UNUSED_PAD src0_sel:WORD_1 src1_sel:DWORD
	v_and_b32_sdwa v39, v36, v155 dst_sel:DWORD dst_unused:UNUSED_PAD src0_sel:WORD_1 src1_sel:DWORD
	v_add3_u32 v37, v37, v38, s68
	v_add3_u32 v36, v36, v39, s68
	v_and_b32_e32 v37, 0xffff0000, v37
	v_and_b32_e32 v36, 0xffff0000, v36
	v_or_b32_sdwa v35, v37, v35 dst_sel:DWORD dst_unused:UNUSED_PAD src0_sel:DWORD src1_sel:WORD_1
	v_or_b32_sdwa v34, v36, v34 dst_sel:DWORD dst_unused:UNUSED_PAD src0_sel:DWORD src1_sel:WORD_1
	ds_read_b128 v[36:39], v46
	v_addc_co_u32_e32 v13, vcc, 0, v13, vcc
	global_store_dwordx4 v[12:13], v[32:35], off offset:1024
	ds_read_b128 v[32:35], v46 offset:16
	s_waitcnt lgkmcnt(1)
	v_mov_b32_e32 v12, v36
	v_mov_b32_e32 v13, v38
	v_pk_mul_f32 v[4:5], v[4:5], v[12:13]
	v_mov_b32_e32 v38, v37
	v_pk_mul_f32 v[12:13], v[28:29], v[38:39]
	v_and_b32_sdwa v28, v5, v155 dst_sel:DWORD dst_unused:UNUSED_PAD src0_sel:WORD_1 src1_sel:DWORD
	v_and_b32_sdwa v29, v4, v155 dst_sel:DWORD dst_unused:UNUSED_PAD src0_sel:WORD_1 src1_sel:DWORD
	v_add3_u32 v4, v4, v29, s68
	v_add3_u32 v5, v5, v28, s68
	v_and_b32_sdwa v28, v13, v155 dst_sel:DWORD dst_unused:UNUSED_PAD src0_sel:WORD_1 src1_sel:DWORD
	v_and_b32_sdwa v29, v12, v155 dst_sel:DWORD dst_unused:UNUSED_PAD src0_sel:WORD_1 src1_sel:DWORD
	v_add3_u32 v13, v13, v28, s68
	v_add3_u32 v12, v12, v29, s68
	v_and_b32_e32 v13, 0xffff0000, v13
	v_and_b32_e32 v12, 0xffff0000, v12
	v_or_b32_sdwa v5, v13, v5 dst_sel:DWORD dst_unused:UNUSED_PAD src0_sel:DWORD src1_sel:WORD_1
	v_or_b32_sdwa v4, v12, v4 dst_sel:DWORD dst_unused:UNUSED_PAD src0_sel:DWORD src1_sel:WORD_1
	s_waitcnt lgkmcnt(0)
	v_mov_b32_e32 v12, v32
	v_mov_b32_e32 v13, v34
	v_pk_mul_f32 v[6:7], v[6:7], v[12:13]
	v_mov_b32_e32 v34, v33
	v_pk_mul_f32 v[12:13], v[30:31], v[34:35]
	v_and_b32_sdwa v28, v7, v155 dst_sel:DWORD dst_unused:UNUSED_PAD src0_sel:WORD_1 src1_sel:DWORD
	v_and_b32_sdwa v29, v6, v155 dst_sel:DWORD dst_unused:UNUSED_PAD src0_sel:WORD_1 src1_sel:DWORD
	v_add3_u32 v6, v6, v29, s68
	v_add3_u32 v7, v7, v28, s68
	v_and_b32_sdwa v28, v13, v155 dst_sel:DWORD dst_unused:UNUSED_PAD src0_sel:WORD_1 src1_sel:DWORD
	v_and_b32_sdwa v29, v12, v155 dst_sel:DWORD dst_unused:UNUSED_PAD src0_sel:WORD_1 src1_sel:DWORD
	v_add3_u32 v13, v13, v28, s68
	v_add3_u32 v12, v12, v29, s68
	ds_read_b128 v[28:31], v45
	v_and_b32_e32 v13, 0xffff0000, v13
	v_and_b32_e32 v12, 0xffff0000, v12
	v_add_co_u32_e32 v10, vcc, s77, v10
	v_or_b32_sdwa v7, v13, v7 dst_sel:DWORD dst_unused:UNUSED_PAD src0_sel:DWORD src1_sel:WORD_1
	v_or_b32_sdwa v6, v12, v6 dst_sel:DWORD dst_unused:UNUSED_PAD src0_sel:DWORD src1_sel:WORD_1
	v_addc_co_u32_e32 v11, vcc, 0, v11, vcc
	global_store_dwordx4 v[10:11], v[4:7], off offset:1024
	s_waitcnt lgkmcnt(0)
; __device__ __forceinline__ unsigned pack2(float a, float b) { return (unsigned)f2bf(a) | ((unsigned)f2bf(b) << 16); }
; __device__ __forceinline__ float bflo(unsigned w) { return __uint_as_float(w << 16); }
; __device__ __forceinline__ float bfhi(unsigned w) { return __uint_as_float(w & 0xffff0000u); }
; __device__ __forceinline__ float silu_f(float g) { return g / (1.f + __expf(-g)); }
; template <int DH, int MODE>
; __device__ void attn_item(const Params& p, int layer, int b, int blk, int head, char* smem) {
;     ...
; #pragma unroll
;     for (int i = 0; i < NCH; ++i) {
;       int q = tid + 256 * i, r = q / CPR, c = (q % CPR) * 8;
;       float4 m0 = *reinterpret_cast<const float4*>(Of + r * OST + c);
;       float4 m1 = *reinterpret_cast<const float4*>(Of + r * OST + c + 4);
;       float mm[8] = {m0.x, m0.y, m0.z, m0.w, m1.x, m1.y, m1.z, m1.w};
;       unsigned gw[4] = {gt[i].x, gt[i].y, gt[i].z, gt[i].w};
;       unsigned ow[4];
; #pragma unroll
;       for (int e = 0; e < 4; ++e)
;         ow[e] = pack2(mm[2 * e] * silu_f(bflo(gw[e])), mm[2 * e + 1] * silu_f(bfhi(gw[e])));
;       *reinterpret_cast<uint4*>(Y + (tq0 + r) * YW + ycol + c) = make_uint4(ow[0], ow[1], ow[2], ow[3]);
;     }
	v_mov_b32_e32 v10, v28
	v_mov_b32_e32 v11, v30
	ds_read_b128 v[4:7], v45 offset:16
	v_pk_mul_f32 v[0:1], v[0:1], v[10:11]
	v_mov_b32_e32 v30, v29
	v_pk_mul_f32 v[10:11], v[24:25], v[30:31]
	v_and_b32_sdwa v12, v1, v155 dst_sel:DWORD dst_unused:UNUSED_PAD src0_sel:WORD_1 src1_sel:DWORD
	v_and_b32_sdwa v13, v0, v155 dst_sel:DWORD dst_unused:UNUSED_PAD src0_sel:WORD_1 src1_sel:DWORD
	v_add3_u32 v0, v0, v13, s68
	v_add3_u32 v1, v1, v12, s68
	v_and_b32_sdwa v12, v11, v155 dst_sel:DWORD dst_unused:UNUSED_PAD src0_sel:WORD_1 src1_sel:DWORD
	v_and_b32_sdwa v13, v10, v155 dst_sel:DWORD dst_unused:UNUSED_PAD src0_sel:WORD_1 src1_sel:DWORD
	v_add3_u32 v11, v11, v12, s68
	v_add3_u32 v10, v10, v13, s68
	v_and_b32_e32 v11, 0xffff0000, v11
	v_and_b32_e32 v10, 0xffff0000, v10
	v_or_b32_sdwa v1, v11, v1 dst_sel:DWORD dst_unused:UNUSED_PAD src0_sel:DWORD src1_sel:WORD_1
	v_or_b32_sdwa v0, v10, v0 dst_sel:DWORD dst_unused:UNUSED_PAD src0_sel:DWORD src1_sel:WORD_1
	s_waitcnt lgkmcnt(0)
	v_mov_b32_e32 v10, v4
	v_mov_b32_e32 v11, v6
	v_pk_mul_f32 v[2:3], v[2:3], v[10:11]
	v_mov_b32_e32 v6, v5
	v_pk_mul_f32 v[4:5], v[26:27], v[6:7]
	v_and_b32_sdwa v6, v3, v155 dst_sel:DWORD dst_unused:UNUSED_PAD src0_sel:WORD_1 src1_sel:DWORD
	v_and_b32_sdwa v7, v2, v155 dst_sel:DWORD dst_unused:UNUSED_PAD src0_sel:WORD_1 src1_sel:DWORD
	v_add3_u32 v2, v2, v7, s68
	v_add3_u32 v3, v3, v6, s68
	v_and_b32_sdwa v6, v5, v155 dst_sel:DWORD dst_unused:UNUSED_PAD src0_sel:WORD_1 src1_sel:DWORD
	v_and_b32_sdwa v7, v4, v155 dst_sel:DWORD dst_unused:UNUSED_PAD src0_sel:WORD_1 src1_sel:DWORD
	v_add3_u32 v5, v5, v6, s68
	v_add3_u32 v4, v4, v7, s68
	v_and_b32_e32 v5, 0xffff0000, v5
	v_and_b32_e32 v4, 0xffff0000, v4
	v_or_b32_sdwa v3, v5, v3 dst_sel:DWORD dst_unused:UNUSED_PAD src0_sel:DWORD src1_sel:WORD_1
	v_or_b32_sdwa v2, v4, v2 dst_sel:DWORD dst_unused:UNUSED_PAD src0_sel:DWORD src1_sel:WORD_1
	ds_read_b128 v[4:7], v44
	v_add_co_u32_e32 v8, vcc, s77, v8
	s_nop 1
	v_addc_co_u32_e32 v9, vcc, 0, v9, vcc
	global_store_dwordx4 v[8:9], v[0:3], off offset:1024
	s_waitcnt lgkmcnt(0)
	v_mov_b32_e32 v8, v4
	v_mov_b32_e32 v9, v6
	ds_read_b128 v[0:3], v44 offset:16
	v_pk_mul_f32 v[8:9], v[16:17], v[8:9]
	v_mov_b32_e32 v6, v5
	v_pk_mul_f32 v[4:5], v[18:19], v[6:7]
	v_and_b32_sdwa v6, v9, v155 dst_sel:DWORD dst_unused:UNUSED_PAD src0_sel:WORD_1 src1_sel:DWORD
	v_and_b32_sdwa v7, v8, v155 dst_sel:DWORD dst_unused:UNUSED_PAD src0_sel:WORD_1 src1_sel:DWORD
	v_add3_u32 v7, v8, v7, s68
	v_add3_u32 v6, v9, v6, s68
	v_and_b32_sdwa v8, v5, v155 dst_sel:DWORD dst_unused:UNUSED_PAD src0_sel:WORD_1 src1_sel:DWORD
	v_and_b32_sdwa v9, v4, v155 dst_sel:DWORD dst_unused:UNUSED_PAD src0_sel:WORD_1 src1_sel:DWORD
	v_add3_u32 v5, v5, v8, s68
	v_add3_u32 v4, v4, v9, s68
	v_and_b32_e32 v5, 0xffff0000, v5
	v_and_b32_e32 v4, 0xffff0000, v4
	v_or_b32_sdwa v5, v5, v6 dst_sel:DWORD dst_unused:UNUSED_PAD src0_sel:DWORD src1_sel:WORD_1
	v_or_b32_sdwa v4, v4, v7 dst_sel:DWORD dst_unused:UNUSED_PAD src0_sel:DWORD src1_sel:WORD_1
	s_waitcnt lgkmcnt(0)
	v_mov_b32_e32 v6, v0
	v_mov_b32_e32 v7, v2
	v_pk_mul_f32 v[6:7], v[20:21], v[6:7]
	v_mov_b32_e32 v2, v1
	v_pk_mul_f32 v[0:1], v[22:23], v[2:3]
	v_and_b32_sdwa v2, v7, v155 dst_sel:DWORD dst_unused:UNUSED_PAD src0_sel:WORD_1 src1_sel:DWORD
	v_and_b32_sdwa v3, v6, v155 dst_sel:DWORD dst_unused:UNUSED_PAD src0_sel:WORD_1 src1_sel:DWORD
	v_add3_u32 v2, v7, v2, s68
	v_and_b32_sdwa v7, v0, v155 dst_sel:DWORD dst_unused:UNUSED_PAD src0_sel:WORD_1 src1_sel:DWORD
	v_add3_u32 v3, v6, v3, s68
	v_and_b32_sdwa v6, v1, v155 dst_sel:DWORD dst_unused:UNUSED_PAD src0_sel:WORD_1 src1_sel:DWORD
	v_add3_u32 v0, v0, v7, s68
	v_add3_u32 v1, v1, v6, s68
	v_and_b32_e32 v0, 0xffff0000, v0
	v_and_b32_e32 v1, 0xffff0000, v1
	v_or_b32_sdwa v6, v0, v3 dst_sel:DWORD dst_unused:UNUSED_PAD src0_sel:DWORD src1_sel:WORD_1
	v_add_co_u32_e32 v0, vcc, 0x184a1000, v14
	v_or_b32_sdwa v7, v1, v2 dst_sel:DWORD dst_unused:UNUSED_PAD src0_sel:DWORD src1_sel:WORD_1
	s_nop 0
	v_addc_co_u32_e32 v1, vcc, 0, v15, vcc
	global_store_dwordx4 v[0:1], v[4:7], off offset:1024
	s_barrier

; template <int DH, int MODE>
; __device__ void attn_item(const Params& p, int layer, int b, int blk, int head, char* smem) {
;     ...
;     uint4 gt[NCH];
; #pragma unroll
;     for (int i = 0; i < NCH; ++i) {
;       int q = tid + 256 * i, r = q / CPR, c = (q % CPR) * 8;
;       gt[i] = *reinterpret_cast<const uint4*>(P + (tq0 + r) * NP + gcol + c);
;     }
;     float lis[2][4];
; #pragma unroll
;     for (int m = 0; m < 2; ++m)
; #pragma unroll
;       for (int j = 0; j < 4; ++j) lis[m][j] = (MODE == 0) ? linv_s[wid * 32 + m * 16 + fq * 4 + j] : 1.f;
;     if (MODE == 0) __syncthreads();
; #pragma unroll
;     for (int m = 0; m < 2; ++m)
; #pragma unroll
;       for (int j = 0; j < 4; ++j) {
;         int r = wid * 32 + m * 16 + fq * 4 + j;
; #pragma unroll
;         for (int n = 0; n < NDT; ++n) Of[r * OST + n * 16 + fr] = o[m][n][j] * lis[m][j];
;       }
;     __syncthreads();
.LBB0_1112:
	s_ashr_i32 s7, s79, 31
	s_add_u32 s6, s28, s79
	s_addc_u32 s7, s29, s7
	s_lshl_b32 s8, s76, 1
	s_add_u32 s10, s42, s8
	s_addc_u32 s11, s43, 0
	v_lshl_add_u64 v[2:3], s[12:13], 0, v[134:135]
	v_mov_b64_e32 v[4:5], s[10:11]
	v_mad_u64_u32 v[0:1], s[10:11], v2, s39, v[4:5]
	v_mad_i32_i24 v1, v3, s39, v1
	s_waitcnt vmcnt(12)
	v_lshl_add_u64 v[76:77], v[0:1], 0, v[138:139]
	v_add_u32_e32 v0, 0x100, v161
	v_ashrrev_i32_e32 v1, 31, v0
	v_lshrrev_b32_e32 v1, 28, v1
	v_add_u32_e32 v1, v0, v1
	v_ashrrev_i32_e32 v8, 4, v1
	v_and_b32_e32 v1, -16, v1
	s_waitcnt vmcnt(5)
	v_sub_u32_e32 v99, v0, v1
	v_lshlrev_b32_e32 v0, 3, v99
	v_ashrrev_i32_e32 v1, 31, v0
	s_waitcnt vmcnt(3)
	v_lshlrev_b64 v[92:93], 1, v[0:1]
	v_add_u32_e32 v0, 0x200, v161
	v_ashrrev_i32_e32 v1, 31, v0
	v_lshrrev_b32_e32 v1, 28, v1
	v_add_u32_e32 v1, v0, v1
	v_ashrrev_i32_e32 v9, 31, v8
	v_ashrrev_i32_e32 v94, 4, v1
	v_and_b32_e32 v1, -16, v1
	v_lshl_add_u64 v[10:11], s[12:13], 0, v[8:9]
	v_sub_u32_e32 v9, v0, v1
	v_lshlrev_b32_e32 v0, 3, v9
	v_ashrrev_i32_e32 v1, 31, v0
	v_lshlrev_b64 v[100:101], 1, v[0:1]
	v_add_u32_e32 v0, 0x300, v161
	v_ashrrev_i32_e32 v1, 31, v0
	v_lshrrev_b32_e32 v1, 28, v1
	v_add_u32_e32 v1, v0, v1
	v_ashrrev_i32_e32 v102, 4, v1
	v_and_b32_e32 v1, -16, v1
	v_sub_u32_e32 v128, v0, v1
	v_lshlrev_b32_e32 v0, 3, v128
	v_ashrrev_i32_e32 v1, 31, v0
	s_waitcnt vmcnt(0)
	v_lshlrev_b64 v[106:107], 1, v[0:1]
	v_add_u32_e32 v0, 0x400, v161
	v_ashrrev_i32_e32 v1, 31, v0
	v_lshrrev_b32_e32 v1, 28, v1
	v_add_u32_e32 v1, v0, v1
	v_ashrrev_i32_e32 v103, 31, v102
	v_ashrrev_i32_e32 v108, 4, v1
	v_and_b32_e32 v1, -16, v1
	v_lshl_add_u64 v[104:105], s[12:13], 0, v[102:103]
	v_sub_u32_e32 v103, v0, v1
	v_lshlrev_b32_e32 v0, 3, v103
	v_ashrrev_i32_e32 v1, 31, v0
	v_lshlrev_b64 v[112:113], 1, v[0:1]
	v_add_u32_e32 v0, 0x500, v161
	v_ashrrev_i32_e32 v1, 31, v0
	v_lshrrev_b32_e32 v1, 28, v1
	v_add_u32_e32 v1, v0, v1
	v_ashrrev_i32_e32 v109, 31, v108
	v_ashrrev_i32_e32 v114, 4, v1
	v_and_b32_e32 v1, -16, v1
	v_mad_u64_u32 v[6:7], s[10:11], v10, s39, v[4:5]
	v_ashrrev_i32_e32 v95, 31, v94
	v_lshl_add_u64 v[110:111], s[12:13], 0, v[108:109]
	v_sub_u32_e32 v109, v0, v1
	v_mad_i32_i24 v7, v11, s39, v7
	v_lshl_add_u64 v[96:97], s[12:13], 0, v[94:95]
	v_lshlrev_b32_e32 v0, 3, v109
	v_lshl_add_u64 v[78:79], v[6:7], 0, v[92:93]
	v_mad_u64_u32 v[6:7], s[10:11], v96, s39, v[4:5]
	v_ashrrev_i32_e32 v1, 31, v0
	v_mad_i32_i24 v7, v97, s39, v7
	v_lshlrev_b64 v[118:119], 1, v[0:1]
	v_add_u32_e32 v0, 0x600, v161
	v_lshl_add_u64 v[80:81], v[6:7], 0, v[100:101]
	v_mad_u64_u32 v[6:7], s[10:11], v104, s39, v[4:5]
	v_ashrrev_i32_e32 v1, 31, v0
	v_mad_i32_i24 v7, v105, s39, v7
	v_lshrrev_b32_e32 v1, 28, v1
	v_lshl_add_u64 v[82:83], v[6:7], 0, v[106:107]
	v_mad_u64_u32 v[6:7], s[10:11], v110, s39, v[4:5]
	v_ashrrev_i32_e32 v115, 31, v114
	v_add_u32_e32 v1, v0, v1
	v_mad_i32_i24 v7, v111, s39, v7
	v_lshl_add_u64 v[116:117], s[12:13], 0, v[114:115]
	v_ashrrev_i32_e32 v120, 4, v1
	v_and_b32_e32 v1, -16, v1
	v_lshl_add_u64 v[84:85], v[6:7], 0, v[112:113]
	v_mad_u64_u32 v[6:7], s[10:11], v116, s39, v[4:5]
	v_sub_u32_e32 v115, v0, v1
	v_ashrrev_i32_e32 v121, 31, v120
	v_mad_i32_i24 v7, v117, s39, v7
	v_lshlrev_b32_e32 v0, 3, v115
	v_lshl_add_u64 v[122:123], s[12:13], 0, v[120:121]
	v_lshl_add_u64 v[86:87], v[6:7], 0, v[118:119]
	v_mad_u64_u32 v[6:7], s[10:11], v122, s39, v[4:5]
	v_ashrrev_i32_e32 v1, 31, v0
	v_mad_i32_i24 v7, v123, s39, v7
	v_lshlrev_b64 v[124:125], 1, v[0:1]
	v_lshl_add_u64 v[0:1], v[6:7], 0, v[124:125]
	v_add_u32_e32 v6, 0x700, v161
	v_ashrrev_i32_e32 v7, 31, v6
	v_lshrrev_b32_e32 v7, 28, v7
	v_add_u32_e32 v7, v6, v7
	v_ashrrev_i32_e32 v126, 4, v7
	v_and_b32_e32 v7, -16, v7
	v_sub_u32_e32 v121, v6, v7
	v_lshlrev_b32_e32 v6, 3, v121
	v_ashrrev_i32_e32 v127, 31, v126
	v_lshl_add_u64 v[88:89], s[12:13], 0, v[126:127]
	v_ashrrev_i32_e32 v7, 31, v6
	v_mad_u64_u32 v[4:5], s[10:11], v88, s39, v[4:5]
	v_lshlrev_b64 v[90:91], 1, v[6:7]
	v_lshl_or_b32 v6, v137, 2, v130
	v_mad_i32_i24 v5, v89, s39, v5
	v_mul_lo_u32 v6, v6, s55
	v_lshl_add_u64 v[4:5], v[4:5], 0, v[90:91]
	v_lshl_add_u32 v95, v162, 2, v6
	s_barrier
	ds_write2_b32 v95, v12, v48 offset1:16
	ds_write2_b32 v95, v52, v56 offset0:32 offset1:48
	ds_write2_b32 v95, v60, v64 offset0:64 offset1:80
	ds_write2_b32 v95, v68, v72 offset0:96 offset1:112
	ds_write2_b32 v95, v13, v49 offset0:132 offset1:148
	ds_write2_b32 v95, v53, v57 offset0:164 offset1:180
	ds_write2_b32 v95, v61, v65 offset0:196 offset1:212
	ds_write2_b32 v95, v69, v73 offset0:228 offset1:244
	v_add_u32_e32 v12, 0x400, v95
	v_add_co_u32_e32 v4, vcc, s73, v4
	ds_write2_b32 v12, v14, v50 offset0:8 offset1:24
	ds_write2_b32 v12, v54, v58 offset0:40 offset1:56
	v_addc_co_u32_e32 v5, vcc, 0, v5, vcc
	global_load_dwordx4 v[4:7], v[4:5], off offset:512
	ds_write2_b32 v12, v62, v66 offset0:72 offset1:88
	ds_write2_b32 v12, v70, v74 offset0:104 offset1:120
	ds_write2_b32 v12, v15, v51 offset0:140 offset1:156
	ds_write2_b32 v12, v55, v59 offset0:172 offset1:188
	ds_write2_b32 v12, v63, v67 offset0:204 offset1:220
	ds_write2_b32 v12, v71, v75 offset0:236 offset1:252
	v_add_u32_e32 v12, 0x2000, v95
	ds_write2_b32 v12, v16, v20 offset0:64 offset1:80
	ds_write2_b32 v12, v24, v36 offset0:96 offset1:112
	ds_write2_b32 v12, v28, v40 offset0:128 offset1:144
	ds_write2_b32 v12, v44, v32 offset0:160 offset1:176
	ds_write2_b32 v12, v17, v21 offset0:196 offset1:212
	ds_write2_b32 v12, v25, v37 offset0:228 offset1:244
	v_add_u32_e32 v12, 0x2400, v95
	s_add_u32 s6, s6, s8
	ds_write2_b32 v12, v29, v41 offset0:4 offset1:20
	ds_write2_b32 v12, v45, v33 offset0:36 offset1:52
; __device__ __forceinline__ unsigned pack2(float a, float b) { return (unsigned)f2bf(a) | ((unsigned)f2bf(b) << 16); }
; __device__ __forceinline__ float bflo(unsigned w) { return __uint_as_float(w << 16); }
; __device__ __forceinline__ float bfhi(unsigned w) { return __uint_as_float(w & 0xffff0000u); }
; __device__ __forceinline__ float silu_f(float g) { return g / (1.f + __expf(-g)); }
; template <int DH, int MODE>
; __device__ void attn_item(const Params& p, int layer, int b, int blk, int head, char* smem) {
;     ...
;     uint4 gt[NCH];
; #pragma unroll
;     for (int i = 0; i < NCH; ++i) {
;       int q = tid + 256 * i, r = q / CPR, c = (q % CPR) * 8;
;       gt[i] = *reinterpret_cast<const uint4*>(P + (tq0 + r) * NP + gcol + c);
;     }
;     float lis[2][4];
; #pragma unroll
;     for (int m = 0; m < 2; ++m)
; #pragma unroll
;       for (int j = 0; j < 4; ++j) lis[m][j] = (MODE == 0) ? linv_s[wid * 32 + m * 16 + fq * 4 + j] : 1.f;
;     if (MODE == 0) __syncthreads();
; #pragma unroll
;     for (int m = 0; m < 2; ++m)
; #pragma unroll
;       for (int j = 0; j < 4; ++j) {
;         int r = wid * 32 + m * 16 + fq * 4 + j;
; #pragma unroll
;         for (int n = 0; n < NDT; ++n) Of[r * OST + n * 16 + fr] = o[m][n][j] * lis[m][j];
;       }
;     __syncthreads();
; #pragma unroll
;     for (int i = 0; i < NCH; ++i) {
;       int q = tid + 256 * i, r = q / CPR, c = (q % CPR) * 8;
;       float4 m0 = *reinterpret_cast<const float4*>(Of + r * OST + c);
;       float4 m1 = *reinterpret_cast<const float4*>(Of + r * OST + c + 4);
;       float mm[8] = {m0.x, m0.y, m0.z, m0.w, m1.x, m1.y, m1.z, m1.w};
;       unsigned gw[4] = {gt[i].x, gt[i].y, gt[i].z, gt[i].w};
;       unsigned ow[4];
; #pragma unroll
;       for (int e = 0; e < 4; ++e)
;         ow[e] = pack2(mm[2 * e] * silu_f(bflo(gw[e])), mm[2 * e + 1] * silu_f(bfhi(gw[e])));
	ds_write2_b32 v12, v18, v22 offset0:72 offset1:88
	ds_write2_b32 v12, v26, v38 offset0:104 offset1:120
	ds_write2_b32 v12, v30, v42 offset0:136 offset1:152
	ds_write2_b32 v12, v46, v34 offset0:168 offset1:184
	ds_write2_b32 v12, v19, v23 offset0:204 offset1:220
	ds_write2_b32 v12, v27, v39 offset0:236 offset1:252
	v_add_u32_e32 v12, 0x2800, v95
	s_addc_u32 s7, s7, 0
	ds_write2_b32 v12, v31, v43 offset0:12 offset1:28
	ds_write2_b32 v12, v47, v35 offset0:44 offset1:60
	v_mul_lo_u32 v12, v134, s55
	v_mov_b64_e32 v[14:15], s[6:7]
	v_lshl_add_u32 v98, v136, 2, v12
	v_mad_u64_u32 v[12:13], s[6:7], v2, s63, v[14:15]
	v_mul_lo_u32 v2, v8, s55
	v_mad_i32_i24 v13, v3, s63, v13
	v_lshl_add_u32 v95, v99, 5, v2
	v_mad_u64_u32 v[2:3], s[6:7], v10, s63, v[14:15]
	v_mad_i32_i24 v3, v11, s63, v3
	v_lshl_add_u64 v[26:27], v[2:3], 0, v[92:93]
	v_mul_lo_u32 v2, v94, s55
	v_lshl_add_u32 v93, v9, 5, v2
	v_mad_u64_u32 v[2:3], s[6:7], v96, s63, v[14:15]
	v_mad_i32_i24 v3, v97, s63, v3
	v_lshl_add_u64 v[20:21], v[2:3], 0, v[100:101]
	v_mul_lo_u32 v2, v102, s55
	v_lshl_add_u32 v92, v128, 5, v2
	v_mad_u64_u32 v[2:3], s[6:7], v104, s63, v[14:15]
	v_mad_i32_i24 v3, v105, s63, v3
	v_lshl_add_u64 v[16:17], v[2:3], 0, v[106:107]
	v_mul_lo_u32 v2, v108, s55
	v_lshl_add_u32 v75, v103, 5, v2
	v_mad_u64_u32 v[2:3], s[6:7], v110, s63, v[14:15]
	v_mad_i32_i24 v3, v111, s63, v3
	v_lshl_add_u64 v[30:31], v[12:13], 0, v[138:139]
	v_lshl_add_u64 v[12:13], v[2:3], 0, v[112:113]
	v_mul_lo_u32 v2, v114, s55
	v_lshl_add_u32 v74, v109, 5, v2
	v_mad_u64_u32 v[2:3], s[6:7], v116, s63, v[14:15]
	v_mad_i32_i24 v3, v117, s63, v3
	v_lshl_add_u64 v[10:11], v[2:3], 0, v[118:119]
	v_mul_lo_u32 v2, v120, s55
	v_lshl_add_u32 v73, v115, 5, v2
	v_mad_u64_u32 v[2:3], s[6:7], v122, s63, v[14:15]
	v_mad_i32_i24 v3, v123, s63, v3
	v_add_co_u32_e32 v0, vcc, s73, v0
	v_lshl_add_u64 v[8:9], v[2:3], 0, v[124:125]
	v_mul_lo_u32 v2, v126, s55
	v_addc_co_u32_e32 v1, vcc, 0, v1, vcc
	v_lshl_add_u32 v72, v121, 5, v2
	global_load_dwordx4 v[0:3], v[0:1], off offset:512
	v_mad_u64_u32 v[14:15], s[6:7], v88, s63, v[14:15]
	v_mad_i32_i24 v15, v89, s63, v15
	v_lshl_add_u64 v[14:15], v[14:15], 0, v[90:91]
	s_waitcnt vmcnt(1)
	v_lshlrev_b32_e32 v22, 16, v5
	v_lshlrev_b32_e32 v23, 16, v4
	v_mul_f32_e32 v18, 0xbfb8aa3b, v23
	v_mul_f32_e32 v19, 0xbfb8aa3b, v22
	v_exp_f32_e32 v18, v18
	v_exp_f32_e32 v19, v19
	v_and_b32_e32 v24, 0xffff0000, v5
	v_and_b32_e32 v28, 0xffff0000, v4
	v_mul_f32_e32 v4, 0xbfb8aa3b, v28
	v_pk_add_f32 v[18:19], v[18:19], 1.0 op_sel_hi:[1,0]
	v_exp_f32_e32 v4, v4
	v_and_b32_e32 v34, 0xffff0000, v6
	v_rcp_f32_e32 v19, v19
	s_nop 0
	v_mul_f32_e32 v19, v22, v19
	v_mul_f32_e32 v5, 0xbfb8aa3b, v24
	v_exp_f32_e32 v5, v5
	s_nop 0
	v_pk_add_f32 v[4:5], v[4:5], 1.0 op_sel_hi:[1,0]
	v_rcp_f32_e32 v18, v18
	s_nop 0
	v_mul_f32_e32 v18, v23, v18
	v_lshlrev_b32_e32 v33, 16, v6
	v_rcp_f32_e32 v23, v5
	s_nop 0
	v_mul_f32_e32 v23, v24, v23
	v_lshlrev_b32_e32 v32, 16, v7
	v_mul_f32_e32 v24, 0xbfb8aa3b, v33
	v_mul_f32_e32 v25, 0xbfb8aa3b, v32
	v_exp_f32_e32 v24, v24
	v_exp_f32_e32 v25, v25
	v_rcp_f32_e32 v22, v4
	s_nop 0
	v_mul_f32_e32 v22, v28, v22
	v_and_b32_e32 v28, 0xffff0000, v7
	v_pk_add_f32 v[4:5], v[24:25], 1.0 op_sel_hi:[1,0]
	v_mul_f32_e32 v6, 0xbfb8aa3b, v34
	v_exp_f32_e32 v6, v6
	s_waitcnt vmcnt(0)
	v_lshlrev_b32_e32 v40, 16, v3
	v_lshlrev_b32_e32 v41, 16, v2
	v_rcp_f32_e32 v25, v5
	s_nop 0
	v_mul_f32_e32 v25, v32, v25
	v_mul_f32_e32 v7, 0xbfb8aa3b, v28
	v_exp_f32_e32 v7, v7
	s_nop 0
	v_pk_add_f32 v[6:7], v[6:7], 1.0 op_sel_hi:[1,0]
	v_rcp_f32_e32 v24, v4
	s_nop 0
	v_mul_f32_e32 v24, v33, v24
	v_rcp_f32_e32 v29, v7
	s_nop 0
	v_mul_f32_e32 v29, v28, v29
	v_lshlrev_b32_e32 v32, 16, v1
	v_lshlrev_b32_e32 v36, 16, v0
	v_mul_f32_e32 v4, 0xbfb8aa3b, v36
	v_mul_f32_e32 v5, 0xbfb8aa3b, v32
	v_exp_f32_e32 v4, v4
	v_exp_f32_e32 v5, v5
	v_rcp_f32_e32 v28, v6
	s_nop 0
	v_mul_f32_e32 v28, v34, v28
	v_and_b32_e32 v6, 0xffff0000, v1
	v_pk_add_f32 v[4:5], v[4:5], 1.0 op_sel_hi:[1,0]
	v_and_b32_e32 v34, 0xffff0000, v0
	v_mul_f32_e32 v0, 0xbfb8aa3b, v34
	v_exp_f32_e32 v0, v0
	v_and_b32_e32 v42, 0xffff0000, v3
	v_rcp_f32_e32 v33, v5
	s_nop 0
	v_mul_f32_e32 v33, v32, v33
	v_mul_f32_e32 v1, 0xbfb8aa3b, v6
	v_exp_f32_e32 v1, v1
	s_nop 0
	v_pk_add_f32 v[0:1], v[0:1], 1.0 op_sel_hi:[1,0]
	v_rcp_f32_e32 v32, v4
	s_nop 0
	v_mul_f32_e32 v32, v36, v32
	v_rcp_f32_e32 v35, v1
	s_nop 0
	v_mul_f32_e32 v35, v6, v35
	v_add_co_u32_e64 v4, s[6:7], s73, v86
	s_nop 0
	s_nop 0
	v_addc_co_u32_e64 v5, s[6:7], 0, v87, s[6:7]
	global_load_dwordx4 v[4:7], v[4:5], off offset:512
	v_mul_f32_e32 v36, 0xbfb8aa3b, v41
	v_mul_f32_e32 v37, 0xbfb8aa3b, v40
	v_exp_f32_e32 v36, v36
	v_exp_f32_e32 v37, v37
	v_rcp_f32_e32 v1, v0
	s_nop 0
	v_mul_f32_e32 v34, v34, v1
	v_and_b32_e32 v43, 0xffff0000, v2
	v_pk_add_f32 v[0:1], v[36:37], 1.0 op_sel_hi:[1,0]
	v_mul_f32_e32 v2, 0xbfb8aa3b, v43
	v_exp_f32_e32 v2, v2
	v_rcp_f32_e32 v37, v1
	s_nop 0
	v_mul_f32_e32 v37, v40, v37
	v_mul_f32_e32 v3, 0xbfb8aa3b, v42
	v_exp_f32_e32 v3, v3
	s_nop 0
	v_pk_add_f32 v[38:39], v[2:3], 1.0 op_sel_hi:[1,0]
	v_rcp_f32_e32 v36, v0
	s_nop 0
	v_mul_f32_e32 v36, v41, v36
	v_rcp_f32_e32 v39, v39
	s_nop 0
	v_mul_f32_e32 v39, v42, v39
	v_add_co_u32_e64 v0, s[6:7], s73, v84
	s_waitcnt vmcnt(0)
; __device__ __forceinline__ unsigned pack2(float a, float b) { return (unsigned)f2bf(a) | ((unsigned)f2bf(b) << 16); }
; __device__ __forceinline__ float bflo(unsigned w) { return __uint_as_float(w << 16); }
; __device__ __forceinline__ float bfhi(unsigned w) { return __uint_as_float(w & 0xffff0000u); }
; __device__ __forceinline__ float silu_f(float g) { return g / (1.f + __expf(-g)); }
; template <int DH, int MODE>
; __device__ void attn_item(const Params& p, int layer, int b, int blk, int head, char* smem) {
;     ...
;     uint4 gt[NCH];
; #pragma unroll
;     for (int i = 0; i < NCH; ++i) {
;       int q = tid + 256 * i, r = q / CPR, c = (q % CPR) * 8;
;       gt[i] = *reinterpret_cast<const uint4*>(P + (tq0 + r) * NP + gcol + c);
;     }
;     float lis[2][4];
; #pragma unroll
;     for (int m = 0; m < 2; ++m)
; #pragma unroll
;       for (int j = 0; j < 4; ++j) lis[m][j] = (MODE == 0) ? linv_s[wid * 32 + m * 16 + fq * 4 + j] : 1.f;
;     if (MODE == 0) __syncthreads();
; #pragma unroll
;     for (int m = 0; m < 2; ++m)
; #pragma unroll
;       for (int j = 0; j < 4; ++j) {
;         int r = wid * 32 + m * 16 + fq * 4 + j;
; #pragma unroll
;         for (int n = 0; n < NDT; ++n) Of[r * OST + n * 16 + fr] = o[m][n][j] * lis[m][j];
;       }
;     __syncthreads();
; #pragma unroll
;     for (int i = 0; i < NCH; ++i) {
;       int q = tid + 256 * i, r = q / CPR, c = (q % CPR) * 8;
;       float4 m0 = *reinterpret_cast<const float4*>(Of + r * OST + c);
;       float4 m1 = *reinterpret_cast<const float4*>(Of + r * OST + c + 4);
;       float mm[8] = {m0.x, m0.y, m0.z, m0.w, m1.x, m1.y, m1.z, m1.w};
;       unsigned gw[4] = {gt[i].x, gt[i].y, gt[i].z, gt[i].w};
;       unsigned ow[4];
; #pragma unroll
;       for (int e = 0; e < 4; ++e)
;         ow[e] = pack2(mm[2 * e] * silu_f(bflo(gw[e])), mm[2 * e + 1] * silu_f(bfhi(gw[e])));
	v_lshlrev_b32_e32 v46, 16, v5
	v_lshlrev_b32_e32 v47, 16, v4
	v_mul_f32_e32 v40, 0xbfb8aa3b, v47
	v_mul_f32_e32 v41, 0xbfb8aa3b, v46
	v_exp_f32_e32 v40, v40
	v_exp_f32_e32 v41, v41
	v_addc_co_u32_e64 v1, s[6:7], 0, v85, s[6:7]
	v_rcp_f32_e32 v38, v38
	s_nop 0
	v_mul_f32_e32 v38, v43, v38
	v_pk_add_f32 v[40:41], v[40:41], 1.0 op_sel_hi:[1,0]
	v_and_b32_e32 v42, 0xffff0000, v5
	global_load_dwordx4 v[0:3], v[0:1], off offset:512
	v_and_b32_e32 v48, 0xffff0000, v4
	v_mul_f32_e32 v4, 0xbfb8aa3b, v48
	v_rcp_f32_e32 v41, v41
	s_nop 0
	v_mul_f32_e32 v41, v46, v41
	v_exp_f32_e32 v4, v4
	v_mul_f32_e32 v5, 0xbfb8aa3b, v42
	v_exp_f32_e32 v5, v5
	s_nop 0
	v_pk_add_f32 v[4:5], v[4:5], 1.0 op_sel_hi:[1,0]
	v_rcp_f32_e32 v40, v40
	s_nop 0
	v_mul_f32_e32 v40, v47, v40
	v_lshlrev_b32_e32 v49, 16, v6
	v_rcp_f32_e32 v43, v5
	s_nop 0
	v_mul_f32_e32 v43, v42, v43
	v_lshlrev_b32_e32 v46, 16, v7
	v_mul_f32_e32 v44, 0xbfb8aa3b, v49
	v_mul_f32_e32 v45, 0xbfb8aa3b, v46
	v_exp_f32_e32 v44, v44
	v_exp_f32_e32 v45, v45
	v_rcp_f32_e32 v42, v4
	s_nop 0
	v_mul_f32_e32 v42, v48, v42
	v_and_b32_e32 v47, 0xffff0000, v7
	v_pk_add_f32 v[4:5], v[44:45], 1.0 op_sel_hi:[1,0]
	v_and_b32_e32 v48, 0xffff0000, v6
	v_mul_f32_e32 v6, 0xbfb8aa3b, v48
	v_exp_f32_e32 v6, v6
	v_rcp_f32_e32 v45, v5
	s_nop 0
	v_mul_f32_e32 v45, v46, v45
	v_mul_f32_e32 v7, 0xbfb8aa3b, v47
	v_exp_f32_e32 v7, v7
	s_nop 0
	v_pk_add_f32 v[6:7], v[6:7], 1.0 op_sel_hi:[1,0]
	v_rcp_f32_e32 v44, v4
	s_nop 0
	v_mul_f32_e32 v44, v49, v44
	v_rcp_f32_e32 v4, v7
	s_nop 0
	v_mul_f32_e32 v47, v47, v4
	s_waitcnt vmcnt(0)
	v_lshlrev_b32_e32 v50, 16, v1
	v_lshlrev_b32_e32 v51, 16, v0
	v_mul_f32_e32 v4, 0xbfb8aa3b, v51
	v_mul_f32_e32 v5, 0xbfb8aa3b, v50
	v_exp_f32_e32 v4, v4
	v_exp_f32_e32 v5, v5
	v_rcp_f32_e32 v46, v6
	s_nop 0
	v_mul_f32_e32 v46, v48, v46
	v_and_b32_e32 v6, 0xffff0000, v1
	v_pk_add_f32 v[4:5], v[4:5], 1.0 op_sel_hi:[1,0]
	v_and_b32_e32 v54, 0xffff0000, v0
	v_mul_f32_e32 v0, 0xbfb8aa3b, v54
	v_exp_f32_e32 v0, v0
	v_lshlrev_b32_e32 v58, 16, v2
	v_rcp_f32_e32 v49, v5
	s_nop 0
	v_mul_f32_e32 v49, v50, v49
	v_mul_f32_e32 v1, 0xbfb8aa3b, v6
	v_exp_f32_e32 v1, v1
	s_nop 0
	v_pk_add_f32 v[0:1], v[0:1], 1.0 op_sel_hi:[1,0]
	v_rcp_f32_e32 v48, v4
	s_nop 0
	v_mul_f32_e32 v48, v51, v48
	v_lshlrev_b32_e32 v57, 16, v3
	v_rcp_f32_e32 v51, v1
	s_nop 0
	v_mul_f32_e32 v51, v6, v51
	v_add_co_u32_e64 v4, s[6:7], s73, v82
	s_nop 0
	s_nop 0
	v_addc_co_u32_e64 v5, s[6:7], 0, v83, s[6:7]
	global_load_dwordx4 v[4:7], v[4:5], off offset:512
	v_mul_f32_e32 v50, 0xbfb8aa3b, v58
	v_exp_f32_e32 v52, v50
	v_mul_f32_e32 v50, 0xbfb8aa3b, v57
	v_exp_f32_e32 v53, v50
	v_rcp_f32_e32 v50, v0
	s_nop 0
	v_mul_f32_e32 v50, v54, v50
	v_and_b32_e32 v56, 0xffff0000, v3
	v_pk_add_f32 v[0:1], v[52:53], 1.0 op_sel_hi:[1,0]
	v_and_b32_e32 v59, 0xffff0000, v2
	v_mul_f32_e32 v2, 0xbfb8aa3b, v59
	v_exp_f32_e32 v2, v2
	v_rcp_f32_e32 v53, v1
	s_nop 0
	v_mul_f32_e32 v53, v57, v53
	v_mul_f32_e32 v3, 0xbfb8aa3b, v56
	v_exp_f32_e32 v3, v3
	s_nop 0
	v_pk_add_f32 v[54:55], v[2:3], 1.0 op_sel_hi:[1,0]
	v_rcp_f32_e32 v52, v0
	s_nop 0
	v_mul_f32_e32 v52, v58, v52
	v_rcp_f32_e32 v55, v55
	s_nop 0
	v_mul_f32_e32 v55, v56, v55
	v_add_co_u32_e64 v0, s[6:7], s73, v80
	s_waitcnt vmcnt(0)
	v_lshlrev_b32_e32 v62, 16, v5
	v_lshlrev_b32_e32 v63, 16, v4
	v_mul_f32_e32 v56, 0xbfb8aa3b, v63
	v_mul_f32_e32 v57, 0xbfb8aa3b, v62
	v_exp_f32_e32 v56, v56
	v_exp_f32_e32 v57, v57
	v_addc_co_u32_e64 v1, s[6:7], 0, v81, s[6:7]
	v_rcp_f32_e32 v54, v54
	s_nop 0
	v_mul_f32_e32 v54, v59, v54
	v_pk_add_f32 v[56:57], v[56:57], 1.0 op_sel_hi:[1,0]
	v_and_b32_e32 v58, 0xffff0000, v5
	global_load_dwordx4 v[0:3], v[0:1], off offset:512
	v_and_b32_e32 v64, 0xffff0000, v4
	v_mul_f32_e32 v4, 0xbfb8aa3b, v64
	v_rcp_f32_e32 v57, v57
	s_nop 0
	v_mul_f32_e32 v57, v62, v57
	v_exp_f32_e32 v4, v4
	v_mul_f32_e32 v5, 0xbfb8aa3b, v58
	v_exp_f32_e32 v5, v5
	s_nop 0
	v_pk_add_f32 v[4:5], v[4:5], 1.0 op_sel_hi:[1,0]
	v_rcp_f32_e32 v56, v56
	s_nop 0
	v_mul_f32_e32 v56, v63, v56
	v_lshlrev_b32_e32 v65, 16, v6
	v_rcp_f32_e32 v59, v5
	s_nop 0
	v_mul_f32_e32 v59, v58, v59
	v_lshlrev_b32_e32 v62, 16, v7
	v_mul_f32_e32 v60, 0xbfb8aa3b, v65
	v_mul_f32_e32 v61, 0xbfb8aa3b, v62
	v_exp_f32_e32 v60, v60
	v_exp_f32_e32 v61, v61
	v_rcp_f32_e32 v58, v4
	s_nop 0
	v_mul_f32_e32 v58, v64, v58
	v_and_b32_e32 v63, 0xffff0000, v7
	v_pk_add_f32 v[4:5], v[60:61], 1.0 op_sel_hi:[1,0]
	v_and_b32_e32 v64, 0xffff0000, v6
	v_mul_f32_e32 v6, 0xbfb8aa3b, v64
	v_exp_f32_e32 v6, v6
	v_rcp_f32_e32 v61, v5
	s_nop 0
	v_mul_f32_e32 v61, v62, v61
	v_mul_f32_e32 v7, 0xbfb8aa3b, v63
	v_exp_f32_e32 v7, v7
	s_nop 0
	v_pk_add_f32 v[6:7], v[6:7], 1.0 op_sel_hi:[1,0]
	v_rcp_f32_e32 v60, v4
	s_nop 0
	v_mul_f32_e32 v60, v65, v60
	v_rcp_f32_e32 v4, v7
	s_nop 0
	v_mul_f32_e32 v63, v63, v4
	s_waitcnt vmcnt(0)
	v_lshlrev_b32_e32 v66, 16, v1
	v_lshlrev_b32_e32 v67, 16, v0
	v_mul_f32_e32 v4, 0xbfb8aa3b, v67
	v_mul_f32_e32 v5, 0xbfb8aa3b, v66
	v_exp_f32_e32 v4, v4
	v_exp_f32_e32 v5, v5
	v_and_b32_e32 v68, 0xffff0000, v1
	v_rcp_f32_e32 v62, v6
	s_nop 0
	v_mul_f32_e32 v62, v64, v62
	v_pk_add_f32 v[4:5], v[4:5], 1.0 op_sel_hi:[1,0]
	v_and_b32_e32 v69, 0xffff0000, v0
	v_mul_f32_e32 v0, 0xbfb8aa3b, v69
	v_exp_f32_e32 v6, v0
	v_and_b32_e32 v80, 0xffff0000, v2
	v_rcp_f32_e32 v1, v5
	s_nop 0
	v_mul_f32_e32 v1, v66, v1
	v_mul_f32_e32 v7, 0xbfb8aa3b, v68
	v_exp_f32_e32 v7, v7
	s_nop 0
	v_pk_add_f32 v[64:65], v[6:7], 1.0 op_sel_hi:[1,0]
	v_rcp_f32_e32 v0, v4
	s_nop 0
	v_mul_f32_e32 v0, v67, v0
	v_rcp_f32_e32 v65, v65
	s_nop 0
	v_mul_f32_e32 v65, v68, v65
	v_add_co_u32_e64 v4, s[6:7], s73, v78
	s_nop 0
	s_nop 0
	v_addc_co_u32_e64 v5, s[6:7], 0, v79, s[6:7]
	global_load_dwordx4 v[4:7], v[4:5], off offset:512
	v_lshlrev_b32_e32 v78, 16, v3
	v_lshlrev_b32_e32 v79, 16, v2
	v_mul_f32_e32 v66, 0xbfb8aa3b, v79
	v_mul_f32_e32 v67, 0xbfb8aa3b, v78
	v_exp_f32_e32 v66, v66
	v_exp_f32_e32 v67, v67
	v_and_b32_e32 v70, 0xffff0000, v3
	v_rcp_f32_e32 v64, v64
	s_nop 0
	v_mul_f32_e32 v64, v69, v64
	v_pk_add_f32 v[66:67], v[66:67], 1.0 op_sel_hi:[1,0]
	v_mul_f32_e32 v2, 0xbfb8aa3b, v80
	v_exp_f32_e32 v68, v2
	v_mul_f32_e32 v69, 0xbfb8aa3b, v70
	v_exp_f32_e32 v69, v69
	v_rcp_f32_e32 v3, v67
	s_nop 0
	v_mul_f32_e32 v3, v78, v3
	v_pk_add_f32 v[68:69], v[68:69], 1.0 op_sel_hi:[1,0]
	v_rcp_f32_e32 v2, v66
	s_nop 0
	v_mul_f32_e32 v2, v79, v2
	v_rcp_f32_e32 v67, v69
	s_nop 0
	v_mul_f32_e32 v67, v70, v67
	v_add_co_u32_e64 v70, s[6:7], s73, v76
	s_nop 0
	s_nop 0
	v_addc_co_u32_e64 v71, s[6:7], 0, v77, s[6:7]
	global_load_dwordx4 v[76:79], v[70:71], off offset:512
	v_rcp_f32_e32 v66, v68
	s_nop 0
	v_mul_f32_e32 v66, v80, v66
	s_waitcnt vmcnt(1)
	v_lshlrev_b32_e32 v82, 16, v5
	v_lshlrev_b32_e32 v83, 16, v4
	v_mul_f32_e32 v70, 0xbfb8aa3b, v83
	v_mul_f32_e32 v71, 0xbfb8aa3b, v82
	v_exp_f32_e32 v70, v70
	v_exp_f32_e32 v71, v71
	v_and_b32_e32 v80, 0xffff0000, v5
	v_and_b32_e32 v84, 0xffff0000, v4
	v_mul_f32_e32 v4, 0xbfb8aa3b, v84
	v_pk_add_f32 v[68:69], v[70:71], 1.0 op_sel_hi:[1,0]
	v_exp_f32_e32 v70, v4
	s_waitcnt lgkmcnt(0)
	s_barrier
; __device__ __forceinline__ unsigned pack2(float a, float b) { return (unsigned)f2bf(a) | ((unsigned)f2bf(b) << 16); }
; __device__ __forceinline__ float bflo(unsigned w) { return __uint_as_float(w << 16); }
; __device__ __forceinline__ float bfhi(unsigned w) { return __uint_as_float(w & 0xffff0000u); }
; __device__ __forceinline__ float silu_f(float g) { return g / (1.f + __expf(-g)); }
; template <int DH, int MODE>
; __device__ void attn_item(const Params& p, int layer, int b, int blk, int head, char* smem) {
;     ...
; #pragma unroll
;     for (int i = 0; i < NCH; ++i) {
;       int q = tid + 256 * i, r = q / CPR, c = (q % CPR) * 8;
;       float4 m0 = *reinterpret_cast<const float4*>(Of + r * OST + c);
;       float4 m1 = *reinterpret_cast<const float4*>(Of + r * OST + c + 4);
;       float mm[8] = {m0.x, m0.y, m0.z, m0.w, m1.x, m1.y, m1.z, m1.w};
;       unsigned gw[4] = {gt[i].x, gt[i].y, gt[i].z, gt[i].w};
;       unsigned ow[4];
; #pragma unroll
;       for (int e = 0; e < 4; ++e)
;         ow[e] = pack2(mm[2 * e] * silu_f(bflo(gw[e])), mm[2 * e + 1] * silu_f(bfhi(gw[e])));
;       *reinterpret_cast<uint4*>(Y + (tq0 + r) * YW + ycol + c) = make_uint4(ow[0], ow[1], ow[2], ow[3]);
;     }
	v_mul_f32_e32 v71, 0xbfb8aa3b, v80
	v_exp_f32_e32 v71, v71
	v_rcp_f32_e32 v5, v69
	s_nop 0
	v_mul_f32_e32 v5, v82, v5
	v_pk_add_f32 v[70:71], v[70:71], 1.0 op_sel_hi:[1,0]
	v_rcp_f32_e32 v4, v68
	s_nop 0
	v_mul_f32_e32 v4, v83, v4
	v_rcp_f32_e32 v69, v71
	s_nop 0
	v_mul_f32_e32 v69, v80, v69
	v_lshlrev_b32_e32 v82, 16, v7
	v_lshlrev_b32_e32 v85, 16, v6
	v_mul_f32_e32 v80, 0xbfb8aa3b, v85
	v_mul_f32_e32 v81, 0xbfb8aa3b, v82
	v_exp_f32_e32 v80, v80
	v_exp_f32_e32 v81, v81
	v_rcp_f32_e32 v68, v70
	s_nop 0
	v_mul_f32_e32 v68, v84, v68
	v_and_b32_e32 v83, 0xffff0000, v7
	v_pk_add_f32 v[70:71], v[80:81], 1.0 op_sel_hi:[1,0]
	v_and_b32_e32 v84, 0xffff0000, v6
	v_mul_f32_e32 v6, 0xbfb8aa3b, v84
	v_exp_f32_e32 v80, v6
	s_waitcnt vmcnt(0)
	v_and_b32_e32 v94, 0xffff0000, v78
	v_mul_f32_e32 v81, 0xbfb8aa3b, v83
	v_exp_f32_e32 v81, v81
	v_rcp_f32_e32 v7, v71
	s_nop 0
	v_mul_f32_e32 v7, v82, v7
	v_pk_add_f32 v[80:81], v[80:81], 1.0 op_sel_hi:[1,0]
	v_rcp_f32_e32 v6, v70
	s_nop 0
	v_mul_f32_e32 v6, v85, v6
	v_rcp_f32_e32 v71, v81
	s_nop 0
	v_mul_f32_e32 v71, v83, v71
	v_lshlrev_b32_e32 v86, 16, v77
	v_lshlrev_b32_e32 v87, 16, v76
	v_mul_f32_e32 v82, 0xbfb8aa3b, v87
	v_mul_f32_e32 v83, 0xbfb8aa3b, v86
	v_exp_f32_e32 v82, v82
	v_exp_f32_e32 v83, v83
	v_rcp_f32_e32 v70, v80
	s_nop 0
	v_mul_f32_e32 v70, v84, v70
	v_and_b32_e32 v88, 0xffff0000, v77
	v_pk_add_f32 v[80:81], v[82:83], 1.0 op_sel_hi:[1,0]
	v_and_b32_e32 v83, 0xffff0000, v76
	v_mul_f32_e32 v76, 0xbfb8aa3b, v83
	v_exp_f32_e32 v76, v76
	v_rcp_f32_e32 v85, v81
	s_nop 0
	v_mul_f32_e32 v85, v86, v85
	v_mul_f32_e32 v77, 0xbfb8aa3b, v88
	v_exp_f32_e32 v77, v77
	s_nop 0
	v_pk_add_f32 v[76:77], v[76:77], 1.0 op_sel_hi:[1,0]
	v_rcp_f32_e32 v84, v80
	s_nop 0
	v_mul_f32_e32 v84, v87, v84
	v_rcp_f32_e32 v87, v77
	s_nop 0
	v_mul_f32_e32 v87, v88, v87
	v_lshlrev_b32_e32 v90, 16, v78
	v_lshlrev_b32_e32 v82, 16, v79
	v_mul_f32_e32 v80, 0xbfb8aa3b, v90
	v_mul_f32_e32 v81, 0xbfb8aa3b, v82
	v_exp_f32_e32 v80, v80
	v_exp_f32_e32 v81, v81
	v_rcp_f32_e32 v86, v76
	s_nop 0
	v_mul_f32_e32 v86, v83, v86
	v_and_b32_e32 v83, 0xffff0000, v79
	v_pk_add_f32 v[76:77], v[80:81], 1.0 op_sel_hi:[1,0]
	v_mul_f32_e32 v78, 0xbfb8aa3b, v94
	v_exp_f32_e32 v78, v78
	v_rcp_f32_e32 v89, v77
	s_nop 0
	v_mul_f32_e32 v89, v82, v89
	v_mul_f32_e32 v79, 0xbfb8aa3b, v83
	v_exp_f32_e32 v79, v79
	s_nop 0
	v_pk_add_f32 v[80:81], v[78:79], 1.0 op_sel_hi:[1,0]
	v_rcp_f32_e32 v88, v76
	s_nop 0
	v_mul_f32_e32 v88, v90, v88
	v_rcp_f32_e32 v91, v81
	s_nop 0
	v_mul_f32_e32 v91, v83, v91
	ds_read_b128 v[76:79], v98
	v_rcp_f32_e32 v90, v80
	s_nop 0
	v_mul_f32_e32 v90, v94, v90
	ds_read_b128 v[80:83], v98 offset:16
	v_add_co_u32_e32 v30, vcc, s70, v30
	s_waitcnt lgkmcnt(1)
	v_mov_b32_e32 v96, v76
	v_mov_b32_e32 v97, v78
	v_pk_mul_f32 v[84:85], v[84:85], v[96:97]
	v_mov_b32_e32 v78, v77
	v_pk_mul_f32 v[76:77], v[86:87], v[78:79]
	v_and_b32_sdwa v78, v85, v155 dst_sel:DWORD dst_unused:UNUSED_PAD src0_sel:WORD_1 src1_sel:DWORD
	v_and_b32_sdwa v79, v84, v155 dst_sel:DWORD dst_unused:UNUSED_PAD src0_sel:WORD_1 src1_sel:DWORD
	v_add3_u32 v79, v84, v79, s54
	v_add3_u32 v78, v85, v78, s54
	v_and_b32_sdwa v84, v77, v155 dst_sel:DWORD dst_unused:UNUSED_PAD src0_sel:WORD_1 src1_sel:DWORD
	v_and_b32_sdwa v85, v76, v155 dst_sel:DWORD dst_unused:UNUSED_PAD src0_sel:WORD_1 src1_sel:DWORD
	v_add3_u32 v77, v77, v84, s54
	v_add3_u32 v76, v76, v85, s54
	v_and_b32_e32 v77, 0xffff0000, v77
	v_and_b32_e32 v76, 0xffff0000, v76
	v_or_b32_sdwa v77, v77, v78 dst_sel:DWORD dst_unused:UNUSED_PAD src0_sel:DWORD src1_sel:WORD_1
	v_or_b32_sdwa v76, v76, v79 dst_sel:DWORD dst_unused:UNUSED_PAD src0_sel:DWORD src1_sel:WORD_1
	s_waitcnt lgkmcnt(0)
	v_mov_b32_e32 v78, v80
	v_mov_b32_e32 v79, v82
	v_pk_mul_f32 v[78:79], v[88:89], v[78:79]
	v_mov_b32_e32 v82, v81
	v_pk_mul_f32 v[80:81], v[90:91], v[82:83]
	v_and_b32_sdwa v82, v79, v155 dst_sel:DWORD dst_unused:UNUSED_PAD src0_sel:WORD_1 src1_sel:DWORD
	v_and_b32_sdwa v83, v78, v155 dst_sel:DWORD dst_unused:UNUSED_PAD src0_sel:WORD_1 src1_sel:DWORD
	v_add3_u32 v78, v78, v83, s54
	v_add3_u32 v79, v79, v82, s54
	v_and_b32_sdwa v82, v81, v155 dst_sel:DWORD dst_unused:UNUSED_PAD src0_sel:WORD_1 src1_sel:DWORD
	v_and_b32_sdwa v83, v80, v155 dst_sel:DWORD dst_unused:UNUSED_PAD src0_sel:WORD_1 src1_sel:DWORD
	v_add3_u32 v81, v81, v82, s54
	v_add3_u32 v80, v80, v83, s54
	v_and_b32_e32 v81, 0xffff0000, v81
	v_and_b32_e32 v80, 0xffff0000, v80
	v_or_b32_sdwa v79, v81, v79 dst_sel:DWORD dst_unused:UNUSED_PAD src0_sel:DWORD src1_sel:WORD_1
	v_or_b32_sdwa v78, v80, v78 dst_sel:DWORD dst_unused:UNUSED_PAD src0_sel:DWORD src1_sel:WORD_1
	ds_read_b128 v[80:83], v95
	v_addc_co_u32_e32 v31, vcc, 0, v31, vcc
	global_store_dwordx4 v[30:31], v[76:79], off offset:2048
	ds_read_b128 v[76:79], v95 offset:16
	s_waitcnt lgkmcnt(1)
	v_mov_b32_e32 v30, v80
	v_mov_b32_e32 v31, v82
	v_pk_mul_f32 v[4:5], v[4:5], v[30:31]
	v_mov_b32_e32 v82, v81
	v_pk_mul_f32 v[30:31], v[68:69], v[82:83]
	v_and_b32_sdwa v68, v5, v155 dst_sel:DWORD dst_unused:UNUSED_PAD src0_sel:WORD_1 src1_sel:DWORD
	v_and_b32_sdwa v69, v4, v155 dst_sel:DWORD dst_unused:UNUSED_PAD src0_sel:WORD_1 src1_sel:DWORD
	v_add3_u32 v4, v4, v69, s54
	v_add3_u32 v5, v5, v68, s54
	v_and_b32_sdwa v68, v31, v155 dst_sel:DWORD dst_unused:UNUSED_PAD src0_sel:WORD_1 src1_sel:DWORD
	v_and_b32_sdwa v69, v30, v155 dst_sel:DWORD dst_unused:UNUSED_PAD src0_sel:WORD_1 src1_sel:DWORD
	v_add3_u32 v31, v31, v68, s54
	v_add3_u32 v30, v30, v69, s54
	v_and_b32_e32 v31, 0xffff0000, v31
	v_and_b32_e32 v30, 0xffff0000, v30
	v_or_b32_sdwa v5, v31, v5 dst_sel:DWORD dst_unused:UNUSED_PAD src0_sel:DWORD src1_sel:WORD_1
	v_or_b32_sdwa v4, v30, v4 dst_sel:DWORD dst_unused:UNUSED_PAD src0_sel:DWORD src1_sel:WORD_1
	s_waitcnt lgkmcnt(0)
; __device__ __forceinline__ unsigned pack2(float a, float b) { return (unsigned)f2bf(a) | ((unsigned)f2bf(b) << 16); }
; __device__ __forceinline__ float bflo(unsigned w) { return __uint_as_float(w << 16); }
; __device__ __forceinline__ float bfhi(unsigned w) { return __uint_as_float(w & 0xffff0000u); }
; __device__ __forceinline__ float silu_f(float g) { return g / (1.f + __expf(-g)); }
; template <int DH, int MODE>
; __device__ void attn_item(const Params& p, int layer, int b, int blk, int head, char* smem) {
;     ...
; #pragma unroll
;     for (int i = 0; i < NCH; ++i) {
;       int q = tid + 256 * i, r = q / CPR, c = (q % CPR) * 8;
;       float4 m0 = *reinterpret_cast<const float4*>(Of + r * OST + c);
;       float4 m1 = *reinterpret_cast<const float4*>(Of + r * OST + c + 4);
;       float mm[8] = {m0.x, m0.y, m0.z, m0.w, m1.x, m1.y, m1.z, m1.w};
;       unsigned gw[4] = {gt[i].x, gt[i].y, gt[i].z, gt[i].w};
;       unsigned ow[4];
; #pragma unroll
;       for (int e = 0; e < 4; ++e)
;         ow[e] = pack2(mm[2 * e] * silu_f(bflo(gw[e])), mm[2 * e + 1] * silu_f(bfhi(gw[e])));
;       *reinterpret_cast<uint4*>(Y + (tq0 + r) * YW + ycol + c) = make_uint4(ow[0], ow[1], ow[2], ow[3]);
;     }
	v_mov_b32_e32 v30, v76
	v_mov_b32_e32 v31, v78
	v_pk_mul_f32 v[6:7], v[6:7], v[30:31]
	v_mov_b32_e32 v78, v77
	v_pk_mul_f32 v[30:31], v[70:71], v[78:79]
	v_and_b32_sdwa v68, v7, v155 dst_sel:DWORD dst_unused:UNUSED_PAD src0_sel:WORD_1 src1_sel:DWORD
	v_and_b32_sdwa v69, v6, v155 dst_sel:DWORD dst_unused:UNUSED_PAD src0_sel:WORD_1 src1_sel:DWORD
	v_add3_u32 v6, v6, v69, s54
	v_add3_u32 v7, v7, v68, s54
	v_and_b32_sdwa v68, v31, v155 dst_sel:DWORD dst_unused:UNUSED_PAD src0_sel:WORD_1 src1_sel:DWORD
	v_and_b32_sdwa v69, v30, v155 dst_sel:DWORD dst_unused:UNUSED_PAD src0_sel:WORD_1 src1_sel:DWORD
	v_add3_u32 v31, v31, v68, s54
	v_add3_u32 v30, v30, v69, s54
	ds_read_b128 v[68:71], v93
	v_and_b32_e32 v31, 0xffff0000, v31
	v_and_b32_e32 v30, 0xffff0000, v30
	v_add_co_u32_e32 v26, vcc, s70, v26
	v_or_b32_sdwa v7, v31, v7 dst_sel:DWORD dst_unused:UNUSED_PAD src0_sel:DWORD src1_sel:WORD_1
	v_or_b32_sdwa v6, v30, v6 dst_sel:DWORD dst_unused:UNUSED_PAD src0_sel:DWORD src1_sel:WORD_1
	v_addc_co_u32_e32 v27, vcc, 0, v27, vcc
	global_store_dwordx4 v[26:27], v[4:7], off offset:2048
	s_waitcnt lgkmcnt(0)
	v_mov_b32_e32 v26, v68
	v_mov_b32_e32 v27, v70
	ds_read_b128 v[4:7], v93 offset:16
	v_pk_mul_f32 v[0:1], v[0:1], v[26:27]
	v_mov_b32_e32 v70, v69
	v_pk_mul_f32 v[26:27], v[64:65], v[70:71]
	v_and_b32_sdwa v30, v1, v155 dst_sel:DWORD dst_unused:UNUSED_PAD src0_sel:WORD_1 src1_sel:DWORD
	v_and_b32_sdwa v31, v0, v155 dst_sel:DWORD dst_unused:UNUSED_PAD src0_sel:WORD_1 src1_sel:DWORD
	v_add3_u32 v0, v0, v31, s54
	v_add3_u32 v1, v1, v30, s54
	v_and_b32_sdwa v30, v27, v155 dst_sel:DWORD dst_unused:UNUSED_PAD src0_sel:WORD_1 src1_sel:DWORD
	v_and_b32_sdwa v31, v26, v155 dst_sel:DWORD dst_unused:UNUSED_PAD src0_sel:WORD_1 src1_sel:DWORD
	v_add3_u32 v27, v27, v30, s54
	v_add3_u32 v26, v26, v31, s54
	v_and_b32_e32 v27, 0xffff0000, v27
	v_and_b32_e32 v26, 0xffff0000, v26
	v_or_b32_sdwa v1, v27, v1 dst_sel:DWORD dst_unused:UNUSED_PAD src0_sel:DWORD src1_sel:WORD_1
	v_or_b32_sdwa v0, v26, v0 dst_sel:DWORD dst_unused:UNUSED_PAD src0_sel:DWORD src1_sel:WORD_1
	s_waitcnt lgkmcnt(0)
	v_mov_b32_e32 v26, v4
	v_mov_b32_e32 v27, v6
	v_pk_mul_f32 v[2:3], v[2:3], v[26:27]
	v_mov_b32_e32 v6, v5
	v_pk_mul_f32 v[4:5], v[66:67], v[6:7]
	v_and_b32_sdwa v6, v3, v155 dst_sel:DWORD dst_unused:UNUSED_PAD src0_sel:WORD_1 src1_sel:DWORD
	v_and_b32_sdwa v7, v2, v155 dst_sel:DWORD dst_unused:UNUSED_PAD src0_sel:WORD_1 src1_sel:DWORD
	v_add3_u32 v2, v2, v7, s54
	v_add3_u32 v3, v3, v6, s54
	v_and_b32_sdwa v6, v5, v155 dst_sel:DWORD dst_unused:UNUSED_PAD src0_sel:WORD_1 src1_sel:DWORD
	v_and_b32_sdwa v7, v4, v155 dst_sel:DWORD dst_unused:UNUSED_PAD src0_sel:WORD_1 src1_sel:DWORD
	v_add3_u32 v5, v5, v6, s54
	v_add3_u32 v4, v4, v7, s54
	v_and_b32_e32 v5, 0xffff0000, v5
	v_and_b32_e32 v4, 0xffff0000, v4
	v_or_b32_sdwa v3, v5, v3 dst_sel:DWORD dst_unused:UNUSED_PAD src0_sel:DWORD src1_sel:WORD_1
	v_or_b32_sdwa v2, v4, v2 dst_sel:DWORD dst_unused:UNUSED_PAD src0_sel:DWORD src1_sel:WORD_1
	ds_read_b128 v[4:7], v92
	v_add_co_u32_e32 v20, vcc, s70, v20
	s_nop 1
	v_addc_co_u32_e32 v21, vcc, 0, v21, vcc
	global_store_dwordx4 v[20:21], v[0:3], off offset:2048
	s_waitcnt lgkmcnt(0)
	v_mov_b32_e32 v20, v4
	v_mov_b32_e32 v21, v6
	ds_read_b128 v[0:3], v92 offset:16
	v_pk_mul_f32 v[20:21], v[56:57], v[20:21]
	v_mov_b32_e32 v6, v5
	v_pk_mul_f32 v[4:5], v[58:59], v[6:7]
	v_and_b32_sdwa v6, v21, v155 dst_sel:DWORD dst_unused:UNUSED_PAD src0_sel:WORD_1 src1_sel:DWORD
	v_and_b32_sdwa v7, v20, v155 dst_sel:DWORD dst_unused:UNUSED_PAD src0_sel:WORD_1 src1_sel:DWORD
	v_add3_u32 v7, v20, v7, s54
	v_add3_u32 v6, v21, v6, s54
	v_and_b32_sdwa v20, v5, v155 dst_sel:DWORD dst_unused:UNUSED_PAD src0_sel:WORD_1 src1_sel:DWORD
	v_and_b32_sdwa v21, v4, v155 dst_sel:DWORD dst_unused:UNUSED_PAD src0_sel:WORD_1 src1_sel:DWORD
	v_add3_u32 v5, v5, v20, s54
	v_add3_u32 v4, v4, v21, s54
	v_and_b32_e32 v5, 0xffff0000, v5
	v_and_b32_e32 v4, 0xffff0000, v4
	v_or_b32_sdwa v5, v5, v6 dst_sel:DWORD dst_unused:UNUSED_PAD src0_sel:DWORD src1_sel:WORD_1
	v_or_b32_sdwa v4, v4, v7 dst_sel:DWORD dst_unused:UNUSED_PAD src0_sel:DWORD src1_sel:WORD_1
	s_waitcnt lgkmcnt(0)
	v_mov_b32_e32 v6, v0
	v_mov_b32_e32 v7, v2
	v_pk_mul_f32 v[6:7], v[60:61], v[6:7]
	v_mov_b32_e32 v2, v1
	v_pk_mul_f32 v[0:1], v[62:63], v[2:3]
	v_and_b32_sdwa v2, v7, v155 dst_sel:DWORD dst_unused:UNUSED_PAD src0_sel:WORD_1 src1_sel:DWORD
	v_and_b32_sdwa v3, v6, v155 dst_sel:DWORD dst_unused:UNUSED_PAD src0_sel:WORD_1 src1_sel:DWORD
	v_add3_u32 v3, v6, v3, s54
	v_add3_u32 v2, v7, v2, s54
	v_and_b32_sdwa v6, v1, v155 dst_sel:DWORD dst_unused:UNUSED_PAD src0_sel:WORD_1 src1_sel:DWORD
	v_and_b32_sdwa v7, v0, v155 dst_sel:DWORD dst_unused:UNUSED_PAD src0_sel:WORD_1 src1_sel:DWORD
	v_add3_u32 v1, v1, v6, s54
	v_add3_u32 v0, v0, v7, s54
	v_and_b32_e32 v1, 0xffff0000, v1
	v_and_b32_e32 v0, 0xffff0000, v0
	v_or_b32_sdwa v7, v1, v2 dst_sel:DWORD dst_unused:UNUSED_PAD src0_sel:DWORD src1_sel:WORD_1
	v_or_b32_sdwa v6, v0, v3 dst_sel:DWORD dst_unused:UNUSED_PAD src0_sel:DWORD src1_sel:WORD_1
	ds_read_b128 v[0:3], v75
	v_add_co_u32_e32 v16, vcc, s70, v16
	s_nop 1
	v_addc_co_u32_e32 v17, vcc, 0, v17, vcc
	global_store_dwordx4 v[16:17], v[4:7], off offset:2048
	s_waitcnt lgkmcnt(0)
; __device__ __forceinline__ unsigned pack2(float a, float b) { return (unsigned)f2bf(a) | ((unsigned)f2bf(b) << 16); }
; __device__ __forceinline__ float bflo(unsigned w) { return __uint_as_float(w << 16); }
; __device__ __forceinline__ float bfhi(unsigned w) { return __uint_as_float(w & 0xffff0000u); }
; __device__ __forceinline__ float silu_f(float g) { return g / (1.f + __expf(-g)); }
; template <int DH, int MODE>
; __device__ void attn_item(const Params& p, int layer, int b, int blk, int head, char* smem) {
;     ...
; #pragma unroll
;     for (int i = 0; i < NCH; ++i) {
;       int q = tid + 256 * i, r = q / CPR, c = (q % CPR) * 8;
;       float4 m0 = *reinterpret_cast<const float4*>(Of + r * OST + c);
;       float4 m1 = *reinterpret_cast<const float4*>(Of + r * OST + c + 4);
;       float mm[8] = {m0.x, m0.y, m0.z, m0.w, m1.x, m1.y, m1.z, m1.w};
;       unsigned gw[4] = {gt[i].x, gt[i].y, gt[i].z, gt[i].w};
;       unsigned ow[4];
; #pragma unroll
;       for (int e = 0; e < 4; ++e)
;         ow[e] = pack2(mm[2 * e] * silu_f(bflo(gw[e])), mm[2 * e + 1] * silu_f(bfhi(gw[e])));
;       *reinterpret_cast<uint4*>(Y + (tq0 + r) * YW + ycol + c) = make_uint4(ow[0], ow[1], ow[2], ow[3]);
;     }
	v_mov_b32_e32 v16, v0
	v_mov_b32_e32 v17, v2
	ds_read_b128 v[4:7], v75 offset:16
	v_pk_mul_f32 v[16:17], v[48:49], v[16:17]
	v_mov_b32_e32 v2, v1
	v_pk_mul_f32 v[0:1], v[50:51], v[2:3]
	v_and_b32_sdwa v2, v17, v155 dst_sel:DWORD dst_unused:UNUSED_PAD src0_sel:WORD_1 src1_sel:DWORD
	v_and_b32_sdwa v3, v16, v155 dst_sel:DWORD dst_unused:UNUSED_PAD src0_sel:WORD_1 src1_sel:DWORD
	v_add3_u32 v3, v16, v3, s54
	v_add3_u32 v2, v17, v2, s54
	v_and_b32_sdwa v16, v1, v155 dst_sel:DWORD dst_unused:UNUSED_PAD src0_sel:WORD_1 src1_sel:DWORD
	v_and_b32_sdwa v17, v0, v155 dst_sel:DWORD dst_unused:UNUSED_PAD src0_sel:WORD_1 src1_sel:DWORD
	v_add3_u32 v1, v1, v16, s54
	v_add3_u32 v0, v0, v17, s54
	v_and_b32_e32 v1, 0xffff0000, v1
	v_and_b32_e32 v0, 0xffff0000, v0
	v_or_b32_sdwa v1, v1, v2 dst_sel:DWORD dst_unused:UNUSED_PAD src0_sel:DWORD src1_sel:WORD_1
	v_or_b32_sdwa v0, v0, v3 dst_sel:DWORD dst_unused:UNUSED_PAD src0_sel:DWORD src1_sel:WORD_1
	s_waitcnt lgkmcnt(0)
	v_mov_b32_e32 v2, v4
	v_mov_b32_e32 v3, v6
	v_pk_mul_f32 v[2:3], v[52:53], v[2:3]
	v_mov_b32_e32 v6, v5
	v_pk_mul_f32 v[4:5], v[54:55], v[6:7]
	v_and_b32_sdwa v6, v3, v155 dst_sel:DWORD dst_unused:UNUSED_PAD src0_sel:WORD_1 src1_sel:DWORD
	v_and_b32_sdwa v7, v2, v155 dst_sel:DWORD dst_unused:UNUSED_PAD src0_sel:WORD_1 src1_sel:DWORD
	v_add3_u32 v2, v2, v7, s54
	v_add3_u32 v3, v3, v6, s54
	v_and_b32_sdwa v6, v5, v155 dst_sel:DWORD dst_unused:UNUSED_PAD src0_sel:WORD_1 src1_sel:DWORD
	v_and_b32_sdwa v7, v4, v155 dst_sel:DWORD dst_unused:UNUSED_PAD src0_sel:WORD_1 src1_sel:DWORD
	v_add3_u32 v5, v5, v6, s54
	v_add3_u32 v4, v4, v7, s54
	v_and_b32_e32 v5, 0xffff0000, v5
	v_and_b32_e32 v4, 0xffff0000, v4
	v_or_b32_sdwa v3, v5, v3 dst_sel:DWORD dst_unused:UNUSED_PAD src0_sel:DWORD src1_sel:WORD_1
	v_or_b32_sdwa v2, v4, v2 dst_sel:DWORD dst_unused:UNUSED_PAD src0_sel:DWORD src1_sel:WORD_1
	ds_read_b128 v[4:7], v74
	v_add_co_u32_e32 v12, vcc, s70, v12
	s_nop 1
	v_addc_co_u32_e32 v13, vcc, 0, v13, vcc
	global_store_dwordx4 v[12:13], v[0:3], off offset:2048
	s_waitcnt lgkmcnt(0)
	v_mov_b32_e32 v12, v4
	v_mov_b32_e32 v13, v6
	ds_read_b128 v[0:3], v74 offset:16
	v_pk_mul_f32 v[12:13], v[40:41], v[12:13]
	v_mov_b32_e32 v6, v5
	v_pk_mul_f32 v[4:5], v[42:43], v[6:7]
	v_and_b32_sdwa v6, v13, v155 dst_sel:DWORD dst_unused:UNUSED_PAD src0_sel:WORD_1 src1_sel:DWORD
	v_and_b32_sdwa v7, v12, v155 dst_sel:DWORD dst_unused:UNUSED_PAD src0_sel:WORD_1 src1_sel:DWORD
	v_add3_u32 v7, v12, v7, s54
	v_add3_u32 v6, v13, v6, s54
	v_and_b32_sdwa v12, v5, v155 dst_sel:DWORD dst_unused:UNUSED_PAD src0_sel:WORD_1 src1_sel:DWORD
	v_and_b32_sdwa v13, v4, v155 dst_sel:DWORD dst_unused:UNUSED_PAD src0_sel:WORD_1 src1_sel:DWORD
	v_add3_u32 v5, v5, v12, s54
	v_add3_u32 v4, v4, v13, s54
	v_and_b32_e32 v5, 0xffff0000, v5
	v_and_b32_e32 v4, 0xffff0000, v4
	v_or_b32_sdwa v5, v5, v6 dst_sel:DWORD dst_unused:UNUSED_PAD src0_sel:DWORD src1_sel:WORD_1
	v_or_b32_sdwa v4, v4, v7 dst_sel:DWORD dst_unused:UNUSED_PAD src0_sel:DWORD src1_sel:WORD_1
	s_waitcnt lgkmcnt(0)
	v_mov_b32_e32 v6, v0
	v_mov_b32_e32 v7, v2
	v_pk_mul_f32 v[6:7], v[44:45], v[6:7]
	v_mov_b32_e32 v2, v1
	v_pk_mul_f32 v[0:1], v[46:47], v[2:3]
	v_and_b32_sdwa v2, v7, v155 dst_sel:DWORD dst_unused:UNUSED_PAD src0_sel:WORD_1 src1_sel:DWORD
	v_and_b32_sdwa v3, v6, v155 dst_sel:DWORD dst_unused:UNUSED_PAD src0_sel:WORD_1 src1_sel:DWORD
	v_add3_u32 v3, v6, v3, s54
	v_add3_u32 v2, v7, v2, s54
	v_and_b32_sdwa v6, v1, v155 dst_sel:DWORD dst_unused:UNUSED_PAD src0_sel:WORD_1 src1_sel:DWORD
	v_and_b32_sdwa v7, v0, v155 dst_sel:DWORD dst_unused:UNUSED_PAD src0_sel:WORD_1 src1_sel:DWORD
	v_add3_u32 v1, v1, v6, s54
	v_add3_u32 v0, v0, v7, s54
	v_and_b32_e32 v1, 0xffff0000, v1
	v_and_b32_e32 v0, 0xffff0000, v0
	v_or_b32_sdwa v7, v1, v2 dst_sel:DWORD dst_unused:UNUSED_PAD src0_sel:DWORD src1_sel:WORD_1
	v_or_b32_sdwa v6, v0, v3 dst_sel:DWORD dst_unused:UNUSED_PAD src0_sel:DWORD src1_sel:WORD_1
	ds_read_b128 v[0:3], v73
	v_add_co_u32_e32 v10, vcc, s70, v10
	s_nop 1
	v_addc_co_u32_e32 v11, vcc, 0, v11, vcc
	global_store_dwordx4 v[10:11], v[4:7], off offset:2048
	s_waitcnt lgkmcnt(0)
; __device__ __forceinline__ unsigned pack2(float a, float b) { return (unsigned)f2bf(a) | ((unsigned)f2bf(b) << 16); }
; __device__ __forceinline__ float bflo(unsigned w) { return __uint_as_float(w << 16); }
; __device__ __forceinline__ float bfhi(unsigned w) { return __uint_as_float(w & 0xffff0000u); }
; __device__ __forceinline__ float silu_f(float g) { return g / (1.f + __expf(-g)); }
; template <int DH, int MODE>
; __device__ void attn_item(const Params& p, int layer, int b, int blk, int head, char* smem) {
;     ...
; #pragma unroll
;     for (int i = 0; i < NCH; ++i) {
;       int q = tid + 256 * i, r = q / CPR, c = (q % CPR) * 8;
;       float4 m0 = *reinterpret_cast<const float4*>(Of + r * OST + c);
;       float4 m1 = *reinterpret_cast<const float4*>(Of + r * OST + c + 4);
;       float mm[8] = {m0.x, m0.y, m0.z, m0.w, m1.x, m1.y, m1.z, m1.w};
;       unsigned gw[4] = {gt[i].x, gt[i].y, gt[i].z, gt[i].w};
;       unsigned ow[4];
; #pragma unroll
;       for (int e = 0; e < 4; ++e)
;         ow[e] = pack2(mm[2 * e] * silu_f(bflo(gw[e])), mm[2 * e + 1] * silu_f(bfhi(gw[e])));
;       *reinterpret_cast<uint4*>(Y + (tq0 + r) * YW + ycol + c) = make_uint4(ow[0], ow[1], ow[2], ow[3]);
;     }
	v_mov_b32_e32 v10, v0
	v_mov_b32_e32 v11, v2
	ds_read_b128 v[4:7], v73 offset:16
	v_pk_mul_f32 v[10:11], v[32:33], v[10:11]
	v_mov_b32_e32 v2, v1
	v_pk_mul_f32 v[0:1], v[34:35], v[2:3]
	v_and_b32_sdwa v2, v11, v155 dst_sel:DWORD dst_unused:UNUSED_PAD src0_sel:WORD_1 src1_sel:DWORD
	v_and_b32_sdwa v3, v10, v155 dst_sel:DWORD dst_unused:UNUSED_PAD src0_sel:WORD_1 src1_sel:DWORD
	v_add3_u32 v3, v10, v3, s54
	v_add3_u32 v2, v11, v2, s54
	v_and_b32_sdwa v10, v1, v155 dst_sel:DWORD dst_unused:UNUSED_PAD src0_sel:WORD_1 src1_sel:DWORD
	v_and_b32_sdwa v11, v0, v155 dst_sel:DWORD dst_unused:UNUSED_PAD src0_sel:WORD_1 src1_sel:DWORD
	v_add3_u32 v1, v1, v10, s54
	v_add3_u32 v0, v0, v11, s54
	v_and_b32_e32 v1, 0xffff0000, v1
	v_and_b32_e32 v0, 0xffff0000, v0
	v_or_b32_sdwa v1, v1, v2 dst_sel:DWORD dst_unused:UNUSED_PAD src0_sel:DWORD src1_sel:WORD_1
	v_or_b32_sdwa v0, v0, v3 dst_sel:DWORD dst_unused:UNUSED_PAD src0_sel:DWORD src1_sel:WORD_1
	s_waitcnt lgkmcnt(0)
	v_mov_b32_e32 v2, v4
	v_mov_b32_e32 v3, v6
	v_pk_mul_f32 v[2:3], v[36:37], v[2:3]
	v_mov_b32_e32 v6, v5
	v_pk_mul_f32 v[4:5], v[38:39], v[6:7]
	v_and_b32_sdwa v6, v3, v155 dst_sel:DWORD dst_unused:UNUSED_PAD src0_sel:WORD_1 src1_sel:DWORD
	v_and_b32_sdwa v7, v2, v155 dst_sel:DWORD dst_unused:UNUSED_PAD src0_sel:WORD_1 src1_sel:DWORD
	v_add3_u32 v2, v2, v7, s54
	v_add3_u32 v3, v3, v6, s54
	v_and_b32_sdwa v6, v5, v155 dst_sel:DWORD dst_unused:UNUSED_PAD src0_sel:WORD_1 src1_sel:DWORD
	v_and_b32_sdwa v7, v4, v155 dst_sel:DWORD dst_unused:UNUSED_PAD src0_sel:WORD_1 src1_sel:DWORD
	v_add3_u32 v5, v5, v6, s54
	v_add3_u32 v4, v4, v7, s54
	v_and_b32_e32 v5, 0xffff0000, v5
	v_and_b32_e32 v4, 0xffff0000, v4
	v_or_b32_sdwa v3, v5, v3 dst_sel:DWORD dst_unused:UNUSED_PAD src0_sel:DWORD src1_sel:WORD_1
	v_or_b32_sdwa v2, v4, v2 dst_sel:DWORD dst_unused:UNUSED_PAD src0_sel:DWORD src1_sel:WORD_1
	ds_read_b128 v[4:7], v72
	v_add_co_u32_e32 v8, vcc, s70, v8
	s_nop 1
	v_addc_co_u32_e32 v9, vcc, 0, v9, vcc
	global_store_dwordx4 v[8:9], v[0:3], off offset:2048
	s_waitcnt lgkmcnt(0)
	v_mov_b32_e32 v8, v4
	v_mov_b32_e32 v9, v6
	ds_read_b128 v[0:3], v72 offset:16
	v_pk_mul_f32 v[8:9], v[18:19], v[8:9]
	v_mov_b32_e32 v6, v5
	v_pk_mul_f32 v[4:5], v[22:23], v[6:7]
	v_and_b32_sdwa v6, v9, v155 dst_sel:DWORD dst_unused:UNUSED_PAD src0_sel:WORD_1 src1_sel:DWORD
	v_and_b32_sdwa v7, v8, v155 dst_sel:DWORD dst_unused:UNUSED_PAD src0_sel:WORD_1 src1_sel:DWORD
	v_add3_u32 v7, v8, v7, s54
	v_add3_u32 v6, v9, v6, s54
	v_and_b32_sdwa v8, v5, v155 dst_sel:DWORD dst_unused:UNUSED_PAD src0_sel:WORD_1 src1_sel:DWORD
	v_and_b32_sdwa v9, v4, v155 dst_sel:DWORD dst_unused:UNUSED_PAD src0_sel:WORD_1 src1_sel:DWORD
	v_add3_u32 v5, v5, v8, s54
	v_add3_u32 v4, v4, v9, s54
	v_and_b32_e32 v5, 0xffff0000, v5
	v_and_b32_e32 v4, 0xffff0000, v4
	v_or_b32_sdwa v5, v5, v6 dst_sel:DWORD dst_unused:UNUSED_PAD src0_sel:DWORD src1_sel:WORD_1
	v_or_b32_sdwa v4, v4, v7 dst_sel:DWORD dst_unused:UNUSED_PAD src0_sel:DWORD src1_sel:WORD_1
	s_waitcnt lgkmcnt(0)
	v_mov_b32_e32 v6, v0
	v_mov_b32_e32 v7, v2
	v_pk_mul_f32 v[6:7], v[24:25], v[6:7]
	v_mov_b32_e32 v2, v1
	v_pk_mul_f32 v[0:1], v[28:29], v[2:3]
	v_and_b32_sdwa v2, v7, v155 dst_sel:DWORD dst_unused:UNUSED_PAD src0_sel:WORD_1 src1_sel:DWORD
	v_and_b32_sdwa v3, v6, v155 dst_sel:DWORD dst_unused:UNUSED_PAD src0_sel:WORD_1 src1_sel:DWORD
	v_add3_u32 v2, v7, v2, s54
	v_and_b32_sdwa v7, v0, v155 dst_sel:DWORD dst_unused:UNUSED_PAD src0_sel:WORD_1 src1_sel:DWORD
	v_add3_u32 v3, v6, v3, s54
	v_and_b32_sdwa v6, v1, v155 dst_sel:DWORD dst_unused:UNUSED_PAD src0_sel:WORD_1 src1_sel:DWORD
	v_add3_u32 v0, v0, v7, s54
	v_add3_u32 v1, v1, v6, s54
	v_and_b32_e32 v0, 0xffff0000, v0
	v_and_b32_e32 v1, 0xffff0000, v1
	v_or_b32_sdwa v6, v0, v3 dst_sel:DWORD dst_unused:UNUSED_PAD src0_sel:DWORD src1_sel:WORD_1
	v_add_co_u32_e32 v0, vcc, 0x184a1000, v14
	v_or_b32_sdwa v7, v1, v2 dst_sel:DWORD dst_unused:UNUSED_PAD src0_sel:DWORD src1_sel:WORD_1
	s_nop 0
	v_addc_co_u32_e32 v1, vcc, 0, v15, vcc
	global_store_dwordx4 v[0:1], v[4:7], off offset:2048
	s_barrier

; #define MFMA16(a, b, c) __builtin_amdgcn_mfma_f32_16x16x32_bf16(a, b, c, 0, 0, 0)
; __device__ void gmlp_item(const Params& p, int layer, int b, int n, int g, char* smem) {
;     ...
; #pragma unroll 2
;   for (int i = 0; i < 8; ++i) {
;     int q = tid + 256 * i;
;     int t = q >> 4, cch = q & 15;
;     uint4 v = *reinterpret_cast<const uint4*>(Ws + (size_t)g * 16384 + t * 128 + cch * 8);
;     *reinterpret_cast<uint4*>(smem + (cch >> 2) * 8192 + t * 64 + (cch & 3) * 16) = v;
;   }
;   __syncthreads();
;   f32x4 acc[4][4];
; #pragma unroll
;   for (int m = 0; m < 4; ++m)
; #pragma unroll
;     for (int nn = 0; nn < 4; ++nn) acc[m][nn] = f32x4{0.f, 0.f, 0.f, 0.f};
; #pragma unroll
;   for (int ks = 0; ks < 4; ++ks) {
;     bf16x8 a[4], bb[4];
; #pragma unroll
;     for (int m = 0; m < 4; ++m)
;       a[m] = *reinterpret_cast<const bf16x8*>(smem + ks * 8192 + (wr * 64 + m * 16 + fr) * 64 + fq * 16);
; #pragma unroll
;     for (int nn = 0; nn < 4; ++nn)
;       bb[nn] = *reinterpret_cast<const bf16x8*>(smem + 32768 + ks * 8192 + (wc * 64 + nn * 16 + fr) * 64 + fq * 16);
; #pragma unroll
;     for (int m = 0; m < 4; ++m)
; #pragma unroll
;       for (int nn = 0; nn < 4; ++nn) acc[m][nn] = MFMA16(a[m], bb[nn], acc[m][nn]);
;   }
.LBB0_1122:
	v_add_u32_e32 v3, s8, v59
	v_ashrrev_i32_e32 v12, 4, v3
	v_add_u32_e32 v3, 0x100, v3
	v_ashrrev_i32_e32 v3, 4, v3
	v_lshlrev_b32_e32 v4, 7, v12
	v_lshlrev_b32_e32 v6, 7, v3
	v_ashrrev_i32_e32 v5, 31, v4
	v_ashrrev_i32_e32 v7, 31, v6
	v_lshl_add_u64 v[4:5], v[4:5], 1, v[0:1]
	v_lshl_add_u64 v[8:9], v[6:7], 1, v[0:1]
	global_load_dwordx4 v[4:7], v[4:5], off
	s_nop 0
	global_load_dwordx4 v[8:11], v[8:9], off
	s_addk_i32 s8, 0x200
	s_cmpk_lg_i32 s8, 0x800
	v_lshl_add_u32 v12, v12, 6, v2
	v_lshl_add_u32 v3, v3, 6, v2
	s_waitcnt vmcnt(1)
	ds_write_b128 v12, v[4:7]
	s_waitcnt vmcnt(0)
	ds_write_b128 v3, v[8:11]
	s_cbranch_scc1 .LBB0_1122
	v_bfe_u32 v54, v59, 4, 2
	v_ashrrev_i32_e32 v55, 7, v59
	v_lshlrev_b32_e32 v4, 4, v54
	v_lshlrev_b32_e32 v0, 12, v55
	v_lshlrev_b32_e32 v5, 6, v49
	v_or3_b32 v57, v4, v0, v5
	s_waitcnt lgkmcnt(0)
	s_barrier
	ds_read_b128 v[0:3], v57
	v_bfe_u32 v61, v59, 6, 1
	v_lshlrev_b32_e32 v6, 12, v61
	v_or3_b32 v63, v4, v6, v5
	ds_read_b128 v[4:7], v63 offset:32768
	ds_read_b128 v[8:11], v57 offset:1024
	ds_read_b128 v[12:15], v63 offset:33792
	ds_read_b128 v[24:27], v63 offset:34816
	ds_read_b128 v[28:31], v63 offset:35840
	s_waitcnt lgkmcnt(4)
	v_mfma_f32_16x16x32_bf16 v[16:19], v[0:3], v[4:7], 0
	s_ashr_i32 s8, s11, 31
	s_add_u32 s11, s28, s11
	s_addc_u32 s12, s29, s8
	s_waitcnt lgkmcnt(2)
	v_mfma_f32_16x16x32_bf16 v[20:23], v[0:3], v[12:15], 0
	s_lshl_b32 s8, s10, 2
	s_add_u32 s8, s20, s8
	v_lshlrev_b32_e32 v55, 6, v55
	s_waitcnt lgkmcnt(1)
	v_mfma_f32_16x16x32_bf16 v[36:39], v[0:3], v[24:27], 0
	s_addc_u32 s9, s21, 0
	v_lshl_or_b32 v54, v54, 2, v55
	s_add_u32 s8, s8, 0x1800
	s_waitcnt lgkmcnt(0)
	v_mfma_f32_16x16x32_bf16 v[40:43], v[0:3], v[28:31], 0
	s_addc_u32 s9, s9, 0
	v_ashrrev_i32_e32 v55, 31, v54
	v_lshl_add_u64 v[126:127], v[54:55], 2, s[8:9]
	v_mfma_f32_16x16x32_bf16 v[44:47], v[8:11], v[4:7], 0
	v_or_b32_e32 v130, 32, v54
	v_ashrrev_i32_e32 v131, 31, v130
	v_lshlrev_b32_e32 v49, 2, v49
	v_mfma_f32_16x16x32_bf16 v[50:53], v[8:11], v[12:15], 0
	v_lshl_add_u64 v[130:131], v[130:131], 2, s[8:9]
	v_ashrrev_i32_e32 v69, 31, v68
	v_ashrrev_i32_e32 v67, 31, v66
	v_mfma_f32_16x16x32_bf16 v[70:73], v[8:11], v[24:27], 0
	v_ashrrev_i32_e32 v65, 31, v64
	v_mfma_f32_16x16x32_bf16 v[74:77], v[8:11], v[28:31], 0
	ds_read_b128 v[0:3], v57 offset:2048
	ds_read_b128 v[8:11], v57 offset:3072
	s_waitcnt lgkmcnt(1)
	v_mfma_f32_16x16x32_bf16 v[82:85], v[0:3], v[12:15], 0
	s_waitcnt lgkmcnt(0)
	v_mfma_f32_16x16x32_bf16 v[98:101], v[8:11], v[12:15], 0
	ds_read_b128 v[12:15], v57 offset:8192
	v_mfma_f32_16x16x32_bf16 v[78:81], v[0:3], v[4:7], 0
	v_mfma_f32_16x16x32_bf16 v[86:89], v[0:3], v[24:27], 0
	v_mfma_f32_16x16x32_bf16 v[94:97], v[8:11], v[4:7], 0
	v_mfma_f32_16x16x32_bf16 v[32:35], v[8:11], v[24:27], 0
	ds_read_b128 v[102:105], v63 offset:40960
	ds_read_b128 v[24:27], v57 offset:9216
	ds_read_b128 v[106:109], v63 offset:41984
	ds_read_b128 v[118:121], v63 offset:43008
	ds_read_b128 v[4:7], v63 offset:44032
	v_mfma_f32_16x16x32_bf16 v[90:93], v[0:3], v[28:31], 0
	s_waitcnt lgkmcnt(4)
	v_mfma_f32_16x16x32_bf16 v[110:113], v[12:15], v[102:105], v[16:19]
	s_waitcnt lgkmcnt(2)
	v_mfma_f32_16x16x32_bf16 v[114:117], v[12:15], v[106:109], v[20:23]
	s_waitcnt lgkmcnt(1)
	v_mfma_f32_16x16x32_bf16 v[122:125], v[12:15], v[118:121], v[36:39]
	s_waitcnt lgkmcnt(0)
	v_mfma_f32_16x16x32_bf16 v[134:137], v[12:15], v[4:7], v[40:43]
	ds_read_b128 v[146:149], v57 offset:10240
	ds_read_b128 v[12:15], v57 offset:11264
	v_mfma_f32_16x16x32_bf16 v[0:3], v[8:11], v[28:31], 0
	ds_read_b128 v[150:153], v57 offset:16384
	ds_read_b128 v[162:165], v57 offset:17408
	ds_read_b128 v[166:169], v57 offset:18432
	ds_read_b128 v[8:11], v57 offset:19456
	ds_read_b128 v[36:39], v63 offset:49152
	ds_read_b128 v[28:31], v63 offset:50176
	ds_read_b128 v[20:23], v63 offset:51200
	ds_read_b128 v[16:19], v63 offset:52224
	v_mfma_f32_16x16x32_bf16 v[138:141], v[24:27], v[102:105], v[44:47]
	v_mfma_f32_16x16x32_bf16 v[50:53], v[24:27], v[106:109], v[50:53]
	v_mfma_f32_16x16x32_bf16 v[70:73], v[24:27], v[118:121], v[70:73]
	v_mfma_f32_16x16x32_bf16 v[74:77], v[24:27], v[4:7], v[74:77]
	ds_read_b128 v[170:173], v57 offset:24576
	ds_read_b128 v[174:177], v57 offset:25600
	ds_read_b128 v[178:181], v57 offset:26624
	ds_read_b128 v[24:27], v57 offset:27648
	ds_read_b128 v[182:185], v63 offset:57344
	ds_read_b128 v[186:189], v63 offset:58368
	ds_read_b128 v[44:47], v63 offset:59392
	ds_read_b128 v[40:43], v63 offset:60416
	s_waitcnt lgkmcnt(0)
	v_mfma_f32_16x16x32_bf16 v[78:81], v[146:149], v[102:105], v[78:81]
	s_barrier
; #define MFMA16(a, b, c) __builtin_amdgcn_mfma_f32_16x16x32_bf16(a, b, c, 0, 0, 0)
; __device__ void gmlp_item(const Params& p, int layer, int b, int n, int g, char* smem) {
;     ...
;   for (int ks = 0; ks < 4; ++ks) {
;     bf16x8 a[4], bb[4];
; #pragma unroll
;     for (int m = 0; m < 4; ++m)
;       a[m] = *reinterpret_cast<const bf16x8*>(smem + ks * 8192 + (wr * 64 + m * 16 + fr) * 64 + fq * 16);
; #pragma unroll
;     for (int nn = 0; nn < 4; ++nn)
;       bb[nn] = *reinterpret_cast<const bf16x8*>(smem + 32768 + ks * 8192 + (wc * 64 + nn * 16 + fr) * 64 + fq * 16);
; #pragma unroll
;     for (int m = 0; m < 4; ++m)
; #pragma unroll
;       for (int nn = 0; nn < 4; ++nn) acc[m][nn] = MFMA16(a[m], bb[nn], acc[m][nn]);
;   }
;   __syncthreads();
;   {
;     float* Tf = reinterpret_cast<float*>(smem);
; #pragma unroll
;     for (int m = 0; m < 4; ++m)
; #pragma unroll
;       for (int j = 0; j < 4; ++j) {
;         int t = wr * 64 + m * 16 + fq * 4 + j;
;         float bias = p.gm_b_s[(size_t)layer * 512 + g * 128 + t];
; #pragma unroll
;         for (int nn = 0; nn < 4; ++nn) Tf[t * 132 + wc * 64 + nn * 16 + fr] = acc[m][nn][j] + bias;
;       }
	global_load_dwordx4 v[190:193], v[130:131], off
	v_mfma_f32_16x16x32_bf16 v[82:85], v[146:149], v[106:109], v[82:85]
	v_ashrrev_i32_e32 v63, 31, v62
	v_mfma_f32_16x16x32_bf16 v[86:89], v[146:149], v[118:121], v[86:89]
	v_mfma_f32_16x16x32_bf16 v[90:93], v[146:149], v[4:7], v[90:93]
	global_load_dwordx4 v[146:149], v[126:127], off
	v_or_b32_e32 v126, 16, v54
	v_ashrrev_i32_e32 v127, 31, v126
	v_lshl_add_u64 v[126:127], v[126:127], 2, s[8:9]
	v_mfma_f32_16x16x32_bf16 v[110:113], v[150:153], v[36:39], v[110:113]
	v_mfma_f32_16x16x32_bf16 v[114:117], v[150:153], v[28:31], v[114:117]
	v_mfma_f32_16x16x32_bf16 v[122:125], v[150:153], v[20:23], v[122:125]
	v_mfma_f32_16x16x32_bf16 v[134:137], v[150:153], v[16:19], v[134:137]
	global_load_dwordx4 v[150:153], v[126:127], off
	v_lshl_or_b32 v126, v61, 8, v49
	v_mad_u64_u32 v[126:127], s[42:43], v54, s55, v[126:127]
	v_mfma_f32_16x16x32_bf16 v[110:113], v[170:173], v[182:185], v[110:113]
	v_add_u32_e32 v57, 0x400, v126
	v_or_b32_e32 v54, 48, v54
	v_ashrrev_i32_e32 v61, 31, v60
	v_mfma_f32_16x16x32_bf16 v[114:117], v[170:173], v[186:189], v[114:117]
	v_mfma_f32_16x16x32_bf16 v[122:125], v[170:173], v[44:47], v[122:125]
	s_waitcnt vmcnt(1)
	s_nop 1
	v_add_f32_e32 v49, v110, v146
	v_mfma_f32_16x16x32_bf16 v[134:137], v[170:173], v[40:43], v[134:137]
	s_nop 1
	v_add_f32_e32 v55, v114, v146
	ds_write2_b32 v126, v49, v55 offset1:16
	v_add_f32_e32 v49, v122, v146
	v_mfma_f32_16x16x32_bf16 v[98:101], v[12:15], v[106:109], v[98:101]
	v_mfma_f32_16x16x32_bf16 v[94:97], v[12:15], v[102:105], v[94:97]
	s_nop 0
	v_add_f32_e32 v55, v134, v146
	ds_write2_b32 v126, v49, v55 offset0:32 offset1:48
	v_add_f32_e32 v49, v111, v147
	v_add_f32_e32 v55, v115, v147
	ds_write2_b32 v126, v49, v55 offset0:132 offset1:148
	v_add_f32_e32 v49, v123, v147
	v_add_f32_e32 v55, v135, v147
	ds_write2_b32 v126, v49, v55 offset0:164 offset1:180
	v_add_f32_e32 v49, v112, v148
	v_add_f32_e32 v55, v116, v148
	ds_write2_b32 v57, v49, v55 offset0:8 offset1:24
	v_add_f32_e32 v49, v124, v148
	v_add_f32_e32 v55, v136, v148
	ds_write2_b32 v57, v49, v55 offset0:40 offset1:56
	v_add_f32_e32 v49, v113, v149
	v_add_f32_e32 v55, v117, v149
	ds_write2_b32 v57, v49, v55 offset0:140 offset1:156
	v_add_f32_e32 v49, v125, v149
	v_add_f32_e32 v55, v137, v149
	ds_write2_b32 v57, v49, v55 offset0:172 offset1:188
	v_ashrrev_i32_e32 v55, 31, v54
	v_lshl_add_u64 v[54:55], v[54:55], 2, s[8:9]
	global_load_dwordx4 v[106:109], v[54:55], off
	v_mfma_f32_16x16x32_bf16 v[102:105], v[162:165], v[36:39], v[138:141]
	v_add_u32_e32 v54, 0x2000, v126
	v_ashrrev_i32_e32 v57, 31, v56
	v_mfma_f32_16x16x32_bf16 v[50:53], v[162:165], v[28:31], v[50:53]
	v_mfma_f32_16x16x32_bf16 v[70:73], v[162:165], v[20:23], v[70:73]
	v_mfma_f32_16x16x32_bf16 v[74:77], v[162:165], v[16:19], v[74:77]
	v_mfma_f32_16x16x32_bf16 v[102:105], v[174:177], v[182:185], v[102:105]
	v_mfma_f32_16x16x32_bf16 v[50:53], v[174:177], v[186:189], v[50:53]
	v_mfma_f32_16x16x32_bf16 v[70:73], v[174:177], v[44:47], v[70:73]
	s_waitcnt vmcnt(1)
	s_nop 4
	v_add_f32_e32 v49, v102, v150
	v_add_f32_e32 v50, v50, v150
	ds_write2_b32 v54, v49, v50 offset0:64 offset1:80
	v_mfma_f32_16x16x32_bf16 v[74:77], v[174:177], v[40:43], v[74:77]
	v_add_f32_e32 v55, v53, v153
	v_add_f32_e32 v49, v70, v150
	v_mfma_f32_16x16x32_bf16 v[78:81], v[166:169], v[36:39], v[78:81]
	v_mfma_f32_16x16x32_bf16 v[82:85], v[166:169], v[28:31], v[82:85]
	s_nop 3
	v_add_f32_e32 v50, v74, v150
	ds_write2_b32 v54, v49, v50 offset0:96 offset1:112
	v_add_f32_e32 v49, v103, v151
	v_add_f32_e32 v50, v51, v151
	ds_write2_b32 v54, v49, v50 offset0:196 offset1:212
	v_add_f32_e32 v49, v71, v151
	v_add_f32_e32 v50, v75, v151
	ds_write2_b32 v54, v49, v50 offset0:228 offset1:244
	v_add_f32_e32 v49, v104, v152
	v_add_f32_e32 v50, v52, v152
	v_add_u32_e32 v54, 0x2400, v126
	v_mfma_f32_16x16x32_bf16 v[86:89], v[166:169], v[20:23], v[86:89]
	ds_write2_b32 v54, v49, v50 offset0:72 offset1:88
	v_add_f32_e32 v49, v72, v152
	v_add_f32_e32 v50, v76, v152
	v_mfma_f32_16x16x32_bf16 v[90:93], v[166:169], v[16:19], v[90:93]
	ds_write2_b32 v54, v49, v50 offset0:104 offset1:120
	v_add_f32_e32 v49, v105, v153
	ds_write2_b32 v54, v49, v55 offset0:204 offset1:220
	v_mfma_f32_16x16x32_bf16 v[50:53], v[178:181], v[182:185], v[78:81]
	v_add_f32_e32 v49, v73, v153
	v_add_f32_e32 v55, v77, v153
	ds_write2_b32 v54, v49, v55 offset0:236 offset1:252
	v_mfma_f32_16x16x32_bf16 v[70:73], v[178:181], v[186:189], v[82:85]
	v_add_u32_e32 v54, 0x4000, v126
	s_nop 2
	v_add_f32_e32 v49, v50, v190
	v_mfma_f32_16x16x32_bf16 v[74:77], v[178:181], v[44:47], v[86:89]
	v_mfma_f32_16x16x32_bf16 v[78:81], v[178:181], v[40:43], v[90:93]
	s_nop 0
	v_add_f32_e32 v50, v70, v190
	ds_write2_b32 v54, v49, v50 offset0:128 offset1:144
	s_nop 3
	v_add_f32_e32 v49, v74, v190
	v_mfma_f32_16x16x32_bf16 v[32:35], v[12:15], v[118:121], v[32:35]
	v_mfma_f32_16x16x32_bf16 v[0:3], v[12:15], v[4:7], v[0:3]
	v_add_f32_e32 v50, v78, v190
	ds_write2_b32 v54, v49, v50 offset0:160 offset1:176
	v_add_f32_e32 v49, v51, v191
	v_add_f32_e32 v4, v71, v191
	v_add_u32_e32 v50, 0x4400, v126
	v_add_f32_e32 v12, v75, v191
	v_add_f32_e32 v13, v79, v191
	ds_write2_b32 v50, v49, v4 offset0:4 offset1:20
	v_mfma_f32_16x16x32_bf16 v[4:7], v[8:11], v[36:39], v[94:97]
	ds_write2_b32 v50, v12, v13 offset0:36 offset1:52
	v_ashrrev_i32_e32 v49, 31, v48
	v_lshl_add_u64 v[70:71], v[56:57], 0, s[16:17]
	v_mfma_f32_16x16x32_bf16 v[12:15], v[8:11], v[28:31], v[98:101]
	v_add_f32_e32 v28, v52, v192
	v_add_f32_e32 v29, v72, v192
	ds_write2_b32 v50, v28, v29 offset0:136 offset1:152
	v_mfma_f32_16x16x32_bf16 v[20:23], v[8:11], v[20:23], v[32:35]
	v_add_f32_e32 v28, v76, v192
	v_add_f32_e32 v29, v80, v192
	ds_write2_b32 v50, v28, v29 offset0:168 offset1:184
	v_mfma_f32_16x16x32_bf16 v[0:3], v[8:11], v[16:19], v[0:3]
	v_add_f32_e32 v8, v53, v193
	v_add_f32_e32 v9, v73, v193
	v_add_u32_e32 v16, 0x4800, v126
	v_mfma_f32_16x16x32_bf16 v[4:7], v[24:27], v[182:185], v[4:7]
	ds_write2_b32 v16, v8, v9 offset0:12 offset1:28
	v_add_f32_e32 v17, v77, v193
	v_add_f32_e32 v18, v81, v193
	v_mfma_f32_16x16x32_bf16 v[8:11], v[24:27], v[186:189], v[12:15]
	ds_write2_b32 v16, v17, v18 offset0:44 offset1:60
	s_waitcnt vmcnt(0)
; __device__ void gmlp_item(const Params& p, int layer, int b, int n, int g, char* smem) {
;     ...
; #pragma unroll
;     for (int m = 0; m < 4; ++m)
; #pragma unroll
;       for (int j = 0; j < 4; ++j) {
;         int t = wr * 64 + m * 16 + fq * 4 + j;
;         float bias = p.gm_b_s[(size_t)layer * 512 + g * 128 + t];
; #pragma unroll
;         for (int nn = 0; nn < 4; ++nn) Tf[t * 132 + wc * 64 + nn * 16 + fr] = acc[m][nn][j] + bias;
;       }
;     __syncthreads();
;     uint4 uu[8], gt[8];
; #pragma unroll
;     for (int i = 0; i < 8; ++i) {
;       int q = tid + 256 * i, t = q >> 4, c = (q & 15) * 8;
;       uu[i] = *reinterpret_cast<const uint4*>(P + (t0 + t) * NP + g * 128 + c);
;       gt[i] = *reinterpret_cast<const uint4*>(P + (t0 + t) * NP + 1024 + g * 128 + c);
;     }
; #pragma unroll
;     for (int i = 0; i < 8; ++i) {
;       int q = tid + 256 * i, t = q >> 4, c = (q & 15) * 8;
;       float4 m0 = *reinterpret_cast<const float4*>(Tf + t * 132 + c);
	s_nop 1
	v_add_f32_e32 v4, v4, v106
	v_add_u32_e32 v16, 0x6000, v126
	v_mfma_f32_16x16x32_bf16 v[12:15], v[24:27], v[44:47], v[20:23]
	v_lshl_add_u64 v[36:37], v[62:63], 0, s[16:17]
	v_add_f32_e32 v8, v8, v106
	ds_write2_b32 v16, v4, v8 offset0:192 offset1:208
	v_mfma_f32_16x16x32_bf16 v[0:3], v[24:27], v[40:43], v[0:3]
	v_lshl_add_u64 v[20:21], v[64:65], 0, s[16:17]
	s_nop 2
	v_add_f32_e32 v4, v12, v106
	v_lshl_add_u64 v[38:39], v[60:61], 0, s[16:17]
	s_nop 1
	v_add_f32_e32 v0, v0, v106
	ds_write2_b32 v16, v4, v0 offset0:224 offset1:240
	v_add_f32_e32 v0, v5, v107
	v_add_f32_e32 v4, v9, v107
	v_add_u32_e32 v5, 0x6400, v126
	ds_write2_b32 v5, v0, v4 offset0:68 offset1:84
	v_add_f32_e32 v0, v13, v107
	v_add_f32_e32 v1, v1, v107
	ds_write2_b32 v5, v0, v1 offset0:100 offset1:116
	v_add_f32_e32 v0, v6, v108
	v_add_f32_e32 v1, v10, v108
	ds_write2_b32 v5, v0, v1 offset0:200 offset1:216
	v_add_f32_e32 v0, v14, v108
	v_add_f32_e32 v1, v2, v108
	ds_write2_b32 v5, v0, v1 offset0:232 offset1:248
	v_add_f32_e32 v0, v7, v109
	v_add_f32_e32 v1, v11, v109
	v_add_u32_e32 v2, 0x6800, v126
	ds_write2_b32 v2, v0, v1 offset0:76 offset1:92
	v_add_f32_e32 v0, v15, v109
	v_add_f32_e32 v1, v3, v109
	ds_write2_b32 v2, v0, v1 offset0:108 offset1:124
	v_lshlrev_b32_e32 v0, 3, v59
	v_lshl_add_u64 v[8:9], v[48:49], 0, s[16:17]
	v_mov_b64_e32 v[10:11], s[6:7]
	v_and_b32_e32 v24, 0x78, v0
	v_mad_u64_u32 v[0:1], s[6:7], v8, s39, v[10:11]
	v_mad_i32_i24 v1, v9, s39, v1
	s_lshl_b32 s6, s10, 1
	s_mov_b32 s7, s17
	v_lshl_add_u64 v[0:1], v[0:1], 0, s[6:7]
	v_lshlrev_b32_e32 v128, 1, v24
	v_lshl_add_u64 v[12:13], v[68:69], 0, s[16:17]
	v_lshl_add_u64 v[52:53], v[0:1], 0, v[128:129]
	v_mad_u64_u32 v[0:1], s[8:9], v12, s39, v[10:11]
	v_mad_i32_i24 v1, v13, s39, v1
	v_lshl_add_u64 v[0:1], v[0:1], 0, s[6:7]
	v_lshl_add_u64 v[32:33], v[0:1], 0, v[128:129]
	v_mad_u64_u32 v[0:1], s[8:9], v70, s39, v[10:11]
	v_mad_i32_i24 v1, v71, s39, v1
	v_lshl_add_u64 v[0:1], v[0:1], 0, s[6:7]
	v_lshl_add_u64 v[4:5], v[0:1], 0, v[128:129]
	s_waitcnt lgkmcnt(0)
	s_barrier
	global_load_dwordx4 v[0:3], v[4:5], off
	s_nop 0
	global_load_dwordx4 v[4:7], v[4:5], off offset:2048
	v_lshl_add_u64 v[16:17], v[66:67], 0, s[16:17]
	v_mad_u64_u32 v[14:15], s[8:9], v16, s39, v[10:11]
	v_mad_i32_i24 v15, v17, s39, v15
	v_lshl_add_u64 v[14:15], v[14:15], 0, s[6:7]
	v_lshl_add_u64 v[30:31], v[14:15], 0, v[128:129]
	v_mad_u64_u32 v[14:15], s[8:9], v20, s39, v[10:11]
	v_mad_i32_i24 v15, v21, s39, v15
	v_lshl_add_u64 v[14:15], v[14:15], 0, s[6:7]
	v_lshl_add_u64 v[26:27], v[14:15], 0, v[128:129]
	v_mad_u64_u32 v[14:15], s[8:9], v36, s39, v[10:11]
	v_mad_i32_i24 v15, v37, s39, v15
	v_ashrrev_i32_e32 v59, 31, v58
	v_lshl_add_u64 v[14:15], v[14:15], 0, s[6:7]
	v_lshl_add_u64 v[72:73], v[58:59], 0, s[16:17]
	v_lshl_add_u64 v[22:23], v[14:15], 0, v[128:129]
	v_mad_u64_u32 v[14:15], s[8:9], v38, s39, v[10:11]
	v_mad_u64_u32 v[10:11], s[8:9], v72, s39, v[10:11]
	v_mad_i32_i24 v15, v39, s39, v15
	v_mad_i32_i24 v11, v73, s39, v11
	v_lshl_add_u64 v[14:15], v[14:15], 0, s[6:7]
	v_lshl_add_u64 v[10:11], v[10:11], 0, s[6:7]
	s_add_u32 s6, s11, s6
	s_addc_u32 s7, s12, 0
	v_lshl_add_u64 v[18:19], v[14:15], 0, v[128:129]
	v_lshl_add_u64 v[14:15], v[10:11], 0, v[128:129]
	v_lshlrev_b32_e32 v10, 2, v24
	v_lshl_add_u64 v[24:25], s[6:7], 0, v[128:129]
	v_lshl_add_u64 v[74:75], v[24:25], 0, s[26:27]
	v_mad_u64_u32 v[54:55], s[6:7], v48, s55, v[10:11]
	v_mad_u64_u32 v[48:49], s[6:7], v12, s63, v[74:75]
	v_mad_u64_u32 v[46:47], s[6:7], v16, s63, v[74:75]
	v_mad_u64_u32 v[50:51], s[6:7], v8, s63, v[74:75]
	v_mad_i32_i24 v49, v13, s63, v49
	v_mad_i32_i24 v47, v17, s63, v47
	v_mad_u64_u32 v[44:45], s[6:7], v20, s63, v[74:75]
	v_mad_u64_u32 v[16:17], s[6:7], v60, s55, v[10:11]
	v_mad_u64_u32 v[12:13], s[6:7], v58, s55, v[10:11]
	v_mad_i32_i24 v51, v9, s63, v51
	v_mad_i32_i24 v45, v21, s63, v45
	v_mad_u64_u32 v[20:21], s[6:7], v62, s55, v[10:11]
	v_mad_u64_u32 v[8:9], s[6:7], v56, s55, v[10:11]
	v_mad_u64_u32 v[28:29], s[6:7], v66, s55, v[10:11]
	v_mad_u64_u32 v[34:35], s[6:7], v68, s55, v[10:11]
	v_mad_u64_u32 v[24:25], s[6:7], v64, s55, v[10:11]
	v_mad_u64_u32 v[42:43], s[6:7], v36, s63, v[74:75]
	v_mad_i32_i24 v43, v37, s63, v43
	v_mad_u64_u32 v[36:37], s[6:7], v70, s63, v[74:75]
	v_mad_u64_u32 v[40:41], s[6:7], v38, s63, v[74:75]
	v_mad_i32_i24 v41, v39, s63, v41
	v_mad_u64_u32 v[38:39], s[6:7], v72, s63, v[74:75]
	v_mad_i32_i24 v39, v73, s63, v39
	v_mad_i32_i24 v37, v71, s63, v37
	s_waitcnt vmcnt(1)
	v_lshlrev_b32_e32 v63, 16, v1
	s_waitcnt vmcnt(0)
	v_lshlrev_b32_e32 v13, 16, v5
	v_lshlrev_b32_e32 v17, 16, v4
	v_mul_f32_e32 v9, 0xbfb8aa3b, v17
	v_and_b32_e32 v21, 0xffff0000, v5
	v_mul_f32_e32 v5, 0xbfb8aa3b, v13
	v_exp_f32_e32 v60, v9
	v_exp_f32_e32 v61, v5
	ds_read_b128 v[56:59], v8
	ds_read_b128 v[8:11], v8 offset:16
	v_and_b32_e32 v25, 0xffff0000, v4
	v_mul_f32_e32 v4, 0xbfb8aa3b, v25
	v_pk_add_f32 v[60:61], v[60:61], 1.0 op_sel_hi:[1,0]
	s_waitcnt lgkmcnt(1)
; __device__ __forceinline__ unsigned pack2(float a, float b) { return (unsigned)f2bf(a) | ((unsigned)f2bf(b) << 16); }
; __device__ __forceinline__ float bflo(unsigned w) { return __uint_as_float(w << 16); }
; __device__ __forceinline__ float bfhi(unsigned w) { return __uint_as_float(w & 0xffff0000u); }
; __device__ __forceinline__ float silu_f(float g) { return g / (1.f + __expf(-g)); }
; __device__ void gmlp_item(const Params& p, int layer, int b, int n, int g, char* smem) {
;     ...
; #pragma unroll
;     for (int i = 0; i < 8; ++i) {
;       int q = tid + 256 * i, t = q >> 4, c = (q & 15) * 8;
;       float4 m0 = *reinterpret_cast<const float4*>(Tf + t * 132 + c);
;       float4 m1 = *reinterpret_cast<const float4*>(Tf + t * 132 + c + 4);
;       float mm[8] = {m0.x, m0.y, m0.z, m0.w, m1.x, m1.y, m1.z, m1.w};
;       unsigned uw[4] = {uu[i].x, uu[i].y, uu[i].z, uu[i].w};
;       unsigned gw[4] = {gt[i].x, gt[i].y, gt[i].z, gt[i].w};
;       unsigned ow[4];
; #pragma unroll
;       for (int e = 0; e < 4; ++e) {
;         float y0 = bflo(uw[e]) * mm[2 * e] * silu_f(bflo(gw[e]));
;         float y1 = bfhi(uw[e]) * mm[2 * e + 1] * silu_f(bfhi(gw[e]));
;         ow[e] = pack2(y0, y1);
;       }
;       *reinterpret_cast<uint4*>(Y + (t0 + t) * YW + g * 128 + c) = make_uint4(ow[0], ow[1], ow[2], ow[3]);
	v_mov_b32_e32 v64, v56
	v_exp_f32_e32 v4, v4
	v_lshlrev_b32_e32 v62, 16, v0
	v_mov_b32_e32 v65, v58
	v_rcp_f32_e32 v61, v61
	s_nop 0
	v_mul_f32_e32 v61, v13, v61
	v_and_b32_e32 v1, 0xffff0000, v1
	v_mul_f32_e32 v5, 0xbfb8aa3b, v21
	v_exp_f32_e32 v5, v5
	v_rcp_f32_e32 v60, v60
	s_nop 0
	v_mul_f32_e32 v60, v17, v60
	v_and_b32_e32 v0, 0xffff0000, v0
	v_mov_b32_e32 v58, v57
	v_pk_add_f32 v[4:5], v[4:5], 1.0 op_sel_hi:[1,0]
	v_pk_mul_f32 v[0:1], v[58:59], v[0:1]
	v_pk_mul_f32 v[62:63], v[64:65], v[62:63]
	v_rcp_f32_e32 v5, v5
	s_nop 0
	v_mul_f32_e32 v5, v21, v5
	v_pk_mul_f32 v[60:61], v[60:61], v[62:63]
	v_rcp_f32_e32 v4, v4
	s_nop 0
	v_mul_f32_e32 v4, v25, v4
	v_pk_mul_f32 v[0:1], v[4:5], v[0:1]
	v_and_b32_sdwa v4, v61, v155 dst_sel:DWORD dst_unused:UNUSED_PAD src0_sel:WORD_1 src1_sel:DWORD
	v_and_b32_sdwa v13, v1, v155 dst_sel:DWORD dst_unused:UNUSED_PAD src0_sel:WORD_1 src1_sel:DWORD
	v_and_b32_sdwa v17, v0, v155 dst_sel:DWORD dst_unused:UNUSED_PAD src0_sel:WORD_1 src1_sel:DWORD
	v_and_b32_sdwa v5, v60, v155 dst_sel:DWORD dst_unused:UNUSED_PAD src0_sel:WORD_1 src1_sel:DWORD
	v_add3_u32 v1, v1, v13, s54
	v_add3_u32 v0, v0, v17, s54
	v_add3_u32 v5, v60, v5, s54
	v_add3_u32 v4, v61, v4, s54
	v_and_b32_e32 v1, 0xffff0000, v1
	v_and_b32_e32 v0, 0xffff0000, v0
	v_lshlrev_b32_e32 v13, 16, v7
	v_lshlrev_b32_e32 v17, 16, v6
	v_or_b32_sdwa v1, v1, v4 dst_sel:DWORD dst_unused:UNUSED_PAD src0_sel:DWORD src1_sel:WORD_1
	v_or_b32_sdwa v0, v0, v5 dst_sel:DWORD dst_unused:UNUSED_PAD src0_sel:DWORD src1_sel:WORD_1
	v_mul_f32_e32 v4, 0xbfb8aa3b, v17
	v_mul_f32_e32 v5, 0xbfb8aa3b, v13
	v_exp_f32_e32 v4, v4
	v_exp_f32_e32 v5, v5
	v_and_b32_e32 v25, 0xffff0000, v6
	v_mul_f32_e32 v6, 0xbfb8aa3b, v25
	v_and_b32_e32 v21, 0xffff0000, v7
	v_exp_f32_e32 v60, v6
	v_pk_add_f32 v[64:65], v[4:5], 1.0 op_sel_hi:[1,0]
	global_load_dwordx4 v[4:7], v[14:15], off
	global_load_dwordx4 v[56:59], v[14:15], off offset:2048
	s_waitcnt lgkmcnt(0)
	v_mov_b32_e32 v14, v8
	v_mov_b32_e32 v15, v10
	v_lshlrev_b32_e32 v63, 16, v3
	v_lshlrev_b32_e32 v62, 16, v2
	v_pk_mul_f32 v[14:15], v[14:15], v[62:63]
	v_rcp_f32_e32 v63, v65
	s_nop 0
	v_mul_f32_e32 v63, v13, v63
	v_mul_f32_e32 v10, 0xbfb8aa3b, v21
	v_exp_f32_e32 v61, v10
	v_rcp_f32_e32 v62, v64
	s_nop 0
	v_mul_f32_e32 v62, v17, v62
	v_mov_b32_e32 v10, v9
	v_and_b32_e32 v3, 0xffff0000, v3
	v_pk_add_f32 v[60:61], v[60:61], 1.0 op_sel_hi:[1,0]
	v_and_b32_e32 v2, 0xffff0000, v2
	v_pk_mul_f32 v[2:3], v[10:11], v[2:3]
	v_pk_mul_f32 v[14:15], v[62:63], v[14:15]
	v_rcp_f32_e32 v9, v61
	s_nop 0
	v_mul_f32_e32 v9, v21, v9
	v_rcp_f32_e32 v8, v60
	s_nop 0
	v_mul_f32_e32 v8, v25, v8
	v_pk_mul_f32 v[2:3], v[8:9], v[2:3]
	v_and_b32_sdwa v8, v15, v155 dst_sel:DWORD dst_unused:UNUSED_PAD src0_sel:WORD_1 src1_sel:DWORD
	v_and_b32_sdwa v10, v3, v155 dst_sel:DWORD dst_unused:UNUSED_PAD src0_sel:WORD_1 src1_sel:DWORD
	v_add3_u32 v3, v3, v10, s54
	v_add3_u32 v8, v15, v8, s54
	v_and_b32_e32 v3, 0xffff0000, v3
	v_or_b32_sdwa v3, v3, v8 dst_sel:DWORD dst_unused:UNUSED_PAD src0_sel:DWORD src1_sel:WORD_1
	v_and_b32_sdwa v11, v2, v155 dst_sel:DWORD dst_unused:UNUSED_PAD src0_sel:WORD_1 src1_sel:DWORD
	v_and_b32_sdwa v9, v14, v155 dst_sel:DWORD dst_unused:UNUSED_PAD src0_sel:WORD_1 src1_sel:DWORD
	v_add3_u32 v2, v2, v11, s54
	v_add3_u32 v9, v14, v9, s54
	v_and_b32_e32 v2, 0xffff0000, v2
	v_or_b32_sdwa v2, v2, v9 dst_sel:DWORD dst_unused:UNUSED_PAD src0_sel:DWORD src1_sel:WORD_1
	s_waitcnt vmcnt(0)
	v_lshlrev_b32_e32 v21, 16, v56
	v_mul_f32_e32 v8, 0xbfb8aa3b, v21
	v_and_b32_e32 v29, 0xffff0000, v56
	v_lshlrev_b32_e32 v17, 16, v57
	v_exp_f32_e32 v60, v8
	v_mul_f32_e32 v8, 0xbfb8aa3b, v29
	v_exp_f32_e32 v56, v8
	v_mul_f32_e32 v8, 0xbfb8aa3b, v17
	v_exp_f32_e32 v61, v8
	ds_read_b128 v[8:11], v12
	ds_read_b128 v[12:15], v12 offset:16
	v_and_b32_e32 v25, 0xffff0000, v57
	v_lshlrev_b32_e32 v63, 16, v5
	v_pk_add_f32 v[60:61], v[60:61], 1.0 op_sel_hi:[1,0]
	s_waitcnt lgkmcnt(1)
	v_mov_b32_e32 v64, v8
	v_mov_b32_e32 v65, v10
	v_lshlrev_b32_e32 v62, 16, v4
	v_and_b32_e32 v5, 0xffff0000, v5
	v_rcp_f32_e32 v61, v61
	s_nop 0
	v_mul_f32_e32 v61, v17, v61
	v_and_b32_e32 v4, 0xffff0000, v4
	v_mul_f32_e32 v10, 0xbfb8aa3b, v25
	v_exp_f32_e32 v57, v10
	v_rcp_f32_e32 v60, v60
	s_nop 0
	v_mul_f32_e32 v60, v21, v60
	v_mov_b32_e32 v10, v9
	v_pk_mul_f32 v[4:5], v[10:11], v[4:5]
	v_pk_add_f32 v[56:57], v[56:57], 1.0 op_sel_hi:[1,0]
	v_pk_mul_f32 v[62:63], v[64:65], v[62:63]
	v_pk_mul_f32 v[60:61], v[60:61], v[62:63]
	v_lshlrev_b32_e32 v63, 16, v7
	v_lshlrev_b32_e32 v62, 16, v6
	v_rcp_f32_e32 v9, v57
	s_nop 0
	v_mul_f32_e32 v9, v25, v9
	v_rcp_f32_e32 v8, v56
	s_nop 0
	v_mul_f32_e32 v8, v29, v8
	v_pk_mul_f32 v[4:5], v[8:9], v[4:5]
	v_and_b32_sdwa v8, v61, v155 dst_sel:DWORD dst_unused:UNUSED_PAD src0_sel:WORD_1 src1_sel:DWORD
	v_and_b32_sdwa v10, v5, v155 dst_sel:DWORD dst_unused:UNUSED_PAD src0_sel:WORD_1 src1_sel:DWORD
	v_and_b32_sdwa v11, v4, v155 dst_sel:DWORD dst_unused:UNUSED_PAD src0_sel:WORD_1 src1_sel:DWORD
	v_and_b32_sdwa v9, v60, v155 dst_sel:DWORD dst_unused:UNUSED_PAD src0_sel:WORD_1 src1_sel:DWORD
	v_add3_u32 v5, v5, v10, s54
	v_add3_u32 v4, v4, v11, s54
	v_add3_u32 v9, v60, v9, s54
	v_add3_u32 v8, v61, v8, s54
	v_and_b32_e32 v5, 0xffff0000, v5
	v_and_b32_e32 v4, 0xffff0000, v4
	v_lshlrev_b32_e32 v17, 16, v59
	v_lshlrev_b32_e32 v21, 16, v58
	v_or_b32_sdwa v5, v5, v8 dst_sel:DWORD dst_unused:UNUSED_PAD src0_sel:DWORD src1_sel:WORD_1
	v_or_b32_sdwa v4, v4, v9 dst_sel:DWORD dst_unused:UNUSED_PAD src0_sel:DWORD src1_sel:WORD_1
	v_mul_f32_e32 v8, 0xbfb8aa3b, v21
	v_mul_f32_e32 v9, 0xbfb8aa3b, v17
	v_exp_f32_e32 v8, v8
	v_exp_f32_e32 v9, v9
	v_and_b32_e32 v29, 0xffff0000, v58
	v_mul_f32_e32 v10, 0xbfb8aa3b, v29
	v_and_b32_e32 v25, 0xffff0000, v59
	v_exp_f32_e32 v60, v10
	v_pk_add_f32 v[64:65], v[8:9], 1.0 op_sel_hi:[1,0]
	global_load_dwordx4 v[8:11], v[18:19], off
	global_load_dwordx4 v[56:59], v[18:19], off offset:2048
	s_waitcnt lgkmcnt(0)
; __device__ __forceinline__ unsigned pack2(float a, float b) { return (unsigned)f2bf(a) | ((unsigned)f2bf(b) << 16); }
; __device__ __forceinline__ float bflo(unsigned w) { return __uint_as_float(w << 16); }
; __device__ __forceinline__ float bfhi(unsigned w) { return __uint_as_float(w & 0xffff0000u); }
; __device__ __forceinline__ float silu_f(float g) { return g / (1.f + __expf(-g)); }
; __device__ void gmlp_item(const Params& p, int layer, int b, int n, int g, char* smem) {
;     ...
; #pragma unroll
;     for (int i = 0; i < 8; ++i) {
;       int q = tid + 256 * i, t = q >> 4, c = (q & 15) * 8;
;       float4 m0 = *reinterpret_cast<const float4*>(Tf + t * 132 + c);
;       float4 m1 = *reinterpret_cast<const float4*>(Tf + t * 132 + c + 4);
;       float mm[8] = {m0.x, m0.y, m0.z, m0.w, m1.x, m1.y, m1.z, m1.w};
;       unsigned uw[4] = {uu[i].x, uu[i].y, uu[i].z, uu[i].w};
;       unsigned gw[4] = {gt[i].x, gt[i].y, gt[i].z, gt[i].w};
;       unsigned ow[4];
; #pragma unroll
;       for (int e = 0; e < 4; ++e) {
;         float y0 = bflo(uw[e]) * mm[2 * e] * silu_f(bflo(gw[e]));
;         float y1 = bfhi(uw[e]) * mm[2 * e + 1] * silu_f(bfhi(gw[e]));
;         ow[e] = pack2(y0, y1);
;       }
;       *reinterpret_cast<uint4*>(Y + (t0 + t) * YW + g * 128 + c) = make_uint4(ow[0], ow[1], ow[2], ow[3]);
	v_mov_b32_e32 v18, v12
	v_mov_b32_e32 v19, v14
	v_pk_mul_f32 v[18:19], v[18:19], v[62:63]
	v_rcp_f32_e32 v63, v65
	s_nop 0
	v_mul_f32_e32 v63, v17, v63
	v_and_b32_e32 v7, 0xffff0000, v7
	v_mul_f32_e32 v14, 0xbfb8aa3b, v25
	v_exp_f32_e32 v61, v14
	v_rcp_f32_e32 v62, v64
	s_nop 0
	v_mul_f32_e32 v62, v21, v62
	v_mov_b32_e32 v14, v13
	v_and_b32_e32 v6, 0xffff0000, v6
	v_pk_add_f32 v[60:61], v[60:61], 1.0 op_sel_hi:[1,0]
	v_pk_mul_f32 v[6:7], v[14:15], v[6:7]
	v_pk_mul_f32 v[18:19], v[62:63], v[18:19]
	v_rcp_f32_e32 v13, v61
	s_nop 0
	v_mul_f32_e32 v13, v25, v13
	v_rcp_f32_e32 v12, v60
	s_nop 0
	v_mul_f32_e32 v12, v29, v12
	v_pk_mul_f32 v[6:7], v[12:13], v[6:7]
	v_and_b32_sdwa v12, v19, v155 dst_sel:DWORD dst_unused:UNUSED_PAD src0_sel:WORD_1 src1_sel:DWORD
	v_and_b32_sdwa v14, v7, v155 dst_sel:DWORD dst_unused:UNUSED_PAD src0_sel:WORD_1 src1_sel:DWORD
	v_add3_u32 v7, v7, v14, s54
	v_add3_u32 v12, v19, v12, s54
	v_and_b32_e32 v7, 0xffff0000, v7
	v_or_b32_sdwa v7, v7, v12 dst_sel:DWORD dst_unused:UNUSED_PAD src0_sel:DWORD src1_sel:WORD_1
	v_and_b32_sdwa v15, v6, v155 dst_sel:DWORD dst_unused:UNUSED_PAD src0_sel:WORD_1 src1_sel:DWORD
	v_and_b32_sdwa v13, v18, v155 dst_sel:DWORD dst_unused:UNUSED_PAD src0_sel:WORD_1 src1_sel:DWORD
	v_add3_u32 v6, v6, v15, s54
	v_add3_u32 v13, v18, v13, s54
	v_and_b32_e32 v6, 0xffff0000, v6
	v_or_b32_sdwa v6, v6, v13 dst_sel:DWORD dst_unused:UNUSED_PAD src0_sel:DWORD src1_sel:WORD_1
	s_waitcnt vmcnt(1)
	v_lshlrev_b32_e32 v63, 16, v9
	s_waitcnt vmcnt(0)
	v_lshlrev_b32_e32 v25, 16, v56
	v_mul_f32_e32 v12, 0xbfb8aa3b, v25
	v_and_b32_e32 v35, 0xffff0000, v56
	v_lshlrev_b32_e32 v21, 16, v57
	v_exp_f32_e32 v60, v12
	v_mul_f32_e32 v12, 0xbfb8aa3b, v35
	v_exp_f32_e32 v56, v12
	v_mul_f32_e32 v12, 0xbfb8aa3b, v21
	v_exp_f32_e32 v61, v12
	v_and_b32_e32 v29, 0xffff0000, v57
	ds_read_b128 v[12:15], v16
	ds_read_b128 v[16:19], v16 offset:16
	v_lshlrev_b32_e32 v62, 16, v8
	v_pk_add_f32 v[60:61], v[60:61], 1.0 op_sel_hi:[1,0]
	v_and_b32_e32 v9, 0xffff0000, v9
	s_waitcnt lgkmcnt(1)
	v_mov_b32_e32 v64, v12
	v_mov_b32_e32 v65, v14
	v_pk_mul_f32 v[62:63], v[64:65], v[62:63]
	v_rcp_f32_e32 v61, v61
	s_nop 0
	v_mul_f32_e32 v61, v21, v61
	v_and_b32_e32 v8, 0xffff0000, v8
	v_mul_f32_e32 v14, 0xbfb8aa3b, v29
	v_exp_f32_e32 v57, v14
	v_rcp_f32_e32 v60, v60
	s_nop 0
	v_mul_f32_e32 v60, v25, v60
	v_mov_b32_e32 v14, v13
	v_pk_mul_f32 v[8:9], v[14:15], v[8:9]
	v_pk_add_f32 v[56:57], v[56:57], 1.0 op_sel_hi:[1,0]
	v_pk_mul_f32 v[60:61], v[60:61], v[62:63]
	v_lshlrev_b32_e32 v63, 16, v11
	v_lshlrev_b32_e32 v62, 16, v10
	v_and_b32_e32 v11, 0xffff0000, v11
	v_rcp_f32_e32 v13, v57
	s_nop 0
	v_mul_f32_e32 v13, v29, v13
	v_rcp_f32_e32 v12, v56
	s_nop 0
	v_mul_f32_e32 v12, v35, v12
	v_pk_mul_f32 v[8:9], v[12:13], v[8:9]
	v_and_b32_sdwa v12, v61, v155 dst_sel:DWORD dst_unused:UNUSED_PAD src0_sel:WORD_1 src1_sel:DWORD
	v_and_b32_sdwa v14, v9, v155 dst_sel:DWORD dst_unused:UNUSED_PAD src0_sel:WORD_1 src1_sel:DWORD
	v_and_b32_sdwa v15, v8, v155 dst_sel:DWORD dst_unused:UNUSED_PAD src0_sel:WORD_1 src1_sel:DWORD
	v_and_b32_sdwa v13, v60, v155 dst_sel:DWORD dst_unused:UNUSED_PAD src0_sel:WORD_1 src1_sel:DWORD
	v_add3_u32 v9, v9, v14, s54
	v_add3_u32 v8, v8, v15, s54
	v_add3_u32 v13, v60, v13, s54
	v_add3_u32 v12, v61, v12, s54
	v_and_b32_e32 v9, 0xffff0000, v9
	v_and_b32_e32 v8, 0xffff0000, v8
	v_lshlrev_b32_e32 v21, 16, v59
	v_lshlrev_b32_e32 v25, 16, v58
	v_or_b32_sdwa v9, v9, v12 dst_sel:DWORD dst_unused:UNUSED_PAD src0_sel:DWORD src1_sel:WORD_1
	v_or_b32_sdwa v8, v8, v13 dst_sel:DWORD dst_unused:UNUSED_PAD src0_sel:DWORD src1_sel:WORD_1
	v_mul_f32_e32 v12, 0xbfb8aa3b, v25
	v_mul_f32_e32 v13, 0xbfb8aa3b, v21
	v_exp_f32_e32 v12, v12
	v_exp_f32_e32 v13, v13
	v_and_b32_e32 v35, 0xffff0000, v58
	v_mul_f32_e32 v14, 0xbfb8aa3b, v35
	v_and_b32_e32 v29, 0xffff0000, v59
	v_exp_f32_e32 v60, v14
	v_pk_add_f32 v[64:65], v[12:13], 1.0 op_sel_hi:[1,0]
	global_load_dwordx4 v[12:15], v[22:23], off
	global_load_dwordx4 v[56:59], v[22:23], off offset:2048
	s_waitcnt lgkmcnt(0)
	v_mov_b32_e32 v22, v16
	v_mov_b32_e32 v23, v18
	v_pk_mul_f32 v[22:23], v[22:23], v[62:63]
	v_rcp_f32_e32 v63, v65
	s_nop 0
	v_mul_f32_e32 v63, v21, v63
	v_and_b32_e32 v10, 0xffff0000, v10
	v_mul_f32_e32 v18, 0xbfb8aa3b, v29
	v_exp_f32_e32 v61, v18
	v_rcp_f32_e32 v62, v64
	s_nop 0
	v_mul_f32_e32 v62, v25, v62
	v_mov_b32_e32 v18, v17
	v_pk_mul_f32 v[10:11], v[18:19], v[10:11]
	v_pk_add_f32 v[60:61], v[60:61], 1.0 op_sel_hi:[1,0]
	v_pk_mul_f32 v[22:23], v[62:63], v[22:23]
	s_waitcnt vmcnt(1)
	v_lshlrev_b32_e32 v63, 16, v13
	v_rcp_f32_e32 v17, v61
	s_nop 0
	v_mul_f32_e32 v17, v29, v17
	v_rcp_f32_e32 v16, v60
	s_nop 0
	v_mul_f32_e32 v16, v35, v16
	v_pk_mul_f32 v[10:11], v[16:17], v[10:11]
	v_and_b32_sdwa v16, v23, v155 dst_sel:DWORD dst_unused:UNUSED_PAD src0_sel:WORD_1 src1_sel:DWORD
	v_and_b32_sdwa v18, v11, v155 dst_sel:DWORD dst_unused:UNUSED_PAD src0_sel:WORD_1 src1_sel:DWORD
	v_add3_u32 v11, v11, v18, s54
	v_add3_u32 v16, v23, v16, s54
	v_and_b32_e32 v11, 0xffff0000, v11
	s_waitcnt vmcnt(0)
	v_lshlrev_b32_e32 v29, 16, v56
	v_or_b32_sdwa v11, v11, v16 dst_sel:DWORD dst_unused:UNUSED_PAD src0_sel:DWORD src1_sel:WORD_1
	v_mul_f32_e32 v16, 0xbfb8aa3b, v29
	v_and_b32_e32 v55, 0xffff0000, v56
	v_lshlrev_b32_e32 v25, 16, v57
	v_exp_f32_e32 v60, v16
	v_mul_f32_e32 v16, 0xbfb8aa3b, v55
	v_exp_f32_e32 v56, v16
	v_mul_f32_e32 v16, 0xbfb8aa3b, v25
	v_exp_f32_e32 v61, v16
	v_and_b32_sdwa v19, v10, v155 dst_sel:DWORD dst_unused:UNUSED_PAD src0_sel:WORD_1 src1_sel:DWORD
	v_and_b32_sdwa v17, v22, v155 dst_sel:DWORD dst_unused:UNUSED_PAD src0_sel:WORD_1 src1_sel:DWORD
	v_add3_u32 v10, v10, v19, s54
	v_pk_add_f32 v[60:61], v[60:61], 1.0 op_sel_hi:[1,0]
	v_add3_u32 v17, v22, v17, s54
	v_and_b32_e32 v10, 0xffff0000, v10
	v_and_b32_e32 v35, 0xffff0000, v57
	v_or_b32_sdwa v10, v10, v17 dst_sel:DWORD dst_unused:UNUSED_PAD src0_sel:DWORD src1_sel:WORD_1
	ds_read_b128 v[16:19], v20
	ds_read_b128 v[20:23], v20 offset:16
	v_lshlrev_b32_e32 v62, 16, v12
	v_and_b32_e32 v13, 0xffff0000, v13
	s_waitcnt lgkmcnt(1)
; __device__ __forceinline__ unsigned pack2(float a, float b) { return (unsigned)f2bf(a) | ((unsigned)f2bf(b) << 16); }
; __device__ __forceinline__ float bflo(unsigned w) { return __uint_as_float(w << 16); }
; __device__ __forceinline__ float bfhi(unsigned w) { return __uint_as_float(w & 0xffff0000u); }
; __device__ __forceinline__ float silu_f(float g) { return g / (1.f + __expf(-g)); }
; __device__ void gmlp_item(const Params& p, int layer, int b, int n, int g, char* smem) {
;     ...
; #pragma unroll
;     for (int i = 0; i < 8; ++i) {
;       int q = tid + 256 * i, t = q >> 4, c = (q & 15) * 8;
;       float4 m0 = *reinterpret_cast<const float4*>(Tf + t * 132 + c);
;       float4 m1 = *reinterpret_cast<const float4*>(Tf + t * 132 + c + 4);
;       float mm[8] = {m0.x, m0.y, m0.z, m0.w, m1.x, m1.y, m1.z, m1.w};
;       unsigned uw[4] = {uu[i].x, uu[i].y, uu[i].z, uu[i].w};
;       unsigned gw[4] = {gt[i].x, gt[i].y, gt[i].z, gt[i].w};
;       unsigned ow[4];
; #pragma unroll
;       for (int e = 0; e < 4; ++e) {
;         float y0 = bflo(uw[e]) * mm[2 * e] * silu_f(bflo(gw[e]));
;         float y1 = bfhi(uw[e]) * mm[2 * e + 1] * silu_f(bfhi(gw[e]));
;         ow[e] = pack2(y0, y1);
;       }
;       *reinterpret_cast<uint4*>(Y + (t0 + t) * YW + g * 128 + c) = make_uint4(ow[0], ow[1], ow[2], ow[3]);
	v_mov_b32_e32 v64, v16
	v_mov_b32_e32 v65, v18
	v_pk_mul_f32 v[62:63], v[64:65], v[62:63]
	v_rcp_f32_e32 v61, v61
	s_nop 0
	v_mul_f32_e32 v61, v25, v61
	v_and_b32_e32 v12, 0xffff0000, v12
	v_mul_f32_e32 v18, 0xbfb8aa3b, v35
	v_exp_f32_e32 v57, v18
	v_rcp_f32_e32 v60, v60
	s_nop 0
	v_mul_f32_e32 v60, v29, v60
	v_mov_b32_e32 v18, v17
	v_pk_mul_f32 v[12:13], v[18:19], v[12:13]
	v_pk_add_f32 v[56:57], v[56:57], 1.0 op_sel_hi:[1,0]
	v_pk_mul_f32 v[60:61], v[60:61], v[62:63]
	v_lshlrev_b32_e32 v63, 16, v15
	v_lshlrev_b32_e32 v62, 16, v14
	v_and_b32_e32 v15, 0xffff0000, v15
	v_rcp_f32_e32 v17, v57
	s_nop 0
	v_mul_f32_e32 v17, v35, v17
	v_rcp_f32_e32 v16, v56
	s_nop 0
	v_mul_f32_e32 v16, v55, v16
	v_pk_mul_f32 v[12:13], v[16:17], v[12:13]
	v_and_b32_sdwa v16, v61, v155 dst_sel:DWORD dst_unused:UNUSED_PAD src0_sel:WORD_1 src1_sel:DWORD
	v_and_b32_sdwa v18, v13, v155 dst_sel:DWORD dst_unused:UNUSED_PAD src0_sel:WORD_1 src1_sel:DWORD
	v_and_b32_sdwa v19, v12, v155 dst_sel:DWORD dst_unused:UNUSED_PAD src0_sel:WORD_1 src1_sel:DWORD
	v_and_b32_sdwa v17, v60, v155 dst_sel:DWORD dst_unused:UNUSED_PAD src0_sel:WORD_1 src1_sel:DWORD
	v_add3_u32 v13, v13, v18, s54
	v_add3_u32 v12, v12, v19, s54
	v_add3_u32 v17, v60, v17, s54
	v_add3_u32 v16, v61, v16, s54
	v_and_b32_e32 v13, 0xffff0000, v13
	v_and_b32_e32 v12, 0xffff0000, v12
	v_lshlrev_b32_e32 v25, 16, v59
	v_lshlrev_b32_e32 v29, 16, v58
	v_or_b32_sdwa v13, v13, v16 dst_sel:DWORD dst_unused:UNUSED_PAD src0_sel:DWORD src1_sel:WORD_1
	v_or_b32_sdwa v12, v12, v17 dst_sel:DWORD dst_unused:UNUSED_PAD src0_sel:DWORD src1_sel:WORD_1
	v_mul_f32_e32 v16, 0xbfb8aa3b, v29
	v_mul_f32_e32 v17, 0xbfb8aa3b, v25
	v_exp_f32_e32 v16, v16
	v_exp_f32_e32 v17, v17
	v_and_b32_e32 v55, 0xffff0000, v58
	v_mul_f32_e32 v18, 0xbfb8aa3b, v55
	v_and_b32_e32 v35, 0xffff0000, v59
	v_exp_f32_e32 v60, v18
	v_pk_add_f32 v[64:65], v[16:17], 1.0 op_sel_hi:[1,0]
	global_load_dwordx4 v[16:19], v[26:27], off
	global_load_dwordx4 v[56:59], v[26:27], off offset:2048
	s_waitcnt lgkmcnt(0)
	v_mov_b32_e32 v26, v20
	v_mov_b32_e32 v27, v22
	v_pk_mul_f32 v[26:27], v[26:27], v[62:63]
	v_rcp_f32_e32 v63, v65
	s_nop 0
	v_mul_f32_e32 v63, v25, v63
	v_and_b32_e32 v14, 0xffff0000, v14
	v_mul_f32_e32 v22, 0xbfb8aa3b, v35
	v_exp_f32_e32 v61, v22
	v_rcp_f32_e32 v62, v64
	s_nop 0
	v_mul_f32_e32 v62, v29, v62
	v_mov_b32_e32 v22, v21
	v_pk_mul_f32 v[14:15], v[22:23], v[14:15]
	v_pk_add_f32 v[60:61], v[60:61], 1.0 op_sel_hi:[1,0]
	v_pk_mul_f32 v[26:27], v[62:63], v[26:27]
	s_waitcnt vmcnt(1)
	v_lshlrev_b32_e32 v63, 16, v17
	v_rcp_f32_e32 v21, v61
	s_nop 0
	v_mul_f32_e32 v21, v35, v21
	v_rcp_f32_e32 v20, v60
	s_nop 0
	v_mul_f32_e32 v20, v55, v20
	v_pk_mul_f32 v[14:15], v[20:21], v[14:15]
	v_and_b32_sdwa v20, v27, v155 dst_sel:DWORD dst_unused:UNUSED_PAD src0_sel:WORD_1 src1_sel:DWORD
	v_and_b32_sdwa v22, v15, v155 dst_sel:DWORD dst_unused:UNUSED_PAD src0_sel:WORD_1 src1_sel:DWORD
	v_add3_u32 v15, v15, v22, s54
	v_add3_u32 v20, v27, v20, s54
	v_and_b32_e32 v15, 0xffff0000, v15
	s_waitcnt vmcnt(0)
	v_lshlrev_b32_e32 v35, 16, v56
	v_or_b32_sdwa v15, v15, v20 dst_sel:DWORD dst_unused:UNUSED_PAD src0_sel:DWORD src1_sel:WORD_1
	v_mul_f32_e32 v20, 0xbfb8aa3b, v35
	v_and_b32_e32 v66, 0xffff0000, v56
	v_lshlrev_b32_e32 v29, 16, v57
	v_exp_f32_e32 v60, v20
	v_mul_f32_e32 v20, 0xbfb8aa3b, v66
	v_exp_f32_e32 v56, v20
	v_mul_f32_e32 v20, 0xbfb8aa3b, v29
	v_exp_f32_e32 v61, v20
	v_and_b32_sdwa v23, v14, v155 dst_sel:DWORD dst_unused:UNUSED_PAD src0_sel:WORD_1 src1_sel:DWORD
	v_and_b32_sdwa v21, v26, v155 dst_sel:DWORD dst_unused:UNUSED_PAD src0_sel:WORD_1 src1_sel:DWORD
	v_add3_u32 v14, v14, v23, s54
	v_pk_add_f32 v[60:61], v[60:61], 1.0 op_sel_hi:[1,0]
	v_add3_u32 v21, v26, v21, s54
	v_and_b32_e32 v14, 0xffff0000, v14
	v_and_b32_e32 v55, 0xffff0000, v57
	v_or_b32_sdwa v14, v14, v21 dst_sel:DWORD dst_unused:UNUSED_PAD src0_sel:DWORD src1_sel:WORD_1
	ds_read_b128 v[20:23], v24
	ds_read_b128 v[24:27], v24 offset:16
	v_lshlrev_b32_e32 v62, 16, v16
	v_and_b32_e32 v17, 0xffff0000, v17
	s_waitcnt lgkmcnt(1)
	v_mov_b32_e32 v64, v20
	v_mov_b32_e32 v65, v22
	v_pk_mul_f32 v[62:63], v[64:65], v[62:63]
	v_rcp_f32_e32 v61, v61
	s_nop 0
	v_mul_f32_e32 v61, v29, v61
	v_and_b32_e32 v16, 0xffff0000, v16
	v_mul_f32_e32 v22, 0xbfb8aa3b, v55
	v_exp_f32_e32 v57, v22
	v_rcp_f32_e32 v60, v60
	s_nop 0
	v_mul_f32_e32 v60, v35, v60
	v_mov_b32_e32 v22, v21
	v_pk_mul_f32 v[16:17], v[22:23], v[16:17]
	v_pk_add_f32 v[56:57], v[56:57], 1.0 op_sel_hi:[1,0]
	v_pk_mul_f32 v[60:61], v[60:61], v[62:63]
	v_lshlrev_b32_e32 v63, 16, v19
	v_lshlrev_b32_e32 v62, 16, v18
	v_and_b32_e32 v19, 0xffff0000, v19
	v_rcp_f32_e32 v21, v57
	s_nop 0
	v_mul_f32_e32 v21, v55, v21
	v_rcp_f32_e32 v20, v56
	s_nop 0
	v_mul_f32_e32 v20, v66, v20
	v_pk_mul_f32 v[16:17], v[20:21], v[16:17]
	v_and_b32_sdwa v20, v61, v155 dst_sel:DWORD dst_unused:UNUSED_PAD src0_sel:WORD_1 src1_sel:DWORD
	v_and_b32_sdwa v22, v17, v155 dst_sel:DWORD dst_unused:UNUSED_PAD src0_sel:WORD_1 src1_sel:DWORD
	v_and_b32_sdwa v23, v16, v155 dst_sel:DWORD dst_unused:UNUSED_PAD src0_sel:WORD_1 src1_sel:DWORD
	v_and_b32_sdwa v21, v60, v155 dst_sel:DWORD dst_unused:UNUSED_PAD src0_sel:WORD_1 src1_sel:DWORD
	v_add3_u32 v17, v17, v22, s54
	v_add3_u32 v16, v16, v23, s54
	v_add3_u32 v21, v60, v21, s54
	v_add3_u32 v20, v61, v20, s54
	v_and_b32_e32 v17, 0xffff0000, v17
	v_and_b32_e32 v16, 0xffff0000, v16
	v_lshlrev_b32_e32 v29, 16, v59
	v_lshlrev_b32_e32 v35, 16, v58
	v_or_b32_sdwa v17, v17, v20 dst_sel:DWORD dst_unused:UNUSED_PAD src0_sel:DWORD src1_sel:WORD_1
	v_or_b32_sdwa v16, v16, v21 dst_sel:DWORD dst_unused:UNUSED_PAD src0_sel:DWORD src1_sel:WORD_1
	v_mul_f32_e32 v20, 0xbfb8aa3b, v35
	v_mul_f32_e32 v21, 0xbfb8aa3b, v29
	v_exp_f32_e32 v20, v20
	v_exp_f32_e32 v21, v21
	v_and_b32_e32 v66, 0xffff0000, v58
	v_mul_f32_e32 v22, 0xbfb8aa3b, v66
	v_and_b32_e32 v55, 0xffff0000, v59
	v_exp_f32_e32 v60, v22
	v_pk_add_f32 v[64:65], v[20:21], 1.0 op_sel_hi:[1,0]
	global_load_dwordx4 v[20:23], v[30:31], off
	global_load_dwordx4 v[56:59], v[30:31], off offset:2048
	s_waitcnt lgkmcnt(0)
; __device__ __forceinline__ unsigned pack2(float a, float b) { return (unsigned)f2bf(a) | ((unsigned)f2bf(b) << 16); }
; __device__ __forceinline__ float bflo(unsigned w) { return __uint_as_float(w << 16); }
; __device__ __forceinline__ float bfhi(unsigned w) { return __uint_as_float(w & 0xffff0000u); }
; __device__ __forceinline__ float silu_f(float g) { return g / (1.f + __expf(-g)); }
; __device__ void gmlp_item(const Params& p, int layer, int b, int n, int g, char* smem) {
;     ...
; #pragma unroll
;     for (int i = 0; i < 8; ++i) {
;       int q = tid + 256 * i, t = q >> 4, c = (q & 15) * 8;
;       float4 m0 = *reinterpret_cast<const float4*>(Tf + t * 132 + c);
;       float4 m1 = *reinterpret_cast<const float4*>(Tf + t * 132 + c + 4);
;       float mm[8] = {m0.x, m0.y, m0.z, m0.w, m1.x, m1.y, m1.z, m1.w};
;       unsigned uw[4] = {uu[i].x, uu[i].y, uu[i].z, uu[i].w};
;       unsigned gw[4] = {gt[i].x, gt[i].y, gt[i].z, gt[i].w};
;       unsigned ow[4];
; #pragma unroll
;       for (int e = 0; e < 4; ++e) {
;         float y0 = bflo(uw[e]) * mm[2 * e] * silu_f(bflo(gw[e]));
;         float y1 = bfhi(uw[e]) * mm[2 * e + 1] * silu_f(bfhi(gw[e]));
;         ow[e] = pack2(y0, y1);
;       }
;       *reinterpret_cast<uint4*>(Y + (t0 + t) * YW + g * 128 + c) = make_uint4(ow[0], ow[1], ow[2], ow[3]);
	v_mov_b32_e32 v30, v24
	v_mov_b32_e32 v31, v26
	v_pk_mul_f32 v[30:31], v[30:31], v[62:63]
	v_rcp_f32_e32 v63, v65
	s_nop 0
	v_mul_f32_e32 v63, v29, v63
	v_and_b32_e32 v18, 0xffff0000, v18
	v_mul_f32_e32 v26, 0xbfb8aa3b, v55
	v_exp_f32_e32 v61, v26
	v_rcp_f32_e32 v62, v64
	s_nop 0
	v_mul_f32_e32 v62, v35, v62
	v_mov_b32_e32 v26, v25
	v_pk_mul_f32 v[18:19], v[26:27], v[18:19]
	v_pk_add_f32 v[60:61], v[60:61], 1.0 op_sel_hi:[1,0]
	v_pk_mul_f32 v[30:31], v[62:63], v[30:31]
	s_waitcnt vmcnt(1)
	v_lshlrev_b32_e32 v63, 16, v21
	v_rcp_f32_e32 v25, v61
	s_nop 0
	v_mul_f32_e32 v25, v55, v25
	v_rcp_f32_e32 v24, v60
	s_nop 0
	v_mul_f32_e32 v24, v66, v24
	v_pk_mul_f32 v[18:19], v[24:25], v[18:19]
	v_and_b32_sdwa v24, v31, v155 dst_sel:DWORD dst_unused:UNUSED_PAD src0_sel:WORD_1 src1_sel:DWORD
	v_and_b32_sdwa v26, v19, v155 dst_sel:DWORD dst_unused:UNUSED_PAD src0_sel:WORD_1 src1_sel:DWORD
	v_add3_u32 v19, v19, v26, s54
	v_add3_u32 v24, v31, v24, s54
	v_and_b32_e32 v19, 0xffff0000, v19
	s_waitcnt vmcnt(0)
	v_lshlrev_b32_e32 v55, 16, v56
	v_or_b32_sdwa v19, v19, v24 dst_sel:DWORD dst_unused:UNUSED_PAD src0_sel:DWORD src1_sel:WORD_1
	v_mul_f32_e32 v24, 0xbfb8aa3b, v55
	v_and_b32_e32 v67, 0xffff0000, v56
	v_lshlrev_b32_e32 v35, 16, v57
	v_exp_f32_e32 v60, v24
	v_mul_f32_e32 v24, 0xbfb8aa3b, v67
	v_exp_f32_e32 v56, v24
	v_mul_f32_e32 v24, 0xbfb8aa3b, v35
	v_exp_f32_e32 v61, v24
	v_and_b32_sdwa v27, v18, v155 dst_sel:DWORD dst_unused:UNUSED_PAD src0_sel:WORD_1 src1_sel:DWORD
	v_and_b32_sdwa v25, v30, v155 dst_sel:DWORD dst_unused:UNUSED_PAD src0_sel:WORD_1 src1_sel:DWORD
	v_add3_u32 v18, v18, v27, s54
	v_pk_add_f32 v[60:61], v[60:61], 1.0 op_sel_hi:[1,0]
	v_add3_u32 v25, v30, v25, s54
	v_and_b32_e32 v18, 0xffff0000, v18
	v_and_b32_e32 v66, 0xffff0000, v57
	v_or_b32_sdwa v18, v18, v25 dst_sel:DWORD dst_unused:UNUSED_PAD src0_sel:DWORD src1_sel:WORD_1
	ds_read_b128 v[24:27], v28
	ds_read_b128 v[28:31], v28 offset:16
	v_lshlrev_b32_e32 v62, 16, v20
	v_and_b32_e32 v21, 0xffff0000, v21
	s_waitcnt lgkmcnt(1)
	v_mov_b32_e32 v64, v24
	v_mov_b32_e32 v65, v26
	v_pk_mul_f32 v[62:63], v[64:65], v[62:63]
	v_rcp_f32_e32 v61, v61
	s_nop 0
	v_mul_f32_e32 v61, v35, v61
	v_and_b32_e32 v20, 0xffff0000, v20
	v_mul_f32_e32 v26, 0xbfb8aa3b, v66
	v_exp_f32_e32 v57, v26
	v_rcp_f32_e32 v60, v60
	s_nop 0
	v_mul_f32_e32 v60, v55, v60
	v_mov_b32_e32 v26, v25
	v_pk_mul_f32 v[20:21], v[26:27], v[20:21]
	v_pk_add_f32 v[56:57], v[56:57], 1.0 op_sel_hi:[1,0]
	v_pk_mul_f32 v[60:61], v[60:61], v[62:63]
	v_lshlrev_b32_e32 v63, 16, v23
	v_lshlrev_b32_e32 v62, 16, v22
	v_and_b32_e32 v23, 0xffff0000, v23
	v_rcp_f32_e32 v25, v57
	s_nop 0
	v_mul_f32_e32 v25, v66, v25
	v_rcp_f32_e32 v24, v56
	s_nop 0
	v_mul_f32_e32 v24, v67, v24
	v_pk_mul_f32 v[20:21], v[24:25], v[20:21]
	v_and_b32_sdwa v24, v61, v155 dst_sel:DWORD dst_unused:UNUSED_PAD src0_sel:WORD_1 src1_sel:DWORD
	v_and_b32_sdwa v26, v21, v155 dst_sel:DWORD dst_unused:UNUSED_PAD src0_sel:WORD_1 src1_sel:DWORD
	v_and_b32_sdwa v27, v20, v155 dst_sel:DWORD dst_unused:UNUSED_PAD src0_sel:WORD_1 src1_sel:DWORD
	v_and_b32_sdwa v25, v60, v155 dst_sel:DWORD dst_unused:UNUSED_PAD src0_sel:WORD_1 src1_sel:DWORD
	v_add3_u32 v21, v21, v26, s54
	v_add3_u32 v20, v20, v27, s54
	v_add3_u32 v25, v60, v25, s54
	v_add3_u32 v24, v61, v24, s54
	v_and_b32_e32 v21, 0xffff0000, v21
	v_and_b32_e32 v20, 0xffff0000, v20
	v_lshlrev_b32_e32 v35, 16, v59
	v_lshlrev_b32_e32 v55, 16, v58
	v_or_b32_sdwa v21, v21, v24 dst_sel:DWORD dst_unused:UNUSED_PAD src0_sel:DWORD src1_sel:WORD_1
	v_or_b32_sdwa v20, v20, v25 dst_sel:DWORD dst_unused:UNUSED_PAD src0_sel:DWORD src1_sel:WORD_1
	v_mul_f32_e32 v24, 0xbfb8aa3b, v55
	v_mul_f32_e32 v25, 0xbfb8aa3b, v35
	v_exp_f32_e32 v24, v24
	v_exp_f32_e32 v25, v25
	v_and_b32_e32 v67, 0xffff0000, v58
	v_mul_f32_e32 v26, 0xbfb8aa3b, v67
	v_and_b32_e32 v66, 0xffff0000, v59
	v_exp_f32_e32 v60, v26
	v_pk_add_f32 v[64:65], v[24:25], 1.0 op_sel_hi:[1,0]
	global_load_dwordx4 v[24:27], v[32:33], off
	global_load_dwordx4 v[56:59], v[32:33], off offset:2048
	s_waitcnt lgkmcnt(0)
	v_mov_b32_e32 v32, v28
	v_mov_b32_e32 v33, v30
	v_pk_mul_f32 v[32:33], v[32:33], v[62:63]
	v_rcp_f32_e32 v63, v65
	s_nop 0
	v_mul_f32_e32 v63, v35, v63
	v_and_b32_e32 v22, 0xffff0000, v22
	v_mul_f32_e32 v30, 0xbfb8aa3b, v66
	v_exp_f32_e32 v61, v30
	v_rcp_f32_e32 v62, v64
	s_nop 0
	v_mul_f32_e32 v62, v55, v62
	v_mov_b32_e32 v30, v29
	v_pk_mul_f32 v[22:23], v[30:31], v[22:23]
	v_pk_add_f32 v[60:61], v[60:61], 1.0 op_sel_hi:[1,0]
	v_pk_mul_f32 v[32:33], v[62:63], v[32:33]
	s_waitcnt vmcnt(1)
	v_lshlrev_b32_e32 v63, 16, v25
	v_rcp_f32_e32 v29, v61
	s_nop 0
	v_mul_f32_e32 v29, v66, v29
	v_rcp_f32_e32 v28, v60
	s_nop 0
	v_mul_f32_e32 v28, v67, v28
	v_pk_mul_f32 v[22:23], v[28:29], v[22:23]
	v_and_b32_sdwa v28, v33, v155 dst_sel:DWORD dst_unused:UNUSED_PAD src0_sel:WORD_1 src1_sel:DWORD
	v_and_b32_sdwa v30, v23, v155 dst_sel:DWORD dst_unused:UNUSED_PAD src0_sel:WORD_1 src1_sel:DWORD
	v_add3_u32 v23, v23, v30, s54
	v_add3_u32 v28, v33, v28, s54
	v_and_b32_e32 v23, 0xffff0000, v23
	s_waitcnt vmcnt(0)
	v_lshlrev_b32_e32 v66, 16, v56
	v_or_b32_sdwa v23, v23, v28 dst_sel:DWORD dst_unused:UNUSED_PAD src0_sel:DWORD src1_sel:WORD_1
	v_mul_f32_e32 v28, 0xbfb8aa3b, v66
	v_and_b32_e32 v68, 0xffff0000, v56
	v_lshlrev_b32_e32 v55, 16, v57
	v_exp_f32_e32 v60, v28
	v_mul_f32_e32 v28, 0xbfb8aa3b, v68
	v_exp_f32_e32 v56, v28
	v_mul_f32_e32 v28, 0xbfb8aa3b, v55
	v_exp_f32_e32 v61, v28
	v_and_b32_sdwa v31, v22, v155 dst_sel:DWORD dst_unused:UNUSED_PAD src0_sel:WORD_1 src1_sel:DWORD
	v_and_b32_sdwa v29, v32, v155 dst_sel:DWORD dst_unused:UNUSED_PAD src0_sel:WORD_1 src1_sel:DWORD
	v_add3_u32 v22, v22, v31, s54
	v_pk_add_f32 v[60:61], v[60:61], 1.0 op_sel_hi:[1,0]
	v_add3_u32 v29, v32, v29, s54
	v_and_b32_e32 v22, 0xffff0000, v22
	v_and_b32_e32 v67, 0xffff0000, v57
	v_or_b32_sdwa v22, v22, v29 dst_sel:DWORD dst_unused:UNUSED_PAD src0_sel:DWORD src1_sel:WORD_1
	ds_read_b128 v[28:31], v34
	ds_read_b128 v[32:35], v34 offset:16
	v_lshlrev_b32_e32 v62, 16, v24
	v_and_b32_e32 v25, 0xffff0000, v25
	s_waitcnt lgkmcnt(1)
; __device__ __forceinline__ unsigned pack2(float a, float b) { return (unsigned)f2bf(a) | ((unsigned)f2bf(b) << 16); }
; __device__ __forceinline__ float bflo(unsigned w) { return __uint_as_float(w << 16); }
; __device__ __forceinline__ float bfhi(unsigned w) { return __uint_as_float(w & 0xffff0000u); }
; __device__ __forceinline__ float silu_f(float g) { return g / (1.f + __expf(-g)); }
; __device__ void gmlp_item(const Params& p, int layer, int b, int n, int g, char* smem) {
;     ...
; #pragma unroll
;     for (int i = 0; i < 8; ++i) {
;       int q = tid + 256 * i, t = q >> 4, c = (q & 15) * 8;
;       float4 m0 = *reinterpret_cast<const float4*>(Tf + t * 132 + c);
;       float4 m1 = *reinterpret_cast<const float4*>(Tf + t * 132 + c + 4);
;       float mm[8] = {m0.x, m0.y, m0.z, m0.w, m1.x, m1.y, m1.z, m1.w};
;       unsigned uw[4] = {uu[i].x, uu[i].y, uu[i].z, uu[i].w};
;       unsigned gw[4] = {gt[i].x, gt[i].y, gt[i].z, gt[i].w};
;       unsigned ow[4];
; #pragma unroll
;       for (int e = 0; e < 4; ++e) {
;         float y0 = bflo(uw[e]) * mm[2 * e] * silu_f(bflo(gw[e]));
;         float y1 = bfhi(uw[e]) * mm[2 * e + 1] * silu_f(bfhi(gw[e]));
;         ow[e] = pack2(y0, y1);
;       }
;       *reinterpret_cast<uint4*>(Y + (t0 + t) * YW + g * 128 + c) = make_uint4(ow[0], ow[1], ow[2], ow[3]);
	v_mov_b32_e32 v64, v28
	v_mov_b32_e32 v65, v30
	v_pk_mul_f32 v[62:63], v[64:65], v[62:63]
	v_rcp_f32_e32 v61, v61
	s_nop 0
	v_mul_f32_e32 v61, v55, v61
	v_and_b32_e32 v24, 0xffff0000, v24
	v_mul_f32_e32 v30, 0xbfb8aa3b, v67
	v_exp_f32_e32 v57, v30
	v_rcp_f32_e32 v60, v60
	s_nop 0
	v_mul_f32_e32 v60, v66, v60
	v_mov_b32_e32 v30, v29
	v_pk_mul_f32 v[24:25], v[30:31], v[24:25]
	v_pk_add_f32 v[56:57], v[56:57], 1.0 op_sel_hi:[1,0]
	v_pk_mul_f32 v[60:61], v[60:61], v[62:63]
	v_lshlrev_b32_e32 v66, 16, v58
	v_lshlrev_b32_e32 v63, 16, v27
	v_and_b32_e32 v27, 0xffff0000, v27
	v_rcp_f32_e32 v29, v57
	s_nop 0
	v_mul_f32_e32 v29, v67, v29
	v_rcp_f32_e32 v28, v56
	s_nop 0
	v_mul_f32_e32 v28, v68, v28
	v_pk_mul_f32 v[24:25], v[28:29], v[24:25]
	v_and_b32_sdwa v28, v61, v155 dst_sel:DWORD dst_unused:UNUSED_PAD src0_sel:WORD_1 src1_sel:DWORD
	v_and_b32_sdwa v30, v25, v155 dst_sel:DWORD dst_unused:UNUSED_PAD src0_sel:WORD_1 src1_sel:DWORD
	v_and_b32_sdwa v31, v24, v155 dst_sel:DWORD dst_unused:UNUSED_PAD src0_sel:WORD_1 src1_sel:DWORD
	v_and_b32_sdwa v29, v60, v155 dst_sel:DWORD dst_unused:UNUSED_PAD src0_sel:WORD_1 src1_sel:DWORD
	v_add3_u32 v25, v25, v30, s54
	v_add3_u32 v24, v24, v31, s54
	v_add3_u32 v29, v60, v29, s54
	v_add3_u32 v28, v61, v28, s54
	v_and_b32_e32 v25, 0xffff0000, v25
	v_and_b32_e32 v24, 0xffff0000, v24
	v_lshlrev_b32_e32 v55, 16, v59
	v_or_b32_sdwa v25, v25, v28 dst_sel:DWORD dst_unused:UNUSED_PAD src0_sel:DWORD src1_sel:WORD_1
	v_or_b32_sdwa v24, v24, v29 dst_sel:DWORD dst_unused:UNUSED_PAD src0_sel:DWORD src1_sel:WORD_1
	v_mul_f32_e32 v28, 0xbfb8aa3b, v66
	v_mul_f32_e32 v29, 0xbfb8aa3b, v55
	v_exp_f32_e32 v28, v28
	v_exp_f32_e32 v29, v29
	v_and_b32_e32 v68, 0xffff0000, v58
	v_mul_f32_e32 v30, 0xbfb8aa3b, v68
	v_and_b32_e32 v67, 0xffff0000, v59
	v_exp_f32_e32 v60, v30
	v_pk_add_f32 v[64:65], v[28:29], 1.0 op_sel_hi:[1,0]
	global_load_dwordx4 v[28:31], v[52:53], off
	global_load_dwordx4 v[56:59], v[52:53], off offset:2048
	s_waitcnt lgkmcnt(0)
	v_mov_b32_e32 v52, v32
	v_lshlrev_b32_e32 v62, 16, v26
	v_mov_b32_e32 v53, v34
	v_pk_mul_f32 v[52:53], v[52:53], v[62:63]
	v_rcp_f32_e32 v63, v65
	s_nop 0
	v_mul_f32_e32 v63, v55, v63
	v_and_b32_e32 v26, 0xffff0000, v26
	v_mul_f32_e32 v34, 0xbfb8aa3b, v67
	v_exp_f32_e32 v61, v34
	v_rcp_f32_e32 v62, v64
	s_nop 0
	v_mul_f32_e32 v62, v66, v62
	v_mov_b32_e32 v34, v33
	v_pk_mul_f32 v[26:27], v[34:35], v[26:27]
	v_pk_add_f32 v[60:61], v[60:61], 1.0 op_sel_hi:[1,0]
	v_pk_mul_f32 v[52:53], v[62:63], v[52:53]
	s_waitcnt vmcnt(1)
	v_lshlrev_b32_e32 v63, 16, v29
	v_rcp_f32_e32 v33, v61
	s_nop 0
	v_mul_f32_e32 v33, v67, v33
	v_rcp_f32_e32 v32, v60
	s_nop 0
	v_mul_f32_e32 v32, v68, v32
	v_pk_mul_f32 v[26:27], v[32:33], v[26:27]
	v_and_b32_sdwa v32, v53, v155 dst_sel:DWORD dst_unused:UNUSED_PAD src0_sel:WORD_1 src1_sel:DWORD
	v_and_b32_sdwa v34, v27, v155 dst_sel:DWORD dst_unused:UNUSED_PAD src0_sel:WORD_1 src1_sel:DWORD
	v_add3_u32 v27, v27, v34, s54
	v_add3_u32 v32, v53, v32, s54
	v_and_b32_e32 v27, 0xffff0000, v27
	s_waitcnt vmcnt(0)
	v_lshlrev_b32_e32 v67, 16, v56
	v_or_b32_sdwa v27, v27, v32 dst_sel:DWORD dst_unused:UNUSED_PAD src0_sel:DWORD src1_sel:WORD_1
	v_mul_f32_e32 v32, 0xbfb8aa3b, v67
	v_and_b32_e32 v69, 0xffff0000, v56
	v_lshlrev_b32_e32 v66, 16, v57
	v_exp_f32_e32 v60, v32
	v_mul_f32_e32 v32, 0xbfb8aa3b, v69
	v_exp_f32_e32 v56, v32
	v_mul_f32_e32 v32, 0xbfb8aa3b, v66
	v_exp_f32_e32 v61, v32
	v_and_b32_sdwa v35, v26, v155 dst_sel:DWORD dst_unused:UNUSED_PAD src0_sel:WORD_1 src1_sel:DWORD
	v_and_b32_sdwa v33, v52, v155 dst_sel:DWORD dst_unused:UNUSED_PAD src0_sel:WORD_1 src1_sel:DWORD
	v_add3_u32 v26, v26, v35, s54
	v_pk_add_f32 v[60:61], v[60:61], 1.0 op_sel_hi:[1,0]
	v_add3_u32 v33, v52, v33, s54
	v_and_b32_e32 v26, 0xffff0000, v26
	v_and_b32_e32 v68, 0xffff0000, v57
	v_or_b32_sdwa v26, v26, v33 dst_sel:DWORD dst_unused:UNUSED_PAD src0_sel:DWORD src1_sel:WORD_1
	ds_read_b128 v[32:35], v54
	ds_read_b128 v[52:55], v54 offset:16
	v_lshlrev_b32_e32 v62, 16, v28
	v_and_b32_e32 v29, 0xffff0000, v29
	s_waitcnt lgkmcnt(1)
; __device__ __forceinline__ unsigned pack2(float a, float b) { return (unsigned)f2bf(a) | ((unsigned)f2bf(b) << 16); }
; __device__ __forceinline__ float bflo(unsigned w) { return __uint_as_float(w << 16); }
; __device__ __forceinline__ float bfhi(unsigned w) { return __uint_as_float(w & 0xffff0000u); }
; __device__ __forceinline__ float silu_f(float g) { return g / (1.f + __expf(-g)); }
; __device__ void gmlp_item(const Params& p, int layer, int b, int n, int g, char* smem) {
;     ...
; #pragma unroll
;     for (int i = 0; i < 8; ++i) {
;       int q = tid + 256 * i, t = q >> 4, c = (q & 15) * 8;
;       float4 m0 = *reinterpret_cast<const float4*>(Tf + t * 132 + c);
;       float4 m1 = *reinterpret_cast<const float4*>(Tf + t * 132 + c + 4);
;       float mm[8] = {m0.x, m0.y, m0.z, m0.w, m1.x, m1.y, m1.z, m1.w};
;       unsigned uw[4] = {uu[i].x, uu[i].y, uu[i].z, uu[i].w};
;       unsigned gw[4] = {gt[i].x, gt[i].y, gt[i].z, gt[i].w};
;       unsigned ow[4];
; #pragma unroll
;       for (int e = 0; e < 4; ++e) {
;         float y0 = bflo(uw[e]) * mm[2 * e] * silu_f(bflo(gw[e]));
;         float y1 = bfhi(uw[e]) * mm[2 * e + 1] * silu_f(bfhi(gw[e]));
;         ow[e] = pack2(y0, y1);
;       }
;       *reinterpret_cast<uint4*>(Y + (t0 + t) * YW + g * 128 + c) = make_uint4(ow[0], ow[1], ow[2], ow[3]);
	v_mov_b32_e32 v64, v32
	v_mov_b32_e32 v65, v34
	v_pk_mul_f32 v[62:63], v[64:65], v[62:63]
	v_rcp_f32_e32 v61, v61
	s_nop 0
	v_mul_f32_e32 v61, v66, v61
	v_and_b32_e32 v28, 0xffff0000, v28
	v_mul_f32_e32 v34, 0xbfb8aa3b, v68
	v_exp_f32_e32 v57, v34
	v_rcp_f32_e32 v60, v60
	s_nop 0
	v_mul_f32_e32 v60, v67, v60
	v_pk_mul_f32 v[60:61], v[60:61], v[62:63]
	v_mov_b32_e32 v34, v33
	v_pk_add_f32 v[56:57], v[56:57], 1.0 op_sel_hi:[1,0]
	v_pk_mul_f32 v[28:29], v[34:35], v[28:29]
	s_nop 0
	v_rcp_f32_e32 v33, v57
	s_nop 0
	v_mul_f32_e32 v33, v68, v33
	v_rcp_f32_e32 v32, v56
	s_nop 0
	v_mul_f32_e32 v32, v69, v32
	v_pk_mul_f32 v[28:29], v[32:33], v[28:29]
	v_and_b32_sdwa v32, v61, v155 dst_sel:DWORD dst_unused:UNUSED_PAD src0_sel:WORD_1 src1_sel:DWORD
	v_and_b32_sdwa v34, v29, v155 dst_sel:DWORD dst_unused:UNUSED_PAD src0_sel:WORD_1 src1_sel:DWORD
	v_and_b32_sdwa v35, v28, v155 dst_sel:DWORD dst_unused:UNUSED_PAD src0_sel:WORD_1 src1_sel:DWORD
	v_and_b32_sdwa v33, v60, v155 dst_sel:DWORD dst_unused:UNUSED_PAD src0_sel:WORD_1 src1_sel:DWORD
	v_add3_u32 v29, v29, v34, s54
	v_add3_u32 v28, v28, v35, s54
	v_add3_u32 v33, v60, v33, s54
	v_add3_u32 v32, v61, v32, s54
	v_and_b32_e32 v29, 0xffff0000, v29
	v_and_b32_e32 v28, 0xffff0000, v28
	v_lshlrev_b32_e32 v35, 16, v59
	v_lshlrev_b32_e32 v60, 16, v58
	v_or_b32_sdwa v29, v29, v32 dst_sel:DWORD dst_unused:UNUSED_PAD src0_sel:DWORD src1_sel:WORD_1
	v_or_b32_sdwa v28, v28, v33 dst_sel:DWORD dst_unused:UNUSED_PAD src0_sel:DWORD src1_sel:WORD_1
	v_mul_f32_e32 v32, 0xbfb8aa3b, v60
	v_mul_f32_e32 v33, 0xbfb8aa3b, v35
	v_exp_f32_e32 v32, v32
	v_exp_f32_e32 v33, v33
	v_and_b32_e32 v62, 0xffff0000, v58
	s_waitcnt lgkmcnt(0)
	v_mov_b32_e32 v58, v52
	v_and_b32_e32 v61, 0xffff0000, v59
	v_pk_add_f32 v[32:33], v[32:33], 1.0 op_sel_hi:[1,0]
	v_lshlrev_b32_e32 v57, 16, v31
	v_lshlrev_b32_e32 v56, 16, v30
	v_mov_b32_e32 v59, v54
	v_pk_mul_f32 v[56:57], v[58:59], v[56:57]
	v_rcp_f32_e32 v33, v33
	s_nop 0
	v_mul_f32_e32 v33, v35, v33
	v_mul_f32_e32 v34, 0xbfb8aa3b, v62
	v_mul_f32_e32 v35, 0xbfb8aa3b, v61
	v_exp_f32_e32 v34, v34
	v_exp_f32_e32 v35, v35
	v_rcp_f32_e32 v32, v32
	s_nop 0
	v_mul_f32_e32 v32, v60, v32
	v_pk_mul_f32 v[32:33], v[32:33], v[56:57]
	v_mov_b32_e32 v54, v53
	v_pk_add_f32 v[34:35], v[34:35], 1.0 op_sel_hi:[1,0]
	v_and_b32_e32 v31, 0xffff0000, v31
	v_and_b32_e32 v30, 0xffff0000, v30
	v_pk_mul_f32 v[30:31], v[54:55], v[30:31]
	v_rcp_f32_e32 v35, v35
	s_nop 0
	v_mul_f32_e32 v35, v61, v35
	s_mov_b64 s[6:7], 0
	v_rcp_f32_e32 v34, v34
	s_nop 0
	v_mul_f32_e32 v34, v62, v34
	v_pk_mul_f32 v[30:31], v[34:35], v[30:31]
	v_and_b32_sdwa v34, v33, v155 dst_sel:DWORD dst_unused:UNUSED_PAD src0_sel:WORD_1 src1_sel:DWORD
	v_and_b32_sdwa v35, v32, v155 dst_sel:DWORD dst_unused:UNUSED_PAD src0_sel:WORD_1 src1_sel:DWORD
	v_add3_u32 v32, v32, v35, s54
	v_add3_u32 v33, v33, v34, s54
	v_and_b32_sdwa v34, v31, v155 dst_sel:DWORD dst_unused:UNUSED_PAD src0_sel:WORD_1 src1_sel:DWORD
	v_and_b32_sdwa v35, v30, v155 dst_sel:DWORD dst_unused:UNUSED_PAD src0_sel:WORD_1 src1_sel:DWORD
	v_add3_u32 v31, v31, v34, s54
	v_add3_u32 v30, v30, v35, s54
	v_and_b32_e32 v31, 0xffff0000, v31
	v_and_b32_e32 v30, 0xffff0000, v30
	v_or_b32_sdwa v31, v31, v33 dst_sel:DWORD dst_unused:UNUSED_PAD src0_sel:DWORD src1_sel:WORD_1
	v_or_b32_sdwa v30, v30, v32 dst_sel:DWORD dst_unused:UNUSED_PAD src0_sel:DWORD src1_sel:WORD_1
	global_store_dwordx4 v[50:51], v[28:31], off
	global_store_dwordx4 v[48:49], v[24:27], off
	global_store_dwordx4 v[46:47], v[20:23], off
	global_store_dwordx4 v[44:45], v[16:19], off
	global_store_dwordx4 v[42:43], v[12:15], off
	global_store_dwordx4 v[40:41], v[8:11], off
	global_store_dwordx4 v[38:39], v[4:7], off
	global_store_dwordx4 v[36:37], v[0:3], off
	s_barrier

; __device__ __forceinline__ unsigned pack2(float a, float b) { return (unsigned)f2bf(a) | ((unsigned)f2bf(b) << 16); }
; __device__ __forceinline__ float bflo(unsigned w) { return __uint_as_float(w << 16); }
; __device__ __forceinline__ float bfhi(unsigned w) { return __uint_as_float(w & 0xffff0000u); }
; __device__ __forceinline__ float silu_f(float g) { return g / (1.f + __expf(-g)); }
; template <int DH, int MODE>
; __device__ void attn_item(const Params& p, int layer, int b, int blk, int head, char* smem) {
;     ...
;   if (MODE == 0 && half == 0) linv_s[row] = 1.f / l_run;
;   __syncthreads();
;   {
;     constexpr int OST = DH + 4;
;     constexpr int CPR = DH / 8;
;     constexpr int NCH = 128 * CPR / 256;
;     float* Of = reinterpret_cast<float*>(smem);
;     uint4 gt[NCH];
; #pragma unroll
;     for (int i = 0; i < NCH; ++i) {
;       int q = tid + 256 * i, r = q / CPR, c = (q % CPR) * 8;
;       gt[i] = *reinterpret_cast<const uint4*>(P + (tq0 + r) * NP + gcol + c);
;     }
;     float lis[2][4];
; #pragma unroll
;     for (int m = 0; m < 2; ++m)
; #pragma unroll
;       for (int j = 0; j < 4; ++j) lis[m][j] = (MODE == 0) ? linv_s[wid * 32 + m * 16 + fq * 4 + j] : 1.f;
;     if (MODE == 0) __syncthreads();
; #pragma unroll
;     for (int m = 0; m < 2; ++m)
; #pragma unroll
;       for (int j = 0; j < 4; ++j) {
;         int r = wid * 32 + m * 16 + fq * 4 + j;
; #pragma unroll
;         for (int n = 0; n < NDT; ++n) Of[r * OST + n * 16 + fr] = o[m][n][j] * lis[m][j];
;       }
;     __syncthreads();
; #pragma unroll
;     for (int i = 0; i < NCH; ++i) {
;       int q = tid + 256 * i, r = q / CPR, c = (q % CPR) * 8;
;       float4 m0 = *reinterpret_cast<const float4*>(Of + r * OST + c);
;       float4 m1 = *reinterpret_cast<const float4*>(Of + r * OST + c + 4);
;       float mm[8] = {m0.x, m0.y, m0.z, m0.w, m1.x, m1.y, m1.z, m1.w};
;       unsigned gw[4] = {gt[i].x, gt[i].y, gt[i].z, gt[i].w};
;       unsigned ow[4];
; #pragma unroll
;       for (int e = 0; e < 4; ++e)
;         ow[e] = pack2(mm[2 * e] * silu_f(bflo(gw[e])), mm[2 * e + 1] * silu_f(bfhi(gw[e])));
.LBB0_1153:
	v_readfirstlane_b32 s10, v85
	s_and_saveexec_b64 s[8:9], s[6:7]
	s_cbranch_execz .LBB0_1155
	v_rcp_f32_e32 v32, v88
	s_nop 0
	v_lshlrev_b32_e32 v33, 2, v74
	ds_write_b32 v33, v32 offset:8704
.LBB0_1155:
	s_or_b64 exec, exec, s[8:9]
	v_lshl_add_u64 v[44:45], v[66:67], 0, s[16:17]
	v_mov_b64_e32 v[46:47], s[42:43]
	v_mad_u64_u32 v[32:33], s[8:9], v44, s39, v[46:47]
	v_mad_i32_i24 v33, v45, s39, v33
	v_lshl_add_u64 v[36:37], v[32:33], 0, v[70:71]
	v_add_u32_e32 v32, 0x100, v81
	v_ashrrev_i32_e32 v33, 31, v32
	v_lshrrev_b32_e32 v33, 29, v33
	v_add_u32_e32 v33, v32, v33
	v_ashrrev_i32_e32 v86, 3, v33
	v_and_b32_e32 v33, -8, v33
	v_sub_u32_e32 v85, v32, v33
	v_lshlrev_b32_e32 v32, 3, v85
	v_ashrrev_i32_e32 v33, 31, v32
	s_waitcnt vmcnt(2)
	v_add_u32_e32 v48, 0x200, v81
	v_lshlrev_b64 v[90:91], 1, v[32:33]
	v_ashrrev_i32_e32 v32, 31, v48
	v_lshrrev_b32_e32 v32, 29, v32
	v_add_u32_e32 v32, v48, v32
	v_ashrrev_i32_e32 v92, 3, v32
	v_and_b32_e32 v49, -8, v32
	v_add_u32_e32 v32, 0x300, v81
	v_ashrrev_i32_e32 v33, 31, v32
	v_lshrrev_b32_e32 v33, 29, v33
	v_ashrrev_i32_e32 v87, 31, v86
	v_add_u32_e32 v33, v32, v33
	v_lshl_add_u64 v[88:89], v[86:87], 0, s[16:17]
	v_ashrrev_i32_e32 v94, 3, v33
	v_and_b32_e32 v33, -8, v33
	v_mad_u64_u32 v[34:35], s[8:9], v88, s39, v[46:47]
	v_sub_u32_e32 v87, v32, v33
	v_ashrrev_i32_e32 v95, 31, v94
	v_mad_i32_i24 v35, v89, s39, v35
	v_lshlrev_b32_e32 v32, 3, v87
	v_lshl_add_u64 v[40:41], v[94:95], 0, s[16:17]
	v_lshl_add_u64 v[38:39], v[34:35], 0, v[90:91]
	v_mad_u64_u32 v[34:35], s[8:9], v40, s39, v[46:47]
	v_ashrrev_i32_e32 v33, 31, v32
	v_mad_i32_i24 v35, v41, s39, v35
	v_lshlrev_b64 v[42:43], 1, v[32:33]
	v_lshl_add_u64 v[32:33], v[34:35], 0, v[42:43]
	v_add_co_u32_e32 v32, vcc, s65, v32
	s_waitcnt lgkmcnt(0)
	s_nop 0
	v_addc_co_u32_e32 v33, vcc, 0, v33, vcc
	s_barrier
	global_load_dwordx4 v[32:35], v[32:33], off offset:512
	v_sub_u32_e32 v95, v48, v49
	v_ashrrev_i32_e32 v93, 31, v92
	v_lshlrev_b32_e32 v48, 3, v95
	v_lshl_add_u64 v[96:97], v[92:93], 0, s[16:17]
	v_mad_u64_u32 v[46:47], s[8:9], v96, s39, v[46:47]
	v_ashrrev_i32_e32 v49, 31, v48
	v_mad_i32_i24 v47, v97, s39, v47
	v_lshlrev_b64 v[98:99], 1, v[48:49]
	v_lshl_add_u64 v[100:101], v[46:47], 0, v[98:99]
	v_lshl_or_b32 v46, v75, 7, v128
	ds_read_b128 v[60:63], v46 offset:8704
	ds_read_b128 v[80:83], v46 offset:8768
	s_ashr_i32 s7, s10, 31
	s_add_u32 s6, s28, s10
	s_addc_u32 s7, s29, s7
	s_lshl_b32 s8, s76, 1
	s_add_u32 s6, s6, s8
	v_lshl_or_b32 v46, v84, 2, v64
	s_waitcnt lgkmcnt(0)
	v_mul_f32_e32 v69, v0, v80
	s_addc_u32 s7, s7, 0
	v_mul_lo_u32 v0, v66, s67
	v_mul_lo_u32 v46, v46, s67
	v_mul_f32_e32 v75, v1, v81
	v_lshl_add_u32 v66, v68, 2, v0
	v_mov_b64_e32 v[0:1], s[6:7]
	v_lshl_add_u32 v47, v73, 2, v46
	v_mul_f32_e32 v48, v16, v60
	v_mul_f32_e32 v49, v28, v60
	v_mul_f32_e32 v50, v24, v60
	v_mul_f32_e32 v51, v20, v60
	s_waitcnt vmcnt(1)
	v_mul_f32_e32 v52, v17, v61
	v_mul_f32_e32 v53, v29, v61
	v_mul_f32_e32 v54, v25, v61
	v_mul_f32_e32 v55, v21, v61
	v_mul_f32_e32 v56, v18, v62
	v_mul_f32_e32 v57, v30, v62
	v_mul_f32_e32 v58, v26, v62
	v_mul_f32_e32 v59, v22, v62
	v_mul_f32_e32 v60, v19, v63
	v_mul_f32_e32 v61, v31, v63
	v_mul_f32_e32 v62, v27, v63
	v_mul_f32_e32 v64, v23, v63
	v_mul_f32_e32 v63, v12, v80
	v_mul_f32_e32 v65, v8, v80
	v_mul_f32_e32 v67, v4, v80
	v_mul_f32_e32 v72, v13, v81
	v_mul_f32_e32 v73, v9, v81
	v_mul_f32_e32 v74, v5, v81
	v_mul_f32_e32 v76, v14, v82
	v_mul_f32_e32 v77, v10, v82
	v_mul_f32_e32 v78, v6, v82
	v_mul_f32_e32 v80, v2, v82
	v_mul_f32_e32 v79, v15, v83
	v_mul_f32_e32 v81, v11, v83
	v_mul_f32_e32 v82, v7, v83
	v_mul_f32_e32 v83, v3, v83
	v_mad_u64_u32 v[2:3], s[6:7], v44, s63, v[0:1]
	v_mad_i32_i24 v3, v45, s63, v3
	v_lshl_add_u64 v[12:13], v[2:3], 0, v[70:71]
	v_mul_lo_u32 v2, v86, s67
	v_lshl_add_u32 v46, v85, 5, v2
	v_mad_u64_u32 v[2:3], s[6:7], v88, s63, v[0:1]
	v_mad_i32_i24 v3, v89, s63, v3
	v_mad_u64_u32 v[4:5], s[6:7], v40, s63, v[0:1]
	v_lshl_add_u64 v[10:11], v[2:3], 0, v[90:91]
	v_mul_lo_u32 v2, v92, s67
	v_mad_i32_i24 v5, v41, s63, v5
	v_lshl_add_u32 v45, v95, 5, v2
	v_mad_u64_u32 v[2:3], s[6:7], v96, s63, v[0:1]
	v_lshl_add_u64 v[14:15], v[4:5], 0, v[42:43]
	v_mad_i32_i24 v3, v97, s63, v3
	v_add_co_u32_e32 v0, vcc, s65, v100
	v_lshl_add_u64 v[8:9], v[2:3], 0, v[98:99]
	v_mul_lo_u32 v2, v94, s67
	s_waitcnt vmcnt(0)
	v_lshlrev_b32_e32 v16, 16, v33
	v_lshlrev_b32_e32 v18, 16, v32
	v_mul_f32_e32 v6, 0xbfb8aa3b, v18
	v_mul_f32_e32 v7, 0xbfb8aa3b, v16
	v_exp_f32_e32 v6, v6
	v_exp_f32_e32 v7, v7
	v_addc_co_u32_e32 v1, vcc, 0, v101, vcc
	v_lshl_add_u32 v44, v87, 5, v2
	v_pk_add_f32 v[4:5], v[6:7], 1.0 op_sel_hi:[1,0]
	global_load_dwordx4 v[0:3], v[0:1], off offset:512
	v_and_b32_e32 v19, 0xffff0000, v33
	v_and_b32_e32 v20, 0xffff0000, v32
	v_mul_f32_e32 v6, 0xbfb8aa3b, v20
	v_rcp_f32_e32 v17, v5
	s_nop 0
	v_mul_f32_e32 v17, v16, v17
	v_mul_f32_e32 v7, 0xbfb8aa3b, v19
	v_exp_f32_e32 v6, v6
	v_exp_f32_e32 v7, v7
	s_nop 0
	v_pk_add_f32 v[6:7], v[6:7], 1.0 op_sel_hi:[1,0]
	v_rcp_f32_e32 v16, v4
	s_nop 0
	v_mul_f32_e32 v16, v18, v16
	v_lshlrev_b32_e32 v23, 16, v34
	v_rcp_f32_e32 v4, v7
	s_nop 0
	v_mul_f32_e32 v19, v19, v4
	v_lshlrev_b32_e32 v22, 16, v35
	v_mul_f32_e32 v4, 0xbfb8aa3b, v23
	v_mul_f32_e32 v5, 0xbfb8aa3b, v22
	v_exp_f32_e32 v4, v4
	v_exp_f32_e32 v5, v5
	v_rcp_f32_e32 v18, v6
	s_nop 0
	v_mul_f32_e32 v18, v20, v18
	v_and_b32_e32 v24, 0xffff0000, v35
	v_pk_add_f32 v[4:5], v[4:5], 1.0 op_sel_hi:[1,0]
	v_and_b32_e32 v25, 0xffff0000, v34
	v_mul_f32_e32 v6, 0xbfb8aa3b, v25
	v_exp_f32_e32 v6, v6
	v_rcp_f32_e32 v21, v5
	s_nop 0
	v_mul_f32_e32 v21, v22, v21
	v_mul_f32_e32 v7, 0xbfb8aa3b, v24
	v_exp_f32_e32 v7, v7
	s_nop 0
	v_pk_add_f32 v[6:7], v[6:7], 1.0 op_sel_hi:[1,0]
	v_rcp_f32_e32 v20, v4
	s_nop 0
	v_mul_f32_e32 v20, v23, v20
	v_rcp_f32_e32 v23, v7
	s_nop 0
	v_mul_f32_e32 v23, v24, v23
	s_waitcnt vmcnt(0)
; __device__ __forceinline__ unsigned pack2(float a, float b) { return (unsigned)f2bf(a) | ((unsigned)f2bf(b) << 16); }
; __device__ __forceinline__ float bflo(unsigned w) { return __uint_as_float(w << 16); }
; __device__ __forceinline__ float bfhi(unsigned w) { return __uint_as_float(w & 0xffff0000u); }
; __device__ __forceinline__ float silu_f(float g) { return g / (1.f + __expf(-g)); }
; template <int DH, int MODE>
; __device__ void attn_item(const Params& p, int layer, int b, int blk, int head, char* smem) {
;     ...
;     for (int m = 0; m < 2; ++m)
; #pragma unroll
;       for (int j = 0; j < 4; ++j) {
;         int r = wid * 32 + m * 16 + fq * 4 + j;
; #pragma unroll
;         for (int n = 0; n < NDT; ++n) Of[r * OST + n * 16 + fr] = o[m][n][j] * lis[m][j];
;       }
;     __syncthreads();
; #pragma unroll
;     for (int i = 0; i < NCH; ++i) {
;       int q = tid + 256 * i, r = q / CPR, c = (q % CPR) * 8;
;       float4 m0 = *reinterpret_cast<const float4*>(Of + r * OST + c);
;       float4 m1 = *reinterpret_cast<const float4*>(Of + r * OST + c + 4);
;       float mm[8] = {m0.x, m0.y, m0.z, m0.w, m1.x, m1.y, m1.z, m1.w};
;       unsigned gw[4] = {gt[i].x, gt[i].y, gt[i].z, gt[i].w};
;       unsigned ow[4];
; #pragma unroll
;       for (int e = 0; e < 4; ++e)
;         ow[e] = pack2(mm[2 * e] * silu_f(bflo(gw[e])), mm[2 * e + 1] * silu_f(bfhi(gw[e])));
	v_lshlrev_b32_e32 v24, 16, v1
	v_lshlrev_b32_e32 v26, 16, v0
	v_mul_f32_e32 v4, 0xbfb8aa3b, v26
	v_mul_f32_e32 v5, 0xbfb8aa3b, v24
	v_exp_f32_e32 v4, v4
	v_exp_f32_e32 v5, v5
	v_and_b32_e32 v27, 0xffff0000, v1
	v_rcp_f32_e32 v22, v6
	s_nop 0
	v_mul_f32_e32 v22, v25, v22
	v_pk_add_f32 v[4:5], v[4:5], 1.0 op_sel_hi:[1,0]
	v_and_b32_e32 v28, 0xffff0000, v0
	v_mul_f32_e32 v0, 0xbfb8aa3b, v28
	v_exp_f32_e32 v6, v0
	v_lshlrev_b32_e32 v32, 16, v3
	v_mul_f32_e32 v7, 0xbfb8aa3b, v27
	v_rcp_f32_e32 v1, v5
	s_nop 0
	v_mul_f32_e32 v1, v24, v1
	v_exp_f32_e32 v7, v7
	s_nop 0
	v_pk_add_f32 v[24:25], v[6:7], 1.0 op_sel_hi:[1,0]
	v_rcp_f32_e32 v0, v4
	s_nop 0
	v_mul_f32_e32 v0, v26, v0
	v_lshlrev_b32_e32 v33, 16, v2
	v_rcp_f32_e32 v25, v25
	s_nop 0
	v_mul_f32_e32 v25, v27, v25
	v_add_co_u32_e64 v4, s[6:7], s65, v38
	s_nop 0
	s_nop 0
	v_addc_co_u32_e64 v5, s[6:7], 0, v39, s[6:7]
	global_load_dwordx4 v[4:7], v[4:5], off offset:512
	v_mul_f32_e32 v26, 0xbfb8aa3b, v33
	v_mul_f32_e32 v27, 0xbfb8aa3b, v32
	v_exp_f32_e32 v26, v26
	v_exp_f32_e32 v27, v27
	v_and_b32_e32 v30, 0xffff0000, v3
	v_rcp_f32_e32 v24, v24
	s_nop 0
	v_mul_f32_e32 v24, v28, v24
	v_pk_add_f32 v[26:27], v[26:27], 1.0 op_sel_hi:[1,0]
	v_and_b32_e32 v38, 0xffff0000, v2
	v_mul_f32_e32 v2, 0xbfb8aa3b, v38
	v_exp_f32_e32 v28, v2
	v_mul_f32_e32 v29, 0xbfb8aa3b, v30
	v_exp_f32_e32 v29, v29
	v_rcp_f32_e32 v3, v27
	s_nop 0
	v_mul_f32_e32 v3, v32, v3
	v_pk_add_f32 v[28:29], v[28:29], 1.0 op_sel_hi:[1,0]
	v_rcp_f32_e32 v2, v26
	s_nop 0
	v_mul_f32_e32 v2, v33, v2
	v_rcp_f32_e32 v27, v29
	s_nop 0
	v_mul_f32_e32 v27, v30, v27
	v_add_co_u32_e64 v30, s[6:7], s65, v36
	s_nop 0
	s_nop 0
	v_addc_co_u32_e64 v31, s[6:7], 0, v37, s[6:7]
	global_load_dwordx4 v[32:35], v[30:31], off offset:512
	v_rcp_f32_e32 v26, v28
	s_nop 0
	v_mul_f32_e32 v26, v38, v26
	s_barrier
	s_waitcnt vmcnt(1)
	v_lshlrev_b32_e32 v36, 16, v5
	v_lshlrev_b32_e32 v37, 16, v4
	v_mul_f32_e32 v30, 0xbfb8aa3b, v37
	v_mul_f32_e32 v31, 0xbfb8aa3b, v36
	v_exp_f32_e32 v30, v30
	v_exp_f32_e32 v31, v31
	v_and_b32_e32 v38, 0xffff0000, v5
	v_and_b32_e32 v39, 0xffff0000, v4
	v_mul_f32_e32 v4, 0xbfb8aa3b, v39
	v_pk_add_f32 v[28:29], v[30:31], 1.0 op_sel_hi:[1,0]
	v_exp_f32_e32 v30, v4
	ds_write2_b32 v47, v48, v49 offset1:16
	ds_write2_b32 v47, v50, v51 offset0:32 offset1:48
	ds_write2_b32 v47, v52, v53 offset0:68 offset1:84
	ds_write2_b32 v47, v54, v55 offset0:100 offset1:116
	ds_write2_b32 v47, v56, v57 offset0:136 offset1:152
	ds_write2_b32 v47, v58, v59 offset0:168 offset1:184
	ds_write2_b32 v47, v60, v61 offset0:204 offset1:220
	ds_write2_b32 v47, v62, v64 offset0:236 offset1:252
	v_mul_f32_e32 v31, 0xbfb8aa3b, v38
	v_exp_f32_e32 v31, v31
	v_rcp_f32_e32 v5, v29
	s_nop 0
	v_mul_f32_e32 v5, v36, v5
	v_pk_add_f32 v[30:31], v[30:31], 1.0 op_sel_hi:[1,0]
	v_rcp_f32_e32 v4, v28
	s_nop 0
	v_mul_f32_e32 v4, v37, v4
	v_rcp_f32_e32 v29, v31
	s_nop 0
	v_mul_f32_e32 v29, v38, v29
	v_lshlrev_b32_e32 v38, 16, v7
	v_lshlrev_b32_e32 v40, 16, v6
	v_mul_f32_e32 v36, 0xbfb8aa3b, v40
	v_mul_f32_e32 v37, 0xbfb8aa3b, v38
	v_exp_f32_e32 v36, v36
	v_exp_f32_e32 v37, v37
	v_rcp_f32_e32 v28, v30
	s_nop 0
	v_mul_f32_e32 v28, v39, v28
	v_and_b32_e32 v39, 0xffff0000, v7
	v_pk_add_f32 v[30:31], v[36:37], 1.0 op_sel_hi:[1,0]
	v_and_b32_e32 v41, 0xffff0000, v6
	v_mul_f32_e32 v6, 0xbfb8aa3b, v41
	v_exp_f32_e32 v36, v6
	v_mul_f32_e32 v37, 0xbfb8aa3b, v39
	v_exp_f32_e32 v37, v37
	v_rcp_f32_e32 v7, v31
	s_nop 0
	v_mul_f32_e32 v7, v38, v7
	v_pk_add_f32 v[36:37], v[36:37], 1.0 op_sel_hi:[1,0]
	v_rcp_f32_e32 v6, v30
	s_nop 0
	v_mul_f32_e32 v6, v40, v6
	v_rcp_f32_e32 v31, v37
	s_nop 0
	v_mul_f32_e32 v31, v39, v31
	s_waitcnt vmcnt(0)
	v_lshlrev_b32_e32 v42, 16, v33
	v_lshlrev_b32_e32 v43, 16, v32
	v_mul_f32_e32 v38, 0xbfb8aa3b, v43
	v_mul_f32_e32 v39, 0xbfb8aa3b, v42
	v_exp_f32_e32 v38, v38
	v_exp_f32_e32 v39, v39
	v_rcp_f32_e32 v30, v36
	s_nop 0
	v_mul_f32_e32 v30, v41, v30
	v_and_b32_e32 v68, 0xffff0000, v33
	v_pk_add_f32 v[36:37], v[38:39], 1.0 op_sel_hi:[1,0]
	v_and_b32_e32 v39, 0xffff0000, v32
	v_mul_f32_e32 v32, 0xbfb8aa3b, v39
	v_exp_f32_e32 v32, v32
	v_rcp_f32_e32 v41, v37
	s_nop 0
	v_mul_f32_e32 v41, v42, v41
	v_mul_f32_e32 v33, 0xbfb8aa3b, v68
	v_exp_f32_e32 v33, v33
	s_nop 0
	v_pk_add_f32 v[32:33], v[32:33], 1.0 op_sel_hi:[1,0]
	v_rcp_f32_e32 v40, v36
	s_nop 0
	v_mul_f32_e32 v40, v43, v40
	v_lshlrev_b32_e32 v70, 16, v34
	v_rcp_f32_e32 v43, v33
	s_nop 0
	v_mul_f32_e32 v43, v68, v43
	v_lshlrev_b32_e32 v38, 16, v35
	v_mul_f32_e32 v36, 0xbfb8aa3b, v70
	v_mul_f32_e32 v37, 0xbfb8aa3b, v38
	v_exp_f32_e32 v36, v36
	v_exp_f32_e32 v37, v37
	v_rcp_f32_e32 v42, v32
	s_nop 0
	v_mul_f32_e32 v42, v39, v42
	v_and_b32_e32 v39, 0xffff0000, v35
	v_pk_add_f32 v[32:33], v[36:37], 1.0 op_sel_hi:[1,0]
	v_and_b32_e32 v68, 0xffff0000, v34
	v_mul_f32_e32 v34, 0xbfb8aa3b, v68
	v_exp_f32_e32 v34, v34
	v_rcp_f32_e32 v71, v33
	s_nop 0
	v_mul_f32_e32 v71, v38, v71
	v_mul_f32_e32 v35, 0xbfb8aa3b, v39
	v_exp_f32_e32 v35, v35
	s_nop 0
	v_pk_add_f32 v[36:37], v[34:35], 1.0 op_sel_hi:[1,0]
	v_rcp_f32_e32 v33, v32
	s_nop 0
	v_mul_f32_e32 v70, v70, v33
	v_rcp_f32_e32 v85, v37
	s_nop 0
	v_mul_f32_e32 v85, v39, v85
	v_add_u32_e32 v32, 0x1000, v47
	ds_write2_b32 v32, v63, v65 offset0:64 offset1:80
	ds_write2_b32 v32, v67, v69 offset0:96 offset1:112
	ds_write2_b32 v32, v72, v73 offset0:132 offset1:148
	ds_write2_b32 v32, v74, v75 offset0:164 offset1:180
	ds_write2_b32 v32, v76, v77 offset0:200 offset1:216
	ds_write2_b32 v32, v78, v80 offset0:232 offset1:248
	v_add_u32_e32 v32, 0x1400, v47
	ds_write2_b32 v32, v79, v81 offset0:12 offset1:28
	ds_write2_b32 v32, v82, v83 offset0:44 offset1:60
	s_waitcnt lgkmcnt(0)
	s_barrier
; __device__ __forceinline__ unsigned pack2(float a, float b) { return (unsigned)f2bf(a) | ((unsigned)f2bf(b) << 16); }
; __device__ __forceinline__ float bflo(unsigned w) { return __uint_as_float(w << 16); }
; __device__ __forceinline__ float bfhi(unsigned w) { return __uint_as_float(w & 0xffff0000u); }
; __device__ __forceinline__ float silu_f(float g) { return g / (1.f + __expf(-g)); }
; template <int DH, int MODE>
; __device__ void attn_item(const Params& p, int layer, int b, int blk, int head, char* smem) {
;     ...
; #pragma unroll
;     for (int i = 0; i < NCH; ++i) {
;       int q = tid + 256 * i, r = q / CPR, c = (q % CPR) * 8;
;       float4 m0 = *reinterpret_cast<const float4*>(Of + r * OST + c);
;       float4 m1 = *reinterpret_cast<const float4*>(Of + r * OST + c + 4);
;       float mm[8] = {m0.x, m0.y, m0.z, m0.w, m1.x, m1.y, m1.z, m1.w};
;       unsigned gw[4] = {gt[i].x, gt[i].y, gt[i].z, gt[i].w};
;       unsigned ow[4];
; #pragma unroll
;       for (int e = 0; e < 4; ++e)
;         ow[e] = pack2(mm[2 * e] * silu_f(bflo(gw[e])), mm[2 * e + 1] * silu_f(bfhi(gw[e])));
;       *reinterpret_cast<uint4*>(Y + (tq0 + r) * YW + ycol + c) = make_uint4(ow[0], ow[1], ow[2], ow[3]);
;     }
	ds_read_b128 v[32:35], v66
	v_rcp_f32_e32 v84, v36
	s_nop 0
	v_mul_f32_e32 v84, v68, v84
	ds_read_b128 v[36:39], v66 offset:16
	v_add_co_u32_e32 v12, vcc, s70, v12
	s_waitcnt lgkmcnt(1)
	v_mov_b32_e32 v48, v32
	v_mov_b32_e32 v49, v34
	v_pk_mul_f32 v[40:41], v[40:41], v[48:49]
	v_mov_b32_e32 v34, v33
	v_pk_mul_f32 v[32:33], v[42:43], v[34:35]
	v_and_b32_sdwa v34, v41, v155 dst_sel:DWORD dst_unused:UNUSED_PAD src0_sel:WORD_1 src1_sel:DWORD
	v_and_b32_sdwa v35, v40, v155 dst_sel:DWORD dst_unused:UNUSED_PAD src0_sel:WORD_1 src1_sel:DWORD
	v_add3_u32 v35, v40, v35, s54
	v_add3_u32 v34, v41, v34, s54
	v_and_b32_sdwa v40, v33, v155 dst_sel:DWORD dst_unused:UNUSED_PAD src0_sel:WORD_1 src1_sel:DWORD
	v_and_b32_sdwa v41, v32, v155 dst_sel:DWORD dst_unused:UNUSED_PAD src0_sel:WORD_1 src1_sel:DWORD
	v_add3_u32 v33, v33, v40, s54
	v_add3_u32 v32, v32, v41, s54
	v_and_b32_e32 v33, 0xffff0000, v33
	v_and_b32_e32 v32, 0xffff0000, v32
	v_or_b32_sdwa v33, v33, v34 dst_sel:DWORD dst_unused:UNUSED_PAD src0_sel:DWORD src1_sel:WORD_1
	v_or_b32_sdwa v32, v32, v35 dst_sel:DWORD dst_unused:UNUSED_PAD src0_sel:DWORD src1_sel:WORD_1
	s_waitcnt lgkmcnt(0)
	v_mov_b32_e32 v34, v36
	v_mov_b32_e32 v35, v38
	v_pk_mul_f32 v[34:35], v[70:71], v[34:35]
	v_mov_b32_e32 v38, v37
	v_pk_mul_f32 v[36:37], v[84:85], v[38:39]
	v_and_b32_sdwa v38, v35, v155 dst_sel:DWORD dst_unused:UNUSED_PAD src0_sel:WORD_1 src1_sel:DWORD
	v_and_b32_sdwa v39, v34, v155 dst_sel:DWORD dst_unused:UNUSED_PAD src0_sel:WORD_1 src1_sel:DWORD
	v_add3_u32 v34, v34, v39, s54
	v_add3_u32 v35, v35, v38, s54
	v_and_b32_sdwa v38, v37, v155 dst_sel:DWORD dst_unused:UNUSED_PAD src0_sel:WORD_1 src1_sel:DWORD
	v_and_b32_sdwa v39, v36, v155 dst_sel:DWORD dst_unused:UNUSED_PAD src0_sel:WORD_1 src1_sel:DWORD
	v_add3_u32 v37, v37, v38, s54
	v_add3_u32 v36, v36, v39, s54
	v_and_b32_e32 v37, 0xffff0000, v37
	v_and_b32_e32 v36, 0xffff0000, v36
	v_or_b32_sdwa v35, v37, v35 dst_sel:DWORD dst_unused:UNUSED_PAD src0_sel:DWORD src1_sel:WORD_1
	v_or_b32_sdwa v34, v36, v34 dst_sel:DWORD dst_unused:UNUSED_PAD src0_sel:DWORD src1_sel:WORD_1
	ds_read_b128 v[36:39], v46
	v_addc_co_u32_e32 v13, vcc, 0, v13, vcc
	global_store_dwordx4 v[12:13], v[32:35], off offset:1024
	ds_read_b128 v[32:35], v46 offset:16
	s_waitcnt lgkmcnt(1)
	v_mov_b32_e32 v12, v36
	v_mov_b32_e32 v13, v38
	v_pk_mul_f32 v[4:5], v[4:5], v[12:13]
	v_mov_b32_e32 v38, v37
	v_pk_mul_f32 v[12:13], v[28:29], v[38:39]
	v_and_b32_sdwa v28, v5, v155 dst_sel:DWORD dst_unused:UNUSED_PAD src0_sel:WORD_1 src1_sel:DWORD
	v_and_b32_sdwa v29, v4, v155 dst_sel:DWORD dst_unused:UNUSED_PAD src0_sel:WORD_1 src1_sel:DWORD
	v_add3_u32 v4, v4, v29, s54
	v_add3_u32 v5, v5, v28, s54
	v_and_b32_sdwa v28, v13, v155 dst_sel:DWORD dst_unused:UNUSED_PAD src0_sel:WORD_1 src1_sel:DWORD
	v_and_b32_sdwa v29, v12, v155 dst_sel:DWORD dst_unused:UNUSED_PAD src0_sel:WORD_1 src1_sel:DWORD
	v_add3_u32 v13, v13, v28, s54
	v_add3_u32 v12, v12, v29, s54
	v_and_b32_e32 v13, 0xffff0000, v13
	v_and_b32_e32 v12, 0xffff0000, v12
	v_or_b32_sdwa v5, v13, v5 dst_sel:DWORD dst_unused:UNUSED_PAD src0_sel:DWORD src1_sel:WORD_1
	v_or_b32_sdwa v4, v12, v4 dst_sel:DWORD dst_unused:UNUSED_PAD src0_sel:DWORD src1_sel:WORD_1
	s_waitcnt lgkmcnt(0)
	v_mov_b32_e32 v12, v32
	v_mov_b32_e32 v13, v34
	v_pk_mul_f32 v[6:7], v[6:7], v[12:13]
	v_mov_b32_e32 v34, v33
	v_pk_mul_f32 v[12:13], v[30:31], v[34:35]
	v_and_b32_sdwa v28, v7, v155 dst_sel:DWORD dst_unused:UNUSED_PAD src0_sel:WORD_1 src1_sel:DWORD
	v_and_b32_sdwa v29, v6, v155 dst_sel:DWORD dst_unused:UNUSED_PAD src0_sel:WORD_1 src1_sel:DWORD
	v_add3_u32 v6, v6, v29, s54
	v_add3_u32 v7, v7, v28, s54
	v_and_b32_sdwa v28, v13, v155 dst_sel:DWORD dst_unused:UNUSED_PAD src0_sel:WORD_1 src1_sel:DWORD
	v_and_b32_sdwa v29, v12, v155 dst_sel:DWORD dst_unused:UNUSED_PAD src0_sel:WORD_1 src1_sel:DWORD
	v_add3_u32 v13, v13, v28, s54
	v_add3_u32 v12, v12, v29, s54
	ds_read_b128 v[28:31], v45
	v_and_b32_e32 v13, 0xffff0000, v13
	v_and_b32_e32 v12, 0xffff0000, v12
	v_add_co_u32_e32 v10, vcc, s70, v10
	v_or_b32_sdwa v7, v13, v7 dst_sel:DWORD dst_unused:UNUSED_PAD src0_sel:DWORD src1_sel:WORD_1
	v_or_b32_sdwa v6, v12, v6 dst_sel:DWORD dst_unused:UNUSED_PAD src0_sel:DWORD src1_sel:WORD_1
	v_addc_co_u32_e32 v11, vcc, 0, v11, vcc
	global_store_dwordx4 v[10:11], v[4:7], off offset:1024
	s_waitcnt lgkmcnt(0)
; __device__ __forceinline__ unsigned pack2(float a, float b) { return (unsigned)f2bf(a) | ((unsigned)f2bf(b) << 16); }
; __device__ __forceinline__ float bflo(unsigned w) { return __uint_as_float(w << 16); }
; __device__ __forceinline__ float bfhi(unsigned w) { return __uint_as_float(w & 0xffff0000u); }
; __device__ __forceinline__ float silu_f(float g) { return g / (1.f + __expf(-g)); }
; template <int DH, int MODE>
; __device__ void attn_item(const Params& p, int layer, int b, int blk, int head, char* smem) {
;     ...
; #pragma unroll
;     for (int i = 0; i < NCH; ++i) {
;       int q = tid + 256 * i, r = q / CPR, c = (q % CPR) * 8;
;       float4 m0 = *reinterpret_cast<const float4*>(Of + r * OST + c);
;       float4 m1 = *reinterpret_cast<const float4*>(Of + r * OST + c + 4);
;       float mm[8] = {m0.x, m0.y, m0.z, m0.w, m1.x, m1.y, m1.z, m1.w};
;       unsigned gw[4] = {gt[i].x, gt[i].y, gt[i].z, gt[i].w};
;       unsigned ow[4];
; #pragma unroll
;       for (int e = 0; e < 4; ++e)
;         ow[e] = pack2(mm[2 * e] * silu_f(bflo(gw[e])), mm[2 * e + 1] * silu_f(bfhi(gw[e])));
;       *reinterpret_cast<uint4*>(Y + (tq0 + r) * YW + ycol + c) = make_uint4(ow[0], ow[1], ow[2], ow[3]);
;     }
;   }
;   __syncthreads();
	v_mov_b32_e32 v10, v28
	v_mov_b32_e32 v11, v30
	ds_read_b128 v[4:7], v45 offset:16
	v_pk_mul_f32 v[0:1], v[0:1], v[10:11]
	v_mov_b32_e32 v30, v29
	v_pk_mul_f32 v[10:11], v[24:25], v[30:31]
	v_and_b32_sdwa v12, v1, v155 dst_sel:DWORD dst_unused:UNUSED_PAD src0_sel:WORD_1 src1_sel:DWORD
	v_and_b32_sdwa v13, v0, v155 dst_sel:DWORD dst_unused:UNUSED_PAD src0_sel:WORD_1 src1_sel:DWORD
	v_add3_u32 v0, v0, v13, s54
	v_add3_u32 v1, v1, v12, s54
	v_and_b32_sdwa v12, v11, v155 dst_sel:DWORD dst_unused:UNUSED_PAD src0_sel:WORD_1 src1_sel:DWORD
	v_and_b32_sdwa v13, v10, v155 dst_sel:DWORD dst_unused:UNUSED_PAD src0_sel:WORD_1 src1_sel:DWORD
	v_add3_u32 v11, v11, v12, s54
	v_add3_u32 v10, v10, v13, s54
	v_and_b32_e32 v11, 0xffff0000, v11
	v_and_b32_e32 v10, 0xffff0000, v10
	v_or_b32_sdwa v1, v11, v1 dst_sel:DWORD dst_unused:UNUSED_PAD src0_sel:DWORD src1_sel:WORD_1
	v_or_b32_sdwa v0, v10, v0 dst_sel:DWORD dst_unused:UNUSED_PAD src0_sel:DWORD src1_sel:WORD_1
	s_waitcnt lgkmcnt(0)
	v_mov_b32_e32 v10, v4
	v_mov_b32_e32 v11, v6
	v_pk_mul_f32 v[2:3], v[2:3], v[10:11]
	v_mov_b32_e32 v6, v5
	v_pk_mul_f32 v[4:5], v[26:27], v[6:7]
	v_and_b32_sdwa v6, v3, v155 dst_sel:DWORD dst_unused:UNUSED_PAD src0_sel:WORD_1 src1_sel:DWORD
	v_and_b32_sdwa v7, v2, v155 dst_sel:DWORD dst_unused:UNUSED_PAD src0_sel:WORD_1 src1_sel:DWORD
	v_add3_u32 v2, v2, v7, s54
	v_add3_u32 v3, v3, v6, s54
	v_and_b32_sdwa v6, v5, v155 dst_sel:DWORD dst_unused:UNUSED_PAD src0_sel:WORD_1 src1_sel:DWORD
	v_and_b32_sdwa v7, v4, v155 dst_sel:DWORD dst_unused:UNUSED_PAD src0_sel:WORD_1 src1_sel:DWORD
	v_add3_u32 v5, v5, v6, s54
	v_add3_u32 v4, v4, v7, s54
	v_and_b32_e32 v5, 0xffff0000, v5
	v_and_b32_e32 v4, 0xffff0000, v4
	v_or_b32_sdwa v3, v5, v3 dst_sel:DWORD dst_unused:UNUSED_PAD src0_sel:DWORD src1_sel:WORD_1
	v_or_b32_sdwa v2, v4, v2 dst_sel:DWORD dst_unused:UNUSED_PAD src0_sel:DWORD src1_sel:WORD_1
	ds_read_b128 v[4:7], v44
	v_add_co_u32_e32 v8, vcc, s70, v8
	s_nop 1
	v_addc_co_u32_e32 v9, vcc, 0, v9, vcc
	global_store_dwordx4 v[8:9], v[0:3], off offset:1024
	s_waitcnt lgkmcnt(0)
	v_mov_b32_e32 v8, v4
	v_mov_b32_e32 v9, v6
	ds_read_b128 v[0:3], v44 offset:16
	v_pk_mul_f32 v[8:9], v[16:17], v[8:9]
	v_mov_b32_e32 v6, v5
	v_pk_mul_f32 v[4:5], v[18:19], v[6:7]
	v_and_b32_sdwa v6, v9, v155 dst_sel:DWORD dst_unused:UNUSED_PAD src0_sel:WORD_1 src1_sel:DWORD
	v_and_b32_sdwa v7, v8, v155 dst_sel:DWORD dst_unused:UNUSED_PAD src0_sel:WORD_1 src1_sel:DWORD
	v_add3_u32 v7, v8, v7, s54
	v_add3_u32 v6, v9, v6, s54
	v_and_b32_sdwa v8, v5, v155 dst_sel:DWORD dst_unused:UNUSED_PAD src0_sel:WORD_1 src1_sel:DWORD
	v_and_b32_sdwa v9, v4, v155 dst_sel:DWORD dst_unused:UNUSED_PAD src0_sel:WORD_1 src1_sel:DWORD
	v_add3_u32 v5, v5, v8, s54
	v_add3_u32 v4, v4, v9, s54
	v_and_b32_e32 v5, 0xffff0000, v5
	v_and_b32_e32 v4, 0xffff0000, v4
	v_or_b32_sdwa v5, v5, v6 dst_sel:DWORD dst_unused:UNUSED_PAD src0_sel:DWORD src1_sel:WORD_1
	v_or_b32_sdwa v4, v4, v7 dst_sel:DWORD dst_unused:UNUSED_PAD src0_sel:DWORD src1_sel:WORD_1
	s_waitcnt lgkmcnt(0)
	v_mov_b32_e32 v6, v0
	v_mov_b32_e32 v7, v2
	v_pk_mul_f32 v[6:7], v[20:21], v[6:7]
	v_mov_b32_e32 v2, v1
	v_pk_mul_f32 v[0:1], v[22:23], v[2:3]
	v_and_b32_sdwa v2, v7, v155 dst_sel:DWORD dst_unused:UNUSED_PAD src0_sel:WORD_1 src1_sel:DWORD
	v_and_b32_sdwa v3, v6, v155 dst_sel:DWORD dst_unused:UNUSED_PAD src0_sel:WORD_1 src1_sel:DWORD
	v_add3_u32 v2, v7, v2, s54
	v_and_b32_sdwa v7, v0, v155 dst_sel:DWORD dst_unused:UNUSED_PAD src0_sel:WORD_1 src1_sel:DWORD
	v_add3_u32 v3, v6, v3, s54
	v_and_b32_sdwa v6, v1, v155 dst_sel:DWORD dst_unused:UNUSED_PAD src0_sel:WORD_1 src1_sel:DWORD
	v_add3_u32 v0, v0, v7, s54
	v_add3_u32 v1, v1, v6, s54
	v_and_b32_e32 v0, 0xffff0000, v0
	v_and_b32_e32 v1, 0xffff0000, v1
	v_or_b32_sdwa v6, v0, v3 dst_sel:DWORD dst_unused:UNUSED_PAD src0_sel:DWORD src1_sel:WORD_1
	v_add_co_u32_e32 v0, vcc, 0x184a1000, v14
	v_or_b32_sdwa v7, v1, v2 dst_sel:DWORD dst_unused:UNUSED_PAD src0_sel:DWORD src1_sel:WORD_1
	s_nop 0
	v_addc_co_u32_e32 v1, vcc, 0, v15, vcc
	global_store_dwordx4 v[0:1], v[4:7], off offset:1024
	s_barrier

; __device__ void phase_merge(const Params& p, int layer, char* smem) {
;     ...
;           int seg = s / 48, r = s - seg * 48;
;           if (r == 31) {
; #pragma unroll
;             for (int n = 0; n < 4; ++n) {
;               float bm = bmp[seg * 1024 + n * 16];
; #pragma unroll
;               for (int m = 0; m < 4; ++m)
; #pragma unroll
;                 for (int j = 0; j < 4; ++j) {
;                   GL[((m * 4 + n) * 4 + j) * 256] = f2bf(1.f / (1.f + __expf(-(acc[m][n][j] + bm))));
;                   acc[m][n][j] = 0.f;
;                 }
;             }
.LBB0_1237:
	s_cmp_eq_u32 s10, 31
	s_cbranch_scc0 .LBB0_1239
	s_mul_i32 s6, s54, 0xab
	s_lshr_b32 s6, s6, 1
	s_and_b32 s14, s6, 0x7000
	v_lshl_add_u64 v[2:3], v[230:231], 0, s[14:15]
	global_load_dword v164, v[2:3], off
	global_load_dword v165, v[2:3], off offset:64
	global_load_dword v166, v[2:3], off offset:128
	global_load_dword v1, v[2:3], off offset:192
	s_waitcnt vmcnt(3)
	v_add_f32_e32 v2, v160, v164
	v_add_f32_e32 v3, v161, v164
	v_mul_f32_e32 v2, 0xbfb8aa3b, v2
	v_add_f32_e32 v167, v162, v164
	v_mul_f32_e32 v3, 0xbfb8aa3b, v3
	v_exp_f32_e32 v2, v2
	v_add_f32_e32 v168, v163, v164
	v_mul_f32_e32 v167, 0xbfb8aa3b, v167
	v_exp_f32_e32 v3, v3
	v_mul_f32_e32 v168, 0xbfb8aa3b, v168
	v_exp_f32_e32 v167, v167
	v_exp_f32_e32 v168, v168
	v_add_f32_e32 v2, 1.0, v2
	v_add_f32_e32 v3, 1.0, v3
	v_add_f32_e32 v169, v144, v164
	v_add_f32_e32 v167, 1.0, v167
	v_mul_f32_e32 v169, 0xbfb8aa3b, v169
	v_add_f32_e32 v168, 1.0, v168
	v_exp_f32_e32 v169, v169
	s_nop 0
	v_add_f32_e32 v169, 1.0, v169
	v_div_scale_f32 v174, s[6:7], 1.0, v3, 1.0
	v_div_scale_f32 v176, s[8:9], 1.0, v167, 1.0
	v_div_scale_f32 v178, s[10:11], 1.0, v168, 1.0
	v_add_f32_e32 v170, v145, v164
	s_mov_b64 vcc, s[6:7]
	v_mul_f32_e32 v170, 0xbfb8aa3b, v170
	v_rcp_f32_e32 v2, v2
	s_nop 0
	s_mov_b64 vcc, s[8:9]
	v_exp_f32_e32 v170, v170
	v_bfe_u32 v172, v2, 16, 1
	v_rcp_f32_e32 v3, v3
	s_nop 0
	s_mov_b64 vcc, s[10:11]
	v_div_scale_f32 v180, s[12:13], 1.0, v169, 1.0
	v_add3_u32 v2, v2, v172, s49
	v_bfe_u32 v172, v3, 16, 1
	v_rcp_f32_e32 v167, v167
	s_nop 0
	ds_write_b16_d16_hi v234, v2 offset:32768
	v_add3_u32 v2, v3, v172, s49
	v_bfe_u32 v3, v167, 16, 1
	v_rcp_f32_e32 v168, v168
	s_nop 0
	ds_write_b16_d16_hi v234, v2 offset:33280
	v_add3_u32 v2, v167, v3, s49
	v_bfe_u32 v3, v168, 16, 1
	ds_write_b16_d16_hi v234, v2 offset:33792
	v_add3_u32 v2, v168, v3, s49
	v_add_f32_e32 v3, 1.0, v170
	s_mov_b64 vcc, s[12:13]
	ds_write_b16_d16_hi v234, v2 offset:34304
	v_rcp_f32_e32 v2, v169
	s_nop 0
	v_bfe_u32 v169, v2, 16, 1
	v_add3_u32 v2, v2, v169, s49
	ds_write_b16_d16_hi v234, v2 offset:40960
	v_add_f32_e32 v167, v146, v164
	v_mul_f32_e32 v167, 0xbfb8aa3b, v167
	v_exp_f32_e32 v167, v167
	v_rcp_f32_e32 v2, v3
	s_nop 0
	v_bfe_u32 v169, v2, 16, 1
	v_add_f32_e32 v3, 1.0, v167
	v_add3_u32 v2, v2, v169, s49
	ds_write_b16_d16_hi v234, v2 offset:41472
	v_add_f32_e32 v167, v147, v164
	v_mul_f32_e32 v167, 0xbfb8aa3b, v167
	v_exp_f32_e32 v167, v167
	v_rcp_f32_e32 v2, v3
	s_nop 0
	v_bfe_u32 v169, v2, 16, 1
	v_add_f32_e32 v3, 1.0, v167
	v_add3_u32 v2, v2, v169, s49
	ds_write_b16_d16_hi v234, v2 offset:41984
	v_add_f32_e32 v167, v128, v164
	v_mul_f32_e32 v167, 0xbfb8aa3b, v167
	v_exp_f32_e32 v167, v167
	v_rcp_f32_e32 v2, v3
	s_nop 0
	v_bfe_u32 v169, v2, 16, 1
	v_add_f32_e32 v3, 1.0, v167
	v_add3_u32 v2, v2, v169, s49
	ds_write_b16_d16_hi v234, v2 offset:42496
	v_add_f32_e32 v167, v129, v164
	v_mul_f32_e32 v167, 0xbfb8aa3b, v167
	v_exp_f32_e32 v167, v167
	v_rcp_f32_e32 v2, v3
	s_nop 0
	v_bfe_u32 v169, v2, 16, 1
	v_add_f32_e32 v3, 1.0, v167
	v_add3_u32 v2, v2, v169, s49
	ds_write_b16_d16_hi v234, v2 offset:49152
	v_add_f32_e32 v167, v130, v164
	v_mul_f32_e32 v167, 0xbfb8aa3b, v167
	v_exp_f32_e32 v167, v167
	v_rcp_f32_e32 v2, v3
	s_nop 0
	v_bfe_u32 v169, v2, 16, 1
	v_add_f32_e32 v3, 1.0, v167
	v_add3_u32 v2, v2, v169, s49
	ds_write_b16_d16_hi v234, v2 offset:49664
	v_add_f32_e32 v167, v131, v164
	v_mul_f32_e32 v167, 0xbfb8aa3b, v167
	v_exp_f32_e32 v167, v167
	v_rcp_f32_e32 v2, v3
	s_nop 0
	v_bfe_u32 v169, v2, 16, 1
	v_add_f32_e32 v3, 1.0, v167
	v_add3_u32 v2, v2, v169, s49
	ds_write_b16_d16_hi v234, v2 offset:50176
	v_add_f32_e32 v167, v112, v164
	v_mul_f32_e32 v167, 0xbfb8aa3b, v167
	v_exp_f32_e32 v167, v167
	v_rcp_f32_e32 v2, v3
	s_nop 0
	v_bfe_u32 v169, v2, 16, 1
	v_add_f32_e32 v3, 1.0, v167
	v_add3_u32 v2, v2, v169, s49
	ds_write_b16_d16_hi v234, v2 offset:50688
	v_add_f32_e32 v167, v113, v164
	v_mul_f32_e32 v167, 0xbfb8aa3b, v167
	v_exp_f32_e32 v167, v167
	v_rcp_f32_e32 v2, v3
	s_nop 0
	v_bfe_u32 v169, v2, 16, 1
	v_add_f32_e32 v3, 1.0, v167
	v_add3_u32 v2, v2, v169, s49
	ds_write_b16_d16_hi v234, v2 offset:57344
	v_add_f32_e32 v167, v114, v164
	v_mul_f32_e32 v167, 0xbfb8aa3b, v167
	v_exp_f32_e32 v167, v167
	v_rcp_f32_e32 v2, v3
	s_nop 0
	v_bfe_u32 v169, v2, 16, 1
	v_add_f32_e32 v3, 1.0, v167
	v_add3_u32 v2, v2, v169, s49
	ds_write_b16_d16_hi v234, v2 offset:57856
	v_add_f32_e32 v164, v115, v164
	v_mul_f32_e32 v164, 0xbfb8aa3b, v164
	v_exp_f32_e32 v164, v164
	v_rcp_f32_e32 v2, v3
	s_nop 0
	v_add_f32_e32 v3, 1.0, v164
	v_bfe_u32 v168, v2, 16, 1
	v_add3_u32 v2, v2, v168, s49
	ds_write_b16_d16_hi v234, v2 offset:58368
	s_waitcnt vmcnt(2)
; __device__ void phase_merge(const Params& p, int layer, char* smem) {
;     ...
;             for (int n = 0; n < 4; ++n) {
;               float bm = bmp[seg * 1024 + n * 16];
; #pragma unroll
;               for (int m = 0; m < 4; ++m)
; #pragma unroll
;                 for (int j = 0; j < 4; ++j) {
;                   GL[((m * 4 + n) * 4 + j) * 256] = f2bf(1.f / (1.f + __expf(-(acc[m][n][j] + bm))));
;                   acc[m][n][j] = 0.f;
;                 }
;             }
	v_add_f32_e32 v164, v156, v165
	v_mul_f32_e32 v164, 0xbfb8aa3b, v164
	v_exp_f32_e32 v164, v164
	v_rcp_f32_e32 v2, v3
	s_nop 0
	v_bfe_u32 v168, v2, 16, 1
	v_add_f32_e32 v3, 1.0, v164
	v_add3_u32 v2, v2, v168, s49
	ds_write_b16_d16_hi v234, v2 offset:58880
	v_add_f32_e32 v164, v157, v165
	v_mul_f32_e32 v164, 0xbfb8aa3b, v164
	v_exp_f32_e32 v164, v164
	v_rcp_f32_e32 v2, v3
	s_nop 0
	v_bfe_u32 v168, v2, 16, 1
	v_add_f32_e32 v3, 1.0, v164
	v_add3_u32 v2, v2, v168, s49
	ds_write_b16_d16_hi v234, v2 offset:34816
	v_add_f32_e32 v164, v158, v165
	v_mul_f32_e32 v164, 0xbfb8aa3b, v164
	v_exp_f32_e32 v164, v164
	v_rcp_f32_e32 v2, v3
	s_nop 0
	v_bfe_u32 v168, v2, 16, 1
	v_add_f32_e32 v3, 1.0, v164
	v_add3_u32 v2, v2, v168, s49
	ds_write_b16_d16_hi v234, v2 offset:35328
	v_add_f32_e32 v164, v159, v165
	v_mul_f32_e32 v164, 0xbfb8aa3b, v164
	v_exp_f32_e32 v164, v164
	v_rcp_f32_e32 v2, v3
	s_nop 0
	v_bfe_u32 v168, v2, 16, 1
	v_add_f32_e32 v3, 1.0, v164
	v_add3_u32 v2, v2, v168, s49
	ds_write_b16_d16_hi v234, v2 offset:35840
	v_add_f32_e32 v164, v140, v165
	v_mul_f32_e32 v164, 0xbfb8aa3b, v164
	v_exp_f32_e32 v164, v164
	v_rcp_f32_e32 v2, v3
	s_nop 0
	v_bfe_u32 v168, v2, 16, 1
	v_add_f32_e32 v3, 1.0, v164
	v_add3_u32 v2, v2, v168, s49
	ds_write_b16_d16_hi v234, v2 offset:36352
	v_add_f32_e32 v164, v141, v165
	v_mul_f32_e32 v164, 0xbfb8aa3b, v164
	v_exp_f32_e32 v164, v164
	v_rcp_f32_e32 v2, v3
	s_nop 0
	v_bfe_u32 v168, v2, 16, 1
	v_add_f32_e32 v3, 1.0, v164
	v_add3_u32 v2, v2, v168, s49
	ds_write_b16_d16_hi v234, v2 offset:43008
	v_add_f32_e32 v164, v142, v165
	v_mul_f32_e32 v164, 0xbfb8aa3b, v164
	v_exp_f32_e32 v164, v164
	v_rcp_f32_e32 v2, v3
	s_nop 0
	v_bfe_u32 v168, v2, 16, 1
	v_add_f32_e32 v3, 1.0, v164
	v_add3_u32 v2, v2, v168, s49
	ds_write_b16_d16_hi v234, v2 offset:43520
	v_add_f32_e32 v164, v143, v165
	v_mul_f32_e32 v164, 0xbfb8aa3b, v164
	v_exp_f32_e32 v164, v164
	v_rcp_f32_e32 v2, v3
	s_nop 0
	v_bfe_u32 v168, v2, 16, 1
	v_add_f32_e32 v3, 1.0, v164
	v_add3_u32 v2, v2, v168, s49
	ds_write_b16_d16_hi v234, v2 offset:44032
	v_add_f32_e32 v164, v124, v165
	v_mul_f32_e32 v164, 0xbfb8aa3b, v164
	v_exp_f32_e32 v164, v164
	v_rcp_f32_e32 v2, v3
	s_nop 0
	v_bfe_u32 v168, v2, 16, 1
	v_add_f32_e32 v3, 1.0, v164
	v_add3_u32 v2, v2, v168, s49
	ds_write_b16_d16_hi v234, v2 offset:44544
	v_add_f32_e32 v164, v125, v165
	v_mul_f32_e32 v164, 0xbfb8aa3b, v164
	v_exp_f32_e32 v164, v164
	v_rcp_f32_e32 v2, v3
	s_nop 0
	v_bfe_u32 v168, v2, 16, 1
	v_add_f32_e32 v3, 1.0, v164
	v_add3_u32 v2, v2, v168, s49
	ds_write_b16_d16_hi v234, v2 offset:51200
	v_add_f32_e32 v164, v126, v165
	v_mul_f32_e32 v164, 0xbfb8aa3b, v164
	v_exp_f32_e32 v164, v164
	v_rcp_f32_e32 v2, v3
	s_nop 0
	v_bfe_u32 v168, v2, 16, 1
	v_add_f32_e32 v3, 1.0, v164
	v_add3_u32 v2, v2, v168, s49
	ds_write_b16_d16_hi v234, v2 offset:51712
	v_add_f32_e32 v164, v127, v165
	v_mul_f32_e32 v164, 0xbfb8aa3b, v164
	v_exp_f32_e32 v164, v164
	v_rcp_f32_e32 v2, v3
	s_nop 0
	v_bfe_u32 v168, v2, 16, 1
	v_add_f32_e32 v3, 1.0, v164
	v_add3_u32 v2, v2, v168, s49
	ds_write_b16_d16_hi v234, v2 offset:52224
	v_add_f32_e32 v164, v108, v165
	v_mul_f32_e32 v164, 0xbfb8aa3b, v164
	v_exp_f32_e32 v164, v164
	v_rcp_f32_e32 v2, v3
	s_nop 0
	v_bfe_u32 v168, v2, 16, 1
	v_add_f32_e32 v3, 1.0, v164
	v_add3_u32 v2, v2, v168, s49
	ds_write_b16_d16_hi v234, v2 offset:52736
	v_add_f32_e32 v164, v109, v165
	v_mul_f32_e32 v164, 0xbfb8aa3b, v164
	v_exp_f32_e32 v164, v164
	v_rcp_f32_e32 v2, v3
	s_nop 0
	v_bfe_u32 v168, v2, 16, 1
	v_add_f32_e32 v3, 1.0, v164
	v_add3_u32 v2, v2, v168, s49
	ds_write_b16_d16_hi v234, v2 offset:59392
	v_add_f32_e32 v164, v110, v165
	v_mul_f32_e32 v164, 0xbfb8aa3b, v164
	v_exp_f32_e32 v164, v164
	v_rcp_f32_e32 v2, v3
	s_nop 0
	v_bfe_u32 v168, v2, 16, 1
	v_add_f32_e32 v3, 1.0, v164
	v_add3_u32 v2, v2, v168, s49
	ds_write_b16_d16_hi v234, v2 offset:59904
	v_add_f32_e32 v164, v111, v165
	v_mul_f32_e32 v164, 0xbfb8aa3b, v164
	v_exp_f32_e32 v164, v164
	v_rcp_f32_e32 v2, v3
	s_nop 0
	v_bfe_u32 v167, v2, 16, 1
	v_add_f32_e32 v3, 1.0, v164
	v_add3_u32 v2, v2, v167, s49
	ds_write_b16_d16_hi v234, v2 offset:60416
	s_waitcnt vmcnt(1)
	v_add_f32_e32 v164, v152, v166
	v_mul_f32_e32 v164, 0xbfb8aa3b, v164
	v_exp_f32_e32 v164, v164
	v_rcp_f32_e32 v2, v3
	s_nop 0
	v_bfe_u32 v167, v2, 16, 1
	v_add_f32_e32 v3, 1.0, v164
	v_add3_u32 v2, v2, v167, s49
	ds_write_b16_d16_hi v234, v2 offset:60928
	v_add_f32_e32 v164, v153, v166
	v_mul_f32_e32 v164, 0xbfb8aa3b, v164
	v_exp_f32_e32 v164, v164
	v_rcp_f32_e32 v2, v3
	s_nop 0
	v_bfe_u32 v167, v2, 16, 1
	v_add_f32_e32 v3, 1.0, v164
	v_add3_u32 v2, v2, v167, s49
	ds_write_b16_d16_hi v234, v2 offset:36864
	v_add_f32_e32 v164, v154, v166
	v_mul_f32_e32 v164, 0xbfb8aa3b, v164
	v_exp_f32_e32 v164, v164
	v_rcp_f32_e32 v2, v3
	s_nop 0
	v_bfe_u32 v167, v2, 16, 1
	v_add_f32_e32 v3, 1.0, v164
	v_add3_u32 v2, v2, v167, s49
	ds_write_b16_d16_hi v234, v2 offset:37376
	v_add_f32_e32 v164, v155, v166
	v_mul_f32_e32 v164, 0xbfb8aa3b, v164
	v_exp_f32_e32 v164, v164
	v_rcp_f32_e32 v2, v3
	s_nop 0
	v_bfe_u32 v167, v2, 16, 1
	v_add_f32_e32 v3, 1.0, v164
	v_add3_u32 v2, v2, v167, s49
	ds_write_b16_d16_hi v234, v2 offset:37888
	v_add_f32_e32 v164, v136, v166
	v_mul_f32_e32 v164, 0xbfb8aa3b, v164
	v_exp_f32_e32 v164, v164
	v_rcp_f32_e32 v2, v3
	s_nop 0
	v_bfe_u32 v167, v2, 16, 1
	v_add_f32_e32 v3, 1.0, v164
	v_add3_u32 v2, v2, v167, s49
	ds_write_b16_d16_hi v234, v2 offset:38400
	v_add_f32_e32 v164, v137, v166
	v_mul_f32_e32 v164, 0xbfb8aa3b, v164
	v_exp_f32_e32 v164, v164
	v_rcp_f32_e32 v2, v3
	s_nop 0
	v_bfe_u32 v167, v2, 16, 1
	v_add_f32_e32 v3, 1.0, v164
	v_add3_u32 v2, v2, v167, s49
	ds_write_b16_d16_hi v234, v2 offset:45056
; __device__ void phase_merge(const Params& p, int layer, char* smem) {
;     ...
;             for (int n = 0; n < 4; ++n) {
;               float bm = bmp[seg * 1024 + n * 16];
; #pragma unroll
;               for (int m = 0; m < 4; ++m)
; #pragma unroll
;                 for (int j = 0; j < 4; ++j) {
;                   GL[((m * 4 + n) * 4 + j) * 256] = f2bf(1.f / (1.f + __expf(-(acc[m][n][j] + bm))));
;                   acc[m][n][j] = 0.f;
;                 }
;             }
	v_add_f32_e32 v164, v138, v166
	v_mul_f32_e32 v164, 0xbfb8aa3b, v164
	v_exp_f32_e32 v164, v164
	v_rcp_f32_e32 v2, v3
	s_nop 0
	v_bfe_u32 v167, v2, 16, 1
	v_add_f32_e32 v3, 1.0, v164
	v_add3_u32 v2, v2, v167, s49
	ds_write_b16_d16_hi v234, v2 offset:45568
	v_add_f32_e32 v164, v139, v166
	v_mul_f32_e32 v164, 0xbfb8aa3b, v164
	v_exp_f32_e32 v164, v164
	v_rcp_f32_e32 v2, v3
	s_nop 0
	v_bfe_u32 v167, v2, 16, 1
	v_add_f32_e32 v3, 1.0, v164
	v_add3_u32 v2, v2, v167, s49
	ds_write_b16_d16_hi v234, v2 offset:46080
	v_add_f32_e32 v164, v120, v166
	v_mul_f32_e32 v164, 0xbfb8aa3b, v164
	v_exp_f32_e32 v164, v164
	v_rcp_f32_e32 v2, v3
	s_nop 0
	v_bfe_u32 v167, v2, 16, 1
	v_add_f32_e32 v3, 1.0, v164
	v_add3_u32 v2, v2, v167, s49
	ds_write_b16_d16_hi v234, v2 offset:46592
	v_add_f32_e32 v164, v121, v166
	v_mul_f32_e32 v164, 0xbfb8aa3b, v164
	v_exp_f32_e32 v164, v164
	v_rcp_f32_e32 v2, v3
	s_nop 0
	v_bfe_u32 v167, v2, 16, 1
	v_add_f32_e32 v3, 1.0, v164
	v_add3_u32 v2, v2, v167, s49
	ds_write_b16_d16_hi v234, v2 offset:53248
	v_add_f32_e32 v164, v122, v166
	v_mul_f32_e32 v164, 0xbfb8aa3b, v164
	v_exp_f32_e32 v164, v164
	v_rcp_f32_e32 v2, v3
	s_nop 0
	v_bfe_u32 v167, v2, 16, 1
	v_add_f32_e32 v3, 1.0, v164
	v_add3_u32 v2, v2, v167, s49
	ds_write_b16_d16_hi v234, v2 offset:53760
	v_add_f32_e32 v164, v123, v166
	v_mul_f32_e32 v164, 0xbfb8aa3b, v164
	v_exp_f32_e32 v164, v164
	v_rcp_f32_e32 v2, v3
	s_nop 0
	v_bfe_u32 v167, v2, 16, 1
	v_add_f32_e32 v3, 1.0, v164
	v_add3_u32 v2, v2, v167, s49
	ds_write_b16_d16_hi v234, v2 offset:54272
	v_add_f32_e32 v164, v100, v166
	v_mul_f32_e32 v164, 0xbfb8aa3b, v164
	v_exp_f32_e32 v164, v164
	v_rcp_f32_e32 v2, v3
	s_nop 0
	v_bfe_u32 v167, v2, 16, 1
	v_add_f32_e32 v3, 1.0, v164
	v_add3_u32 v2, v2, v167, s49
	ds_write_b16_d16_hi v234, v2 offset:54784
	v_add_f32_e32 v164, v101, v166
	v_mul_f32_e32 v164, 0xbfb8aa3b, v164
	v_exp_f32_e32 v164, v164
	v_rcp_f32_e32 v2, v3
	s_nop 0
	v_bfe_u32 v167, v2, 16, 1
	v_add_f32_e32 v3, 1.0, v164
	v_add3_u32 v2, v2, v167, s49
	ds_write_b16_d16_hi v234, v2 offset:61440
	v_add_f32_e32 v164, v102, v166
	v_mul_f32_e32 v164, 0xbfb8aa3b, v164
	v_exp_f32_e32 v164, v164
	v_rcp_f32_e32 v2, v3
	s_nop 0
	v_bfe_u32 v167, v2, 16, 1
	v_add_f32_e32 v3, 1.0, v164
	v_add3_u32 v2, v2, v167, s49
	ds_write_b16_d16_hi v234, v2 offset:61952
	v_add_f32_e32 v164, v103, v166
	v_mul_f32_e32 v164, 0xbfb8aa3b, v164
	v_exp_f32_e32 v164, v164
	v_rcp_f32_e32 v2, v3
	s_nop 0
	v_bfe_u32 v166, v2, 16, 1
	v_add_f32_e32 v3, 1.0, v164
	v_add3_u32 v2, v2, v166, s49
	ds_write_b16_d16_hi v234, v2 offset:62464
	s_waitcnt vmcnt(0)
	v_add_f32_e32 v164, v148, v1
	v_mul_f32_e32 v164, 0xbfb8aa3b, v164
	v_exp_f32_e32 v164, v164
	v_rcp_f32_e32 v2, v3
	s_nop 0
	v_bfe_u32 v166, v2, 16, 1
	v_add_f32_e32 v3, 1.0, v164
	v_add3_u32 v2, v2, v166, s49
	ds_write_b16_d16_hi v234, v2 offset:62976
	v_add_f32_e32 v164, v149, v1
	v_mul_f32_e32 v164, 0xbfb8aa3b, v164
	v_exp_f32_e32 v164, v164
	v_rcp_f32_e32 v2, v3
	s_nop 0
	v_bfe_u32 v166, v2, 16, 1
	v_add_f32_e32 v3, 1.0, v164
	v_add3_u32 v2, v2, v166, s49
	ds_write_b16_d16_hi v234, v2 offset:38912
	v_add_f32_e32 v164, v150, v1
	v_mul_f32_e32 v164, 0xbfb8aa3b, v164
	v_exp_f32_e32 v164, v164
	v_rcp_f32_e32 v2, v3
	s_nop 0
	v_bfe_u32 v166, v2, 16, 1
	v_add_f32_e32 v3, 1.0, v164
	v_add3_u32 v2, v2, v166, s49
	ds_write_b16_d16_hi v234, v2 offset:39424
	v_add_f32_e32 v164, v151, v1
	v_mul_f32_e32 v164, 0xbfb8aa3b, v164
	v_exp_f32_e32 v164, v164
	v_rcp_f32_e32 v2, v3
	s_nop 0
	v_bfe_u32 v166, v2, 16, 1
	v_add_f32_e32 v3, 1.0, v164
	v_add3_u32 v2, v2, v166, s49
	ds_write_b16_d16_hi v234, v2 offset:39936
	v_add_f32_e32 v164, v132, v1
	v_mul_f32_e32 v164, 0xbfb8aa3b, v164
	v_exp_f32_e32 v164, v164
	v_rcp_f32_e32 v2, v3
	s_nop 0
	v_bfe_u32 v166, v2, 16, 1
	v_add_f32_e32 v3, 1.0, v164
	v_add3_u32 v2, v2, v166, s49
	ds_write_b16_d16_hi v234, v2 offset:40448
	v_add_f32_e32 v164, v133, v1
	v_mul_f32_e32 v164, 0xbfb8aa3b, v164
	v_exp_f32_e32 v164, v164
	v_rcp_f32_e32 v2, v3
	s_nop 0
	v_bfe_u32 v166, v2, 16, 1
	v_add_f32_e32 v3, 1.0, v164
	v_add3_u32 v2, v2, v166, s49
	ds_write_b16_d16_hi v234, v2 offset:47104
	v_add_f32_e32 v164, v134, v1
	v_mul_f32_e32 v164, 0xbfb8aa3b, v164
	v_exp_f32_e32 v164, v164
	v_rcp_f32_e32 v2, v3
	s_nop 0
	v_bfe_u32 v166, v2, 16, 1
	v_add_f32_e32 v3, 1.0, v164
	v_add3_u32 v2, v2, v166, s49
	ds_write_b16_d16_hi v234, v2 offset:47616
	v_add_f32_e32 v164, v135, v1
	v_mul_f32_e32 v164, 0xbfb8aa3b, v164
	v_exp_f32_e32 v164, v164
	v_rcp_f32_e32 v2, v3
	s_nop 0
	v_bfe_u32 v166, v2, 16, 1
	v_add_f32_e32 v3, 1.0, v164
	v_add3_u32 v2, v2, v166, s49
	ds_write_b16_d16_hi v234, v2 offset:48128
	v_add_f32_e32 v164, v116, v1
	v_mul_f32_e32 v164, 0xbfb8aa3b, v164
	v_exp_f32_e32 v164, v164
	v_rcp_f32_e32 v2, v3
	s_nop 0
	v_bfe_u32 v166, v2, 16, 1
	v_add_f32_e32 v3, 1.0, v164
	v_add3_u32 v2, v2, v166, s49
	ds_write_b16_d16_hi v234, v2 offset:48640
	v_add_f32_e32 v164, v117, v1
	v_mul_f32_e32 v164, 0xbfb8aa3b, v164
	v_exp_f32_e32 v164, v164
	v_rcp_f32_e32 v2, v3
	s_nop 0
	v_bfe_u32 v166, v2, 16, 1
	v_add_f32_e32 v3, 1.0, v164
	v_add3_u32 v2, v2, v166, s49
	ds_write_b16_d16_hi v234, v2 offset:55296
	v_add_f32_e32 v164, v118, v1
	v_mul_f32_e32 v164, 0xbfb8aa3b, v164
	v_exp_f32_e32 v164, v164
	v_rcp_f32_e32 v2, v3
	s_nop 0
	v_bfe_u32 v166, v2, 16, 1
	v_add_f32_e32 v3, 1.0, v164
	v_add3_u32 v2, v2, v166, s49
	ds_write_b16_d16_hi v234, v2 offset:55808
	v_add_f32_e32 v164, v119, v1
	v_mul_f32_e32 v164, 0xbfb8aa3b, v164
	v_exp_f32_e32 v164, v164
	v_rcp_f32_e32 v2, v3
	s_nop 0
	v_bfe_u32 v166, v2, 16, 1
	v_add_f32_e32 v3, 1.0, v164
	v_add3_u32 v2, v2, v166, s49
	ds_write_b16_d16_hi v234, v2 offset:56320
	v_add_f32_e32 v164, v104, v1
	v_mul_f32_e32 v164, 0xbfb8aa3b, v164
	v_exp_f32_e32 v164, v164
	v_rcp_f32_e32 v2, v3
	s_nop 0
	v_bfe_u32 v166, v2, 16, 1
	v_add_f32_e32 v3, 1.0, v164
	v_add3_u32 v2, v2, v166, s49
	ds_write_b16_d16_hi v234, v2 offset:56832
	v_add_f32_e32 v164, v105, v1
	v_mul_f32_e32 v164, 0xbfb8aa3b, v164
	v_exp_f32_e32 v164, v164
	v_rcp_f32_e32 v2, v3
	s_nop 0
	v_bfe_u32 v166, v2, 16, 1
	v_add_f32_e32 v3, 1.0, v164
	v_add3_u32 v2, v2, v166, s49
	ds_write_b16_d16_hi v234, v2 offset:63488
	v_add_f32_e32 v164, v106, v1
	v_mul_f32_e32 v164, 0xbfb8aa3b, v164
	v_exp_f32_e32 v164, v164
	v_rcp_f32_e32 v2, v3
	s_nop 0
	v_bfe_u32 v166, v2, 16, 1
	v_add_f32_e32 v3, 1.0, v164
	v_add3_u32 v2, v2, v166, s49
	ds_write_b16_d16_hi v234, v2 offset:64000
	v_add_f32_e32 v1, v107, v1
	v_mul_f32_e32 v1, 0xbfb8aa3b, v1
	v_exp_f32_e32 v1, v1
	v_rcp_f32_e32 v2, v3
	s_nop 0
	v_bfe_u32 v3, v2, 16, 1
	v_add3_u32 v2, v2, v3, s49
	v_add_f32_e32 v3, 1.0, v1
	ds_write_b16_d16_hi v234, v2 offset:64512
	v_mov_b32_e32 v1, v0
	v_mov_b32_e32 v2, v0
	v_rcp_f32_e32 v3, v3
	s_nop 0
	v_bfe_u32 v164, v3, 16, 1
	v_add3_u32 v3, v3, v164, s49
	ds_write_b16_d16_hi v234, v3 offset:65024
	s_mov_b64 s[6:7], -1
